# flat->global addressing for all VMEM ops + vmcnt waits re-derived per register dependency (counted waits at first consumer)
# speedup vs baseline: 1.0236x; 1.0236x over previous
; #define LAS __attribute__((address_space(3)))
;     ...
;     const int nblk = N / 32, kb = item / nblk, nb = item % nblk, k0 = 64 * kb, n0 = 32 * nb;
;     float tv_[32];
; #pragma unroll
;     for (int i = 0; i < 32; ++i) tv_[i] = W[(size_t)(k0 + 2 * i + (lane >> 5)) * N + n0 + (lane & 31)];
; #pragma unroll
;     for (int i = 0; i < 32; ++i) scr[(2 * i + (lane >> 5)) * 33 + (lane & 31)] = tv_[i];
;     LDS_WAIT(); asm volatile("" ::: "memory");
;     const int c = lane & 7;
; #pragma unroll
;     for (int j = 0; j < 4; ++j) { const int n = (lane >> 3) + 8 * j; const LAS float* s = scr + (8 * c) * 33 + n;
;         v4u o; o.x = pk2(s[0 * 33], s[1 * 33]); o.y = pk2(s[2 * 33], s[3 * 33]); o.z = pk2(s[4 * 33], s[5 * 33]); o.w = pk2(s[6 * 33], s[7 * 33]);
;         *(v4u*)(WT + (size_t)(n0 + n) * ldw + koff + k0 + 8 * c) = o; }
;     LDS_WAIT(); asm volatile("" ::: "memory");
; }
; __device__ __forceinline__ void convert_range(LAS unsigned char* lds, const Params& p, const int lo, const int hi, const int gw, const int NGW) {
;     int tid_ = threadIdx.x; asm volatile("" : "+v"(tid_)); const int lane = tid_ & 63, wave = tid_ >> 6;
;     LAS float* scr = (LAS float*)(lds + wave * 16384);
;     unsigned char* ws = p.ws; asm volatile("" : "+s"(ws));
;     for (int it = lo + gw; it < hi; it += NGW) {
;         int r = it;
;         if (r < 2 * I_IN) { const int l = r / I_IN; r -= l * I_IN; p0_transpose_item(p.in[5] + (size_t)l * DM * NC, DM, NC, (bf16*)(ws + WS_WIN + l * SZ_WIN), scr, r, lane); continue; } r -= 2 * I_IN;
;         if (r < 2 * I_PA) { const int l = r / I_PA; r -= l * I_PA; p0_transpose_item(p.in[16] + (size_t)l * PW * DM, PW, DM, (bf16*)(ws + WS_WCAT + l * SZ_WCAT), scr, r, lane, KCAT, 0); continue; } r -= 2 * I_PA;
;         if (r < 2 * I_PB) { const int l = r / I_PB; r -= l * I_PB; p0_transpose_item(p.in[17] + (size_t)l * LW * DM, LW, DM, (bf16*)(ws + WS_WCAT + l * SZ_WCAT), scr, r, lane, KCAT, PW); continue; } r -= 2 * I_PB;
;         if (r < 2 * I_OUT) { const int l = r / I_OUT; r -= l * I_OUT; p0_transpose_item(p.in[18] + (size_t)l * DM * DM, DM, DM, (bf16*)(ws + WS_WOUT + l * SZ_WOUT), scr, r, lane); continue; } r -= 2 * I_OUT;
;         if (r < I_PL) { const int mi = r / 32; r -= mi * 32; p0_transpose_item(p.in[7] + (size_t)mi * 65536, 256, 256, (bf16*)(ws + WS_POOLW) + (size_t)mi * 65536, scr, r, lane); continue; } r -= I_PL;
.LBB0_22:
	v_add_u32_e32 v20, 0x7a00, v27
	s_movk_i32 s24, 0x4fff
	v_cmp_lt_i32_e32 vcc, s24, v20
	s_and_saveexec_b64 s[24:25], vcc
	s_xor_b64 s[24:25], exec, s[24:25]
	s_cbranch_execz .LBB0_44
	s_movk_i32 s26, 0x57ff
	v_cmp_lt_u32_e32 vcc, s26, v20
	s_and_saveexec_b64 s[26:27], vcc
	s_xor_b64 s[26:27], exec, s[26:27]
	s_cbranch_execz .LBB0_41
	s_movk_i32 s28, 0x67ff
	v_cmp_lt_u32_e32 vcc, s28, v20
	s_and_saveexec_b64 s[28:29], vcc
	s_xor_b64 s[28:29], exec, s[28:29]
	s_cbranch_execz .LBB0_38
	s_movk_i32 s30, 0x77ff
	v_cmp_lt_u32_e32 vcc, s30, v20
	s_and_saveexec_b64 s[30:31], vcc
	s_xor_b64 s[30:31], exec, s[30:31]
	s_cbranch_execz .LBB0_35
	s_movk_i32 s34, 0x78ff
	v_cmp_lt_u32_e32 vcc, s34, v20
	s_and_saveexec_b64 s[34:35], vcc
	s_xor_b64 s[34:35], exec, s[34:35]
	s_cbranch_execz .LBB0_32
	s_movk_i32 s36, 0x79ff
	v_cmp_lt_u32_e32 vcc, s36, v20
	v_and_b32_e32 v20, 64, v28
	v_or_b32_e32 v4, v20, v1
	v_lshlrev_b32_e32 v21, 7, v4
	s_and_saveexec_b64 s[36:37], vcc
	s_xor_b64 s[36:37], exec, s[36:37]
	s_cbranch_execz .LBB0_29
	v_lshrrev_b32_e32 v4, 3, v27
	v_lshlrev_b64 v[36:37], 16, v[4:5]
	v_lshlrev_b64 v[34:35], 15, v[4:5]
	v_lshl_add_u64 v[36:37], v[16:17], 0, v[36:37]
	v_lshlrev_b32_e32 v4, 2, v21
	v_lshl_add_u64 v[36:37], v[36:37], 0, v[4:5]
	v_add_co_u32_e32 v38, vcc, 0x1000, v36
	v_add_u32_e32 v66, 0x1000, v3
	s_nop 0
	v_addc_co_u32_e32 v39, vcc, 0, v37, vcc
	global_load_dword v4, v[36:37], off
	global_load_dword v21, v[36:37], off offset:1024
	global_load_dword v33, v[36:37], off offset:2048
	global_load_dword v42, v[36:37], off offset:3072
	global_load_dword v43, v[38:39], off
	global_load_dword v44, v[38:39], off offset:1024
	global_load_dword v45, v[38:39], off offset:2048
	global_load_dword v46, v[38:39], off offset:3072
	v_add_co_u32_e32 v38, vcc, 0x2000, v36
	v_add_u32_e32 v67, 0x1400, v3
	s_nop 0
	v_addc_co_u32_e32 v39, vcc, 0, v37, vcc
	v_add_co_u32_e32 v40, vcc, 0x3000, v36
	v_add_u32_e32 v68, 0x1800, v3
	s_nop 0
	v_addc_co_u32_e32 v41, vcc, 0, v37, vcc
	global_load_dword v47, v[38:39], off
	global_load_dword v48, v[38:39], off offset:1024
	global_load_dword v49, v[38:39], off offset:2048
	global_load_dword v50, v[38:39], off offset:3072
	global_load_dword v51, v[40:41], off
	global_load_dword v52, v[40:41], off offset:1024
	global_load_dword v53, v[40:41], off offset:2048
	global_load_dword v54, v[40:41], off offset:3072
	v_add_co_u32_e32 v38, vcc, 0x4000, v36
	v_add_u32_e32 v69, 0x1c00, v3
	s_nop 0
	v_addc_co_u32_e32 v39, vcc, 0, v37, vcc
	v_add_co_u32_e32 v40, vcc, 0x5000, v36
	v_lshl_add_u64 v[34:35], s[12:13], 0, v[34:35]
	s_nop 0
	v_addc_co_u32_e32 v41, vcc, 0, v37, vcc
	global_load_dword v55, v[38:39], off
	global_load_dword v56, v[38:39], off offset:1024
	global_load_dword v57, v[38:39], off offset:2048
	global_load_dword v58, v[38:39], off offset:3072
	global_load_dword v59, v[40:41], off
	global_load_dword v60, v[40:41], off offset:1024
	global_load_dword v61, v[40:41], off offset:2048
	s_nop 0
	global_load_dword v40, v[40:41], off offset:3072
	v_add_co_u32_e32 v38, vcc, 0x6000, v36
	s_nop 1
	v_addc_co_u32_e32 v39, vcc, 0, v37, vcc
	v_add_co_u32_e32 v36, vcc, 0x7000, v36
	s_nop 1
	v_addc_co_u32_e32 v37, vcc, 0, v37, vcc
	global_load_dword v41, v[38:39], off
	global_load_dword v62, v[38:39], off offset:1024
	global_load_dword v63, v[38:39], off offset:2048
	s_nop 0
	global_load_dword v38, v[38:39], off offset:3072
	s_nop 0
	global_load_dword v39, v[36:37], off
	global_load_dword v64, v[36:37], off offset:1024
	global_load_dword v65, v[36:37], off offset:2048
	s_nop 0
	global_load_dword v36, v[36:37], off offset:3072
	v_add_u32_e32 v37, 0xc00, v3
	s_waitcnt vmcnt(30)
	ds_write2_b32 v3, v4, v21 offset1:66
	s_waitcnt vmcnt(28)
	ds_write2_b32 v3, v33, v42 offset0:132 offset1:198
	s_waitcnt vmcnt(26)
	ds_write2_b32 v31, v43, v44 offset0:8 offset1:74
	s_waitcnt vmcnt(24)
	ds_write2_b32 v31, v45, v46 offset0:140 offset1:206
	s_waitcnt vmcnt(22)
	ds_write2_b32 v32, v47, v48 offset0:16 offset1:82
	s_waitcnt vmcnt(20)
	ds_write2_b32 v32, v49, v50 offset0:148 offset1:214
	s_waitcnt vmcnt(18)
	ds_write2_b32 v37, v51, v52 offset0:24 offset1:90
	s_waitcnt vmcnt(16)
	ds_write2_b32 v37, v53, v54 offset0:156 offset1:222
	s_waitcnt vmcnt(14)
	ds_write2_b32 v66, v55, v56 offset0:32 offset1:98
	s_waitcnt vmcnt(12)
	ds_write2_b32 v66, v57, v58 offset0:164 offset1:230
	s_waitcnt vmcnt(10)
	ds_write2_b32 v67, v59, v60 offset0:40 offset1:106
	s_waitcnt vmcnt(8)
	ds_write2_b32 v67, v61, v40 offset0:172 offset1:238
	s_waitcnt vmcnt(6)
	ds_write2_b32 v68, v41, v62 offset0:48 offset1:114
	s_waitcnt vmcnt(4)
	ds_write2_b32 v68, v63, v38 offset0:180 offset1:246
	s_waitcnt vmcnt(2)
	ds_write2_b32 v69, v39, v64 offset0:56 offset1:122
	s_waitcnt vmcnt(0)
	ds_write2_b32 v69, v65, v36 offset0:188 offset1:254
	s_waitcnt lgkmcnt(0)
	v_lshlrev_b32_e32 v4, 1, v20
	v_lshl_add_u64 v[20:21], v[34:35], 0, v[4:5]
	v_lshlrev_b32_e32 v4, 1, v6
	v_lshl_add_u64 v[20:21], v[20:21], 0, v[4:5]
	ds_read_b32 v4, v23
	ds_read_b32 v33, v23 offset:132
	ds_read_b32 v35, v23 offset:264
	ds_read_b32 v36, v23 offset:396
	ds_read_b32 v37, v23 offset:528
	ds_read_b32 v38, v23 offset:660
	ds_read_b32 v39, v23 offset:792
	ds_read_b32 v40, v23 offset:924
	s_waitcnt lgkmcnt(7)
	v_bfe_u32 v34, v4, 16, 1
	v_add3_u32 v4, v4, v34, s41
	s_waitcnt lgkmcnt(6)
	v_bfe_u32 v34, v33, 16, 1
	v_lshrrev_b32_e32 v4, 16, v4
	v_add3_u32 v33, v33, v34, s41
	v_and_or_b32 v34, v33, s42, v4
	s_waitcnt lgkmcnt(5)
	v_bfe_u32 v4, v35, 16, 1
	v_add3_u32 v4, v35, v4, s41
	s_waitcnt lgkmcnt(4)
	v_bfe_u32 v33, v36, 16, 1
	v_lshrrev_b32_e32 v4, 16, v4
	v_add3_u32 v33, v36, v33, s41
	v_and_or_b32 v35, v33, s42, v4
	s_waitcnt lgkmcnt(3)
; #define LAS __attribute__((address_space(3)))
; #define LDS_WAIT() asm volatile("s_waitcnt lgkmcnt(0)" ::: "memory")
; __device__ __forceinline__ unsigned pk2(float lo, float hi) { return f2bf(lo) | (f2bf(hi) << 16); }
;     ...
;     const int c = lane & 7;
; #pragma unroll
;     for (int j = 0; j < 4; ++j) { const int n = (lane >> 3) + 8 * j; const LAS float* s = scr + (8 * c) * 33 + n;
;         v4u o; o.x = pk2(s[0 * 33], s[1 * 33]); o.y = pk2(s[2 * 33], s[3 * 33]); o.z = pk2(s[4 * 33], s[5 * 33]); o.w = pk2(s[6 * 33], s[7 * 33]);
;         *(v4u*)(WT + (size_t)(n0 + n) * ldw + koff + k0 + 8 * c) = o; }
;     LDS_WAIT(); asm volatile("" ::: "memory");
; __device__ __forceinline__ void convert_range(LAS unsigned char* lds, const Params& p, const int lo, const int hi, const int gw, const int NGW) {
;     ...
;         if (r < I_LR) { const int mi = r / 8; r -= mi * 8; p0_transpose_item(p.in[11] + (size_t)mi * 16384, 128, 128, (bf16*)(ws + WS_WA) + (size_t)mi * 16384, scr, r, lane); continue; } r -= I_LR;
	v_bfe_u32 v4, v37, 16, 1
	v_add3_u32 v4, v37, v4, s41
	s_waitcnt lgkmcnt(2)
	v_bfe_u32 v33, v38, 16, 1
	v_lshrrev_b32_e32 v4, 16, v4
	v_add3_u32 v33, v38, v33, s41
	v_and_or_b32 v36, v33, s42, v4
	s_waitcnt lgkmcnt(1)
	v_bfe_u32 v4, v39, 16, 1
	v_add3_u32 v4, v39, v4, s41
	s_waitcnt lgkmcnt(0)
	v_bfe_u32 v33, v40, 16, 1
	v_lshrrev_b32_e32 v4, 16, v4
	v_add3_u32 v33, v40, v33, s41
	v_and_or_b32 v37, v33, s42, v4
	v_lshl_add_u64 v[38:39], v[20:21], 0, v[8:9]
	global_store_dwordx4 v[38:39], v[34:37], off
	ds_read_b32 v4, v23 offset:32
	ds_read_b32 v33, v23 offset:164
	ds_read_b32 v35, v23 offset:296
	ds_read_b32 v36, v23 offset:428
	ds_read_b32 v37, v23 offset:560
	ds_read_b32 v38, v23 offset:692
	ds_read_b32 v39, v23 offset:824
	ds_read_b32 v40, v23 offset:956
	s_waitcnt lgkmcnt(0)
	v_bfe_u32 v34, v4, 16, 1
	v_add3_u32 v4, v4, v34, s41
	v_bfe_u32 v34, v33, 16, 1
	v_lshrrev_b32_e32 v4, 16, v4
	v_add3_u32 v33, v33, v34, s41
	v_and_or_b32 v34, v33, s42, v4
	v_bfe_u32 v4, v35, 16, 1
	v_add3_u32 v4, v35, v4, s41
	v_bfe_u32 v33, v36, 16, 1
	v_lshrrev_b32_e32 v4, 16, v4
	v_add3_u32 v33, v36, v33, s41
	v_and_or_b32 v35, v33, s42, v4
	v_bfe_u32 v4, v37, 16, 1
	v_add3_u32 v4, v37, v4, s41
	v_bfe_u32 v33, v38, 16, 1
	v_lshrrev_b32_e32 v4, 16, v4
	v_add3_u32 v33, v38, v33, s41
	v_and_or_b32 v36, v33, s42, v4
	v_bfe_u32 v4, v39, 16, 1
	v_add3_u32 v4, v39, v4, s41
	v_bfe_u32 v33, v40, 16, 1
	v_lshrrev_b32_e32 v4, 16, v4
	v_add3_u32 v33, v40, v33, s41
	v_and_or_b32 v37, v33, s42, v4
	v_lshl_add_u64 v[38:39], v[20:21], 0, v[10:11]
	global_store_dwordx4 v[38:39], v[34:37], off
	ds_read_b32 v4, v23 offset:64
	ds_read_b32 v33, v23 offset:196
	ds_read_b32 v35, v23 offset:328
	ds_read_b32 v36, v23 offset:460
	ds_read_b32 v37, v23 offset:592
	ds_read_b32 v38, v23 offset:724
	ds_read_b32 v39, v23 offset:856
	ds_read_b32 v40, v23 offset:988
	s_waitcnt lgkmcnt(0)
	v_bfe_u32 v34, v4, 16, 1
	v_add3_u32 v4, v4, v34, s41
	v_bfe_u32 v34, v33, 16, 1
	v_lshrrev_b32_e32 v4, 16, v4
	v_add3_u32 v33, v33, v34, s41
	v_and_or_b32 v34, v33, s42, v4
	v_bfe_u32 v4, v35, 16, 1
	v_add3_u32 v4, v35, v4, s41
	v_bfe_u32 v33, v36, 16, 1
	v_lshrrev_b32_e32 v4, 16, v4
	v_add3_u32 v33, v36, v33, s41
	v_and_or_b32 v35, v33, s42, v4
	v_bfe_u32 v4, v37, 16, 1
	v_add3_u32 v4, v37, v4, s41
	v_bfe_u32 v33, v38, 16, 1
	v_lshrrev_b32_e32 v4, 16, v4
	v_add3_u32 v33, v38, v33, s41
	v_and_or_b32 v36, v33, s42, v4
	v_bfe_u32 v4, v39, 16, 1
	v_add3_u32 v4, v39, v4, s41
	v_bfe_u32 v33, v40, 16, 1
	v_lshrrev_b32_e32 v4, 16, v4
	v_add3_u32 v33, v40, v33, s41
	v_and_or_b32 v37, v33, s42, v4
	v_lshl_add_u64 v[38:39], v[20:21], 0, v[12:13]
	global_store_dwordx4 v[38:39], v[34:37], off
	ds_read_b32 v4, v23 offset:96
	ds_read_b32 v33, v23 offset:228
	ds_read_b32 v35, v23 offset:360
	ds_read_b32 v36, v23 offset:492
	ds_read_b32 v37, v23 offset:624
	ds_read_b32 v38, v23 offset:756
	ds_read_b32 v39, v23 offset:888
	ds_read_b32 v40, v23 offset:1020
	s_waitcnt lgkmcnt(0)
	v_bfe_u32 v34, v4, 16, 1
	v_add3_u32 v4, v4, v34, s41
	v_bfe_u32 v34, v33, 16, 1
	v_lshrrev_b32_e32 v4, 16, v4
	v_add3_u32 v33, v33, v34, s41
	v_and_or_b32 v34, v33, s42, v4
	v_bfe_u32 v4, v35, 16, 1
	v_add3_u32 v4, v35, v4, s41
	v_bfe_u32 v33, v36, 16, 1
	v_lshrrev_b32_e32 v4, 16, v4
	v_add3_u32 v33, v36, v33, s41
	v_and_or_b32 v35, v33, s42, v4
	v_bfe_u32 v4, v37, 16, 1
	v_add3_u32 v4, v37, v4, s41
	v_bfe_u32 v33, v38, 16, 1
	v_lshrrev_b32_e32 v4, 16, v4
	v_add3_u32 v33, v38, v33, s41
	v_and_or_b32 v36, v33, s42, v4
	v_bfe_u32 v4, v39, 16, 1
	v_add3_u32 v4, v39, v4, s41
	v_bfe_u32 v33, v40, 16, 1
	v_lshrrev_b32_e32 v4, 16, v4
	v_add3_u32 v33, v40, v33, s41
	v_and_or_b32 v37, v33, s42, v4
	v_lshl_add_u64 v[20:21], v[20:21], 0, v[14:15]
	global_store_dwordx4 v[20:21], v[34:37], off
	s_waitcnt lgkmcnt(0)
.LBB0_29:
	s_andn2_saveexec_b64 s[36:37], s[36:37]
	s_cbranch_execz .LBB0_31
	v_add_u32_e32 v4, 0x100, v27
	v_lshrrev_b32_e32 v4, 3, v4
	v_lshlrev_b64 v[36:37], 16, v[4:5]
	v_lshlrev_b64 v[34:35], 15, v[4:5]
	v_lshl_add_u64 v[36:37], v[18:19], 0, v[36:37]
	v_lshlrev_b32_e32 v4, 2, v21
	v_lshl_add_u64 v[36:37], v[36:37], 0, v[4:5]
	v_add_co_u32_e32 v38, vcc, 0x1000, v36
	v_add_u32_e32 v66, 0x1000, v3
	s_nop 0
	v_addc_co_u32_e32 v39, vcc, 0, v37, vcc
	global_load_dword v4, v[36:37], off
	global_load_dword v21, v[36:37], off offset:1024
	global_load_dword v33, v[36:37], off offset:2048
	global_load_dword v42, v[36:37], off offset:3072
	global_load_dword v43, v[38:39], off
	global_load_dword v44, v[38:39], off offset:1024
	global_load_dword v45, v[38:39], off offset:2048
	global_load_dword v46, v[38:39], off offset:3072
	v_add_co_u32_e32 v38, vcc, 0x2000, v36
	v_add_u32_e32 v67, 0x1400, v3
	s_nop 0
	v_addc_co_u32_e32 v39, vcc, 0, v37, vcc
	v_add_co_u32_e32 v40, vcc, 0x3000, v36
	v_add_u32_e32 v68, 0x1800, v3
	s_nop 0
	v_addc_co_u32_e32 v41, vcc, 0, v37, vcc
	global_load_dword v47, v[38:39], off
	global_load_dword v48, v[38:39], off offset:1024
	global_load_dword v49, v[38:39], off offset:2048
	global_load_dword v50, v[38:39], off offset:3072
	global_load_dword v51, v[40:41], off
	global_load_dword v52, v[40:41], off offset:1024
	global_load_dword v53, v[40:41], off offset:2048
	global_load_dword v54, v[40:41], off offset:3072
	v_add_co_u32_e32 v38, vcc, 0x4000, v36
	v_add_u32_e32 v69, 0x1c00, v3
	s_nop 0
	v_addc_co_u32_e32 v39, vcc, 0, v37, vcc
	v_add_co_u32_e32 v40, vcc, 0x5000, v36
	v_lshl_add_u64 v[34:35], s[14:15], 0, v[34:35]
	s_nop 0
	v_addc_co_u32_e32 v41, vcc, 0, v37, vcc
	global_load_dword v55, v[38:39], off
	global_load_dword v56, v[38:39], off offset:1024
	global_load_dword v57, v[38:39], off offset:2048
	global_load_dword v58, v[38:39], off offset:3072
	global_load_dword v59, v[40:41], off
	global_load_dword v60, v[40:41], off offset:1024
	global_load_dword v61, v[40:41], off offset:2048
	s_nop 0
	global_load_dword v40, v[40:41], off offset:3072
	v_add_co_u32_e32 v38, vcc, 0x6000, v36
	s_nop 1
	v_addc_co_u32_e32 v39, vcc, 0, v37, vcc
	v_add_co_u32_e32 v36, vcc, 0x7000, v36
	s_nop 1
	v_addc_co_u32_e32 v37, vcc, 0, v37, vcc
	global_load_dword v41, v[38:39], off
	global_load_dword v62, v[38:39], off offset:1024
	global_load_dword v63, v[38:39], off offset:2048
	s_nop 0
	global_load_dword v38, v[38:39], off offset:3072
	s_nop 0
	global_load_dword v39, v[36:37], off
	global_load_dword v64, v[36:37], off offset:1024
	global_load_dword v65, v[36:37], off offset:2048
	s_nop 0
	global_load_dword v36, v[36:37], off offset:3072
	v_add_u32_e32 v37, 0xc00, v3
	s_waitcnt vmcnt(30)
; #define LAS __attribute__((address_space(3)))
; #define LDS_WAIT() asm volatile("s_waitcnt lgkmcnt(0)" ::: "memory")
; __device__ __forceinline__ unsigned pk2(float lo, float hi) { return f2bf(lo) | (f2bf(hi) << 16); }
;     ...
;     for (int i = 0; i < 32; ++i) scr[(2 * i + (lane >> 5)) * 33 + (lane & 31)] = tv_[i];
;     LDS_WAIT(); asm volatile("" ::: "memory");
;     const int c = lane & 7;
; #pragma unroll
;     for (int j = 0; j < 4; ++j) { const int n = (lane >> 3) + 8 * j; const LAS float* s = scr + (8 * c) * 33 + n;
;         v4u o; o.x = pk2(s[0 * 33], s[1 * 33]); o.y = pk2(s[2 * 33], s[3 * 33]); o.z = pk2(s[4 * 33], s[5 * 33]); o.w = pk2(s[6 * 33], s[7 * 33]);
;         *(v4u*)(WT + (size_t)(n0 + n) * ldw + koff + k0 + 8 * c) = o; }
;     LDS_WAIT(); asm volatile("" ::: "memory");
	ds_write2_b32 v3, v4, v21 offset1:66
	s_waitcnt vmcnt(28)
	ds_write2_b32 v3, v33, v42 offset0:132 offset1:198
	s_waitcnt vmcnt(26)
	ds_write2_b32 v31, v43, v44 offset0:8 offset1:74
	s_waitcnt vmcnt(24)
	ds_write2_b32 v31, v45, v46 offset0:140 offset1:206
	s_waitcnt vmcnt(22)
	ds_write2_b32 v32, v47, v48 offset0:16 offset1:82
	s_waitcnt vmcnt(20)
	ds_write2_b32 v32, v49, v50 offset0:148 offset1:214
	s_waitcnt vmcnt(18)
	ds_write2_b32 v37, v51, v52 offset0:24 offset1:90
	s_waitcnt vmcnt(16)
	ds_write2_b32 v37, v53, v54 offset0:156 offset1:222
	s_waitcnt vmcnt(14)
	ds_write2_b32 v66, v55, v56 offset0:32 offset1:98
	s_waitcnt vmcnt(12)
	ds_write2_b32 v66, v57, v58 offset0:164 offset1:230
	s_waitcnt vmcnt(10)
	ds_write2_b32 v67, v59, v60 offset0:40 offset1:106
	s_waitcnt vmcnt(8)
	ds_write2_b32 v67, v61, v40 offset0:172 offset1:238
	s_waitcnt vmcnt(6)
	ds_write2_b32 v68, v41, v62 offset0:48 offset1:114
	s_waitcnt vmcnt(4)
	ds_write2_b32 v68, v63, v38 offset0:180 offset1:246
	s_waitcnt vmcnt(2)
	ds_write2_b32 v69, v39, v64 offset0:56 offset1:122
	s_waitcnt vmcnt(0)
	ds_write2_b32 v69, v65, v36 offset0:188 offset1:254
	s_waitcnt lgkmcnt(0)
	v_lshlrev_b32_e32 v4, 1, v20
	v_lshl_add_u64 v[20:21], v[34:35], 0, v[4:5]
	v_lshlrev_b32_e32 v4, 1, v6
	v_lshl_add_u64 v[20:21], v[20:21], 0, v[4:5]
	ds_read_b32 v4, v23
	ds_read_b32 v33, v23 offset:132
	ds_read_b32 v35, v23 offset:264
	ds_read_b32 v36, v23 offset:396
	ds_read_b32 v37, v23 offset:528
	ds_read_b32 v38, v23 offset:660
	ds_read_b32 v39, v23 offset:792
	ds_read_b32 v40, v23 offset:924
	s_waitcnt lgkmcnt(0)
	v_bfe_u32 v34, v4, 16, 1
	v_add3_u32 v4, v4, v34, s41
	v_bfe_u32 v34, v33, 16, 1
	v_lshrrev_b32_e32 v4, 16, v4
	v_add3_u32 v33, v33, v34, s41
	v_and_or_b32 v34, v33, s42, v4
	v_bfe_u32 v4, v35, 16, 1
	v_add3_u32 v4, v35, v4, s41
	v_bfe_u32 v33, v36, 16, 1
	v_lshrrev_b32_e32 v4, 16, v4
	v_add3_u32 v33, v36, v33, s41
	v_and_or_b32 v35, v33, s42, v4
	v_bfe_u32 v4, v37, 16, 1
	v_add3_u32 v4, v37, v4, s41
	v_bfe_u32 v33, v38, 16, 1
	v_lshrrev_b32_e32 v4, 16, v4
	v_add3_u32 v33, v38, v33, s41
	v_and_or_b32 v36, v33, s42, v4
	v_bfe_u32 v4, v39, 16, 1
	v_add3_u32 v4, v39, v4, s41
	v_bfe_u32 v33, v40, 16, 1
	v_lshrrev_b32_e32 v4, 16, v4
	v_add3_u32 v33, v40, v33, s41
	v_and_or_b32 v37, v33, s42, v4
	v_lshl_add_u64 v[38:39], v[20:21], 0, v[8:9]
	global_store_dwordx4 v[38:39], v[34:37], off
	ds_read_b32 v4, v23 offset:32
	ds_read_b32 v33, v23 offset:164
	ds_read_b32 v35, v23 offset:296
	ds_read_b32 v36, v23 offset:428
	ds_read_b32 v37, v23 offset:560
	ds_read_b32 v38, v23 offset:692
	ds_read_b32 v39, v23 offset:824
	ds_read_b32 v40, v23 offset:956
	s_waitcnt lgkmcnt(0)
	v_bfe_u32 v34, v4, 16, 1
	v_add3_u32 v4, v4, v34, s41
	v_bfe_u32 v34, v33, 16, 1
	v_lshrrev_b32_e32 v4, 16, v4
	v_add3_u32 v33, v33, v34, s41
	v_and_or_b32 v34, v33, s42, v4
	v_bfe_u32 v4, v35, 16, 1
	v_add3_u32 v4, v35, v4, s41
	v_bfe_u32 v33, v36, 16, 1
	v_lshrrev_b32_e32 v4, 16, v4
	v_add3_u32 v33, v36, v33, s41
	v_and_or_b32 v35, v33, s42, v4
	v_bfe_u32 v4, v37, 16, 1
	v_add3_u32 v4, v37, v4, s41
	v_bfe_u32 v33, v38, 16, 1
	v_lshrrev_b32_e32 v4, 16, v4
	v_add3_u32 v33, v38, v33, s41
	v_and_or_b32 v36, v33, s42, v4
	v_bfe_u32 v4, v39, 16, 1
	v_add3_u32 v4, v39, v4, s41
	v_bfe_u32 v33, v40, 16, 1
	v_lshrrev_b32_e32 v4, 16, v4
	v_add3_u32 v33, v40, v33, s41
	v_and_or_b32 v37, v33, s42, v4
	v_lshl_add_u64 v[38:39], v[20:21], 0, v[10:11]
	global_store_dwordx4 v[38:39], v[34:37], off
	ds_read_b32 v4, v23 offset:64
	ds_read_b32 v33, v23 offset:196
	ds_read_b32 v35, v23 offset:328
	ds_read_b32 v36, v23 offset:460
	ds_read_b32 v37, v23 offset:592
	ds_read_b32 v38, v23 offset:724
	ds_read_b32 v39, v23 offset:856
	ds_read_b32 v40, v23 offset:988
	s_waitcnt lgkmcnt(0)
	v_bfe_u32 v34, v4, 16, 1
	v_add3_u32 v4, v4, v34, s41
	v_bfe_u32 v34, v33, 16, 1
	v_lshrrev_b32_e32 v4, 16, v4
	v_add3_u32 v33, v33, v34, s41
	v_and_or_b32 v34, v33, s42, v4
	v_bfe_u32 v4, v35, 16, 1
	v_add3_u32 v4, v35, v4, s41
	v_bfe_u32 v33, v36, 16, 1
	v_lshrrev_b32_e32 v4, 16, v4
	v_add3_u32 v33, v36, v33, s41
	v_and_or_b32 v35, v33, s42, v4
	v_bfe_u32 v4, v37, 16, 1
	v_add3_u32 v4, v37, v4, s41
	v_bfe_u32 v33, v38, 16, 1
	v_lshrrev_b32_e32 v4, 16, v4
	v_add3_u32 v33, v38, v33, s41
	v_and_or_b32 v36, v33, s42, v4
	v_bfe_u32 v4, v39, 16, 1
	v_add3_u32 v4, v39, v4, s41
	v_bfe_u32 v33, v40, 16, 1
	v_lshrrev_b32_e32 v4, 16, v4
	v_add3_u32 v33, v40, v33, s41
	v_and_or_b32 v37, v33, s42, v4
	v_lshl_add_u64 v[38:39], v[20:21], 0, v[12:13]
	global_store_dwordx4 v[38:39], v[34:37], off
	ds_read_b32 v4, v23 offset:96
	ds_read_b32 v33, v23 offset:228
	ds_read_b32 v35, v23 offset:360
	ds_read_b32 v36, v23 offset:492
	ds_read_b32 v37, v23 offset:624
	ds_read_b32 v38, v23 offset:756
	ds_read_b32 v39, v23 offset:888
	ds_read_b32 v40, v23 offset:1020
	s_waitcnt lgkmcnt(0)
	v_bfe_u32 v34, v4, 16, 1
	v_add3_u32 v4, v4, v34, s41
	v_bfe_u32 v34, v33, 16, 1
	v_lshrrev_b32_e32 v4, 16, v4
	v_add3_u32 v33, v33, v34, s41
	v_and_or_b32 v34, v33, s42, v4
	v_bfe_u32 v4, v35, 16, 1
	v_add3_u32 v4, v35, v4, s41
	v_bfe_u32 v33, v36, 16, 1
	v_lshrrev_b32_e32 v4, 16, v4
	v_add3_u32 v33, v36, v33, s41
	v_and_or_b32 v35, v33, s42, v4
	v_bfe_u32 v4, v37, 16, 1
	v_add3_u32 v4, v37, v4, s41
	v_bfe_u32 v33, v38, 16, 1
	v_lshrrev_b32_e32 v4, 16, v4
	v_add3_u32 v33, v38, v33, s41
	v_and_or_b32 v36, v33, s42, v4
	v_bfe_u32 v4, v39, 16, 1
	v_add3_u32 v4, v39, v4, s41
	v_bfe_u32 v33, v40, 16, 1
	v_lshrrev_b32_e32 v4, 16, v4
	v_add3_u32 v33, v40, v33, s41
	v_and_or_b32 v37, v33, s42, v4
	v_lshl_add_u64 v[20:21], v[20:21], 0, v[14:15]
	global_store_dwordx4 v[20:21], v[34:37], off
	s_waitcnt lgkmcnt(0)

;     ...
;     const int nblk = N / 32, kb = item / nblk, nb = item % nblk, k0 = 64 * kb, n0 = 32 * nb;
;     float tv_[32];
; #pragma unroll
;     for (int i = 0; i < 32; ++i) tv_[i] = W[(size_t)(k0 + 2 * i + (lane >> 5)) * N + n0 + (lane & 31)];
;     ...
;     for (int i = 0; i < 32; ++i) scr[(2 * i + (lane >> 5)) * 33 + (lane & 31)] = tv_[i];
; __device__ __forceinline__ void convert_range(LAS unsigned char* lds, const Params& p, const int lo, const int hi, const int gw, const int NGW) {
;     ...
;         if (r < I_PL) { const int mi = r / 32; r -= mi * 32; p0_transpose_item(p.in[7] + (size_t)mi * 65536, 256, 256, (bf16*)(ws + WS_POOLW) + (size_t)mi * 65536, scr, r, lane); continue; } r -= I_PL;
.LBB0_32:
	s_andn2_saveexec_b64 s[34:35], s[34:35]
	s_cbranch_execz .LBB0_34
	v_add_u32_e32 v4, 0x200, v27
	v_lshrrev_b32_e32 v4, 5, v4
	v_readlane_b32 s60, v251, 21
	v_lshlrev_b64 v[20:21], 18, v[4:5]
	v_readlane_b32 s74, v251, 35
	v_readlane_b32 s75, v251, 36
	v_and_b32_e32 v54, 0xe0, v30
	v_lshlrev_b64 v[34:35], 17, v[4:5]
	v_lshl_add_u64 v[20:21], s[74:75], 0, v[20:21]
	v_and_b32_e32 v33, 0xc0, v29
	v_lshlrev_b32_e32 v4, 2, v54
	v_or_b32_e32 v36, v33, v1
	v_lshl_add_u64 v[20:21], v[20:21], 0, v[4:5]
	v_lshlrev_b32_e32 v4, 2, v2
	v_lshl_add_u64 v[20:21], v[20:21], 0, v[4:5]
	v_lshlrev_b32_e32 v4, 10, v36
	v_lshl_add_u64 v[20:21], v[20:21], 0, v[4:5]
	s_movk_i32 s36, 0x1000
	v_add_co_u32_e32 v36, vcc, s36, v20
	s_movk_i32 s36, 0x2000
	s_nop 0
	v_addc_co_u32_e32 v37, vcc, 0, v21, vcc
	v_add_co_u32_e32 v38, vcc, s36, v20
	s_movk_i32 s36, 0x3000
	s_nop 0
	v_addc_co_u32_e32 v39, vcc, 0, v21, vcc
	v_add_co_u32_e32 v40, vcc, s36, v20
	s_movk_i32 s36, 0x5000
	s_nop 0
	v_addc_co_u32_e32 v41, vcc, 0, v21, vcc
	v_add_co_u32_e32 v42, vcc, s40, v20
	v_readlane_b32 s61, v251, 22
	s_nop 0
	v_addc_co_u32_e32 v43, vcc, 0, v21, vcc
	global_load_dword v4, v[38:39], off offset:-4096
	global_load_dword v55, v[38:39], off
	global_load_dword v56, v[38:39], off offset:2048
	global_load_dword v57, v[42:43], off offset:-4096
	global_load_dword v58, v[42:43], off
	v_add_co_u32_e32 v38, vcc, s36, v20
	s_movk_i32 s36, 0x6000
	s_nop 0
	v_addc_co_u32_e32 v39, vcc, 0, v21, vcc
	v_add_co_u32_e32 v44, vcc, s36, v20
	s_movk_i32 s36, 0x7000
	s_nop 0
	v_addc_co_u32_e32 v45, vcc, 0, v21, vcc
	v_add_co_u32_e32 v46, vcc, s36, v20
	s_mov_b32 s36, 0x9000
	s_nop 0
	v_addc_co_u32_e32 v47, vcc, 0, v21, vcc
	v_add_co_u32_e32 v48, vcc, s43, v20
	v_readlane_b32 s62, v251, 23
	s_nop 0
	v_addc_co_u32_e32 v49, vcc, 0, v21, vcc
	v_add_co_u32_e32 v50, vcc, s36, v20
	s_mov_b32 s36, 0xb000
	s_nop 0
	v_addc_co_u32_e32 v51, vcc, 0, v21, vcc
	v_add_co_u32_e32 v52, vcc, s44, v20
	v_readlane_b32 s63, v251, 24
	s_nop 0
	v_addc_co_u32_e32 v53, vcc, 0, v21, vcc
	global_load_dword v59, v[42:43], off offset:2048
	global_load_dword v60, v[44:45], off offset:-4096
	global_load_dword v61, v[44:45], off
	global_load_dword v62, v[44:45], off offset:2048
	global_load_dword v63, v[48:49], off offset:-4096
	global_load_dword v64, v[48:49], off
	s_nop 0
	global_load_dword v48, v[48:49], off offset:2048
	s_nop 0
	global_load_dword v49, v[52:53], off offset:-4096
	v_add_co_u32_e32 v42, vcc, s36, v20
	s_mov_b32 s36, 0xd000
	s_nop 0
	v_addc_co_u32_e32 v43, vcc, 0, v21, vcc
	v_add_co_u32_e32 v44, vcc, s45, v20
	global_load_dword v65, v[20:21], off
	global_load_dword v66, v[20:21], off offset:2048
	global_load_dword v67, v[36:37], off offset:2048
	s_nop 0
	global_load_dword v40, v[40:41], off offset:2048
	s_nop 0
	global_load_dword v41, v[38:39], off offset:2048
	s_nop 0
	global_load_dword v46, v[46:47], off offset:2048
	s_nop 0
	global_load_dword v47, v[50:51], off offset:2048
	s_nop 0
	global_load_dword v42, v[42:43], off offset:2048
	v_addc_co_u32_e32 v45, vcc, 0, v21, vcc
	v_add_co_u32_e32 v36, vcc, s36, v20
	s_mov_b32 s36, 0xe000
	s_nop 0
	v_addc_co_u32_e32 v37, vcc, 0, v21, vcc
	v_add_co_u32_e32 v38, vcc, s36, v20
	s_mov_b32 s36, 0xf000
	s_nop 0
	v_addc_co_u32_e32 v39, vcc, 0, v21, vcc
	v_add_co_u32_e32 v20, vcc, s36, v20
	global_load_dword v36, v[36:37], off offset:2048
	s_nop 0
	global_load_dword v37, v[52:53], off
	global_load_dword v43, v[52:53], off offset:2048
	global_load_dword v50, v[44:45], off offset:-4096
	global_load_dword v51, v[44:45], off
	s_nop 0
	global_load_dword v44, v[44:45], off offset:2048
	s_nop 0
	global_load_dword v45, v[38:39], off offset:-4096
	global_load_dword v52, v[38:39], off
	s_nop 0
	global_load_dword v38, v[38:39], off offset:2048
	v_addc_co_u32_e32 v21, vcc, 0, v21, vcc
	global_load_dword v39, v[20:21], off
	global_load_dword v53, v[20:21], off offset:2048
	v_lshl_add_u64 v[20:21], s[16:17], 0, v[34:35]
	v_readlane_b32 s64, v251, 25
	v_readlane_b32 s65, v251, 26
	v_readlane_b32 s66, v251, 27
	v_readlane_b32 s67, v251, 28
	v_readlane_b32 s68, v251, 29
	v_readlane_b32 s69, v251, 30
	v_readlane_b32 s70, v251, 31
	v_readlane_b32 s71, v251, 32
	s_waitcnt vmcnt(17)
	ds_write2_b32 v3, v65, v66 offset1:66
	s_waitcnt vmcnt(16)
	ds_write2_b32 v3, v4, v67 offset0:132 offset1:198
	ds_write2_b32 v31, v55, v56 offset0:8 offset1:74
	s_waitcnt vmcnt(15)
	ds_write2_b32 v31, v57, v40 offset0:140 offset1:206
	ds_write2_b32 v32, v58, v59 offset0:16 offset1:82
	s_waitcnt vmcnt(14)
	ds_write2_b32 v32, v60, v41 offset0:148 offset1:214
	v_add_u32_e32 v4, 0xc00, v3
	ds_write2_b32 v4, v61, v62 offset0:24 offset1:90
	s_waitcnt vmcnt(13)
	ds_write2_b32 v4, v63, v46 offset0:156 offset1:222
	v_add_u32_e32 v4, 0x1000, v3
	ds_write2_b32 v4, v64, v48 offset0:32 offset1:98
	s_waitcnt vmcnt(12)
	ds_write2_b32 v4, v49, v47 offset0:164 offset1:230
	v_add_u32_e32 v4, 0x1400, v3
	s_waitcnt vmcnt(8)
	ds_write2_b32 v4, v37, v43 offset0:40 offset1:106
	s_waitcnt vmcnt(7)
	ds_write2_b32 v4, v50, v42 offset0:172 offset1:238
	v_add_u32_e32 v4, 0x1800, v3
	s_waitcnt vmcnt(5)
; #define LAS __attribute__((address_space(3)))
; #define LDS_WAIT() asm volatile("s_waitcnt lgkmcnt(0)" ::: "memory")
; __device__ __forceinline__ unsigned pk2(float lo, float hi) { return f2bf(lo) | (f2bf(hi) << 16); }
;     ...
;     for (int i = 0; i < 32; ++i) scr[(2 * i + (lane >> 5)) * 33 + (lane & 31)] = tv_[i];
;     LDS_WAIT(); asm volatile("" ::: "memory");
;     const int c = lane & 7;
; #pragma unroll
;     for (int j = 0; j < 4; ++j) { const int n = (lane >> 3) + 8 * j; const LAS float* s = scr + (8 * c) * 33 + n;
;         v4u o; o.x = pk2(s[0 * 33], s[1 * 33]); o.y = pk2(s[2 * 33], s[3 * 33]); o.z = pk2(s[4 * 33], s[5 * 33]); o.w = pk2(s[6 * 33], s[7 * 33]);
;         *(v4u*)(WT + (size_t)(n0 + n) * ldw + koff + k0 + 8 * c) = o; }
;     LDS_WAIT(); asm volatile("" ::: "memory");
	ds_write2_b32 v4, v51, v44 offset0:48 offset1:114
	s_waitcnt vmcnt(4)
	ds_write2_b32 v4, v45, v36 offset0:180 offset1:246
	v_add_u32_e32 v4, 0x1c00, v3
	s_waitcnt vmcnt(2)
	ds_write2_b32 v4, v52, v38 offset0:56 offset1:122
	s_waitcnt vmcnt(0)
	ds_write2_b32 v4, v39, v53 offset0:188 offset1:254
	s_waitcnt lgkmcnt(0)
	v_lshlrev_b32_e32 v4, 1, v33
	v_lshl_add_u64 v[20:21], v[20:21], 0, v[4:5]
	v_lshlrev_b32_e32 v4, 1, v6
	v_lshl_add_u64 v[20:21], v[20:21], 0, v[4:5]
	ds_read_b32 v4, v23
	ds_read_b32 v33, v23 offset:132
	ds_read_b32 v35, v23 offset:264
	ds_read_b32 v36, v23 offset:396
	ds_read_b32 v37, v23 offset:528
	ds_read_b32 v38, v23 offset:660
	ds_read_b32 v39, v23 offset:792
	ds_read_b32 v40, v23 offset:924
	s_waitcnt lgkmcnt(0)
	v_bfe_u32 v34, v4, 16, 1
	v_add3_u32 v4, v4, v34, s41
	v_bfe_u32 v34, v33, 16, 1
	v_lshrrev_b32_e32 v4, 16, v4
	v_add3_u32 v33, v33, v34, s41
	v_and_or_b32 v34, v33, s42, v4
	v_bfe_u32 v4, v35, 16, 1
	v_add3_u32 v4, v35, v4, s41
	v_bfe_u32 v33, v36, 16, 1
	v_lshrrev_b32_e32 v4, 16, v4
	v_add3_u32 v33, v36, v33, s41
	v_and_or_b32 v35, v33, s42, v4
	v_bfe_u32 v4, v37, 16, 1
	v_add3_u32 v4, v37, v4, s41
	v_bfe_u32 v33, v38, 16, 1
	v_lshrrev_b32_e32 v4, 16, v4
	v_add3_u32 v33, v38, v33, s41
	v_and_or_b32 v36, v33, s42, v4
	v_bfe_u32 v4, v39, 16, 1
	v_add3_u32 v4, v39, v4, s41
	v_bfe_u32 v33, v40, 16, 1
	v_lshrrev_b32_e32 v4, 16, v4
	v_add3_u32 v33, v40, v33, s41
	v_and_or_b32 v37, v33, s42, v4
	v_or_b32_e32 v4, v54, v7
	v_lshlrev_b32_e32 v4, 9, v4
	v_lshl_add_u64 v[38:39], v[20:21], 0, v[4:5]
	global_store_dwordx4 v[38:39], v[34:37], off
	ds_read_b32 v4, v23 offset:32
	ds_read_b32 v33, v23 offset:164
	ds_read_b32 v35, v23 offset:296
	ds_read_b32 v36, v23 offset:428
	ds_read_b32 v37, v23 offset:560
	ds_read_b32 v38, v23 offset:692
	ds_read_b32 v39, v23 offset:824
	ds_read_b32 v40, v23 offset:956
	s_waitcnt lgkmcnt(0)
	v_bfe_u32 v34, v4, 16, 1
	v_add3_u32 v4, v4, v34, s41
	v_bfe_u32 v34, v33, 16, 1
	v_lshrrev_b32_e32 v4, 16, v4
	v_add3_u32 v33, v33, v34, s41
	v_and_or_b32 v34, v33, s42, v4
	v_bfe_u32 v4, v35, 16, 1
	v_add3_u32 v4, v35, v4, s41
	v_bfe_u32 v33, v36, 16, 1
	v_lshrrev_b32_e32 v4, 16, v4
	v_add3_u32 v33, v36, v33, s41
	v_and_or_b32 v35, v33, s42, v4
	v_bfe_u32 v4, v37, 16, 1
	v_add3_u32 v4, v37, v4, s41
	v_bfe_u32 v33, v38, 16, 1
	v_lshrrev_b32_e32 v4, 16, v4
	v_add3_u32 v33, v38, v33, s41
	v_and_or_b32 v36, v33, s42, v4
	v_bfe_u32 v4, v39, 16, 1
	v_add3_u32 v4, v39, v4, s41
	v_bfe_u32 v33, v40, 16, 1
	v_lshrrev_b32_e32 v4, 16, v4
	v_add3_u32 v33, v40, v33, s41
	v_and_or_b32 v37, v33, s42, v4
	v_or_b32_e32 v4, v54, v24
	v_lshlrev_b32_e32 v4, 9, v4
	v_lshl_add_u64 v[38:39], v[20:21], 0, v[4:5]
	global_store_dwordx4 v[38:39], v[34:37], off
	ds_read_b32 v4, v23 offset:64
	ds_read_b32 v33, v23 offset:196
	ds_read_b32 v35, v23 offset:328
	ds_read_b32 v36, v23 offset:460
	ds_read_b32 v37, v23 offset:592
	ds_read_b32 v38, v23 offset:724
	ds_read_b32 v39, v23 offset:856
	ds_read_b32 v40, v23 offset:988
	s_waitcnt lgkmcnt(0)
	v_bfe_u32 v34, v4, 16, 1
	v_add3_u32 v4, v4, v34, s41
	v_bfe_u32 v34, v33, 16, 1
	v_lshrrev_b32_e32 v4, 16, v4
	v_add3_u32 v33, v33, v34, s41
	v_and_or_b32 v34, v33, s42, v4
	v_bfe_u32 v4, v35, 16, 1
	v_add3_u32 v4, v35, v4, s41
	v_bfe_u32 v33, v36, 16, 1
	v_lshrrev_b32_e32 v4, 16, v4
	v_add3_u32 v33, v36, v33, s41
	v_and_or_b32 v35, v33, s42, v4
	v_bfe_u32 v4, v37, 16, 1
	v_add3_u32 v4, v37, v4, s41
	v_bfe_u32 v33, v38, 16, 1
	v_lshrrev_b32_e32 v4, 16, v4
	v_add3_u32 v33, v38, v33, s41
	v_and_or_b32 v36, v33, s42, v4
	v_bfe_u32 v4, v39, 16, 1
	v_add3_u32 v4, v39, v4, s41
	v_bfe_u32 v33, v40, 16, 1
	v_lshrrev_b32_e32 v4, 16, v4
	v_add3_u32 v33, v40, v33, s41
	v_and_or_b32 v37, v33, s42, v4
	v_or_b32_e32 v4, v54, v25
	v_lshlrev_b32_e32 v4, 9, v4
	v_lshl_add_u64 v[38:39], v[20:21], 0, v[4:5]
	global_store_dwordx4 v[38:39], v[34:37], off
	ds_read_b32 v4, v23 offset:96
	ds_read_b32 v33, v23 offset:228
	ds_read_b32 v35, v23 offset:360
	ds_read_b32 v36, v23 offset:492
	ds_read_b32 v37, v23 offset:624
	ds_read_b32 v38, v23 offset:756
	ds_read_b32 v39, v23 offset:888
	ds_read_b32 v40, v23 offset:1020
	s_waitcnt lgkmcnt(0)
	v_bfe_u32 v34, v4, 16, 1
	v_add3_u32 v4, v4, v34, s41
	v_bfe_u32 v34, v33, 16, 1
	v_lshrrev_b32_e32 v4, 16, v4
	v_add3_u32 v33, v33, v34, s41
	v_and_or_b32 v34, v33, s42, v4
	v_bfe_u32 v4, v35, 16, 1
	v_add3_u32 v4, v35, v4, s41
	v_bfe_u32 v33, v36, 16, 1
	v_lshrrev_b32_e32 v4, 16, v4
	v_add3_u32 v33, v36, v33, s41
	v_and_or_b32 v35, v33, s42, v4
	v_bfe_u32 v4, v37, 16, 1
	v_add3_u32 v4, v37, v4, s41
	v_bfe_u32 v33, v38, 16, 1
	v_lshrrev_b32_e32 v4, 16, v4
	v_add3_u32 v33, v38, v33, s41
	v_and_or_b32 v36, v33, s42, v4
	v_bfe_u32 v4, v39, 16, 1
	v_add3_u32 v4, v39, v4, s41
	v_bfe_u32 v33, v40, 16, 1
	v_lshrrev_b32_e32 v4, 16, v4
	v_add3_u32 v33, v40, v33, s41
	v_and_or_b32 v37, v33, s42, v4
	v_or_b32_e32 v4, v54, v26
	v_lshlrev_b32_e32 v4, 9, v4
	v_lshl_add_u64 v[20:21], v[20:21], 0, v[4:5]
	global_store_dwordx4 v[20:21], v[34:37], off
	s_waitcnt lgkmcnt(0)
	v_readlane_b32 s72, v251, 33
	v_readlane_b32 s73, v251, 34

;     ...
;     const int nblk = N / 32, kb = item / nblk, nb = item % nblk, k0 = 64 * kb, n0 = 32 * nb;
;     float tv_[32];
; #pragma unroll
;     for (int i = 0; i < 32; ++i) tv_[i] = W[(size_t)(k0 + 2 * i + (lane >> 5)) * N + n0 + (lane & 31)];
; #pragma unroll
;     for (int i = 0; i < 32; ++i) scr[(2 * i + (lane >> 5)) * 33 + (lane & 31)] = tv_[i];
; __device__ __forceinline__ void convert_range(LAS unsigned char* lds, const Params& p, const int lo, const int hi, const int gw, const int NGW) {
;     ...
;         if (r < 2 * I_OUT) { const int l = r / I_OUT; r -= l * I_OUT; p0_transpose_item(p.in[18] + (size_t)l * DM * DM, DM, DM, (bf16*)(ws + WS_WOUT + l * SZ_WOUT), scr, r, lane); continue; } r -= 2 * I_OUT;
.LBB0_35:
	s_andn2_saveexec_b64 s[30:31], s[30:31]
	s_cbranch_execz .LBB0_37
	v_add_u32_e32 v4, 0x1200, v27
	v_lshrrev_b32_e32 v4, 11, v4
	v_readlane_b32 s68, v251, 9
	v_lshlrev_b64 v[34:35], 24, v[4:5]
	v_readlane_b32 s72, v251, 13
	v_readlane_b32 s73, v251, 14
	v_and_b32_e32 v52, 0x7e0, v30
	v_lshlrev_b64 v[36:37], 23, v[4:5]
	v_lshl_add_u64 v[34:35], s[72:73], 0, v[34:35]
	v_and_b32_e32 v33, 0x7c0, v20
	v_lshlrev_b32_e32 v4, 2, v52
	v_or_b32_e32 v38, v33, v1
	v_lshl_add_u64 v[20:21], v[34:35], 0, v[4:5]
	v_lshlrev_b32_e32 v4, 2, v2
	v_lshl_add_u64 v[20:21], v[20:21], 0, v[4:5]
	v_lshlrev_b32_e32 v4, 13, v38
	v_lshl_add_u64 v[20:21], v[20:21], 0, v[4:5]
	v_add_co_u32_e32 v34, vcc, s40, v20
	v_readlane_b32 s69, v251, 10
	s_nop 0
	v_addc_co_u32_e32 v35, vcc, 0, v21, vcc
	v_add_co_u32_e32 v38, vcc, s43, v20
	v_readlane_b32 s70, v251, 11
	s_nop 0
	v_addc_co_u32_e32 v39, vcc, 0, v21, vcc
	v_add_co_u32_e32 v40, vcc, s45, v20
	v_readlane_b32 s71, v251, 12
	s_nop 0
	v_addc_co_u32_e32 v41, vcc, 0, v21, vcc
	v_add_co_u32_e32 v42, vcc, s47, v20
	v_readlane_b32 s74, v251, 15
	s_nop 0
	v_addc_co_u32_e32 v43, vcc, 0, v21, vcc
	v_add_co_u32_e32 v44, vcc, s48, v20
	v_readlane_b32 s75, v251, 16
	s_nop 0
	v_addc_co_u32_e32 v45, vcc, 0, v21, vcc
	v_add_co_u32_e32 v46, vcc, s49, v20
	s_nop 1
	v_addc_co_u32_e32 v47, vcc, 0, v21, vcc
	v_add_co_u32_e32 v48, vcc, s50, v20
	s_nop 1
	v_addc_co_u32_e32 v49, vcc, 0, v21, vcc
	global_load_dword v4, v[20:21], off
	global_load_dword v53, v[34:35], off
	global_load_dword v54, v[38:39], off
	global_load_dword v55, v[40:41], off
	global_load_dword v56, v[42:43], off
	global_load_dword v57, v[44:45], off
	global_load_dword v58, v[46:47], off
	global_load_dword v59, v[48:49], off
	v_add_co_u32_e32 v34, vcc, s51, v20
	s_nop 1
	v_addc_co_u32_e32 v35, vcc, 0, v21, vcc
	v_add_co_u32_e32 v38, vcc, s52, v20
	s_nop 1
	v_addc_co_u32_e32 v39, vcc, 0, v21, vcc
	v_add_co_u32_e32 v40, vcc, s53, v20
	s_nop 1
	v_addc_co_u32_e32 v41, vcc, 0, v21, vcc
	v_add_co_u32_e32 v42, vcc, s54, v20
	s_nop 1
	v_addc_co_u32_e32 v43, vcc, 0, v21, vcc
	v_add_co_u32_e32 v44, vcc, s55, v20
	s_nop 1
	v_addc_co_u32_e32 v45, vcc, 0, v21, vcc
	v_add_co_u32_e32 v46, vcc, s56, v20
	s_nop 1
	v_addc_co_u32_e32 v47, vcc, 0, v21, vcc
	v_add_co_u32_e32 v48, vcc, s57, v20
	s_nop 1
	v_addc_co_u32_e32 v49, vcc, 0, v21, vcc
	v_add_co_u32_e32 v50, vcc, s58, v20
	s_nop 1
	v_addc_co_u32_e32 v51, vcc, 0, v21, vcc
	global_load_dword v60, v[34:35], off
	global_load_dword v61, v[38:39], off
	global_load_dword v62, v[40:41], off
	global_load_dword v63, v[42:43], off
	global_load_dword v64, v[44:45], off
	global_load_dword v65, v[46:47], off
	global_load_dword v66, v[48:49], off
	global_load_dword v67, v[50:51], off
	v_add_co_u32_e32 v34, vcc, s59, v20
	s_nop 1
	v_addc_co_u32_e32 v35, vcc, 0, v21, vcc
	v_add_co_u32_e32 v38, vcc, s76, v20
	s_nop 1
	v_addc_co_u32_e32 v39, vcc, 0, v21, vcc
	v_add_co_u32_e32 v40, vcc, s77, v20
	s_nop 1
	v_addc_co_u32_e32 v41, vcc, 0, v21, vcc
	v_add_co_u32_e32 v42, vcc, s78, v20
	s_nop 1
	v_addc_co_u32_e32 v43, vcc, 0, v21, vcc
	v_add_co_u32_e32 v44, vcc, s79, v20
	s_nop 1
	v_addc_co_u32_e32 v45, vcc, 0, v21, vcc
	v_add_co_u32_e32 v46, vcc, s80, v20
	s_nop 1
	v_addc_co_u32_e32 v47, vcc, 0, v21, vcc
	v_add_co_u32_e32 v48, vcc, s81, v20
	s_nop 1
	v_addc_co_u32_e32 v49, vcc, 0, v21, vcc
	v_add_co_u32_e32 v50, vcc, s82, v20
	s_nop 1
	v_addc_co_u32_e32 v51, vcc, 0, v21, vcc
	global_load_dword v68, v[34:35], off
	global_load_dword v69, v[38:39], off
	global_load_dword v70, v[40:41], off
	global_load_dword v71, v[42:43], off
	global_load_dword v72, v[44:45], off
	global_load_dword v73, v[46:47], off
	global_load_dword v74, v[48:49], off
	s_nop 0
	global_load_dword v50, v[50:51], off
	v_add_co_u32_e32 v34, vcc, s83, v20
	s_nop 1
	v_addc_co_u32_e32 v35, vcc, 0, v21, vcc
	v_add_co_u32_e32 v38, vcc, s84, v20
	s_nop 1
	v_addc_co_u32_e32 v39, vcc, 0, v21, vcc
	v_add_co_u32_e32 v40, vcc, s85, v20
	s_nop 1
	v_addc_co_u32_e32 v41, vcc, 0, v21, vcc
	v_add_co_u32_e32 v42, vcc, s86, v20
	s_nop 1
	v_addc_co_u32_e32 v43, vcc, 0, v21, vcc
	v_add_co_u32_e32 v44, vcc, s87, v20
	s_nop 1
	v_addc_co_u32_e32 v45, vcc, 0, v21, vcc
	v_add_co_u32_e32 v46, vcc, s88, v20
	s_nop 1
	v_addc_co_u32_e32 v47, vcc, 0, v21, vcc
	v_add_co_u32_e32 v48, vcc, s89, v20
	s_nop 1
	v_addc_co_u32_e32 v49, vcc, 0, v21, vcc
	v_add_co_u32_e32 v20, vcc, s90, v20
	s_nop 1
	v_addc_co_u32_e32 v21, vcc, 0, v21, vcc
	global_load_dword v34, v[34:35], off
	s_nop 0
	global_load_dword v35, v[38:39], off
	s_nop 0
	global_load_dword v38, v[40:41], off
	global_load_dword v39, v[42:43], off
	s_nop 0
	global_load_dword v40, v[44:45], off
	global_load_dword v41, v[46:47], off
	global_load_dword v42, v[48:49], off
	global_load_dword v43, v[20:21], off
	s_waitcnt vmcnt(30)
	ds_write2_b32 v3, v4, v53 offset1:66
	s_waitcnt vmcnt(28)
	ds_write2_b32 v3, v54, v55 offset0:132 offset1:198
	s_waitcnt vmcnt(26)
	ds_write2_b32 v31, v56, v57 offset0:8 offset1:74
	s_waitcnt vmcnt(24)
	ds_write2_b32 v31, v58, v59 offset0:140 offset1:206
	s_waitcnt vmcnt(22)
	ds_write2_b32 v32, v60, v61 offset0:16 offset1:82
	s_waitcnt vmcnt(20)
	ds_write2_b32 v32, v62, v63 offset0:148 offset1:214
	v_add_u32_e32 v4, 0xc00, v3
	s_waitcnt vmcnt(18)
	ds_write2_b32 v4, v64, v65 offset0:24 offset1:90
	s_waitcnt vmcnt(16)
	ds_write2_b32 v4, v66, v67 offset0:156 offset1:222
	v_add_u32_e32 v4, 0x1000, v3
	s_waitcnt vmcnt(14)
; #define LAS __attribute__((address_space(3)))
; #define LDS_WAIT() asm volatile("s_waitcnt lgkmcnt(0)" ::: "memory")
; __device__ __forceinline__ unsigned pk2(float lo, float hi) { return f2bf(lo) | (f2bf(hi) << 16); }
;     ...
;     for (int i = 0; i < 32; ++i) scr[(2 * i + (lane >> 5)) * 33 + (lane & 31)] = tv_[i];
;     LDS_WAIT(); asm volatile("" ::: "memory");
;     const int c = lane & 7;
; #pragma unroll
;     for (int j = 0; j < 4; ++j) { const int n = (lane >> 3) + 8 * j; const LAS float* s = scr + (8 * c) * 33 + n;
;         v4u o; o.x = pk2(s[0 * 33], s[1 * 33]); o.y = pk2(s[2 * 33], s[3 * 33]); o.z = pk2(s[4 * 33], s[5 * 33]); o.w = pk2(s[6 * 33], s[7 * 33]);
;         *(v4u*)(WT + (size_t)(n0 + n) * ldw + koff + k0 + 8 * c) = o; }
;     LDS_WAIT(); asm volatile("" ::: "memory");
	ds_write2_b32 v4, v68, v69 offset0:32 offset1:98
	s_waitcnt vmcnt(12)
	ds_write2_b32 v4, v70, v71 offset0:164 offset1:230
	v_add_u32_e32 v4, 0x1400, v3
	s_waitcnt vmcnt(10)
	ds_write2_b32 v4, v72, v73 offset0:40 offset1:106
	s_waitcnt vmcnt(8)
	ds_write2_b32 v4, v74, v50 offset0:172 offset1:238
	v_add_u32_e32 v4, 0x1800, v3
	s_waitcnt vmcnt(6)
	ds_write2_b32 v4, v34, v35 offset0:48 offset1:114
	s_waitcnt vmcnt(4)
	ds_write2_b32 v4, v38, v39 offset0:180 offset1:246
	v_add_u32_e32 v4, 0x1c00, v3
	s_waitcnt vmcnt(2)
	ds_write2_b32 v4, v40, v41 offset0:56 offset1:122
	s_waitcnt vmcnt(0)
	ds_write2_b32 v4, v42, v43 offset0:188 offset1:254
	v_lshl_add_u64 v[20:21], s[18:19], 0, v[36:37]
	s_waitcnt lgkmcnt(0)
	v_lshlrev_b32_e32 v4, 1, v33
	v_lshl_add_u64 v[20:21], v[20:21], 0, v[4:5]
	v_lshlrev_b32_e32 v4, 1, v6
	v_lshl_add_u64 v[20:21], v[20:21], 0, v[4:5]
	ds_read_b32 v4, v23
	ds_read_b32 v33, v23 offset:132
	ds_read_b32 v35, v23 offset:264
	ds_read_b32 v36, v23 offset:396
	ds_read_b32 v37, v23 offset:528
	ds_read_b32 v38, v23 offset:660
	ds_read_b32 v39, v23 offset:792
	ds_read_b32 v40, v23 offset:924
	s_waitcnt lgkmcnt(0)
	v_bfe_u32 v34, v4, 16, 1
	v_add3_u32 v4, v4, v34, s41
	v_bfe_u32 v34, v33, 16, 1
	v_lshrrev_b32_e32 v4, 16, v4
	v_add3_u32 v33, v33, v34, s41
	v_and_or_b32 v34, v33, s42, v4
	v_bfe_u32 v4, v35, 16, 1
	v_add3_u32 v4, v35, v4, s41
	v_bfe_u32 v33, v36, 16, 1
	v_lshrrev_b32_e32 v4, 16, v4
	v_add3_u32 v33, v36, v33, s41
	v_and_or_b32 v35, v33, s42, v4
	v_bfe_u32 v4, v37, 16, 1
	v_add3_u32 v4, v37, v4, s41
	v_bfe_u32 v33, v38, 16, 1
	v_lshrrev_b32_e32 v4, 16, v4
	v_add3_u32 v33, v38, v33, s41
	v_and_or_b32 v36, v33, s42, v4
	v_bfe_u32 v4, v39, 16, 1
	v_add3_u32 v4, v39, v4, s41
	v_bfe_u32 v33, v40, 16, 1
	v_lshrrev_b32_e32 v4, 16, v4
	v_add3_u32 v33, v40, v33, s41
	v_and_or_b32 v37, v33, s42, v4
	v_or_b32_e32 v4, v52, v7
	v_lshlrev_b32_e32 v4, 12, v4
	v_lshl_add_u64 v[38:39], v[20:21], 0, v[4:5]
	global_store_dwordx4 v[38:39], v[34:37], off
	ds_read_b32 v4, v23 offset:32
	ds_read_b32 v33, v23 offset:164
	ds_read_b32 v35, v23 offset:296
	ds_read_b32 v36, v23 offset:428
	ds_read_b32 v37, v23 offset:560
	ds_read_b32 v38, v23 offset:692
	ds_read_b32 v39, v23 offset:824
	ds_read_b32 v40, v23 offset:956
	s_waitcnt lgkmcnt(0)
	v_bfe_u32 v34, v4, 16, 1
	v_add3_u32 v4, v4, v34, s41
	v_bfe_u32 v34, v33, 16, 1
	v_lshrrev_b32_e32 v4, 16, v4
	v_add3_u32 v33, v33, v34, s41
	v_and_or_b32 v34, v33, s42, v4
	v_bfe_u32 v4, v35, 16, 1
	v_add3_u32 v4, v35, v4, s41
	v_bfe_u32 v33, v36, 16, 1
	v_lshrrev_b32_e32 v4, 16, v4
	v_add3_u32 v33, v36, v33, s41
	v_and_or_b32 v35, v33, s42, v4
	v_bfe_u32 v4, v37, 16, 1
	v_add3_u32 v4, v37, v4, s41
	v_bfe_u32 v33, v38, 16, 1
	v_lshrrev_b32_e32 v4, 16, v4
	v_add3_u32 v33, v38, v33, s41
	v_and_or_b32 v36, v33, s42, v4
	v_bfe_u32 v4, v39, 16, 1
	v_add3_u32 v4, v39, v4, s41
	v_bfe_u32 v33, v40, 16, 1
	v_lshrrev_b32_e32 v4, 16, v4
	v_add3_u32 v33, v40, v33, s41
	v_and_or_b32 v37, v33, s42, v4
	v_or_b32_e32 v4, v52, v24
	v_lshlrev_b32_e32 v4, 12, v4
	v_lshl_add_u64 v[38:39], v[20:21], 0, v[4:5]
	global_store_dwordx4 v[38:39], v[34:37], off
	ds_read_b32 v4, v23 offset:64
	ds_read_b32 v33, v23 offset:196
	ds_read_b32 v35, v23 offset:328
	ds_read_b32 v36, v23 offset:460
	ds_read_b32 v37, v23 offset:592
	ds_read_b32 v38, v23 offset:724
	ds_read_b32 v39, v23 offset:856
	ds_read_b32 v40, v23 offset:988
	s_waitcnt lgkmcnt(0)
	v_bfe_u32 v34, v4, 16, 1
	v_add3_u32 v4, v4, v34, s41
	v_bfe_u32 v34, v33, 16, 1
	v_lshrrev_b32_e32 v4, 16, v4
	v_add3_u32 v33, v33, v34, s41
	v_and_or_b32 v34, v33, s42, v4
	v_bfe_u32 v4, v35, 16, 1
	v_add3_u32 v4, v35, v4, s41
	v_bfe_u32 v33, v36, 16, 1
	v_lshrrev_b32_e32 v4, 16, v4
	v_add3_u32 v33, v36, v33, s41
	v_and_or_b32 v35, v33, s42, v4
	v_bfe_u32 v4, v37, 16, 1
	v_add3_u32 v4, v37, v4, s41
	v_bfe_u32 v33, v38, 16, 1
	v_lshrrev_b32_e32 v4, 16, v4
	v_add3_u32 v33, v38, v33, s41
	v_and_or_b32 v36, v33, s42, v4
	v_bfe_u32 v4, v39, 16, 1
	v_add3_u32 v4, v39, v4, s41
	v_bfe_u32 v33, v40, 16, 1
	v_lshrrev_b32_e32 v4, 16, v4
	v_add3_u32 v33, v40, v33, s41
	v_and_or_b32 v37, v33, s42, v4
	v_or_b32_e32 v4, v52, v25
	v_lshlrev_b32_e32 v4, 12, v4
	v_lshl_add_u64 v[38:39], v[20:21], 0, v[4:5]
	global_store_dwordx4 v[38:39], v[34:37], off
	ds_read_b32 v4, v23 offset:96
	ds_read_b32 v33, v23 offset:228
	ds_read_b32 v35, v23 offset:360
	ds_read_b32 v36, v23 offset:492
	ds_read_b32 v37, v23 offset:624
	ds_read_b32 v38, v23 offset:756
	ds_read_b32 v39, v23 offset:888
	ds_read_b32 v40, v23 offset:1020
	s_waitcnt lgkmcnt(0)
	v_bfe_u32 v34, v4, 16, 1
	v_add3_u32 v4, v4, v34, s41
	v_bfe_u32 v34, v33, 16, 1
	v_lshrrev_b32_e32 v4, 16, v4
	v_add3_u32 v33, v33, v34, s41
	v_and_or_b32 v34, v33, s42, v4
	v_bfe_u32 v4, v35, 16, 1
	v_add3_u32 v4, v35, v4, s41
	v_bfe_u32 v33, v36, 16, 1
	v_lshrrev_b32_e32 v4, 16, v4
	v_add3_u32 v33, v36, v33, s41
	v_and_or_b32 v35, v33, s42, v4
	v_bfe_u32 v4, v37, 16, 1
	v_add3_u32 v4, v37, v4, s41
	v_bfe_u32 v33, v38, 16, 1
	v_lshrrev_b32_e32 v4, 16, v4
	v_add3_u32 v33, v38, v33, s41
	v_and_or_b32 v36, v33, s42, v4
	v_bfe_u32 v4, v39, 16, 1
	v_add3_u32 v4, v39, v4, s41
	v_bfe_u32 v33, v40, 16, 1
	v_lshrrev_b32_e32 v4, 16, v4
	v_add3_u32 v33, v40, v33, s41
	v_and_or_b32 v37, v33, s42, v4
	v_or_b32_e32 v4, v52, v26
	v_lshlrev_b32_e32 v4, 12, v4
	v_lshl_add_u64 v[20:21], v[20:21], 0, v[4:5]
	global_store_dwordx4 v[20:21], v[34:37], off
	s_waitcnt lgkmcnt(0)

;     ...
;     const int nblk = N / 32, kb = item / nblk, nb = item % nblk, k0 = 64 * kb, n0 = 32 * nb;
;     float tv_[32];
; #pragma unroll
;     for (int i = 0; i < 32; ++i) tv_[i] = W[(size_t)(k0 + 2 * i + (lane >> 5)) * N + n0 + (lane & 31)];
; #pragma unroll
;     for (int i = 0; i < 32; ++i) scr[(2 * i + (lane >> 5)) * 33 + (lane & 31)] = tv_[i];
; __device__ __forceinline__ void convert_range(LAS unsigned char* lds, const Params& p, const int lo, const int hi, const int gw, const int NGW) {
;     ...
;         if (r < 2 * I_PB) { const int l = r / I_PB; r -= l * I_PB; p0_transpose_item(p.in[17] + (size_t)l * LW * DM, LW, DM, (bf16*)(ws + WS_WCAT + l * SZ_WCAT), scr, r, lane, KCAT, PW); continue; } r -= 2 * I_PB;
.LBB0_38:
	s_andn2_saveexec_b64 s[28:29], s[28:29]
	s_cbranch_execz .LBB0_40
	v_add_u32_e32 v4, 0x2200, v27
	v_lshrrev_b32_e32 v4, 11, v4
	v_readlane_b32 s68, v251, 9
	v_lshlrev_b64 v[34:35], 24, v[4:5]
	v_readlane_b32 s70, v251, 11
	v_readlane_b32 s71, v251, 12
	v_mov_b64_e32 v[36:37], s[8:9]
	v_and_b32_e32 v52, 0x7e0, v30
	v_lshl_add_u64 v[34:35], s[70:71], 0, v[34:35]
	v_mad_u64_u32 v[36:37], s[30:31], v4, s91, v[36:37]
	v_and_b32_e32 v33, 0x7c0, v20
	v_lshlrev_b32_e32 v4, 2, v52
	v_or_b32_e32 v38, v33, v1
	v_lshl_add_u64 v[20:21], v[34:35], 0, v[4:5]
	v_lshlrev_b32_e32 v4, 2, v2
	v_lshl_add_u64 v[20:21], v[20:21], 0, v[4:5]
	v_lshlrev_b32_e32 v4, 13, v38
	v_lshl_add_u64 v[20:21], v[20:21], 0, v[4:5]
	v_add_co_u32_e32 v34, vcc, s40, v20
	s_mov_b64 s[30:31], 0x5000800
	s_nop 0
	v_addc_co_u32_e32 v35, vcc, 0, v21, vcc
	v_add_co_u32_e32 v38, vcc, s43, v20
	v_readlane_b32 s69, v251, 10
	s_nop 0
	v_addc_co_u32_e32 v39, vcc, 0, v21, vcc
	v_add_co_u32_e32 v40, vcc, s45, v20
	v_readlane_b32 s72, v251, 13
	s_nop 0
	v_addc_co_u32_e32 v41, vcc, 0, v21, vcc
	v_add_co_u32_e32 v42, vcc, s47, v20
	v_readlane_b32 s73, v251, 14
	s_nop 0
	v_addc_co_u32_e32 v43, vcc, 0, v21, vcc
	v_add_co_u32_e32 v44, vcc, s48, v20
	v_readlane_b32 s74, v251, 15
	s_nop 0
	v_addc_co_u32_e32 v45, vcc, 0, v21, vcc
	v_add_co_u32_e32 v46, vcc, s49, v20
	v_readlane_b32 s75, v251, 16
	s_nop 0
	v_addc_co_u32_e32 v47, vcc, 0, v21, vcc
	v_add_co_u32_e32 v48, vcc, s50, v20
	s_nop 1
	v_addc_co_u32_e32 v49, vcc, 0, v21, vcc
	global_load_dword v4, v[20:21], off
	global_load_dword v53, v[34:35], off
	global_load_dword v54, v[38:39], off
	global_load_dword v55, v[40:41], off
	global_load_dword v56, v[42:43], off
	global_load_dword v57, v[44:45], off
	global_load_dword v58, v[46:47], off
	global_load_dword v59, v[48:49], off
	v_add_co_u32_e32 v34, vcc, s51, v20
	s_nop 1
	v_addc_co_u32_e32 v35, vcc, 0, v21, vcc
	v_add_co_u32_e32 v38, vcc, s52, v20
	s_nop 1
	v_addc_co_u32_e32 v39, vcc, 0, v21, vcc
	v_add_co_u32_e32 v40, vcc, s53, v20
	s_nop 1
	v_addc_co_u32_e32 v41, vcc, 0, v21, vcc
	v_add_co_u32_e32 v42, vcc, s54, v20
	s_nop 1
	v_addc_co_u32_e32 v43, vcc, 0, v21, vcc
	v_add_co_u32_e32 v44, vcc, s55, v20
	s_nop 1
	v_addc_co_u32_e32 v45, vcc, 0, v21, vcc
	v_add_co_u32_e32 v46, vcc, s56, v20
	s_nop 1
	v_addc_co_u32_e32 v47, vcc, 0, v21, vcc
	v_add_co_u32_e32 v48, vcc, s57, v20
	s_nop 1
	v_addc_co_u32_e32 v49, vcc, 0, v21, vcc
	v_add_co_u32_e32 v50, vcc, s58, v20
	s_nop 1
	v_addc_co_u32_e32 v51, vcc, 0, v21, vcc
	global_load_dword v60, v[34:35], off
	global_load_dword v61, v[38:39], off
	global_load_dword v62, v[40:41], off
	global_load_dword v63, v[42:43], off
	global_load_dword v64, v[44:45], off
	global_load_dword v65, v[46:47], off
	global_load_dword v66, v[48:49], off
	global_load_dword v67, v[50:51], off
	v_add_co_u32_e32 v34, vcc, s59, v20
	s_nop 1
	v_addc_co_u32_e32 v35, vcc, 0, v21, vcc
	v_add_co_u32_e32 v38, vcc, s76, v20
	s_nop 1
	v_addc_co_u32_e32 v39, vcc, 0, v21, vcc
	v_add_co_u32_e32 v40, vcc, s77, v20
	s_nop 1
	v_addc_co_u32_e32 v41, vcc, 0, v21, vcc
	v_add_co_u32_e32 v42, vcc, s78, v20
	s_nop 1
	v_addc_co_u32_e32 v43, vcc, 0, v21, vcc
	v_add_co_u32_e32 v44, vcc, s79, v20
	s_nop 1
	v_addc_co_u32_e32 v45, vcc, 0, v21, vcc
	v_add_co_u32_e32 v46, vcc, s80, v20
	s_nop 1
	v_addc_co_u32_e32 v47, vcc, 0, v21, vcc
	v_add_co_u32_e32 v48, vcc, s81, v20
	s_nop 1
	v_addc_co_u32_e32 v49, vcc, 0, v21, vcc
	v_add_co_u32_e32 v50, vcc, s82, v20
	s_nop 1
	v_addc_co_u32_e32 v51, vcc, 0, v21, vcc
	global_load_dword v68, v[34:35], off
	global_load_dword v69, v[38:39], off
	global_load_dword v70, v[40:41], off
	global_load_dword v71, v[42:43], off
	global_load_dword v72, v[44:45], off
	global_load_dword v73, v[46:47], off
	global_load_dword v74, v[48:49], off
	s_nop 0
	global_load_dword v50, v[50:51], off
	v_add_co_u32_e32 v34, vcc, s83, v20
	s_nop 1
	v_addc_co_u32_e32 v35, vcc, 0, v21, vcc
	v_add_co_u32_e32 v38, vcc, s84, v20
	s_nop 1
	v_addc_co_u32_e32 v39, vcc, 0, v21, vcc
	v_add_co_u32_e32 v40, vcc, s85, v20
	s_nop 1
	v_addc_co_u32_e32 v41, vcc, 0, v21, vcc
	v_add_co_u32_e32 v42, vcc, s86, v20
	s_nop 1
	v_addc_co_u32_e32 v43, vcc, 0, v21, vcc
	v_add_co_u32_e32 v44, vcc, s87, v20
	s_nop 1
	v_addc_co_u32_e32 v45, vcc, 0, v21, vcc
	v_add_co_u32_e32 v46, vcc, s88, v20
	s_nop 1
	v_addc_co_u32_e32 v47, vcc, 0, v21, vcc
	v_add_co_u32_e32 v48, vcc, s89, v20
	s_nop 1
	v_addc_co_u32_e32 v49, vcc, 0, v21, vcc
	v_add_co_u32_e32 v20, vcc, s90, v20
	s_nop 1
	v_addc_co_u32_e32 v21, vcc, 0, v21, vcc
	global_load_dword v34, v[34:35], off
	s_nop 0
	global_load_dword v35, v[38:39], off
	s_nop 0
	global_load_dword v38, v[40:41], off
	global_load_dword v39, v[42:43], off
	s_nop 0
	global_load_dword v40, v[44:45], off
	global_load_dword v41, v[46:47], off
	global_load_dword v42, v[48:49], off
	s_nop 0
	global_load_dword v20, v[20:21], off
	s_waitcnt vmcnt(30)
	ds_write2_b32 v3, v4, v53 offset1:66
	s_waitcnt vmcnt(28)
	ds_write2_b32 v3, v54, v55 offset0:132 offset1:198
	s_waitcnt vmcnt(26)
	ds_write2_b32 v31, v56, v57 offset0:8 offset1:74
	s_waitcnt vmcnt(24)
	ds_write2_b32 v31, v58, v59 offset0:140 offset1:206
	s_waitcnt vmcnt(22)
	ds_write2_b32 v32, v60, v61 offset0:16 offset1:82
	s_waitcnt vmcnt(20)
	ds_write2_b32 v32, v62, v63 offset0:148 offset1:214
	v_add_u32_e32 v4, 0xc00, v3
	s_waitcnt vmcnt(18)
	ds_write2_b32 v4, v64, v65 offset0:24 offset1:90
	s_waitcnt vmcnt(16)
	ds_write2_b32 v4, v66, v67 offset0:156 offset1:222
	v_add_u32_e32 v4, 0x1000, v3
	s_waitcnt vmcnt(14)
; #define LAS __attribute__((address_space(3)))
; #define LDS_WAIT() asm volatile("s_waitcnt lgkmcnt(0)" ::: "memory")
; __device__ __forceinline__ unsigned pk2(float lo, float hi) { return f2bf(lo) | (f2bf(hi) << 16); }
;     ...
;     for (int i = 0; i < 32; ++i) scr[(2 * i + (lane >> 5)) * 33 + (lane & 31)] = tv_[i];
;     LDS_WAIT(); asm volatile("" ::: "memory");
;     const int c = lane & 7;
; #pragma unroll
;     for (int j = 0; j < 4; ++j) { const int n = (lane >> 3) + 8 * j; const LAS float* s = scr + (8 * c) * 33 + n;
;         v4u o; o.x = pk2(s[0 * 33], s[1 * 33]); o.y = pk2(s[2 * 33], s[3 * 33]); o.z = pk2(s[4 * 33], s[5 * 33]); o.w = pk2(s[6 * 33], s[7 * 33]);
;         *(v4u*)(WT + (size_t)(n0 + n) * ldw + koff + k0 + 8 * c) = o; }
;     LDS_WAIT(); asm volatile("" ::: "memory");
; __device__ __forceinline__ void convert_range(LAS unsigned char* lds, const Params& p, const int lo, const int hi, const int gw, const int NGW) {
;     ...
;         if (r < 2 * I_PB) { const int l = r / I_PB; r -= l * I_PB; p0_transpose_item(p.in[17] + (size_t)l * LW * DM, LW, DM, (bf16*)(ws + WS_WCAT + l * SZ_WCAT), scr, r, lane, KCAT, PW); continue; } r -= 2 * I_PB;
	ds_write2_b32 v4, v68, v69 offset0:32 offset1:98
	s_waitcnt vmcnt(12)
	ds_write2_b32 v4, v70, v71 offset0:164 offset1:230
	v_add_u32_e32 v4, 0x1400, v3
	s_waitcnt vmcnt(10)
	ds_write2_b32 v4, v72, v73 offset0:40 offset1:106
	s_waitcnt vmcnt(8)
	ds_write2_b32 v4, v74, v50 offset0:172 offset1:238
	v_add_u32_e32 v4, 0x1800, v3
	s_waitcnt vmcnt(6)
	ds_write2_b32 v4, v34, v35 offset0:48 offset1:114
	s_waitcnt vmcnt(4)
	ds_write2_b32 v4, v38, v39 offset0:180 offset1:246
	v_add_u32_e32 v4, 0x1c00, v3
	s_waitcnt vmcnt(2)
	ds_write2_b32 v4, v40, v41 offset0:56 offset1:122
	s_waitcnt vmcnt(0)
	ds_write2_b32 v4, v42, v20 offset0:188 offset1:254
	s_waitcnt lgkmcnt(0)
	v_lshlrev_b32_e32 v4, 1, v33
	v_lshl_add_u64 v[20:21], v[36:37], 0, v[4:5]
	v_lshlrev_b32_e32 v4, 1, v6
	v_lshl_add_u64 v[20:21], v[20:21], 0, v[4:5]
	ds_read_b32 v4, v23
	ds_read_b32 v33, v23 offset:132
	ds_read_b32 v35, v23 offset:264
	ds_read_b32 v36, v23 offset:396
	ds_read_b32 v37, v23 offset:528
	ds_read_b32 v38, v23 offset:660
	ds_read_b32 v39, v23 offset:792
	ds_read_b32 v40, v23 offset:924
	s_waitcnt lgkmcnt(0)
	v_bfe_u32 v34, v4, 16, 1
	v_add3_u32 v4, v4, v34, s41
	v_bfe_u32 v34, v33, 16, 1
	v_lshrrev_b32_e32 v4, 16, v4
	v_add3_u32 v33, v33, v34, s41
	v_and_or_b32 v34, v33, s42, v4
	v_bfe_u32 v4, v35, 16, 1
	v_add3_u32 v4, v35, v4, s41
	v_bfe_u32 v33, v36, 16, 1
	v_lshrrev_b32_e32 v4, 16, v4
	v_add3_u32 v33, v36, v33, s41
	v_and_or_b32 v35, v33, s42, v4
	v_bfe_u32 v4, v37, 16, 1
	v_add3_u32 v4, v37, v4, s41
	v_bfe_u32 v33, v38, 16, 1
	v_lshrrev_b32_e32 v4, 16, v4
	v_add3_u32 v33, v38, v33, s41
	v_and_or_b32 v36, v33, s42, v4
	v_bfe_u32 v4, v39, 16, 1
	v_add3_u32 v4, v39, v4, s41
	v_bfe_u32 v33, v40, 16, 1
	v_lshrrev_b32_e32 v4, 16, v4
	v_add3_u32 v33, v40, v33, s41
	v_and_or_b32 v37, v33, s42, v4
	v_or_b32_e32 v4, v52, v7
	v_mul_u32_u24_e32 v4, 0xc00, v4
	v_lshl_add_u64 v[20:21], v[20:21], 0, s[30:31]
	v_lshlrev_b32_e32 v4, 1, v4
	v_lshl_add_u64 v[38:39], v[20:21], 0, v[4:5]
	global_store_dwordx4 v[38:39], v[34:37], off
	ds_read_b32 v4, v23 offset:32
	ds_read_b32 v33, v23 offset:164
	ds_read_b32 v35, v23 offset:296
	ds_read_b32 v36, v23 offset:428
	ds_read_b32 v37, v23 offset:560
	ds_read_b32 v38, v23 offset:692
	ds_read_b32 v39, v23 offset:824
	ds_read_b32 v40, v23 offset:956
	s_waitcnt lgkmcnt(0)
	v_bfe_u32 v34, v4, 16, 1
	v_add3_u32 v4, v4, v34, s41
	v_bfe_u32 v34, v33, 16, 1
	v_lshrrev_b32_e32 v4, 16, v4
	v_add3_u32 v33, v33, v34, s41
	v_and_or_b32 v34, v33, s42, v4
	v_bfe_u32 v4, v35, 16, 1
	v_add3_u32 v4, v35, v4, s41
	v_bfe_u32 v33, v36, 16, 1
	v_lshrrev_b32_e32 v4, 16, v4
	v_add3_u32 v33, v36, v33, s41
	v_and_or_b32 v35, v33, s42, v4
	v_bfe_u32 v4, v37, 16, 1
	v_add3_u32 v4, v37, v4, s41
	v_bfe_u32 v33, v38, 16, 1
	v_lshrrev_b32_e32 v4, 16, v4
	v_add3_u32 v33, v38, v33, s41
	v_and_or_b32 v36, v33, s42, v4
	v_bfe_u32 v4, v39, 16, 1
	v_add3_u32 v4, v39, v4, s41
	v_bfe_u32 v33, v40, 16, 1
	v_lshrrev_b32_e32 v4, 16, v4
	v_add3_u32 v33, v40, v33, s41
	v_and_or_b32 v37, v33, s42, v4
	v_or_b32_e32 v4, v52, v24
	v_mul_u32_u24_e32 v4, 0xc00, v4
	v_lshlrev_b32_e32 v4, 1, v4
	v_lshl_add_u64 v[38:39], v[20:21], 0, v[4:5]
	global_store_dwordx4 v[38:39], v[34:37], off
	ds_read_b32 v4, v23 offset:64
	ds_read_b32 v33, v23 offset:196
	ds_read_b32 v35, v23 offset:328
	ds_read_b32 v36, v23 offset:460
	ds_read_b32 v37, v23 offset:592
	ds_read_b32 v38, v23 offset:724
	ds_read_b32 v39, v23 offset:856
	ds_read_b32 v40, v23 offset:988
	s_waitcnt lgkmcnt(0)
	v_bfe_u32 v34, v4, 16, 1
	v_add3_u32 v4, v4, v34, s41
	v_bfe_u32 v34, v33, 16, 1
	v_lshrrev_b32_e32 v4, 16, v4
	v_add3_u32 v33, v33, v34, s41
	v_and_or_b32 v34, v33, s42, v4
	v_bfe_u32 v4, v35, 16, 1
	v_add3_u32 v4, v35, v4, s41
	v_bfe_u32 v33, v36, 16, 1
	v_lshrrev_b32_e32 v4, 16, v4
	v_add3_u32 v33, v36, v33, s41
	v_and_or_b32 v35, v33, s42, v4
	v_bfe_u32 v4, v37, 16, 1
	v_add3_u32 v4, v37, v4, s41
	v_bfe_u32 v33, v38, 16, 1
	v_lshrrev_b32_e32 v4, 16, v4
	v_add3_u32 v33, v38, v33, s41
	v_and_or_b32 v36, v33, s42, v4
	v_bfe_u32 v4, v39, 16, 1
	v_add3_u32 v4, v39, v4, s41
	v_bfe_u32 v33, v40, 16, 1
	v_lshrrev_b32_e32 v4, 16, v4
	v_add3_u32 v33, v40, v33, s41
	v_and_or_b32 v37, v33, s42, v4
	v_or_b32_e32 v4, v52, v25
	v_mul_u32_u24_e32 v4, 0xc00, v4
	v_lshlrev_b32_e32 v4, 1, v4
	v_lshl_add_u64 v[38:39], v[20:21], 0, v[4:5]
	global_store_dwordx4 v[38:39], v[34:37], off
	ds_read_b32 v4, v23 offset:96
	ds_read_b32 v33, v23 offset:228
	ds_read_b32 v35, v23 offset:360
	ds_read_b32 v36, v23 offset:492
	ds_read_b32 v37, v23 offset:624
	ds_read_b32 v38, v23 offset:756
	ds_read_b32 v39, v23 offset:888
	ds_read_b32 v40, v23 offset:1020
	s_waitcnt lgkmcnt(0)
	v_bfe_u32 v34, v4, 16, 1
	v_add3_u32 v4, v4, v34, s41
	v_bfe_u32 v34, v33, 16, 1
	v_lshrrev_b32_e32 v4, 16, v4
	v_add3_u32 v33, v33, v34, s41
	v_and_or_b32 v34, v33, s42, v4
	v_bfe_u32 v4, v35, 16, 1
	v_add3_u32 v4, v35, v4, s41
	v_bfe_u32 v33, v36, 16, 1
	v_lshrrev_b32_e32 v4, 16, v4
	v_add3_u32 v33, v36, v33, s41
	v_and_or_b32 v35, v33, s42, v4
	v_bfe_u32 v4, v37, 16, 1
	v_add3_u32 v4, v37, v4, s41
	v_bfe_u32 v33, v38, 16, 1
	v_lshrrev_b32_e32 v4, 16, v4
	v_add3_u32 v33, v38, v33, s41
	v_and_or_b32 v36, v33, s42, v4
	v_bfe_u32 v4, v39, 16, 1
	v_add3_u32 v4, v39, v4, s41
	v_bfe_u32 v33, v40, 16, 1
	v_lshrrev_b32_e32 v4, 16, v4
	v_add3_u32 v33, v40, v33, s41
	v_and_or_b32 v37, v33, s42, v4
	v_or_b32_e32 v4, v52, v26
	v_mul_u32_u24_e32 v4, 0xc00, v4
	v_lshlrev_b32_e32 v4, 1, v4
	v_lshl_add_u64 v[20:21], v[20:21], 0, v[4:5]
	global_store_dwordx4 v[20:21], v[34:37], off
	s_waitcnt lgkmcnt(0)

;     ...
;     const int nblk = N / 32, kb = item / nblk, nb = item % nblk, k0 = 64 * kb, n0 = 32 * nb;
;     float tv_[32];
; #pragma unroll
;     for (int i = 0; i < 32; ++i) tv_[i] = W[(size_t)(k0 + 2 * i + (lane >> 5)) * N + n0 + (lane & 31)];
; #pragma unroll
;     for (int i = 0; i < 32; ++i) scr[(2 * i + (lane >> 5)) * 33 + (lane & 31)] = tv_[i];
; __device__ __forceinline__ void convert_range(LAS unsigned char* lds, const Params& p, const int lo, const int hi, const int gw, const int NGW) {
;     ...
;         if (r < 2 * I_PA) { const int l = r / I_PA; r -= l * I_PA; p0_transpose_item(p.in[16] + (size_t)l * PW * DM, PW, DM, (bf16*)(ws + WS_WCAT + l * SZ_WCAT), scr, r, lane, KCAT, 0); continue; } r -= 2 * I_PA;
.LBB0_41:
	s_andn2_saveexec_b64 s[26:27], s[26:27]
	s_cbranch_execz .LBB0_43
	v_add_u32_e32 v4, 0x2a00, v27
	v_lshrrev_b32_e32 v4, 10, v4
	v_readlane_b32 s68, v251, 9
	v_lshlrev_b64 v[34:35], 23, v[4:5]
	v_readlane_b32 s69, v251, 10
	v_mov_b64_e32 v[36:37], s[20:21]
	v_and_b32_e32 v52, 0x7e0, v30
	v_lshl_add_u64 v[34:35], s[68:69], 0, v[34:35]
	v_mad_u64_u32 v[36:37], s[28:29], v4, s91, v[36:37]
	v_and_b32_e32 v33, 0x3c0, v20
	v_lshlrev_b32_e32 v4, 2, v52
	v_or_b32_e32 v38, v33, v1
	v_lshl_add_u64 v[20:21], v[34:35], 0, v[4:5]
	v_lshlrev_b32_e32 v4, 2, v2
	v_lshl_add_u64 v[20:21], v[20:21], 0, v[4:5]
	v_lshlrev_b32_e32 v4, 13, v38
	v_lshl_add_u64 v[20:21], v[20:21], 0, v[4:5]
	v_add_co_u32_e32 v34, vcc, s40, v20
	v_readlane_b32 s70, v251, 11
	s_nop 0
	v_addc_co_u32_e32 v35, vcc, 0, v21, vcc
	v_add_co_u32_e32 v38, vcc, s43, v20
	v_readlane_b32 s71, v251, 12
	s_nop 0
	v_addc_co_u32_e32 v39, vcc, 0, v21, vcc
	v_add_co_u32_e32 v40, vcc, s45, v20
	v_readlane_b32 s72, v251, 13
	s_nop 0
	v_addc_co_u32_e32 v41, vcc, 0, v21, vcc
	v_add_co_u32_e32 v42, vcc, s47, v20
	v_readlane_b32 s73, v251, 14
	s_nop 0
	v_addc_co_u32_e32 v43, vcc, 0, v21, vcc
	v_add_co_u32_e32 v44, vcc, s48, v20
	v_readlane_b32 s74, v251, 15
	s_nop 0
	v_addc_co_u32_e32 v45, vcc, 0, v21, vcc
	v_add_co_u32_e32 v46, vcc, s49, v20
	v_readlane_b32 s75, v251, 16
	s_nop 0
	v_addc_co_u32_e32 v47, vcc, 0, v21, vcc
	v_add_co_u32_e32 v48, vcc, s50, v20
	s_nop 1
	v_addc_co_u32_e32 v49, vcc, 0, v21, vcc
	global_load_dword v4, v[20:21], off
	global_load_dword v53, v[34:35], off
	global_load_dword v54, v[38:39], off
	global_load_dword v55, v[40:41], off
	global_load_dword v56, v[42:43], off
	global_load_dword v57, v[44:45], off
	global_load_dword v58, v[46:47], off
	global_load_dword v59, v[48:49], off
	v_add_co_u32_e32 v34, vcc, s51, v20
	s_nop 1
	v_addc_co_u32_e32 v35, vcc, 0, v21, vcc
	v_add_co_u32_e32 v38, vcc, s52, v20
	s_nop 1
	v_addc_co_u32_e32 v39, vcc, 0, v21, vcc
	v_add_co_u32_e32 v40, vcc, s53, v20
	s_nop 1
	v_addc_co_u32_e32 v41, vcc, 0, v21, vcc
	v_add_co_u32_e32 v42, vcc, s54, v20
	s_nop 1
	v_addc_co_u32_e32 v43, vcc, 0, v21, vcc
	v_add_co_u32_e32 v44, vcc, s55, v20
	s_nop 1
	v_addc_co_u32_e32 v45, vcc, 0, v21, vcc
	v_add_co_u32_e32 v46, vcc, s56, v20
	s_nop 1
	v_addc_co_u32_e32 v47, vcc, 0, v21, vcc
	v_add_co_u32_e32 v48, vcc, s57, v20
	s_nop 1
	v_addc_co_u32_e32 v49, vcc, 0, v21, vcc
	v_add_co_u32_e32 v50, vcc, s58, v20
	s_nop 1
	v_addc_co_u32_e32 v51, vcc, 0, v21, vcc
	global_load_dword v60, v[34:35], off
	global_load_dword v61, v[38:39], off
	global_load_dword v62, v[40:41], off
	global_load_dword v63, v[42:43], off
	global_load_dword v64, v[44:45], off
	global_load_dword v65, v[46:47], off
	global_load_dword v66, v[48:49], off
	global_load_dword v67, v[50:51], off
	v_add_co_u32_e32 v34, vcc, s59, v20
	s_nop 1
	v_addc_co_u32_e32 v35, vcc, 0, v21, vcc
	v_add_co_u32_e32 v38, vcc, s76, v20
	s_nop 1
	v_addc_co_u32_e32 v39, vcc, 0, v21, vcc
	v_add_co_u32_e32 v40, vcc, s77, v20
	s_nop 1
	v_addc_co_u32_e32 v41, vcc, 0, v21, vcc
	v_add_co_u32_e32 v42, vcc, s78, v20
	s_nop 1
	v_addc_co_u32_e32 v43, vcc, 0, v21, vcc
	v_add_co_u32_e32 v44, vcc, s79, v20
	s_nop 1
	v_addc_co_u32_e32 v45, vcc, 0, v21, vcc
	v_add_co_u32_e32 v46, vcc, s80, v20
	s_nop 1
	v_addc_co_u32_e32 v47, vcc, 0, v21, vcc
	v_add_co_u32_e32 v48, vcc, s81, v20
	s_nop 1
	v_addc_co_u32_e32 v49, vcc, 0, v21, vcc
	v_add_co_u32_e32 v50, vcc, s82, v20
	s_nop 1
	v_addc_co_u32_e32 v51, vcc, 0, v21, vcc
	global_load_dword v68, v[34:35], off
	global_load_dword v69, v[38:39], off
	global_load_dword v70, v[40:41], off
	global_load_dword v71, v[42:43], off
	global_load_dword v72, v[44:45], off
	global_load_dword v73, v[46:47], off
	global_load_dword v74, v[48:49], off
	s_nop 0
	global_load_dword v50, v[50:51], off
	v_add_co_u32_e32 v34, vcc, s83, v20
	s_nop 1
	v_addc_co_u32_e32 v35, vcc, 0, v21, vcc
	v_add_co_u32_e32 v38, vcc, s84, v20
	s_nop 1
	v_addc_co_u32_e32 v39, vcc, 0, v21, vcc
	v_add_co_u32_e32 v40, vcc, s85, v20
	s_nop 1
	v_addc_co_u32_e32 v41, vcc, 0, v21, vcc
	v_add_co_u32_e32 v42, vcc, s86, v20
	s_nop 1
	v_addc_co_u32_e32 v43, vcc, 0, v21, vcc
	v_add_co_u32_e32 v44, vcc, s87, v20
	s_nop 1
	v_addc_co_u32_e32 v45, vcc, 0, v21, vcc
	v_add_co_u32_e32 v46, vcc, s88, v20
	s_nop 1
	v_addc_co_u32_e32 v47, vcc, 0, v21, vcc
	v_add_co_u32_e32 v48, vcc, s89, v20
	s_nop 1
	v_addc_co_u32_e32 v49, vcc, 0, v21, vcc
	v_add_co_u32_e32 v20, vcc, s90, v20
	s_nop 1
	v_addc_co_u32_e32 v21, vcc, 0, v21, vcc
	global_load_dword v34, v[34:35], off
	s_nop 0
	global_load_dword v35, v[38:39], off
	s_nop 0
	global_load_dword v38, v[40:41], off
	global_load_dword v39, v[42:43], off
	s_nop 0
	global_load_dword v40, v[44:45], off
	global_load_dword v41, v[46:47], off
	global_load_dword v42, v[48:49], off
	s_nop 0
	global_load_dword v20, v[20:21], off
	s_waitcnt vmcnt(30)
	ds_write2_b32 v3, v4, v53 offset1:66
	s_waitcnt vmcnt(28)
	ds_write2_b32 v3, v54, v55 offset0:132 offset1:198
	s_waitcnt vmcnt(26)
	ds_write2_b32 v31, v56, v57 offset0:8 offset1:74
	s_waitcnt vmcnt(24)
	ds_write2_b32 v31, v58, v59 offset0:140 offset1:206
	s_waitcnt vmcnt(22)
	ds_write2_b32 v32, v60, v61 offset0:16 offset1:82
	s_waitcnt vmcnt(20)
	ds_write2_b32 v32, v62, v63 offset0:148 offset1:214
	v_add_u32_e32 v4, 0xc00, v3
	s_waitcnt vmcnt(18)
	ds_write2_b32 v4, v64, v65 offset0:24 offset1:90
	s_waitcnt vmcnt(16)
	ds_write2_b32 v4, v66, v67 offset0:156 offset1:222
	v_add_u32_e32 v4, 0x1000, v3
	s_waitcnt vmcnt(14)
; #define LAS __attribute__((address_space(3)))
; #define LDS_WAIT() asm volatile("s_waitcnt lgkmcnt(0)" ::: "memory")
; __device__ __forceinline__ unsigned pk2(float lo, float hi) { return f2bf(lo) | (f2bf(hi) << 16); }
;     ...
;     for (int i = 0; i < 32; ++i) scr[(2 * i + (lane >> 5)) * 33 + (lane & 31)] = tv_[i];
;     LDS_WAIT(); asm volatile("" ::: "memory");
;     const int c = lane & 7;
; #pragma unroll
;     for (int j = 0; j < 4; ++j) { const int n = (lane >> 3) + 8 * j; const LAS float* s = scr + (8 * c) * 33 + n;
;         v4u o; o.x = pk2(s[0 * 33], s[1 * 33]); o.y = pk2(s[2 * 33], s[3 * 33]); o.z = pk2(s[4 * 33], s[5 * 33]); o.w = pk2(s[6 * 33], s[7 * 33]);
;         *(v4u*)(WT + (size_t)(n0 + n) * ldw + koff + k0 + 8 * c) = o; }
;     LDS_WAIT(); asm volatile("" ::: "memory");
	ds_write2_b32 v4, v68, v69 offset0:32 offset1:98
	s_waitcnt vmcnt(12)
	ds_write2_b32 v4, v70, v71 offset0:164 offset1:230
	v_add_u32_e32 v4, 0x1400, v3
	s_waitcnt vmcnt(10)
	ds_write2_b32 v4, v72, v73 offset0:40 offset1:106
	s_waitcnt vmcnt(8)
	ds_write2_b32 v4, v74, v50 offset0:172 offset1:238
	v_add_u32_e32 v4, 0x1800, v3
	s_waitcnt vmcnt(6)
	ds_write2_b32 v4, v34, v35 offset0:48 offset1:114
	s_waitcnt vmcnt(4)
	ds_write2_b32 v4, v38, v39 offset0:180 offset1:246
	v_add_u32_e32 v4, 0x1c00, v3
	s_waitcnt vmcnt(2)
	ds_write2_b32 v4, v40, v41 offset0:56 offset1:122
	s_waitcnt vmcnt(0)
	ds_write2_b32 v4, v42, v20 offset0:188 offset1:254
	s_waitcnt lgkmcnt(0)
	v_lshlrev_b32_e32 v4, 1, v33
	v_lshl_add_u64 v[20:21], v[36:37], 0, v[4:5]
	v_lshlrev_b32_e32 v4, 1, v6
	v_lshl_add_u64 v[20:21], v[20:21], 0, v[4:5]
	ds_read_b32 v4, v23
	ds_read_b32 v33, v23 offset:132
	ds_read_b32 v35, v23 offset:264
	ds_read_b32 v36, v23 offset:396
	ds_read_b32 v37, v23 offset:528
	ds_read_b32 v38, v23 offset:660
	ds_read_b32 v39, v23 offset:792
	ds_read_b32 v40, v23 offset:924
	s_waitcnt lgkmcnt(0)
	v_bfe_u32 v34, v4, 16, 1
	v_add3_u32 v4, v4, v34, s41
	v_bfe_u32 v34, v33, 16, 1
	v_lshrrev_b32_e32 v4, 16, v4
	v_add3_u32 v33, v33, v34, s41
	v_and_or_b32 v34, v33, s42, v4
	v_bfe_u32 v4, v35, 16, 1
	v_add3_u32 v4, v35, v4, s41
	v_bfe_u32 v33, v36, 16, 1
	v_lshrrev_b32_e32 v4, 16, v4
	v_add3_u32 v33, v36, v33, s41
	v_and_or_b32 v35, v33, s42, v4
	v_bfe_u32 v4, v37, 16, 1
	v_add3_u32 v4, v37, v4, s41
	v_bfe_u32 v33, v38, 16, 1
	v_lshrrev_b32_e32 v4, 16, v4
	v_add3_u32 v33, v38, v33, s41
	v_and_or_b32 v36, v33, s42, v4
	v_bfe_u32 v4, v39, 16, 1
	v_add3_u32 v4, v39, v4, s41
	v_bfe_u32 v33, v40, 16, 1
	v_lshrrev_b32_e32 v4, 16, v4
	v_add3_u32 v33, v40, v33, s41
	v_and_or_b32 v37, v33, s42, v4
	v_or_b32_e32 v4, v52, v7
	v_mul_u32_u24_e32 v4, 0xc00, v4
	v_lshlrev_b32_e32 v4, 1, v4
	v_lshl_add_u64 v[38:39], v[20:21], 0, v[4:5]
	global_store_dwordx4 v[38:39], v[34:37], off
	ds_read_b32 v4, v23 offset:32
	ds_read_b32 v33, v23 offset:164
	ds_read_b32 v35, v23 offset:296
	ds_read_b32 v36, v23 offset:428
	ds_read_b32 v37, v23 offset:560
	ds_read_b32 v38, v23 offset:692
	ds_read_b32 v39, v23 offset:824
	ds_read_b32 v40, v23 offset:956
	s_waitcnt lgkmcnt(0)
	v_bfe_u32 v34, v4, 16, 1
	v_add3_u32 v4, v4, v34, s41
	v_bfe_u32 v34, v33, 16, 1
	v_lshrrev_b32_e32 v4, 16, v4
	v_add3_u32 v33, v33, v34, s41
	v_and_or_b32 v34, v33, s42, v4
	v_bfe_u32 v4, v35, 16, 1
	v_add3_u32 v4, v35, v4, s41
	v_bfe_u32 v33, v36, 16, 1
	v_lshrrev_b32_e32 v4, 16, v4
	v_add3_u32 v33, v36, v33, s41
	v_and_or_b32 v35, v33, s42, v4
	v_bfe_u32 v4, v37, 16, 1
	v_add3_u32 v4, v37, v4, s41
	v_bfe_u32 v33, v38, 16, 1
	v_lshrrev_b32_e32 v4, 16, v4
	v_add3_u32 v33, v38, v33, s41
	v_and_or_b32 v36, v33, s42, v4
	v_bfe_u32 v4, v39, 16, 1
	v_add3_u32 v4, v39, v4, s41
	v_bfe_u32 v33, v40, 16, 1
	v_lshrrev_b32_e32 v4, 16, v4
	v_add3_u32 v33, v40, v33, s41
	v_and_or_b32 v37, v33, s42, v4
	v_or_b32_e32 v4, v52, v24
	v_mul_u32_u24_e32 v4, 0xc00, v4
	v_lshlrev_b32_e32 v4, 1, v4
	v_lshl_add_u64 v[38:39], v[20:21], 0, v[4:5]
	global_store_dwordx4 v[38:39], v[34:37], off
	ds_read_b32 v4, v23 offset:64
	ds_read_b32 v33, v23 offset:196
	ds_read_b32 v35, v23 offset:328
	ds_read_b32 v36, v23 offset:460
	ds_read_b32 v37, v23 offset:592
	ds_read_b32 v38, v23 offset:724
	ds_read_b32 v39, v23 offset:856
	ds_read_b32 v40, v23 offset:988
	s_waitcnt lgkmcnt(0)
	v_bfe_u32 v34, v4, 16, 1
	v_add3_u32 v4, v4, v34, s41
	v_bfe_u32 v34, v33, 16, 1
	v_lshrrev_b32_e32 v4, 16, v4
	v_add3_u32 v33, v33, v34, s41
	v_and_or_b32 v34, v33, s42, v4
	v_bfe_u32 v4, v35, 16, 1
	v_add3_u32 v4, v35, v4, s41
	v_bfe_u32 v33, v36, 16, 1
	v_lshrrev_b32_e32 v4, 16, v4
	v_add3_u32 v33, v36, v33, s41
	v_and_or_b32 v35, v33, s42, v4
	v_bfe_u32 v4, v37, 16, 1
	v_add3_u32 v4, v37, v4, s41
	v_bfe_u32 v33, v38, 16, 1
	v_lshrrev_b32_e32 v4, 16, v4
	v_add3_u32 v33, v38, v33, s41
	v_and_or_b32 v36, v33, s42, v4
	v_bfe_u32 v4, v39, 16, 1
	v_add3_u32 v4, v39, v4, s41
	v_bfe_u32 v33, v40, 16, 1
	v_lshrrev_b32_e32 v4, 16, v4
	v_add3_u32 v33, v40, v33, s41
	v_and_or_b32 v37, v33, s42, v4
	v_or_b32_e32 v4, v52, v25
	v_mul_u32_u24_e32 v4, 0xc00, v4
	v_lshlrev_b32_e32 v4, 1, v4
	v_lshl_add_u64 v[38:39], v[20:21], 0, v[4:5]
	global_store_dwordx4 v[38:39], v[34:37], off
	ds_read_b32 v4, v23 offset:96
	ds_read_b32 v33, v23 offset:228
	ds_read_b32 v35, v23 offset:360
	ds_read_b32 v36, v23 offset:492
	ds_read_b32 v37, v23 offset:624
	ds_read_b32 v38, v23 offset:756
	ds_read_b32 v39, v23 offset:888
	ds_read_b32 v40, v23 offset:1020
	s_waitcnt lgkmcnt(0)
	v_bfe_u32 v34, v4, 16, 1
	v_add3_u32 v4, v4, v34, s41
	v_bfe_u32 v34, v33, 16, 1
	v_lshrrev_b32_e32 v4, 16, v4
	v_add3_u32 v33, v33, v34, s41
	v_and_or_b32 v34, v33, s42, v4
	v_bfe_u32 v4, v35, 16, 1
	v_add3_u32 v4, v35, v4, s41
	v_bfe_u32 v33, v36, 16, 1
	v_lshrrev_b32_e32 v4, 16, v4
	v_add3_u32 v33, v36, v33, s41
	v_and_or_b32 v35, v33, s42, v4
	v_bfe_u32 v4, v37, 16, 1
	v_add3_u32 v4, v37, v4, s41
	v_bfe_u32 v33, v38, 16, 1
	v_lshrrev_b32_e32 v4, 16, v4
	v_add3_u32 v33, v38, v33, s41
	v_and_or_b32 v36, v33, s42, v4
	v_bfe_u32 v4, v39, 16, 1
	v_add3_u32 v4, v39, v4, s41
	v_bfe_u32 v33, v40, 16, 1
	v_lshrrev_b32_e32 v4, 16, v4
	v_add3_u32 v33, v40, v33, s41
	v_and_or_b32 v37, v33, s42, v4
	v_or_b32_e32 v4, v52, v26
	v_mul_u32_u24_e32 v4, 0xc00, v4
	v_lshlrev_b32_e32 v4, 1, v4
	v_lshl_add_u64 v[20:21], v[20:21], 0, v[4:5]
	global_store_dwordx4 v[20:21], v[34:37], off
	s_waitcnt lgkmcnt(0)

;     ...
;     const int nblk = N / 32, kb = item / nblk, nb = item % nblk, k0 = 64 * kb, n0 = 32 * nb;
;     float tv_[32];
; #pragma unroll
;     for (int i = 0; i < 32; ++i) tv_[i] = W[(size_t)(k0 + 2 * i + (lane >> 5)) * N + n0 + (lane & 31)];
; #pragma unroll
;     for (int i = 0; i < 32; ++i) scr[(2 * i + (lane >> 5)) * 33 + (lane & 31)] = tv_[i];
; __device__ __forceinline__ void convert_range(LAS unsigned char* lds, const Params& p, const int lo, const int hi, const int gw, const int NGW) {
;     ...
;         if (r < 2 * I_IN) { const int l = r / I_IN; r -= l * I_IN; p0_transpose_item(p.in[5] + (size_t)l * DM * NC, DM, NC, (bf16*)(ws + WS_WIN + l * SZ_WIN), scr, r, lane); continue; } r -= 2 * I_IN;
.LBB0_44:
	s_andn2_saveexec_b64 s[24:25], s[24:25]
	s_cbranch_execz .LBB0_21
	v_mul_hi_i32 v4, v20, s92
	v_lshrrev_b32_e32 v20, 31, v4
	v_ashrrev_i32_e32 v4, 12, v4
	v_add_u32_e32 v33, v4, v20
	v_readlane_b32 s60, v251, 21
	v_mul_i32_i24_e32 v4, 0xffffd800, v33
	s_movk_i32 s26, 0x7a00
	v_readlane_b32 s70, v251, 31
	v_readlane_b32 s71, v251, 32
	v_add3_u32 v4, v4, v27, s26
	s_mov_b32 s26, 0x5000000
	v_mov_b64_e32 v[20:21], s[70:71]
	v_mad_i64_i32 v[34:35], s[26:27], v33, s26, v[20:21]
	v_mul_hi_i32 v20, v4, s92
	v_lshrrev_b32_e32 v21, 31, v20
	v_ashrrev_i32_e32 v20, 7, v20
	v_add_u32_e32 v20, v20, v21
	v_mul_i32_i24_e32 v21, 0x140, v20
	v_sub_u32_e32 v4, v4, v21
	v_lshlrev_b32_e32 v36, 6, v20
	v_lshlrev_b32_e32 v20, 5, v4
	v_ashrrev_i32_e32 v21, 31, v20
	v_or_b32_e32 v37, v36, v1
	v_lshl_add_u64 v[34:35], v[20:21], 2, v[34:35]
	v_lshlrev_b32_e32 v4, 2, v2
	v_lshl_add_u64 v[34:35], v[34:35], 0, v[4:5]
	v_or_b32_e32 v4, 2, v37
	v_mad_i64_i32 v[40:41], s[26:27], v4, s44, v[34:35]
	v_or_b32_e32 v4, 4, v37
	v_mad_i64_i32 v[42:43], s[26:27], v4, s44, v[34:35]
	v_or_b32_e32 v4, 6, v37
	v_mad_i64_i32 v[44:45], s[26:27], v4, s44, v[34:35]
	v_or_b32_e32 v4, 8, v37
	v_mad_i64_i32 v[46:47], s[26:27], v4, s44, v[34:35]
	v_or_b32_e32 v4, 10, v37
	v_mad_i64_i32 v[48:49], s[26:27], v4, s44, v[34:35]
	v_or_b32_e32 v4, 12, v37
	v_mad_i64_i32 v[50:51], s[26:27], v4, s44, v[34:35]
	v_or_b32_e32 v4, 14, v37
	v_mad_i64_i32 v[38:39], s[26:27], v37, s44, v[34:35]
	v_mad_i64_i32 v[52:53], s[26:27], v4, s44, v[34:35]
	global_load_dword v4, v[38:39], off
	global_load_dword v21, v[40:41], off
	global_load_dword v54, v[42:43], off
	global_load_dword v55, v[44:45], off
	global_load_dword v56, v[46:47], off
	global_load_dword v57, v[48:49], off
	global_load_dword v58, v[50:51], off
	global_load_dword v59, v[52:53], off
	v_or_b32_e32 v38, 16, v37
	v_or_b32_e32 v40, 18, v37
	v_or_b32_e32 v42, 20, v37
	v_or_b32_e32 v44, 22, v37
	v_or_b32_e32 v52, 30, v37
	v_mad_i64_i32 v[38:39], s[26:27], v38, s44, v[34:35]
	v_mad_i64_i32 v[40:41], s[26:27], v40, s44, v[34:35]
	v_mad_i64_i32 v[42:43], s[26:27], v42, s44, v[34:35]
	v_mad_i64_i32 v[44:45], s[26:27], v44, s44, v[34:35]
	v_or_b32_e32 v46, 24, v37
	v_or_b32_e32 v48, 26, v37
	v_or_b32_e32 v50, 28, v37
	v_mad_i64_i32 v[52:53], s[26:27], v52, s44, v[34:35]
	v_mad_i64_i32 v[46:47], s[26:27], v46, s44, v[34:35]
	v_mad_i64_i32 v[48:49], s[26:27], v48, s44, v[34:35]
	v_mad_i64_i32 v[50:51], s[26:27], v50, s44, v[34:35]
	global_load_dword v60, v[38:39], off
	global_load_dword v61, v[40:41], off
	global_load_dword v62, v[42:43], off
	global_load_dword v63, v[44:45], off
	global_load_dword v64, v[46:47], off
	global_load_dword v65, v[48:49], off
	global_load_dword v66, v[50:51], off
	global_load_dword v67, v[52:53], off
	v_or_b32_e32 v38, 32, v37
	v_or_b32_e32 v40, 34, v37
	v_or_b32_e32 v42, 36, v37
	v_or_b32_e32 v44, 38, v37
	v_or_b32_e32 v52, 46, v37
	v_mad_i64_i32 v[38:39], s[26:27], v38, s44, v[34:35]
	v_mad_i64_i32 v[40:41], s[26:27], v40, s44, v[34:35]
	v_mad_i64_i32 v[42:43], s[26:27], v42, s44, v[34:35]
	v_mad_i64_i32 v[44:45], s[26:27], v44, s44, v[34:35]
	v_or_b32_e32 v46, 40, v37
	v_or_b32_e32 v48, 42, v37
	v_or_b32_e32 v50, 44, v37
	v_mad_i64_i32 v[52:53], s[26:27], v52, s44, v[34:35]
	v_mad_i64_i32 v[46:47], s[26:27], v46, s44, v[34:35]
	v_mad_i64_i32 v[48:49], s[26:27], v48, s44, v[34:35]
	v_mad_i64_i32 v[50:51], s[26:27], v50, s44, v[34:35]
	global_load_dword v68, v[38:39], off
	global_load_dword v69, v[40:41], off
	global_load_dword v70, v[42:43], off
	global_load_dword v71, v[44:45], off
	global_load_dword v72, v[46:47], off
	global_load_dword v73, v[48:49], off
	global_load_dword v74, v[50:51], off
	s_nop 0
	global_load_dword v52, v[52:53], off
	v_or_b32_e32 v38, 48, v37
	v_or_b32_e32 v40, 50, v37
	v_or_b32_e32 v42, 52, v37
	v_or_b32_e32 v44, 54, v37
	v_mad_i64_i32 v[38:39], s[26:27], v38, s44, v[34:35]
	v_mad_i64_i32 v[40:41], s[26:27], v40, s44, v[34:35]
	v_mad_i64_i32 v[42:43], s[26:27], v42, s44, v[34:35]
	v_mad_i64_i32 v[44:45], s[26:27], v44, s44, v[34:35]
	v_or_b32_e32 v46, 56, v37
	v_or_b32_e32 v48, 58, v37
	v_or_b32_e32 v50, 60, v37
	v_or_b32_e32 v37, 62, v37
	v_mad_i64_i32 v[46:47], s[26:27], v46, s44, v[34:35]
	v_mad_i64_i32 v[48:49], s[26:27], v48, s44, v[34:35]
	v_mad_i64_i32 v[50:51], s[26:27], v50, s44, v[34:35]
	v_mad_i64_i32 v[34:35], s[26:27], v37, s44, v[34:35]
	global_load_dword v37, v[38:39], off
	s_nop 0
	global_load_dword v38, v[40:41], off
	global_load_dword v39, v[42:43], off
	s_nop 0
	global_load_dword v40, v[44:45], off
	global_load_dword v41, v[46:47], off
	global_load_dword v42, v[48:49], off
	global_load_dword v43, v[50:51], off
	s_nop 0
	global_load_dword v44, v[34:35], off
	s_waitcnt vmcnt(30)
	ds_write2_b32 v3, v4, v21 offset1:66
	s_waitcnt vmcnt(28)
	ds_write2_b32 v3, v54, v55 offset0:132 offset1:198
	s_waitcnt vmcnt(26)
	ds_write2_b32 v31, v56, v57 offset0:8 offset1:74
	s_waitcnt vmcnt(24)
	ds_write2_b32 v31, v58, v59 offset0:140 offset1:206
	s_waitcnt vmcnt(22)
	ds_write2_b32 v32, v60, v61 offset0:16 offset1:82
	s_waitcnt vmcnt(20)
	ds_write2_b32 v32, v62, v63 offset0:148 offset1:214
	v_add_u32_e32 v4, 0xc00, v3
	s_waitcnt vmcnt(18)
	ds_write2_b32 v4, v64, v65 offset0:24 offset1:90
	s_waitcnt vmcnt(16)
	ds_write2_b32 v4, v66, v67 offset0:156 offset1:222
	v_add_u32_e32 v4, 0x1000, v3
	s_waitcnt vmcnt(14)
	ds_write2_b32 v4, v68, v69 offset0:32 offset1:98
	s_waitcnt vmcnt(12)
	ds_write2_b32 v4, v70, v71 offset0:164 offset1:230
	v_add_u32_e32 v4, 0x1400, v3
	s_waitcnt vmcnt(10)
	ds_write2_b32 v4, v72, v73 offset0:40 offset1:106
	s_waitcnt vmcnt(8)
; #define LAS __attribute__((address_space(3)))
; #define LDS_WAIT() asm volatile("s_waitcnt lgkmcnt(0)" ::: "memory")
; __device__ __forceinline__ unsigned pk2(float lo, float hi) { return f2bf(lo) | (f2bf(hi) << 16); }
;     ...
;     for (int i = 0; i < 32; ++i) scr[(2 * i + (lane >> 5)) * 33 + (lane & 31)] = tv_[i];
;     LDS_WAIT(); asm volatile("" ::: "memory");
;     const int c = lane & 7;
; #pragma unroll
;     for (int j = 0; j < 4; ++j) { const int n = (lane >> 3) + 8 * j; const LAS float* s = scr + (8 * c) * 33 + n;
;         v4u o; o.x = pk2(s[0 * 33], s[1 * 33]); o.y = pk2(s[2 * 33], s[3 * 33]); o.z = pk2(s[4 * 33], s[5 * 33]); o.w = pk2(s[6 * 33], s[7 * 33]);
;         *(v4u*)(WT + (size_t)(n0 + n) * ldw + koff + k0 + 8 * c) = o; }
;     LDS_WAIT(); asm volatile("" ::: "memory");
; __device__ __forceinline__ void convert_range(LAS unsigned char* lds, const Params& p, const int lo, const int hi, const int gw, const int NGW) {
;     ...
;         if (r < 2 * I_IN) { const int l = r / I_IN; r -= l * I_IN; p0_transpose_item(p.in[5] + (size_t)l * DM * NC, DM, NC, (bf16*)(ws + WS_WIN + l * SZ_WIN), scr, r, lane); continue; } r -= 2 * I_IN;
	ds_write2_b32 v4, v74, v52 offset0:172 offset1:238
	v_add_u32_e32 v4, 0x1800, v3
	s_waitcnt vmcnt(6)
	ds_write2_b32 v4, v37, v38 offset0:48 offset1:114
	s_waitcnt vmcnt(4)
	ds_write2_b32 v4, v39, v40 offset0:180 offset1:246
	v_add_u32_e32 v4, 0x1c00, v3
	v_mov_b64_e32 v[34:35], s[8:9]
	s_mov_b32 s26, 0x2800000
	s_waitcnt vmcnt(2)
	ds_write2_b32 v4, v41, v42 offset0:56 offset1:122
	s_waitcnt vmcnt(0)
	ds_write2_b32 v4, v43, v44 offset0:188 offset1:254
	v_mad_i64_i32 v[34:35], s[26:27], v33, s26, v[34:35]
	s_waitcnt lgkmcnt(0)
	v_ashrrev_i32_e32 v37, 31, v36
	v_lshl_add_u64 v[34:35], v[36:37], 1, v[34:35]
	v_lshlrev_b32_e32 v4, 1, v6
	v_lshl_add_u64 v[38:39], v[34:35], 0, v[4:5]
	ds_read_b32 v4, v23
	ds_read_b32 v21, v23 offset:132
	ds_read_b32 v33, v23 offset:264
	ds_read_b32 v35, v23 offset:396
	ds_read_b32 v36, v23 offset:528
	ds_read_b32 v37, v23 offset:660
	ds_read_b32 v40, v23 offset:792
	ds_read_b32 v41, v23 offset:924
	s_waitcnt lgkmcnt(0)
	v_bfe_u32 v34, v4, 16, 1
	v_add3_u32 v4, v4, v34, s41
	v_bfe_u32 v34, v21, 16, 1
	v_lshrrev_b32_e32 v4, 16, v4
	v_add3_u32 v21, v21, v34, s41
	v_and_or_b32 v34, v21, s42, v4
	v_bfe_u32 v4, v33, 16, 1
	v_add3_u32 v4, v33, v4, s41
	v_bfe_u32 v21, v35, 16, 1
	v_lshrrev_b32_e32 v4, 16, v4
	v_add3_u32 v21, v35, v21, s41
	v_and_or_b32 v35, v21, s42, v4
	v_bfe_u32 v4, v36, 16, 1
	v_add3_u32 v4, v36, v4, s41
	v_bfe_u32 v21, v37, 16, 1
	v_lshrrev_b32_e32 v4, 16, v4
	v_add3_u32 v21, v37, v21, s41
	v_and_or_b32 v36, v21, s42, v4
	v_bfe_u32 v4, v40, 16, 1
	v_add3_u32 v4, v40, v4, s41
	v_bfe_u32 v21, v41, 16, 1
	v_or_b32_e32 v40, v20, v7
	v_add3_u32 v21, v41, v21, s41
	v_ashrrev_i32_e32 v41, 31, v40
	v_lshrrev_b32_e32 v4, 16, v4
	v_lshlrev_b64 v[40:41], 12, v[40:41]
	v_and_or_b32 v37, v21, s42, v4
	v_lshl_add_u64 v[40:41], v[38:39], 0, v[40:41]
	global_store_dwordx4 v[40:41], v[34:37], off
	ds_read_b32 v4, v23 offset:32
	ds_read_b32 v21, v23 offset:164
	ds_read_b32 v33, v23 offset:296
	ds_read_b32 v35, v23 offset:428
	ds_read_b32 v36, v23 offset:560
	ds_read_b32 v37, v23 offset:692
	ds_read_b32 v40, v23 offset:824
	ds_read_b32 v41, v23 offset:956
	s_waitcnt lgkmcnt(0)
	v_bfe_u32 v34, v4, 16, 1
	v_add3_u32 v4, v4, v34, s41
	v_bfe_u32 v34, v21, 16, 1
	v_lshrrev_b32_e32 v4, 16, v4
	v_add3_u32 v21, v21, v34, s41
	v_and_or_b32 v34, v21, s42, v4
	v_bfe_u32 v4, v33, 16, 1
	v_add3_u32 v4, v33, v4, s41
	v_bfe_u32 v21, v35, 16, 1
	v_lshrrev_b32_e32 v4, 16, v4
	v_add3_u32 v21, v35, v21, s41
	v_and_or_b32 v35, v21, s42, v4
	v_bfe_u32 v4, v36, 16, 1
	v_add3_u32 v4, v36, v4, s41
	v_bfe_u32 v21, v37, 16, 1
	v_lshrrev_b32_e32 v4, 16, v4
	v_add3_u32 v21, v37, v21, s41
	v_and_or_b32 v36, v21, s42, v4
	v_bfe_u32 v4, v40, 16, 1
	v_add3_u32 v4, v40, v4, s41
	v_bfe_u32 v21, v41, 16, 1
	v_or_b32_e32 v40, v20, v24
	v_add3_u32 v21, v41, v21, s41
	v_ashrrev_i32_e32 v41, 31, v40
	v_lshrrev_b32_e32 v4, 16, v4
	v_lshlrev_b64 v[40:41], 12, v[40:41]
	v_and_or_b32 v37, v21, s42, v4
	v_lshl_add_u64 v[40:41], v[38:39], 0, v[40:41]
	global_store_dwordx4 v[40:41], v[34:37], off
	ds_read_b32 v4, v23 offset:64
	ds_read_b32 v21, v23 offset:196
	ds_read_b32 v33, v23 offset:328
	ds_read_b32 v35, v23 offset:460
	ds_read_b32 v36, v23 offset:592
	ds_read_b32 v37, v23 offset:724
	ds_read_b32 v40, v23 offset:856
	ds_read_b32 v41, v23 offset:988
	s_waitcnt lgkmcnt(0)
	v_bfe_u32 v34, v4, 16, 1
	v_add3_u32 v4, v4, v34, s41
	v_bfe_u32 v34, v21, 16, 1
	v_lshrrev_b32_e32 v4, 16, v4
	v_add3_u32 v21, v21, v34, s41
	v_and_or_b32 v34, v21, s42, v4
	v_bfe_u32 v4, v33, 16, 1
	v_add3_u32 v4, v33, v4, s41
	v_bfe_u32 v21, v35, 16, 1
	v_lshrrev_b32_e32 v4, 16, v4
	v_add3_u32 v21, v35, v21, s41
	v_and_or_b32 v35, v21, s42, v4
	v_bfe_u32 v4, v36, 16, 1
	v_add3_u32 v4, v36, v4, s41
	v_bfe_u32 v21, v37, 16, 1
	v_lshrrev_b32_e32 v4, 16, v4
	v_add3_u32 v21, v37, v21, s41
	v_and_or_b32 v36, v21, s42, v4
	v_bfe_u32 v4, v40, 16, 1
	v_add3_u32 v4, v40, v4, s41
	v_bfe_u32 v21, v41, 16, 1
	v_or_b32_e32 v40, v20, v25
	v_add3_u32 v21, v41, v21, s41
	v_ashrrev_i32_e32 v41, 31, v40
	v_lshrrev_b32_e32 v4, 16, v4
	v_lshlrev_b64 v[40:41], 12, v[40:41]
	v_and_or_b32 v37, v21, s42, v4
	v_lshl_add_u64 v[40:41], v[38:39], 0, v[40:41]
	global_store_dwordx4 v[40:41], v[34:37], off
	ds_read_b32 v4, v23 offset:96
	ds_read_b32 v21, v23 offset:228
	ds_read_b32 v33, v23 offset:360
	ds_read_b32 v35, v23 offset:492
	ds_read_b32 v36, v23 offset:624
	ds_read_b32 v37, v23 offset:756
	ds_read_b32 v40, v23 offset:888
	ds_read_b32 v41, v23 offset:1020
	s_waitcnt lgkmcnt(0)
	v_bfe_u32 v34, v4, 16, 1
	v_add3_u32 v4, v4, v34, s41
	v_bfe_u32 v34, v21, 16, 1
	v_lshrrev_b32_e32 v4, 16, v4
	v_add3_u32 v21, v21, v34, s41
	v_and_or_b32 v34, v21, s42, v4
	v_bfe_u32 v4, v33, 16, 1
	v_add3_u32 v4, v33, v4, s41
	v_bfe_u32 v21, v35, 16, 1
	v_lshrrev_b32_e32 v4, 16, v4
	v_add3_u32 v21, v35, v21, s41
	v_and_or_b32 v35, v21, s42, v4
	v_bfe_u32 v4, v36, 16, 1
	v_add3_u32 v4, v36, v4, s41
	v_bfe_u32 v21, v37, 16, 1
	v_lshrrev_b32_e32 v4, 16, v4
	v_add3_u32 v21, v37, v21, s41
	v_and_or_b32 v36, v21, s42, v4
	v_bfe_u32 v4, v40, 16, 1
	v_add3_u32 v4, v40, v4, s41
	v_bfe_u32 v21, v41, 16, 1
	v_lshrrev_b32_e32 v4, 16, v4
	v_add3_u32 v21, v41, v21, s41
	v_or_b32_e32 v20, v20, v26
	v_and_or_b32 v37, v21, s42, v4
	v_ashrrev_i32_e32 v21, 31, v20
	v_lshlrev_b64 v[20:21], 12, v[20:21]
	v_lshl_add_u64 v[20:21], v[38:39], 0, v[20:21]
	global_store_dwordx4 v[20:21], v[34:37], off
	s_waitcnt lgkmcnt(0)
	v_readlane_b32 s61, v251, 22
	v_readlane_b32 s62, v251, 23
	v_readlane_b32 s63, v251, 24
	v_readlane_b32 s64, v251, 25
	v_readlane_b32 s65, v251, 26
	v_readlane_b32 s66, v251, 27
	v_readlane_b32 s67, v251, 28
	v_readlane_b32 s68, v251, 29
	v_readlane_b32 s69, v251, 30
	v_readlane_b32 s72, v251, 33
	v_readlane_b32 s73, v251, 34
	v_readlane_b32 s74, v251, 35
	v_readlane_b32 s75, v251, 36
	s_branch .LBB0_21

;     ...
;     const int nblk = N / 32, kb = item / nblk, nb = item % nblk, k0 = 64 * kb, n0 = 32 * nb;
;     float tv_[32];
; #pragma unroll
;     for (int i = 0; i < 32; ++i) tv_[i] = W[(size_t)(k0 + 2 * i + (lane >> 5)) * N + n0 + (lane & 31)];
; #pragma unroll
;     for (int i = 0; i < 32; ++i) scr[(2 * i + (lane >> 5)) * 33 + (lane & 31)] = tv_[i];
; __device__ __forceinline__ void convert_range(LAS unsigned char* lds, const Params& p, const int lo, const int hi, const int gw, const int NGW) {
;     ...
;     for (int it = lo + gw; it < hi; it += NGW) {
;         int r = it;
;         if (r < 2 * I_IN) { const int l = r / I_IN; r -= l * I_IN; p0_transpose_item(p.in[5] + (size_t)l * DM * NC, DM, NC, (bf16*)(ws + WS_WIN + l * SZ_WIN), scr, r, lane); continue; } r -= 2 * I_IN;
.LBB0_49:
	v_mul_hi_i32 v10, v28, s7
	v_lshrrev_b32_e32 v11, 31, v10
	v_ashrrev_i32_e32 v10, 12, v10
	v_add_u32_e32 v12, v10, v11
	v_mul_i32_i24_e32 v29, 0xffffd800, v12
	v_add_u32_e32 v29, v29, v28
	v_mul_hi_i32 v30, v29, s7
	v_lshrrev_b32_e32 v31, 31, v30
	v_ashrrev_i32_e32 v30, 7, v30
	v_add_u32_e32 v30, v30, v31
	v_mul_i32_i24_e32 v31, 0x140, v30
	v_lshlrev_b32_e32 v30, 6, v30
	v_sub_u32_e32 v29, v29, v31
	v_mad_i64_i32 v[10:11], s[18:19], v12, s14, v[4:5]
	v_mad_i64_i32 v[12:13], s[18:19], v12, s15, v[6:7]
	v_ashrrev_i32_e32 v31, 31, v30
	v_lshlrev_b32_e32 v32, 5, v29
	v_or_b32_e32 v40, v30, v1
	v_lshl_add_u64 v[12:13], v[30:31], 1, v[12:13]
	v_ashrrev_i32_e32 v33, 31, v32
	v_or_b32_e32 v30, v32, v14
	v_or_b32_e32 v34, v32, v16
	v_or_b32_e32 v36, v32, v17
	v_or_b32_e32 v38, v32, v18
	v_lshl_add_u64 v[10:11], v[32:33], 2, v[10:11]
	v_ashrrev_i32_e32 v31, 31, v30
	v_ashrrev_i32_e32 v35, 31, v34
	v_ashrrev_i32_e32 v37, 31, v36
	v_ashrrev_i32_e32 v39, 31, v38
	v_or_b32_e32 v29, 2, v40
	v_or_b32_e32 v41, 4, v40
	v_or_b32_e32 v42, 6, v40
	v_or_b32_e32 v44, 8, v40
	v_or_b32_e32 v46, 10, v40
	v_or_b32_e32 v48, 12, v40
	v_or_b32_e32 v50, 14, v40
	v_or_b32_e32 v52, 16, v40
	v_or_b32_e32 v54, 18, v40
	v_or_b32_e32 v56, 20, v40
	v_or_b32_e32 v58, 22, v40
	v_or_b32_e32 v60, 24, v40
	v_or_b32_e32 v62, 26, v40
	v_or_b32_e32 v64, 28, v40
	v_or_b32_e32 v66, 30, v40
	v_or_b32_e32 v68, 32, v40
	v_or_b32_e32 v70, 34, v40
	v_or_b32_e32 v72, 36, v40
	v_or_b32_e32 v74, 38, v40
	v_or_b32_e32 v76, 40, v40
	v_or_b32_e32 v78, 42, v40
	v_or_b32_e32 v80, 44, v40
	v_or_b32_e32 v82, 46, v40
	v_or_b32_e32 v84, 48, v40
	v_or_b32_e32 v86, 50, v40
	v_or_b32_e32 v88, 52, v40
	v_or_b32_e32 v90, 54, v40
	v_or_b32_e32 v92, 56, v40
	v_or_b32_e32 v94, 58, v40
	v_or_b32_e32 v96, 60, v40
	v_or_b32_e32 v98, 62, v40
	v_lshl_add_u64 v[12:13], v[12:13], 0, v[8:9]
	v_lshl_add_u64 v[10:11], v[10:11], 0, v[2:3]
	v_lshlrev_b64 v[30:31], 12, v[30:31]
	v_lshlrev_b64 v[32:33], 12, v[34:35]
	v_lshlrev_b64 v[34:35], 12, v[36:37]
	v_lshlrev_b64 v[36:37], 12, v[38:39]
	v_lshl_add_u64 v[30:31], v[12:13], 0, v[30:31]
	v_lshl_add_u64 v[32:33], v[12:13], 0, v[32:33]
	v_lshl_add_u64 v[34:35], v[12:13], 0, v[34:35]
	v_lshl_add_u64 v[36:37], v[12:13], 0, v[36:37]
	v_mad_i64_i32 v[12:13], s[18:19], v40, s12, v[10:11]
	v_mad_i64_i32 v[38:39], s[18:19], v29, s12, v[10:11]
	v_mad_i64_i32 v[40:41], s[18:19], v41, s12, v[10:11]
	v_mad_i64_i32 v[42:43], s[18:19], v42, s12, v[10:11]
	v_mad_i64_i32 v[44:45], s[18:19], v44, s12, v[10:11]
	v_mad_i64_i32 v[46:47], s[18:19], v46, s12, v[10:11]
	v_mad_i64_i32 v[48:49], s[18:19], v48, s12, v[10:11]
	v_mad_i64_i32 v[50:51], s[18:19], v50, s12, v[10:11]
	v_mad_i64_i32 v[52:53], s[18:19], v52, s12, v[10:11]
	v_mad_i64_i32 v[54:55], s[18:19], v54, s12, v[10:11]
	v_mad_i64_i32 v[56:57], s[18:19], v56, s12, v[10:11]
	v_mad_i64_i32 v[58:59], s[18:19], v58, s12, v[10:11]
	v_mad_i64_i32 v[60:61], s[18:19], v60, s12, v[10:11]
	v_mad_i64_i32 v[62:63], s[18:19], v62, s12, v[10:11]
	v_mad_i64_i32 v[64:65], s[18:19], v64, s12, v[10:11]
	v_mad_i64_i32 v[66:67], s[18:19], v66, s12, v[10:11]
	v_mad_i64_i32 v[68:69], s[18:19], v68, s12, v[10:11]
	v_mad_i64_i32 v[70:71], s[18:19], v70, s12, v[10:11]
	v_mad_i64_i32 v[72:73], s[18:19], v72, s12, v[10:11]
	v_mad_i64_i32 v[74:75], s[18:19], v74, s12, v[10:11]
	v_mad_i64_i32 v[76:77], s[18:19], v76, s12, v[10:11]
	v_mad_i64_i32 v[78:79], s[18:19], v78, s12, v[10:11]
	v_mad_i64_i32 v[80:81], s[18:19], v80, s12, v[10:11]
	v_mad_i64_i32 v[82:83], s[18:19], v82, s12, v[10:11]
	v_mad_i64_i32 v[84:85], s[18:19], v84, s12, v[10:11]
	v_mad_i64_i32 v[86:87], s[18:19], v86, s12, v[10:11]
	v_mad_i64_i32 v[88:89], s[18:19], v88, s12, v[10:11]
	v_mad_i64_i32 v[90:91], s[18:19], v90, s12, v[10:11]
	v_mad_i64_i32 v[92:93], s[18:19], v92, s12, v[10:11]
	v_mad_i64_i32 v[94:95], s[18:19], v94, s12, v[10:11]
	v_mad_i64_i32 v[96:97], s[18:19], v96, s12, v[10:11]
	v_mad_i64_i32 v[10:11], s[18:19], v98, s12, v[10:11]
	global_load_dword v12, v[12:13], off
	s_nop 0
	global_load_dword v13, v[38:39], off
	global_load_dword v29, v[40:41], off
	s_nop 0
	global_load_dword v38, v[42:43], off
	global_load_dword v39, v[44:45], off
	global_load_dword v40, v[46:47], off
	global_load_dword v41, v[48:49], off
	s_nop 0
	global_load_dword v42, v[50:51], off
	global_load_dword v43, v[52:53], off
	global_load_dword v44, v[54:55], off
	global_load_dword v45, v[56:57], off
	global_load_dword v46, v[58:59], off
	global_load_dword v47, v[60:61], off
	global_load_dword v48, v[62:63], off
	global_load_dword v49, v[64:65], off
	global_load_dword v50, v[66:67], off
	global_load_dword v51, v[68:69], off
	global_load_dword v52, v[70:71], off
	global_load_dword v53, v[72:73], off
	global_load_dword v54, v[74:75], off
	global_load_dword v55, v[76:77], off
	global_load_dword v56, v[78:79], off
	global_load_dword v57, v[80:81], off
	global_load_dword v58, v[82:83], off
	global_load_dword v59, v[84:85], off
	global_load_dword v60, v[86:87], off
	global_load_dword v61, v[88:89], off
	global_load_dword v62, v[90:91], off
	global_load_dword v63, v[92:93], off
	global_load_dword v64, v[94:95], off
	global_load_dword v65, v[96:97], off
	s_nop 0
	global_load_dword v10, v[10:11], off
	s_waitcnt vmcnt(30)
	ds_write2_b32 v19, v12, v13 offset1:66
	s_waitcnt vmcnt(28)
	ds_write2_b32 v19, v29, v38 offset0:132 offset1:198
	s_waitcnt vmcnt(26)
; #define LAS __attribute__((address_space(3)))
; #define LDS_WAIT() asm volatile("s_waitcnt lgkmcnt(0)" ::: "memory")
; __device__ __forceinline__ unsigned pk2(float lo, float hi) { return f2bf(lo) | (f2bf(hi) << 16); }
;     ...
;     for (int i = 0; i < 32; ++i) scr[(2 * i + (lane >> 5)) * 33 + (lane & 31)] = tv_[i];
;     LDS_WAIT(); asm volatile("" ::: "memory");
;     const int c = lane & 7;
; #pragma unroll
;     for (int j = 0; j < 4; ++j) { const int n = (lane >> 3) + 8 * j; const LAS float* s = scr + (8 * c) * 33 + n;
;         v4u o; o.x = pk2(s[0 * 33], s[1 * 33]); o.y = pk2(s[2 * 33], s[3 * 33]); o.z = pk2(s[4 * 33], s[5 * 33]); o.w = pk2(s[6 * 33], s[7 * 33]);
;         *(v4u*)(WT + (size_t)(n0 + n) * ldw + koff + k0 + 8 * c) = o; }
;     LDS_WAIT(); asm volatile("" ::: "memory");
; __device__ __forceinline__ void convert_range(LAS unsigned char* lds, const Params& p, const int lo, const int hi, const int gw, const int NGW) {
;     ...
;     for (int it = lo + gw; it < hi; it += NGW) {
	ds_write2_b32 v20, v39, v40 offset0:8 offset1:74
	s_waitcnt vmcnt(24)
	ds_write2_b32 v20, v41, v42 offset0:140 offset1:206
	s_waitcnt vmcnt(22)
	ds_write2_b32 v21, v43, v44 offset0:16 offset1:82
	s_waitcnt vmcnt(20)
	ds_write2_b32 v21, v45, v46 offset0:148 offset1:214
	s_waitcnt vmcnt(18)
	ds_write2_b32 v23, v47, v48 offset0:24 offset1:90
	s_waitcnt vmcnt(16)
	ds_write2_b32 v23, v49, v50 offset0:156 offset1:222
	s_waitcnt vmcnt(14)
	ds_write2_b32 v24, v51, v52 offset0:32 offset1:98
	s_waitcnt vmcnt(12)
	ds_write2_b32 v24, v53, v54 offset0:164 offset1:230
	s_waitcnt vmcnt(10)
	ds_write2_b32 v25, v55, v56 offset0:40 offset1:106
	s_waitcnt vmcnt(8)
	ds_write2_b32 v25, v57, v58 offset0:172 offset1:238
	s_waitcnt vmcnt(6)
	ds_write2_b32 v26, v59, v60 offset0:48 offset1:114
	s_waitcnt vmcnt(4)
	ds_write2_b32 v26, v61, v62 offset0:180 offset1:246
	s_waitcnt vmcnt(2)
	ds_write2_b32 v27, v63, v64 offset0:56 offset1:122
	s_waitcnt vmcnt(0)
	ds_write2_b32 v27, v65, v10 offset0:188 offset1:254
	s_waitcnt lgkmcnt(0)
	ds_read_b32 v10, v15
	ds_read_b32 v11, v15 offset:132
	ds_read_b32 v12, v15 offset:264
	ds_read_b32 v13, v15 offset:396
	ds_read_b32 v29, v15 offset:528
	ds_read_b32 v38, v15 offset:660
	ds_read_b32 v39, v15 offset:792
	ds_read_b32 v40, v15 offset:924
	s_waitcnt lgkmcnt(0)
	v_bfe_u32 v41, v10, 16, 1
	v_bfe_u32 v43, v12, 16, 1
	v_bfe_u32 v45, v29, 16, 1
	v_bfe_u32 v47, v39, 16, 1
	v_bfe_u32 v42, v11, 16, 1
	v_bfe_u32 v44, v13, 16, 1
	v_bfe_u32 v46, v38, 16, 1
	v_bfe_u32 v48, v40, 16, 1
	v_add3_u32 v10, v10, v41, s13
	v_add3_u32 v12, v12, v43, s13
	v_add3_u32 v29, v29, v45, s13
	v_add3_u32 v39, v39, v47, s13
	v_add3_u32 v11, v11, v42, s13
	v_add3_u32 v13, v13, v44, s13
	v_add3_u32 v38, v38, v46, s13
	v_add3_u32 v40, v40, v48, s13
	v_lshrrev_b32_e32 v10, 16, v10
	v_lshrrev_b32_e32 v12, 16, v12
	v_lshrrev_b32_e32 v29, 16, v29
	v_lshrrev_b32_e32 v39, 16, v39
	v_and_or_b32 v10, v11, s16, v10
	v_and_or_b32 v11, v13, s16, v12
	v_and_or_b32 v12, v38, s16, v29
	v_and_or_b32 v13, v40, s16, v39
	global_store_dwordx4 v[30:31], v[10:13], off
	ds_read_b32 v10, v15 offset:32
	ds_read_b32 v11, v15 offset:164
	ds_read_b32 v12, v15 offset:296
	ds_read_b32 v13, v15 offset:428
	ds_read_b32 v29, v15 offset:560
	ds_read_b32 v30, v15 offset:692
	ds_read_b32 v31, v15 offset:824
	ds_read_b32 v38, v15 offset:956
	s_waitcnt lgkmcnt(0)
	v_bfe_u32 v39, v10, 16, 1
	v_bfe_u32 v41, v12, 16, 1
	v_bfe_u32 v43, v29, 16, 1
	v_bfe_u32 v45, v31, 16, 1
	v_bfe_u32 v40, v11, 16, 1
	v_bfe_u32 v42, v13, 16, 1
	v_bfe_u32 v44, v30, 16, 1
	v_bfe_u32 v46, v38, 16, 1
	v_add3_u32 v10, v10, v39, s13
	v_add3_u32 v12, v12, v41, s13
	v_add3_u32 v29, v29, v43, s13
	v_add3_u32 v31, v31, v45, s13
	v_add3_u32 v11, v11, v40, s13
	v_add3_u32 v13, v13, v42, s13
	v_add3_u32 v30, v30, v44, s13
	v_add3_u32 v38, v38, v46, s13
	v_lshrrev_b32_e32 v10, 16, v10
	v_lshrrev_b32_e32 v12, 16, v12
	v_lshrrev_b32_e32 v29, 16, v29
	v_lshrrev_b32_e32 v31, 16, v31
	v_and_or_b32 v10, v11, s16, v10
	v_and_or_b32 v11, v13, s16, v12
	v_and_or_b32 v12, v30, s16, v29
	v_and_or_b32 v13, v38, s16, v31
	global_store_dwordx4 v[32:33], v[10:13], off
	ds_read_b32 v10, v15 offset:64
	ds_read_b32 v11, v15 offset:196
	ds_read_b32 v12, v15 offset:328
	ds_read_b32 v13, v15 offset:460
	ds_read_b32 v29, v15 offset:592
	ds_read_b32 v30, v15 offset:724
	ds_read_b32 v31, v15 offset:856
	ds_read_b32 v32, v15 offset:988
	s_waitcnt lgkmcnt(0)
	v_bfe_u32 v33, v10, 16, 1
	v_bfe_u32 v39, v12, 16, 1
	v_bfe_u32 v41, v29, 16, 1
	v_bfe_u32 v43, v31, 16, 1
	v_bfe_u32 v38, v11, 16, 1
	v_bfe_u32 v40, v13, 16, 1
	v_bfe_u32 v42, v30, 16, 1
	v_bfe_u32 v44, v32, 16, 1
	v_add3_u32 v10, v10, v33, s13
	v_add3_u32 v12, v12, v39, s13
	v_add3_u32 v29, v29, v41, s13
	v_add3_u32 v31, v31, v43, s13
	v_add3_u32 v11, v11, v38, s13
	v_add3_u32 v13, v13, v40, s13
	v_add3_u32 v30, v30, v42, s13
	v_add3_u32 v32, v32, v44, s13
	v_lshrrev_b32_e32 v10, 16, v10
	v_lshrrev_b32_e32 v12, 16, v12
	v_lshrrev_b32_e32 v29, 16, v29
	v_lshrrev_b32_e32 v31, 16, v31
	v_and_or_b32 v10, v11, s16, v10
	v_and_or_b32 v11, v13, s16, v12
	v_and_or_b32 v12, v30, s16, v29
	v_and_or_b32 v13, v32, s16, v31
	global_store_dwordx4 v[34:35], v[10:13], off
	ds_read_b32 v10, v15 offset:96
	ds_read_b32 v11, v15 offset:228
	ds_read_b32 v12, v15 offset:360
	ds_read_b32 v13, v15 offset:492
	ds_read_b32 v29, v15 offset:624
	ds_read_b32 v30, v15 offset:756
	ds_read_b32 v31, v15 offset:888
	ds_read_b32 v32, v15 offset:1020
	s_waitcnt lgkmcnt(0)
	v_bfe_u32 v33, v10, 16, 1
	v_bfe_u32 v35, v12, 16, 1
	v_bfe_u32 v39, v29, 16, 1
	v_bfe_u32 v41, v31, 16, 1
	v_bfe_u32 v34, v11, 16, 1
	v_bfe_u32 v38, v13, 16, 1
	v_bfe_u32 v40, v30, 16, 1
	v_bfe_u32 v42, v32, 16, 1
	v_add3_u32 v10, v10, v33, s13
	v_add3_u32 v12, v12, v35, s13
	v_add3_u32 v29, v29, v39, s13
	v_add3_u32 v31, v31, v41, s13
	v_add3_u32 v11, v11, v34, s13
	v_add3_u32 v13, v13, v38, s13
	v_add3_u32 v30, v30, v40, s13
	v_add3_u32 v32, v32, v42, s13
	v_lshrrev_b32_e32 v10, 16, v10
	v_lshrrev_b32_e32 v12, 16, v12
	v_lshrrev_b32_e32 v29, 16, v29
	v_lshrrev_b32_e32 v31, 16, v31
	v_and_or_b32 v10, v11, s16, v10
	v_and_or_b32 v11, v13, s16, v12
	v_and_or_b32 v12, v30, s16, v29
	v_and_or_b32 v13, v32, s16, v31
	global_store_dwordx4 v[36:37], v[10:13], off
	s_waitcnt lgkmcnt(0)
	v_add_u32_e32 v28, s6, v28
	v_cmp_lt_i32_e32 vcc, s17, v28
	s_or_b64 s[10:11], vcc, s[10:11]
	s_andn2_b64 exec, exec, s[10:11]
	s_cbranch_execnz .LBB0_49

;     ...
;     const int nblk = N / 32, kb = item / nblk, nb = item % nblk, k0 = 64 * kb, n0 = 32 * nb;
;     float tv_[32];
; #pragma unroll
;     for (int i = 0; i < 32; ++i) tv_[i] = W[(size_t)(k0 + 2 * i + (lane >> 5)) * N + n0 + (lane & 31)];
; #pragma unroll
;     for (int i = 0; i < 32; ++i) scr[(2 * i + (lane >> 5)) * 33 + (lane & 31)] = tv_[i];
; __device__ __forceinline__ void convert_range(LAS unsigned char* lds, const Params& p, const int lo, const int hi, const int gw, const int NGW) {
;     ...
;     for (int it = lo + gw; it < hi; it += NGW) {
;         int r = it;
;         if (r < 2 * I_IN) { const int l = r / I_IN; r -= l * I_IN; p0_transpose_item(p.in[5] + (size_t)l * DM * NC, DM, NC, (bf16*)(ws + WS_WIN + l * SZ_WIN), scr, r, lane); continue; } r -= 2 * I_IN;
;         if (r < 2 * I_PA) { const int l = r / I_PA; r -= l * I_PA; p0_transpose_item(p.in[16] + (size_t)l * PW * DM, PW, DM, (bf16*)(ws + WS_WCAT + l * SZ_WCAT), scr, r, lane, KCAT, 0); continue; } r -= 2 * I_PA;
;         if (r < 2 * I_PB) { const int l = r / I_PB; r -= l * I_PB; p0_transpose_item(p.in[17] + (size_t)l * LW * DM, LW, DM, (bf16*)(ws + WS_WCAT + l * SZ_WCAT), scr, r, lane, KCAT, PW); continue; } r -= 2 * I_PB;
;         if (r < 2 * I_OUT) { const int l = r / I_OUT; r -= l * I_OUT; p0_transpose_item(p.in[18] + (size_t)l * DM * DM, DM, DM, (bf16*)(ws + WS_WOUT + l * SZ_WOUT), scr, r, lane); continue; } r -= 2 * I_OUT;
;         if (r < I_PL) { const int mi = r / 32; r -= mi * 32; p0_transpose_item(p.in[7] + (size_t)mi * 65536, 256, 256, (bf16*)(ws + WS_POOLW) + (size_t)mi * 65536, scr, r, lane); continue; } r -= I_PL;
;         if (r < I_LR) { const int mi = r / 8; r -= mi * 8; p0_transpose_item(p.in[11] + (size_t)mi * 16384, 128, 128, (bf16*)(ws + WS_WA) + (size_t)mi * 16384, scr, r, lane); continue; } r -= I_LR;
;         { const int mi = r / 8; r -= mi * 8; p0_transpose_item(p.in[13] + (size_t)mi * 16384, 128, 128, (bf16*)(ws + WS_WX) + (size_t)mi * 16384, scr, r, lane); }
.LBB0_53:
	v_add_u32_e32 v20, 0x7a00, v27
	s_movk_i32 s24, 0x4fff
	v_cmp_lt_i32_e32 vcc, s24, v20
	s_and_saveexec_b64 s[24:25], vcc
	s_xor_b64 s[24:25], exec, s[24:25]
	s_cbranch_execz .LBB0_75
	s_movk_i32 s26, 0x57ff
	v_cmp_lt_u32_e32 vcc, s26, v20
	s_and_saveexec_b64 s[26:27], vcc
	s_xor_b64 s[26:27], exec, s[26:27]
	s_cbranch_execz .LBB0_72
	s_movk_i32 s28, 0x67ff
	v_cmp_lt_u32_e32 vcc, s28, v20
	s_and_saveexec_b64 s[28:29], vcc
	s_xor_b64 s[28:29], exec, s[28:29]
	s_cbranch_execz .LBB0_69
	s_movk_i32 s30, 0x77ff
	v_cmp_lt_u32_e32 vcc, s30, v20
	s_and_saveexec_b64 s[30:31], vcc
	s_xor_b64 s[30:31], exec, s[30:31]
	s_cbranch_execz .LBB0_66
	s_movk_i32 s34, 0x78ff
	v_cmp_lt_u32_e32 vcc, s34, v20
	s_and_saveexec_b64 s[34:35], vcc
	s_xor_b64 s[34:35], exec, s[34:35]
	s_cbranch_execz .LBB0_63
	s_movk_i32 s36, 0x79ff
	v_cmp_lt_u32_e32 vcc, s36, v20
	v_and_b32_e32 v20, 64, v28
	v_or_b32_e32 v4, v20, v1
	v_lshlrev_b32_e32 v21, 7, v4
	s_and_saveexec_b64 s[36:37], vcc
	s_xor_b64 s[36:37], exec, s[36:37]
	s_cbranch_execz .LBB0_60
	v_lshrrev_b32_e32 v4, 3, v27
	v_lshlrev_b64 v[36:37], 16, v[4:5]
	v_lshlrev_b64 v[34:35], 15, v[4:5]
	v_lshl_add_u64 v[36:37], v[16:17], 0, v[36:37]
	v_lshlrev_b32_e32 v4, 2, v21
	v_lshl_add_u64 v[36:37], v[36:37], 0, v[4:5]
	v_add_co_u32_e32 v38, vcc, 0x1000, v36
	v_add_u32_e32 v66, 0x1000, v3
	s_nop 0
	v_addc_co_u32_e32 v39, vcc, 0, v37, vcc
	global_load_dword v4, v[36:37], off
	global_load_dword v21, v[36:37], off offset:1024
	global_load_dword v33, v[36:37], off offset:2048
	global_load_dword v42, v[36:37], off offset:3072
	global_load_dword v43, v[38:39], off
	global_load_dword v44, v[38:39], off offset:1024
	global_load_dword v45, v[38:39], off offset:2048
	global_load_dword v46, v[38:39], off offset:3072
	v_add_co_u32_e32 v38, vcc, 0x2000, v36
	v_add_u32_e32 v67, 0x1400, v3
	s_nop 0
	v_addc_co_u32_e32 v39, vcc, 0, v37, vcc
	v_add_co_u32_e32 v40, vcc, 0x3000, v36
	v_add_u32_e32 v68, 0x1800, v3
	s_nop 0
	v_addc_co_u32_e32 v41, vcc, 0, v37, vcc
	global_load_dword v47, v[38:39], off
	global_load_dword v48, v[38:39], off offset:1024
	global_load_dword v49, v[38:39], off offset:2048
	global_load_dword v50, v[38:39], off offset:3072
	global_load_dword v51, v[40:41], off
	global_load_dword v52, v[40:41], off offset:1024
	global_load_dword v53, v[40:41], off offset:2048
	global_load_dword v54, v[40:41], off offset:3072
	v_add_co_u32_e32 v38, vcc, 0x4000, v36
	v_add_u32_e32 v69, 0x1c00, v3
	s_nop 0
	v_addc_co_u32_e32 v39, vcc, 0, v37, vcc
	v_add_co_u32_e32 v40, vcc, 0x5000, v36
	v_lshl_add_u64 v[34:35], s[12:13], 0, v[34:35]
	s_nop 0
	v_addc_co_u32_e32 v41, vcc, 0, v37, vcc
	global_load_dword v55, v[38:39], off
	global_load_dword v56, v[38:39], off offset:1024
	global_load_dword v57, v[38:39], off offset:2048
	global_load_dword v58, v[38:39], off offset:3072
	global_load_dword v59, v[40:41], off
	global_load_dword v60, v[40:41], off offset:1024
	global_load_dword v61, v[40:41], off offset:2048
	s_nop 0
	global_load_dword v40, v[40:41], off offset:3072
	v_add_co_u32_e32 v38, vcc, 0x6000, v36
	s_nop 1
	v_addc_co_u32_e32 v39, vcc, 0, v37, vcc
	v_add_co_u32_e32 v36, vcc, 0x7000, v36
	s_nop 1
	v_addc_co_u32_e32 v37, vcc, 0, v37, vcc
	global_load_dword v41, v[38:39], off
	global_load_dword v62, v[38:39], off offset:1024
	global_load_dword v63, v[38:39], off offset:2048
	s_nop 0
	global_load_dword v38, v[38:39], off offset:3072
	s_nop 0
	global_load_dword v39, v[36:37], off
	global_load_dword v64, v[36:37], off offset:1024
	global_load_dword v65, v[36:37], off offset:2048
	s_nop 0
	global_load_dword v36, v[36:37], off offset:3072
	v_add_u32_e32 v37, 0xc00, v3
	s_waitcnt vmcnt(30)
	ds_write2_b32 v3, v4, v21 offset1:66
	s_waitcnt vmcnt(28)
	ds_write2_b32 v3, v33, v42 offset0:132 offset1:198
	s_waitcnt vmcnt(26)
	ds_write2_b32 v31, v43, v44 offset0:8 offset1:74
	s_waitcnt vmcnt(24)
	ds_write2_b32 v31, v45, v46 offset0:140 offset1:206
	s_waitcnt vmcnt(22)
	ds_write2_b32 v32, v47, v48 offset0:16 offset1:82
	s_waitcnt vmcnt(20)
	ds_write2_b32 v32, v49, v50 offset0:148 offset1:214
	s_waitcnt vmcnt(18)
	ds_write2_b32 v37, v51, v52 offset0:24 offset1:90
	s_waitcnt vmcnt(16)
	ds_write2_b32 v37, v53, v54 offset0:156 offset1:222
	s_waitcnt vmcnt(14)
	ds_write2_b32 v66, v55, v56 offset0:32 offset1:98
	s_waitcnt vmcnt(12)
	ds_write2_b32 v66, v57, v58 offset0:164 offset1:230
	s_waitcnt vmcnt(10)
	ds_write2_b32 v67, v59, v60 offset0:40 offset1:106
	s_waitcnt vmcnt(8)
	ds_write2_b32 v67, v61, v40 offset0:172 offset1:238
	s_waitcnt vmcnt(6)
	ds_write2_b32 v68, v41, v62 offset0:48 offset1:114
	s_waitcnt vmcnt(4)
	ds_write2_b32 v68, v63, v38 offset0:180 offset1:246
	s_waitcnt vmcnt(2)
	ds_write2_b32 v69, v39, v64 offset0:56 offset1:122
	s_waitcnt vmcnt(0)
	ds_write2_b32 v69, v65, v36 offset0:188 offset1:254
	s_waitcnt lgkmcnt(0)
	v_lshlrev_b32_e32 v4, 1, v20
	v_lshl_add_u64 v[20:21], v[34:35], 0, v[4:5]
	v_lshlrev_b32_e32 v4, 1, v6
	v_lshl_add_u64 v[20:21], v[20:21], 0, v[4:5]
	ds_read_b32 v4, v23
	ds_read_b32 v33, v23 offset:132
	ds_read_b32 v35, v23 offset:264
	ds_read_b32 v36, v23 offset:396
	ds_read_b32 v37, v23 offset:528
	ds_read_b32 v38, v23 offset:660
	ds_read_b32 v39, v23 offset:792
	ds_read_b32 v40, v23 offset:924
	s_waitcnt lgkmcnt(0)
; #define LAS __attribute__((address_space(3)))
; #define LDS_WAIT() asm volatile("s_waitcnt lgkmcnt(0)" ::: "memory")
; __device__ __forceinline__ unsigned pk2(float lo, float hi) { return f2bf(lo) | (f2bf(hi) << 16); }
;     ...
;     const int c = lane & 7;
; #pragma unroll
;     for (int j = 0; j < 4; ++j) { const int n = (lane >> 3) + 8 * j; const LAS float* s = scr + (8 * c) * 33 + n;
;         v4u o; o.x = pk2(s[0 * 33], s[1 * 33]); o.y = pk2(s[2 * 33], s[3 * 33]); o.z = pk2(s[4 * 33], s[5 * 33]); o.w = pk2(s[6 * 33], s[7 * 33]);
;         *(v4u*)(WT + (size_t)(n0 + n) * ldw + koff + k0 + 8 * c) = o; }
;     LDS_WAIT(); asm volatile("" ::: "memory");
; __device__ __forceinline__ void convert_range(LAS unsigned char* lds, const Params& p, const int lo, const int hi, const int gw, const int NGW) {
;     ...
;         if (r < I_LR) { const int mi = r / 8; r -= mi * 8; p0_transpose_item(p.in[11] + (size_t)mi * 16384, 128, 128, (bf16*)(ws + WS_WA) + (size_t)mi * 16384, scr, r, lane); continue; } r -= I_LR;
	v_bfe_u32 v34, v4, 16, 1
	v_add3_u32 v4, v4, v34, s38
	v_bfe_u32 v34, v33, 16, 1
	v_lshrrev_b32_e32 v4, 16, v4
	v_add3_u32 v33, v33, v34, s38
	v_and_or_b32 v34, v33, s39, v4
	v_bfe_u32 v4, v35, 16, 1
	v_add3_u32 v4, v35, v4, s38
	v_bfe_u32 v33, v36, 16, 1
	v_lshrrev_b32_e32 v4, 16, v4
	v_add3_u32 v33, v36, v33, s38
	v_and_or_b32 v35, v33, s39, v4
	v_bfe_u32 v4, v37, 16, 1
	v_add3_u32 v4, v37, v4, s38
	v_bfe_u32 v33, v38, 16, 1
	v_lshrrev_b32_e32 v4, 16, v4
	v_add3_u32 v33, v38, v33, s38
	v_and_or_b32 v36, v33, s39, v4
	v_bfe_u32 v4, v39, 16, 1
	v_add3_u32 v4, v39, v4, s38
	v_bfe_u32 v33, v40, 16, 1
	v_lshrrev_b32_e32 v4, 16, v4
	v_add3_u32 v33, v40, v33, s38
	v_and_or_b32 v37, v33, s39, v4
	v_lshl_add_u64 v[38:39], v[20:21], 0, v[8:9]
	global_store_dwordx4 v[38:39], v[34:37], off
	ds_read_b32 v4, v23 offset:32
	ds_read_b32 v33, v23 offset:164
	ds_read_b32 v35, v23 offset:296
	ds_read_b32 v36, v23 offset:428
	ds_read_b32 v37, v23 offset:560
	ds_read_b32 v38, v23 offset:692
	ds_read_b32 v39, v23 offset:824
	ds_read_b32 v40, v23 offset:956
	s_waitcnt lgkmcnt(0)
	v_bfe_u32 v34, v4, 16, 1
	v_add3_u32 v4, v4, v34, s38
	v_bfe_u32 v34, v33, 16, 1
	v_lshrrev_b32_e32 v4, 16, v4
	v_add3_u32 v33, v33, v34, s38
	v_and_or_b32 v34, v33, s39, v4
	v_bfe_u32 v4, v35, 16, 1
	v_add3_u32 v4, v35, v4, s38
	v_bfe_u32 v33, v36, 16, 1
	v_lshrrev_b32_e32 v4, 16, v4
	v_add3_u32 v33, v36, v33, s38
	v_and_or_b32 v35, v33, s39, v4
	v_bfe_u32 v4, v37, 16, 1
	v_add3_u32 v4, v37, v4, s38
	v_bfe_u32 v33, v38, 16, 1
	v_lshrrev_b32_e32 v4, 16, v4
	v_add3_u32 v33, v38, v33, s38
	v_and_or_b32 v36, v33, s39, v4
	v_bfe_u32 v4, v39, 16, 1
	v_add3_u32 v4, v39, v4, s38
	v_bfe_u32 v33, v40, 16, 1
	v_lshrrev_b32_e32 v4, 16, v4
	v_add3_u32 v33, v40, v33, s38
	v_and_or_b32 v37, v33, s39, v4
	v_lshl_add_u64 v[38:39], v[20:21], 0, v[10:11]
	global_store_dwordx4 v[38:39], v[34:37], off
	ds_read_b32 v4, v23 offset:64
	ds_read_b32 v33, v23 offset:196
	ds_read_b32 v35, v23 offset:328
	ds_read_b32 v36, v23 offset:460
	ds_read_b32 v37, v23 offset:592
	ds_read_b32 v38, v23 offset:724
	ds_read_b32 v39, v23 offset:856
	ds_read_b32 v40, v23 offset:988
	s_waitcnt lgkmcnt(0)
	v_bfe_u32 v34, v4, 16, 1
	v_add3_u32 v4, v4, v34, s38
	v_bfe_u32 v34, v33, 16, 1
	v_lshrrev_b32_e32 v4, 16, v4
	v_add3_u32 v33, v33, v34, s38
	v_and_or_b32 v34, v33, s39, v4
	v_bfe_u32 v4, v35, 16, 1
	v_add3_u32 v4, v35, v4, s38
	v_bfe_u32 v33, v36, 16, 1
	v_lshrrev_b32_e32 v4, 16, v4
	v_add3_u32 v33, v36, v33, s38
	v_and_or_b32 v35, v33, s39, v4
	v_bfe_u32 v4, v37, 16, 1
	v_add3_u32 v4, v37, v4, s38
	v_bfe_u32 v33, v38, 16, 1
	v_lshrrev_b32_e32 v4, 16, v4
	v_add3_u32 v33, v38, v33, s38
	v_and_or_b32 v36, v33, s39, v4
	v_bfe_u32 v4, v39, 16, 1
	v_add3_u32 v4, v39, v4, s38
	v_bfe_u32 v33, v40, 16, 1
	v_lshrrev_b32_e32 v4, 16, v4
	v_add3_u32 v33, v40, v33, s38
	v_and_or_b32 v37, v33, s39, v4
	v_lshl_add_u64 v[38:39], v[20:21], 0, v[12:13]
	global_store_dwordx4 v[38:39], v[34:37], off
	ds_read_b32 v4, v23 offset:96
	ds_read_b32 v33, v23 offset:228
	ds_read_b32 v35, v23 offset:360
	ds_read_b32 v36, v23 offset:492
	ds_read_b32 v37, v23 offset:624
	ds_read_b32 v38, v23 offset:756
	ds_read_b32 v39, v23 offset:888
	ds_read_b32 v40, v23 offset:1020
	s_waitcnt lgkmcnt(0)
	v_bfe_u32 v34, v4, 16, 1
	v_add3_u32 v4, v4, v34, s38
	v_bfe_u32 v34, v33, 16, 1
	v_lshrrev_b32_e32 v4, 16, v4
	v_add3_u32 v33, v33, v34, s38
	v_and_or_b32 v34, v33, s39, v4
	v_bfe_u32 v4, v35, 16, 1
	v_add3_u32 v4, v35, v4, s38
	v_bfe_u32 v33, v36, 16, 1
	v_lshrrev_b32_e32 v4, 16, v4
	v_add3_u32 v33, v36, v33, s38
	v_and_or_b32 v35, v33, s39, v4
	v_bfe_u32 v4, v37, 16, 1
	v_add3_u32 v4, v37, v4, s38
	v_bfe_u32 v33, v38, 16, 1
	v_lshrrev_b32_e32 v4, 16, v4
	v_add3_u32 v33, v38, v33, s38
	v_and_or_b32 v36, v33, s39, v4
	v_bfe_u32 v4, v39, 16, 1
	v_add3_u32 v4, v39, v4, s38
	v_bfe_u32 v33, v40, 16, 1
	v_lshrrev_b32_e32 v4, 16, v4
	v_add3_u32 v33, v40, v33, s38
	v_and_or_b32 v37, v33, s39, v4
	v_lshl_add_u64 v[20:21], v[20:21], 0, v[14:15]
	global_store_dwordx4 v[20:21], v[34:37], off
	s_waitcnt lgkmcnt(0)
.LBB0_60:
	s_andn2_saveexec_b64 s[36:37], s[36:37]
	s_cbranch_execz .LBB0_62
	v_add_u32_e32 v4, 0x100, v27
	v_lshrrev_b32_e32 v4, 3, v4
	v_lshlrev_b64 v[36:37], 16, v[4:5]
	v_lshlrev_b64 v[34:35], 15, v[4:5]
	v_lshl_add_u64 v[36:37], v[18:19], 0, v[36:37]
	v_lshlrev_b32_e32 v4, 2, v21
	v_lshl_add_u64 v[36:37], v[36:37], 0, v[4:5]
	v_add_co_u32_e32 v38, vcc, 0x1000, v36
	v_add_u32_e32 v66, 0x1000, v3
	s_nop 0
	v_addc_co_u32_e32 v39, vcc, 0, v37, vcc
	global_load_dword v4, v[36:37], off
	global_load_dword v21, v[36:37], off offset:1024
	global_load_dword v33, v[36:37], off offset:2048
	global_load_dword v42, v[36:37], off offset:3072
	global_load_dword v43, v[38:39], off
	global_load_dword v44, v[38:39], off offset:1024
	global_load_dword v45, v[38:39], off offset:2048
	global_load_dword v46, v[38:39], off offset:3072
	v_add_co_u32_e32 v38, vcc, 0x2000, v36
	v_add_u32_e32 v67, 0x1400, v3
	s_nop 0
	v_addc_co_u32_e32 v39, vcc, 0, v37, vcc
	v_add_co_u32_e32 v40, vcc, 0x3000, v36
	v_add_u32_e32 v68, 0x1800, v3
	s_nop 0
	v_addc_co_u32_e32 v41, vcc, 0, v37, vcc
	global_load_dword v47, v[38:39], off
	global_load_dword v48, v[38:39], off offset:1024
	global_load_dword v49, v[38:39], off offset:2048
	global_load_dword v50, v[38:39], off offset:3072
	global_load_dword v51, v[40:41], off
	global_load_dword v52, v[40:41], off offset:1024
	global_load_dword v53, v[40:41], off offset:2048
	global_load_dword v54, v[40:41], off offset:3072
	v_add_co_u32_e32 v38, vcc, 0x4000, v36
	v_add_u32_e32 v69, 0x1c00, v3
	s_nop 0
	v_addc_co_u32_e32 v39, vcc, 0, v37, vcc
	v_add_co_u32_e32 v40, vcc, 0x5000, v36
	v_lshl_add_u64 v[34:35], s[14:15], 0, v[34:35]
	s_nop 0
	v_addc_co_u32_e32 v41, vcc, 0, v37, vcc
	global_load_dword v55, v[38:39], off
	global_load_dword v56, v[38:39], off offset:1024
	global_load_dword v57, v[38:39], off offset:2048
	global_load_dword v58, v[38:39], off offset:3072
	global_load_dword v59, v[40:41], off
	global_load_dword v60, v[40:41], off offset:1024
	global_load_dword v61, v[40:41], off offset:2048
	s_nop 0
	global_load_dword v40, v[40:41], off offset:3072
	v_add_co_u32_e32 v38, vcc, 0x6000, v36
	s_nop 1
	v_addc_co_u32_e32 v39, vcc, 0, v37, vcc
	v_add_co_u32_e32 v36, vcc, 0x7000, v36
	s_nop 1
	v_addc_co_u32_e32 v37, vcc, 0, v37, vcc
	global_load_dword v41, v[38:39], off
	global_load_dword v62, v[38:39], off offset:1024
	global_load_dword v63, v[38:39], off offset:2048
	s_nop 0
	global_load_dword v38, v[38:39], off offset:3072
	s_nop 0
	global_load_dword v39, v[36:37], off
	global_load_dword v64, v[36:37], off offset:1024
	global_load_dword v65, v[36:37], off offset:2048
	s_nop 0
	global_load_dword v36, v[36:37], off offset:3072
	v_add_u32_e32 v37, 0xc00, v3
	s_waitcnt vmcnt(30)
; #define LAS __attribute__((address_space(3)))
; #define LDS_WAIT() asm volatile("s_waitcnt lgkmcnt(0)" ::: "memory")
; __device__ __forceinline__ unsigned pk2(float lo, float hi) { return f2bf(lo) | (f2bf(hi) << 16); }
;     ...
;     for (int i = 0; i < 32; ++i) scr[(2 * i + (lane >> 5)) * 33 + (lane & 31)] = tv_[i];
;     LDS_WAIT(); asm volatile("" ::: "memory");
;     const int c = lane & 7;
; #pragma unroll
;     for (int j = 0; j < 4; ++j) { const int n = (lane >> 3) + 8 * j; const LAS float* s = scr + (8 * c) * 33 + n;
;         v4u o; o.x = pk2(s[0 * 33], s[1 * 33]); o.y = pk2(s[2 * 33], s[3 * 33]); o.z = pk2(s[4 * 33], s[5 * 33]); o.w = pk2(s[6 * 33], s[7 * 33]);
;         *(v4u*)(WT + (size_t)(n0 + n) * ldw + koff + k0 + 8 * c) = o; }
;     LDS_WAIT(); asm volatile("" ::: "memory");
	ds_write2_b32 v3, v4, v21 offset1:66
	s_waitcnt vmcnt(28)
	ds_write2_b32 v3, v33, v42 offset0:132 offset1:198
	s_waitcnt vmcnt(26)
	ds_write2_b32 v31, v43, v44 offset0:8 offset1:74
	s_waitcnt vmcnt(24)
	ds_write2_b32 v31, v45, v46 offset0:140 offset1:206
	s_waitcnt vmcnt(22)
	ds_write2_b32 v32, v47, v48 offset0:16 offset1:82
	s_waitcnt vmcnt(20)
	ds_write2_b32 v32, v49, v50 offset0:148 offset1:214
	s_waitcnt vmcnt(18)
	ds_write2_b32 v37, v51, v52 offset0:24 offset1:90
	s_waitcnt vmcnt(16)
	ds_write2_b32 v37, v53, v54 offset0:156 offset1:222
	s_waitcnt vmcnt(14)
	ds_write2_b32 v66, v55, v56 offset0:32 offset1:98
	s_waitcnt vmcnt(12)
	ds_write2_b32 v66, v57, v58 offset0:164 offset1:230
	s_waitcnt vmcnt(10)
	ds_write2_b32 v67, v59, v60 offset0:40 offset1:106
	s_waitcnt vmcnt(8)
	ds_write2_b32 v67, v61, v40 offset0:172 offset1:238
	s_waitcnt vmcnt(6)
	ds_write2_b32 v68, v41, v62 offset0:48 offset1:114
	s_waitcnt vmcnt(4)
	ds_write2_b32 v68, v63, v38 offset0:180 offset1:246
	s_waitcnt vmcnt(2)
	ds_write2_b32 v69, v39, v64 offset0:56 offset1:122
	s_waitcnt vmcnt(0)
	ds_write2_b32 v69, v65, v36 offset0:188 offset1:254
	s_waitcnt lgkmcnt(0)
	v_lshlrev_b32_e32 v4, 1, v20
	v_lshl_add_u64 v[20:21], v[34:35], 0, v[4:5]
	v_lshlrev_b32_e32 v4, 1, v6
	v_lshl_add_u64 v[20:21], v[20:21], 0, v[4:5]
	ds_read_b32 v4, v23
	ds_read_b32 v33, v23 offset:132
	ds_read_b32 v35, v23 offset:264
	ds_read_b32 v36, v23 offset:396
	ds_read_b32 v37, v23 offset:528
	ds_read_b32 v38, v23 offset:660
	ds_read_b32 v39, v23 offset:792
	ds_read_b32 v40, v23 offset:924
	s_waitcnt lgkmcnt(0)
	v_bfe_u32 v34, v4, 16, 1
	v_add3_u32 v4, v4, v34, s38
	v_bfe_u32 v34, v33, 16, 1
	v_lshrrev_b32_e32 v4, 16, v4
	v_add3_u32 v33, v33, v34, s38
	v_and_or_b32 v34, v33, s39, v4
	v_bfe_u32 v4, v35, 16, 1
	v_add3_u32 v4, v35, v4, s38
	v_bfe_u32 v33, v36, 16, 1
	v_lshrrev_b32_e32 v4, 16, v4
	v_add3_u32 v33, v36, v33, s38
	v_and_or_b32 v35, v33, s39, v4
	v_bfe_u32 v4, v37, 16, 1
	v_add3_u32 v4, v37, v4, s38
	v_bfe_u32 v33, v38, 16, 1
	v_lshrrev_b32_e32 v4, 16, v4
	v_add3_u32 v33, v38, v33, s38
	v_and_or_b32 v36, v33, s39, v4
	v_bfe_u32 v4, v39, 16, 1
	v_add3_u32 v4, v39, v4, s38
	v_bfe_u32 v33, v40, 16, 1
	v_lshrrev_b32_e32 v4, 16, v4
	v_add3_u32 v33, v40, v33, s38
	v_and_or_b32 v37, v33, s39, v4
	v_lshl_add_u64 v[38:39], v[20:21], 0, v[8:9]
	global_store_dwordx4 v[38:39], v[34:37], off
	ds_read_b32 v4, v23 offset:32
	ds_read_b32 v33, v23 offset:164
	ds_read_b32 v35, v23 offset:296
	ds_read_b32 v36, v23 offset:428
	ds_read_b32 v37, v23 offset:560
	ds_read_b32 v38, v23 offset:692
	ds_read_b32 v39, v23 offset:824
	ds_read_b32 v40, v23 offset:956
	s_waitcnt lgkmcnt(0)
	v_bfe_u32 v34, v4, 16, 1
	v_add3_u32 v4, v4, v34, s38
	v_bfe_u32 v34, v33, 16, 1
	v_lshrrev_b32_e32 v4, 16, v4
	v_add3_u32 v33, v33, v34, s38
	v_and_or_b32 v34, v33, s39, v4
	v_bfe_u32 v4, v35, 16, 1
	v_add3_u32 v4, v35, v4, s38
	v_bfe_u32 v33, v36, 16, 1
	v_lshrrev_b32_e32 v4, 16, v4
	v_add3_u32 v33, v36, v33, s38
	v_and_or_b32 v35, v33, s39, v4
	v_bfe_u32 v4, v37, 16, 1
	v_add3_u32 v4, v37, v4, s38
	v_bfe_u32 v33, v38, 16, 1
	v_lshrrev_b32_e32 v4, 16, v4
	v_add3_u32 v33, v38, v33, s38
	v_and_or_b32 v36, v33, s39, v4
	v_bfe_u32 v4, v39, 16, 1
	v_add3_u32 v4, v39, v4, s38
	v_bfe_u32 v33, v40, 16, 1
	v_lshrrev_b32_e32 v4, 16, v4
	v_add3_u32 v33, v40, v33, s38
	v_and_or_b32 v37, v33, s39, v4
	v_lshl_add_u64 v[38:39], v[20:21], 0, v[10:11]
	global_store_dwordx4 v[38:39], v[34:37], off
	ds_read_b32 v4, v23 offset:64
	ds_read_b32 v33, v23 offset:196
	ds_read_b32 v35, v23 offset:328
	ds_read_b32 v36, v23 offset:460
	ds_read_b32 v37, v23 offset:592
	ds_read_b32 v38, v23 offset:724
	ds_read_b32 v39, v23 offset:856
	ds_read_b32 v40, v23 offset:988
	s_waitcnt lgkmcnt(0)
	v_bfe_u32 v34, v4, 16, 1
	v_add3_u32 v4, v4, v34, s38
	v_bfe_u32 v34, v33, 16, 1
	v_lshrrev_b32_e32 v4, 16, v4
	v_add3_u32 v33, v33, v34, s38
	v_and_or_b32 v34, v33, s39, v4
	v_bfe_u32 v4, v35, 16, 1
	v_add3_u32 v4, v35, v4, s38
	v_bfe_u32 v33, v36, 16, 1
	v_lshrrev_b32_e32 v4, 16, v4
	v_add3_u32 v33, v36, v33, s38
	v_and_or_b32 v35, v33, s39, v4
	v_bfe_u32 v4, v37, 16, 1
	v_add3_u32 v4, v37, v4, s38
	v_bfe_u32 v33, v38, 16, 1
	v_lshrrev_b32_e32 v4, 16, v4
	v_add3_u32 v33, v38, v33, s38
	v_and_or_b32 v36, v33, s39, v4
	v_bfe_u32 v4, v39, 16, 1
	v_add3_u32 v4, v39, v4, s38
	v_bfe_u32 v33, v40, 16, 1
	v_lshrrev_b32_e32 v4, 16, v4
	v_add3_u32 v33, v40, v33, s38
	v_and_or_b32 v37, v33, s39, v4
	v_lshl_add_u64 v[38:39], v[20:21], 0, v[12:13]
	global_store_dwordx4 v[38:39], v[34:37], off
	ds_read_b32 v4, v23 offset:96
	ds_read_b32 v33, v23 offset:228
	ds_read_b32 v35, v23 offset:360
	ds_read_b32 v36, v23 offset:492
	ds_read_b32 v37, v23 offset:624
	ds_read_b32 v38, v23 offset:756
	ds_read_b32 v39, v23 offset:888
	ds_read_b32 v40, v23 offset:1020
	s_waitcnt lgkmcnt(0)
	v_bfe_u32 v34, v4, 16, 1
	v_add3_u32 v4, v4, v34, s38
	v_bfe_u32 v34, v33, 16, 1
	v_lshrrev_b32_e32 v4, 16, v4
	v_add3_u32 v33, v33, v34, s38
	v_and_or_b32 v34, v33, s39, v4
	v_bfe_u32 v4, v35, 16, 1
	v_add3_u32 v4, v35, v4, s38
	v_bfe_u32 v33, v36, 16, 1
	v_lshrrev_b32_e32 v4, 16, v4
	v_add3_u32 v33, v36, v33, s38
	v_and_or_b32 v35, v33, s39, v4
	v_bfe_u32 v4, v37, 16, 1
	v_add3_u32 v4, v37, v4, s38
	v_bfe_u32 v33, v38, 16, 1
	v_lshrrev_b32_e32 v4, 16, v4
	v_add3_u32 v33, v38, v33, s38
	v_and_or_b32 v36, v33, s39, v4
	v_bfe_u32 v4, v39, 16, 1
	v_add3_u32 v4, v39, v4, s38
	v_bfe_u32 v33, v40, 16, 1
	v_lshrrev_b32_e32 v4, 16, v4
	v_add3_u32 v33, v40, v33, s38
	v_and_or_b32 v37, v33, s39, v4
	v_lshl_add_u64 v[20:21], v[20:21], 0, v[14:15]
	global_store_dwordx4 v[20:21], v[34:37], off
	s_waitcnt lgkmcnt(0)

;     ...
;     const int nblk = N / 32, kb = item / nblk, nb = item % nblk, k0 = 64 * kb, n0 = 32 * nb;
;     float tv_[32];
; #pragma unroll
;     for (int i = 0; i < 32; ++i) tv_[i] = W[(size_t)(k0 + 2 * i + (lane >> 5)) * N + n0 + (lane & 31)];
;     ...
;     for (int i = 0; i < 32; ++i) scr[(2 * i + (lane >> 5)) * 33 + (lane & 31)] = tv_[i];
; __device__ __forceinline__ void convert_range(LAS unsigned char* lds, const Params& p, const int lo, const int hi, const int gw, const int NGW) {
;     ...
;         if (r < I_PL) { const int mi = r / 32; r -= mi * 32; p0_transpose_item(p.in[7] + (size_t)mi * 65536, 256, 256, (bf16*)(ws + WS_POOLW) + (size_t)mi * 65536, scr, r, lane); continue; } r -= I_PL;
.LBB0_63:
	s_andn2_saveexec_b64 s[34:35], s[34:35]
	s_cbranch_execz .LBB0_65
	v_add_u32_e32 v4, 0x200, v27
	v_lshrrev_b32_e32 v4, 5, v4
	v_readlane_b32 s60, v251, 21
	v_lshlrev_b64 v[20:21], 18, v[4:5]
	v_readlane_b32 s74, v251, 35
	v_readlane_b32 s75, v251, 36
	v_and_b32_e32 v54, 0xe0, v30
	v_lshlrev_b64 v[34:35], 17, v[4:5]
	v_lshl_add_u64 v[20:21], s[74:75], 0, v[20:21]
	v_and_b32_e32 v33, 0xc0, v29
	v_lshlrev_b32_e32 v4, 2, v54
	v_or_b32_e32 v36, v33, v1
	v_lshl_add_u64 v[20:21], v[20:21], 0, v[4:5]
	v_lshlrev_b32_e32 v4, 2, v2
	v_lshl_add_u64 v[20:21], v[20:21], 0, v[4:5]
	v_lshlrev_b32_e32 v4, 10, v36
	v_lshl_add_u64 v[20:21], v[20:21], 0, v[4:5]
	s_movk_i32 s36, 0x1000
	v_add_co_u32_e32 v36, vcc, s36, v20
	s_movk_i32 s36, 0x2000
	s_nop 0
	v_addc_co_u32_e32 v37, vcc, 0, v21, vcc
	v_add_co_u32_e32 v38, vcc, s36, v20
	s_movk_i32 s36, 0x3000
	s_nop 0
	v_addc_co_u32_e32 v39, vcc, 0, v21, vcc
	v_add_co_u32_e32 v40, vcc, s36, v20
	s_movk_i32 s36, 0x5000
	s_nop 0
	v_addc_co_u32_e32 v41, vcc, 0, v21, vcc
	v_add_co_u32_e32 v42, vcc, s7, v20
	v_readlane_b32 s61, v251, 22
	s_nop 0
	v_addc_co_u32_e32 v43, vcc, 0, v21, vcc
	global_load_dword v4, v[38:39], off offset:-4096
	global_load_dword v55, v[38:39], off
	global_load_dword v56, v[38:39], off offset:2048
	global_load_dword v57, v[42:43], off offset:-4096
	global_load_dword v58, v[42:43], off
	v_add_co_u32_e32 v38, vcc, s36, v20
	s_movk_i32 s36, 0x6000
	s_nop 0
	v_addc_co_u32_e32 v39, vcc, 0, v21, vcc
	v_add_co_u32_e32 v44, vcc, s36, v20
	s_movk_i32 s36, 0x7000
	s_nop 0
	v_addc_co_u32_e32 v45, vcc, 0, v21, vcc
	v_add_co_u32_e32 v46, vcc, s36, v20
	s_mov_b32 s36, 0x9000
	s_nop 0
	v_addc_co_u32_e32 v47, vcc, 0, v21, vcc
	v_add_co_u32_e32 v48, vcc, s40, v20
	v_readlane_b32 s62, v251, 23
	s_nop 0
	v_addc_co_u32_e32 v49, vcc, 0, v21, vcc
	v_add_co_u32_e32 v50, vcc, s36, v20
	s_mov_b32 s36, 0xb000
	s_nop 0
	v_addc_co_u32_e32 v51, vcc, 0, v21, vcc
	v_add_co_u32_e32 v52, vcc, s41, v20
	v_readlane_b32 s63, v251, 24
	s_nop 0
	v_addc_co_u32_e32 v53, vcc, 0, v21, vcc
	global_load_dword v59, v[42:43], off offset:2048
	global_load_dword v60, v[44:45], off offset:-4096
	global_load_dword v61, v[44:45], off
	global_load_dword v62, v[44:45], off offset:2048
	global_load_dword v63, v[48:49], off offset:-4096
	global_load_dword v64, v[48:49], off
	s_nop 0
	global_load_dword v48, v[48:49], off offset:2048
	s_nop 0
	global_load_dword v49, v[52:53], off offset:-4096
	v_add_co_u32_e32 v42, vcc, s36, v20
	s_mov_b32 s36, 0xd000
	s_nop 0
	v_addc_co_u32_e32 v43, vcc, 0, v21, vcc
	v_add_co_u32_e32 v44, vcc, s42, v20
	global_load_dword v65, v[20:21], off
	global_load_dword v66, v[20:21], off offset:2048
	global_load_dword v67, v[36:37], off offset:2048
	s_nop 0
	global_load_dword v40, v[40:41], off offset:2048
	s_nop 0
	global_load_dword v41, v[38:39], off offset:2048
	s_nop 0
	global_load_dword v46, v[46:47], off offset:2048
	s_nop 0
	global_load_dword v47, v[50:51], off offset:2048
	s_nop 0
	global_load_dword v42, v[42:43], off offset:2048
	v_addc_co_u32_e32 v45, vcc, 0, v21, vcc
	v_add_co_u32_e32 v36, vcc, s36, v20
	s_mov_b32 s36, 0xe000
	s_nop 0
	v_addc_co_u32_e32 v37, vcc, 0, v21, vcc
	v_add_co_u32_e32 v38, vcc, s36, v20
	s_mov_b32 s36, 0xf000
	s_nop 0
	v_addc_co_u32_e32 v39, vcc, 0, v21, vcc
	v_add_co_u32_e32 v20, vcc, s36, v20
	global_load_dword v36, v[36:37], off offset:2048
	s_nop 0
	global_load_dword v37, v[52:53], off
	global_load_dword v43, v[52:53], off offset:2048
	global_load_dword v50, v[44:45], off offset:-4096
	global_load_dword v51, v[44:45], off
	s_nop 0
	global_load_dword v44, v[44:45], off offset:2048
	s_nop 0
	global_load_dword v45, v[38:39], off offset:-4096
	global_load_dword v52, v[38:39], off
	s_nop 0
	global_load_dword v38, v[38:39], off offset:2048
	v_addc_co_u32_e32 v21, vcc, 0, v21, vcc
	global_load_dword v39, v[20:21], off
	global_load_dword v53, v[20:21], off offset:2048
	v_lshl_add_u64 v[20:21], s[16:17], 0, v[34:35]
	v_readlane_b32 s64, v251, 25
	v_readlane_b32 s65, v251, 26
	v_readlane_b32 s66, v251, 27
	v_readlane_b32 s67, v251, 28
	v_readlane_b32 s68, v251, 29
	v_readlane_b32 s69, v251, 30
	v_readlane_b32 s70, v251, 31
	v_readlane_b32 s71, v251, 32
	s_waitcnt vmcnt(17)
	ds_write2_b32 v3, v65, v66 offset1:66
	s_waitcnt vmcnt(16)
	ds_write2_b32 v3, v4, v67 offset0:132 offset1:198
	ds_write2_b32 v31, v55, v56 offset0:8 offset1:74
	s_waitcnt vmcnt(15)
	ds_write2_b32 v31, v57, v40 offset0:140 offset1:206
	ds_write2_b32 v32, v58, v59 offset0:16 offset1:82
	s_waitcnt vmcnt(14)
	ds_write2_b32 v32, v60, v41 offset0:148 offset1:214
	v_add_u32_e32 v4, 0xc00, v3
	ds_write2_b32 v4, v61, v62 offset0:24 offset1:90
	s_waitcnt vmcnt(13)
	ds_write2_b32 v4, v63, v46 offset0:156 offset1:222
	v_add_u32_e32 v4, 0x1000, v3
	ds_write2_b32 v4, v64, v48 offset0:32 offset1:98
	s_waitcnt vmcnt(12)
	ds_write2_b32 v4, v49, v47 offset0:164 offset1:230
	v_add_u32_e32 v4, 0x1400, v3
	s_waitcnt vmcnt(8)
	ds_write2_b32 v4, v37, v43 offset0:40 offset1:106
	s_waitcnt vmcnt(7)
	ds_write2_b32 v4, v50, v42 offset0:172 offset1:238
	v_add_u32_e32 v4, 0x1800, v3
	s_waitcnt vmcnt(5)
; #define LAS __attribute__((address_space(3)))
; #define LDS_WAIT() asm volatile("s_waitcnt lgkmcnt(0)" ::: "memory")
; __device__ __forceinline__ unsigned pk2(float lo, float hi) { return f2bf(lo) | (f2bf(hi) << 16); }
;     ...
;     for (int i = 0; i < 32; ++i) scr[(2 * i + (lane >> 5)) * 33 + (lane & 31)] = tv_[i];
;     LDS_WAIT(); asm volatile("" ::: "memory");
;     const int c = lane & 7;
; #pragma unroll
;     for (int j = 0; j < 4; ++j) { const int n = (lane >> 3) + 8 * j; const LAS float* s = scr + (8 * c) * 33 + n;
;         v4u o; o.x = pk2(s[0 * 33], s[1 * 33]); o.y = pk2(s[2 * 33], s[3 * 33]); o.z = pk2(s[4 * 33], s[5 * 33]); o.w = pk2(s[6 * 33], s[7 * 33]);
;         *(v4u*)(WT + (size_t)(n0 + n) * ldw + koff + k0 + 8 * c) = o; }
;     LDS_WAIT(); asm volatile("" ::: "memory");
	ds_write2_b32 v4, v51, v44 offset0:48 offset1:114
	s_waitcnt vmcnt(4)
	ds_write2_b32 v4, v45, v36 offset0:180 offset1:246
	v_add_u32_e32 v4, 0x1c00, v3
	s_waitcnt vmcnt(2)
	ds_write2_b32 v4, v52, v38 offset0:56 offset1:122
	s_waitcnt vmcnt(0)
	ds_write2_b32 v4, v39, v53 offset0:188 offset1:254
	s_waitcnt lgkmcnt(0)
	v_lshlrev_b32_e32 v4, 1, v33
	v_lshl_add_u64 v[20:21], v[20:21], 0, v[4:5]
	v_lshlrev_b32_e32 v4, 1, v6
	v_lshl_add_u64 v[20:21], v[20:21], 0, v[4:5]
	ds_read_b32 v4, v23
	ds_read_b32 v33, v23 offset:132
	ds_read_b32 v35, v23 offset:264
	ds_read_b32 v36, v23 offset:396
	ds_read_b32 v37, v23 offset:528
	ds_read_b32 v38, v23 offset:660
	ds_read_b32 v39, v23 offset:792
	ds_read_b32 v40, v23 offset:924
	s_waitcnt lgkmcnt(0)
	v_bfe_u32 v34, v4, 16, 1
	v_add3_u32 v4, v4, v34, s38
	v_bfe_u32 v34, v33, 16, 1
	v_lshrrev_b32_e32 v4, 16, v4
	v_add3_u32 v33, v33, v34, s38
	v_and_or_b32 v34, v33, s39, v4
	v_bfe_u32 v4, v35, 16, 1
	v_add3_u32 v4, v35, v4, s38
	v_bfe_u32 v33, v36, 16, 1
	v_lshrrev_b32_e32 v4, 16, v4
	v_add3_u32 v33, v36, v33, s38
	v_and_or_b32 v35, v33, s39, v4
	v_bfe_u32 v4, v37, 16, 1
	v_add3_u32 v4, v37, v4, s38
	v_bfe_u32 v33, v38, 16, 1
	v_lshrrev_b32_e32 v4, 16, v4
	v_add3_u32 v33, v38, v33, s38
	v_and_or_b32 v36, v33, s39, v4
	v_bfe_u32 v4, v39, 16, 1
	v_add3_u32 v4, v39, v4, s38
	v_bfe_u32 v33, v40, 16, 1
	v_lshrrev_b32_e32 v4, 16, v4
	v_add3_u32 v33, v40, v33, s38
	v_and_or_b32 v37, v33, s39, v4
	v_or_b32_e32 v4, v54, v7
	v_lshlrev_b32_e32 v4, 9, v4
	v_lshl_add_u64 v[38:39], v[20:21], 0, v[4:5]
	global_store_dwordx4 v[38:39], v[34:37], off
	ds_read_b32 v4, v23 offset:32
	ds_read_b32 v33, v23 offset:164
	ds_read_b32 v35, v23 offset:296
	ds_read_b32 v36, v23 offset:428
	ds_read_b32 v37, v23 offset:560
	ds_read_b32 v38, v23 offset:692
	ds_read_b32 v39, v23 offset:824
	ds_read_b32 v40, v23 offset:956
	s_waitcnt lgkmcnt(0)
	v_bfe_u32 v34, v4, 16, 1
	v_add3_u32 v4, v4, v34, s38
	v_bfe_u32 v34, v33, 16, 1
	v_lshrrev_b32_e32 v4, 16, v4
	v_add3_u32 v33, v33, v34, s38
	v_and_or_b32 v34, v33, s39, v4
	v_bfe_u32 v4, v35, 16, 1
	v_add3_u32 v4, v35, v4, s38
	v_bfe_u32 v33, v36, 16, 1
	v_lshrrev_b32_e32 v4, 16, v4
	v_add3_u32 v33, v36, v33, s38
	v_and_or_b32 v35, v33, s39, v4
	v_bfe_u32 v4, v37, 16, 1
	v_add3_u32 v4, v37, v4, s38
	v_bfe_u32 v33, v38, 16, 1
	v_lshrrev_b32_e32 v4, 16, v4
	v_add3_u32 v33, v38, v33, s38
	v_and_or_b32 v36, v33, s39, v4
	v_bfe_u32 v4, v39, 16, 1
	v_add3_u32 v4, v39, v4, s38
	v_bfe_u32 v33, v40, 16, 1
	v_lshrrev_b32_e32 v4, 16, v4
	v_add3_u32 v33, v40, v33, s38
	v_and_or_b32 v37, v33, s39, v4
	v_or_b32_e32 v4, v54, v24
	v_lshlrev_b32_e32 v4, 9, v4
	v_lshl_add_u64 v[38:39], v[20:21], 0, v[4:5]
	global_store_dwordx4 v[38:39], v[34:37], off
	ds_read_b32 v4, v23 offset:64
	ds_read_b32 v33, v23 offset:196
	ds_read_b32 v35, v23 offset:328
	ds_read_b32 v36, v23 offset:460
	ds_read_b32 v37, v23 offset:592
	ds_read_b32 v38, v23 offset:724
	ds_read_b32 v39, v23 offset:856
	ds_read_b32 v40, v23 offset:988
	s_waitcnt lgkmcnt(0)
	v_bfe_u32 v34, v4, 16, 1
	v_add3_u32 v4, v4, v34, s38
	v_bfe_u32 v34, v33, 16, 1
	v_lshrrev_b32_e32 v4, 16, v4
	v_add3_u32 v33, v33, v34, s38
	v_and_or_b32 v34, v33, s39, v4
	v_bfe_u32 v4, v35, 16, 1
	v_add3_u32 v4, v35, v4, s38
	v_bfe_u32 v33, v36, 16, 1
	v_lshrrev_b32_e32 v4, 16, v4
	v_add3_u32 v33, v36, v33, s38
	v_and_or_b32 v35, v33, s39, v4
	v_bfe_u32 v4, v37, 16, 1
	v_add3_u32 v4, v37, v4, s38
	v_bfe_u32 v33, v38, 16, 1
	v_lshrrev_b32_e32 v4, 16, v4
	v_add3_u32 v33, v38, v33, s38
	v_and_or_b32 v36, v33, s39, v4
	v_bfe_u32 v4, v39, 16, 1
	v_add3_u32 v4, v39, v4, s38
	v_bfe_u32 v33, v40, 16, 1
	v_lshrrev_b32_e32 v4, 16, v4
	v_add3_u32 v33, v40, v33, s38
	v_and_or_b32 v37, v33, s39, v4
	v_or_b32_e32 v4, v54, v25
	v_lshlrev_b32_e32 v4, 9, v4
	v_lshl_add_u64 v[38:39], v[20:21], 0, v[4:5]
	global_store_dwordx4 v[38:39], v[34:37], off
	ds_read_b32 v4, v23 offset:96
	ds_read_b32 v33, v23 offset:228
	ds_read_b32 v35, v23 offset:360
	ds_read_b32 v36, v23 offset:492
	ds_read_b32 v37, v23 offset:624
	ds_read_b32 v38, v23 offset:756
	ds_read_b32 v39, v23 offset:888
	ds_read_b32 v40, v23 offset:1020
	s_waitcnt lgkmcnt(0)
	v_bfe_u32 v34, v4, 16, 1
	v_add3_u32 v4, v4, v34, s38
	v_bfe_u32 v34, v33, 16, 1
	v_lshrrev_b32_e32 v4, 16, v4
	v_add3_u32 v33, v33, v34, s38
	v_and_or_b32 v34, v33, s39, v4
	v_bfe_u32 v4, v35, 16, 1
	v_add3_u32 v4, v35, v4, s38
	v_bfe_u32 v33, v36, 16, 1
	v_lshrrev_b32_e32 v4, 16, v4
	v_add3_u32 v33, v36, v33, s38
	v_and_or_b32 v35, v33, s39, v4
	v_bfe_u32 v4, v37, 16, 1
	v_add3_u32 v4, v37, v4, s38
	v_bfe_u32 v33, v38, 16, 1
	v_lshrrev_b32_e32 v4, 16, v4
	v_add3_u32 v33, v38, v33, s38
	v_and_or_b32 v36, v33, s39, v4
	v_bfe_u32 v4, v39, 16, 1
	v_add3_u32 v4, v39, v4, s38
	v_bfe_u32 v33, v40, 16, 1
	v_lshrrev_b32_e32 v4, 16, v4
	v_add3_u32 v33, v40, v33, s38
	v_and_or_b32 v37, v33, s39, v4
	v_or_b32_e32 v4, v54, v26
	v_lshlrev_b32_e32 v4, 9, v4
	v_lshl_add_u64 v[20:21], v[20:21], 0, v[4:5]
	global_store_dwordx4 v[20:21], v[34:37], off
	s_waitcnt lgkmcnt(0)
	v_readlane_b32 s72, v251, 33
	v_readlane_b32 s73, v251, 34

;     ...
;     const int nblk = N / 32, kb = item / nblk, nb = item % nblk, k0 = 64 * kb, n0 = 32 * nb;
;     float tv_[32];
; #pragma unroll
;     for (int i = 0; i < 32; ++i) tv_[i] = W[(size_t)(k0 + 2 * i + (lane >> 5)) * N + n0 + (lane & 31)];
; #pragma unroll
;     for (int i = 0; i < 32; ++i) scr[(2 * i + (lane >> 5)) * 33 + (lane & 31)] = tv_[i];
; __device__ __forceinline__ void convert_range(LAS unsigned char* lds, const Params& p, const int lo, const int hi, const int gw, const int NGW) {
;     ...
;         if (r < 2 * I_OUT) { const int l = r / I_OUT; r -= l * I_OUT; p0_transpose_item(p.in[18] + (size_t)l * DM * DM, DM, DM, (bf16*)(ws + WS_WOUT + l * SZ_WOUT), scr, r, lane); continue; } r -= 2 * I_OUT;
.LBB0_66:
	s_andn2_saveexec_b64 s[30:31], s[30:31]
	s_cbranch_execz .LBB0_68
	v_add_u32_e32 v4, 0x1200, v27
	v_lshrrev_b32_e32 v4, 11, v4
	v_readlane_b32 s68, v251, 9
	v_lshlrev_b64 v[34:35], 24, v[4:5]
	v_readlane_b32 s72, v251, 13
	v_readlane_b32 s73, v251, 14
	v_and_b32_e32 v52, 0x7e0, v30
	v_lshlrev_b64 v[36:37], 23, v[4:5]
	v_lshl_add_u64 v[34:35], s[72:73], 0, v[34:35]
	v_and_b32_e32 v33, 0x7c0, v20
	v_lshlrev_b32_e32 v4, 2, v52
	v_or_b32_e32 v38, v33, v1
	v_lshl_add_u64 v[20:21], v[34:35], 0, v[4:5]
	v_lshlrev_b32_e32 v4, 2, v2
	v_lshl_add_u64 v[20:21], v[20:21], 0, v[4:5]
	v_lshlrev_b32_e32 v4, 13, v38
	v_lshl_add_u64 v[20:21], v[20:21], 0, v[4:5]
	v_add_co_u32_e32 v34, vcc, s7, v20
	v_readlane_b32 s69, v251, 10
	s_nop 0
	v_addc_co_u32_e32 v35, vcc, 0, v21, vcc
	v_add_co_u32_e32 v38, vcc, s40, v20
	v_readlane_b32 s70, v251, 11
	s_nop 0
	v_addc_co_u32_e32 v39, vcc, 0, v21, vcc
	v_add_co_u32_e32 v40, vcc, s42, v20
	v_readlane_b32 s71, v251, 12
	s_nop 0
	v_addc_co_u32_e32 v41, vcc, 0, v21, vcc
	v_add_co_u32_e32 v42, vcc, s43, v20
	v_readlane_b32 s74, v251, 15
	s_nop 0
	v_addc_co_u32_e32 v43, vcc, 0, v21, vcc
	v_add_co_u32_e32 v44, vcc, s44, v20
	v_readlane_b32 s75, v251, 16
	s_nop 0
	v_addc_co_u32_e32 v45, vcc, 0, v21, vcc
	v_add_co_u32_e32 v46, vcc, s45, v20
	s_nop 1
	v_addc_co_u32_e32 v47, vcc, 0, v21, vcc
	v_add_co_u32_e32 v48, vcc, s47, v20
	s_nop 1
	v_addc_co_u32_e32 v49, vcc, 0, v21, vcc
	global_load_dword v4, v[20:21], off
	global_load_dword v53, v[34:35], off
	global_load_dword v54, v[38:39], off
	global_load_dword v55, v[40:41], off
	global_load_dword v56, v[42:43], off
	global_load_dword v57, v[44:45], off
	global_load_dword v58, v[46:47], off
	global_load_dword v59, v[48:49], off
	v_add_co_u32_e32 v34, vcc, s48, v20
	s_nop 1
	v_addc_co_u32_e32 v35, vcc, 0, v21, vcc
	v_add_co_u32_e32 v38, vcc, s49, v20
	s_nop 1
	v_addc_co_u32_e32 v39, vcc, 0, v21, vcc
	v_add_co_u32_e32 v40, vcc, s50, v20
	s_nop 1
	v_addc_co_u32_e32 v41, vcc, 0, v21, vcc
	v_add_co_u32_e32 v42, vcc, s51, v20
	s_nop 1
	v_addc_co_u32_e32 v43, vcc, 0, v21, vcc
	v_add_co_u32_e32 v44, vcc, s52, v20
	s_nop 1
	v_addc_co_u32_e32 v45, vcc, 0, v21, vcc
	v_add_co_u32_e32 v46, vcc, s53, v20
	s_nop 1
	v_addc_co_u32_e32 v47, vcc, 0, v21, vcc
	v_add_co_u32_e32 v48, vcc, s54, v20
	s_nop 1
	v_addc_co_u32_e32 v49, vcc, 0, v21, vcc
	v_add_co_u32_e32 v50, vcc, s55, v20
	s_nop 1
	v_addc_co_u32_e32 v51, vcc, 0, v21, vcc
	global_load_dword v60, v[34:35], off
	global_load_dword v61, v[38:39], off
	global_load_dword v62, v[40:41], off
	global_load_dword v63, v[42:43], off
	global_load_dword v64, v[44:45], off
	global_load_dword v65, v[46:47], off
	global_load_dword v66, v[48:49], off
	global_load_dword v67, v[50:51], off
	v_add_co_u32_e32 v34, vcc, s56, v20
	s_nop 1
	v_addc_co_u32_e32 v35, vcc, 0, v21, vcc
	v_add_co_u32_e32 v38, vcc, s57, v20
	s_nop 1
	v_addc_co_u32_e32 v39, vcc, 0, v21, vcc
	v_add_co_u32_e32 v40, vcc, s58, v20
	s_nop 1
	v_addc_co_u32_e32 v41, vcc, 0, v21, vcc
	v_add_co_u32_e32 v42, vcc, s59, v20
	s_nop 1
	v_addc_co_u32_e32 v43, vcc, 0, v21, vcc
	v_add_co_u32_e32 v44, vcc, s76, v20
	s_nop 1
	v_addc_co_u32_e32 v45, vcc, 0, v21, vcc
	v_add_co_u32_e32 v46, vcc, s77, v20
	s_nop 1
	v_addc_co_u32_e32 v47, vcc, 0, v21, vcc
	v_add_co_u32_e32 v48, vcc, s78, v20
	s_nop 1
	v_addc_co_u32_e32 v49, vcc, 0, v21, vcc
	v_add_co_u32_e32 v50, vcc, s79, v20
	s_nop 1
	v_addc_co_u32_e32 v51, vcc, 0, v21, vcc
	global_load_dword v68, v[34:35], off
	global_load_dword v69, v[38:39], off
	global_load_dword v70, v[40:41], off
	global_load_dword v71, v[42:43], off
	global_load_dword v72, v[44:45], off
	global_load_dword v73, v[46:47], off
	global_load_dword v74, v[48:49], off
	s_nop 0
	global_load_dword v50, v[50:51], off
	v_add_co_u32_e32 v34, vcc, s80, v20
	s_nop 1
	v_addc_co_u32_e32 v35, vcc, 0, v21, vcc
	v_add_co_u32_e32 v38, vcc, s81, v20
	s_nop 1
	v_addc_co_u32_e32 v39, vcc, 0, v21, vcc
	v_add_co_u32_e32 v40, vcc, s82, v20
	s_nop 1
	v_addc_co_u32_e32 v41, vcc, 0, v21, vcc
	v_add_co_u32_e32 v42, vcc, s83, v20
	s_nop 1
	v_addc_co_u32_e32 v43, vcc, 0, v21, vcc
	v_add_co_u32_e32 v44, vcc, s84, v20
	s_nop 1
	v_addc_co_u32_e32 v45, vcc, 0, v21, vcc
	v_add_co_u32_e32 v46, vcc, s85, v20
	s_nop 1
	v_addc_co_u32_e32 v47, vcc, 0, v21, vcc
	v_add_co_u32_e32 v48, vcc, s86, v20
	s_nop 1
	v_addc_co_u32_e32 v49, vcc, 0, v21, vcc
	v_add_co_u32_e32 v20, vcc, s87, v20
	s_nop 1
	v_addc_co_u32_e32 v21, vcc, 0, v21, vcc
	global_load_dword v34, v[34:35], off
	s_nop 0
	global_load_dword v35, v[38:39], off
	s_nop 0
	global_load_dword v38, v[40:41], off
	global_load_dword v39, v[42:43], off
	s_nop 0
	global_load_dword v40, v[44:45], off
	global_load_dword v41, v[46:47], off
	global_load_dword v42, v[48:49], off
	global_load_dword v43, v[20:21], off
	s_waitcnt vmcnt(30)
	ds_write2_b32 v3, v4, v53 offset1:66
	s_waitcnt vmcnt(28)
	ds_write2_b32 v3, v54, v55 offset0:132 offset1:198
	s_waitcnt vmcnt(26)
	ds_write2_b32 v31, v56, v57 offset0:8 offset1:74
	s_waitcnt vmcnt(24)
	ds_write2_b32 v31, v58, v59 offset0:140 offset1:206
	s_waitcnt vmcnt(22)
	ds_write2_b32 v32, v60, v61 offset0:16 offset1:82
	s_waitcnt vmcnt(20)
	ds_write2_b32 v32, v62, v63 offset0:148 offset1:214
	v_add_u32_e32 v4, 0xc00, v3
	s_waitcnt vmcnt(18)
	ds_write2_b32 v4, v64, v65 offset0:24 offset1:90
	s_waitcnt vmcnt(16)
	ds_write2_b32 v4, v66, v67 offset0:156 offset1:222
	v_add_u32_e32 v4, 0x1000, v3
	s_waitcnt vmcnt(14)
; #define LAS __attribute__((address_space(3)))
; #define LDS_WAIT() asm volatile("s_waitcnt lgkmcnt(0)" ::: "memory")
; __device__ __forceinline__ unsigned pk2(float lo, float hi) { return f2bf(lo) | (f2bf(hi) << 16); }
;     ...
;     for (int i = 0; i < 32; ++i) scr[(2 * i + (lane >> 5)) * 33 + (lane & 31)] = tv_[i];
;     LDS_WAIT(); asm volatile("" ::: "memory");
;     const int c = lane & 7;
; #pragma unroll
;     for (int j = 0; j < 4; ++j) { const int n = (lane >> 3) + 8 * j; const LAS float* s = scr + (8 * c) * 33 + n;
;         v4u o; o.x = pk2(s[0 * 33], s[1 * 33]); o.y = pk2(s[2 * 33], s[3 * 33]); o.z = pk2(s[4 * 33], s[5 * 33]); o.w = pk2(s[6 * 33], s[7 * 33]);
;         *(v4u*)(WT + (size_t)(n0 + n) * ldw + koff + k0 + 8 * c) = o; }
	ds_write2_b32 v4, v68, v69 offset0:32 offset1:98
	s_waitcnt vmcnt(12)
	ds_write2_b32 v4, v70, v71 offset0:164 offset1:230
	v_add_u32_e32 v4, 0x1400, v3
	s_waitcnt vmcnt(10)
	ds_write2_b32 v4, v72, v73 offset0:40 offset1:106
	s_waitcnt vmcnt(8)
	ds_write2_b32 v4, v74, v50 offset0:172 offset1:238
	v_add_u32_e32 v4, 0x1800, v3
	s_waitcnt vmcnt(6)
	ds_write2_b32 v4, v34, v35 offset0:48 offset1:114
	s_waitcnt vmcnt(4)
	ds_write2_b32 v4, v38, v39 offset0:180 offset1:246
	v_add_u32_e32 v4, 0x1c00, v3
	s_waitcnt vmcnt(2)
	ds_write2_b32 v4, v40, v41 offset0:56 offset1:122
	s_waitcnt vmcnt(0)
	ds_write2_b32 v4, v42, v43 offset0:188 offset1:254
	v_lshl_add_u64 v[20:21], s[18:19], 0, v[36:37]
	s_waitcnt lgkmcnt(0)
	v_lshlrev_b32_e32 v4, 1, v33
	v_lshl_add_u64 v[20:21], v[20:21], 0, v[4:5]
	v_lshlrev_b32_e32 v4, 1, v6
	v_lshl_add_u64 v[20:21], v[20:21], 0, v[4:5]
	ds_read_b32 v4, v23
	ds_read_b32 v33, v23 offset:132
	ds_read_b32 v35, v23 offset:264
	ds_read_b32 v36, v23 offset:396
	ds_read_b32 v37, v23 offset:528
	ds_read_b32 v38, v23 offset:660
	ds_read_b32 v39, v23 offset:792
	ds_read_b32 v40, v23 offset:924
	s_waitcnt lgkmcnt(0)
	v_bfe_u32 v34, v4, 16, 1
	v_add3_u32 v4, v4, v34, s38
	v_bfe_u32 v34, v33, 16, 1
	v_lshrrev_b32_e32 v4, 16, v4
	v_add3_u32 v33, v33, v34, s38
	v_and_or_b32 v34, v33, s39, v4
	v_bfe_u32 v4, v35, 16, 1
	v_add3_u32 v4, v35, v4, s38
	v_bfe_u32 v33, v36, 16, 1
	v_lshrrev_b32_e32 v4, 16, v4
	v_add3_u32 v33, v36, v33, s38
	v_and_or_b32 v35, v33, s39, v4
	v_bfe_u32 v4, v37, 16, 1
	v_add3_u32 v4, v37, v4, s38
	v_bfe_u32 v33, v38, 16, 1
	v_lshrrev_b32_e32 v4, 16, v4
	v_add3_u32 v33, v38, v33, s38
	v_and_or_b32 v36, v33, s39, v4
	v_bfe_u32 v4, v39, 16, 1
	v_add3_u32 v4, v39, v4, s38
	v_bfe_u32 v33, v40, 16, 1
	v_lshrrev_b32_e32 v4, 16, v4
	v_add3_u32 v33, v40, v33, s38
	v_and_or_b32 v37, v33, s39, v4
	v_or_b32_e32 v4, v52, v7
	v_lshlrev_b32_e32 v4, 12, v4
	v_lshl_add_u64 v[38:39], v[20:21], 0, v[4:5]
	global_store_dwordx4 v[38:39], v[34:37], off
	ds_read_b32 v4, v23 offset:32
	ds_read_b32 v33, v23 offset:164
	ds_read_b32 v35, v23 offset:296
	ds_read_b32 v36, v23 offset:428
	ds_read_b32 v37, v23 offset:560
	ds_read_b32 v38, v23 offset:692
	ds_read_b32 v39, v23 offset:824
	ds_read_b32 v40, v23 offset:956
	s_waitcnt lgkmcnt(0)
	v_bfe_u32 v34, v4, 16, 1
	v_add3_u32 v4, v4, v34, s38
	v_bfe_u32 v34, v33, 16, 1
	v_lshrrev_b32_e32 v4, 16, v4
	v_add3_u32 v33, v33, v34, s38
	v_and_or_b32 v34, v33, s39, v4
	v_bfe_u32 v4, v35, 16, 1
	v_add3_u32 v4, v35, v4, s38
	v_bfe_u32 v33, v36, 16, 1
	v_lshrrev_b32_e32 v4, 16, v4
	v_add3_u32 v33, v36, v33, s38
	v_and_or_b32 v35, v33, s39, v4
	v_bfe_u32 v4, v37, 16, 1
	v_add3_u32 v4, v37, v4, s38
	v_bfe_u32 v33, v38, 16, 1
	v_lshrrev_b32_e32 v4, 16, v4
	v_add3_u32 v33, v38, v33, s38
	v_and_or_b32 v36, v33, s39, v4
	v_bfe_u32 v4, v39, 16, 1
	v_add3_u32 v4, v39, v4, s38
	v_bfe_u32 v33, v40, 16, 1
	v_lshrrev_b32_e32 v4, 16, v4
	v_add3_u32 v33, v40, v33, s38
	v_and_or_b32 v37, v33, s39, v4
	v_or_b32_e32 v4, v52, v24
	v_lshlrev_b32_e32 v4, 12, v4
	v_lshl_add_u64 v[38:39], v[20:21], 0, v[4:5]
	global_store_dwordx4 v[38:39], v[34:37], off
	ds_read_b32 v4, v23 offset:64
	ds_read_b32 v33, v23 offset:196
	ds_read_b32 v35, v23 offset:328
	ds_read_b32 v36, v23 offset:460
	ds_read_b32 v37, v23 offset:592
	ds_read_b32 v38, v23 offset:724
	ds_read_b32 v39, v23 offset:856
	ds_read_b32 v40, v23 offset:988
	s_waitcnt lgkmcnt(0)
	v_bfe_u32 v34, v4, 16, 1
	v_add3_u32 v4, v4, v34, s38
	v_bfe_u32 v34, v33, 16, 1
	v_lshrrev_b32_e32 v4, 16, v4
	v_add3_u32 v33, v33, v34, s38
	v_and_or_b32 v34, v33, s39, v4
	v_bfe_u32 v4, v35, 16, 1
	v_add3_u32 v4, v35, v4, s38
	v_bfe_u32 v33, v36, 16, 1
	v_lshrrev_b32_e32 v4, 16, v4
	v_add3_u32 v33, v36, v33, s38
	v_and_or_b32 v35, v33, s39, v4
	v_bfe_u32 v4, v37, 16, 1
	v_add3_u32 v4, v37, v4, s38
	v_bfe_u32 v33, v38, 16, 1
	v_lshrrev_b32_e32 v4, 16, v4
	v_add3_u32 v33, v38, v33, s38
	v_and_or_b32 v36, v33, s39, v4
	v_bfe_u32 v4, v39, 16, 1
	v_add3_u32 v4, v39, v4, s38
	v_bfe_u32 v33, v40, 16, 1
	v_lshrrev_b32_e32 v4, 16, v4
	v_add3_u32 v33, v40, v33, s38
	v_and_or_b32 v37, v33, s39, v4
	v_or_b32_e32 v4, v52, v25
	v_lshlrev_b32_e32 v4, 12, v4
	v_lshl_add_u64 v[38:39], v[20:21], 0, v[4:5]
	global_store_dwordx4 v[38:39], v[34:37], off
	ds_read_b32 v4, v23 offset:96
	ds_read_b32 v33, v23 offset:228
	ds_read_b32 v35, v23 offset:360
	ds_read_b32 v36, v23 offset:492
	ds_read_b32 v37, v23 offset:624
	ds_read_b32 v38, v23 offset:756
	ds_read_b32 v39, v23 offset:888
	ds_read_b32 v40, v23 offset:1020
	s_waitcnt lgkmcnt(0)
	v_bfe_u32 v34, v4, 16, 1
	v_add3_u32 v4, v4, v34, s38
	v_bfe_u32 v34, v33, 16, 1
	v_lshrrev_b32_e32 v4, 16, v4
	v_add3_u32 v33, v33, v34, s38
	v_and_or_b32 v34, v33, s39, v4
	v_bfe_u32 v4, v35, 16, 1
	v_add3_u32 v4, v35, v4, s38
	v_bfe_u32 v33, v36, 16, 1
	v_lshrrev_b32_e32 v4, 16, v4
	v_add3_u32 v33, v36, v33, s38
	v_and_or_b32 v35, v33, s39, v4
	v_bfe_u32 v4, v37, 16, 1
	v_add3_u32 v4, v37, v4, s38
	v_bfe_u32 v33, v38, 16, 1
	v_lshrrev_b32_e32 v4, 16, v4
	v_add3_u32 v33, v38, v33, s38
	v_and_or_b32 v36, v33, s39, v4
	v_bfe_u32 v4, v39, 16, 1
	v_add3_u32 v4, v39, v4, s38
	v_bfe_u32 v33, v40, 16, 1
	v_lshrrev_b32_e32 v4, 16, v4
	v_add3_u32 v33, v40, v33, s38
	v_and_or_b32 v37, v33, s39, v4
	v_or_b32_e32 v4, v52, v26
	v_lshlrev_b32_e32 v4, 12, v4
	v_lshl_add_u64 v[20:21], v[20:21], 0, v[4:5]
	global_store_dwordx4 v[20:21], v[34:37], off
	s_waitcnt lgkmcnt(0)

;     ...
;     for (int i = 0; i < 32; ++i) tv_[i] = W[(size_t)(k0 + 2 * i + (lane >> 5)) * N + n0 + (lane & 31)];
; #pragma unroll
;     for (int i = 0; i < 32; ++i) scr[(2 * i + (lane >> 5)) * 33 + (lane & 31)] = tv_[i];
; __device__ __forceinline__ void convert_range(LAS unsigned char* lds, const Params& p, const int lo, const int hi, const int gw, const int NGW) {
;     ...
;         if (r < 2 * I_PB) { const int l = r / I_PB; r -= l * I_PB; p0_transpose_item(p.in[17] + (size_t)l * LW * DM, LW, DM, (bf16*)(ws + WS_WCAT + l * SZ_WCAT), scr, r, lane, KCAT, PW); continue; } r -= 2 * I_PB;
.LBB0_69:
	s_andn2_saveexec_b64 s[28:29], s[28:29]
	s_cbranch_execz .LBB0_71
	v_add_u32_e32 v4, 0x2200, v27
	v_lshrrev_b32_e32 v4, 11, v4
	v_readlane_b32 s68, v251, 9
	v_lshlrev_b64 v[34:35], 24, v[4:5]
	v_readlane_b32 s70, v251, 11
	v_readlane_b32 s71, v251, 12
	v_mov_b64_e32 v[36:37], s[8:9]
	v_and_b32_e32 v52, 0x7e0, v30
	v_lshl_add_u64 v[34:35], s[70:71], 0, v[34:35]
	v_mad_u64_u32 v[36:37], s[30:31], v4, s88, v[36:37]
	v_and_b32_e32 v33, 0x7c0, v20
	v_lshlrev_b32_e32 v4, 2, v52
	v_or_b32_e32 v38, v33, v1
	v_lshl_add_u64 v[20:21], v[34:35], 0, v[4:5]
	v_lshlrev_b32_e32 v4, 2, v2
	v_lshl_add_u64 v[20:21], v[20:21], 0, v[4:5]
	v_lshlrev_b32_e32 v4, 13, v38
	v_lshl_add_u64 v[20:21], v[20:21], 0, v[4:5]
	v_add_co_u32_e32 v34, vcc, s7, v20
	s_mov_b64 s[30:31], 0x5000800
	s_nop 0
	v_addc_co_u32_e32 v35, vcc, 0, v21, vcc
	v_add_co_u32_e32 v38, vcc, s40, v20
	v_readlane_b32 s69, v251, 10
	s_nop 0
	v_addc_co_u32_e32 v39, vcc, 0, v21, vcc
	v_add_co_u32_e32 v40, vcc, s42, v20
	v_readlane_b32 s72, v251, 13
	s_nop 0
	v_addc_co_u32_e32 v41, vcc, 0, v21, vcc
	v_add_co_u32_e32 v42, vcc, s43, v20
	v_readlane_b32 s73, v251, 14
	s_nop 0
	v_addc_co_u32_e32 v43, vcc, 0, v21, vcc
	v_add_co_u32_e32 v44, vcc, s44, v20
	v_readlane_b32 s74, v251, 15
	s_nop 0
	v_addc_co_u32_e32 v45, vcc, 0, v21, vcc
	v_add_co_u32_e32 v46, vcc, s45, v20
	v_readlane_b32 s75, v251, 16
	s_nop 0
	v_addc_co_u32_e32 v47, vcc, 0, v21, vcc
	v_add_co_u32_e32 v48, vcc, s47, v20
	s_nop 1
	v_addc_co_u32_e32 v49, vcc, 0, v21, vcc
	global_load_dword v4, v[20:21], off
	global_load_dword v53, v[34:35], off
	global_load_dword v54, v[38:39], off
	global_load_dword v55, v[40:41], off
	global_load_dword v56, v[42:43], off
	global_load_dword v57, v[44:45], off
	global_load_dword v58, v[46:47], off
	global_load_dword v59, v[48:49], off
	v_add_co_u32_e32 v34, vcc, s48, v20
	s_nop 1
	v_addc_co_u32_e32 v35, vcc, 0, v21, vcc
	v_add_co_u32_e32 v38, vcc, s49, v20
	s_nop 1
	v_addc_co_u32_e32 v39, vcc, 0, v21, vcc
	v_add_co_u32_e32 v40, vcc, s50, v20
	s_nop 1
	v_addc_co_u32_e32 v41, vcc, 0, v21, vcc
	v_add_co_u32_e32 v42, vcc, s51, v20
	s_nop 1
	v_addc_co_u32_e32 v43, vcc, 0, v21, vcc
	v_add_co_u32_e32 v44, vcc, s52, v20
	s_nop 1
	v_addc_co_u32_e32 v45, vcc, 0, v21, vcc
	v_add_co_u32_e32 v46, vcc, s53, v20
	s_nop 1
	v_addc_co_u32_e32 v47, vcc, 0, v21, vcc
	v_add_co_u32_e32 v48, vcc, s54, v20
	s_nop 1
	v_addc_co_u32_e32 v49, vcc, 0, v21, vcc
	v_add_co_u32_e32 v50, vcc, s55, v20
	s_nop 1
	v_addc_co_u32_e32 v51, vcc, 0, v21, vcc
	global_load_dword v60, v[34:35], off
	global_load_dword v61, v[38:39], off
	global_load_dword v62, v[40:41], off
	global_load_dword v63, v[42:43], off
	global_load_dword v64, v[44:45], off
	global_load_dword v65, v[46:47], off
	global_load_dword v66, v[48:49], off
	global_load_dword v67, v[50:51], off
	v_add_co_u32_e32 v34, vcc, s56, v20
	s_nop 1
	v_addc_co_u32_e32 v35, vcc, 0, v21, vcc
	v_add_co_u32_e32 v38, vcc, s57, v20
	s_nop 1
	v_addc_co_u32_e32 v39, vcc, 0, v21, vcc
	v_add_co_u32_e32 v40, vcc, s58, v20
	s_nop 1
	v_addc_co_u32_e32 v41, vcc, 0, v21, vcc
	v_add_co_u32_e32 v42, vcc, s59, v20
	s_nop 1
	v_addc_co_u32_e32 v43, vcc, 0, v21, vcc
	v_add_co_u32_e32 v44, vcc, s76, v20
	s_nop 1
	v_addc_co_u32_e32 v45, vcc, 0, v21, vcc
	v_add_co_u32_e32 v46, vcc, s77, v20
	s_nop 1
	v_addc_co_u32_e32 v47, vcc, 0, v21, vcc
	v_add_co_u32_e32 v48, vcc, s78, v20
	s_nop 1
	v_addc_co_u32_e32 v49, vcc, 0, v21, vcc
	v_add_co_u32_e32 v50, vcc, s79, v20
	s_nop 1
	v_addc_co_u32_e32 v51, vcc, 0, v21, vcc
	global_load_dword v68, v[34:35], off
	global_load_dword v69, v[38:39], off
	global_load_dword v70, v[40:41], off
	global_load_dword v71, v[42:43], off
	global_load_dword v72, v[44:45], off
	global_load_dword v73, v[46:47], off
	global_load_dword v74, v[48:49], off
	s_nop 0
	global_load_dword v50, v[50:51], off
	v_add_co_u32_e32 v34, vcc, s80, v20
	s_nop 1
	v_addc_co_u32_e32 v35, vcc, 0, v21, vcc
	v_add_co_u32_e32 v38, vcc, s81, v20
	s_nop 1
	v_addc_co_u32_e32 v39, vcc, 0, v21, vcc
	v_add_co_u32_e32 v40, vcc, s82, v20
	s_nop 1
	v_addc_co_u32_e32 v41, vcc, 0, v21, vcc
	v_add_co_u32_e32 v42, vcc, s83, v20
	s_nop 1
	v_addc_co_u32_e32 v43, vcc, 0, v21, vcc
	v_add_co_u32_e32 v44, vcc, s84, v20
	s_nop 1
	v_addc_co_u32_e32 v45, vcc, 0, v21, vcc
	v_add_co_u32_e32 v46, vcc, s85, v20
	s_nop 1
	v_addc_co_u32_e32 v47, vcc, 0, v21, vcc
	v_add_co_u32_e32 v48, vcc, s86, v20
	s_nop 1
	v_addc_co_u32_e32 v49, vcc, 0, v21, vcc
	v_add_co_u32_e32 v20, vcc, s87, v20
	s_nop 1
	v_addc_co_u32_e32 v21, vcc, 0, v21, vcc
	global_load_dword v34, v[34:35], off
	s_nop 0
	global_load_dword v35, v[38:39], off
	s_nop 0
	global_load_dword v38, v[40:41], off
	global_load_dword v39, v[42:43], off
	s_nop 0
	global_load_dword v40, v[44:45], off
	global_load_dword v41, v[46:47], off
	global_load_dword v42, v[48:49], off
	s_nop 0
	global_load_dword v20, v[20:21], off
	s_waitcnt vmcnt(30)
	ds_write2_b32 v3, v4, v53 offset1:66
	s_waitcnt vmcnt(28)
	ds_write2_b32 v3, v54, v55 offset0:132 offset1:198
	s_waitcnt vmcnt(26)
	ds_write2_b32 v31, v56, v57 offset0:8 offset1:74
	s_waitcnt vmcnt(24)
	ds_write2_b32 v31, v58, v59 offset0:140 offset1:206
	s_waitcnt vmcnt(22)
	ds_write2_b32 v32, v60, v61 offset0:16 offset1:82
	s_waitcnt vmcnt(20)
	ds_write2_b32 v32, v62, v63 offset0:148 offset1:214
	v_add_u32_e32 v4, 0xc00, v3
	s_waitcnt vmcnt(18)
	ds_write2_b32 v4, v64, v65 offset0:24 offset1:90
	s_waitcnt vmcnt(16)
	ds_write2_b32 v4, v66, v67 offset0:156 offset1:222
	v_add_u32_e32 v4, 0x1000, v3
	s_waitcnt vmcnt(14)
; #define LAS __attribute__((address_space(3)))
; #define LDS_WAIT() asm volatile("s_waitcnt lgkmcnt(0)" ::: "memory")
; __device__ __forceinline__ unsigned pk2(float lo, float hi) { return f2bf(lo) | (f2bf(hi) << 16); }
;     ...
;     for (int i = 0; i < 32; ++i) scr[(2 * i + (lane >> 5)) * 33 + (lane & 31)] = tv_[i];
;     LDS_WAIT(); asm volatile("" ::: "memory");
;     const int c = lane & 7;
; #pragma unroll
;     for (int j = 0; j < 4; ++j) { const int n = (lane >> 3) + 8 * j; const LAS float* s = scr + (8 * c) * 33 + n;
;         v4u o; o.x = pk2(s[0 * 33], s[1 * 33]); o.y = pk2(s[2 * 33], s[3 * 33]); o.z = pk2(s[4 * 33], s[5 * 33]); o.w = pk2(s[6 * 33], s[7 * 33]);
;         *(v4u*)(WT + (size_t)(n0 + n) * ldw + koff + k0 + 8 * c) = o; }
	ds_write2_b32 v4, v68, v69 offset0:32 offset1:98
	s_waitcnt vmcnt(12)
	ds_write2_b32 v4, v70, v71 offset0:164 offset1:230
	v_add_u32_e32 v4, 0x1400, v3
	s_waitcnt vmcnt(10)
	ds_write2_b32 v4, v72, v73 offset0:40 offset1:106
	s_waitcnt vmcnt(8)
	ds_write2_b32 v4, v74, v50 offset0:172 offset1:238
	v_add_u32_e32 v4, 0x1800, v3
	s_waitcnt vmcnt(6)
	ds_write2_b32 v4, v34, v35 offset0:48 offset1:114
	s_waitcnt vmcnt(4)
	ds_write2_b32 v4, v38, v39 offset0:180 offset1:246
	v_add_u32_e32 v4, 0x1c00, v3
	s_waitcnt vmcnt(2)
	ds_write2_b32 v4, v40, v41 offset0:56 offset1:122
	s_waitcnt vmcnt(0)
	ds_write2_b32 v4, v42, v20 offset0:188 offset1:254
	s_waitcnt lgkmcnt(0)
	v_lshlrev_b32_e32 v4, 1, v33
	v_lshl_add_u64 v[20:21], v[36:37], 0, v[4:5]
	v_lshlrev_b32_e32 v4, 1, v6
	v_lshl_add_u64 v[20:21], v[20:21], 0, v[4:5]
	ds_read_b32 v4, v23
	ds_read_b32 v33, v23 offset:132
	ds_read_b32 v35, v23 offset:264
	ds_read_b32 v36, v23 offset:396
	ds_read_b32 v37, v23 offset:528
	ds_read_b32 v38, v23 offset:660
	ds_read_b32 v39, v23 offset:792
	ds_read_b32 v40, v23 offset:924
	s_waitcnt lgkmcnt(0)
	v_bfe_u32 v34, v4, 16, 1
	v_add3_u32 v4, v4, v34, s38
	v_bfe_u32 v34, v33, 16, 1
	v_lshrrev_b32_e32 v4, 16, v4
	v_add3_u32 v33, v33, v34, s38
	v_and_or_b32 v34, v33, s39, v4
	v_bfe_u32 v4, v35, 16, 1
	v_add3_u32 v4, v35, v4, s38
	v_bfe_u32 v33, v36, 16, 1
	v_lshrrev_b32_e32 v4, 16, v4
	v_add3_u32 v33, v36, v33, s38
	v_and_or_b32 v35, v33, s39, v4
	v_bfe_u32 v4, v37, 16, 1
	v_add3_u32 v4, v37, v4, s38
	v_bfe_u32 v33, v38, 16, 1
	v_lshrrev_b32_e32 v4, 16, v4
	v_add3_u32 v33, v38, v33, s38
	v_and_or_b32 v36, v33, s39, v4
	v_bfe_u32 v4, v39, 16, 1
	v_add3_u32 v4, v39, v4, s38
	v_bfe_u32 v33, v40, 16, 1
	v_lshrrev_b32_e32 v4, 16, v4
	v_add3_u32 v33, v40, v33, s38
	v_and_or_b32 v37, v33, s39, v4
	v_or_b32_e32 v4, v52, v7
	v_mul_u32_u24_e32 v4, 0xc00, v4
	v_lshl_add_u64 v[20:21], v[20:21], 0, s[30:31]
	v_lshlrev_b32_e32 v4, 1, v4
	v_lshl_add_u64 v[38:39], v[20:21], 0, v[4:5]
	global_store_dwordx4 v[38:39], v[34:37], off
	ds_read_b32 v4, v23 offset:32
	ds_read_b32 v33, v23 offset:164
	ds_read_b32 v35, v23 offset:296
	ds_read_b32 v36, v23 offset:428
	ds_read_b32 v37, v23 offset:560
	ds_read_b32 v38, v23 offset:692
	ds_read_b32 v39, v23 offset:824
	ds_read_b32 v40, v23 offset:956
	s_waitcnt lgkmcnt(0)
	v_bfe_u32 v34, v4, 16, 1
	v_add3_u32 v4, v4, v34, s38
	v_bfe_u32 v34, v33, 16, 1
	v_lshrrev_b32_e32 v4, 16, v4
	v_add3_u32 v33, v33, v34, s38
	v_and_or_b32 v34, v33, s39, v4
	v_bfe_u32 v4, v35, 16, 1
	v_add3_u32 v4, v35, v4, s38
	v_bfe_u32 v33, v36, 16, 1
	v_lshrrev_b32_e32 v4, 16, v4
	v_add3_u32 v33, v36, v33, s38
	v_and_or_b32 v35, v33, s39, v4
	v_bfe_u32 v4, v37, 16, 1
	v_add3_u32 v4, v37, v4, s38
	v_bfe_u32 v33, v38, 16, 1
	v_lshrrev_b32_e32 v4, 16, v4
	v_add3_u32 v33, v38, v33, s38
	v_and_or_b32 v36, v33, s39, v4
	v_bfe_u32 v4, v39, 16, 1
	v_add3_u32 v4, v39, v4, s38
	v_bfe_u32 v33, v40, 16, 1
	v_lshrrev_b32_e32 v4, 16, v4
	v_add3_u32 v33, v40, v33, s38
	v_and_or_b32 v37, v33, s39, v4
	v_or_b32_e32 v4, v52, v24
	v_mul_u32_u24_e32 v4, 0xc00, v4
	v_lshlrev_b32_e32 v4, 1, v4
	v_lshl_add_u64 v[38:39], v[20:21], 0, v[4:5]
	global_store_dwordx4 v[38:39], v[34:37], off
	ds_read_b32 v4, v23 offset:64
	ds_read_b32 v33, v23 offset:196
	ds_read_b32 v35, v23 offset:328
	ds_read_b32 v36, v23 offset:460
	ds_read_b32 v37, v23 offset:592
	ds_read_b32 v38, v23 offset:724
	ds_read_b32 v39, v23 offset:856
	ds_read_b32 v40, v23 offset:988
	s_waitcnt lgkmcnt(0)
	v_bfe_u32 v34, v4, 16, 1
	v_add3_u32 v4, v4, v34, s38
	v_bfe_u32 v34, v33, 16, 1
	v_lshrrev_b32_e32 v4, 16, v4
	v_add3_u32 v33, v33, v34, s38
	v_and_or_b32 v34, v33, s39, v4
	v_bfe_u32 v4, v35, 16, 1
	v_add3_u32 v4, v35, v4, s38
	v_bfe_u32 v33, v36, 16, 1
	v_lshrrev_b32_e32 v4, 16, v4
	v_add3_u32 v33, v36, v33, s38
	v_and_or_b32 v35, v33, s39, v4
	v_bfe_u32 v4, v37, 16, 1
	v_add3_u32 v4, v37, v4, s38
	v_bfe_u32 v33, v38, 16, 1
	v_lshrrev_b32_e32 v4, 16, v4
	v_add3_u32 v33, v38, v33, s38
	v_and_or_b32 v36, v33, s39, v4
	v_bfe_u32 v4, v39, 16, 1
	v_add3_u32 v4, v39, v4, s38
	v_bfe_u32 v33, v40, 16, 1
	v_lshrrev_b32_e32 v4, 16, v4
	v_add3_u32 v33, v40, v33, s38
	v_and_or_b32 v37, v33, s39, v4
	v_or_b32_e32 v4, v52, v25
	v_mul_u32_u24_e32 v4, 0xc00, v4
	v_lshlrev_b32_e32 v4, 1, v4
	v_lshl_add_u64 v[38:39], v[20:21], 0, v[4:5]
	global_store_dwordx4 v[38:39], v[34:37], off
	ds_read_b32 v4, v23 offset:96
	ds_read_b32 v33, v23 offset:228
	ds_read_b32 v35, v23 offset:360
	ds_read_b32 v36, v23 offset:492
	ds_read_b32 v37, v23 offset:624
	ds_read_b32 v38, v23 offset:756
	ds_read_b32 v39, v23 offset:888
	ds_read_b32 v40, v23 offset:1020
	s_waitcnt lgkmcnt(0)
	v_bfe_u32 v34, v4, 16, 1
	v_add3_u32 v4, v4, v34, s38
	v_bfe_u32 v34, v33, 16, 1
	v_lshrrev_b32_e32 v4, 16, v4
	v_add3_u32 v33, v33, v34, s38
	v_and_or_b32 v34, v33, s39, v4
	v_bfe_u32 v4, v35, 16, 1
	v_add3_u32 v4, v35, v4, s38
	v_bfe_u32 v33, v36, 16, 1
	v_lshrrev_b32_e32 v4, 16, v4
	v_add3_u32 v33, v36, v33, s38
	v_and_or_b32 v35, v33, s39, v4
	v_bfe_u32 v4, v37, 16, 1
	v_add3_u32 v4, v37, v4, s38
	v_bfe_u32 v33, v38, 16, 1
	v_lshrrev_b32_e32 v4, 16, v4
	v_add3_u32 v33, v38, v33, s38
	v_and_or_b32 v36, v33, s39, v4
	v_bfe_u32 v4, v39, 16, 1
	v_add3_u32 v4, v39, v4, s38
	v_bfe_u32 v33, v40, 16, 1
	v_lshrrev_b32_e32 v4, 16, v4
	v_add3_u32 v33, v40, v33, s38
	v_and_or_b32 v37, v33, s39, v4
	v_or_b32_e32 v4, v52, v26
	v_mul_u32_u24_e32 v4, 0xc00, v4
	v_lshlrev_b32_e32 v4, 1, v4
	v_lshl_add_u64 v[20:21], v[20:21], 0, v[4:5]
	global_store_dwordx4 v[20:21], v[34:37], off
	s_waitcnt lgkmcnt(0)

;     ...
;     for (int i = 0; i < 32; ++i) tv_[i] = W[(size_t)(k0 + 2 * i + (lane >> 5)) * N + n0 + (lane & 31)];
; #pragma unroll
;     for (int i = 0; i < 32; ++i) scr[(2 * i + (lane >> 5)) * 33 + (lane & 31)] = tv_[i];
; __device__ __forceinline__ void convert_range(LAS unsigned char* lds, const Params& p, const int lo, const int hi, const int gw, const int NGW) {
;     ...
;         if (r < 2 * I_PA) { const int l = r / I_PA; r -= l * I_PA; p0_transpose_item(p.in[16] + (size_t)l * PW * DM, PW, DM, (bf16*)(ws + WS_WCAT + l * SZ_WCAT), scr, r, lane, KCAT, 0); continue; } r -= 2 * I_PA;
.LBB0_72:
	s_andn2_saveexec_b64 s[26:27], s[26:27]
	s_cbranch_execz .LBB0_74
	v_add_u32_e32 v4, 0x2a00, v27
	v_lshrrev_b32_e32 v4, 10, v4
	v_readlane_b32 s68, v251, 9
	v_lshlrev_b64 v[34:35], 23, v[4:5]
	v_readlane_b32 s69, v251, 10
	v_mov_b64_e32 v[36:37], s[20:21]
	v_and_b32_e32 v52, 0x7e0, v30
	v_lshl_add_u64 v[34:35], s[68:69], 0, v[34:35]
	v_mad_u64_u32 v[36:37], s[28:29], v4, s88, v[36:37]
	v_and_b32_e32 v33, 0x3c0, v20
	v_lshlrev_b32_e32 v4, 2, v52
	v_or_b32_e32 v38, v33, v1
	v_lshl_add_u64 v[20:21], v[34:35], 0, v[4:5]
	v_lshlrev_b32_e32 v4, 2, v2
	v_lshl_add_u64 v[20:21], v[20:21], 0, v[4:5]
	v_lshlrev_b32_e32 v4, 13, v38
	v_lshl_add_u64 v[20:21], v[20:21], 0, v[4:5]
	v_add_co_u32_e32 v34, vcc, s7, v20
	v_readlane_b32 s70, v251, 11
	s_nop 0
	v_addc_co_u32_e32 v35, vcc, 0, v21, vcc
	v_add_co_u32_e32 v38, vcc, s40, v20
	v_readlane_b32 s71, v251, 12
	s_nop 0
	v_addc_co_u32_e32 v39, vcc, 0, v21, vcc
	v_add_co_u32_e32 v40, vcc, s42, v20
	v_readlane_b32 s72, v251, 13
	s_nop 0
	v_addc_co_u32_e32 v41, vcc, 0, v21, vcc
	v_add_co_u32_e32 v42, vcc, s43, v20
	v_readlane_b32 s73, v251, 14
	s_nop 0
	v_addc_co_u32_e32 v43, vcc, 0, v21, vcc
	v_add_co_u32_e32 v44, vcc, s44, v20
	v_readlane_b32 s74, v251, 15
	s_nop 0
	v_addc_co_u32_e32 v45, vcc, 0, v21, vcc
	v_add_co_u32_e32 v46, vcc, s45, v20
	v_readlane_b32 s75, v251, 16
	s_nop 0
	v_addc_co_u32_e32 v47, vcc, 0, v21, vcc
	v_add_co_u32_e32 v48, vcc, s47, v20
	s_nop 1
	v_addc_co_u32_e32 v49, vcc, 0, v21, vcc
	global_load_dword v4, v[20:21], off
	global_load_dword v53, v[34:35], off
	global_load_dword v54, v[38:39], off
	global_load_dword v55, v[40:41], off
	global_load_dword v56, v[42:43], off
	global_load_dword v57, v[44:45], off
	global_load_dword v58, v[46:47], off
	global_load_dword v59, v[48:49], off
	v_add_co_u32_e32 v34, vcc, s48, v20
	s_nop 1
	v_addc_co_u32_e32 v35, vcc, 0, v21, vcc
	v_add_co_u32_e32 v38, vcc, s49, v20
	s_nop 1
	v_addc_co_u32_e32 v39, vcc, 0, v21, vcc
	v_add_co_u32_e32 v40, vcc, s50, v20
	s_nop 1
	v_addc_co_u32_e32 v41, vcc, 0, v21, vcc
	v_add_co_u32_e32 v42, vcc, s51, v20
	s_nop 1
	v_addc_co_u32_e32 v43, vcc, 0, v21, vcc
	v_add_co_u32_e32 v44, vcc, s52, v20
	s_nop 1
	v_addc_co_u32_e32 v45, vcc, 0, v21, vcc
	v_add_co_u32_e32 v46, vcc, s53, v20
	s_nop 1
	v_addc_co_u32_e32 v47, vcc, 0, v21, vcc
	v_add_co_u32_e32 v48, vcc, s54, v20
	s_nop 1
	v_addc_co_u32_e32 v49, vcc, 0, v21, vcc
	v_add_co_u32_e32 v50, vcc, s55, v20
	s_nop 1
	v_addc_co_u32_e32 v51, vcc, 0, v21, vcc
	global_load_dword v60, v[34:35], off
	global_load_dword v61, v[38:39], off
	global_load_dword v62, v[40:41], off
	global_load_dword v63, v[42:43], off
	global_load_dword v64, v[44:45], off
	global_load_dword v65, v[46:47], off
	global_load_dword v66, v[48:49], off
	global_load_dword v67, v[50:51], off
	v_add_co_u32_e32 v34, vcc, s56, v20
	s_nop 1
	v_addc_co_u32_e32 v35, vcc, 0, v21, vcc
	v_add_co_u32_e32 v38, vcc, s57, v20
	s_nop 1
	v_addc_co_u32_e32 v39, vcc, 0, v21, vcc
	v_add_co_u32_e32 v40, vcc, s58, v20
	s_nop 1
	v_addc_co_u32_e32 v41, vcc, 0, v21, vcc
	v_add_co_u32_e32 v42, vcc, s59, v20
	s_nop 1
	v_addc_co_u32_e32 v43, vcc, 0, v21, vcc
	v_add_co_u32_e32 v44, vcc, s76, v20
	s_nop 1
	v_addc_co_u32_e32 v45, vcc, 0, v21, vcc
	v_add_co_u32_e32 v46, vcc, s77, v20
	s_nop 1
	v_addc_co_u32_e32 v47, vcc, 0, v21, vcc
	v_add_co_u32_e32 v48, vcc, s78, v20
	s_nop 1
	v_addc_co_u32_e32 v49, vcc, 0, v21, vcc
	v_add_co_u32_e32 v50, vcc, s79, v20
	s_nop 1
	v_addc_co_u32_e32 v51, vcc, 0, v21, vcc
	global_load_dword v68, v[34:35], off
	global_load_dword v69, v[38:39], off
	global_load_dword v70, v[40:41], off
	global_load_dword v71, v[42:43], off
	global_load_dword v72, v[44:45], off
	global_load_dword v73, v[46:47], off
	global_load_dword v74, v[48:49], off
	s_nop 0
	global_load_dword v50, v[50:51], off
	v_add_co_u32_e32 v34, vcc, s80, v20
	s_nop 1
	v_addc_co_u32_e32 v35, vcc, 0, v21, vcc
	v_add_co_u32_e32 v38, vcc, s81, v20
	s_nop 1
	v_addc_co_u32_e32 v39, vcc, 0, v21, vcc
	v_add_co_u32_e32 v40, vcc, s82, v20
	s_nop 1
	v_addc_co_u32_e32 v41, vcc, 0, v21, vcc
	v_add_co_u32_e32 v42, vcc, s83, v20
	s_nop 1
	v_addc_co_u32_e32 v43, vcc, 0, v21, vcc
	v_add_co_u32_e32 v44, vcc, s84, v20
	s_nop 1
	v_addc_co_u32_e32 v45, vcc, 0, v21, vcc
	v_add_co_u32_e32 v46, vcc, s85, v20
	s_nop 1
	v_addc_co_u32_e32 v47, vcc, 0, v21, vcc
	v_add_co_u32_e32 v48, vcc, s86, v20
	s_nop 1
	v_addc_co_u32_e32 v49, vcc, 0, v21, vcc
	v_add_co_u32_e32 v20, vcc, s87, v20
	s_nop 1
	v_addc_co_u32_e32 v21, vcc, 0, v21, vcc
	global_load_dword v34, v[34:35], off
	s_nop 0
	global_load_dword v35, v[38:39], off
	s_nop 0
	global_load_dword v38, v[40:41], off
	global_load_dword v39, v[42:43], off
	s_nop 0
	global_load_dword v40, v[44:45], off
	global_load_dword v41, v[46:47], off
	global_load_dword v42, v[48:49], off
	s_nop 0
	global_load_dword v20, v[20:21], off
	s_waitcnt vmcnt(30)
	ds_write2_b32 v3, v4, v53 offset1:66
	s_waitcnt vmcnt(28)
	ds_write2_b32 v3, v54, v55 offset0:132 offset1:198
	s_waitcnt vmcnt(26)
	ds_write2_b32 v31, v56, v57 offset0:8 offset1:74
	s_waitcnt vmcnt(24)
	ds_write2_b32 v31, v58, v59 offset0:140 offset1:206
	s_waitcnt vmcnt(22)
	ds_write2_b32 v32, v60, v61 offset0:16 offset1:82
	s_waitcnt vmcnt(20)
	ds_write2_b32 v32, v62, v63 offset0:148 offset1:214
	v_add_u32_e32 v4, 0xc00, v3
	s_waitcnt vmcnt(18)
	ds_write2_b32 v4, v64, v65 offset0:24 offset1:90
	s_waitcnt vmcnt(16)
	ds_write2_b32 v4, v66, v67 offset0:156 offset1:222
	v_add_u32_e32 v4, 0x1000, v3
	s_waitcnt vmcnt(14)
; #define LAS __attribute__((address_space(3)))
; #define LDS_WAIT() asm volatile("s_waitcnt lgkmcnt(0)" ::: "memory")
; __device__ __forceinline__ unsigned pk2(float lo, float hi) { return f2bf(lo) | (f2bf(hi) << 16); }
;     ...
;     for (int i = 0; i < 32; ++i) scr[(2 * i + (lane >> 5)) * 33 + (lane & 31)] = tv_[i];
;     LDS_WAIT(); asm volatile("" ::: "memory");
;     const int c = lane & 7;
; #pragma unroll
;     for (int j = 0; j < 4; ++j) { const int n = (lane >> 3) + 8 * j; const LAS float* s = scr + (8 * c) * 33 + n;
;         v4u o; o.x = pk2(s[0 * 33], s[1 * 33]); o.y = pk2(s[2 * 33], s[3 * 33]); o.z = pk2(s[4 * 33], s[5 * 33]); o.w = pk2(s[6 * 33], s[7 * 33]);
;         *(v4u*)(WT + (size_t)(n0 + n) * ldw + koff + k0 + 8 * c) = o; }
	ds_write2_b32 v4, v68, v69 offset0:32 offset1:98
	s_waitcnt vmcnt(12)
	ds_write2_b32 v4, v70, v71 offset0:164 offset1:230
	v_add_u32_e32 v4, 0x1400, v3
	s_waitcnt vmcnt(10)
	ds_write2_b32 v4, v72, v73 offset0:40 offset1:106
	s_waitcnt vmcnt(8)
	ds_write2_b32 v4, v74, v50 offset0:172 offset1:238
	v_add_u32_e32 v4, 0x1800, v3
	s_waitcnt vmcnt(6)
	ds_write2_b32 v4, v34, v35 offset0:48 offset1:114
	s_waitcnt vmcnt(4)
	ds_write2_b32 v4, v38, v39 offset0:180 offset1:246
	v_add_u32_e32 v4, 0x1c00, v3
	s_waitcnt vmcnt(2)
	ds_write2_b32 v4, v40, v41 offset0:56 offset1:122
	s_waitcnt vmcnt(0)
	ds_write2_b32 v4, v42, v20 offset0:188 offset1:254
	s_waitcnt lgkmcnt(0)
	v_lshlrev_b32_e32 v4, 1, v33
	v_lshl_add_u64 v[20:21], v[36:37], 0, v[4:5]
	v_lshlrev_b32_e32 v4, 1, v6
	v_lshl_add_u64 v[20:21], v[20:21], 0, v[4:5]
	ds_read_b32 v4, v23
	ds_read_b32 v33, v23 offset:132
	ds_read_b32 v35, v23 offset:264
	ds_read_b32 v36, v23 offset:396
	ds_read_b32 v37, v23 offset:528
	ds_read_b32 v38, v23 offset:660
	ds_read_b32 v39, v23 offset:792
	ds_read_b32 v40, v23 offset:924
	s_waitcnt lgkmcnt(0)
	v_bfe_u32 v34, v4, 16, 1
	v_add3_u32 v4, v4, v34, s38
	v_bfe_u32 v34, v33, 16, 1
	v_lshrrev_b32_e32 v4, 16, v4
	v_add3_u32 v33, v33, v34, s38
	v_and_or_b32 v34, v33, s39, v4
	v_bfe_u32 v4, v35, 16, 1
	v_add3_u32 v4, v35, v4, s38
	v_bfe_u32 v33, v36, 16, 1
	v_lshrrev_b32_e32 v4, 16, v4
	v_add3_u32 v33, v36, v33, s38
	v_and_or_b32 v35, v33, s39, v4
	v_bfe_u32 v4, v37, 16, 1
	v_add3_u32 v4, v37, v4, s38
	v_bfe_u32 v33, v38, 16, 1
	v_lshrrev_b32_e32 v4, 16, v4
	v_add3_u32 v33, v38, v33, s38
	v_and_or_b32 v36, v33, s39, v4
	v_bfe_u32 v4, v39, 16, 1
	v_add3_u32 v4, v39, v4, s38
	v_bfe_u32 v33, v40, 16, 1
	v_lshrrev_b32_e32 v4, 16, v4
	v_add3_u32 v33, v40, v33, s38
	v_and_or_b32 v37, v33, s39, v4
	v_or_b32_e32 v4, v52, v7
	v_mul_u32_u24_e32 v4, 0xc00, v4
	v_lshlrev_b32_e32 v4, 1, v4
	v_lshl_add_u64 v[38:39], v[20:21], 0, v[4:5]
	global_store_dwordx4 v[38:39], v[34:37], off
	ds_read_b32 v4, v23 offset:32
	ds_read_b32 v33, v23 offset:164
	ds_read_b32 v35, v23 offset:296
	ds_read_b32 v36, v23 offset:428
	ds_read_b32 v37, v23 offset:560
	ds_read_b32 v38, v23 offset:692
	ds_read_b32 v39, v23 offset:824
	ds_read_b32 v40, v23 offset:956
	s_waitcnt lgkmcnt(0)
	v_bfe_u32 v34, v4, 16, 1
	v_add3_u32 v4, v4, v34, s38
	v_bfe_u32 v34, v33, 16, 1
	v_lshrrev_b32_e32 v4, 16, v4
	v_add3_u32 v33, v33, v34, s38
	v_and_or_b32 v34, v33, s39, v4
	v_bfe_u32 v4, v35, 16, 1
	v_add3_u32 v4, v35, v4, s38
	v_bfe_u32 v33, v36, 16, 1
	v_lshrrev_b32_e32 v4, 16, v4
	v_add3_u32 v33, v36, v33, s38
	v_and_or_b32 v35, v33, s39, v4
	v_bfe_u32 v4, v37, 16, 1
	v_add3_u32 v4, v37, v4, s38
	v_bfe_u32 v33, v38, 16, 1
	v_lshrrev_b32_e32 v4, 16, v4
	v_add3_u32 v33, v38, v33, s38
	v_and_or_b32 v36, v33, s39, v4
	v_bfe_u32 v4, v39, 16, 1
	v_add3_u32 v4, v39, v4, s38
	v_bfe_u32 v33, v40, 16, 1
	v_lshrrev_b32_e32 v4, 16, v4
	v_add3_u32 v33, v40, v33, s38
	v_and_or_b32 v37, v33, s39, v4
	v_or_b32_e32 v4, v52, v24
	v_mul_u32_u24_e32 v4, 0xc00, v4
	v_lshlrev_b32_e32 v4, 1, v4
	v_lshl_add_u64 v[38:39], v[20:21], 0, v[4:5]
	global_store_dwordx4 v[38:39], v[34:37], off
	ds_read_b32 v4, v23 offset:64
	ds_read_b32 v33, v23 offset:196
	ds_read_b32 v35, v23 offset:328
	ds_read_b32 v36, v23 offset:460
	ds_read_b32 v37, v23 offset:592
	ds_read_b32 v38, v23 offset:724
	ds_read_b32 v39, v23 offset:856
	ds_read_b32 v40, v23 offset:988
	s_waitcnt lgkmcnt(0)
	v_bfe_u32 v34, v4, 16, 1
	v_add3_u32 v4, v4, v34, s38
	v_bfe_u32 v34, v33, 16, 1
	v_lshrrev_b32_e32 v4, 16, v4
	v_add3_u32 v33, v33, v34, s38
	v_and_or_b32 v34, v33, s39, v4
	v_bfe_u32 v4, v35, 16, 1
	v_add3_u32 v4, v35, v4, s38
	v_bfe_u32 v33, v36, 16, 1
	v_lshrrev_b32_e32 v4, 16, v4
	v_add3_u32 v33, v36, v33, s38
	v_and_or_b32 v35, v33, s39, v4
	v_bfe_u32 v4, v37, 16, 1
	v_add3_u32 v4, v37, v4, s38
	v_bfe_u32 v33, v38, 16, 1
	v_lshrrev_b32_e32 v4, 16, v4
	v_add3_u32 v33, v38, v33, s38
	v_and_or_b32 v36, v33, s39, v4
	v_bfe_u32 v4, v39, 16, 1
	v_add3_u32 v4, v39, v4, s38
	v_bfe_u32 v33, v40, 16, 1
	v_lshrrev_b32_e32 v4, 16, v4
	v_add3_u32 v33, v40, v33, s38
	v_and_or_b32 v37, v33, s39, v4
	v_or_b32_e32 v4, v52, v25
	v_mul_u32_u24_e32 v4, 0xc00, v4
	v_lshlrev_b32_e32 v4, 1, v4
	v_lshl_add_u64 v[38:39], v[20:21], 0, v[4:5]
	global_store_dwordx4 v[38:39], v[34:37], off
	ds_read_b32 v4, v23 offset:96
	ds_read_b32 v33, v23 offset:228
	ds_read_b32 v35, v23 offset:360
	ds_read_b32 v36, v23 offset:492
	ds_read_b32 v37, v23 offset:624
	ds_read_b32 v38, v23 offset:756
	ds_read_b32 v39, v23 offset:888
	ds_read_b32 v40, v23 offset:1020
	s_waitcnt lgkmcnt(0)
	v_bfe_u32 v34, v4, 16, 1
	v_add3_u32 v4, v4, v34, s38
	v_bfe_u32 v34, v33, 16, 1
	v_lshrrev_b32_e32 v4, 16, v4
	v_add3_u32 v33, v33, v34, s38
	v_and_or_b32 v34, v33, s39, v4
	v_bfe_u32 v4, v35, 16, 1
	v_add3_u32 v4, v35, v4, s38
	v_bfe_u32 v33, v36, 16, 1
	v_lshrrev_b32_e32 v4, 16, v4
	v_add3_u32 v33, v36, v33, s38
	v_and_or_b32 v35, v33, s39, v4
	v_bfe_u32 v4, v37, 16, 1
	v_add3_u32 v4, v37, v4, s38
	v_bfe_u32 v33, v38, 16, 1
	v_lshrrev_b32_e32 v4, 16, v4
	v_add3_u32 v33, v38, v33, s38
	v_and_or_b32 v36, v33, s39, v4
	v_bfe_u32 v4, v39, 16, 1
	v_add3_u32 v4, v39, v4, s38
	v_bfe_u32 v33, v40, 16, 1
	v_lshrrev_b32_e32 v4, 16, v4
	v_add3_u32 v33, v40, v33, s38
	v_and_or_b32 v37, v33, s39, v4
	v_or_b32_e32 v4, v52, v26
	v_mul_u32_u24_e32 v4, 0xc00, v4
	v_lshlrev_b32_e32 v4, 1, v4
	v_lshl_add_u64 v[20:21], v[20:21], 0, v[4:5]
	global_store_dwordx4 v[20:21], v[34:37], off
	s_waitcnt lgkmcnt(0)

;     ...
;     float tv_[32];
; #pragma unroll
;     for (int i = 0; i < 32; ++i) tv_[i] = W[(size_t)(k0 + 2 * i + (lane >> 5)) * N + n0 + (lane & 31)];
; #pragma unroll
;     for (int i = 0; i < 32; ++i) scr[(2 * i + (lane >> 5)) * 33 + (lane & 31)] = tv_[i];
; __device__ __forceinline__ void convert_range(LAS unsigned char* lds, const Params& p, const int lo, const int hi, const int gw, const int NGW) {
;     ...
;         if (r < 2 * I_IN) { const int l = r / I_IN; r -= l * I_IN; p0_transpose_item(p.in[5] + (size_t)l * DM * NC, DM, NC, (bf16*)(ws + WS_WIN + l * SZ_WIN), scr, r, lane); continue; } r -= 2 * I_IN;
.LBB0_75:
	s_andn2_saveexec_b64 s[24:25], s[24:25]
	s_cbranch_execz .LBB0_52
	v_mul_hi_i32 v4, v20, s89
	v_lshrrev_b32_e32 v20, 31, v4
	v_ashrrev_i32_e32 v4, 12, v4
	v_add_u32_e32 v33, v4, v20
	v_readlane_b32 s60, v251, 21
	v_mul_i32_i24_e32 v4, 0xffffd800, v33
	s_movk_i32 s26, 0x7a00
	v_readlane_b32 s70, v251, 31
	v_readlane_b32 s71, v251, 32
	v_add3_u32 v4, v4, v27, s26
	s_mov_b32 s26, 0x5000000
	v_mov_b64_e32 v[20:21], s[70:71]
	v_mad_i64_i32 v[34:35], s[26:27], v33, s26, v[20:21]
	v_mul_hi_i32 v20, v4, s89
	v_lshrrev_b32_e32 v21, 31, v20
	v_ashrrev_i32_e32 v20, 7, v20
	v_add_u32_e32 v20, v20, v21
	v_mul_i32_i24_e32 v21, 0x140, v20
	v_sub_u32_e32 v4, v4, v21
	v_lshlrev_b32_e32 v36, 6, v20
	v_lshlrev_b32_e32 v20, 5, v4
	v_ashrrev_i32_e32 v21, 31, v20
	v_or_b32_e32 v37, v36, v1
	v_lshl_add_u64 v[34:35], v[20:21], 2, v[34:35]
	v_lshlrev_b32_e32 v4, 2, v2
	v_lshl_add_u64 v[34:35], v[34:35], 0, v[4:5]
	v_or_b32_e32 v4, 2, v37
	v_mad_i64_i32 v[40:41], s[26:27], v4, s41, v[34:35]
	v_or_b32_e32 v4, 4, v37
	v_mad_i64_i32 v[42:43], s[26:27], v4, s41, v[34:35]
	v_or_b32_e32 v4, 6, v37
	v_mad_i64_i32 v[44:45], s[26:27], v4, s41, v[34:35]
	v_or_b32_e32 v4, 8, v37
	v_mad_i64_i32 v[46:47], s[26:27], v4, s41, v[34:35]
	v_or_b32_e32 v4, 10, v37
	v_mad_i64_i32 v[48:49], s[26:27], v4, s41, v[34:35]
	v_or_b32_e32 v4, 12, v37
	v_mad_i64_i32 v[50:51], s[26:27], v4, s41, v[34:35]
	v_or_b32_e32 v4, 14, v37
	v_mad_i64_i32 v[38:39], s[26:27], v37, s41, v[34:35]
	v_mad_i64_i32 v[52:53], s[26:27], v4, s41, v[34:35]
	global_load_dword v4, v[38:39], off
	global_load_dword v21, v[40:41], off
	global_load_dword v54, v[42:43], off
	global_load_dword v55, v[44:45], off
	global_load_dword v56, v[46:47], off
	global_load_dword v57, v[48:49], off
	global_load_dword v58, v[50:51], off
	global_load_dword v59, v[52:53], off
	v_or_b32_e32 v38, 16, v37
	v_or_b32_e32 v40, 18, v37
	v_or_b32_e32 v42, 20, v37
	v_or_b32_e32 v44, 22, v37
	v_or_b32_e32 v52, 30, v37
	v_mad_i64_i32 v[38:39], s[26:27], v38, s41, v[34:35]
	v_mad_i64_i32 v[40:41], s[26:27], v40, s41, v[34:35]
	v_mad_i64_i32 v[42:43], s[26:27], v42, s41, v[34:35]
	v_mad_i64_i32 v[44:45], s[26:27], v44, s41, v[34:35]
	v_or_b32_e32 v46, 24, v37
	v_or_b32_e32 v48, 26, v37
	v_or_b32_e32 v50, 28, v37
	v_mad_i64_i32 v[52:53], s[26:27], v52, s41, v[34:35]
	v_mad_i64_i32 v[46:47], s[26:27], v46, s41, v[34:35]
	v_mad_i64_i32 v[48:49], s[26:27], v48, s41, v[34:35]
	v_mad_i64_i32 v[50:51], s[26:27], v50, s41, v[34:35]
	global_load_dword v60, v[38:39], off
	global_load_dword v61, v[40:41], off
	global_load_dword v62, v[42:43], off
	global_load_dword v63, v[44:45], off
	global_load_dword v64, v[46:47], off
	global_load_dword v65, v[48:49], off
	global_load_dword v66, v[50:51], off
	global_load_dword v67, v[52:53], off
	v_or_b32_e32 v38, 32, v37
	v_or_b32_e32 v40, 34, v37
	v_or_b32_e32 v42, 36, v37
	v_or_b32_e32 v44, 38, v37
	v_or_b32_e32 v52, 46, v37
	v_mad_i64_i32 v[38:39], s[26:27], v38, s41, v[34:35]
	v_mad_i64_i32 v[40:41], s[26:27], v40, s41, v[34:35]
	v_mad_i64_i32 v[42:43], s[26:27], v42, s41, v[34:35]
	v_mad_i64_i32 v[44:45], s[26:27], v44, s41, v[34:35]
	v_or_b32_e32 v46, 40, v37
	v_or_b32_e32 v48, 42, v37
	v_or_b32_e32 v50, 44, v37
	v_mad_i64_i32 v[52:53], s[26:27], v52, s41, v[34:35]
	v_mad_i64_i32 v[46:47], s[26:27], v46, s41, v[34:35]
	v_mad_i64_i32 v[48:49], s[26:27], v48, s41, v[34:35]
	v_mad_i64_i32 v[50:51], s[26:27], v50, s41, v[34:35]
	global_load_dword v68, v[38:39], off
	global_load_dword v69, v[40:41], off
	global_load_dword v70, v[42:43], off
	global_load_dword v71, v[44:45], off
	global_load_dword v72, v[46:47], off
	global_load_dword v73, v[48:49], off
	global_load_dword v74, v[50:51], off
	s_nop 0
	global_load_dword v52, v[52:53], off
	v_or_b32_e32 v38, 48, v37
	v_or_b32_e32 v40, 50, v37
	v_or_b32_e32 v42, 52, v37
	v_or_b32_e32 v44, 54, v37
	v_mad_i64_i32 v[38:39], s[26:27], v38, s41, v[34:35]
	v_mad_i64_i32 v[40:41], s[26:27], v40, s41, v[34:35]
	v_mad_i64_i32 v[42:43], s[26:27], v42, s41, v[34:35]
	v_mad_i64_i32 v[44:45], s[26:27], v44, s41, v[34:35]
	v_or_b32_e32 v46, 56, v37
	v_or_b32_e32 v48, 58, v37
	v_or_b32_e32 v50, 60, v37
	v_or_b32_e32 v37, 62, v37
	v_mad_i64_i32 v[46:47], s[26:27], v46, s41, v[34:35]
	v_mad_i64_i32 v[48:49], s[26:27], v48, s41, v[34:35]
	v_mad_i64_i32 v[50:51], s[26:27], v50, s41, v[34:35]
	v_mad_i64_i32 v[34:35], s[26:27], v37, s41, v[34:35]
	global_load_dword v37, v[38:39], off
	s_nop 0
	global_load_dword v38, v[40:41], off
	global_load_dword v39, v[42:43], off
	s_nop 0
	global_load_dword v40, v[44:45], off
	global_load_dword v41, v[46:47], off
	global_load_dword v42, v[48:49], off
	global_load_dword v43, v[50:51], off
	s_nop 0
	global_load_dword v44, v[34:35], off
	s_waitcnt vmcnt(30)
	ds_write2_b32 v3, v4, v21 offset1:66
	s_waitcnt vmcnt(28)
	ds_write2_b32 v3, v54, v55 offset0:132 offset1:198
	s_waitcnt vmcnt(26)
	ds_write2_b32 v31, v56, v57 offset0:8 offset1:74
	s_waitcnt vmcnt(24)
	ds_write2_b32 v31, v58, v59 offset0:140 offset1:206
	s_waitcnt vmcnt(22)
	ds_write2_b32 v32, v60, v61 offset0:16 offset1:82
	s_waitcnt vmcnt(20)
	ds_write2_b32 v32, v62, v63 offset0:148 offset1:214
	v_add_u32_e32 v4, 0xc00, v3
	s_waitcnt vmcnt(18)
	ds_write2_b32 v4, v64, v65 offset0:24 offset1:90
	s_waitcnt vmcnt(16)
	ds_write2_b32 v4, v66, v67 offset0:156 offset1:222
	v_add_u32_e32 v4, 0x1000, v3
	s_waitcnt vmcnt(14)
	ds_write2_b32 v4, v68, v69 offset0:32 offset1:98
	s_waitcnt vmcnt(12)
	ds_write2_b32 v4, v70, v71 offset0:164 offset1:230
	v_add_u32_e32 v4, 0x1400, v3
	s_waitcnt vmcnt(10)
	ds_write2_b32 v4, v72, v73 offset0:40 offset1:106
	s_waitcnt vmcnt(8)
; #define LAS __attribute__((address_space(3)))
; #define LDS_WAIT() asm volatile("s_waitcnt lgkmcnt(0)" ::: "memory")
; __device__ __forceinline__ unsigned pk2(float lo, float hi) { return f2bf(lo) | (f2bf(hi) << 16); }
;     ...
;     for (int i = 0; i < 32; ++i) scr[(2 * i + (lane >> 5)) * 33 + (lane & 31)] = tv_[i];
;     LDS_WAIT(); asm volatile("" ::: "memory");
;     const int c = lane & 7;
; #pragma unroll
;     for (int j = 0; j < 4; ++j) { const int n = (lane >> 3) + 8 * j; const LAS float* s = scr + (8 * c) * 33 + n;
;         v4u o; o.x = pk2(s[0 * 33], s[1 * 33]); o.y = pk2(s[2 * 33], s[3 * 33]); o.z = pk2(s[4 * 33], s[5 * 33]); o.w = pk2(s[6 * 33], s[7 * 33]);
;         *(v4u*)(WT + (size_t)(n0 + n) * ldw + koff + k0 + 8 * c) = o; }
;     LDS_WAIT(); asm volatile("" ::: "memory");
	ds_write2_b32 v4, v74, v52 offset0:172 offset1:238
	v_add_u32_e32 v4, 0x1800, v3
	s_waitcnt vmcnt(6)
	ds_write2_b32 v4, v37, v38 offset0:48 offset1:114
	s_waitcnt vmcnt(4)
	ds_write2_b32 v4, v39, v40 offset0:180 offset1:246
	v_add_u32_e32 v4, 0x1c00, v3
	v_mov_b64_e32 v[34:35], s[8:9]
	s_mov_b32 s26, 0x2800000
	s_waitcnt vmcnt(2)
	ds_write2_b32 v4, v41, v42 offset0:56 offset1:122
	s_waitcnt vmcnt(0)
	ds_write2_b32 v4, v43, v44 offset0:188 offset1:254
	v_mad_i64_i32 v[34:35], s[26:27], v33, s26, v[34:35]
	s_waitcnt lgkmcnt(0)
	v_ashrrev_i32_e32 v37, 31, v36
	v_lshl_add_u64 v[34:35], v[36:37], 1, v[34:35]
	v_lshlrev_b32_e32 v4, 1, v6
	v_lshl_add_u64 v[38:39], v[34:35], 0, v[4:5]
	ds_read_b32 v4, v23
	ds_read_b32 v21, v23 offset:132
	ds_read_b32 v33, v23 offset:264
	ds_read_b32 v35, v23 offset:396
	ds_read_b32 v36, v23 offset:528
	ds_read_b32 v37, v23 offset:660
	ds_read_b32 v40, v23 offset:792
	ds_read_b32 v41, v23 offset:924
	s_waitcnt lgkmcnt(0)
	v_bfe_u32 v34, v4, 16, 1
	v_add3_u32 v4, v4, v34, s38
	v_bfe_u32 v34, v21, 16, 1
	v_lshrrev_b32_e32 v4, 16, v4
	v_add3_u32 v21, v21, v34, s38
	v_and_or_b32 v34, v21, s39, v4
	v_bfe_u32 v4, v33, 16, 1
	v_add3_u32 v4, v33, v4, s38
	v_bfe_u32 v21, v35, 16, 1
	v_lshrrev_b32_e32 v4, 16, v4
	v_add3_u32 v21, v35, v21, s38
	v_and_or_b32 v35, v21, s39, v4
	v_bfe_u32 v4, v36, 16, 1
	v_add3_u32 v4, v36, v4, s38
	v_bfe_u32 v21, v37, 16, 1
	v_lshrrev_b32_e32 v4, 16, v4
	v_add3_u32 v21, v37, v21, s38
	v_and_or_b32 v36, v21, s39, v4
	v_bfe_u32 v4, v40, 16, 1
	v_add3_u32 v4, v40, v4, s38
	v_bfe_u32 v21, v41, 16, 1
	v_or_b32_e32 v40, v20, v7
	v_add3_u32 v21, v41, v21, s38
	v_ashrrev_i32_e32 v41, 31, v40
	v_lshrrev_b32_e32 v4, 16, v4
	v_lshlrev_b64 v[40:41], 12, v[40:41]
	v_and_or_b32 v37, v21, s39, v4
	v_lshl_add_u64 v[40:41], v[38:39], 0, v[40:41]
	global_store_dwordx4 v[40:41], v[34:37], off
	ds_read_b32 v4, v23 offset:32
	ds_read_b32 v21, v23 offset:164
	ds_read_b32 v33, v23 offset:296
	ds_read_b32 v35, v23 offset:428
	ds_read_b32 v36, v23 offset:560
	ds_read_b32 v37, v23 offset:692
	ds_read_b32 v40, v23 offset:824
	ds_read_b32 v41, v23 offset:956
	s_waitcnt lgkmcnt(0)
	v_bfe_u32 v34, v4, 16, 1
	v_add3_u32 v4, v4, v34, s38
	v_bfe_u32 v34, v21, 16, 1
	v_lshrrev_b32_e32 v4, 16, v4
	v_add3_u32 v21, v21, v34, s38
	v_and_or_b32 v34, v21, s39, v4
	v_bfe_u32 v4, v33, 16, 1
	v_add3_u32 v4, v33, v4, s38
	v_bfe_u32 v21, v35, 16, 1
	v_lshrrev_b32_e32 v4, 16, v4
	v_add3_u32 v21, v35, v21, s38
	v_and_or_b32 v35, v21, s39, v4
	v_bfe_u32 v4, v36, 16, 1
	v_add3_u32 v4, v36, v4, s38
	v_bfe_u32 v21, v37, 16, 1
	v_lshrrev_b32_e32 v4, 16, v4
	v_add3_u32 v21, v37, v21, s38
	v_and_or_b32 v36, v21, s39, v4
	v_bfe_u32 v4, v40, 16, 1
	v_add3_u32 v4, v40, v4, s38
	v_bfe_u32 v21, v41, 16, 1
	v_or_b32_e32 v40, v20, v24
	v_add3_u32 v21, v41, v21, s38
	v_ashrrev_i32_e32 v41, 31, v40
	v_lshrrev_b32_e32 v4, 16, v4
	v_lshlrev_b64 v[40:41], 12, v[40:41]
	v_and_or_b32 v37, v21, s39, v4
	v_lshl_add_u64 v[40:41], v[38:39], 0, v[40:41]
	global_store_dwordx4 v[40:41], v[34:37], off
	ds_read_b32 v4, v23 offset:64
	ds_read_b32 v21, v23 offset:196
	ds_read_b32 v33, v23 offset:328
	ds_read_b32 v35, v23 offset:460
	ds_read_b32 v36, v23 offset:592
	ds_read_b32 v37, v23 offset:724
	ds_read_b32 v40, v23 offset:856
	ds_read_b32 v41, v23 offset:988
	s_waitcnt lgkmcnt(0)
	v_bfe_u32 v34, v4, 16, 1
	v_add3_u32 v4, v4, v34, s38
	v_bfe_u32 v34, v21, 16, 1
	v_lshrrev_b32_e32 v4, 16, v4
	v_add3_u32 v21, v21, v34, s38
	v_and_or_b32 v34, v21, s39, v4
	v_bfe_u32 v4, v33, 16, 1
	v_add3_u32 v4, v33, v4, s38
	v_bfe_u32 v21, v35, 16, 1
	v_lshrrev_b32_e32 v4, 16, v4
	v_add3_u32 v21, v35, v21, s38
	v_and_or_b32 v35, v21, s39, v4
	v_bfe_u32 v4, v36, 16, 1
	v_add3_u32 v4, v36, v4, s38
	v_bfe_u32 v21, v37, 16, 1
	v_lshrrev_b32_e32 v4, 16, v4
	v_add3_u32 v21, v37, v21, s38
	v_and_or_b32 v36, v21, s39, v4
	v_bfe_u32 v4, v40, 16, 1
	v_add3_u32 v4, v40, v4, s38
	v_bfe_u32 v21, v41, 16, 1
	v_or_b32_e32 v40, v20, v25
	v_add3_u32 v21, v41, v21, s38
	v_ashrrev_i32_e32 v41, 31, v40
	v_lshrrev_b32_e32 v4, 16, v4
	v_lshlrev_b64 v[40:41], 12, v[40:41]
	v_and_or_b32 v37, v21, s39, v4
	v_lshl_add_u64 v[40:41], v[38:39], 0, v[40:41]
	global_store_dwordx4 v[40:41], v[34:37], off
	ds_read_b32 v4, v23 offset:96
	ds_read_b32 v21, v23 offset:228
	ds_read_b32 v33, v23 offset:360
	ds_read_b32 v35, v23 offset:492
	ds_read_b32 v36, v23 offset:624
	ds_read_b32 v37, v23 offset:756
	ds_read_b32 v40, v23 offset:888
	ds_read_b32 v41, v23 offset:1020
	s_waitcnt lgkmcnt(0)
	v_bfe_u32 v34, v4, 16, 1
	v_add3_u32 v4, v4, v34, s38
	v_bfe_u32 v34, v21, 16, 1
	v_lshrrev_b32_e32 v4, 16, v4
	v_add3_u32 v21, v21, v34, s38
	v_and_or_b32 v34, v21, s39, v4
	v_bfe_u32 v4, v33, 16, 1
	v_add3_u32 v4, v33, v4, s38
	v_bfe_u32 v21, v35, 16, 1
	v_lshrrev_b32_e32 v4, 16, v4
	v_add3_u32 v21, v35, v21, s38
	v_and_or_b32 v35, v21, s39, v4
	v_bfe_u32 v4, v36, 16, 1
	v_add3_u32 v4, v36, v4, s38
	v_bfe_u32 v21, v37, 16, 1
	v_lshrrev_b32_e32 v4, 16, v4
	v_add3_u32 v21, v37, v21, s38
	v_and_or_b32 v36, v21, s39, v4
	v_bfe_u32 v4, v40, 16, 1
	v_add3_u32 v4, v40, v4, s38
	v_bfe_u32 v21, v41, 16, 1
	v_lshrrev_b32_e32 v4, 16, v4
	v_add3_u32 v21, v41, v21, s38
	v_or_b32_e32 v20, v20, v26
	v_and_or_b32 v37, v21, s39, v4
	v_ashrrev_i32_e32 v21, 31, v20
	v_lshlrev_b64 v[20:21], 12, v[20:21]
	v_lshl_add_u64 v[20:21], v[38:39], 0, v[20:21]
	global_store_dwordx4 v[20:21], v[34:37], off
	s_waitcnt lgkmcnt(0)
	v_readlane_b32 s61, v251, 22
	v_readlane_b32 s62, v251, 23
	v_readlane_b32 s63, v251, 24
	v_readlane_b32 s64, v251, 25
	v_readlane_b32 s65, v251, 26
	v_readlane_b32 s66, v251, 27
	v_readlane_b32 s67, v251, 28
	v_readlane_b32 s68, v251, 29
	v_readlane_b32 s69, v251, 30
	v_readlane_b32 s72, v251, 33
	v_readlane_b32 s73, v251, 34
	v_readlane_b32 s74, v251, 35
	v_readlane_b32 s75, v251, 36
	s_branch .LBB0_52

; __device__ __forceinline__ unsigned pk2(float lo, float hi) { return f2bf(lo) | (f2bf(hi) << 16); }
; __device__ __forceinline__ void p0_prologue(LAS unsigned char* lds, const Params& p) {
;     ...
;     for (int m = gw; m < MT; m += NGW) {
;         const float* xr = (m < NP) ? p.in[0] + (size_t)m * DM : p.in[1] + (size_t)(m - NP) * DM;
;         unsigned long long* o8 = (unsigned long long*)(XB + (size_t)m * DM) + lane;
; #pragma unroll
;         for (int j = 0; j < 8; ++j) { const f32x4 v = *((const f32x4*)xr + lane + 64 * j); o8[64 * j] = (unsigned long long)pk2(v.x, v.y) | ((unsigned long long)pk2(v.z, v.w) << 32); }
;     }
.LBB0_81:
	s_or_b64 exec, exec, s[14:15]
	v_lshl_add_u64 v[18:19], v[10:11], 0, v[8:9]
	global_load_dwordx4 v[14:17], v[18:19], off
	v_lshlrev_b64 v[10:11], 12, v[12:13]
	v_lshl_add_u64 v[20:21], v[4:5], 0, v[10:11]
	v_lshl_add_u64 v[0:1], v[0:1], 0, s[6:7]
	v_lshl_add_u64 v[6:7], v[6:7], 0, s[10:11]
	s_waitcnt vmcnt(0)
	v_bfe_u32 v2, v14, 16, 1
	v_bfe_u32 v11, v16, 16, 1
	v_bfe_u32 v10, v15, 16, 1
	v_bfe_u32 v12, v17, 16, 1
	v_add3_u32 v2, v14, v2, s17
	v_add3_u32 v11, v16, v11, s17
	v_add3_u32 v10, v15, v10, s17
	v_add3_u32 v12, v17, v12, s17
	v_lshrrev_b32_e32 v2, 16, v2
	v_lshrrev_b32_e32 v11, 16, v11
	v_and_or_b32 v10, v10, s18, v2
	v_and_or_b32 v11, v12, s18, v11
	global_store_dwordx2 v[20:21], v[10:11], off
	global_load_dwordx4 v[10:13], v[18:19], off offset:1024
	s_waitcnt vmcnt(0)
	v_bfe_u32 v2, v10, 16, 1
	v_bfe_u32 v14, v11, 16, 1
	v_bfe_u32 v15, v12, 16, 1
	v_bfe_u32 v16, v13, 16, 1
	v_add3_u32 v2, v10, v2, s17
	v_add3_u32 v10, v11, v14, s17
	v_add3_u32 v11, v12, v15, s17
	v_add3_u32 v12, v13, v16, s17
	v_lshrrev_b32_e32 v2, 16, v2
	v_lshrrev_b32_e32 v11, 16, v11
	v_and_or_b32 v10, v10, s18, v2
	v_and_or_b32 v11, v12, s18, v11
	global_store_dwordx2 v[20:21], v[10:11], off offset:512
	global_load_dwordx4 v[10:13], v[18:19], off offset:2048
	s_waitcnt vmcnt(0)
	v_bfe_u32 v2, v10, 16, 1
	v_bfe_u32 v14, v11, 16, 1
	v_bfe_u32 v15, v12, 16, 1
	v_bfe_u32 v16, v13, 16, 1
	v_add3_u32 v2, v10, v2, s17
	v_add3_u32 v10, v11, v14, s17
	v_add3_u32 v11, v12, v15, s17
	v_add3_u32 v12, v13, v16, s17
	v_lshrrev_b32_e32 v2, 16, v2
	v_lshrrev_b32_e32 v11, 16, v11
	v_and_or_b32 v10, v10, s18, v2
	v_and_or_b32 v11, v12, s18, v11
	global_store_dwordx2 v[20:21], v[10:11], off offset:1024
	global_load_dwordx4 v[10:13], v[18:19], off offset:3072
	v_add_co_u32_e32 v14, vcc, s19, v18
	s_waitcnt vmcnt(0)
	v_bfe_u32 v2, v10, 16, 1
	v_bfe_u32 v16, v11, 16, 1
	v_bfe_u32 v17, v12, 16, 1
	v_bfe_u32 v18, v13, 16, 1
	v_add3_u32 v2, v10, v2, s17
	v_add3_u32 v10, v11, v16, s17
	v_add3_u32 v11, v12, v17, s17
	v_add3_u32 v12, v13, v18, s17
	v_lshrrev_b32_e32 v2, 16, v2
	v_lshrrev_b32_e32 v11, 16, v11
	v_and_or_b32 v10, v10, s18, v2
	v_and_or_b32 v11, v12, s18, v11
	v_addc_co_u32_e32 v15, vcc, 0, v19, vcc
	global_store_dwordx2 v[20:21], v[10:11], off offset:1536
	global_load_dwordx4 v[10:13], v[14:15], off
	v_cmp_lt_i32_e32 vcc, s20, v0
	s_or_b64 s[12:13], vcc, s[12:13]
	s_waitcnt vmcnt(0)
	v_bfe_u32 v2, v10, 16, 1
	v_bfe_u32 v16, v11, 16, 1
	v_bfe_u32 v17, v12, 16, 1
	v_bfe_u32 v18, v13, 16, 1
	v_add3_u32 v2, v10, v2, s17
	v_add3_u32 v10, v11, v16, s17
	v_add3_u32 v11, v12, v17, s17
	v_add3_u32 v12, v13, v18, s17
	v_lshrrev_b32_e32 v2, 16, v2
	v_lshrrev_b32_e32 v11, 16, v11
	v_and_or_b32 v10, v10, s18, v2
	v_and_or_b32 v11, v12, s18, v11
	global_store_dwordx2 v[20:21], v[10:11], off offset:2048
	global_load_dwordx4 v[10:13], v[14:15], off offset:1024
	s_waitcnt vmcnt(0)
	v_bfe_u32 v2, v10, 16, 1
	v_bfe_u32 v16, v11, 16, 1
	v_bfe_u32 v17, v12, 16, 1
	v_bfe_u32 v18, v13, 16, 1
	v_add3_u32 v2, v10, v2, s17
	v_add3_u32 v10, v11, v16, s17
	v_add3_u32 v11, v12, v17, s17
	v_add3_u32 v12, v13, v18, s17
	v_lshrrev_b32_e32 v2, 16, v2
	v_lshrrev_b32_e32 v11, 16, v11
	v_and_or_b32 v10, v10, s18, v2
	v_and_or_b32 v11, v12, s18, v11
	global_store_dwordx2 v[20:21], v[10:11], off offset:2560
	global_load_dwordx4 v[10:13], v[14:15], off offset:2048
	s_waitcnt vmcnt(0)
	v_bfe_u32 v2, v10, 16, 1
	v_bfe_u32 v16, v11, 16, 1
	v_bfe_u32 v17, v12, 16, 1
	v_bfe_u32 v18, v13, 16, 1
	v_add3_u32 v2, v10, v2, s17
	v_add3_u32 v10, v11, v16, s17
	v_add3_u32 v11, v12, v17, s17
	v_add3_u32 v12, v13, v18, s17
	v_lshrrev_b32_e32 v2, 16, v2
	v_lshrrev_b32_e32 v11, 16, v11
	v_and_or_b32 v10, v10, s18, v2
	v_and_or_b32 v11, v12, s18, v11
	global_store_dwordx2 v[20:21], v[10:11], off offset:3072
	global_load_dwordx4 v[10:13], v[14:15], off offset:3072
	s_waitcnt vmcnt(0)
	v_bfe_u32 v2, v10, 16, 1
	v_bfe_u32 v14, v11, 16, 1
	v_bfe_u32 v15, v12, 16, 1
	v_bfe_u32 v16, v13, 16, 1
	v_add3_u32 v2, v10, v2, s17
	v_add3_u32 v10, v11, v14, s17
	v_add3_u32 v11, v12, v15, s17
	v_add3_u32 v12, v13, v16, s17
	v_lshrrev_b32_e32 v2, 16, v2
	v_lshrrev_b32_e32 v11, 16, v11
	v_and_or_b32 v10, v10, s18, v2
	v_and_or_b32 v11, v12, s18, v11
	global_store_dwordx2 v[20:21], v[10:11], off offset:3584
	s_andn2_b64 exec, exec, s[12:13]
	s_cbranch_execz .LBB0_84

; __device__ __forceinline__ void p0_prologue(LAS unsigned char* lds, const Params& p) {
;     ...
;     for (int i = blockIdx.x * NTHR + tid; i < 2 * LW; i += gridDim.x * NTHR) { const float x = -p.in[15][i]; C8[i] = 8.0f * (fmaxf(x, 0.f) + log1pf(expf(-fabsf(x)))); }
.LBB0_86:
	v_ashrrev_i32_e32 v1, 31, v0
	v_lshlrev_b64 v[6:7], 2, v[0:1]
	v_lshl_add_u64 v[8:9], s[78:79], 0, v[6:7]
	global_load_dword v1, v[8:9], off
	v_add_u32_e32 v0, s12, v0
	v_cmp_lt_i32_e32 vcc, s21, v0
	v_lshl_add_u64 v[6:7], s[8:9], 0, v[6:7]
	s_or_b64 s[10:11], vcc, s[10:11]
	s_waitcnt vmcnt(0)
	v_mul_f32_e64 v3, |v1|, s13
	v_fma_f32 v8, |v1|, s13, -v3
	v_rndne_f32_e32 v9, v3
	v_fma_f32 v8, |v1|, s14, v8
	v_sub_f32_e32 v3, v3, v9
	v_add_f32_e32 v3, v3, v8
	v_cvt_i32_f32_e32 v9, v9
	v_exp_f32_e32 v3, v3
	v_cmp_ngt_f32_e64 s[0:1], |v1|, s15
	v_max_f32_e64 v8, -v1, -v1
	v_max_f32_e32 v22, 0, v8
	v_ldexp_f32 v3, v3, v9
	v_cndmask_b32_e64 v3, 0, v3, s[0:1]
	v_cmp_nlt_f32_e64 s[0:1], |v1|, s16
	s_nop 1
	v_cndmask_b32_e64 v1, v4, v3, s[0:1]
	v_add_f32_e32 v3, 1.0, v1
	v_add_f32_e32 v10, -1.0, v3
	v_frexp_mant_f32_e32 v11, v3
	v_cvt_f64_f32_e32 v[8:9], v3
	v_sub_f32_e32 v12, v10, v3
	v_frexp_exp_i32_f64_e32 v8, v[8:9]
	v_cmp_gt_f32_e64 s[0:1], s18, v11
	v_sub_f32_e32 v10, v1, v10
	v_add_f32_e32 v9, 1.0, v12
	v_subbrev_co_u32_e64 v8, s[0:1], 0, v8, s[0:1]
	v_add_f32_e32 v9, v10, v9
	v_sub_u32_e32 v10, 0, v8
	v_ldexp_f32 v3, v3, v10
	v_ldexp_f32 v9, v9, v10
	v_add_f32_e32 v10, -1.0, v3
	v_add_f32_e32 v12, 1.0, v3
	v_add_f32_e32 v11, 1.0, v10
	v_add_f32_e32 v13, -1.0, v12
	v_sub_f32_e32 v11, v3, v11
	v_sub_f32_e32 v3, v3, v13
	v_add_f32_e32 v3, v9, v3
	v_add_f32_e32 v13, v9, v11
	v_add_f32_e32 v9, v12, v3
	v_rcp_f32_e32 v16, v9
	v_add_f32_e32 v11, v10, v13
	v_sub_f32_e32 v12, v12, v9
	v_add_f32_e32 v3, v3, v12
	v_mul_f32_e32 v18, v11, v16
	v_mul_f32_e32 v12, v9, v18
	v_fma_f32 v14, v18, v9, -v12
	v_sub_f32_e32 v10, v10, v11
	v_fmac_f32_e32 v14, v18, v3
	v_add_f32_e32 v17, v13, v10
	v_add_f32_e32 v10, v12, v14
	v_sub_f32_e32 v13, v11, v10
	v_mov_b32_e32 v15, v10
	v_pk_add_f32 v[10:11], v[10:11], v[12:13] neg_lo:[0,1] neg_hi:[0,1]
	v_cvt_f32_i32_e32 v8, v8
	v_pk_add_f32 v[10:11], v[10:11], v[14:15] neg_lo:[0,1] neg_hi:[0,1]
	v_cmp_neq_f32_e64 s[0:1], s17, v1
	v_add_f32_e32 v11, v17, v11
	v_add_f32_e32 v10, v10, v11
	v_add_f32_e32 v11, v13, v10
	v_mul_f32_e32 v15, v16, v11
	v_mul_f32_e32 v12, v9, v15
	v_fma_f32 v14, v15, v9, -v12
	v_sub_f32_e32 v13, v13, v11
	v_fmac_f32_e32 v14, v15, v3
	v_add_f32_e32 v17, v10, v13
	v_add_f32_e32 v19, v18, v15
	v_add_f32_e32 v10, v12, v14
	v_sub_f32_e32 v9, v19, v18
	v_sub_f32_e32 v13, v11, v10
	v_sub_f32_e32 v3, v15, v9
	v_mov_b32_e32 v15, v10
	v_pk_add_f32 v[10:11], v[10:11], v[12:13] neg_lo:[0,1] neg_hi:[0,1]
	s_nop 0
	v_pk_add_f32 v[10:11], v[10:11], v[14:15] neg_lo:[0,1] neg_hi:[0,1]
	s_nop 0
	v_add_f32_e32 v9, v17, v11
	v_add_f32_e32 v9, v10, v9
	v_add_f32_e32 v9, v13, v9
	v_mul_f32_e32 v9, v16, v9
	v_add_f32_e32 v3, v3, v9
	v_add_f32_e32 v9, v19, v3
	v_mul_f32_e32 v10, v9, v9
	v_sub_f32_e32 v12, v9, v19
	v_fmamk_f32 v13, v10, 0x3e9b6dac, v5
	v_ldexp_f32 v11, v9, 1
	v_sub_f32_e32 v12, v3, v12
	v_mul_f32_e32 v9, v9, v10
	v_fmaak_f32 v3, v10, v13, 0x3f2aaada
	v_ldexp_f32 v15, v12, 1
	v_pk_mul_f32 v[12:13], v[8:9], v[2:3]
	s_nop 0
	v_fma_f32 v10, v8, s19, -v12
	v_fmac_f32_e32 v10, 0xb102e308, v8
	v_pk_add_f32 v[8:9], v[12:13], v[10:11]
	v_mov_b32_e32 v14, v12
	v_sub_f32_e32 v3, v9, v11
	v_sub_f32_e32 v3, v13, v3
	v_add_f32_e32 v15, v15, v3
	v_pk_add_f32 v[16:17], v[8:9], v[12:13] neg_lo:[0,1] neg_hi:[0,1]
	v_pk_add_f32 v[12:13], v[8:9], v[14:15]
	v_mov_b32_e32 v11, v8
	v_mov_b32_e32 v17, v13
	v_pk_add_f32 v[20:21], v[10:11], v[16:17] neg_lo:[0,1] neg_hi:[0,1]
	v_pk_add_f32 v[10:11], v[10:11], v[16:17]
	v_mov_b32_e32 v19, v8
	v_pk_add_f32 v[16:17], v[10:11], v[8:9] op_sel:[1,0] op_sel_hi:[0,1] neg_lo:[0,1] neg_hi:[0,1]
	v_mov_b32_e32 v18, v15
	v_mov_b32_e32 v14, v13
	v_mov_b32_e32 v15, v11
	v_pk_mov_b32 v[8:9], v[8:9], v[16:17] op_sel:[1,0]
	v_pk_add_f32 v[12:13], v[12:13], v[16:17] op_sel_hi:[1,0] neg_lo:[0,1] neg_hi:[0,1]
	v_pk_add_f32 v[8:9], v[14:15], v[8:9] neg_lo:[0,1] neg_hi:[0,1]
	v_mov_b32_e32 v12, v20
	v_pk_add_f32 v[8:9], v[18:19], v[8:9] neg_lo:[0,1] neg_hi:[0,1]
	v_mov_b32_e32 v21, v11
	v_pk_add_f32 v[12:13], v[12:13], v[8:9]
	s_nop 0
	v_pk_add_f32 v[14:15], v[12:13], v[12:13] op_sel:[0,1] op_sel_hi:[1,0]
	s_nop 0
	v_pk_add_f32 v[10:11], v[10:11], v[14:15] op_sel:[1,0] op_sel_hi:[0,1]
	v_mov_b32_e32 v13, v10
	v_mov_b32_e32 v9, v14
	v_pk_add_f32 v[14:15], v[12:13], v[20:21] neg_lo:[0,1] neg_hi:[0,1]
	s_nop 0
	v_sub_f32_e32 v3, v12, v14
	v_pk_add_f32 v[8:9], v[8:9], v[14:15] neg_lo:[0,1] neg_hi:[0,1]
	v_sub_f32_e32 v3, v20, v3
	v_add_f32_e32 v3, v8, v3
	v_add_f32_e32 v3, v3, v9
	v_add_f32_e32 v3, v10, v3
	v_cndmask_b32_e64 v3, v4, v3, s[0:1]
	v_cmp_lt_f32_e64 s[0:1], |v1|, s20
	s_nop 1
	v_cndmask_b32_e64 v1, v3, v1, s[0:1]
	v_add_f32_e32 v1, v22, v1
	v_mul_f32_e32 v1, 0x41000000, v1
	global_store_dword v[6:7], v1, off
	s_andn2_b64 exec, exec, s[10:11]
	s_cbranch_execnz .LBB0_86

; #define PG8_WAIT_V(n) asm volatile("s_waitcnt vmcnt(" #n ")" ::: "memory")
; #define PG8_BAR __builtin_amdgcn_s_barrier()
; template <class Epi, class Sched, bool ALIGN_EPI = false, bool SP2 = false>
; __device__ __forceinline__ void gemm_phase(PG8_LAS unsigned char* lds, const Gemm g, const Sched& S, const Epi& E) {
;     int tid_ = threadIdx.x; asm volatile("" : "+v"(tid_)); const int tid = tid_, wid = __builtin_amdgcn_readfirstlane(tid >> 6), lane = tid & 63, wr = wid >> 2, wc = wid & 3, fr = lane & 15, fq = lane >> 4;
;     const int K = g.ld, nt = g.K / BK;
;     unsigned voffA[2], voffB[2];
; #pragma unroll
;     for (int i = 0; i < 2; ++i) { int R, C; stage_rc(tid * 16 + i * 8192, R, C); const int Rb = Epi::PERM ? ((R & ~31) + perm32(R & 31)) : R;
;         voffA[i] = (unsigned)(R * K + C) * 2u; voffB[i] = (unsigned)(Rb * K + C) * 2u; }
;     const size_t kstep = (size_t)(BK * 2);
;     const size_t hstep = (size_t)HALF * K * 2;
;     const size_t tstep = 2 * hstep;
;     const unsigned ldsw = (unsigned)wid * 1024u;
;     const int aoff = lds_byte(wr * 64 + fr, fq * 8), boff = lds_byte(wc * 32 + fr, fq * 8);
;     ...
;     Unit cur, nxt; int ui = 0;
;     if (!S.next(0, cur)) return;
;     f32x4 acc[2][2][4][2];
; #pragma unroll
;     for (int a = 0; a < 2; ++a)
; #pragma unroll
;         for (int b = 0; b < 2; ++b)
; #pragma unroll
;             for (int m = 0; m < 4; ++m)
; #pragma unroll
;                 for (int n = 0; n < 2; ++n) acc[a][b][m][n] = (f32x4){0.f, 0.f, 0.f, 0.f};
;     bf16x8 At[4][2], B0[2][2], B1[2][2];
;     const char* cA = (const char*)g.A + (size_t)cur.pm * tstep; const char* cB = (const char*)g.Bt + (size_t)cur.pn * tstep;
;     S.a_ready(cur);
;     if constexpr (SP2) {
;         PG8_STAGE(PG8_SB(0, 0), cB, voffB); PG8_STAGE(PG8_SB(0, 1), cB + hstep, voffB); PG8_STAGE(PG8_SA(0, 0), cA, voffA); PG8_STAGE(PG8_SA(0, 1), cA + hstep, voffA);
;         if (wr == 1) PG8_BAR;
;         PG8_WAIT_V(2); PG8_BAR;
;         PG8_STAGE(PG8_SB(1, 0), cB + kstep, voffB); PG8_STAGE(PG8_SA(1, 0), cA + kstep, voffA); PG8_STAGE(PG8_SB(1, 1), cB + hstep + kstep, voffB);
;         PG8_WAIT_V(6); PG8_BAR;
;     } else {
;         PG8_STAGE(PG8_SB(0, 0), cB, voffB); PG8_STAGE(PG8_SA(0, 0), cA, voffA); PG8_STAGE(PG8_SB(0, 1), cB + hstep, voffB); PG8_STAGE(PG8_SA(0, 1), cA + hstep, voffA);
;         if (wr == 1) PG8_BAR;
;         PG8_WAIT_V(4); PG8_BAR;
.LBB0_151:
	s_and_b64 vcc, exec, s[0:1]
	s_cbranch_vccnz .LBB0_271
	v_ashrrev_i32_e32 v0, 31, v10
	v_lshrrev_b32_e32 v0, 26, v0
	v_add_u32_e32 v0, v10, v0
	v_ashrrev_i32_e32 v11, 6, v0
	v_bfe_i32 v0, v10, 27, 1
	s_waitcnt vmcnt(1)
	v_lshlrev_b32_e32 v2, 4, v10
	v_lshrrev_b32_e32 v0, 22, v0
	v_add_u32_e32 v0, v2, v0
	v_and_b32_e32 v0, 0xfffffc00, v0
	v_sub_u32_e32 v0, v2, v0
	v_lshrrev_b32_e32 v3, 4, v0
	v_bitop3_b32 v0, v3, v0, 32 bitop3:0x6c
	v_ashrrev_i32_e32 v4, 31, v0
	v_lshrrev_b32_e32 v4, 26, v4
	v_add_u32_e32 v4, v0, v4
	v_readlane_b32 s6, v248, 29
	v_lshlrev_b32_e32 v3, 3, v11
	v_ashrrev_i32_e32 v12, 6, v4
	v_and_b32_e32 v4, 0xc0, v4
	v_readlane_b32 s7, v248, 30
	s_add_u32 s35, s6, 0x7b04000
	v_and_b32_e32 v3, -16, v3
	v_sub_u32_e32 v0, v0, v4
	s_addc_u32 s81, s7, 0
	s_mul_i32 s0, s56, 0x2800000
	v_add_u32_e32 v3, v12, v3
	v_ashrrev_i16_sdwa v0, v216, sext(v0) dst_sel:DWORD dst_unused:UNUSED_PAD src0_sel:DWORD src1_sel:BYTE_0
	s_add_u32 s84, s6, s0
	v_lshlrev_b32_e32 v5, 5, v11
	v_bfe_i32 v13, v0, 0, 16
	v_lshlrev_b32_e32 v0, 1, v3
	v_lshrrev_b32_e32 v4, 2, v3
	v_and_b32_e32 v6, 3, v12
	s_mov_b32 s0, 0xfffe0
	v_and_b32_e32 v5, 32, v5
	v_and_b32_e32 v0, 24, v0
	v_and_b32_e32 v4, 4, v4
	v_and_or_b32 v6, v3, s0, v6
	v_or3_b32 v0, v6, v4, v0
	v_add_lshl_u32 v4, v5, v13, 1
	v_add_u32_e32 v2, 0x2000, v2
	v_lshl_add_u32 v146, v3, 12, v4
	v_ashrrev_i32_e32 v3, 31, v2
	v_lshrrev_b32_e32 v3, 22, v3
	v_add_u32_e32 v3, v2, v3
	v_ashrrev_i32_e32 v14, 10, v3
	v_mul_i32_i24_e32 v3, 0x400, v14
	v_sub_u32_e32 v2, v2, v3
	v_lshrrev_b32_e32 v3, 4, v2
	v_bitop3_b32 v2, v3, v2, 32 bitop3:0x6c
	v_lshl_add_u32 v0, v0, 12, v4
	v_ashrrev_i32_e32 v4, 31, v2
	v_lshrrev_b32_e32 v4, 26, v4
	v_lshlrev_b32_e32 v3, 3, v14
	v_add_u32_e32 v4, v2, v4
	v_and_b32_e32 v3, -16, v3
	v_ashrrev_i32_e32 v15, 6, v4
	s_addc_u32 s86, s7, 0
	v_add_u32_e32 v3, v15, v3
	v_and_b32_e32 v4, 0xc0, v4
	v_and_b32_e32 v6, 3, v15
	s_ashr_i32 s5, s2, 6
	s_ashr_i32 s51, s50, 31
	s_ashr_i32 s53, s52, 31
	s_ashr_i32 s3, s2, 8
	v_sub_u32_e32 v2, v2, v4
	v_and_or_b32 v6, v3, s0, v6
	s_lshl_b32 s87, s5, 10
	s_lshl_b64 s[6:7], s[50:51], 20
	s_lshl_b64 s[0:1], s[52:53], 20
	v_ashrrev_i16_sdwa v2, v216, sext(v2) dst_sel:DWORD dst_unused:UNUSED_PAD src0_sel:DWORD src1_sel:BYTE_0
	s_add_u32 s0, s84, s0
	v_lshlrev_b32_e32 v5, 5, v14
	v_bfe_i32 v16, v2, 0, 16
	v_lshlrev_b32_e32 v2, 1, v3
	v_lshrrev_b32_e32 v4, 2, v3
	s_addc_u32 s1, s86, s1
	s_add_i32 s51, s87, 0
	v_and_b32_e32 v5, 32, v5
	v_and_b32_e32 v2, 24, v2
	v_and_b32_e32 v4, 4, v4
	s_add_i32 m0, s51, 0x10000
	v_or3_b32 v2, v6, v4, v2
	v_add_lshl_u32 v4, v5, v16, 1
	global_load_lds_dwordx4 v0, s[0:1]
	s_add_i32 m0, s51, 0x12000
	v_lshl_add_u32 v150, v2, 12, v4
	s_add_u32 s10, s0, 0x80000
	global_load_lds_dwordx4 v150, s[0:1]
	s_addc_u32 s11, s1, 0
	s_add_i32 m0, s51, 0x14000
	v_lshl_add_u32 v148, v3, 12, v4
	global_load_lds_dwordx4 v0, s[10:11]
	s_add_i32 m0, s51, 0x16000
	s_add_u32 s74, s35, s6
	s_addc_u32 s75, s81, s7
	s_add_i32 s53, s51, 0x2000
	global_load_lds_dwordx4 v150, s[10:11]
	s_mov_b32 m0, s51
	s_add_u32 s6, s74, 0x80000
	global_load_lds_dwordx4 v146, s[74:75]
	s_mov_b32 m0, s53
	s_addc_u32 s7, s75, 0
	s_add_i32 s90, s51, 0x4000
	global_load_lds_dwordx4 v148, s[74:75]
	s_mov_b32 m0, s90
	s_add_i32 s91, s51, 0x6000
	global_load_lds_dwordx4 v146, s[6:7]
	s_mov_b32 m0, s91
	v_mov_b32_e32 v151, v1
	global_load_lds_dwordx4 v148, s[6:7]
	v_mov_b32_e32 v147, v1
	v_mov_b32_e32 v149, v1
	s_cmp_eq_u32 s3, 1
	v_lshl_add_u64 v[8:9], s[0:1], 0, v[0:1]
	v_lshl_add_u64 v[6:7], s[0:1], 0, v[150:151]
	v_lshl_add_u64 v[2:3], s[74:75], 0, v[146:147]
	s_cselect_b64 s[10:11], -1, 0
	s_cmp_lg_u32 s3, 1
	v_lshl_add_u64 v[4:5], s[74:75], 0, v[148:149]
	s_cbranch_scc1 .LBB0_154
	s_barrier

;     __device__ __forceinline__ bool next(int i, pg8::Unit& u) const { if (i >= count) return false; const int L = start + i * stride; u.pm = L >> 3; u.pn = L & 7; return true; }
; template <class Epi, class Sched, bool ALIGN_EPI = false, bool SP2 = false>
; __device__ __forceinline__ void gemm_phase(PG8_LAS unsigned char* lds, const Gemm g, const Sched& S, const Epi& E) {
;     ...
;         const bool has_next = S.next(ui + 1, nxt);
;         const char* nA = has_next ? (const char*)g.A + (size_t)nxt.pm * tstep : cA; const char* nB = has_next ? (const char*)g.Bt + (size_t)nxt.pn * tstep : cB;
;         for (int t = 0; t < nt; t += 2) {
;             if constexpr (Epi::HOOK) { if (t == E.hook_t) E.hook(acc, cur, wr, wc, fr, fq); }
;             const bool last = (t == nt - 2);
;             const char* a1 = cA + (size_t)(t + 1) * kstep;
;             const char* a2 = last ? nA : cA + (size_t)(t + 2) * kstep; const char* b2 = last ? nB : cB + (size_t)(t + 2) * kstep;
;             const char* a3 = a2 + kstep; const char* b3 = b2 + kstep;
;     ...
; #pragma unroll
;         for (int a = 0; a < 2; ++a)
; #pragma unroll
;             for (int b = 0; b < 2; ++b)
; #pragma unroll
;                 for (int m = 0; m < 4; ++m)
; #pragma unroll
;                     for (int n = 0; n < 2; ++n) acc[a][b][m][n] = (f32x4){0.f, 0.f, 0.f, 0.f};
;         cur = nxt; cA = nA; cB = nB; ++ui;
.LBB0_159:
	s_ashr_i32 s45, s44, 31
	s_lshl_b64 s[2:3], s[44:45], 20
	s_add_u32 s46, s35, s2
	s_addc_u32 s47, s81, s3
	s_and_b64 s[2:3], s[38:39], exec
	s_cselect_b32 s2, s47, s75
	s_cselect_b32 s3, s46, s74
	s_ashr_i32 s43, s42, 31
	s_lshl_b64 s[6:7], s[42:43], 20
	s_add_u32 s48, s84, s6
	s_addc_u32 s49, s86, s7
	s_and_b64 s[6:7], s[38:39], exec
	s_cselect_b32 s5, s49, s1
	s_cselect_b32 s6, s48, s0
	s_add_u32 s7, s0, 0x100
	s_addc_u32 s12, s1, 0
	s_add_u32 s0, s74, 0x80080
	v_mov_b32_e32 v2, 0
	s_addc_u32 s1, s75, 0
	s_mov_b32 s13, -2
	v_mov_b32_e32 v3, v2
	v_mov_b32_e32 v4, v2
	v_mov_b32_e32 v5, v2
	v_mov_b32_e32 v6, v2
	v_mov_b32_e32 v7, v2
	v_mov_b32_e32 v8, v2
	v_mov_b32_e32 v9, v2
	v_mov_b32_e32 v18, v2
	v_mov_b32_e32 v19, v2
	v_mov_b32_e32 v20, v2
	v_mov_b32_e32 v21, v2
	v_mov_b32_e32 v22, v2
	v_mov_b32_e32 v23, v2
	s_waitcnt lgkmcnt(0)
	v_mov_b32_e32 v24, v2
	v_mov_b32_e32 v25, v2
	v_mov_b32_e32 v50, v2
	v_mov_b32_e32 v51, v2
	v_mov_b32_e32 v52, v2
	v_mov_b32_e32 v53, v2
	v_mov_b32_e32 v54, v2
	v_mov_b32_e32 v55, v2
	v_mov_b32_e32 v56, v2
	v_mov_b32_e32 v57, v2
	v_mov_b32_e32 v66, v2
	v_mov_b32_e32 v67, v2
	v_mov_b32_e32 v68, v2
	v_mov_b32_e32 v69, v2
	v_mov_b32_e32 v70, v2
	v_mov_b32_e32 v71, v2
	v_mov_b32_e32 v72, v2
	v_mov_b32_e32 v73, v2
	v_mov_b32_e32 v10, v2
	v_mov_b32_e32 v11, v2
	v_mov_b32_e32 v12, v2
	v_mov_b32_e32 v13, v2
	v_mov_b32_e32 v14, v2
	v_mov_b32_e32 v15, v2
	v_mov_b32_e32 v16, v2
	v_mov_b32_e32 v17, v2
	v_mov_b32_e32 v34, v2
	v_mov_b32_e32 v35, v2
	v_mov_b32_e32 v36, v2
	v_mov_b32_e32 v37, v2
	v_mov_b32_e32 v38, v2
	v_mov_b32_e32 v39, v2
	v_mov_b32_e32 v40, v2
	v_mov_b32_e32 v41, v2
	v_mov_b32_e32 v58, v2
	v_mov_b32_e32 v59, v2
	v_mov_b32_e32 v60, v2
	v_mov_b32_e32 v61, v2
	v_mov_b32_e32 v62, v2
	v_mov_b32_e32 v63, v2
	v_mov_b32_e32 v64, v2
	v_mov_b32_e32 v65, v2
	v_mov_b32_e32 v74, v2
	v_mov_b32_e32 v75, v2
	v_mov_b32_e32 v76, v2
	v_mov_b32_e32 v77, v2
	v_mov_b32_e32 v78, v2
	v_mov_b32_e32 v79, v2
	v_mov_b32_e32 v80, v2
	v_mov_b32_e32 v81, v2
	v_mov_b32_e32 v82, v2
	v_mov_b32_e32 v83, v2
	v_mov_b32_e32 v84, v2
	v_mov_b32_e32 v85, v2
	v_mov_b32_e32 v86, v2
	v_mov_b32_e32 v87, v2
	v_mov_b32_e32 v88, v2
	v_mov_b32_e32 v89, v2
	v_mov_b32_e32 v98, v2
	v_mov_b32_e32 v99, v2
	v_mov_b32_e32 v100, v2
	v_mov_b32_e32 v101, v2
	v_mov_b32_e32 v102, v2
	v_mov_b32_e32 v103, v2
	v_mov_b32_e32 v104, v2
	v_mov_b32_e32 v105, v2
	v_mov_b32_e32 v114, v2
	v_mov_b32_e32 v115, v2
	v_mov_b32_e32 v116, v2
	v_mov_b32_e32 v117, v2
	v_mov_b32_e32 v118, v2
	v_mov_b32_e32 v119, v2
	v_mov_b32_e32 v120, v2
	v_mov_b32_e32 v121, v2
	v_mov_b32_e32 v130, v2
	v_mov_b32_e32 v131, v2
	v_mov_b32_e32 v132, v2
	v_mov_b32_e32 v133, v2
	v_mov_b32_e32 v134, v2
	v_mov_b32_e32 v135, v2
	v_mov_b32_e32 v136, v2
	v_mov_b32_e32 v137, v2
	v_mov_b32_e32 v90, v2
	v_mov_b32_e32 v91, v2
	v_mov_b32_e32 v92, v2
	v_mov_b32_e32 v93, v2
	v_mov_b32_e32 v94, v2
	v_mov_b32_e32 v95, v2
	v_mov_b32_e32 v96, v2
	v_mov_b32_e32 v97, v2
	v_mov_b32_e32 v106, v2
	v_mov_b32_e32 v107, v2
	v_mov_b32_e32 v108, v2
	v_mov_b32_e32 v109, v2
	v_mov_b32_e32 v110, v2
	v_mov_b32_e32 v111, v2
	v_mov_b32_e32 v112, v2
	v_mov_b32_e32 v113, v2
	v_mov_b32_e32 v122, v2
	v_mov_b32_e32 v123, v2
	v_mov_b32_e32 v124, v2
	v_mov_b32_e32 v125, v2
	v_mov_b32_e32 v126, v2
	v_mov_b32_e32 v127, v2
	v_mov_b32_e32 v128, v2
	v_mov_b32_e32 v129, v2
	v_mov_b32_e32 v138, v2
	v_mov_b32_e32 v139, v2
	v_mov_b32_e32 v140, v2
	v_mov_b32_e32 v141, v2
	v_mov_b32_e32 v142, v2
	v_mov_b32_e32 v143, v2
	v_mov_b32_e32 v144, v2
	v_mov_b32_e32 v145, v2

; __device__ __forceinline__ unsigned cvt_pk_bf16(float lo, float hi) { unsigned r; asm volatile("v_cvt_pk_bf16_f32 %0, %1, %2" : "=v"(r) : "v"(lo), "v"(hi)); return r; }
; __device__ __forceinline__ float fast_sigmoid(float v) { return __builtin_amdgcn_rcpf(1.0f + __expf(-v)); }
;     __device__ __forceinline__ void operator()(const f32x4 (&acc)[2][2][4][2], const Unit& u, int wr, int wc, int fr, int fq) const {
;     ...
;             for (int m = 0; m < 4; ++m) { bf16_t* rowp = O + (size_t)(row0 + ai * HALF + m * 16) * ldc + col0;
; #pragma unroll
;                 for (int bj = 0; bj < 2; ++bj) { f32x4 v0 = acc[ai][bj][m][0] + bv[bj][0], v1 = acc[ai][bj][m][1] + bv[bj][1];
;                     if (mode == 1) {
; #pragma unroll
;                         for (int j = 0; j < 4; ++j) { v0[j] = v0[j] * fast_sigmoid(v0[j]); v1[j] = v1[j] * fast_sigmoid(v1[j]); } }
;                     else if (mode == 2) {
; #pragma unroll
;                         for (int j = 0; j < 4; ++j) { v0[j] = fast_sigmoid(v0[j]); v1[j] = fast_sigmoid(v1[j]); } }
;                     u32x4 w; w.x = cvt_pk_bf16(v0[0], v0[1]); w.y = cvt_pk_bf16(v0[2], v0[3]); w.z = cvt_pk_bf16(v1[0], v1[1]); w.w = cvt_pk_bf16(v1[2], v1[3]);
;                     *(u32x4*)(rowp + bj * HALF) = w; } }
.LBB0_177:
	v_lshl_add_u32 v140, s50, 8, v160
	v_mov_b64_e32 v[138:139], s[8:9]
	v_ashrrev_i32_e32 v157, 31, v156
	v_mad_i64_i32 v[138:139], s[0:1], v140, s25, v[138:139]
	v_lshl_add_u64 v[138:139], v[156:157], 1, v[138:139]
	v_cvt_pk_bf16_f32 v142, v158, v168
	v_cvt_pk_bf16_f32 v143, v170, v173
	v_cvt_pk_bf16_f32 v144, v159, v169
	v_cvt_pk_bf16_f32 v145, v171, v172
	v_pk_add_f32 v[136:137], v[136:137], v[32:33]
	v_pk_add_f32 v[134:135], v[134:135], v[30:31]
	v_pk_add_f32 v[132:133], v[132:133], v[28:29]
	v_pk_add_f32 v[130:131], v[130:131], v[26:27]
	s_cmp_gt_i32 s20, 1
	s_mov_b64 s[0:1], -1
	global_store_dwordx4 v[138:139], v[142:145], off
	s_cbranch_scc0 .LBB0_179
	v_mul_f32_e32 v159, 0xbfb8aa3b, v137
	v_mul_f32_e32 v141, 0xbfb8aa3b, v134
	v_mul_f32_e32 v142, 0xbfb8aa3b, v130
	v_mul_f32_e32 v143, 0xbfb8aa3b, v135
	v_mul_f32_e32 v144, 0xbfb8aa3b, v131
	v_mul_f32_e32 v145, 0xbfb8aa3b, v136
	v_mul_f32_e32 v158, 0xbfb8aa3b, v132
	v_exp_f32_e32 v159, v159
	v_mul_f32_e32 v168, 0xbfb8aa3b, v133
	v_exp_f32_e32 v141, v141
	v_exp_f32_e32 v142, v142
	v_exp_f32_e32 v143, v143
	v_exp_f32_e32 v144, v144
	v_exp_f32_e32 v145, v145
	v_exp_f32_e32 v158, v158
	v_exp_f32_e32 v169, v168
	v_add_f32_e32 v159, 1.0, v159
	v_add_f32_e32 v141, 1.0, v141
	v_add_f32_e32 v142, 1.0, v142
	v_add_f32_e32 v143, 1.0, v143
	v_add_f32_e32 v144, 1.0, v144
	v_add_f32_e32 v145, 1.0, v145
	v_add_f32_e32 v158, 1.0, v158
	v_rcp_f32_e32 v168, v159
	v_add_f32_e32 v159, 1.0, v169
	v_rcp_f32_e32 v141, v141
	v_rcp_f32_e32 v142, v142
	v_rcp_f32_e32 v143, v143
	v_rcp_f32_e32 v144, v144
	v_rcp_f32_e32 v145, v145
	v_rcp_f32_e32 v158, v158
	v_rcp_f32_e32 v159, v159
	s_mov_b64 s[0:1], 0

; __device__ __forceinline__ unsigned cvt_pk_bf16(float lo, float hi) { unsigned r; asm volatile("v_cvt_pk_bf16_f32 %0, %1, %2" : "=v"(r) : "v"(lo), "v"(hi)); return r; }
; __device__ __forceinline__ float fast_sigmoid(float v) { return __builtin_amdgcn_rcpf(1.0f + __expf(-v)); }
;     __device__ __forceinline__ void operator()(const f32x4 (&acc)[2][2][4][2], const Unit& u, int wr, int wc, int fr, int fq) const {
;     ...
;             for (int m = 0; m < 4; ++m) { bf16_t* rowp = O + (size_t)(row0 + ai * HALF + m * 16) * ldc + col0;
; #pragma unroll
;                 for (int bj = 0; bj < 2; ++bj) { f32x4 v0 = acc[ai][bj][m][0] + bv[bj][0], v1 = acc[ai][bj][m][1] + bv[bj][1];
;                     if (mode == 1) {
; #pragma unroll
;                         for (int j = 0; j < 4; ++j) { v0[j] = v0[j] * fast_sigmoid(v0[j]); v1[j] = v1[j] * fast_sigmoid(v1[j]); } }
;                     else if (mode == 2) {
; #pragma unroll
;                         for (int j = 0; j < 4; ++j) { v0[j] = fast_sigmoid(v0[j]); v1[j] = fast_sigmoid(v1[j]); } }
;                     u32x4 w; w.x = cvt_pk_bf16(v0[0], v0[1]); w.y = cvt_pk_bf16(v0[2], v0[3]); w.z = cvt_pk_bf16(v1[0], v1[1]); w.w = cvt_pk_bf16(v1[2], v1[3]);
;                     *(u32x4*)(rowp + bj * HALF) = w; } }
.LBB0_183:
	v_cvt_pk_bf16_f32 v130, v141, v143
	v_cvt_pk_bf16_f32 v131, v145, v168
	v_cvt_pk_bf16_f32 v132, v142, v144
	v_cvt_pk_bf16_f32 v133, v158, v159
	v_pk_add_f32 v[128:129], v[128:129], v[48:49]
	v_pk_add_f32 v[126:127], v[126:127], v[46:47]
	v_pk_add_f32 v[124:125], v[124:125], v[44:45]
	v_pk_add_f32 v[122:123], v[122:123], v[42:43]
	s_cmp_gt_i32 s20, 1
	s_mov_b64 s[0:1], -1
	global_store_dwordx4 v[138:139], v[130:133], off offset:256
	s_cbranch_scc0 .LBB0_185
	v_mul_f32_e32 v136, 0xbfb8aa3b, v129
	v_mul_f32_e32 v130, 0xbfb8aa3b, v126
	v_mul_f32_e32 v131, 0xbfb8aa3b, v122
	v_mul_f32_e32 v132, 0xbfb8aa3b, v127
	v_mul_f32_e32 v133, 0xbfb8aa3b, v123
	v_mul_f32_e32 v134, 0xbfb8aa3b, v128
	v_mul_f32_e32 v135, 0xbfb8aa3b, v124
	v_exp_f32_e32 v136, v136
	v_mul_f32_e32 v137, 0xbfb8aa3b, v125
	v_exp_f32_e32 v130, v130
	v_exp_f32_e32 v131, v131
	v_exp_f32_e32 v132, v132
	v_exp_f32_e32 v133, v133
	v_exp_f32_e32 v134, v134
	v_exp_f32_e32 v135, v135
	v_exp_f32_e32 v138, v137
	v_add_f32_e32 v136, 1.0, v136
	v_add_f32_e32 v130, 1.0, v130
	v_add_f32_e32 v131, 1.0, v131
	v_add_f32_e32 v132, 1.0, v132
	v_add_f32_e32 v133, 1.0, v133
	v_add_f32_e32 v134, 1.0, v134
	v_add_f32_e32 v135, 1.0, v135
	v_rcp_f32_e32 v137, v136
	v_add_f32_e32 v136, 1.0, v138
	v_rcp_f32_e32 v130, v130
	v_rcp_f32_e32 v131, v131
	v_rcp_f32_e32 v132, v132
	v_rcp_f32_e32 v133, v133
	v_rcp_f32_e32 v134, v134
	v_rcp_f32_e32 v135, v135
	v_rcp_f32_e32 v136, v136
	s_mov_b64 s[0:1], 0

; __device__ __forceinline__ unsigned cvt_pk_bf16(float lo, float hi) { unsigned r; asm volatile("v_cvt_pk_bf16_f32 %0, %1, %2" : "=v"(r) : "v"(lo), "v"(hi)); return r; }
; __device__ __forceinline__ float fast_sigmoid(float v) { return __builtin_amdgcn_rcpf(1.0f + __expf(-v)); }
;     __device__ __forceinline__ void operator()(const f32x4 (&acc)[2][2][4][2], const Unit& u, int wr, int wc, int fr, int fq) const {
;     ...
;             for (int m = 0; m < 4; ++m) { bf16_t* rowp = O + (size_t)(row0 + ai * HALF + m * 16) * ldc + col0;
; #pragma unroll
;                 for (int bj = 0; bj < 2; ++bj) { f32x4 v0 = acc[ai][bj][m][0] + bv[bj][0], v1 = acc[ai][bj][m][1] + bv[bj][1];
;                     if (mode == 1) {
; #pragma unroll
;                         for (int j = 0; j < 4; ++j) { v0[j] = v0[j] * fast_sigmoid(v0[j]); v1[j] = v1[j] * fast_sigmoid(v1[j]); } }
;                     else if (mode == 2) {
; #pragma unroll
;                         for (int j = 0; j < 4; ++j) { v0[j] = fast_sigmoid(v0[j]); v1[j] = fast_sigmoid(v1[j]); } }
;                     u32x4 w; w.x = cvt_pk_bf16(v0[0], v0[1]); w.y = cvt_pk_bf16(v0[2], v0[3]); w.z = cvt_pk_bf16(v1[0], v1[1]); w.w = cvt_pk_bf16(v1[2], v1[3]);
;                     *(u32x4*)(rowp + bj * HALF) = w; } }
.LBB0_189:
	v_or_b32_e32 v124, 16, v140
	v_mov_b64_e32 v[122:123], s[8:9]
	v_mad_i64_i32 v[122:123], s[0:1], v124, s25, v[122:123]
	v_lshl_add_u64 v[122:123], v[156:157], 1, v[122:123]
	v_cvt_pk_bf16_f32 v124, v130, v132
	v_cvt_pk_bf16_f32 v125, v134, v137
	v_cvt_pk_bf16_f32 v126, v131, v133
	v_cvt_pk_bf16_f32 v127, v135, v136
	v_pk_add_f32 v[120:121], v[120:121], v[32:33]
	v_pk_add_f32 v[118:119], v[118:119], v[30:31]
	v_pk_add_f32 v[116:117], v[116:117], v[28:29]
	v_pk_add_f32 v[114:115], v[114:115], v[26:27]
	s_cmp_gt_i32 s20, 1
	s_mov_b64 s[0:1], -1
	global_store_dwordx4 v[122:123], v[124:127], off
	s_cbranch_scc0 .LBB0_191
	v_mul_f32_e32 v130, 0xbfb8aa3b, v121
	v_mul_f32_e32 v124, 0xbfb8aa3b, v118
	v_mul_f32_e32 v125, 0xbfb8aa3b, v114
	v_mul_f32_e32 v126, 0xbfb8aa3b, v119
	v_mul_f32_e32 v127, 0xbfb8aa3b, v115
	v_mul_f32_e32 v128, 0xbfb8aa3b, v120
	v_mul_f32_e32 v129, 0xbfb8aa3b, v116
	v_exp_f32_e32 v130, v130
	v_mul_f32_e32 v131, 0xbfb8aa3b, v117
	v_exp_f32_e32 v124, v124
	v_exp_f32_e32 v125, v125
	v_exp_f32_e32 v126, v126
	v_exp_f32_e32 v127, v127
	v_exp_f32_e32 v128, v128
	v_exp_f32_e32 v129, v129
	v_exp_f32_e32 v132, v131
	v_add_f32_e32 v130, 1.0, v130
	v_add_f32_e32 v124, 1.0, v124
	v_add_f32_e32 v125, 1.0, v125
	v_add_f32_e32 v126, 1.0, v126
	v_add_f32_e32 v127, 1.0, v127
	v_add_f32_e32 v128, 1.0, v128
	v_add_f32_e32 v129, 1.0, v129
	v_rcp_f32_e32 v131, v130
	v_add_f32_e32 v130, 1.0, v132
	v_rcp_f32_e32 v124, v124
	v_rcp_f32_e32 v125, v125
	v_rcp_f32_e32 v126, v126
	v_rcp_f32_e32 v127, v127
	v_rcp_f32_e32 v128, v128
	v_rcp_f32_e32 v129, v129
	v_rcp_f32_e32 v130, v130
	s_mov_b64 s[0:1], 0

; __device__ __forceinline__ unsigned cvt_pk_bf16(float lo, float hi) { unsigned r; asm volatile("v_cvt_pk_bf16_f32 %0, %1, %2" : "=v"(r) : "v"(lo), "v"(hi)); return r; }
; __device__ __forceinline__ float fast_sigmoid(float v) { return __builtin_amdgcn_rcpf(1.0f + __expf(-v)); }
;     __device__ __forceinline__ void operator()(const f32x4 (&acc)[2][2][4][2], const Unit& u, int wr, int wc, int fr, int fq) const {
;     ...
;             for (int m = 0; m < 4; ++m) { bf16_t* rowp = O + (size_t)(row0 + ai * HALF + m * 16) * ldc + col0;
; #pragma unroll
;                 for (int bj = 0; bj < 2; ++bj) { f32x4 v0 = acc[ai][bj][m][0] + bv[bj][0], v1 = acc[ai][bj][m][1] + bv[bj][1];
;                     if (mode == 1) {
; #pragma unroll
;                         for (int j = 0; j < 4; ++j) { v0[j] = v0[j] * fast_sigmoid(v0[j]); v1[j] = v1[j] * fast_sigmoid(v1[j]); } }
;                     else if (mode == 2) {
; #pragma unroll
;                         for (int j = 0; j < 4; ++j) { v0[j] = fast_sigmoid(v0[j]); v1[j] = fast_sigmoid(v1[j]); } }
;                     u32x4 w; w.x = cvt_pk_bf16(v0[0], v0[1]); w.y = cvt_pk_bf16(v0[2], v0[3]); w.z = cvt_pk_bf16(v1[0], v1[1]); w.w = cvt_pk_bf16(v1[2], v1[3]);
;                     *(u32x4*)(rowp + bj * HALF) = w; } }
.LBB0_195:
	v_cvt_pk_bf16_f32 v114, v124, v126
	v_cvt_pk_bf16_f32 v115, v128, v131
	v_cvt_pk_bf16_f32 v116, v125, v127
	v_cvt_pk_bf16_f32 v117, v129, v130
	v_pk_add_f32 v[112:113], v[112:113], v[48:49]
	v_pk_add_f32 v[110:111], v[110:111], v[46:47]
	v_pk_add_f32 v[108:109], v[108:109], v[44:45]
	v_pk_add_f32 v[106:107], v[106:107], v[42:43]
	s_cmp_gt_i32 s20, 1
	s_mov_b64 s[0:1], -1
	global_store_dwordx4 v[122:123], v[114:117], off offset:256
	s_cbranch_scc0 .LBB0_197
	v_mul_f32_e32 v120, 0xbfb8aa3b, v113
	v_mul_f32_e32 v114, 0xbfb8aa3b, v110
	v_mul_f32_e32 v115, 0xbfb8aa3b, v106
	v_mul_f32_e32 v116, 0xbfb8aa3b, v111
	v_mul_f32_e32 v117, 0xbfb8aa3b, v107
	v_mul_f32_e32 v118, 0xbfb8aa3b, v112
	v_mul_f32_e32 v119, 0xbfb8aa3b, v108
	v_exp_f32_e32 v120, v120
	v_mul_f32_e32 v121, 0xbfb8aa3b, v109
	v_exp_f32_e32 v114, v114
	v_exp_f32_e32 v115, v115
	v_exp_f32_e32 v116, v116
	v_exp_f32_e32 v117, v117
	v_exp_f32_e32 v118, v118
	v_exp_f32_e32 v119, v119
	v_exp_f32_e32 v122, v121
	v_add_f32_e32 v120, 1.0, v120
	v_add_f32_e32 v114, 1.0, v114
	v_add_f32_e32 v115, 1.0, v115
	v_add_f32_e32 v116, 1.0, v116
	v_add_f32_e32 v117, 1.0, v117
	v_add_f32_e32 v118, 1.0, v118
	v_add_f32_e32 v119, 1.0, v119
	v_rcp_f32_e32 v121, v120
	v_add_f32_e32 v120, 1.0, v122
	v_rcp_f32_e32 v114, v114
	v_rcp_f32_e32 v115, v115
	v_rcp_f32_e32 v116, v116
	v_rcp_f32_e32 v117, v117
	v_rcp_f32_e32 v118, v118
	v_rcp_f32_e32 v119, v119
	v_rcp_f32_e32 v120, v120
	s_mov_b64 s[0:1], 0

; __device__ __forceinline__ unsigned cvt_pk_bf16(float lo, float hi) { unsigned r; asm volatile("v_cvt_pk_bf16_f32 %0, %1, %2" : "=v"(r) : "v"(lo), "v"(hi)); return r; }
; __device__ __forceinline__ float fast_sigmoid(float v) { return __builtin_amdgcn_rcpf(1.0f + __expf(-v)); }
;     __device__ __forceinline__ void operator()(const f32x4 (&acc)[2][2][4][2], const Unit& u, int wr, int wc, int fr, int fq) const {
;     ...
;             for (int m = 0; m < 4; ++m) { bf16_t* rowp = O + (size_t)(row0 + ai * HALF + m * 16) * ldc + col0;
; #pragma unroll
;                 for (int bj = 0; bj < 2; ++bj) { f32x4 v0 = acc[ai][bj][m][0] + bv[bj][0], v1 = acc[ai][bj][m][1] + bv[bj][1];
;                     if (mode == 1) {
; #pragma unroll
;                         for (int j = 0; j < 4; ++j) { v0[j] = v0[j] * fast_sigmoid(v0[j]); v1[j] = v1[j] * fast_sigmoid(v1[j]); } }
;                     else if (mode == 2) {
; #pragma unroll
;                         for (int j = 0; j < 4; ++j) { v0[j] = fast_sigmoid(v0[j]); v1[j] = fast_sigmoid(v1[j]); } }
;                     u32x4 w; w.x = cvt_pk_bf16(v0[0], v0[1]); w.y = cvt_pk_bf16(v0[2], v0[3]); w.z = cvt_pk_bf16(v1[0], v1[1]); w.w = cvt_pk_bf16(v1[2], v1[3]);
;                     *(u32x4*)(rowp + bj * HALF) = w; } }
.LBB0_201:
	v_or_b32_e32 v108, 32, v140
	v_mov_b64_e32 v[106:107], s[8:9]
	v_mad_i64_i32 v[106:107], s[0:1], v108, s25, v[106:107]
	v_lshl_add_u64 v[106:107], v[156:157], 1, v[106:107]
	v_cvt_pk_bf16_f32 v108, v114, v116
	v_cvt_pk_bf16_f32 v109, v118, v121
	v_cvt_pk_bf16_f32 v110, v115, v117
	v_cvt_pk_bf16_f32 v111, v119, v120
	v_pk_add_f32 v[104:105], v[104:105], v[32:33]
	v_pk_add_f32 v[102:103], v[102:103], v[30:31]
	v_pk_add_f32 v[100:101], v[100:101], v[28:29]
	v_pk_add_f32 v[98:99], v[98:99], v[26:27]
	s_cmp_gt_i32 s20, 1
	s_mov_b64 s[0:1], -1
	global_store_dwordx4 v[106:107], v[108:111], off
	s_cbranch_scc0 .LBB0_203
	v_mul_f32_e32 v114, 0xbfb8aa3b, v105
	v_mul_f32_e32 v108, 0xbfb8aa3b, v102
	v_mul_f32_e32 v109, 0xbfb8aa3b, v98
	v_mul_f32_e32 v110, 0xbfb8aa3b, v103
	v_mul_f32_e32 v111, 0xbfb8aa3b, v99
	v_mul_f32_e32 v112, 0xbfb8aa3b, v104
	v_mul_f32_e32 v113, 0xbfb8aa3b, v100
	v_exp_f32_e32 v114, v114
	v_mul_f32_e32 v115, 0xbfb8aa3b, v101
	v_exp_f32_e32 v108, v108
	v_exp_f32_e32 v109, v109
	v_exp_f32_e32 v110, v110
	v_exp_f32_e32 v111, v111
	v_exp_f32_e32 v112, v112
	v_exp_f32_e32 v113, v113
	v_exp_f32_e32 v116, v115
	v_add_f32_e32 v114, 1.0, v114
	v_add_f32_e32 v108, 1.0, v108
	v_add_f32_e32 v109, 1.0, v109
	v_add_f32_e32 v110, 1.0, v110
	v_add_f32_e32 v111, 1.0, v111
	v_add_f32_e32 v112, 1.0, v112
	v_add_f32_e32 v113, 1.0, v113
	v_rcp_f32_e32 v115, v114
	v_add_f32_e32 v114, 1.0, v116
	v_rcp_f32_e32 v108, v108
	v_rcp_f32_e32 v109, v109
	v_rcp_f32_e32 v110, v110
	v_rcp_f32_e32 v111, v111
	v_rcp_f32_e32 v112, v112
	v_rcp_f32_e32 v113, v113
	v_rcp_f32_e32 v114, v114
	s_mov_b64 s[0:1], 0

; __device__ __forceinline__ unsigned cvt_pk_bf16(float lo, float hi) { unsigned r; asm volatile("v_cvt_pk_bf16_f32 %0, %1, %2" : "=v"(r) : "v"(lo), "v"(hi)); return r; }
; __device__ __forceinline__ float fast_sigmoid(float v) { return __builtin_amdgcn_rcpf(1.0f + __expf(-v)); }
;     __device__ __forceinline__ void operator()(const f32x4 (&acc)[2][2][4][2], const Unit& u, int wr, int wc, int fr, int fq) const {
;     ...
;             for (int m = 0; m < 4; ++m) { bf16_t* rowp = O + (size_t)(row0 + ai * HALF + m * 16) * ldc + col0;
; #pragma unroll
;                 for (int bj = 0; bj < 2; ++bj) { f32x4 v0 = acc[ai][bj][m][0] + bv[bj][0], v1 = acc[ai][bj][m][1] + bv[bj][1];
;                     if (mode == 1) {
; #pragma unroll
;                         for (int j = 0; j < 4; ++j) { v0[j] = v0[j] * fast_sigmoid(v0[j]); v1[j] = v1[j] * fast_sigmoid(v1[j]); } }
;                     else if (mode == 2) {
; #pragma unroll
;                         for (int j = 0; j < 4; ++j) { v0[j] = fast_sigmoid(v0[j]); v1[j] = fast_sigmoid(v1[j]); } }
;                     u32x4 w; w.x = cvt_pk_bf16(v0[0], v0[1]); w.y = cvt_pk_bf16(v0[2], v0[3]); w.z = cvt_pk_bf16(v1[0], v1[1]); w.w = cvt_pk_bf16(v1[2], v1[3]);
;                     *(u32x4*)(rowp + bj * HALF) = w; } }
.LBB0_207:
	v_cvt_pk_bf16_f32 v98, v108, v110
	v_cvt_pk_bf16_f32 v99, v112, v115
	v_cvt_pk_bf16_f32 v100, v109, v111
	v_cvt_pk_bf16_f32 v101, v113, v114
	v_pk_add_f32 v[96:97], v[96:97], v[48:49]
	v_pk_add_f32 v[94:95], v[94:95], v[46:47]
	v_pk_add_f32 v[92:93], v[92:93], v[44:45]
	v_pk_add_f32 v[90:91], v[90:91], v[42:43]
	s_cmp_gt_i32 s20, 1
	s_mov_b64 s[0:1], -1
	global_store_dwordx4 v[106:107], v[98:101], off offset:256
	s_cbranch_scc0 .LBB0_209
	v_mul_f32_e32 v104, 0xbfb8aa3b, v97
	v_mul_f32_e32 v98, 0xbfb8aa3b, v94
	v_mul_f32_e32 v99, 0xbfb8aa3b, v90
	v_mul_f32_e32 v100, 0xbfb8aa3b, v95
	v_mul_f32_e32 v101, 0xbfb8aa3b, v91
	v_mul_f32_e32 v102, 0xbfb8aa3b, v96
	v_mul_f32_e32 v103, 0xbfb8aa3b, v92
	v_exp_f32_e32 v104, v104
	v_mul_f32_e32 v105, 0xbfb8aa3b, v93
	v_exp_f32_e32 v98, v98
	v_exp_f32_e32 v99, v99
	v_exp_f32_e32 v100, v100
	v_exp_f32_e32 v101, v101
	v_exp_f32_e32 v102, v102
	v_exp_f32_e32 v103, v103
	v_exp_f32_e32 v106, v105
	v_add_f32_e32 v104, 1.0, v104
	v_add_f32_e32 v98, 1.0, v98
	v_add_f32_e32 v99, 1.0, v99
	v_add_f32_e32 v100, 1.0, v100
	v_add_f32_e32 v101, 1.0, v101
	v_add_f32_e32 v102, 1.0, v102
	v_add_f32_e32 v103, 1.0, v103
	v_rcp_f32_e32 v105, v104
	v_add_f32_e32 v104, 1.0, v106
	v_rcp_f32_e32 v98, v98
	v_rcp_f32_e32 v99, v99
	v_rcp_f32_e32 v100, v100
	v_rcp_f32_e32 v101, v101
	v_rcp_f32_e32 v102, v102
	v_rcp_f32_e32 v103, v103
	v_rcp_f32_e32 v104, v104
	s_mov_b64 s[0:1], 0

; __device__ __forceinline__ unsigned cvt_pk_bf16(float lo, float hi) { unsigned r; asm volatile("v_cvt_pk_bf16_f32 %0, %1, %2" : "=v"(r) : "v"(lo), "v"(hi)); return r; }
; __device__ __forceinline__ float fast_sigmoid(float v) { return __builtin_amdgcn_rcpf(1.0f + __expf(-v)); }
;     __device__ __forceinline__ void operator()(const f32x4 (&acc)[2][2][4][2], const Unit& u, int wr, int wc, int fr, int fq) const {
;     ...
;             for (int m = 0; m < 4; ++m) { bf16_t* rowp = O + (size_t)(row0 + ai * HALF + m * 16) * ldc + col0;
; #pragma unroll
;                 for (int bj = 0; bj < 2; ++bj) { f32x4 v0 = acc[ai][bj][m][0] + bv[bj][0], v1 = acc[ai][bj][m][1] + bv[bj][1];
;                     if (mode == 1) {
; #pragma unroll
;                         for (int j = 0; j < 4; ++j) { v0[j] = v0[j] * fast_sigmoid(v0[j]); v1[j] = v1[j] * fast_sigmoid(v1[j]); } }
;                     else if (mode == 2) {
; #pragma unroll
;                         for (int j = 0; j < 4; ++j) { v0[j] = fast_sigmoid(v0[j]); v1[j] = fast_sigmoid(v1[j]); } }
;                     u32x4 w; w.x = cvt_pk_bf16(v0[0], v0[1]); w.y = cvt_pk_bf16(v0[2], v0[3]); w.z = cvt_pk_bf16(v1[0], v1[1]); w.w = cvt_pk_bf16(v1[2], v1[3]);
;                     *(u32x4*)(rowp + bj * HALF) = w; } }
.LBB0_213:
	v_or_b32_e32 v92, 48, v140
	v_mov_b64_e32 v[90:91], s[8:9]
	v_mad_i64_i32 v[90:91], s[0:1], v92, s25, v[90:91]
	v_lshl_add_u64 v[90:91], v[156:157], 1, v[90:91]
	v_cvt_pk_bf16_f32 v92, v98, v100
	v_cvt_pk_bf16_f32 v93, v102, v105
	v_cvt_pk_bf16_f32 v94, v99, v101
	v_cvt_pk_bf16_f32 v95, v103, v104
	v_pk_add_f32 v[88:89], v[88:89], v[32:33]
	v_pk_add_f32 v[86:87], v[86:87], v[30:31]
	v_pk_add_f32 v[84:85], v[84:85], v[28:29]
	v_pk_add_f32 v[82:83], v[82:83], v[26:27]
	s_cmp_gt_i32 s20, 1
	s_mov_b64 s[0:1], -1
	global_store_dwordx4 v[90:91], v[92:95], off
	s_cbranch_scc0 .LBB0_215
	v_mul_f32_e32 v98, 0xbfb8aa3b, v89
	v_mul_f32_e32 v92, 0xbfb8aa3b, v86
	v_mul_f32_e32 v93, 0xbfb8aa3b, v82
	v_mul_f32_e32 v94, 0xbfb8aa3b, v87
	v_mul_f32_e32 v95, 0xbfb8aa3b, v83
	v_mul_f32_e32 v96, 0xbfb8aa3b, v88
	v_mul_f32_e32 v97, 0xbfb8aa3b, v84
	v_exp_f32_e32 v98, v98
	v_mul_f32_e32 v99, 0xbfb8aa3b, v85
	v_exp_f32_e32 v92, v92
	v_exp_f32_e32 v93, v93
	v_exp_f32_e32 v94, v94
	v_exp_f32_e32 v95, v95
	v_exp_f32_e32 v96, v96
	v_exp_f32_e32 v97, v97
	v_exp_f32_e32 v100, v99
	v_add_f32_e32 v98, 1.0, v98
	v_add_f32_e32 v92, 1.0, v92
	v_add_f32_e32 v93, 1.0, v93
	v_add_f32_e32 v94, 1.0, v94
	v_add_f32_e32 v95, 1.0, v95
	v_add_f32_e32 v96, 1.0, v96
	v_add_f32_e32 v97, 1.0, v97
	v_rcp_f32_e32 v99, v98
	v_add_f32_e32 v98, 1.0, v100
	v_rcp_f32_e32 v92, v92
	v_rcp_f32_e32 v93, v93
	v_rcp_f32_e32 v94, v94
	v_rcp_f32_e32 v95, v95
	v_rcp_f32_e32 v96, v96
	v_rcp_f32_e32 v97, v97
	v_rcp_f32_e32 v98, v98
	s_mov_b64 s[0:1], 0

; __device__ __forceinline__ unsigned cvt_pk_bf16(float lo, float hi) { unsigned r; asm volatile("v_cvt_pk_bf16_f32 %0, %1, %2" : "=v"(r) : "v"(lo), "v"(hi)); return r; }
; __device__ __forceinline__ float fast_sigmoid(float v) { return __builtin_amdgcn_rcpf(1.0f + __expf(-v)); }
;     __device__ __forceinline__ void operator()(const f32x4 (&acc)[2][2][4][2], const Unit& u, int wr, int wc, int fr, int fq) const {
;     ...
;             for (int m = 0; m < 4; ++m) { bf16_t* rowp = O + (size_t)(row0 + ai * HALF + m * 16) * ldc + col0;
; #pragma unroll
;                 for (int bj = 0; bj < 2; ++bj) { f32x4 v0 = acc[ai][bj][m][0] + bv[bj][0], v1 = acc[ai][bj][m][1] + bv[bj][1];
;                     if (mode == 1) {
; #pragma unroll
;                         for (int j = 0; j < 4; ++j) { v0[j] = v0[j] * fast_sigmoid(v0[j]); v1[j] = v1[j] * fast_sigmoid(v1[j]); } }
;                     else if (mode == 2) {
; #pragma unroll
;                         for (int j = 0; j < 4; ++j) { v0[j] = fast_sigmoid(v0[j]); v1[j] = fast_sigmoid(v1[j]); } }
;                     u32x4 w; w.x = cvt_pk_bf16(v0[0], v0[1]); w.y = cvt_pk_bf16(v0[2], v0[3]); w.z = cvt_pk_bf16(v1[0], v1[1]); w.w = cvt_pk_bf16(v1[2], v1[3]);
;                     *(u32x4*)(rowp + bj * HALF) = w; } }
.LBB0_219:
	v_cvt_pk_bf16_f32 v82, v92, v94
	v_cvt_pk_bf16_f32 v83, v96, v99
	v_cvt_pk_bf16_f32 v84, v93, v95
	v_cvt_pk_bf16_f32 v85, v97, v98
	v_pk_add_f32 v[80:81], v[80:81], v[48:49]
	v_pk_add_f32 v[78:79], v[78:79], v[46:47]
	v_pk_add_f32 v[76:77], v[76:77], v[44:45]
	v_pk_add_f32 v[74:75], v[74:75], v[42:43]
	s_cmp_gt_i32 s20, 1
	s_mov_b64 s[0:1], -1
	global_store_dwordx4 v[90:91], v[82:85], off offset:256
	s_cbranch_scc0 .LBB0_221
	v_mul_f32_e32 v88, 0xbfb8aa3b, v81
	v_mul_f32_e32 v82, 0xbfb8aa3b, v78
	v_mul_f32_e32 v83, 0xbfb8aa3b, v74
	v_mul_f32_e32 v84, 0xbfb8aa3b, v79
	v_mul_f32_e32 v85, 0xbfb8aa3b, v75
	v_mul_f32_e32 v86, 0xbfb8aa3b, v80
	v_mul_f32_e32 v87, 0xbfb8aa3b, v76
	v_exp_f32_e32 v88, v88
	v_mul_f32_e32 v89, 0xbfb8aa3b, v77
	v_exp_f32_e32 v82, v82
	v_exp_f32_e32 v83, v83
	v_exp_f32_e32 v84, v84
	v_exp_f32_e32 v85, v85
	v_exp_f32_e32 v86, v86
	v_exp_f32_e32 v87, v87
	v_exp_f32_e32 v90, v89
	v_add_f32_e32 v88, 1.0, v88
	v_add_f32_e32 v82, 1.0, v82
	v_add_f32_e32 v83, 1.0, v83
	v_add_f32_e32 v84, 1.0, v84
	v_add_f32_e32 v85, 1.0, v85
	v_add_f32_e32 v86, 1.0, v86
	v_add_f32_e32 v87, 1.0, v87
	v_rcp_f32_e32 v89, v88
	v_add_f32_e32 v88, 1.0, v90
	v_rcp_f32_e32 v82, v82
	v_rcp_f32_e32 v83, v83
	v_rcp_f32_e32 v84, v84
	v_rcp_f32_e32 v85, v85
	v_rcp_f32_e32 v86, v86
	v_rcp_f32_e32 v87, v87
	v_rcp_f32_e32 v88, v88
	s_mov_b64 s[0:1], 0

; __device__ __forceinline__ unsigned cvt_pk_bf16(float lo, float hi) { unsigned r; asm volatile("v_cvt_pk_bf16_f32 %0, %1, %2" : "=v"(r) : "v"(lo), "v"(hi)); return r; }
; __device__ __forceinline__ float fast_sigmoid(float v) { return __builtin_amdgcn_rcpf(1.0f + __expf(-v)); }
;     __device__ __forceinline__ void operator()(const f32x4 (&acc)[2][2][4][2], const Unit& u, int wr, int wc, int fr, int fq) const {
;     ...
;             for (int m = 0; m < 4; ++m) { bf16_t* rowp = O + (size_t)(row0 + ai * HALF + m * 16) * ldc + col0;
; #pragma unroll
;                 for (int bj = 0; bj < 2; ++bj) { f32x4 v0 = acc[ai][bj][m][0] + bv[bj][0], v1 = acc[ai][bj][m][1] + bv[bj][1];
;                     if (mode == 1) {
; #pragma unroll
;                         for (int j = 0; j < 4; ++j) { v0[j] = v0[j] * fast_sigmoid(v0[j]); v1[j] = v1[j] * fast_sigmoid(v1[j]); } }
;                     else if (mode == 2) {
; #pragma unroll
;                         for (int j = 0; j < 4; ++j) { v0[j] = fast_sigmoid(v0[j]); v1[j] = fast_sigmoid(v1[j]); } }
;                     u32x4 w; w.x = cvt_pk_bf16(v0[0], v0[1]); w.y = cvt_pk_bf16(v0[2], v0[3]); w.z = cvt_pk_bf16(v1[0], v1[1]); w.w = cvt_pk_bf16(v1[2], v1[3]);
;                     *(u32x4*)(rowp + bj * HALF) = w; } }
.LBB0_225:
	v_add_u32_e32 v76, 0x80, v140
	v_mov_b64_e32 v[74:75], s[8:9]
	v_mad_i64_i32 v[74:75], s[0:1], v76, s25, v[74:75]
	v_lshl_add_u64 v[74:75], v[156:157], 1, v[74:75]
	v_cvt_pk_bf16_f32 v76, v82, v84
	v_cvt_pk_bf16_f32 v77, v86, v89
	v_cvt_pk_bf16_f32 v78, v83, v85
	v_cvt_pk_bf16_f32 v79, v87, v88
	v_pk_add_f32 v[72:73], v[72:73], v[32:33]
	v_pk_add_f32 v[70:71], v[70:71], v[30:31]
	v_pk_add_f32 v[68:69], v[68:69], v[28:29]
	v_pk_add_f32 v[66:67], v[66:67], v[26:27]
	s_cmp_gt_i32 s20, 1
	s_mov_b64 s[0:1], -1
	global_store_dwordx4 v[74:75], v[76:79], off
	s_cbranch_scc0 .LBB0_227
	v_mul_f32_e32 v82, 0xbfb8aa3b, v73
	v_mul_f32_e32 v76, 0xbfb8aa3b, v70
	v_mul_f32_e32 v77, 0xbfb8aa3b, v66
	v_mul_f32_e32 v78, 0xbfb8aa3b, v71
	v_mul_f32_e32 v79, 0xbfb8aa3b, v67
	v_mul_f32_e32 v80, 0xbfb8aa3b, v72
	v_mul_f32_e32 v81, 0xbfb8aa3b, v68
	v_exp_f32_e32 v82, v82
	v_mul_f32_e32 v83, 0xbfb8aa3b, v69
	v_exp_f32_e32 v76, v76
	v_exp_f32_e32 v77, v77
	v_exp_f32_e32 v78, v78
	v_exp_f32_e32 v79, v79
	v_exp_f32_e32 v80, v80
	v_exp_f32_e32 v81, v81
	v_exp_f32_e32 v84, v83
	v_add_f32_e32 v82, 1.0, v82
	v_add_f32_e32 v76, 1.0, v76
	v_add_f32_e32 v77, 1.0, v77
	v_add_f32_e32 v78, 1.0, v78
	v_add_f32_e32 v79, 1.0, v79
	v_add_f32_e32 v80, 1.0, v80
	v_add_f32_e32 v81, 1.0, v81
	v_rcp_f32_e32 v83, v82
	v_add_f32_e32 v82, 1.0, v84
	v_rcp_f32_e32 v76, v76
	v_rcp_f32_e32 v77, v77
	v_rcp_f32_e32 v78, v78
	v_rcp_f32_e32 v79, v79
	v_rcp_f32_e32 v80, v80
	v_rcp_f32_e32 v81, v81
	v_rcp_f32_e32 v82, v82
	s_mov_b64 s[0:1], 0

; __device__ __forceinline__ unsigned cvt_pk_bf16(float lo, float hi) { unsigned r; asm volatile("v_cvt_pk_bf16_f32 %0, %1, %2" : "=v"(r) : "v"(lo), "v"(hi)); return r; }
; __device__ __forceinline__ float fast_sigmoid(float v) { return __builtin_amdgcn_rcpf(1.0f + __expf(-v)); }
;     __device__ __forceinline__ void operator()(const f32x4 (&acc)[2][2][4][2], const Unit& u, int wr, int wc, int fr, int fq) const {
;     ...
;             for (int m = 0; m < 4; ++m) { bf16_t* rowp = O + (size_t)(row0 + ai * HALF + m * 16) * ldc + col0;
; #pragma unroll
;                 for (int bj = 0; bj < 2; ++bj) { f32x4 v0 = acc[ai][bj][m][0] + bv[bj][0], v1 = acc[ai][bj][m][1] + bv[bj][1];
;                     if (mode == 1) {
; #pragma unroll
;                         for (int j = 0; j < 4; ++j) { v0[j] = v0[j] * fast_sigmoid(v0[j]); v1[j] = v1[j] * fast_sigmoid(v1[j]); } }
;                     else if (mode == 2) {
; #pragma unroll
;                         for (int j = 0; j < 4; ++j) { v0[j] = fast_sigmoid(v0[j]); v1[j] = fast_sigmoid(v1[j]); } }
;                     u32x4 w; w.x = cvt_pk_bf16(v0[0], v0[1]); w.y = cvt_pk_bf16(v0[2], v0[3]); w.z = cvt_pk_bf16(v1[0], v1[1]); w.w = cvt_pk_bf16(v1[2], v1[3]);
;                     *(u32x4*)(rowp + bj * HALF) = w; } }
.LBB0_231:
	v_cvt_pk_bf16_f32 v66, v76, v78
	v_cvt_pk_bf16_f32 v67, v80, v83
	v_cvt_pk_bf16_f32 v68, v77, v79
	v_cvt_pk_bf16_f32 v69, v81, v82
	v_pk_add_f32 v[64:65], v[64:65], v[48:49]
	v_pk_add_f32 v[62:63], v[62:63], v[46:47]
	v_pk_add_f32 v[60:61], v[60:61], v[44:45]
	v_pk_add_f32 v[58:59], v[58:59], v[42:43]
	s_cmp_gt_i32 s20, 1
	s_mov_b64 s[0:1], -1
	global_store_dwordx4 v[74:75], v[66:69], off offset:256
	s_cbranch_scc0 .LBB0_233
	v_mul_f32_e32 v72, 0xbfb8aa3b, v65
	v_mul_f32_e32 v66, 0xbfb8aa3b, v62
	v_mul_f32_e32 v67, 0xbfb8aa3b, v58
	v_mul_f32_e32 v68, 0xbfb8aa3b, v63
	v_mul_f32_e32 v69, 0xbfb8aa3b, v59
	v_mul_f32_e32 v70, 0xbfb8aa3b, v64
	v_mul_f32_e32 v71, 0xbfb8aa3b, v60
	v_exp_f32_e32 v72, v72
	v_mul_f32_e32 v73, 0xbfb8aa3b, v61
	v_exp_f32_e32 v66, v66
	v_exp_f32_e32 v67, v67
	v_exp_f32_e32 v68, v68
	v_exp_f32_e32 v69, v69
	v_exp_f32_e32 v70, v70
	v_exp_f32_e32 v71, v71
	v_exp_f32_e32 v74, v73
	v_add_f32_e32 v72, 1.0, v72
	v_add_f32_e32 v66, 1.0, v66
	v_add_f32_e32 v67, 1.0, v67
	v_add_f32_e32 v68, 1.0, v68
	v_add_f32_e32 v69, 1.0, v69
	v_add_f32_e32 v70, 1.0, v70
	v_add_f32_e32 v71, 1.0, v71
	v_rcp_f32_e32 v73, v72
	v_add_f32_e32 v72, 1.0, v74
	v_rcp_f32_e32 v66, v66
	v_rcp_f32_e32 v67, v67
	v_rcp_f32_e32 v68, v68
	v_rcp_f32_e32 v69, v69
	v_rcp_f32_e32 v70, v70
	v_rcp_f32_e32 v71, v71
	v_rcp_f32_e32 v72, v72
	s_mov_b64 s[0:1], 0

; __device__ __forceinline__ unsigned cvt_pk_bf16(float lo, float hi) { unsigned r; asm volatile("v_cvt_pk_bf16_f32 %0, %1, %2" : "=v"(r) : "v"(lo), "v"(hi)); return r; }
; __device__ __forceinline__ float fast_sigmoid(float v) { return __builtin_amdgcn_rcpf(1.0f + __expf(-v)); }
;     __device__ __forceinline__ void operator()(const f32x4 (&acc)[2][2][4][2], const Unit& u, int wr, int wc, int fr, int fq) const {
;     ...
;             for (int m = 0; m < 4; ++m) { bf16_t* rowp = O + (size_t)(row0 + ai * HALF + m * 16) * ldc + col0;
; #pragma unroll
;                 for (int bj = 0; bj < 2; ++bj) { f32x4 v0 = acc[ai][bj][m][0] + bv[bj][0], v1 = acc[ai][bj][m][1] + bv[bj][1];
;                     if (mode == 1) {
; #pragma unroll
;                         for (int j = 0; j < 4; ++j) { v0[j] = v0[j] * fast_sigmoid(v0[j]); v1[j] = v1[j] * fast_sigmoid(v1[j]); } }
;                     else if (mode == 2) {
; #pragma unroll
;                         for (int j = 0; j < 4; ++j) { v0[j] = fast_sigmoid(v0[j]); v1[j] = fast_sigmoid(v1[j]); } }
;                     u32x4 w; w.x = cvt_pk_bf16(v0[0], v0[1]); w.y = cvt_pk_bf16(v0[2], v0[3]); w.z = cvt_pk_bf16(v1[0], v1[1]); w.w = cvt_pk_bf16(v1[2], v1[3]);
;                     *(u32x4*)(rowp + bj * HALF) = w; } }
.LBB0_237:
	v_add_u32_e32 v60, 0x90, v140
	v_mov_b64_e32 v[58:59], s[8:9]
	v_mad_i64_i32 v[58:59], s[0:1], v60, s25, v[58:59]
	v_lshl_add_u64 v[58:59], v[156:157], 1, v[58:59]
	v_cvt_pk_bf16_f32 v60, v66, v68
	v_cvt_pk_bf16_f32 v61, v70, v73
	v_cvt_pk_bf16_f32 v62, v67, v69
	v_cvt_pk_bf16_f32 v63, v71, v72
	v_pk_add_f32 v[56:57], v[56:57], v[32:33]
	v_pk_add_f32 v[54:55], v[54:55], v[30:31]
	v_pk_add_f32 v[52:53], v[52:53], v[28:29]
	v_pk_add_f32 v[50:51], v[50:51], v[26:27]
	s_cmp_gt_i32 s20, 1
	s_mov_b64 s[0:1], -1
	global_store_dwordx4 v[58:59], v[60:63], off
	s_cbranch_scc0 .LBB0_239
	v_mul_f32_e32 v66, 0xbfb8aa3b, v57
	v_mul_f32_e32 v60, 0xbfb8aa3b, v54
	v_mul_f32_e32 v61, 0xbfb8aa3b, v50
	v_mul_f32_e32 v62, 0xbfb8aa3b, v55
	v_mul_f32_e32 v63, 0xbfb8aa3b, v51
	v_mul_f32_e32 v64, 0xbfb8aa3b, v56
	v_mul_f32_e32 v65, 0xbfb8aa3b, v52
	v_exp_f32_e32 v66, v66
	v_mul_f32_e32 v67, 0xbfb8aa3b, v53
	v_exp_f32_e32 v60, v60
	v_exp_f32_e32 v61, v61
	v_exp_f32_e32 v62, v62
	v_exp_f32_e32 v63, v63
	v_exp_f32_e32 v64, v64
	v_exp_f32_e32 v65, v65
	v_exp_f32_e32 v68, v67
	v_add_f32_e32 v66, 1.0, v66
	v_add_f32_e32 v60, 1.0, v60
	v_add_f32_e32 v61, 1.0, v61
	v_add_f32_e32 v62, 1.0, v62
	v_add_f32_e32 v63, 1.0, v63
	v_add_f32_e32 v64, 1.0, v64
	v_add_f32_e32 v65, 1.0, v65
	v_rcp_f32_e32 v67, v66
	v_add_f32_e32 v66, 1.0, v68
	v_rcp_f32_e32 v60, v60
	v_rcp_f32_e32 v61, v61
	v_rcp_f32_e32 v62, v62
	v_rcp_f32_e32 v63, v63
	v_rcp_f32_e32 v64, v64
	v_rcp_f32_e32 v65, v65
	v_rcp_f32_e32 v66, v66
	s_mov_b64 s[0:1], 0

; __device__ __forceinline__ unsigned cvt_pk_bf16(float lo, float hi) { unsigned r; asm volatile("v_cvt_pk_bf16_f32 %0, %1, %2" : "=v"(r) : "v"(lo), "v"(hi)); return r; }
; __device__ __forceinline__ float fast_sigmoid(float v) { return __builtin_amdgcn_rcpf(1.0f + __expf(-v)); }
;     __device__ __forceinline__ void operator()(const f32x4 (&acc)[2][2][4][2], const Unit& u, int wr, int wc, int fr, int fq) const {
;     ...
;             for (int m = 0; m < 4; ++m) { bf16_t* rowp = O + (size_t)(row0 + ai * HALF + m * 16) * ldc + col0;
; #pragma unroll
;                 for (int bj = 0; bj < 2; ++bj) { f32x4 v0 = acc[ai][bj][m][0] + bv[bj][0], v1 = acc[ai][bj][m][1] + bv[bj][1];
;                     if (mode == 1) {
; #pragma unroll
;                         for (int j = 0; j < 4; ++j) { v0[j] = v0[j] * fast_sigmoid(v0[j]); v1[j] = v1[j] * fast_sigmoid(v1[j]); } }
;                     else if (mode == 2) {
; #pragma unroll
;                         for (int j = 0; j < 4; ++j) { v0[j] = fast_sigmoid(v0[j]); v1[j] = fast_sigmoid(v1[j]); } }
;                     u32x4 w; w.x = cvt_pk_bf16(v0[0], v0[1]); w.y = cvt_pk_bf16(v0[2], v0[3]); w.z = cvt_pk_bf16(v1[0], v1[1]); w.w = cvt_pk_bf16(v1[2], v1[3]);
;                     *(u32x4*)(rowp + bj * HALF) = w; } }
.LBB0_243:
	v_cvt_pk_bf16_f32 v50, v60, v62
	v_cvt_pk_bf16_f32 v51, v64, v67
	v_cvt_pk_bf16_f32 v52, v61, v63
	v_cvt_pk_bf16_f32 v53, v65, v66
	v_pk_add_f32 v[40:41], v[40:41], v[48:49]
	v_pk_add_f32 v[38:39], v[38:39], v[46:47]
	v_pk_add_f32 v[36:37], v[36:37], v[44:45]
	v_pk_add_f32 v[34:35], v[34:35], v[42:43]
	s_cmp_gt_i32 s20, 1
	s_mov_b64 s[0:1], -1
	global_store_dwordx4 v[58:59], v[50:53], off offset:256
	s_cbranch_scc0 .LBB0_245
	v_mul_f32_e32 v56, 0xbfb8aa3b, v41
	v_mul_f32_e32 v50, 0xbfb8aa3b, v38
	v_mul_f32_e32 v51, 0xbfb8aa3b, v34
	v_mul_f32_e32 v52, 0xbfb8aa3b, v39
	v_mul_f32_e32 v53, 0xbfb8aa3b, v35
	v_mul_f32_e32 v54, 0xbfb8aa3b, v40
	v_mul_f32_e32 v55, 0xbfb8aa3b, v36
	v_exp_f32_e32 v56, v56
	v_mul_f32_e32 v57, 0xbfb8aa3b, v37
	v_exp_f32_e32 v50, v50
	v_exp_f32_e32 v51, v51
	v_exp_f32_e32 v52, v52
	v_exp_f32_e32 v53, v53
	v_exp_f32_e32 v54, v54
	v_exp_f32_e32 v55, v55
	v_exp_f32_e32 v58, v57
	v_add_f32_e32 v56, 1.0, v56
	v_add_f32_e32 v50, 1.0, v50
	v_add_f32_e32 v51, 1.0, v51
	v_add_f32_e32 v52, 1.0, v52
	v_add_f32_e32 v53, 1.0, v53
	v_add_f32_e32 v54, 1.0, v54
	v_add_f32_e32 v55, 1.0, v55
	v_rcp_f32_e32 v57, v56
	v_add_f32_e32 v56, 1.0, v58
	v_rcp_f32_e32 v50, v50
	v_rcp_f32_e32 v51, v51
	v_rcp_f32_e32 v52, v52
	v_rcp_f32_e32 v53, v53
	v_rcp_f32_e32 v54, v54
	v_rcp_f32_e32 v55, v55
	v_rcp_f32_e32 v56, v56
	s_mov_b64 s[0:1], 0

; __device__ __forceinline__ unsigned cvt_pk_bf16(float lo, float hi) { unsigned r; asm volatile("v_cvt_pk_bf16_f32 %0, %1, %2" : "=v"(r) : "v"(lo), "v"(hi)); return r; }
; __device__ __forceinline__ float fast_sigmoid(float v) { return __builtin_amdgcn_rcpf(1.0f + __expf(-v)); }
;     __device__ __forceinline__ void operator()(const f32x4 (&acc)[2][2][4][2], const Unit& u, int wr, int wc, int fr, int fq) const {
;     ...
;             for (int m = 0; m < 4; ++m) { bf16_t* rowp = O + (size_t)(row0 + ai * HALF + m * 16) * ldc + col0;
; #pragma unroll
;                 for (int bj = 0; bj < 2; ++bj) { f32x4 v0 = acc[ai][bj][m][0] + bv[bj][0], v1 = acc[ai][bj][m][1] + bv[bj][1];
;                     if (mode == 1) {
; #pragma unroll
;                         for (int j = 0; j < 4; ++j) { v0[j] = v0[j] * fast_sigmoid(v0[j]); v1[j] = v1[j] * fast_sigmoid(v1[j]); } }
;                     else if (mode == 2) {
; #pragma unroll
;                         for (int j = 0; j < 4; ++j) { v0[j] = fast_sigmoid(v0[j]); v1[j] = fast_sigmoid(v1[j]); } }
;                     u32x4 w; w.x = cvt_pk_bf16(v0[0], v0[1]); w.y = cvt_pk_bf16(v0[2], v0[3]); w.z = cvt_pk_bf16(v1[0], v1[1]); w.w = cvt_pk_bf16(v1[2], v1[3]);
;                     *(u32x4*)(rowp + bj * HALF) = w; } }
.LBB0_249:
	v_add_u32_e32 v36, 0xa0, v140
	v_mov_b64_e32 v[34:35], s[8:9]
	v_mad_i64_i32 v[34:35], s[0:1], v36, s25, v[34:35]
	v_lshl_add_u64 v[34:35], v[156:157], 1, v[34:35]
	v_cvt_pk_bf16_f32 v36, v50, v52
	v_cvt_pk_bf16_f32 v37, v54, v57
	v_cvt_pk_bf16_f32 v38, v51, v53
	v_cvt_pk_bf16_f32 v39, v55, v56
	v_pk_add_f32 v[24:25], v[24:25], v[32:33]
	v_pk_add_f32 v[22:23], v[22:23], v[30:31]
	v_pk_add_f32 v[20:21], v[20:21], v[28:29]
	v_pk_add_f32 v[18:19], v[18:19], v[26:27]
	s_cmp_gt_i32 s20, 1
	s_mov_b64 s[0:1], -1
	global_store_dwordx4 v[34:35], v[36:39], off
	s_cbranch_scc0 .LBB0_251
	v_mul_f32_e32 v50, 0xbfb8aa3b, v25
	v_mul_f32_e32 v36, 0xbfb8aa3b, v22
	v_mul_f32_e32 v37, 0xbfb8aa3b, v18
	v_mul_f32_e32 v38, 0xbfb8aa3b, v23
	v_mul_f32_e32 v39, 0xbfb8aa3b, v19
	v_mul_f32_e32 v40, 0xbfb8aa3b, v24
	v_mul_f32_e32 v41, 0xbfb8aa3b, v20
	v_exp_f32_e32 v50, v50
	v_mul_f32_e32 v51, 0xbfb8aa3b, v21
	v_exp_f32_e32 v36, v36
	v_exp_f32_e32 v37, v37
	v_exp_f32_e32 v38, v38
	v_exp_f32_e32 v39, v39
	v_exp_f32_e32 v40, v40
	v_exp_f32_e32 v41, v41
	v_exp_f32_e32 v52, v51
	v_add_f32_e32 v50, 1.0, v50
	v_add_f32_e32 v36, 1.0, v36
	v_add_f32_e32 v37, 1.0, v37
	v_add_f32_e32 v38, 1.0, v38
	v_add_f32_e32 v39, 1.0, v39
	v_add_f32_e32 v40, 1.0, v40
	v_add_f32_e32 v41, 1.0, v41
	v_rcp_f32_e32 v51, v50
	v_add_f32_e32 v50, 1.0, v52
	v_rcp_f32_e32 v36, v36
	v_rcp_f32_e32 v37, v37
	v_rcp_f32_e32 v38, v38
	v_rcp_f32_e32 v39, v39
	v_rcp_f32_e32 v40, v40
	v_rcp_f32_e32 v41, v41
	v_rcp_f32_e32 v50, v50
	s_mov_b64 s[0:1], 0

; __device__ __forceinline__ unsigned cvt_pk_bf16(float lo, float hi) { unsigned r; asm volatile("v_cvt_pk_bf16_f32 %0, %1, %2" : "=v"(r) : "v"(lo), "v"(hi)); return r; }
; __device__ __forceinline__ float fast_sigmoid(float v) { return __builtin_amdgcn_rcpf(1.0f + __expf(-v)); }
;     __device__ __forceinline__ void operator()(const f32x4 (&acc)[2][2][4][2], const Unit& u, int wr, int wc, int fr, int fq) const {
;     ...
;             for (int m = 0; m < 4; ++m) { bf16_t* rowp = O + (size_t)(row0 + ai * HALF + m * 16) * ldc + col0;
; #pragma unroll
;                 for (int bj = 0; bj < 2; ++bj) { f32x4 v0 = acc[ai][bj][m][0] + bv[bj][0], v1 = acc[ai][bj][m][1] + bv[bj][1];
;                     if (mode == 1) {
; #pragma unroll
;                         for (int j = 0; j < 4; ++j) { v0[j] = v0[j] * fast_sigmoid(v0[j]); v1[j] = v1[j] * fast_sigmoid(v1[j]); } }
;                     else if (mode == 2) {
; #pragma unroll
;                         for (int j = 0; j < 4; ++j) { v0[j] = fast_sigmoid(v0[j]); v1[j] = fast_sigmoid(v1[j]); } }
;                     u32x4 w; w.x = cvt_pk_bf16(v0[0], v0[1]); w.y = cvt_pk_bf16(v0[2], v0[3]); w.z = cvt_pk_bf16(v1[0], v1[1]); w.w = cvt_pk_bf16(v1[2], v1[3]);
;                     *(u32x4*)(rowp + bj * HALF) = w; } }
.LBB0_255:
	v_cvt_pk_bf16_f32 v18, v36, v38
	v_cvt_pk_bf16_f32 v19, v40, v51
	v_cvt_pk_bf16_f32 v20, v37, v39
	v_cvt_pk_bf16_f32 v21, v41, v50
	v_pk_add_f32 v[16:17], v[16:17], v[48:49]
	v_pk_add_f32 v[14:15], v[14:15], v[46:47]
	v_pk_add_f32 v[12:13], v[12:13], v[44:45]
	v_pk_add_f32 v[10:11], v[10:11], v[42:43]
	s_cmp_gt_i32 s20, 1
	s_mov_b64 s[0:1], -1
	global_store_dwordx4 v[34:35], v[18:21], off offset:256
	s_cbranch_scc0 .LBB0_257
	v_mul_f32_e32 v24, 0xbfb8aa3b, v17
	v_mul_f32_e32 v18, 0xbfb8aa3b, v14
	v_mul_f32_e32 v19, 0xbfb8aa3b, v10
	v_mul_f32_e32 v20, 0xbfb8aa3b, v15
	v_mul_f32_e32 v21, 0xbfb8aa3b, v11
	v_mul_f32_e32 v22, 0xbfb8aa3b, v16
	v_mul_f32_e32 v23, 0xbfb8aa3b, v12
	v_exp_f32_e32 v24, v24
	v_mul_f32_e32 v25, 0xbfb8aa3b, v13
	v_exp_f32_e32 v18, v18
	v_exp_f32_e32 v19, v19
	v_exp_f32_e32 v20, v20
	v_exp_f32_e32 v21, v21
	v_exp_f32_e32 v22, v22
	v_exp_f32_e32 v23, v23
	v_exp_f32_e32 v34, v25
	v_add_f32_e32 v24, 1.0, v24
	v_add_f32_e32 v18, 1.0, v18
	v_add_f32_e32 v19, 1.0, v19
	v_add_f32_e32 v20, 1.0, v20
	v_add_f32_e32 v21, 1.0, v21
	v_add_f32_e32 v22, 1.0, v22
	v_add_f32_e32 v23, 1.0, v23
	v_rcp_f32_e32 v25, v24
	v_add_f32_e32 v24, 1.0, v34
	v_rcp_f32_e32 v18, v18
	v_rcp_f32_e32 v19, v19
	v_rcp_f32_e32 v20, v20
	v_rcp_f32_e32 v21, v21
	v_rcp_f32_e32 v22, v22
	v_rcp_f32_e32 v23, v23
	v_rcp_f32_e32 v24, v24
	s_mov_b64 s[0:1], 0

; __device__ __forceinline__ unsigned cvt_pk_bf16(float lo, float hi) { unsigned r; asm volatile("v_cvt_pk_bf16_f32 %0, %1, %2" : "=v"(r) : "v"(lo), "v"(hi)); return r; }
; __device__ __forceinline__ float fast_sigmoid(float v) { return __builtin_amdgcn_rcpf(1.0f + __expf(-v)); }
;     __device__ __forceinline__ void operator()(const f32x4 (&acc)[2][2][4][2], const Unit& u, int wr, int wc, int fr, int fq) const {
;     ...
;             for (int m = 0; m < 4; ++m) { bf16_t* rowp = O + (size_t)(row0 + ai * HALF + m * 16) * ldc + col0;
; #pragma unroll
;                 for (int bj = 0; bj < 2; ++bj) { f32x4 v0 = acc[ai][bj][m][0] + bv[bj][0], v1 = acc[ai][bj][m][1] + bv[bj][1];
;                     if (mode == 1) {
; #pragma unroll
;                         for (int j = 0; j < 4; ++j) { v0[j] = v0[j] * fast_sigmoid(v0[j]); v1[j] = v1[j] * fast_sigmoid(v1[j]); } }
;                     else if (mode == 2) {
; #pragma unroll
;                         for (int j = 0; j < 4; ++j) { v0[j] = fast_sigmoid(v0[j]); v1[j] = fast_sigmoid(v1[j]); } }
;                     u32x4 w; w.x = cvt_pk_bf16(v0[0], v0[1]); w.y = cvt_pk_bf16(v0[2], v0[3]); w.z = cvt_pk_bf16(v1[0], v1[1]); w.w = cvt_pk_bf16(v1[2], v1[3]);
;                     *(u32x4*)(rowp + bj * HALF) = w; } }
.LBB0_261:
	v_add_u32_e32 v12, 0xb0, v140
	v_mov_b64_e32 v[10:11], s[8:9]
	v_mad_i64_i32 v[10:11], s[0:1], v12, s25, v[10:11]
	v_lshl_add_u64 v[10:11], v[156:157], 1, v[10:11]
	v_cvt_pk_bf16_f32 v12, v18, v20
	v_cvt_pk_bf16_f32 v13, v22, v25
	v_cvt_pk_bf16_f32 v14, v19, v21
	v_cvt_pk_bf16_f32 v15, v23, v24
	v_pk_add_f32 v[8:9], v[8:9], v[32:33]
	v_pk_add_f32 v[6:7], v[6:7], v[30:31]
	v_pk_add_f32 v[4:5], v[4:5], v[28:29]
	v_pk_add_f32 v[2:3], v[2:3], v[26:27]
	s_cmp_gt_i32 s20, 1
	s_mov_b64 s[0:1], -1
	global_store_dwordx4 v[10:11], v[12:15], off
	s_cbranch_scc0 .LBB0_263
	v_mul_f32_e32 v18, 0xbfb8aa3b, v9
	v_mul_f32_e32 v12, 0xbfb8aa3b, v6
	v_mul_f32_e32 v13, 0xbfb8aa3b, v2
	v_mul_f32_e32 v14, 0xbfb8aa3b, v7
	v_mul_f32_e32 v15, 0xbfb8aa3b, v3
	v_mul_f32_e32 v16, 0xbfb8aa3b, v8
	v_mul_f32_e32 v17, 0xbfb8aa3b, v4
	v_exp_f32_e32 v18, v18
	v_mul_f32_e32 v19, 0xbfb8aa3b, v5
	v_exp_f32_e32 v12, v12
	v_exp_f32_e32 v13, v13
	v_exp_f32_e32 v14, v14
	v_exp_f32_e32 v15, v15
	v_exp_f32_e32 v16, v16
	v_exp_f32_e32 v17, v17
	v_exp_f32_e32 v20, v19
	v_add_f32_e32 v18, 1.0, v18
	v_add_f32_e32 v12, 1.0, v12
	v_add_f32_e32 v13, 1.0, v13
	v_add_f32_e32 v14, 1.0, v14
	v_add_f32_e32 v15, 1.0, v15
	v_add_f32_e32 v16, 1.0, v16
	v_add_f32_e32 v17, 1.0, v17
	v_rcp_f32_e32 v19, v18
	v_add_f32_e32 v18, 1.0, v20
	v_rcp_f32_e32 v12, v12
	v_rcp_f32_e32 v13, v13
	v_rcp_f32_e32 v14, v14
	v_rcp_f32_e32 v15, v15
	v_rcp_f32_e32 v16, v16
	v_rcp_f32_e32 v17, v17
	v_rcp_f32_e32 v18, v18
	s_mov_b64 s[0:1], 0

; __device__ __forceinline__ unsigned cvt_pk_bf16(float lo, float hi) { unsigned r; asm volatile("v_cvt_pk_bf16_f32 %0, %1, %2" : "=v"(r) : "v"(lo), "v"(hi)); return r; }
; #define PG8_BAR __builtin_amdgcn_s_barrier()
;     __device__ __forceinline__ void operator()(const f32x4 (&acc)[2][2][4][2], const Unit& u, int wr, int wc, int fr, int fq) const {
;     ...
;                     u32x4 w; w.x = cvt_pk_bf16(v0[0], v0[1]); w.y = cvt_pk_bf16(v0[2], v0[3]); w.z = cvt_pk_bf16(v1[0], v1[1]); w.w = cvt_pk_bf16(v1[2], v1[3]);
;                     *(u32x4*)(rowp + bj * HALF) = w; } }
; template <class Epi, class Sched, bool ALIGN_EPI = false, bool SP2 = false>
; __device__ __forceinline__ void gemm_phase(PG8_LAS unsigned char* lds, const Gemm g, const Sched& S, const Epi& E) {
;     ...
;         if constexpr (!Epi::AFTER_DRAIN) { E(acc, cur, wr, wc, fr, fq); S.done(cur); }
;         if (!has_next) break;
; #pragma unroll
;         for (int a = 0; a < 2; ++a)
; #pragma unroll
;             for (int b = 0; b < 2; ++b)
; #pragma unroll
;                 for (int m = 0; m < 4; ++m)
; #pragma unroll
;                     for (int n = 0; n < 2; ++n) acc[a][b][m][n] = (f32x4){0.f, 0.f, 0.f, 0.f};
;         cur = nxt; cA = nA; cB = nB; ++ui;
;         if constexpr (ALIGN_EPI) { if (wr == 1) PG8_BAR; }
.LBB0_267:
	s_andn2_b64 vcc, exec, s[38:39]
	s_mov_b64 s[0:1], -1
	v_cvt_pk_bf16_f32 v2, v12, v14
	v_cvt_pk_bf16_f32 v3, v16, v19
	v_cvt_pk_bf16_f32 v4, v13, v15
	v_cvt_pk_bf16_f32 v5, v17, v18
	global_store_dwordx4 v[10:11], v[2:5], off offset:256
	s_cbranch_vccnz .LBB0_156
	s_andn2_b64 vcc, exec, s[10:11]
	s_cbranch_vccnz .LBB0_155
	s_barrier
	s_branch .LBB0_155

; #define LAS __attribute__((address_space(3)))
; __device__ __forceinline__ int wave_id_l() { int t = threadIdx.x; asm volatile("" : "+v"(t)); return t >> 6; }
; __device__ __forceinline__ void convert_range(LAS unsigned char* lds, const Params& p, const int lo, const int hi, const int gw, const int NGW) {
;     int tid_ = threadIdx.x; asm volatile("" : "+v"(tid_)); const int lane = tid_ & 63, wave = tid_ >> 6;
;     LAS float* scr = (LAS float*)(lds + wave * 16384);
;     unsigned char* ws = p.ws; asm volatile("" : "+s"(ws));
;     for (int it = lo + gw; it < hi; it += NGW) {
;         int r = it;
;         if (r < 2 * I_IN) { const int l = r / I_IN; r -= l * I_IN; p0_transpose_item(p.in[5] + (size_t)l * DM * NC, DM, NC, (bf16*)(ws + WS_WIN + l * SZ_WIN), scr, r, lane); continue; } r -= 2 * I_IN;
; __global__ void __launch_bounds__(NTHR, 2) hybrid_fwd(Params p) {
;     ...
;             if (gridDim.x == 256 && blockIdx.x >= 160) {
;                 const int gw = ((int)blockIdx.x - 160) * NWAVES + wave_id_l(), NGW = ((int)gridDim.x - 160) * NWAVES;
;                 convert_range(lds, p, IT_PA + l * I_PA, IT_PA + (l + 1) * I_PA, gw, NGW); convert_range(lds, p, IT_PB + l * I_PB, IT_PB + (l + 1) * I_PB, gw, NGW);
;                 convert_range(lds, p, IT_OUT + l * I_OUT, IT_OUT + (l + 1) * I_OUT, gw, NGW);
;                 if (l == 0) convert_range(lds, p, IT_IN + I_IN, IT_IN + I_IN + W1_EARLY, gw, NGW); }
.LBB0_271:
	v_readlane_b32 s0, v251, 55
	v_readlane_b32 s1, v251, 56
	s_andn2_b64 vcc, exec, s[0:1]
	s_cbranch_vccnz .LBB0_310
	v_mov_b32_e32 v0, v193
	v_readlane_b32 s0, v251, 57
	v_ashrrev_i32_e32 v0, 6, v0
	s_add_i32 s3, s56, 1
	s_waitcnt vmcnt(1)
	v_add_u32_e32 v3, s0, v0
	s_lshl_b32 s0, s3, 10
	v_readlane_b32 s12, v251, 1
	v_lshl_add_u32 v2, s56, 10, v3
	s_or_b32 s2, s0, 0x5000
	v_readlane_b32 s16, v251, 5
	v_readlane_b32 s17, v251, 6
	v_add_u32_e32 v5, 0x5000, v2
	v_mov_b32_e32 v0, v193
	v_readlane_b32 s14, v251, 3
	v_readlane_b32 s15, v251, 4
	s_mov_b64 s[0:1], s[16:17]
	v_cmp_gt_i32_e32 vcc, s2, v5
	v_readlane_b32 s13, v251, 2
	v_readlane_b32 s18, v251, 7
	v_readlane_b32 s19, v251, 8
	s_and_saveexec_b64 s[10:11], vcc
	s_mov_b32 s5, 0x66666667
	s_mov_b32 s14, 0x40000
	s_mov_b32 s15, 0x10000
	s_cbranch_execz .LBB0_279
	v_lshlrev_b32_e32 v2, 8, v0
	v_and_b32_e32 v2, 0xffffc000, v2
	v_add_u32_e32 v6, 0, v2
	v_bfe_u32 v12, v0, 5, 1
	v_and_b32_e32 v2, 31, v0
	v_bfe_u32 v13, v0, 3, 3
	v_lshlrev_b32_e32 v0, 3, v0
	v_and_b32_e32 v4, 56, v0
	v_lshl_add_u32 v7, v2, 2, v6
	v_mul_u32_u24_e32 v8, 0x84, v12
	v_mul_u32_u24_e32 v0, 0x84, v4
	v_lshlrev_b32_e32 v9, 2, v13
	s_add_u32 s18, s0, 0x5000000
	v_add3_u32 v14, v6, v0, v9
	v_or_b32_e32 v15, 8, v13
	v_or_b32_e32 v16, 16, v13
	v_or_b32_e32 v17, 24, v13
	s_addc_u32 s19, s1, 0
	v_lshlrev_b32_e32 v18, 5, v5
	s_mov_b64 s[38:39], 0
	v_add_u32_e32 v19, v7, v8
	s_branch .LBB0_275

;     ...
;     float tv_[32];
; #pragma unroll
;     for (int i = 0; i < 32; ++i) tv_[i] = W[(size_t)(k0 + 2 * i + (lane >> 5)) * N + n0 + (lane & 31)];
; __device__ __forceinline__ void convert_range(LAS unsigned char* lds, const Params& p, const int lo, const int hi, const int gw, const int NGW) {
;     ...
;     for (int it = lo + gw; it < hi; it += NGW) {
;         int r = it;
;         if (r < 2 * I_IN) { const int l = r / I_IN; r -= l * I_IN; p0_transpose_item(p.in[5] + (size_t)l * DM * NC, DM, NC, (bf16*)(ws + WS_WIN + l * SZ_WIN), scr, r, lane); continue; } r -= 2 * I_IN;
;         if (r < 2 * I_PA) { const int l = r / I_PA; r -= l * I_PA; p0_transpose_item(p.in[16] + (size_t)l * PW * DM, PW, DM, (bf16*)(ws + WS_WCAT + l * SZ_WCAT), scr, r, lane, KCAT, 0); continue; } r -= 2 * I_PA;
;         if (r < 2 * I_PB) { const int l = r / I_PB; r -= l * I_PB; p0_transpose_item(p.in[17] + (size_t)l * LW * DM, LW, DM, (bf16*)(ws + WS_WCAT + l * SZ_WCAT), scr, r, lane, KCAT, PW); continue; } r -= 2 * I_PB;
.LBB0_275:
	s_movk_i32 s6, 0x4fff
	v_cmp_lt_i32_e32 vcc, s6, v5
	v_lshlrev_b32_e32 v0, 2, v2
	s_waitcnt lgkmcnt(0)
	v_add_u32_e32 v26, 0x400, v19
	v_add_u32_e32 v25, 0x800, v19
	v_add_u32_e32 v24, 0xc00, v19
	v_add_u32_e32 v23, 0x1000, v19
	v_add_u32_e32 v22, 0x1400, v19
	v_add_u32_e32 v21, 0x1800, v19
	v_add_u32_e32 v9, 0x1c00, v19
	v_lshlrev_b32_e32 v8, 1, v4
	s_and_saveexec_b64 s[6:7], vcc
	s_xor_b64 s[40:41], exec, s[6:7]
	s_cbranch_execz .LBB0_277
	v_add_u32_e32 v6, 0xffffb000, v5
	v_lshrrev_b32_e32 v6, 10, v6
	v_mov_b32_e32 v7, v1
	v_readlane_b32 s44, v251, 9
	v_lshlrev_b64 v[10:11], 23, v[6:7]
	v_readlane_b32 s45, v251, 10
	v_mov_b64_e32 v[28:29], s[18:19]
	s_mov_b32 s6, 0xc00000
	v_and_b32_e32 v20, 0x7e0, v18
	v_lshl_add_u64 v[10:11], s[44:45], 0, v[10:11]
	v_mad_u64_u32 v[6:7], s[6:7], v6, s6, v[28:29]
	v_and_b32_e32 v27, 0x3c0, v5
	v_lshlrev_b32_e32 v28, 2, v20
	v_mov_b32_e32 v29, v1
	v_or_b32_e32 v30, v27, v12
	v_lshl_add_u64 v[10:11], v[10:11], 0, v[28:29]
	v_lshl_add_u64 v[10:11], v[10:11], 0, v[0:1]
	v_lshlrev_b32_e32 v0, 13, v30
	v_lshl_add_u64 v[10:11], v[10:11], 0, v[0:1]
	v_add_co_u32_e32 v28, vcc, s22, v10
	s_mov_b32 s6, 0x8000
	s_nop 0
	v_addc_co_u32_e32 v29, vcc, 0, v11, vcc
	global_load_dword v0, v[10:11], off
	global_load_dword v30, v[28:29], off
	v_add_co_u32_e32 v28, vcc, s6, v10
	s_mov_b32 s6, 0xc000
	s_nop 0
	v_addc_co_u32_e32 v29, vcc, 0, v11, vcc
	global_load_dword v31, v[28:29], off
	v_add_co_u32_e32 v28, vcc, s6, v10
	s_mov_b32 s6, 0x14000
	s_nop 0
	v_addc_co_u32_e32 v29, vcc, 0, v11, vcc
	global_load_dword v32, v[28:29], off
	v_add_co_u32_e32 v28, vcc, s15, v10
	v_readlane_b32 s46, v251, 11
	s_nop 0
	v_addc_co_u32_e32 v29, vcc, 0, v11, vcc
	global_load_dword v33, v[28:29], off
	v_add_co_u32_e32 v28, vcc, s6, v10
	s_mov_b32 s6, 0x18000
	s_nop 0
	v_addc_co_u32_e32 v29, vcc, 0, v11, vcc
	global_load_dword v34, v[28:29], off
	v_add_co_u32_e32 v28, vcc, s6, v10
	s_mov_b32 s6, 0x1c000
	s_nop 0
	v_addc_co_u32_e32 v29, vcc, 0, v11, vcc
	global_load_dword v35, v[28:29], off
	v_add_co_u32_e32 v28, vcc, s6, v10
	s_mov_b32 s6, 0x20000
	s_nop 0
	v_addc_co_u32_e32 v29, vcc, 0, v11, vcc
	global_load_dword v36, v[28:29], off
	v_add_co_u32_e32 v28, vcc, s6, v10
	s_mov_b32 s6, 0x24000
	s_nop 0
	v_addc_co_u32_e32 v29, vcc, 0, v11, vcc
	global_load_dword v37, v[28:29], off
	v_add_co_u32_e32 v28, vcc, s6, v10
	s_mov_b32 s6, 0x28000
	s_nop 0
	v_addc_co_u32_e32 v29, vcc, 0, v11, vcc
	global_load_dword v38, v[28:29], off
	v_add_co_u32_e32 v28, vcc, s6, v10
	s_mov_b32 s6, 0x2c000
	s_nop 0
	v_addc_co_u32_e32 v29, vcc, 0, v11, vcc
	global_load_dword v39, v[28:29], off
	v_add_co_u32_e32 v28, vcc, s6, v10
	s_mov_b32 s6, 0x30000
	s_nop 0
	v_addc_co_u32_e32 v29, vcc, 0, v11, vcc
	global_load_dword v40, v[28:29], off
	v_add_co_u32_e32 v28, vcc, s6, v10
	s_mov_b32 s6, 0x34000
	s_nop 0
	v_addc_co_u32_e32 v29, vcc, 0, v11, vcc
	global_load_dword v41, v[28:29], off
	v_add_co_u32_e32 v28, vcc, s6, v10
	s_mov_b32 s6, 0x38000
	s_nop 0
	v_addc_co_u32_e32 v29, vcc, 0, v11, vcc
	global_load_dword v42, v[28:29], off
	v_add_co_u32_e32 v28, vcc, s6, v10
	s_mov_b32 s6, 0x3c000
	s_nop 0
	v_addc_co_u32_e32 v29, vcc, 0, v11, vcc
	global_load_dword v43, v[28:29], off
	v_add_co_u32_e32 v28, vcc, s6, v10
	s_mov_b32 s6, 0x44000
	s_nop 0
	v_addc_co_u32_e32 v29, vcc, 0, v11, vcc
	global_load_dword v44, v[28:29], off
	v_add_co_u32_e32 v28, vcc, s14, v10
	v_readlane_b32 s47, v251, 12
	s_nop 0
	v_addc_co_u32_e32 v29, vcc, 0, v11, vcc
	global_load_dword v45, v[28:29], off
	v_add_co_u32_e32 v28, vcc, s6, v10
	s_mov_b32 s6, 0x48000
	s_nop 0
	v_addc_co_u32_e32 v29, vcc, 0, v11, vcc
	global_load_dword v46, v[28:29], off
	v_add_co_u32_e32 v28, vcc, s6, v10
	s_mov_b32 s6, 0x4c000
	s_nop 0
	v_addc_co_u32_e32 v29, vcc, 0, v11, vcc
	global_load_dword v47, v[28:29], off
	v_add_co_u32_e32 v28, vcc, s6, v10
	s_mov_b32 s6, 0x50000
	s_nop 0
	v_addc_co_u32_e32 v29, vcc, 0, v11, vcc
	global_load_dword v48, v[28:29], off
	v_add_co_u32_e32 v28, vcc, s6, v10
	s_mov_b32 s6, 0x54000
	s_nop 0
	v_addc_co_u32_e32 v29, vcc, 0, v11, vcc
	global_load_dword v49, v[28:29], off
	v_add_co_u32_e32 v28, vcc, s6, v10
	s_mov_b32 s6, 0x58000
	s_nop 0
	v_addc_co_u32_e32 v29, vcc, 0, v11, vcc
	global_load_dword v50, v[28:29], off
	v_add_co_u32_e32 v28, vcc, s6, v10
	s_mov_b32 s6, 0x5c000
	s_nop 0
	v_addc_co_u32_e32 v29, vcc, 0, v11, vcc
	global_load_dword v51, v[28:29], off
	v_add_co_u32_e32 v28, vcc, s6, v10
	s_mov_b32 s6, 0x60000
	s_nop 0
	v_addc_co_u32_e32 v29, vcc, 0, v11, vcc
	global_load_dword v52, v[28:29], off
	v_add_co_u32_e32 v28, vcc, s6, v10
	s_mov_b32 s6, 0x64000
	s_nop 0
	v_addc_co_u32_e32 v29, vcc, 0, v11, vcc
	global_load_dword v53, v[28:29], off
	v_add_co_u32_e32 v28, vcc, s6, v10
	s_mov_b32 s6, 0x68000
	s_nop 0
	v_addc_co_u32_e32 v29, vcc, 0, v11, vcc
	global_load_dword v54, v[28:29], off
	v_add_co_u32_e32 v28, vcc, s6, v10
	s_mov_b32 s6, 0x6c000
	s_nop 0
	v_addc_co_u32_e32 v29, vcc, 0, v11, vcc
	global_load_dword v55, v[28:29], off
	v_add_co_u32_e32 v28, vcc, s6, v10
	s_mov_b32 s6, 0x70000
	s_nop 0
	v_addc_co_u32_e32 v29, vcc, 0, v11, vcc
	global_load_dword v56, v[28:29], off
	v_add_co_u32_e32 v28, vcc, s6, v10
	s_mov_b32 s6, 0x74000
	s_nop 0
	v_addc_co_u32_e32 v29, vcc, 0, v11, vcc
	global_load_dword v57, v[28:29], off
	v_add_co_u32_e32 v28, vcc, s6, v10
	s_mov_b32 s6, 0x78000
	s_nop 0
	v_addc_co_u32_e32 v29, vcc, 0, v11, vcc
	global_load_dword v58, v[28:29], off
	v_add_co_u32_e32 v28, vcc, s6, v10
	s_mov_b32 s6, 0x7c000
	s_nop 0
	v_addc_co_u32_e32 v29, vcc, 0, v11, vcc
	v_add_co_u32_e32 v10, vcc, s6, v10
	global_load_dword v28, v[28:29], off
	s_nop 0
	v_addc_co_u32_e32 v11, vcc, 0, v11, vcc
	global_load_dword v10, v[10:11], off
	s_waitcnt vmcnt(30)
; #define LAS __attribute__((address_space(3)))
; #define LDS_WAIT() asm volatile("s_waitcnt lgkmcnt(0)" ::: "memory")
; __device__ __forceinline__ unsigned pk2(float lo, float hi) { return f2bf(lo) | (f2bf(hi) << 16); }
;     ...
;     for (int i = 0; i < 32; ++i) tv_[i] = W[(size_t)(k0 + 2 * i + (lane >> 5)) * N + n0 + (lane & 31)];
; #pragma unroll
;     for (int i = 0; i < 32; ++i) scr[(2 * i + (lane >> 5)) * 33 + (lane & 31)] = tv_[i];
;     LDS_WAIT(); asm volatile("" ::: "memory");
;     const int c = lane & 7;
; #pragma unroll
;     for (int j = 0; j < 4; ++j) { const int n = (lane >> 3) + 8 * j; const LAS float* s = scr + (8 * c) * 33 + n;
;         v4u o; o.x = pk2(s[0 * 33], s[1 * 33]); o.y = pk2(s[2 * 33], s[3 * 33]); o.z = pk2(s[4 * 33], s[5 * 33]); o.w = pk2(s[6 * 33], s[7 * 33]);
;         *(v4u*)(WT + (size_t)(n0 + n) * ldw + koff + k0 + 8 * c) = o; }
;     LDS_WAIT(); asm volatile("" ::: "memory");
	ds_write2_b32 v19, v0, v30 offset1:66
	s_waitcnt vmcnt(28)
	ds_write2_b32 v19, v31, v32 offset0:132 offset1:198
	s_waitcnt vmcnt(26)
	ds_write2_b32 v26, v33, v34 offset0:8 offset1:74
	s_waitcnt vmcnt(24)
	ds_write2_b32 v26, v35, v36 offset0:140 offset1:206
	s_waitcnt vmcnt(22)
	ds_write2_b32 v25, v37, v38 offset0:16 offset1:82
	s_waitcnt vmcnt(20)
	ds_write2_b32 v25, v39, v40 offset0:148 offset1:214
	s_waitcnt vmcnt(18)
	ds_write2_b32 v24, v41, v42 offset0:24 offset1:90
	s_waitcnt vmcnt(16)
	ds_write2_b32 v24, v43, v44 offset0:156 offset1:222
	s_waitcnt vmcnt(14)
	ds_write2_b32 v23, v45, v46 offset0:32 offset1:98
	s_waitcnt vmcnt(12)
	ds_write2_b32 v23, v47, v48 offset0:164 offset1:230
	s_waitcnt vmcnt(10)
	ds_write2_b32 v22, v49, v50 offset0:40 offset1:106
	s_waitcnt vmcnt(8)
	ds_write2_b32 v22, v51, v52 offset0:172 offset1:238
	s_waitcnt vmcnt(6)
	ds_write2_b32 v21, v53, v54 offset0:48 offset1:114
	s_waitcnt vmcnt(4)
	ds_write2_b32 v21, v55, v56 offset0:180 offset1:246
	s_waitcnt vmcnt(2)
	ds_write2_b32 v9, v57, v58 offset0:56 offset1:122
	s_waitcnt vmcnt(0)
	ds_write2_b32 v9, v28, v10 offset0:188 offset1:254
	s_waitcnt lgkmcnt(0)
	v_lshlrev_b32_e32 v0, 1, v27
	v_lshl_add_u64 v[6:7], v[6:7], 0, v[0:1]
	v_mov_b32_e32 v9, v1
	v_lshl_add_u64 v[6:7], v[6:7], 0, v[8:9]
	ds_read_b32 v0, v14
	ds_read_b32 v8, v14 offset:132
	v_readlane_b32 s48, v251, 13
	v_readlane_b32 s49, v251, 14
	v_readlane_b32 s50, v251, 15
	s_waitcnt lgkmcnt(0)
	v_bfe_u32 v9, v0, 16, 1
	v_add3_u32 v0, v0, v9, s26
	v_bfe_u32 v9, v8, 16, 1
	v_lshrrev_b32_e32 v0, 16, v0
	v_add3_u32 v8, v8, v9, s26
	v_and_or_b32 v8, v8, s24, v0
	ds_read_b32 v0, v14 offset:264
	ds_read_b32 v9, v14 offset:396
	v_readlane_b32 s51, v251, 16
	s_waitcnt lgkmcnt(1)
	v_bfe_u32 v10, v0, 16, 1
	v_add3_u32 v0, v0, v10, s26
	s_waitcnt lgkmcnt(0)
	v_bfe_u32 v10, v9, 16, 1
	v_lshrrev_b32_e32 v0, 16, v0
	v_add3_u32 v9, v9, v10, s26
	v_and_or_b32 v9, v9, s24, v0
	ds_read_b32 v0, v14 offset:528
	ds_read_b32 v10, v14 offset:660
	s_waitcnt lgkmcnt(1)
	v_bfe_u32 v11, v0, 16, 1
	v_add3_u32 v0, v0, v11, s26
	s_waitcnt lgkmcnt(0)
	v_bfe_u32 v11, v10, 16, 1
	v_lshrrev_b32_e32 v0, 16, v0
	v_add3_u32 v10, v10, v11, s26
	v_and_or_b32 v10, v10, s24, v0
	ds_read_b32 v0, v14 offset:792
	ds_read_b32 v11, v14 offset:924
	s_waitcnt lgkmcnt(1)
	v_bfe_u32 v21, v0, 16, 1
	v_add3_u32 v0, v0, v21, s26
	s_waitcnt lgkmcnt(0)
	v_bfe_u32 v21, v11, 16, 1
	v_lshrrev_b32_e32 v0, 16, v0
	v_add3_u32 v11, v11, v21, s26
	v_and_or_b32 v11, v11, s24, v0
	v_or_b32_e32 v0, v20, v13
	v_mul_u32_u24_e32 v0, 0xc00, v0
	v_lshlrev_b32_e32 v0, 1, v0
	v_lshl_add_u64 v[22:23], v[6:7], 0, v[0:1]
	global_store_dwordx4 v[22:23], v[8:11], off
	ds_read_b32 v0, v14 offset:32
	ds_read_b32 v8, v14 offset:164
	s_waitcnt lgkmcnt(0)
	v_bfe_u32 v9, v0, 16, 1
	v_add3_u32 v0, v0, v9, s26
	v_bfe_u32 v9, v8, 16, 1
	v_lshrrev_b32_e32 v0, 16, v0
	v_add3_u32 v8, v8, v9, s26
	v_and_or_b32 v8, v8, s24, v0
	ds_read_b32 v0, v14 offset:296
	ds_read_b32 v9, v14 offset:428
	s_waitcnt lgkmcnt(0)
	v_bfe_u32 v10, v0, 16, 1
	v_add3_u32 v0, v0, v10, s26
	v_bfe_u32 v10, v9, 16, 1
	v_lshrrev_b32_e32 v0, 16, v0
	v_add3_u32 v9, v9, v10, s26
	v_and_or_b32 v9, v9, s24, v0
	ds_read_b32 v0, v14 offset:560
	ds_read_b32 v10, v14 offset:692
	s_waitcnt lgkmcnt(0)
	v_bfe_u32 v11, v0, 16, 1
	v_add3_u32 v0, v0, v11, s26
	v_bfe_u32 v11, v10, 16, 1
	v_lshrrev_b32_e32 v0, 16, v0
	v_add3_u32 v10, v10, v11, s26
	v_and_or_b32 v10, v10, s24, v0
	ds_read_b32 v0, v14 offset:824
	ds_read_b32 v11, v14 offset:956
	s_waitcnt lgkmcnt(0)
	v_bfe_u32 v21, v0, 16, 1
	v_add3_u32 v0, v0, v21, s26
	v_bfe_u32 v21, v11, 16, 1
	v_lshrrev_b32_e32 v0, 16, v0
	v_add3_u32 v11, v11, v21, s26
	v_and_or_b32 v11, v11, s24, v0
	v_or_b32_e32 v0, v20, v15
	v_mul_u32_u24_e32 v0, 0xc00, v0
	v_lshlrev_b32_e32 v0, 1, v0
	v_lshl_add_u64 v[22:23], v[6:7], 0, v[0:1]
	global_store_dwordx4 v[22:23], v[8:11], off
	ds_read_b32 v0, v14 offset:64
	ds_read_b32 v8, v14 offset:196
	s_waitcnt lgkmcnt(0)
	v_bfe_u32 v9, v0, 16, 1
	v_add3_u32 v0, v0, v9, s26
	v_bfe_u32 v9, v8, 16, 1
	v_lshrrev_b32_e32 v0, 16, v0
	v_add3_u32 v8, v8, v9, s26
	v_and_or_b32 v8, v8, s24, v0
	ds_read_b32 v0, v14 offset:328
	ds_read_b32 v9, v14 offset:460
	s_waitcnt lgkmcnt(0)
	v_bfe_u32 v10, v0, 16, 1
	v_add3_u32 v0, v0, v10, s26
	v_bfe_u32 v10, v9, 16, 1
	v_lshrrev_b32_e32 v0, 16, v0
	v_add3_u32 v9, v9, v10, s26
	v_and_or_b32 v9, v9, s24, v0
	ds_read_b32 v0, v14 offset:592
	ds_read_b32 v10, v14 offset:724
	s_waitcnt lgkmcnt(0)
	v_bfe_u32 v11, v0, 16, 1
	v_add3_u32 v0, v0, v11, s26
	v_bfe_u32 v11, v10, 16, 1
	v_lshrrev_b32_e32 v0, 16, v0
	v_add3_u32 v10, v10, v11, s26
	v_and_or_b32 v10, v10, s24, v0
	ds_read_b32 v0, v14 offset:856
	ds_read_b32 v11, v14 offset:988
	s_waitcnt lgkmcnt(0)
	v_bfe_u32 v21, v0, 16, 1
	v_add3_u32 v0, v0, v21, s26
	v_bfe_u32 v21, v11, 16, 1
	v_lshrrev_b32_e32 v0, 16, v0
	v_add3_u32 v11, v11, v21, s26
	v_and_or_b32 v11, v11, s24, v0
	v_or_b32_e32 v0, v20, v16
	v_mul_u32_u24_e32 v0, 0xc00, v0
	v_lshlrev_b32_e32 v0, 1, v0
	v_lshl_add_u64 v[22:23], v[6:7], 0, v[0:1]
	global_store_dwordx4 v[22:23], v[8:11], off
	ds_read_b32 v0, v14 offset:96
	ds_read_b32 v8, v14 offset:228
	s_waitcnt lgkmcnt(0)
	v_bfe_u32 v9, v0, 16, 1
	v_add3_u32 v0, v0, v9, s26
	v_bfe_u32 v9, v8, 16, 1
	v_lshrrev_b32_e32 v0, 16, v0
	v_add3_u32 v8, v8, v9, s26
	v_and_or_b32 v8, v8, s24, v0
	ds_read_b32 v0, v14 offset:360
	ds_read_b32 v9, v14 offset:492
	s_waitcnt lgkmcnt(0)
	v_bfe_u32 v10, v0, 16, 1
	v_add3_u32 v0, v0, v10, s26
	v_bfe_u32 v10, v9, 16, 1
	v_lshrrev_b32_e32 v0, 16, v0
	v_add3_u32 v9, v9, v10, s26
	v_and_or_b32 v9, v9, s24, v0
	ds_read_b32 v0, v14 offset:624
	ds_read_b32 v10, v14 offset:756
	s_waitcnt lgkmcnt(0)
	v_bfe_u32 v11, v0, 16, 1
	v_add3_u32 v0, v0, v11, s26
	v_bfe_u32 v11, v10, 16, 1
	v_lshrrev_b32_e32 v0, 16, v0
	v_add3_u32 v10, v10, v11, s26
	v_and_or_b32 v10, v10, s24, v0
	ds_read_b32 v0, v14 offset:888
	ds_read_b32 v11, v14 offset:1020
	s_waitcnt lgkmcnt(0)
	v_bfe_u32 v21, v0, 16, 1
	v_add3_u32 v0, v0, v21, s26
	v_bfe_u32 v21, v11, 16, 1
	v_lshrrev_b32_e32 v0, 16, v0
	v_add3_u32 v11, v11, v21, s26
	v_and_or_b32 v11, v11, s24, v0
	v_or_b32_e32 v0, v20, v17
	v_mul_u32_u24_e32 v0, 0xc00, v0
	v_lshlrev_b32_e32 v0, 1, v0
	v_lshl_add_u64 v[6:7], v[6:7], 0, v[0:1]
	global_store_dwordx4 v[6:7], v[8:11], off
	s_waitcnt lgkmcnt(0)
;     ...
;     float tv_[32];
; #pragma unroll
;     for (int i = 0; i < 32; ++i) tv_[i] = W[(size_t)(k0 + 2 * i + (lane >> 5)) * N + n0 + (lane & 31)];
; #pragma unroll
;     for (int i = 0; i < 32; ++i) scr[(2 * i + (lane >> 5)) * 33 + (lane & 31)] = tv_[i];
; __device__ __forceinline__ void convert_range(LAS unsigned char* lds, const Params& p, const int lo, const int hi, const int gw, const int NGW) {
;     ...
;     for (int it = lo + gw; it < hi; it += NGW) {
;         int r = it;
;         if (r < 2 * I_IN) { const int l = r / I_IN; r -= l * I_IN; p0_transpose_item(p.in[5] + (size_t)l * DM * NC, DM, NC, (bf16*)(ws + WS_WIN + l * SZ_WIN), scr, r, lane); continue; } r -= 2 * I_IN;
.LBB0_277:
	s_andn2_saveexec_b64 s[40:41], s[40:41]
	s_cbranch_execz .LBB0_274
	v_mul_hi_i32 v6, v5, s5
	v_lshrrev_b32_e32 v7, 31, v6
	v_ashrrev_i32_e32 v6, 12, v6
	v_add_u32_e32 v11, v6, v7
	v_readlane_b32 s60, v251, 21
	v_mul_i32_i24_e32 v6, 0xffffd800, v11
	v_readlane_b32 s70, v251, 31
	v_readlane_b32 s71, v251, 32
	v_add_u32_e32 v10, v6, v5
	s_mov_b32 s6, 0x5000000
	v_mov_b64_e32 v[6:7], s[70:71]
	v_mad_i64_i32 v[28:29], s[6:7], v11, s6, v[6:7]
	v_mul_hi_i32 v6, v10, s5
	v_lshrrev_b32_e32 v7, 31, v6
	v_ashrrev_i32_e32 v6, 7, v6
	v_add_u32_e32 v6, v6, v7
	v_mul_i32_i24_e32 v7, 0x140, v6
	v_sub_u32_e32 v7, v10, v7
	v_lshlrev_b32_e32 v10, 6, v6
	v_lshlrev_b32_e32 v6, 5, v7
	v_ashrrev_i32_e32 v7, 31, v6
	v_lshl_add_u64 v[28:29], v[6:7], 2, v[28:29]
	v_or_b32_e32 v20, v10, v12
	v_lshl_add_u64 v[28:29], v[28:29], 0, v[0:1]
	v_mad_i64_i32 v[30:31], s[6:7], v20, s23, v[28:29]
	v_or_b32_e32 v7, 2, v20
	global_load_dword v0, v[30:31], off
	v_mad_i64_i32 v[30:31], s[6:7], v7, s23, v[28:29]
	v_or_b32_e32 v27, 4, v20
	global_load_dword v7, v[30:31], off
	v_mad_i64_i32 v[30:31], s[6:7], v27, s23, v[28:29]
	global_load_dword v27, v[30:31], off
	v_or_b32_e32 v30, 6, v20
	v_mad_i64_i32 v[30:31], s[6:7], v30, s23, v[28:29]
	global_load_dword v32, v[30:31], off
	v_or_b32_e32 v30, 8, v20
	v_mad_i64_i32 v[30:31], s[6:7], v30, s23, v[28:29]
	global_load_dword v33, v[30:31], off
	v_or_b32_e32 v30, 10, v20
	v_mad_i64_i32 v[30:31], s[6:7], v30, s23, v[28:29]
	global_load_dword v34, v[30:31], off
	v_or_b32_e32 v30, 12, v20
	v_mad_i64_i32 v[30:31], s[6:7], v30, s23, v[28:29]
	global_load_dword v35, v[30:31], off
	v_or_b32_e32 v30, 14, v20
	v_mad_i64_i32 v[30:31], s[6:7], v30, s23, v[28:29]
	global_load_dword v36, v[30:31], off
	v_or_b32_e32 v30, 16, v20
	v_mad_i64_i32 v[30:31], s[6:7], v30, s23, v[28:29]
	global_load_dword v37, v[30:31], off
	v_or_b32_e32 v30, 18, v20
	v_mad_i64_i32 v[30:31], s[6:7], v30, s23, v[28:29]
	global_load_dword v38, v[30:31], off
	v_or_b32_e32 v30, 20, v20
	v_mad_i64_i32 v[30:31], s[6:7], v30, s23, v[28:29]
	global_load_dword v39, v[30:31], off
	v_or_b32_e32 v30, 22, v20
	v_mad_i64_i32 v[30:31], s[6:7], v30, s23, v[28:29]
	global_load_dword v40, v[30:31], off
	v_or_b32_e32 v30, 24, v20
	v_mad_i64_i32 v[30:31], s[6:7], v30, s23, v[28:29]
	global_load_dword v41, v[30:31], off
	v_or_b32_e32 v30, 26, v20
	v_mad_i64_i32 v[30:31], s[6:7], v30, s23, v[28:29]
	global_load_dword v42, v[30:31], off
	v_or_b32_e32 v30, 28, v20
	v_mad_i64_i32 v[30:31], s[6:7], v30, s23, v[28:29]
	global_load_dword v43, v[30:31], off
	v_or_b32_e32 v30, 30, v20
	v_mad_i64_i32 v[30:31], s[6:7], v30, s23, v[28:29]
	global_load_dword v44, v[30:31], off
	v_or_b32_e32 v30, 32, v20
	v_mad_i64_i32 v[30:31], s[6:7], v30, s23, v[28:29]
	global_load_dword v45, v[30:31], off
	v_or_b32_e32 v30, 34, v20
	v_mad_i64_i32 v[30:31], s[6:7], v30, s23, v[28:29]
	global_load_dword v46, v[30:31], off
	v_or_b32_e32 v30, 36, v20
	v_mad_i64_i32 v[30:31], s[6:7], v30, s23, v[28:29]
	global_load_dword v47, v[30:31], off
	v_or_b32_e32 v30, 38, v20
	v_mad_i64_i32 v[30:31], s[6:7], v30, s23, v[28:29]
	global_load_dword v48, v[30:31], off
	v_or_b32_e32 v30, 40, v20
	v_mad_i64_i32 v[30:31], s[6:7], v30, s23, v[28:29]
	global_load_dword v49, v[30:31], off
	v_or_b32_e32 v30, 42, v20
	v_mad_i64_i32 v[30:31], s[6:7], v30, s23, v[28:29]
	global_load_dword v50, v[30:31], off
	v_or_b32_e32 v30, 44, v20
	v_mad_i64_i32 v[30:31], s[6:7], v30, s23, v[28:29]
	global_load_dword v51, v[30:31], off
	v_or_b32_e32 v30, 46, v20
	v_mad_i64_i32 v[30:31], s[6:7], v30, s23, v[28:29]
	global_load_dword v52, v[30:31], off
	v_or_b32_e32 v30, 48, v20
	v_mad_i64_i32 v[30:31], s[6:7], v30, s23, v[28:29]
	global_load_dword v53, v[30:31], off
	v_or_b32_e32 v30, 50, v20
	v_mad_i64_i32 v[30:31], s[6:7], v30, s23, v[28:29]
	global_load_dword v54, v[30:31], off
	v_or_b32_e32 v30, 52, v20
	v_mad_i64_i32 v[30:31], s[6:7], v30, s23, v[28:29]
	global_load_dword v55, v[30:31], off
	v_or_b32_e32 v30, 54, v20
	v_mad_i64_i32 v[30:31], s[6:7], v30, s23, v[28:29]
	global_load_dword v56, v[30:31], off
	v_or_b32_e32 v30, 56, v20
	v_mad_i64_i32 v[30:31], s[6:7], v30, s23, v[28:29]
	global_load_dword v57, v[30:31], off
	v_or_b32_e32 v30, 58, v20
	v_mad_i64_i32 v[30:31], s[6:7], v30, s23, v[28:29]
	global_load_dword v58, v[30:31], off
	v_or_b32_e32 v30, 60, v20
	v_or_b32_e32 v20, 62, v20
	v_mad_i64_i32 v[30:31], s[6:7], v30, s23, v[28:29]
	v_mad_i64_i32 v[28:29], s[6:7], v20, s23, v[28:29]
	global_load_dword v30, v[30:31], off
	s_mov_b32 s6, 0x2800000
	global_load_dword v20, v[28:29], off
	s_waitcnt vmcnt(30)
	ds_write2_b32 v19, v0, v7 offset1:66
	s_waitcnt vmcnt(28)
	ds_write2_b32 v19, v27, v32 offset0:132 offset1:198
	s_waitcnt vmcnt(26)
	ds_write2_b32 v26, v33, v34 offset0:8 offset1:74
	s_waitcnt vmcnt(24)
	ds_write2_b32 v26, v35, v36 offset0:140 offset1:206
	s_waitcnt vmcnt(22)
	ds_write2_b32 v25, v37, v38 offset0:16 offset1:82
	s_waitcnt vmcnt(20)
	ds_write2_b32 v25, v39, v40 offset0:148 offset1:214
	s_waitcnt vmcnt(18)
	ds_write2_b32 v24, v41, v42 offset0:24 offset1:90
	s_waitcnt vmcnt(16)
	ds_write2_b32 v24, v43, v44 offset0:156 offset1:222
	s_waitcnt vmcnt(14)
	ds_write2_b32 v23, v45, v46 offset0:32 offset1:98
	s_waitcnt vmcnt(12)
	ds_write2_b32 v23, v47, v48 offset0:164 offset1:230
	s_waitcnt vmcnt(10)
	ds_write2_b32 v22, v49, v50 offset0:40 offset1:106
	s_waitcnt vmcnt(8)
	ds_write2_b32 v22, v51, v52 offset0:172 offset1:238
	s_waitcnt vmcnt(6)
	ds_write2_b32 v21, v53, v54 offset0:48 offset1:114
	s_waitcnt vmcnt(4)
	ds_write2_b32 v21, v55, v56 offset0:180 offset1:246
	s_waitcnt vmcnt(2)
	ds_write2_b32 v9, v57, v58 offset0:56 offset1:122
	s_waitcnt vmcnt(0)
; #define LAS __attribute__((address_space(3)))
; #define LDS_WAIT() asm volatile("s_waitcnt lgkmcnt(0)" ::: "memory")
; __device__ __forceinline__ unsigned pk2(float lo, float hi) { return f2bf(lo) | (f2bf(hi) << 16); }
;     ...
;     for (int i = 0; i < 32; ++i) scr[(2 * i + (lane >> 5)) * 33 + (lane & 31)] = tv_[i];
;     LDS_WAIT(); asm volatile("" ::: "memory");
;     const int c = lane & 7;
; #pragma unroll
;     for (int j = 0; j < 4; ++j) { const int n = (lane >> 3) + 8 * j; const LAS float* s = scr + (8 * c) * 33 + n;
;         v4u o; o.x = pk2(s[0 * 33], s[1 * 33]); o.y = pk2(s[2 * 33], s[3 * 33]); o.z = pk2(s[4 * 33], s[5 * 33]); o.w = pk2(s[6 * 33], s[7 * 33]);
;         *(v4u*)(WT + (size_t)(n0 + n) * ldw + koff + k0 + 8 * c) = o; }
;     LDS_WAIT(); asm volatile("" ::: "memory");
	ds_write2_b32 v9, v30, v20 offset0:188 offset1:254
	s_waitcnt lgkmcnt(0)
	ds_read_b32 v0, v14
	ds_read_b32 v7, v14 offset:132
	v_mov_b64_e32 v[28:29], s[0:1]
	v_mad_i64_i32 v[28:29], s[6:7], v11, s6, v[28:29]
	v_ashrrev_i32_e32 v11, 31, v10
	v_lshl_add_u64 v[10:11], v[10:11], 1, v[28:29]
	v_mov_b32_e32 v9, v1
	v_lshl_add_u64 v[8:9], v[10:11], 0, v[8:9]
	s_waitcnt lgkmcnt(0)
	v_bfe_u32 v10, v0, 16, 1
	v_add3_u32 v0, v0, v10, s26
	v_bfe_u32 v11, v7, 16, 1
	v_lshrrev_b32_e32 v0, 16, v0
	ds_read_b32 v10, v14 offset:264
	v_add3_u32 v7, v7, v11, s26
	v_and_or_b32 v20, v7, s24, v0
	ds_read_b32 v0, v14 offset:396
	v_readlane_b32 s72, v251, 33
	s_waitcnt lgkmcnt(1)
	v_bfe_u32 v7, v10, 16, 1
	v_add3_u32 v7, v10, v7, s26
	v_lshrrev_b32_e32 v7, 16, v7
	s_waitcnt lgkmcnt(0)
	v_bfe_u32 v11, v0, 16, 1
	ds_read_b32 v10, v14 offset:528
	v_add3_u32 v0, v0, v11, s26
	v_and_or_b32 v21, v0, s24, v7
	ds_read_b32 v0, v14 offset:660
	v_readlane_b32 s73, v251, 34
	s_waitcnt lgkmcnt(1)
	v_bfe_u32 v7, v10, 16, 1
	v_add3_u32 v7, v10, v7, s26
	ds_read_b32 v10, v14 offset:792
	s_waitcnt lgkmcnt(1)
	v_bfe_u32 v11, v0, 16, 1
	v_add3_u32 v0, v0, v11, s26
	ds_read_b32 v11, v14 offset:924
	v_lshrrev_b32_e32 v7, 16, v7
	v_and_or_b32 v22, v0, s24, v7
	s_waitcnt lgkmcnt(1)
	v_bfe_u32 v0, v10, 16, 1
	v_add3_u32 v0, v10, v0, s26
	s_waitcnt lgkmcnt(0)
	v_bfe_u32 v7, v11, 16, 1
	v_or_b32_e32 v10, v6, v13
	v_add3_u32 v7, v11, v7, s26
	v_ashrrev_i32_e32 v11, 31, v10
	v_lshrrev_b32_e32 v0, 16, v0
	v_lshlrev_b64 v[10:11], 12, v[10:11]
	v_and_or_b32 v23, v7, s24, v0
	v_lshl_add_u64 v[10:11], v[8:9], 0, v[10:11]
	global_store_dwordx4 v[10:11], v[20:23], off
	ds_read_b32 v0, v14 offset:32
	ds_read_b32 v7, v14 offset:164
	v_readlane_b32 s72, v248, 24
	v_readlane_b32 s73, v248, 25
	v_readlane_b32 s61, v251, 22
	s_waitcnt lgkmcnt(0)
	v_bfe_u32 v10, v0, 16, 1
	v_add3_u32 v0, v0, v10, s26
	v_bfe_u32 v11, v7, 16, 1
	v_lshrrev_b32_e32 v0, 16, v0
	ds_read_b32 v10, v14 offset:296
	v_add3_u32 v7, v7, v11, s26
	v_and_or_b32 v20, v7, s24, v0
	ds_read_b32 v0, v14 offset:428
	v_readlane_b32 s62, v251, 23
	s_waitcnt lgkmcnt(0)
	v_bfe_u32 v7, v10, 16, 1
	v_add3_u32 v7, v10, v7, s26
	v_lshrrev_b32_e32 v7, 16, v7
	v_bfe_u32 v11, v0, 16, 1
	ds_read_b32 v10, v14 offset:560
	v_add3_u32 v0, v0, v11, s26
	v_and_or_b32 v21, v0, s24, v7
	ds_read_b32 v0, v14 offset:692
	v_readlane_b32 s63, v251, 24
	s_waitcnt lgkmcnt(0)
	v_bfe_u32 v7, v10, 16, 1
	v_add3_u32 v7, v10, v7, s26
	ds_read_b32 v10, v14 offset:824
	v_bfe_u32 v11, v0, 16, 1
	v_add3_u32 v0, v0, v11, s26
	ds_read_b32 v11, v14 offset:956
	v_lshrrev_b32_e32 v7, 16, v7
	v_and_or_b32 v22, v0, s24, v7
	s_waitcnt lgkmcnt(0)
	v_bfe_u32 v0, v10, 16, 1
	v_add3_u32 v0, v10, v0, s26
	v_bfe_u32 v7, v11, 16, 1
	v_or_b32_e32 v10, v6, v15
	v_add3_u32 v7, v11, v7, s26
	v_ashrrev_i32_e32 v11, 31, v10
	v_lshrrev_b32_e32 v0, 16, v0
	v_lshlrev_b64 v[10:11], 12, v[10:11]
	v_and_or_b32 v23, v7, s24, v0
	v_lshl_add_u64 v[10:11], v[8:9], 0, v[10:11]
	global_store_dwordx4 v[10:11], v[20:23], off
	ds_read_b32 v0, v14 offset:64
	ds_read_b32 v7, v14 offset:196
	v_readlane_b32 s64, v251, 25
	v_readlane_b32 s65, v251, 26
	v_readlane_b32 s66, v251, 27
	s_waitcnt lgkmcnt(0)
	v_bfe_u32 v10, v0, 16, 1
	v_add3_u32 v0, v0, v10, s26
	v_bfe_u32 v11, v7, 16, 1
	v_lshrrev_b32_e32 v0, 16, v0
	ds_read_b32 v10, v14 offset:328
	v_add3_u32 v7, v7, v11, s26
	v_and_or_b32 v20, v7, s24, v0
	ds_read_b32 v0, v14 offset:460
	v_readlane_b32 s67, v251, 28
	s_waitcnt lgkmcnt(0)
	v_bfe_u32 v7, v10, 16, 1
	v_add3_u32 v7, v10, v7, s26
	v_lshrrev_b32_e32 v7, 16, v7
	v_bfe_u32 v11, v0, 16, 1
	ds_read_b32 v10, v14 offset:592
	v_add3_u32 v0, v0, v11, s26
	v_and_or_b32 v21, v0, s24, v7
	ds_read_b32 v0, v14 offset:724
	v_readlane_b32 s68, v251, 29
	s_waitcnt lgkmcnt(0)
	v_bfe_u32 v7, v10, 16, 1
	v_add3_u32 v7, v10, v7, s26
	ds_read_b32 v10, v14 offset:856
	v_bfe_u32 v11, v0, 16, 1
	v_add3_u32 v0, v0, v11, s26
	ds_read_b32 v11, v14 offset:988
	v_lshrrev_b32_e32 v7, 16, v7
	v_and_or_b32 v22, v0, s24, v7
	s_waitcnt lgkmcnt(0)
	v_bfe_u32 v0, v10, 16, 1
	v_add3_u32 v0, v10, v0, s26
	v_bfe_u32 v7, v11, 16, 1
	v_or_b32_e32 v10, v6, v16
	v_add3_u32 v7, v11, v7, s26
	v_ashrrev_i32_e32 v11, 31, v10
	v_lshrrev_b32_e32 v0, 16, v0
	v_lshlrev_b64 v[10:11], 12, v[10:11]
	v_and_or_b32 v23, v7, s24, v0
	v_lshl_add_u64 v[10:11], v[8:9], 0, v[10:11]
	global_store_dwordx4 v[10:11], v[20:23], off
	ds_read_b32 v0, v14 offset:96
	ds_read_b32 v7, v14 offset:228
	v_or_b32_e32 v6, v6, v17
	v_readlane_b32 s69, v251, 30
	v_readlane_b32 s74, v251, 35
	s_waitcnt lgkmcnt(0)
	v_bfe_u32 v10, v0, 16, 1
	v_add3_u32 v0, v0, v10, s26
	v_bfe_u32 v11, v7, 16, 1
	v_lshrrev_b32_e32 v0, 16, v0
	ds_read_b32 v10, v14 offset:360
	v_add3_u32 v7, v7, v11, s26
	v_and_or_b32 v20, v7, s24, v0
	ds_read_b32 v0, v14 offset:492
	v_readlane_b32 s75, v251, 36
	s_waitcnt lgkmcnt(0)
	v_bfe_u32 v7, v10, 16, 1
	v_add3_u32 v7, v10, v7, s26
	v_lshrrev_b32_e32 v7, 16, v7
	v_bfe_u32 v11, v0, 16, 1
	ds_read_b32 v10, v14 offset:624
	v_add3_u32 v0, v0, v11, s26
	v_and_or_b32 v21, v0, s24, v7
	ds_read_b32 v0, v14 offset:756
	s_waitcnt lgkmcnt(0)
	v_bfe_u32 v7, v10, 16, 1
	v_add3_u32 v7, v10, v7, s26
	ds_read_b32 v10, v14 offset:888
	v_bfe_u32 v11, v0, 16, 1
	v_add3_u32 v0, v0, v11, s26
	ds_read_b32 v11, v14 offset:1020
	v_lshrrev_b32_e32 v7, 16, v7
	v_and_or_b32 v22, v0, s24, v7
	s_waitcnt lgkmcnt(0)
	v_bfe_u32 v0, v10, 16, 1
	v_add3_u32 v0, v10, v0, s26
	v_bfe_u32 v7, v11, 16, 1
	v_lshrrev_b32_e32 v0, 16, v0
	v_add3_u32 v7, v11, v7, s26
	v_and_or_b32 v23, v7, s24, v0
	v_ashrrev_i32_e32 v7, 31, v6
	v_lshlrev_b64 v[6:7], 12, v[6:7]
	v_lshl_add_u64 v[6:7], v[8:9], 0, v[6:7]
	global_store_dwordx4 v[6:7], v[20:23], off
	s_waitcnt lgkmcnt(0)
	s_branch .LBB0_274

;     ...
;     float tv_[32];
; #pragma unroll
;     for (int i = 0; i < 32; ++i) tv_[i] = W[(size_t)(k0 + 2 * i + (lane >> 5)) * N + n0 + (lane & 31)];
; #pragma unroll
;     for (int i = 0; i < 32; ++i) scr[(2 * i + (lane >> 5)) * 33 + (lane & 31)] = tv_[i];
; __device__ __forceinline__ void convert_range(LAS unsigned char* lds, const Params& p, const int lo, const int hi, const int gw, const int NGW) {
;     ...
;     for (int it = lo + gw; it < hi; it += NGW) {
;         int r = it;
;         if (r < 2 * I_IN) { const int l = r / I_IN; r -= l * I_IN; p0_transpose_item(p.in[5] + (size_t)l * DM * NC, DM, NC, (bf16*)(ws + WS_WIN + l * SZ_WIN), scr, r, lane); continue; } r -= 2 * I_IN;
;         if (r < 2 * I_PA) { const int l = r / I_PA; r -= l * I_PA; p0_transpose_item(p.in[16] + (size_t)l * PW * DM, PW, DM, (bf16*)(ws + WS_WCAT + l * SZ_WCAT), scr, r, lane, KCAT, 0); continue; } r -= 2 * I_PA;
;         if (r < 2 * I_PB) { const int l = r / I_PB; r -= l * I_PB; p0_transpose_item(p.in[17] + (size_t)l * LW * DM, LW, DM, (bf16*)(ws + WS_WCAT + l * SZ_WCAT), scr, r, lane, KCAT, PW); continue; } r -= 2 * I_PB;
.LBB0_282:
	v_add_u32_e32 v8, 0x5800, v18
	s_movk_i32 s6, 0x4fff
	v_cmp_lt_i32_e32 vcc, s6, v8
	s_and_saveexec_b64 s[6:7], vcc
	s_xor_b64 s[40:41], exec, s[6:7]
	s_cbranch_execz .LBB0_288
	s_movk_i32 s6, 0x57ff
	v_cmp_lt_u32_e32 vcc, s6, v8
	v_and_b32_e32 v19, 0x7e0, v17
	s_and_saveexec_b64 s[6:7], vcc
	s_xor_b64 s[42:43], exec, s[6:7]
	s_cbranch_execz .LBB0_285
	v_lshrrev_b32_e32 v0, 11, v18
	v_readlane_b32 s44, v251, 9
	v_lshlrev_b64 v[6:7], 24, v[0:1]
	v_readlane_b32 s46, v251, 11
	v_readlane_b32 s47, v251, 12
	s_mov_b32 s6, 0xc00000
	v_and_b32_e32 v22, 0x7c0, v8
	v_lshl_add_u64 v[20:21], s[46:47], 0, v[6:7]
	v_mov_b64_e32 v[6:7], s[0:1]
	v_mad_u64_u32 v[6:7], s[6:7], v0, s6, v[6:7]
	v_lshlrev_b32_e32 v0, 2, v19
	v_or_b32_e32 v23, v22, v10
	v_lshl_add_u64 v[8:9], v[20:21], 0, v[0:1]
	v_lshlrev_b32_e32 v0, 2, v2
	v_lshl_add_u64 v[8:9], v[8:9], 0, v[0:1]
	v_lshlrev_b32_e32 v0, 13, v23
	v_lshl_add_u64 v[8:9], v[8:9], 0, v[0:1]
	v_add_co_u32_e32 v20, vcc, s22, v8
	s_mov_b32 s6, 0x8000
	s_nop 0
	v_addc_co_u32_e32 v21, vcc, 0, v9, vcc
	global_load_dword v0, v[8:9], off
	global_load_dword v23, v[20:21], off
	v_add_co_u32_e32 v20, vcc, s6, v8
	s_mov_b32 s6, 0xc000
	s_nop 0
	v_addc_co_u32_e32 v21, vcc, 0, v9, vcc
	s_waitcnt lgkmcnt(0)
	global_load_dword v24, v[20:21], off
	v_add_co_u32_e32 v20, vcc, s6, v8
	s_mov_b32 s6, 0x14000
	s_nop 0
	v_addc_co_u32_e32 v21, vcc, 0, v9, vcc
	global_load_dword v25, v[20:21], off
	v_add_co_u32_e32 v20, vcc, s20, v8
	v_readlane_b32 s45, v251, 10
	s_nop 0
	v_addc_co_u32_e32 v21, vcc, 0, v9, vcc
	global_load_dword v26, v[20:21], off
	v_add_co_u32_e32 v20, vcc, s6, v8
	s_mov_b32 s6, 0x18000
	s_nop 0
	v_addc_co_u32_e32 v21, vcc, 0, v9, vcc
	global_load_dword v27, v[20:21], off
	v_add_co_u32_e32 v20, vcc, s6, v8
	s_mov_b32 s6, 0x1c000
	s_nop 0
	v_addc_co_u32_e32 v21, vcc, 0, v9, vcc
	global_load_dword v28, v[20:21], off
	v_add_co_u32_e32 v20, vcc, s6, v8
	s_mov_b32 s6, 0x20000
	s_nop 0
	v_addc_co_u32_e32 v21, vcc, 0, v9, vcc
	global_load_dword v29, v[20:21], off
	v_add_co_u32_e32 v20, vcc, s6, v8
	s_mov_b32 s6, 0x24000
	s_nop 0
	v_addc_co_u32_e32 v21, vcc, 0, v9, vcc
	global_load_dword v30, v[20:21], off
	v_add_co_u32_e32 v20, vcc, s6, v8
	s_mov_b32 s6, 0x28000
	s_nop 0
	v_addc_co_u32_e32 v21, vcc, 0, v9, vcc
	global_load_dword v31, v[20:21], off
	v_add_co_u32_e32 v20, vcc, s6, v8
	s_mov_b32 s6, 0x2c000
	s_nop 0
	v_addc_co_u32_e32 v21, vcc, 0, v9, vcc
	global_load_dword v32, v[20:21], off
	v_add_co_u32_e32 v20, vcc, s6, v8
	s_mov_b32 s6, 0x30000
	s_nop 0
	v_addc_co_u32_e32 v21, vcc, 0, v9, vcc
	global_load_dword v33, v[20:21], off
	v_add_co_u32_e32 v20, vcc, s6, v8
	s_mov_b32 s6, 0x34000
	s_nop 0
	v_addc_co_u32_e32 v21, vcc, 0, v9, vcc
	global_load_dword v34, v[20:21], off
	v_add_co_u32_e32 v20, vcc, s6, v8
	s_mov_b32 s6, 0x38000
	s_nop 0
	v_addc_co_u32_e32 v21, vcc, 0, v9, vcc
	global_load_dword v35, v[20:21], off
	v_add_co_u32_e32 v20, vcc, s6, v8
	s_mov_b32 s6, 0x3c000
	s_nop 0
	v_addc_co_u32_e32 v21, vcc, 0, v9, vcc
	global_load_dword v36, v[20:21], off
	v_add_co_u32_e32 v20, vcc, s6, v8
	s_mov_b32 s6, 0x44000
	s_nop 0
	v_addc_co_u32_e32 v21, vcc, 0, v9, vcc
	global_load_dword v37, v[20:21], off
	v_add_co_u32_e32 v20, vcc, s15, v8
	v_readlane_b32 s48, v251, 13
	s_nop 0
	v_addc_co_u32_e32 v21, vcc, 0, v9, vcc
	global_load_dword v38, v[20:21], off
	v_add_co_u32_e32 v20, vcc, s6, v8
	s_mov_b32 s6, 0x48000
	s_nop 0
	v_addc_co_u32_e32 v21, vcc, 0, v9, vcc
	global_load_dword v39, v[20:21], off
	v_add_co_u32_e32 v20, vcc, s6, v8
	s_mov_b32 s6, 0x4c000
	s_nop 0
	v_addc_co_u32_e32 v21, vcc, 0, v9, vcc
	global_load_dword v40, v[20:21], off
	v_add_co_u32_e32 v20, vcc, s6, v8
	s_mov_b32 s6, 0x50000
	s_nop 0
	v_addc_co_u32_e32 v21, vcc, 0, v9, vcc
	global_load_dword v41, v[20:21], off
	v_add_co_u32_e32 v20, vcc, s6, v8
	s_mov_b32 s6, 0x54000
	s_nop 0
	v_addc_co_u32_e32 v21, vcc, 0, v9, vcc
	global_load_dword v42, v[20:21], off
	v_add_co_u32_e32 v20, vcc, s6, v8
	s_mov_b32 s6, 0x58000
	s_nop 0
	v_addc_co_u32_e32 v21, vcc, 0, v9, vcc
	global_load_dword v43, v[20:21], off
	v_add_co_u32_e32 v20, vcc, s6, v8
	s_mov_b32 s6, 0x5c000
	s_nop 0
	v_addc_co_u32_e32 v21, vcc, 0, v9, vcc
	global_load_dword v44, v[20:21], off
	v_add_co_u32_e32 v20, vcc, s6, v8
	s_mov_b32 s6, 0x60000
	s_nop 0
	v_addc_co_u32_e32 v21, vcc, 0, v9, vcc
	global_load_dword v45, v[20:21], off
	v_add_co_u32_e32 v20, vcc, s6, v8
	s_mov_b32 s6, 0x64000
	s_nop 0
	v_addc_co_u32_e32 v21, vcc, 0, v9, vcc
	global_load_dword v46, v[20:21], off
	v_add_co_u32_e32 v20, vcc, s6, v8
	s_mov_b32 s6, 0x68000
	s_nop 0
	v_addc_co_u32_e32 v21, vcc, 0, v9, vcc
	global_load_dword v47, v[20:21], off
	v_add_co_u32_e32 v20, vcc, s6, v8
	s_mov_b32 s6, 0x6c000
	s_nop 0
	v_addc_co_u32_e32 v21, vcc, 0, v9, vcc
	global_load_dword v48, v[20:21], off
	v_add_co_u32_e32 v20, vcc, s6, v8
	s_mov_b32 s6, 0x70000
	s_nop 0
	v_addc_co_u32_e32 v21, vcc, 0, v9, vcc
	global_load_dword v49, v[20:21], off
	v_add_co_u32_e32 v20, vcc, s6, v8
	s_mov_b32 s6, 0x74000
	s_nop 0
	v_addc_co_u32_e32 v21, vcc, 0, v9, vcc
	global_load_dword v50, v[20:21], off
	v_add_co_u32_e32 v20, vcc, s6, v8
	s_mov_b32 s6, 0x78000
	s_nop 0
	v_addc_co_u32_e32 v21, vcc, 0, v9, vcc
	global_load_dword v51, v[20:21], off
	v_add_co_u32_e32 v20, vcc, s6, v8
	s_mov_b32 s6, 0x7c000
	s_nop 0
	v_addc_co_u32_e32 v21, vcc, 0, v9, vcc
	v_add_co_u32_e32 v8, vcc, s6, v8
	global_load_dword v20, v[20:21], off
	s_nop 0
	v_addc_co_u32_e32 v9, vcc, 0, v9, vcc
	global_load_dword v8, v[8:9], off
	s_waitcnt vmcnt(30)
	ds_write2_b32 v11, v0, v23 offset1:66
	s_waitcnt vmcnt(28)
	ds_write2_b32 v11, v24, v25 offset0:132 offset1:198
	v_add_u32_e32 v0, 0x400, v11
	s_waitcnt vmcnt(26)
; #define LAS __attribute__((address_space(3)))
; #define LDS_WAIT() asm volatile("s_waitcnt lgkmcnt(0)" ::: "memory")
; __device__ __forceinline__ unsigned pk2(float lo, float hi) { return f2bf(lo) | (f2bf(hi) << 16); }
;     ...
;     for (int i = 0; i < 32; ++i) scr[(2 * i + (lane >> 5)) * 33 + (lane & 31)] = tv_[i];
;     LDS_WAIT(); asm volatile("" ::: "memory");
;     const int c = lane & 7;
; #pragma unroll
;     for (int j = 0; j < 4; ++j) { const int n = (lane >> 3) + 8 * j; const LAS float* s = scr + (8 * c) * 33 + n;
;         v4u o; o.x = pk2(s[0 * 33], s[1 * 33]); o.y = pk2(s[2 * 33], s[3 * 33]); o.z = pk2(s[4 * 33], s[5 * 33]); o.w = pk2(s[6 * 33], s[7 * 33]);
;         *(v4u*)(WT + (size_t)(n0 + n) * ldw + koff + k0 + 8 * c) = o; }
;     LDS_WAIT(); asm volatile("" ::: "memory");
	ds_write2_b32 v0, v26, v27 offset0:8 offset1:74
	s_waitcnt vmcnt(24)
	ds_write2_b32 v0, v28, v29 offset0:140 offset1:206
	v_add_u32_e32 v0, 0x800, v11
	s_waitcnt vmcnt(22)
	ds_write2_b32 v0, v30, v31 offset0:16 offset1:82
	s_waitcnt vmcnt(20)
	ds_write2_b32 v0, v32, v33 offset0:148 offset1:214
	v_add_u32_e32 v0, 0xc00, v11
	s_waitcnt vmcnt(18)
	ds_write2_b32 v0, v34, v35 offset0:24 offset1:90
	s_waitcnt vmcnt(16)
	ds_write2_b32 v0, v36, v37 offset0:156 offset1:222
	v_add_u32_e32 v0, 0x1000, v11
	s_waitcnt vmcnt(14)
	ds_write2_b32 v0, v38, v39 offset0:32 offset1:98
	s_waitcnt vmcnt(12)
	ds_write2_b32 v0, v40, v41 offset0:164 offset1:230
	v_add_u32_e32 v0, 0x1400, v11
	s_waitcnt vmcnt(10)
	ds_write2_b32 v0, v42, v43 offset0:40 offset1:106
	s_waitcnt vmcnt(8)
	ds_write2_b32 v0, v44, v45 offset0:172 offset1:238
	v_add_u32_e32 v0, 0x1800, v11
	s_waitcnt vmcnt(6)
	ds_write2_b32 v0, v46, v47 offset0:48 offset1:114
	s_waitcnt vmcnt(4)
	ds_write2_b32 v0, v48, v49 offset0:180 offset1:246
	v_add_u32_e32 v0, 0x1c00, v11
	s_waitcnt vmcnt(2)
	ds_write2_b32 v0, v50, v51 offset0:56 offset1:122
	s_waitcnt vmcnt(0)
	ds_write2_b32 v0, v20, v8 offset0:188 offset1:254
	s_waitcnt lgkmcnt(0)
	v_lshlrev_b32_e32 v0, 1, v22
	v_lshl_add_u64 v[6:7], v[6:7], 0, v[0:1]
	v_lshlrev_b32_e32 v0, 1, v4
	v_lshl_add_u64 v[6:7], v[6:7], 0, v[0:1]
	ds_read_b32 v0, v13
	ds_read_b32 v8, v13 offset:132
	s_mov_b64 s[6:7], 0x5000800
	v_lshl_add_u64 v[6:7], v[6:7], 0, s[6:7]
	v_readlane_b32 s49, v251, 14
	s_waitcnt lgkmcnt(0)
	v_bfe_u32 v9, v0, 16, 1
	v_add3_u32 v0, v0, v9, s26
	v_bfe_u32 v9, v8, 16, 1
	v_lshrrev_b32_e32 v0, 16, v0
	v_add3_u32 v8, v8, v9, s26
	v_and_or_b32 v20, v8, s24, v0
	ds_read_b32 v0, v13 offset:264
	ds_read_b32 v8, v13 offset:396
	v_readlane_b32 s50, v251, 15
	v_readlane_b32 s51, v251, 16
	s_waitcnt lgkmcnt(1)
	v_bfe_u32 v9, v0, 16, 1
	v_add3_u32 v0, v0, v9, s26
	s_waitcnt lgkmcnt(0)
	v_bfe_u32 v9, v8, 16, 1
	v_lshrrev_b32_e32 v0, 16, v0
	v_add3_u32 v8, v8, v9, s26
	v_and_or_b32 v21, v8, s24, v0
	ds_read_b32 v0, v13 offset:528
	ds_read_b32 v8, v13 offset:660
	s_waitcnt lgkmcnt(1)
	v_bfe_u32 v9, v0, 16, 1
	v_add3_u32 v0, v0, v9, s26
	s_waitcnt lgkmcnt(0)
	v_bfe_u32 v9, v8, 16, 1
	v_lshrrev_b32_e32 v0, 16, v0
	v_add3_u32 v8, v8, v9, s26
	v_and_or_b32 v22, v8, s24, v0
	ds_read_b32 v0, v13 offset:792
	ds_read_b32 v8, v13 offset:924
	s_waitcnt lgkmcnt(1)
	v_bfe_u32 v9, v0, 16, 1
	v_add3_u32 v0, v0, v9, s26
	s_waitcnt lgkmcnt(0)
	v_bfe_u32 v9, v8, 16, 1
	v_lshrrev_b32_e32 v0, 16, v0
	v_add3_u32 v8, v8, v9, s26
	v_and_or_b32 v23, v8, s24, v0
	v_or_b32_e32 v0, v19, v12
	v_mul_u32_u24_e32 v0, 0xc00, v0
	v_lshlrev_b32_e32 v0, 1, v0
	v_lshl_add_u64 v[8:9], v[6:7], 0, v[0:1]
	global_store_dwordx4 v[8:9], v[20:23], off
	ds_read_b32 v0, v13 offset:32
	ds_read_b32 v8, v13 offset:164
	s_waitcnt lgkmcnt(0)
	v_bfe_u32 v9, v0, 16, 1
	v_add3_u32 v0, v0, v9, s26
	v_bfe_u32 v9, v8, 16, 1
	v_lshrrev_b32_e32 v0, 16, v0
	v_add3_u32 v8, v8, v9, s26
	v_and_or_b32 v20, v8, s24, v0
	ds_read_b32 v0, v13 offset:296
	ds_read_b32 v8, v13 offset:428
	s_waitcnt lgkmcnt(0)
	v_bfe_u32 v9, v0, 16, 1
	v_add3_u32 v0, v0, v9, s26
	v_bfe_u32 v9, v8, 16, 1
	v_lshrrev_b32_e32 v0, 16, v0
	v_add3_u32 v8, v8, v9, s26
	v_and_or_b32 v21, v8, s24, v0
	ds_read_b32 v0, v13 offset:560
	ds_read_b32 v8, v13 offset:692
	s_waitcnt lgkmcnt(0)
	v_bfe_u32 v9, v0, 16, 1
	v_add3_u32 v0, v0, v9, s26
	v_bfe_u32 v9, v8, 16, 1
	v_lshrrev_b32_e32 v0, 16, v0
	v_add3_u32 v8, v8, v9, s26
	v_and_or_b32 v22, v8, s24, v0
	ds_read_b32 v0, v13 offset:824
	ds_read_b32 v8, v13 offset:956
	s_waitcnt lgkmcnt(0)
	v_bfe_u32 v9, v0, 16, 1
	v_add3_u32 v0, v0, v9, s26
	v_bfe_u32 v9, v8, 16, 1
	v_lshrrev_b32_e32 v0, 16, v0
	v_add3_u32 v8, v8, v9, s26
	v_and_or_b32 v23, v8, s24, v0
	v_or_b32_e32 v0, v19, v14
	v_mul_u32_u24_e32 v0, 0xc00, v0
	v_lshlrev_b32_e32 v0, 1, v0
	v_lshl_add_u64 v[8:9], v[6:7], 0, v[0:1]
	global_store_dwordx4 v[8:9], v[20:23], off
	ds_read_b32 v0, v13 offset:64
	ds_read_b32 v8, v13 offset:196
	s_waitcnt lgkmcnt(0)
	v_bfe_u32 v9, v0, 16, 1
	v_add3_u32 v0, v0, v9, s26
	v_bfe_u32 v9, v8, 16, 1
	v_lshrrev_b32_e32 v0, 16, v0
	v_add3_u32 v8, v8, v9, s26
	v_and_or_b32 v20, v8, s24, v0
	ds_read_b32 v0, v13 offset:328
	ds_read_b32 v8, v13 offset:460
	s_waitcnt lgkmcnt(0)
	v_bfe_u32 v9, v0, 16, 1
	v_add3_u32 v0, v0, v9, s26
	v_bfe_u32 v9, v8, 16, 1
	v_lshrrev_b32_e32 v0, 16, v0
	v_add3_u32 v8, v8, v9, s26
	v_and_or_b32 v21, v8, s24, v0
	ds_read_b32 v0, v13 offset:592
	ds_read_b32 v8, v13 offset:724
	s_waitcnt lgkmcnt(0)
	v_bfe_u32 v9, v0, 16, 1
	v_add3_u32 v0, v0, v9, s26
	v_bfe_u32 v9, v8, 16, 1
	v_lshrrev_b32_e32 v0, 16, v0
	v_add3_u32 v8, v8, v9, s26
	v_and_or_b32 v22, v8, s24, v0
	ds_read_b32 v0, v13 offset:856
	ds_read_b32 v8, v13 offset:988
	s_waitcnt lgkmcnt(0)
	v_bfe_u32 v9, v0, 16, 1
	v_add3_u32 v0, v0, v9, s26
	v_bfe_u32 v9, v8, 16, 1
	v_lshrrev_b32_e32 v0, 16, v0
	v_add3_u32 v8, v8, v9, s26
	v_and_or_b32 v23, v8, s24, v0
	v_or_b32_e32 v0, v19, v15
	v_mul_u32_u24_e32 v0, 0xc00, v0
	v_lshlrev_b32_e32 v0, 1, v0
	v_lshl_add_u64 v[8:9], v[6:7], 0, v[0:1]
	global_store_dwordx4 v[8:9], v[20:23], off
	ds_read_b32 v0, v13 offset:96
	ds_read_b32 v8, v13 offset:228
	s_waitcnt lgkmcnt(0)
	v_bfe_u32 v9, v0, 16, 1
	v_add3_u32 v0, v0, v9, s26
	v_bfe_u32 v9, v8, 16, 1
	v_lshrrev_b32_e32 v0, 16, v0
	v_add3_u32 v8, v8, v9, s26
	v_and_or_b32 v20, v8, s24, v0
	ds_read_b32 v0, v13 offset:360
	ds_read_b32 v8, v13 offset:492
	s_waitcnt lgkmcnt(0)
	v_bfe_u32 v9, v0, 16, 1
	v_add3_u32 v0, v0, v9, s26
	v_bfe_u32 v9, v8, 16, 1
	v_lshrrev_b32_e32 v0, 16, v0
	v_add3_u32 v8, v8, v9, s26
	v_and_or_b32 v21, v8, s24, v0
	ds_read_b32 v0, v13 offset:624
	ds_read_b32 v8, v13 offset:756
	s_waitcnt lgkmcnt(0)
	v_bfe_u32 v9, v0, 16, 1
	v_add3_u32 v0, v0, v9, s26
	v_bfe_u32 v9, v8, 16, 1
	v_lshrrev_b32_e32 v0, 16, v0
	v_add3_u32 v8, v8, v9, s26
	v_and_or_b32 v22, v8, s24, v0
	ds_read_b32 v0, v13 offset:888
	ds_read_b32 v8, v13 offset:1020
	s_waitcnt lgkmcnt(0)
	v_bfe_u32 v9, v0, 16, 1
	v_add3_u32 v0, v0, v9, s26
	v_bfe_u32 v9, v8, 16, 1
	v_lshrrev_b32_e32 v0, 16, v0
	v_add3_u32 v8, v8, v9, s26
	v_and_or_b32 v23, v8, s24, v0
	v_or_b32_e32 v0, v19, v16
	v_mul_u32_u24_e32 v0, 0xc00, v0
	v_lshlrev_b32_e32 v0, 1, v0
	v_lshl_add_u64 v[6:7], v[6:7], 0, v[0:1]
	global_store_dwordx4 v[6:7], v[20:23], off
	s_waitcnt lgkmcnt(0)
; #define LDS_WAIT() asm volatile("s_waitcnt lgkmcnt(0)" ::: "memory")
;     ...
;     float tv_[32];
; #pragma unroll
;     for (int i = 0; i < 32; ++i) tv_[i] = W[(size_t)(k0 + 2 * i + (lane >> 5)) * N + n0 + (lane & 31)];
; #pragma unroll
;     for (int i = 0; i < 32; ++i) scr[(2 * i + (lane >> 5)) * 33 + (lane & 31)] = tv_[i];
;     LDS_WAIT(); asm volatile("" ::: "memory");
; __device__ __forceinline__ void convert_range(LAS unsigned char* lds, const Params& p, const int lo, const int hi, const int gw, const int NGW) {
;     ...
;         if (r < 2 * I_IN) { const int l = r / I_IN; r -= l * I_IN; p0_transpose_item(p.in[5] + (size_t)l * DM * NC, DM, NC, (bf16*)(ws + WS_WIN + l * SZ_WIN), scr, r, lane); continue; } r -= 2 * I_IN;
;         if (r < 2 * I_PA) { const int l = r / I_PA; r -= l * I_PA; p0_transpose_item(p.in[16] + (size_t)l * PW * DM, PW, DM, (bf16*)(ws + WS_WCAT + l * SZ_WCAT), scr, r, lane, KCAT, 0); continue; } r -= 2 * I_PA;
;         if (r < 2 * I_PB) { const int l = r / I_PB; r -= l * I_PB; p0_transpose_item(p.in[17] + (size_t)l * LW * DM, LW, DM, (bf16*)(ws + WS_WCAT + l * SZ_WCAT), scr, r, lane, KCAT, PW); continue; } r -= 2 * I_PB;
;         if (r < 2 * I_OUT) { const int l = r / I_OUT; r -= l * I_OUT; p0_transpose_item(p.in[18] + (size_t)l * DM * DM, DM, DM, (bf16*)(ws + WS_WOUT + l * SZ_WOUT), scr, r, lane); continue; } r -= 2 * I_OUT;
;         if (r < I_PL) { const int mi = r / 32; r -= mi * 32; p0_transpose_item(p.in[7] + (size_t)mi * 65536, 256, 256, (bf16*)(ws + WS_POOLW) + (size_t)mi * 65536, scr, r, lane); continue; } r -= I_PL;
;         if (r < I_LR) { const int mi = r / 8; r -= mi * 8; p0_transpose_item(p.in[11] + (size_t)mi * 16384, 128, 128, (bf16*)(ws + WS_WA) + (size_t)mi * 16384, scr, r, lane); continue; } r -= I_LR;
;         { const int mi = r / 8; r -= mi * 8; p0_transpose_item(p.in[13] + (size_t)mi * 16384, 128, 128, (bf16*)(ws + WS_WX) + (size_t)mi * 16384, scr, r, lane); }
.LBB0_285:
	s_andn2_saveexec_b64 s[42:43], s[42:43]
	s_cbranch_execz .LBB0_287
	v_add_u32_e32 v0, 0x800, v18
	v_lshrrev_b32_e32 v0, 10, v0
	v_readlane_b32 s44, v251, 9
	v_lshlrev_b64 v[6:7], 23, v[0:1]
	v_readlane_b32 s45, v251, 10
	s_mov_b32 s6, 0xc00000
	v_and_b32_e32 v22, 0x3c0, v8
	v_lshl_add_u64 v[20:21], s[44:45], 0, v[6:7]
	v_mov_b64_e32 v[6:7], s[18:19]
	v_mad_u64_u32 v[6:7], s[6:7], v0, s6, v[6:7]
	v_lshlrev_b32_e32 v0, 2, v19
	v_or_b32_e32 v23, v22, v10
	v_lshl_add_u64 v[8:9], v[20:21], 0, v[0:1]
	v_lshlrev_b32_e32 v0, 2, v2
	v_lshl_add_u64 v[8:9], v[8:9], 0, v[0:1]
	v_lshlrev_b32_e32 v0, 13, v23
	v_lshl_add_u64 v[8:9], v[8:9], 0, v[0:1]
	v_add_co_u32_e32 v20, vcc, s22, v8
	s_mov_b32 s6, 0x8000
	s_nop 0
	v_addc_co_u32_e32 v21, vcc, 0, v9, vcc
	global_load_dword v0, v[8:9], off
	global_load_dword v23, v[20:21], off
	v_add_co_u32_e32 v20, vcc, s6, v8
	s_mov_b32 s6, 0xc000
	s_nop 0
	v_addc_co_u32_e32 v21, vcc, 0, v9, vcc
	s_waitcnt lgkmcnt(0)
	global_load_dword v24, v[20:21], off
	v_add_co_u32_e32 v20, vcc, s6, v8
	s_mov_b32 s6, 0x14000
	s_nop 0
	v_addc_co_u32_e32 v21, vcc, 0, v9, vcc
	global_load_dword v25, v[20:21], off
	v_add_co_u32_e32 v20, vcc, s20, v8
	v_readlane_b32 s46, v251, 11
	s_nop 0
	v_addc_co_u32_e32 v21, vcc, 0, v9, vcc
	global_load_dword v26, v[20:21], off
	v_add_co_u32_e32 v20, vcc, s6, v8
	s_mov_b32 s6, 0x18000
	s_nop 0
	v_addc_co_u32_e32 v21, vcc, 0, v9, vcc
	global_load_dword v27, v[20:21], off
	v_add_co_u32_e32 v20, vcc, s6, v8
	s_mov_b32 s6, 0x1c000
	s_nop 0
	v_addc_co_u32_e32 v21, vcc, 0, v9, vcc
	global_load_dword v28, v[20:21], off
	v_add_co_u32_e32 v20, vcc, s6, v8
	s_mov_b32 s6, 0x20000
	s_nop 0
	v_addc_co_u32_e32 v21, vcc, 0, v9, vcc
	global_load_dword v29, v[20:21], off
	v_add_co_u32_e32 v20, vcc, s6, v8
	s_mov_b32 s6, 0x24000
	s_nop 0
	v_addc_co_u32_e32 v21, vcc, 0, v9, vcc
	global_load_dword v30, v[20:21], off
	v_add_co_u32_e32 v20, vcc, s6, v8
	s_mov_b32 s6, 0x28000
	s_nop 0
	v_addc_co_u32_e32 v21, vcc, 0, v9, vcc
	global_load_dword v31, v[20:21], off
	v_add_co_u32_e32 v20, vcc, s6, v8
	s_mov_b32 s6, 0x2c000
	s_nop 0
	v_addc_co_u32_e32 v21, vcc, 0, v9, vcc
	global_load_dword v32, v[20:21], off
	v_add_co_u32_e32 v20, vcc, s6, v8
	s_mov_b32 s6, 0x30000
	s_nop 0
	v_addc_co_u32_e32 v21, vcc, 0, v9, vcc
	global_load_dword v33, v[20:21], off
	v_add_co_u32_e32 v20, vcc, s6, v8
	s_mov_b32 s6, 0x34000
	s_nop 0
	v_addc_co_u32_e32 v21, vcc, 0, v9, vcc
	global_load_dword v34, v[20:21], off
	v_add_co_u32_e32 v20, vcc, s6, v8
	s_mov_b32 s6, 0x38000
	s_nop 0
	v_addc_co_u32_e32 v21, vcc, 0, v9, vcc
	global_load_dword v35, v[20:21], off
	v_add_co_u32_e32 v20, vcc, s6, v8
	s_mov_b32 s6, 0x3c000
	s_nop 0
	v_addc_co_u32_e32 v21, vcc, 0, v9, vcc
	global_load_dword v36, v[20:21], off
	v_add_co_u32_e32 v20, vcc, s6, v8
	s_mov_b32 s6, 0x44000
	s_nop 0
	v_addc_co_u32_e32 v21, vcc, 0, v9, vcc
	global_load_dword v37, v[20:21], off
	v_add_co_u32_e32 v20, vcc, s15, v8
	v_readlane_b32 s47, v251, 12
	s_nop 0
	v_addc_co_u32_e32 v21, vcc, 0, v9, vcc
	global_load_dword v38, v[20:21], off
	v_add_co_u32_e32 v20, vcc, s6, v8
	s_mov_b32 s6, 0x48000
	s_nop 0
	v_addc_co_u32_e32 v21, vcc, 0, v9, vcc
	global_load_dword v39, v[20:21], off
	v_add_co_u32_e32 v20, vcc, s6, v8
	s_mov_b32 s6, 0x4c000
	s_nop 0
	v_addc_co_u32_e32 v21, vcc, 0, v9, vcc
	global_load_dword v40, v[20:21], off
	v_add_co_u32_e32 v20, vcc, s6, v8
	s_mov_b32 s6, 0x50000
	s_nop 0
	v_addc_co_u32_e32 v21, vcc, 0, v9, vcc
	global_load_dword v41, v[20:21], off
	v_add_co_u32_e32 v20, vcc, s6, v8
	s_mov_b32 s6, 0x54000
	s_nop 0
	v_addc_co_u32_e32 v21, vcc, 0, v9, vcc
	global_load_dword v42, v[20:21], off
	v_add_co_u32_e32 v20, vcc, s6, v8
	s_mov_b32 s6, 0x58000
	s_nop 0
	v_addc_co_u32_e32 v21, vcc, 0, v9, vcc
	global_load_dword v43, v[20:21], off
	v_add_co_u32_e32 v20, vcc, s6, v8
	s_mov_b32 s6, 0x5c000
	s_nop 0
	v_addc_co_u32_e32 v21, vcc, 0, v9, vcc
	global_load_dword v44, v[20:21], off
	v_add_co_u32_e32 v20, vcc, s6, v8
	s_mov_b32 s6, 0x60000
	s_nop 0
	v_addc_co_u32_e32 v21, vcc, 0, v9, vcc
	global_load_dword v45, v[20:21], off
	v_add_co_u32_e32 v20, vcc, s6, v8
	s_mov_b32 s6, 0x64000
	s_nop 0
	v_addc_co_u32_e32 v21, vcc, 0, v9, vcc
	global_load_dword v46, v[20:21], off
	v_add_co_u32_e32 v20, vcc, s6, v8
	s_mov_b32 s6, 0x68000
	s_nop 0
	v_addc_co_u32_e32 v21, vcc, 0, v9, vcc
	global_load_dword v47, v[20:21], off
	v_add_co_u32_e32 v20, vcc, s6, v8
	s_mov_b32 s6, 0x6c000
	s_nop 0
	v_addc_co_u32_e32 v21, vcc, 0, v9, vcc
	global_load_dword v48, v[20:21], off
	v_add_co_u32_e32 v20, vcc, s6, v8
	s_mov_b32 s6, 0x70000
	s_nop 0
	v_addc_co_u32_e32 v21, vcc, 0, v9, vcc
	global_load_dword v49, v[20:21], off
	v_add_co_u32_e32 v20, vcc, s6, v8
	s_mov_b32 s6, 0x74000
	s_nop 0
	v_addc_co_u32_e32 v21, vcc, 0, v9, vcc
	global_load_dword v50, v[20:21], off
	v_add_co_u32_e32 v20, vcc, s6, v8
	s_mov_b32 s6, 0x78000
	s_nop 0
	v_addc_co_u32_e32 v21, vcc, 0, v9, vcc
	global_load_dword v51, v[20:21], off
	v_add_co_u32_e32 v20, vcc, s6, v8
	s_mov_b32 s6, 0x7c000
	s_nop 0
	v_addc_co_u32_e32 v21, vcc, 0, v9, vcc
	v_add_co_u32_e32 v8, vcc, s6, v8
	global_load_dword v20, v[20:21], off
	s_nop 0
	v_addc_co_u32_e32 v9, vcc, 0, v9, vcc
	global_load_dword v8, v[8:9], off
	s_waitcnt vmcnt(30)
	ds_write2_b32 v11, v0, v23 offset1:66
	s_waitcnt vmcnt(28)
	ds_write2_b32 v11, v24, v25 offset0:132 offset1:198
	v_add_u32_e32 v0, 0x400, v11
	s_waitcnt vmcnt(26)
	ds_write2_b32 v0, v26, v27 offset0:8 offset1:74
	s_waitcnt vmcnt(24)
	ds_write2_b32 v0, v28, v29 offset0:140 offset1:206
	v_add_u32_e32 v0, 0x800, v11
	s_waitcnt vmcnt(22)
	ds_write2_b32 v0, v30, v31 offset0:16 offset1:82
	s_waitcnt vmcnt(20)
; #define LAS __attribute__((address_space(3)))
; #define LDS_WAIT() asm volatile("s_waitcnt lgkmcnt(0)" ::: "memory")
; __device__ __forceinline__ unsigned pk2(float lo, float hi) { return f2bf(lo) | (f2bf(hi) << 16); }
;     ...
;     for (int i = 0; i < 32; ++i) scr[(2 * i + (lane >> 5)) * 33 + (lane & 31)] = tv_[i];
;     LDS_WAIT(); asm volatile("" ::: "memory");
;     const int c = lane & 7;
; #pragma unroll
;     for (int j = 0; j < 4; ++j) { const int n = (lane >> 3) + 8 * j; const LAS float* s = scr + (8 * c) * 33 + n;
;         v4u o; o.x = pk2(s[0 * 33], s[1 * 33]); o.y = pk2(s[2 * 33], s[3 * 33]); o.z = pk2(s[4 * 33], s[5 * 33]); o.w = pk2(s[6 * 33], s[7 * 33]);
;         *(v4u*)(WT + (size_t)(n0 + n) * ldw + koff + k0 + 8 * c) = o; }
;     LDS_WAIT(); asm volatile("" ::: "memory");
	ds_write2_b32 v0, v32, v33 offset0:148 offset1:214
	v_add_u32_e32 v0, 0xc00, v11
	s_waitcnt vmcnt(18)
	ds_write2_b32 v0, v34, v35 offset0:24 offset1:90
	s_waitcnt vmcnt(16)
	ds_write2_b32 v0, v36, v37 offset0:156 offset1:222
	v_add_u32_e32 v0, 0x1000, v11
	s_waitcnt vmcnt(14)
	ds_write2_b32 v0, v38, v39 offset0:32 offset1:98
	s_waitcnt vmcnt(12)
	ds_write2_b32 v0, v40, v41 offset0:164 offset1:230
	v_add_u32_e32 v0, 0x1400, v11
	s_waitcnt vmcnt(10)
	ds_write2_b32 v0, v42, v43 offset0:40 offset1:106
	s_waitcnt vmcnt(8)
	ds_write2_b32 v0, v44, v45 offset0:172 offset1:238
	v_add_u32_e32 v0, 0x1800, v11
	s_waitcnt vmcnt(6)
	ds_write2_b32 v0, v46, v47 offset0:48 offset1:114
	s_waitcnt vmcnt(4)
	ds_write2_b32 v0, v48, v49 offset0:180 offset1:246
	v_add_u32_e32 v0, 0x1c00, v11
	s_waitcnt vmcnt(2)
	ds_write2_b32 v0, v50, v51 offset0:56 offset1:122
	s_waitcnt vmcnt(0)
	ds_write2_b32 v0, v20, v8 offset0:188 offset1:254
	s_waitcnt lgkmcnt(0)
	v_lshlrev_b32_e32 v0, 1, v22
	v_lshl_add_u64 v[6:7], v[6:7], 0, v[0:1]
	v_lshlrev_b32_e32 v0, 1, v4
	v_lshl_add_u64 v[6:7], v[6:7], 0, v[0:1]
	ds_read_b32 v0, v13
	ds_read_b32 v8, v13 offset:132
	v_readlane_b32 s48, v251, 13
	v_readlane_b32 s49, v251, 14
	v_readlane_b32 s50, v251, 15
	s_waitcnt lgkmcnt(0)
	v_bfe_u32 v9, v0, 16, 1
	v_add3_u32 v0, v0, v9, s26
	v_bfe_u32 v9, v8, 16, 1
	v_lshrrev_b32_e32 v0, 16, v0
	v_add3_u32 v8, v8, v9, s26
	v_and_or_b32 v20, v8, s24, v0
	ds_read_b32 v0, v13 offset:264
	ds_read_b32 v8, v13 offset:396
	v_readlane_b32 s51, v251, 16
	s_waitcnt lgkmcnt(1)
	v_bfe_u32 v9, v0, 16, 1
	v_add3_u32 v0, v0, v9, s26
	s_waitcnt lgkmcnt(0)
	v_bfe_u32 v9, v8, 16, 1
	v_lshrrev_b32_e32 v0, 16, v0
	v_add3_u32 v8, v8, v9, s26
	v_and_or_b32 v21, v8, s24, v0
	ds_read_b32 v0, v13 offset:528
	ds_read_b32 v8, v13 offset:660
	s_waitcnt lgkmcnt(1)
	v_bfe_u32 v9, v0, 16, 1
	v_add3_u32 v0, v0, v9, s26
	s_waitcnt lgkmcnt(0)
	v_bfe_u32 v9, v8, 16, 1
	v_lshrrev_b32_e32 v0, 16, v0
	v_add3_u32 v8, v8, v9, s26
	v_and_or_b32 v22, v8, s24, v0
	ds_read_b32 v0, v13 offset:792
	ds_read_b32 v8, v13 offset:924
	s_waitcnt lgkmcnt(1)
	v_bfe_u32 v9, v0, 16, 1
	v_add3_u32 v0, v0, v9, s26
	s_waitcnt lgkmcnt(0)
	v_bfe_u32 v9, v8, 16, 1
	v_lshrrev_b32_e32 v0, 16, v0
	v_add3_u32 v8, v8, v9, s26
	v_and_or_b32 v23, v8, s24, v0
	v_or_b32_e32 v0, v19, v12
	v_mul_u32_u24_e32 v0, 0xc00, v0
	v_lshlrev_b32_e32 v0, 1, v0
	v_lshl_add_u64 v[8:9], v[6:7], 0, v[0:1]
	global_store_dwordx4 v[8:9], v[20:23], off
	ds_read_b32 v0, v13 offset:32
	ds_read_b32 v8, v13 offset:164
	s_waitcnt lgkmcnt(0)
	v_bfe_u32 v9, v0, 16, 1
	v_add3_u32 v0, v0, v9, s26
	v_bfe_u32 v9, v8, 16, 1
	v_lshrrev_b32_e32 v0, 16, v0
	v_add3_u32 v8, v8, v9, s26
	v_and_or_b32 v20, v8, s24, v0
	ds_read_b32 v0, v13 offset:296
	ds_read_b32 v8, v13 offset:428
	s_waitcnt lgkmcnt(0)
	v_bfe_u32 v9, v0, 16, 1
	v_add3_u32 v0, v0, v9, s26
	v_bfe_u32 v9, v8, 16, 1
	v_lshrrev_b32_e32 v0, 16, v0
	v_add3_u32 v8, v8, v9, s26
	v_and_or_b32 v21, v8, s24, v0
	ds_read_b32 v0, v13 offset:560
	ds_read_b32 v8, v13 offset:692
	s_waitcnt lgkmcnt(0)
	v_bfe_u32 v9, v0, 16, 1
	v_add3_u32 v0, v0, v9, s26
	v_bfe_u32 v9, v8, 16, 1
	v_lshrrev_b32_e32 v0, 16, v0
	v_add3_u32 v8, v8, v9, s26
	v_and_or_b32 v22, v8, s24, v0
	ds_read_b32 v0, v13 offset:824
	ds_read_b32 v8, v13 offset:956
	s_waitcnt lgkmcnt(0)
	v_bfe_u32 v9, v0, 16, 1
	v_add3_u32 v0, v0, v9, s26
	v_bfe_u32 v9, v8, 16, 1
	v_lshrrev_b32_e32 v0, 16, v0
	v_add3_u32 v8, v8, v9, s26
	v_and_or_b32 v23, v8, s24, v0
	v_or_b32_e32 v0, v19, v14
	v_mul_u32_u24_e32 v0, 0xc00, v0
	v_lshlrev_b32_e32 v0, 1, v0
	v_lshl_add_u64 v[8:9], v[6:7], 0, v[0:1]
	global_store_dwordx4 v[8:9], v[20:23], off
	ds_read_b32 v0, v13 offset:64
	ds_read_b32 v8, v13 offset:196
	s_waitcnt lgkmcnt(0)
	v_bfe_u32 v9, v0, 16, 1
	v_add3_u32 v0, v0, v9, s26
	v_bfe_u32 v9, v8, 16, 1
	v_lshrrev_b32_e32 v0, 16, v0
	v_add3_u32 v8, v8, v9, s26
	v_and_or_b32 v20, v8, s24, v0
	ds_read_b32 v0, v13 offset:328
	ds_read_b32 v8, v13 offset:460
	s_waitcnt lgkmcnt(0)
	v_bfe_u32 v9, v0, 16, 1
	v_add3_u32 v0, v0, v9, s26
	v_bfe_u32 v9, v8, 16, 1
	v_lshrrev_b32_e32 v0, 16, v0
	v_add3_u32 v8, v8, v9, s26
	v_and_or_b32 v21, v8, s24, v0
	ds_read_b32 v0, v13 offset:592
	ds_read_b32 v8, v13 offset:724
	s_waitcnt lgkmcnt(0)
	v_bfe_u32 v9, v0, 16, 1
	v_add3_u32 v0, v0, v9, s26
	v_bfe_u32 v9, v8, 16, 1
	v_lshrrev_b32_e32 v0, 16, v0
	v_add3_u32 v8, v8, v9, s26
	v_and_or_b32 v22, v8, s24, v0
	ds_read_b32 v0, v13 offset:856
	ds_read_b32 v8, v13 offset:988
	s_waitcnt lgkmcnt(0)
	v_bfe_u32 v9, v0, 16, 1
	v_add3_u32 v0, v0, v9, s26
	v_bfe_u32 v9, v8, 16, 1
	v_lshrrev_b32_e32 v0, 16, v0
	v_add3_u32 v8, v8, v9, s26
	v_and_or_b32 v23, v8, s24, v0
	v_or_b32_e32 v0, v19, v15
	v_mul_u32_u24_e32 v0, 0xc00, v0
	v_lshlrev_b32_e32 v0, 1, v0
	v_lshl_add_u64 v[8:9], v[6:7], 0, v[0:1]
	global_store_dwordx4 v[8:9], v[20:23], off
	ds_read_b32 v0, v13 offset:96
	ds_read_b32 v8, v13 offset:228
	s_waitcnt lgkmcnt(0)
	v_bfe_u32 v9, v0, 16, 1
	v_add3_u32 v0, v0, v9, s26
	v_bfe_u32 v9, v8, 16, 1
	v_lshrrev_b32_e32 v0, 16, v0
	v_add3_u32 v8, v8, v9, s26
	v_and_or_b32 v20, v8, s24, v0
	ds_read_b32 v0, v13 offset:360
	ds_read_b32 v8, v13 offset:492
	s_waitcnt lgkmcnt(0)
	v_bfe_u32 v9, v0, 16, 1
	v_add3_u32 v0, v0, v9, s26
	v_bfe_u32 v9, v8, 16, 1
	v_lshrrev_b32_e32 v0, 16, v0
	v_add3_u32 v8, v8, v9, s26
	v_and_or_b32 v21, v8, s24, v0
	ds_read_b32 v0, v13 offset:624
	ds_read_b32 v8, v13 offset:756
	s_waitcnt lgkmcnt(0)
	v_bfe_u32 v9, v0, 16, 1
	v_add3_u32 v0, v0, v9, s26
	v_bfe_u32 v9, v8, 16, 1
	v_lshrrev_b32_e32 v0, 16, v0
	v_add3_u32 v8, v8, v9, s26
	v_and_or_b32 v22, v8, s24, v0
	ds_read_b32 v0, v13 offset:888
	ds_read_b32 v8, v13 offset:1020
	s_waitcnt lgkmcnt(0)
	v_bfe_u32 v9, v0, 16, 1
	v_add3_u32 v0, v0, v9, s26
	v_bfe_u32 v9, v8, 16, 1
	v_lshrrev_b32_e32 v0, 16, v0
	v_add3_u32 v8, v8, v9, s26
	v_and_or_b32 v23, v8, s24, v0
	v_or_b32_e32 v0, v19, v16
	v_mul_u32_u24_e32 v0, 0xc00, v0
	v_lshlrev_b32_e32 v0, 1, v0
	v_lshl_add_u64 v[6:7], v[6:7], 0, v[0:1]
	global_store_dwordx4 v[6:7], v[20:23], off
	s_waitcnt lgkmcnt(0)

; #define LDS_WAIT() asm volatile("s_waitcnt lgkmcnt(0)" ::: "memory")
;     ...
;     float tv_[32];
; #pragma unroll
;     for (int i = 0; i < 32; ++i) tv_[i] = W[(size_t)(k0 + 2 * i + (lane >> 5)) * N + n0 + (lane & 31)];
; #pragma unroll
;     for (int i = 0; i < 32; ++i) scr[(2 * i + (lane >> 5)) * 33 + (lane & 31)] = tv_[i];
;     LDS_WAIT(); asm volatile("" ::: "memory");
; __device__ __forceinline__ void convert_range(LAS unsigned char* lds, const Params& p, const int lo, const int hi, const int gw, const int NGW) {
;     ...
;         if (r < 2 * I_IN) { const int l = r / I_IN; r -= l * I_IN; p0_transpose_item(p.in[5] + (size_t)l * DM * NC, DM, NC, (bf16*)(ws + WS_WIN + l * SZ_WIN), scr, r, lane); continue; } r -= 2 * I_IN;
.LBB0_288:
	s_andn2_saveexec_b64 s[40:41], s[40:41]
	s_cbranch_execz .LBB0_281
	v_mul_hi_i32 v0, v8, s14
	v_lshrrev_b32_e32 v6, 31, v0
	v_ashrrev_i32_e32 v0, 12, v0
	v_add_u32_e32 v9, v0, v6
	v_readlane_b32 s60, v251, 21
	v_mul_i32_i24_e32 v0, 0xffffd800, v9
	s_movk_i32 s6, 0x5800
	v_readlane_b32 s70, v251, 31
	v_readlane_b32 s71, v251, 32
	v_add3_u32 v0, v0, v18, s6
	s_mov_b32 s6, 0x5000000
	v_mov_b64_e32 v[6:7], s[70:71]
	v_mad_i64_i32 v[20:21], s[6:7], v9, s6, v[6:7]
	v_mul_hi_i32 v6, v0, s14
	v_lshrrev_b32_e32 v7, 31, v6
	v_ashrrev_i32_e32 v6, 7, v6
	v_add_u32_e32 v6, v6, v7
	v_mul_i32_i24_e32 v7, 0x140, v6
	v_sub_u32_e32 v0, v0, v7
	v_lshlrev_b32_e32 v8, 6, v6
	v_lshlrev_b32_e32 v6, 5, v0
	v_ashrrev_i32_e32 v7, 31, v6
	v_lshl_add_u64 v[20:21], v[6:7], 2, v[20:21]
	v_lshlrev_b32_e32 v0, 2, v2
	v_or_b32_e32 v19, v8, v10
	v_lshl_add_u64 v[20:21], v[20:21], 0, v[0:1]
	v_mad_i64_i32 v[22:23], s[6:7], v19, s23, v[20:21]
	v_or_b32_e32 v7, 2, v19
	global_load_dword v0, v[22:23], off
	v_mad_i64_i32 v[22:23], s[6:7], v7, s23, v[20:21]
	global_load_dword v7, v[22:23], off
	v_or_b32_e32 v22, 4, v19
	v_mad_i64_i32 v[22:23], s[6:7], v22, s23, v[20:21]
	s_waitcnt lgkmcnt(0)
	global_load_dword v24, v[22:23], off
	v_or_b32_e32 v22, 6, v19
	v_mad_i64_i32 v[22:23], s[6:7], v22, s23, v[20:21]
	global_load_dword v25, v[22:23], off
	v_or_b32_e32 v22, 8, v19
	v_mad_i64_i32 v[22:23], s[6:7], v22, s23, v[20:21]
	global_load_dword v26, v[22:23], off
	v_or_b32_e32 v22, 10, v19
	v_mad_i64_i32 v[22:23], s[6:7], v22, s23, v[20:21]
	global_load_dword v27, v[22:23], off
	v_or_b32_e32 v22, 12, v19
	v_mad_i64_i32 v[22:23], s[6:7], v22, s23, v[20:21]
	global_load_dword v28, v[22:23], off
	v_or_b32_e32 v22, 14, v19
	v_mad_i64_i32 v[22:23], s[6:7], v22, s23, v[20:21]
	global_load_dword v29, v[22:23], off
	v_or_b32_e32 v22, 16, v19
	v_mad_i64_i32 v[22:23], s[6:7], v22, s23, v[20:21]
	global_load_dword v30, v[22:23], off
	v_or_b32_e32 v22, 18, v19
	v_mad_i64_i32 v[22:23], s[6:7], v22, s23, v[20:21]
	global_load_dword v31, v[22:23], off
	v_or_b32_e32 v22, 20, v19
	v_mad_i64_i32 v[22:23], s[6:7], v22, s23, v[20:21]
	global_load_dword v32, v[22:23], off
	v_or_b32_e32 v22, 22, v19
	v_mad_i64_i32 v[22:23], s[6:7], v22, s23, v[20:21]
	global_load_dword v33, v[22:23], off
	v_or_b32_e32 v22, 24, v19
	v_mad_i64_i32 v[22:23], s[6:7], v22, s23, v[20:21]
	global_load_dword v34, v[22:23], off
	v_or_b32_e32 v22, 26, v19
	v_mad_i64_i32 v[22:23], s[6:7], v22, s23, v[20:21]
	global_load_dword v35, v[22:23], off
	v_or_b32_e32 v22, 28, v19
	v_mad_i64_i32 v[22:23], s[6:7], v22, s23, v[20:21]
	global_load_dword v36, v[22:23], off
	v_or_b32_e32 v22, 30, v19
	v_mad_i64_i32 v[22:23], s[6:7], v22, s23, v[20:21]
	global_load_dword v37, v[22:23], off
	v_or_b32_e32 v22, 32, v19
	v_mad_i64_i32 v[22:23], s[6:7], v22, s23, v[20:21]
	global_load_dword v38, v[22:23], off
	v_or_b32_e32 v22, 34, v19
	v_mad_i64_i32 v[22:23], s[6:7], v22, s23, v[20:21]
	global_load_dword v39, v[22:23], off
	v_or_b32_e32 v22, 36, v19
	v_mad_i64_i32 v[22:23], s[6:7], v22, s23, v[20:21]
	global_load_dword v40, v[22:23], off
	v_or_b32_e32 v22, 38, v19
	v_mad_i64_i32 v[22:23], s[6:7], v22, s23, v[20:21]
	global_load_dword v41, v[22:23], off
	v_or_b32_e32 v22, 40, v19
	v_mad_i64_i32 v[22:23], s[6:7], v22, s23, v[20:21]
	global_load_dword v42, v[22:23], off
	v_or_b32_e32 v22, 42, v19
	v_mad_i64_i32 v[22:23], s[6:7], v22, s23, v[20:21]
	global_load_dword v43, v[22:23], off
	v_or_b32_e32 v22, 44, v19
	v_mad_i64_i32 v[22:23], s[6:7], v22, s23, v[20:21]
	global_load_dword v44, v[22:23], off
	v_or_b32_e32 v22, 46, v19
	v_mad_i64_i32 v[22:23], s[6:7], v22, s23, v[20:21]
	global_load_dword v45, v[22:23], off
	v_or_b32_e32 v22, 48, v19
	v_mad_i64_i32 v[22:23], s[6:7], v22, s23, v[20:21]
	global_load_dword v46, v[22:23], off
	v_or_b32_e32 v22, 50, v19
	v_mad_i64_i32 v[22:23], s[6:7], v22, s23, v[20:21]
	global_load_dword v47, v[22:23], off
	v_or_b32_e32 v22, 52, v19
	v_mad_i64_i32 v[22:23], s[6:7], v22, s23, v[20:21]
	global_load_dword v48, v[22:23], off
	v_or_b32_e32 v22, 54, v19
	v_mad_i64_i32 v[22:23], s[6:7], v22, s23, v[20:21]
	global_load_dword v49, v[22:23], off
	v_or_b32_e32 v22, 56, v19
	v_mad_i64_i32 v[22:23], s[6:7], v22, s23, v[20:21]
	global_load_dword v50, v[22:23], off
	v_or_b32_e32 v22, 58, v19
	v_mad_i64_i32 v[22:23], s[6:7], v22, s23, v[20:21]
	global_load_dword v51, v[22:23], off
	v_or_b32_e32 v22, 60, v19
	v_or_b32_e32 v19, 62, v19
	v_mad_i64_i32 v[22:23], s[6:7], v22, s23, v[20:21]
	v_mad_i64_i32 v[20:21], s[6:7], v19, s23, v[20:21]
	global_load_dword v22, v[22:23], off
	s_mov_b32 s6, 0x2800000
	global_load_dword v19, v[20:21], off
	s_waitcnt vmcnt(30)
	ds_write2_b32 v11, v0, v7 offset1:66
	s_waitcnt vmcnt(28)
	ds_write2_b32 v11, v24, v25 offset0:132 offset1:198
	v_add_u32_e32 v0, 0x400, v11
	s_waitcnt vmcnt(26)
	ds_write2_b32 v0, v26, v27 offset0:8 offset1:74
	s_waitcnt vmcnt(24)
	ds_write2_b32 v0, v28, v29 offset0:140 offset1:206
	v_add_u32_e32 v0, 0x800, v11
	s_waitcnt vmcnt(22)
	ds_write2_b32 v0, v30, v31 offset0:16 offset1:82
	s_waitcnt vmcnt(20)
	ds_write2_b32 v0, v32, v33 offset0:148 offset1:214
	v_add_u32_e32 v0, 0xc00, v11
	s_waitcnt vmcnt(18)
	ds_write2_b32 v0, v34, v35 offset0:24 offset1:90
	s_waitcnt vmcnt(16)
	ds_write2_b32 v0, v36, v37 offset0:156 offset1:222
	v_add_u32_e32 v0, 0x1000, v11
	s_waitcnt vmcnt(14)
	ds_write2_b32 v0, v38, v39 offset0:32 offset1:98
	s_waitcnt vmcnt(12)
	ds_write2_b32 v0, v40, v41 offset0:164 offset1:230
	v_add_u32_e32 v0, 0x1400, v11
	s_waitcnt vmcnt(10)
	ds_write2_b32 v0, v42, v43 offset0:40 offset1:106
	s_waitcnt vmcnt(8)
; #define LAS __attribute__((address_space(3)))
; #define LDS_WAIT() asm volatile("s_waitcnt lgkmcnt(0)" ::: "memory")
; __device__ __forceinline__ unsigned pk2(float lo, float hi) { return f2bf(lo) | (f2bf(hi) << 16); }
;     ...
;     for (int i = 0; i < 32; ++i) scr[(2 * i + (lane >> 5)) * 33 + (lane & 31)] = tv_[i];
;     LDS_WAIT(); asm volatile("" ::: "memory");
;     const int c = lane & 7;
; #pragma unroll
;     for (int j = 0; j < 4; ++j) { const int n = (lane >> 3) + 8 * j; const LAS float* s = scr + (8 * c) * 33 + n;
;         v4u o; o.x = pk2(s[0 * 33], s[1 * 33]); o.y = pk2(s[2 * 33], s[3 * 33]); o.z = pk2(s[4 * 33], s[5 * 33]); o.w = pk2(s[6 * 33], s[7 * 33]);
;         *(v4u*)(WT + (size_t)(n0 + n) * ldw + koff + k0 + 8 * c) = o; }
;     LDS_WAIT(); asm volatile("" ::: "memory");
	ds_write2_b32 v0, v44, v45 offset0:172 offset1:238
	v_add_u32_e32 v0, 0x1800, v11
	s_waitcnt vmcnt(6)
	ds_write2_b32 v0, v46, v47 offset0:48 offset1:114
	s_waitcnt vmcnt(4)
	ds_write2_b32 v0, v48, v49 offset0:180 offset1:246
	v_add_u32_e32 v0, 0x1c00, v11
	s_waitcnt vmcnt(2)
	ds_write2_b32 v0, v50, v51 offset0:56 offset1:122
	s_waitcnt vmcnt(0)
	ds_write2_b32 v0, v22, v19 offset0:188 offset1:254
	s_waitcnt lgkmcnt(0)
	v_mov_b64_e32 v[20:21], s[0:1]
	v_mad_i64_i32 v[20:21], s[6:7], v9, s6, v[20:21]
	v_ashrrev_i32_e32 v9, 31, v8
	ds_read_b32 v7, v13
	ds_read_b32 v23, v13 offset:924
	v_lshl_add_u64 v[8:9], v[8:9], 1, v[20:21]
	v_lshlrev_b32_e32 v0, 1, v4
	v_lshl_add_u64 v[8:9], v[8:9], 0, v[0:1]
	ds_read_b32 v0, v13 offset:132
	s_waitcnt lgkmcnt(0)
	v_bfe_u32 v19, v7, 16, 1
	v_add3_u32 v7, v7, v19, s26
	ds_read_b32 v19, v13 offset:264
	v_lshrrev_b32_e32 v7, 16, v7
	v_bfe_u32 v20, v0, 16, 1
	v_add3_u32 v0, v0, v20, s26
	v_and_or_b32 v20, v0, s24, v7
	ds_read_b32 v0, v13 offset:396
	s_waitcnt lgkmcnt(1)
	v_bfe_u32 v7, v19, 16, 1
	v_add3_u32 v7, v19, v7, s26
	ds_read_b32 v19, v13 offset:528
	v_lshrrev_b32_e32 v7, 16, v7
	s_waitcnt lgkmcnt(1)
	v_bfe_u32 v21, v0, 16, 1
	v_add3_u32 v0, v0, v21, s26
	v_and_or_b32 v21, v0, s24, v7
	ds_read_b32 v0, v13 offset:660
	s_waitcnt lgkmcnt(1)
	v_bfe_u32 v7, v19, 16, 1
	v_add3_u32 v7, v19, v7, s26
	ds_read_b32 v19, v13 offset:792
	v_lshrrev_b32_e32 v7, 16, v7
	s_waitcnt lgkmcnt(1)
	v_bfe_u32 v22, v0, 16, 1
	v_add3_u32 v0, v0, v22, s26
	v_and_or_b32 v22, v0, s24, v7
	s_waitcnt lgkmcnt(0)
	v_bfe_u32 v0, v19, 16, 1
	v_or_b32_e32 v24, v6, v12
	v_add3_u32 v0, v19, v0, s26
	v_bfe_u32 v7, v23, 16, 1
	v_ashrrev_i32_e32 v25, 31, v24
	v_lshrrev_b32_e32 v0, 16, v0
	v_add3_u32 v7, v23, v7, s26
	v_lshlrev_b64 v[24:25], 12, v[24:25]
	v_and_or_b32 v23, v7, s24, v0
	v_lshl_add_u64 v[24:25], v[8:9], 0, v[24:25]
	global_store_dwordx4 v[24:25], v[20:23], off
	ds_read_b32 v0, v13 offset:32
	ds_read_b32 v7, v13 offset:164
	ds_read_b32 v23, v13 offset:956
	v_or_b32_e32 v24, v6, v14
	v_ashrrev_i32_e32 v25, 31, v24
	s_waitcnt lgkmcnt(0)
	v_bfe_u32 v19, v0, 16, 1
	v_add3_u32 v0, v0, v19, s26
	ds_read_b32 v19, v13 offset:296
	v_bfe_u32 v20, v7, 16, 1
	v_lshrrev_b32_e32 v0, 16, v0
	v_add3_u32 v7, v7, v20, s26
	v_and_or_b32 v20, v7, s24, v0
	ds_read_b32 v0, v13 offset:428
	s_waitcnt lgkmcnt(0)
	v_bfe_u32 v7, v19, 16, 1
	v_add3_u32 v7, v19, v7, s26
	ds_read_b32 v19, v13 offset:560
	v_lshrrev_b32_e32 v7, 16, v7
	v_bfe_u32 v21, v0, 16, 1
	v_add3_u32 v0, v0, v21, s26
	v_and_or_b32 v21, v0, s24, v7
	ds_read_b32 v0, v13 offset:692
	s_waitcnt lgkmcnt(0)
	v_bfe_u32 v7, v19, 16, 1
	v_add3_u32 v7, v19, v7, s26
	ds_read_b32 v19, v13 offset:824
	v_lshrrev_b32_e32 v7, 16, v7
	v_bfe_u32 v22, v0, 16, 1
	v_add3_u32 v0, v0, v22, s26
	v_and_or_b32 v22, v0, s24, v7
	s_waitcnt lgkmcnt(0)
	v_bfe_u32 v0, v19, 16, 1
	v_add3_u32 v0, v19, v0, s26
	v_bfe_u32 v7, v23, 16, 1
	v_lshrrev_b32_e32 v0, 16, v0
	v_add3_u32 v7, v23, v7, s26
	v_lshlrev_b64 v[24:25], 12, v[24:25]
	v_and_or_b32 v23, v7, s24, v0
	v_lshl_add_u64 v[24:25], v[8:9], 0, v[24:25]
	global_store_dwordx4 v[24:25], v[20:23], off
	ds_read_b32 v0, v13 offset:64
	ds_read_b32 v7, v13 offset:196
	ds_read_b32 v23, v13 offset:988
	v_or_b32_e32 v24, v6, v15
	v_ashrrev_i32_e32 v25, 31, v24
	s_waitcnt lgkmcnt(0)
	v_bfe_u32 v19, v0, 16, 1
	v_add3_u32 v0, v0, v19, s26
	ds_read_b32 v19, v13 offset:328
	v_bfe_u32 v20, v7, 16, 1
	v_lshrrev_b32_e32 v0, 16, v0
	v_add3_u32 v7, v7, v20, s26
	v_and_or_b32 v20, v7, s24, v0
	ds_read_b32 v0, v13 offset:460
	s_waitcnt lgkmcnt(0)
	v_bfe_u32 v7, v19, 16, 1
	v_add3_u32 v7, v19, v7, s26
	ds_read_b32 v19, v13 offset:592
	v_lshrrev_b32_e32 v7, 16, v7
	v_bfe_u32 v21, v0, 16, 1
	v_add3_u32 v0, v0, v21, s26
	v_and_or_b32 v21, v0, s24, v7
	ds_read_b32 v0, v13 offset:724
	s_waitcnt lgkmcnt(0)
	v_bfe_u32 v7, v19, 16, 1
	v_add3_u32 v7, v19, v7, s26
	ds_read_b32 v19, v13 offset:856
	v_lshrrev_b32_e32 v7, 16, v7
	v_bfe_u32 v22, v0, 16, 1
	v_add3_u32 v0, v0, v22, s26
	v_and_or_b32 v22, v0, s24, v7
	s_waitcnt lgkmcnt(0)
	v_bfe_u32 v0, v19, 16, 1
	v_add3_u32 v0, v19, v0, s26
	v_bfe_u32 v7, v23, 16, 1
	v_lshrrev_b32_e32 v0, 16, v0
	v_add3_u32 v7, v23, v7, s26
	v_lshlrev_b64 v[24:25], 12, v[24:25]
	v_and_or_b32 v23, v7, s24, v0
	v_lshl_add_u64 v[24:25], v[8:9], 0, v[24:25]
	global_store_dwordx4 v[24:25], v[20:23], off
	ds_read_b32 v0, v13 offset:96
	ds_read_b32 v7, v13 offset:228
	ds_read_b32 v23, v13 offset:1020
	v_or_b32_e32 v6, v6, v16
	v_readlane_b32 s72, v251, 33
	s_waitcnt lgkmcnt(0)
	v_bfe_u32 v19, v0, 16, 1
	v_add3_u32 v0, v0, v19, s26
	ds_read_b32 v19, v13 offset:360
	v_bfe_u32 v20, v7, 16, 1
	v_lshrrev_b32_e32 v0, 16, v0
	v_add3_u32 v7, v7, v20, s26
	v_and_or_b32 v20, v7, s24, v0
	ds_read_b32 v0, v13 offset:492
	s_waitcnt lgkmcnt(0)
	v_bfe_u32 v7, v19, 16, 1
	v_add3_u32 v7, v19, v7, s26
	ds_read_b32 v19, v13 offset:624
	v_lshrrev_b32_e32 v7, 16, v7
	v_bfe_u32 v21, v0, 16, 1
	v_add3_u32 v0, v0, v21, s26
	v_and_or_b32 v21, v0, s24, v7
	ds_read_b32 v0, v13 offset:756
	s_waitcnt lgkmcnt(0)
	v_bfe_u32 v7, v19, 16, 1
	v_add3_u32 v7, v19, v7, s26
	ds_read_b32 v19, v13 offset:888
	v_lshrrev_b32_e32 v7, 16, v7
	v_bfe_u32 v22, v0, 16, 1
	v_add3_u32 v0, v0, v22, s26
	v_and_or_b32 v22, v0, s24, v7
	s_waitcnt lgkmcnt(0)
	v_bfe_u32 v0, v19, 16, 1
	v_add3_u32 v0, v19, v0, s26
	v_bfe_u32 v7, v23, 16, 1
	v_lshrrev_b32_e32 v0, 16, v0
	v_add3_u32 v7, v23, v7, s26
	v_and_or_b32 v23, v7, s24, v0
	v_ashrrev_i32_e32 v7, 31, v6
	v_lshlrev_b64 v[6:7], 12, v[6:7]
	v_lshl_add_u64 v[6:7], v[8:9], 0, v[6:7]
	global_store_dwordx4 v[6:7], v[20:23], off
	s_waitcnt lgkmcnt(0)
	v_readlane_b32 s73, v251, 34
	v_readlane_b32 s72, v248, 24
	v_readlane_b32 s73, v248, 25
	v_readlane_b32 s61, v251, 22
	v_readlane_b32 s62, v251, 23
	v_readlane_b32 s63, v251, 24
	v_readlane_b32 s64, v251, 25
	v_readlane_b32 s65, v251, 26
	v_readlane_b32 s66, v251, 27
	v_readlane_b32 s67, v251, 28
	v_readlane_b32 s68, v251, 29
	v_readlane_b32 s69, v251, 30
	v_readlane_b32 s74, v251, 35
	v_readlane_b32 s75, v251, 36
	s_branch .LBB0_281

; #define LDS_WAIT() asm volatile("s_waitcnt lgkmcnt(0)" ::: "memory")
;     ...
;     float tv_[32];
; #pragma unroll
;     for (int i = 0; i < 32; ++i) tv_[i] = W[(size_t)(k0 + 2 * i + (lane >> 5)) * N + n0 + (lane & 31)];
; #pragma unroll
;     for (int i = 0; i < 32; ++i) scr[(2 * i + (lane >> 5)) * 33 + (lane & 31)] = tv_[i];
;     LDS_WAIT(); asm volatile("" ::: "memory");
; __device__ __forceinline__ void convert_range(LAS unsigned char* lds, const Params& p, const int lo, const int hi, const int gw, const int NGW) {
;     ...
;         if (r < 2 * I_OUT) { const int l = r / I_OUT; r -= l * I_OUT; p0_transpose_item(p.in[18] + (size_t)l * DM * DM, DM, DM, (bf16*)(ws + WS_WOUT + l * SZ_WOUT), scr, r, lane); continue; } r -= 2 * I_OUT;
.LBB0_293:
	v_add_u32_e32 v8, 0x6800, v5
	s_movk_i32 s3, 0x4fff
	v_cmp_lt_i32_e32 vcc, s3, v8
	s_and_saveexec_b64 s[6:7], vcc
	s_xor_b64 s[42:43], exec, s[6:7]
	s_cbranch_execz .LBB0_303
	s_movk_i32 s3, 0x57ff
	v_cmp_lt_u32_e32 vcc, s3, v8
	s_and_saveexec_b64 s[6:7], vcc
	s_xor_b64 s[44:45], exec, s[6:7]
	s_cbranch_execz .LBB0_300
	v_and_b32_e32 v0, 0x7c0, v8
	s_movk_i32 s3, 0x67ff
	v_or_b32_e32 v6, v0, v14
	v_cmp_lt_u32_e32 vcc, s3, v8
	v_and_b32_e32 v7, 0x7e0, v21
	v_lshlrev_b32_e32 v8, 11, v6
	v_lshlrev_b32_e32 v6, 1, v0
	v_lshlrev_b32_e32 v12, 2, v7
	v_lshlrev_b32_e32 v10, 2, v8
	s_waitcnt lgkmcnt(0)
	v_or_b32_e32 v25, v7, v16
	v_or_b32_e32 v24, v7, v18
	v_or_b32_e32 v23, v7, v19
	v_or_b32_e32 v22, v7, v20
	s_and_saveexec_b64 s[6:7], vcc
	s_xor_b64 s[46:47], exec, s[6:7]
	s_cbranch_execz .LBB0_297
	v_lshrrev_b32_e32 v0, 11, v5
	v_readlane_b32 s68, v251, 9
	v_lshlrev_b64 v[8:9], 24, v[0:1]
	v_readlane_b32 s72, v251, 13
	v_readlane_b32 s73, v251, 14
	v_mov_b32_e32 v13, v1
	v_mov_b32_e32 v11, v1
	v_lshl_add_u64 v[26:27], s[72:73], 0, v[8:9]
	v_lshlrev_b64 v[8:9], 23, v[0:1]
	v_lshl_add_u64 v[12:13], v[26:27], 0, v[12:13]
	v_lshlrev_b32_e32 v0, 2, v2
	v_lshl_add_u64 v[12:13], v[12:13], 0, v[0:1]
	v_lshl_add_u64 v[10:11], v[12:13], 0, v[10:11]
	v_add_co_u32_e32 v12, vcc, s22, v10
	s_mov_b32 s3, 0x8000
	s_nop 0
	v_addc_co_u32_e32 v13, vcc, 0, v11, vcc
	global_load_dword v0, v[10:11], off
	global_load_dword v7, v[12:13], off
	v_add_co_u32_e32 v12, vcc, s3, v10
	s_mov_b32 s3, 0xc000
	s_nop 0
	v_addc_co_u32_e32 v13, vcc, 0, v11, vcc
	global_load_dword v26, v[12:13], off
	v_add_co_u32_e32 v12, vcc, s3, v10
	s_mov_b32 s3, 0x14000
	s_nop 0
	v_addc_co_u32_e32 v13, vcc, 0, v11, vcc
	global_load_dword v27, v[12:13], off
	v_add_co_u32_e32 v12, vcc, s15, v10
	v_lshl_add_u64 v[8:9], s[18:19], 0, v[8:9]
	s_nop 0
	v_addc_co_u32_e32 v13, vcc, 0, v11, vcc
	global_load_dword v28, v[12:13], off
	v_add_co_u32_e32 v12, vcc, s3, v10
	s_mov_b32 s3, 0x18000
	s_nop 0
	v_addc_co_u32_e32 v13, vcc, 0, v11, vcc
	global_load_dword v29, v[12:13], off
	v_add_co_u32_e32 v12, vcc, s3, v10
	s_mov_b32 s3, 0x1c000
	s_nop 0
	v_addc_co_u32_e32 v13, vcc, 0, v11, vcc
	global_load_dword v30, v[12:13], off
	v_add_co_u32_e32 v12, vcc, s3, v10
	s_mov_b32 s3, 0x20000
	s_nop 0
	v_addc_co_u32_e32 v13, vcc, 0, v11, vcc
	global_load_dword v31, v[12:13], off
	v_add_co_u32_e32 v12, vcc, s3, v10
	s_mov_b32 s3, 0x24000
	s_nop 0
	v_addc_co_u32_e32 v13, vcc, 0, v11, vcc
	global_load_dword v32, v[12:13], off
	v_add_co_u32_e32 v12, vcc, s3, v10
	s_mov_b32 s3, 0x28000
	s_nop 0
	v_addc_co_u32_e32 v13, vcc, 0, v11, vcc
	global_load_dword v33, v[12:13], off
	v_add_co_u32_e32 v12, vcc, s3, v10
	s_mov_b32 s3, 0x2c000
	s_nop 0
	v_addc_co_u32_e32 v13, vcc, 0, v11, vcc
	global_load_dword v34, v[12:13], off
	v_add_co_u32_e32 v12, vcc, s3, v10
	s_mov_b32 s3, 0x30000
	s_nop 0
	v_addc_co_u32_e32 v13, vcc, 0, v11, vcc
	global_load_dword v35, v[12:13], off
	v_add_co_u32_e32 v12, vcc, s3, v10
	s_mov_b32 s3, 0x34000
	s_nop 0
	v_addc_co_u32_e32 v13, vcc, 0, v11, vcc
	global_load_dword v36, v[12:13], off
	v_add_co_u32_e32 v12, vcc, s3, v10
	s_mov_b32 s3, 0x38000
	s_nop 0
	v_addc_co_u32_e32 v13, vcc, 0, v11, vcc
	global_load_dword v37, v[12:13], off
	v_add_co_u32_e32 v12, vcc, s3, v10
	s_mov_b32 s3, 0x3c000
	s_nop 0
	v_addc_co_u32_e32 v13, vcc, 0, v11, vcc
	global_load_dword v38, v[12:13], off
	v_add_co_u32_e32 v12, vcc, s3, v10
	s_mov_b32 s3, 0x44000
	s_nop 0
	v_addc_co_u32_e32 v13, vcc, 0, v11, vcc
	global_load_dword v39, v[12:13], off
	v_add_co_u32_e32 v12, vcc, s14, v10
	v_readlane_b32 s72, v248, 24
	s_nop 0
	v_addc_co_u32_e32 v13, vcc, 0, v11, vcc
	global_load_dword v40, v[12:13], off
	v_add_co_u32_e32 v12, vcc, s3, v10
	s_mov_b32 s3, 0x48000
	s_nop 0
	v_addc_co_u32_e32 v13, vcc, 0, v11, vcc
	global_load_dword v41, v[12:13], off
	v_add_co_u32_e32 v12, vcc, s3, v10
	s_mov_b32 s3, 0x4c000
	s_nop 0
	v_addc_co_u32_e32 v13, vcc, 0, v11, vcc
	global_load_dword v42, v[12:13], off
	v_add_co_u32_e32 v12, vcc, s3, v10
	s_mov_b32 s3, 0x50000
	s_nop 0
	v_addc_co_u32_e32 v13, vcc, 0, v11, vcc
	global_load_dword v43, v[12:13], off
	v_add_co_u32_e32 v12, vcc, s3, v10
	s_mov_b32 s3, 0x54000
	s_nop 0
	v_addc_co_u32_e32 v13, vcc, 0, v11, vcc
	global_load_dword v44, v[12:13], off
	v_add_co_u32_e32 v12, vcc, s3, v10
	s_mov_b32 s3, 0x58000
	s_nop 0
	v_addc_co_u32_e32 v13, vcc, 0, v11, vcc
	global_load_dword v45, v[12:13], off
	v_add_co_u32_e32 v12, vcc, s3, v10
	s_mov_b32 s3, 0x5c000
	s_nop 0
	v_addc_co_u32_e32 v13, vcc, 0, v11, vcc
	global_load_dword v46, v[12:13], off
	v_add_co_u32_e32 v12, vcc, s3, v10
	s_mov_b32 s3, 0x60000
	s_nop 0
	v_addc_co_u32_e32 v13, vcc, 0, v11, vcc
	global_load_dword v47, v[12:13], off
	v_add_co_u32_e32 v12, vcc, s3, v10
	s_mov_b32 s3, 0x64000
	s_nop 0
	v_addc_co_u32_e32 v13, vcc, 0, v11, vcc
	global_load_dword v48, v[12:13], off
	v_add_co_u32_e32 v12, vcc, s3, v10
	s_mov_b32 s3, 0x68000
	s_nop 0
	v_addc_co_u32_e32 v13, vcc, 0, v11, vcc
	global_load_dword v49, v[12:13], off
	v_add_co_u32_e32 v12, vcc, s3, v10
	s_mov_b32 s3, 0x6c000
	s_nop 0
	v_addc_co_u32_e32 v13, vcc, 0, v11, vcc
	global_load_dword v50, v[12:13], off
	v_add_co_u32_e32 v12, vcc, s3, v10
	s_mov_b32 s3, 0x70000
	s_nop 0
	v_addc_co_u32_e32 v13, vcc, 0, v11, vcc
	global_load_dword v51, v[12:13], off
	v_add_co_u32_e32 v12, vcc, s3, v10
	s_mov_b32 s3, 0x74000
	s_nop 0
	v_addc_co_u32_e32 v13, vcc, 0, v11, vcc
	global_load_dword v52, v[12:13], off
	v_add_co_u32_e32 v12, vcc, s3, v10
	s_mov_b32 s3, 0x78000
	s_nop 0
	v_addc_co_u32_e32 v13, vcc, 0, v11, vcc
	global_load_dword v53, v[12:13], off
	v_add_co_u32_e32 v12, vcc, s3, v10
	s_mov_b32 s3, 0x7c000
	s_nop 0
	v_addc_co_u32_e32 v13, vcc, 0, v11, vcc
	v_add_co_u32_e32 v10, vcc, s3, v10
	global_load_dword v12, v[12:13], off
	s_nop 0
	v_addc_co_u32_e32 v11, vcc, 0, v11, vcc
	global_load_dword v10, v[10:11], off
	s_waitcnt vmcnt(30)
; #define LAS __attribute__((address_space(3)))
; #define LDS_WAIT() asm volatile("s_waitcnt lgkmcnt(0)" ::: "memory")
; __device__ __forceinline__ unsigned pk2(float lo, float hi) { return f2bf(lo) | (f2bf(hi) << 16); }
;     ...
;     for (int i = 0; i < 32; ++i) scr[(2 * i + (lane >> 5)) * 33 + (lane & 31)] = tv_[i];
;     LDS_WAIT(); asm volatile("" ::: "memory");
;     const int c = lane & 7;
; #pragma unroll
;     for (int j = 0; j < 4; ++j) { const int n = (lane >> 3) + 8 * j; const LAS float* s = scr + (8 * c) * 33 + n;
;         v4u o; o.x = pk2(s[0 * 33], s[1 * 33]); o.y = pk2(s[2 * 33], s[3 * 33]); o.z = pk2(s[4 * 33], s[5 * 33]); o.w = pk2(s[6 * 33], s[7 * 33]);
;         *(v4u*)(WT + (size_t)(n0 + n) * ldw + koff + k0 + 8 * c) = o; }
;     LDS_WAIT(); asm volatile("" ::: "memory");
	ds_write2_b32 v15, v0, v7 offset1:66
	s_waitcnt vmcnt(28)
	ds_write2_b32 v15, v26, v27 offset0:132 offset1:198
	v_add_u32_e32 v0, 0x400, v15
	s_waitcnt vmcnt(26)
	ds_write2_b32 v0, v28, v29 offset0:8 offset1:74
	s_waitcnt vmcnt(24)
	ds_write2_b32 v0, v30, v31 offset0:140 offset1:206
	v_add_u32_e32 v0, 0x800, v15
	s_waitcnt vmcnt(22)
	ds_write2_b32 v0, v32, v33 offset0:16 offset1:82
	s_waitcnt vmcnt(20)
	ds_write2_b32 v0, v34, v35 offset0:148 offset1:214
	v_add_u32_e32 v0, 0xc00, v15
	s_waitcnt vmcnt(18)
	ds_write2_b32 v0, v36, v37 offset0:24 offset1:90
	s_waitcnt vmcnt(16)
	ds_write2_b32 v0, v38, v39 offset0:156 offset1:222
	v_add_u32_e32 v0, 0x1000, v15
	s_waitcnt vmcnt(14)
	ds_write2_b32 v0, v40, v41 offset0:32 offset1:98
	s_waitcnt vmcnt(12)
	ds_write2_b32 v0, v42, v43 offset0:164 offset1:230
	v_add_u32_e32 v0, 0x1400, v15
	s_waitcnt vmcnt(10)
	ds_write2_b32 v0, v44, v45 offset0:40 offset1:106
	s_waitcnt vmcnt(8)
	ds_write2_b32 v0, v46, v47 offset0:172 offset1:238
	v_add_u32_e32 v0, 0x1800, v15
	s_waitcnt vmcnt(6)
	ds_write2_b32 v0, v48, v49 offset0:48 offset1:114
	s_waitcnt vmcnt(4)
	ds_write2_b32 v0, v50, v51 offset0:180 offset1:246
	v_add_u32_e32 v0, 0x1c00, v15
	s_waitcnt vmcnt(2)
	ds_write2_b32 v0, v52, v53 offset0:56 offset1:122
	s_waitcnt vmcnt(0)
	ds_write2_b32 v0, v12, v10 offset0:188 offset1:254
	s_waitcnt lgkmcnt(0)
	v_mov_b32_e32 v7, v1
	v_lshl_add_u64 v[6:7], v[8:9], 0, v[6:7]
	v_lshlrev_b32_e32 v0, 1, v4
	v_lshl_add_u64 v[6:7], v[6:7], 0, v[0:1]
	ds_read_b32 v0, v17
	ds_read_b32 v8, v17 offset:132
	v_readlane_b32 s69, v251, 10
	v_readlane_b32 s70, v251, 11
	v_readlane_b32 s71, v251, 12
	s_waitcnt lgkmcnt(0)
	v_bfe_u32 v9, v0, 16, 1
	v_add3_u32 v0, v0, v9, s26
	v_bfe_u32 v9, v8, 16, 1
	v_lshrrev_b32_e32 v0, 16, v0
	v_add3_u32 v8, v8, v9, s26
	v_and_or_b32 v8, v8, s24, v0
	ds_read_b32 v0, v17 offset:264
	ds_read_b32 v9, v17 offset:396
	v_readlane_b32 s74, v251, 15
	v_readlane_b32 s75, v251, 16
	v_readlane_b32 s73, v248, 25
	s_waitcnt lgkmcnt(1)
	v_bfe_u32 v10, v0, 16, 1
	v_add3_u32 v0, v0, v10, s26
	s_waitcnt lgkmcnt(0)
	v_bfe_u32 v10, v9, 16, 1
	v_lshrrev_b32_e32 v0, 16, v0
	v_add3_u32 v9, v9, v10, s26
	v_and_or_b32 v9, v9, s24, v0
	ds_read_b32 v0, v17 offset:528
	ds_read_b32 v10, v17 offset:660
	s_waitcnt lgkmcnt(1)
	v_bfe_u32 v11, v0, 16, 1
	v_add3_u32 v0, v0, v11, s26
	s_waitcnt lgkmcnt(0)
	v_bfe_u32 v11, v10, 16, 1
	v_lshrrev_b32_e32 v0, 16, v0
	v_add3_u32 v10, v10, v11, s26
	v_and_or_b32 v10, v10, s24, v0
	ds_read_b32 v0, v17 offset:792
	ds_read_b32 v11, v17 offset:924
	s_waitcnt lgkmcnt(1)
	v_bfe_u32 v12, v0, 16, 1
	v_add3_u32 v0, v0, v12, s26
	s_waitcnt lgkmcnt(0)
	v_bfe_u32 v12, v11, 16, 1
	v_lshrrev_b32_e32 v0, 16, v0
	v_add3_u32 v11, v11, v12, s26
	v_and_or_b32 v11, v11, s24, v0
	v_lshlrev_b32_e32 v0, 12, v25
	v_lshl_add_u64 v[12:13], v[6:7], 0, v[0:1]
	global_store_dwordx4 v[12:13], v[8:11], off
	ds_read_b32 v0, v17 offset:32
	ds_read_b32 v8, v17 offset:164
	s_waitcnt lgkmcnt(0)
	v_bfe_u32 v9, v0, 16, 1
	v_add3_u32 v0, v0, v9, s26
	v_bfe_u32 v9, v8, 16, 1
	v_lshrrev_b32_e32 v0, 16, v0
	v_add3_u32 v8, v8, v9, s26
	v_and_or_b32 v8, v8, s24, v0
	ds_read_b32 v0, v17 offset:296
	ds_read_b32 v9, v17 offset:428
	s_waitcnt lgkmcnt(0)
	v_bfe_u32 v10, v0, 16, 1
	v_add3_u32 v0, v0, v10, s26
	v_bfe_u32 v10, v9, 16, 1
	v_lshrrev_b32_e32 v0, 16, v0
	v_add3_u32 v9, v9, v10, s26
	v_and_or_b32 v9, v9, s24, v0
	ds_read_b32 v0, v17 offset:560
	ds_read_b32 v10, v17 offset:692
	s_waitcnt lgkmcnt(0)
	v_bfe_u32 v11, v0, 16, 1
	v_add3_u32 v0, v0, v11, s26
	v_bfe_u32 v11, v10, 16, 1
	v_lshrrev_b32_e32 v0, 16, v0
	v_add3_u32 v10, v10, v11, s26
	v_and_or_b32 v10, v10, s24, v0
	ds_read_b32 v0, v17 offset:824
	ds_read_b32 v11, v17 offset:956
	s_waitcnt lgkmcnt(0)
	v_bfe_u32 v12, v0, 16, 1
	v_add3_u32 v0, v0, v12, s26
	v_bfe_u32 v12, v11, 16, 1
	v_lshrrev_b32_e32 v0, 16, v0
	v_add3_u32 v11, v11, v12, s26
	v_and_or_b32 v11, v11, s24, v0
	v_lshlrev_b32_e32 v0, 12, v24
	v_lshl_add_u64 v[12:13], v[6:7], 0, v[0:1]
	global_store_dwordx4 v[12:13], v[8:11], off
	ds_read_b32 v0, v17 offset:64
	ds_read_b32 v8, v17 offset:196
	s_waitcnt lgkmcnt(0)
	v_bfe_u32 v9, v0, 16, 1
	v_add3_u32 v0, v0, v9, s26
	v_bfe_u32 v9, v8, 16, 1
	v_lshrrev_b32_e32 v0, 16, v0
	v_add3_u32 v8, v8, v9, s26
	v_and_or_b32 v8, v8, s24, v0
	ds_read_b32 v0, v17 offset:328
	ds_read_b32 v9, v17 offset:460
	s_waitcnt lgkmcnt(0)
	v_bfe_u32 v10, v0, 16, 1
	v_add3_u32 v0, v0, v10, s26
	v_bfe_u32 v10, v9, 16, 1
	v_lshrrev_b32_e32 v0, 16, v0
	v_add3_u32 v9, v9, v10, s26
	v_and_or_b32 v9, v9, s24, v0
	ds_read_b32 v0, v17 offset:592
	ds_read_b32 v10, v17 offset:724
	s_waitcnt lgkmcnt(0)
	v_bfe_u32 v11, v0, 16, 1
	v_add3_u32 v0, v0, v11, s26
	v_bfe_u32 v11, v10, 16, 1
	v_lshrrev_b32_e32 v0, 16, v0
	v_add3_u32 v10, v10, v11, s26
	v_and_or_b32 v10, v10, s24, v0
	ds_read_b32 v0, v17 offset:856
	ds_read_b32 v11, v17 offset:988
	s_waitcnt lgkmcnt(0)
	v_bfe_u32 v12, v0, 16, 1
	v_add3_u32 v0, v0, v12, s26
	v_bfe_u32 v12, v11, 16, 1
	v_lshrrev_b32_e32 v0, 16, v0
	v_add3_u32 v11, v11, v12, s26
	v_and_or_b32 v11, v11, s24, v0
	v_lshlrev_b32_e32 v0, 12, v23
	v_lshl_add_u64 v[12:13], v[6:7], 0, v[0:1]
	global_store_dwordx4 v[12:13], v[8:11], off
	ds_read_b32 v0, v17 offset:96
	ds_read_b32 v8, v17 offset:228
	s_waitcnt lgkmcnt(0)
	v_bfe_u32 v9, v0, 16, 1
	v_add3_u32 v0, v0, v9, s26
	v_bfe_u32 v9, v8, 16, 1
	v_lshrrev_b32_e32 v0, 16, v0
	v_add3_u32 v8, v8, v9, s26
	v_and_or_b32 v8, v8, s24, v0
	ds_read_b32 v0, v17 offset:360
	ds_read_b32 v9, v17 offset:492
	s_waitcnt lgkmcnt(0)
	v_bfe_u32 v10, v0, 16, 1
	v_add3_u32 v0, v0, v10, s26
	v_bfe_u32 v10, v9, 16, 1
	v_lshrrev_b32_e32 v0, 16, v0
	v_add3_u32 v9, v9, v10, s26
	v_and_or_b32 v9, v9, s24, v0
	ds_read_b32 v0, v17 offset:624
	ds_read_b32 v10, v17 offset:756
	s_waitcnt lgkmcnt(0)
	v_bfe_u32 v11, v0, 16, 1
	v_add3_u32 v0, v0, v11, s26
	v_bfe_u32 v11, v10, 16, 1
	v_lshrrev_b32_e32 v0, 16, v0
	v_add3_u32 v10, v10, v11, s26
	v_and_or_b32 v10, v10, s24, v0
	ds_read_b32 v0, v17 offset:888
	ds_read_b32 v11, v17 offset:1020
	s_waitcnt lgkmcnt(0)
	v_bfe_u32 v12, v0, 16, 1
	v_add3_u32 v0, v0, v12, s26
	v_bfe_u32 v12, v11, 16, 1
	v_lshrrev_b32_e32 v0, 16, v0
	v_add3_u32 v11, v11, v12, s26
	v_and_or_b32 v11, v11, s24, v0
	v_lshlrev_b32_e32 v0, 12, v22
	v_lshl_add_u64 v[6:7], v[6:7], 0, v[0:1]
	global_store_dwordx4 v[6:7], v[8:11], off
	s_waitcnt lgkmcnt(0)
; #define LDS_WAIT() asm volatile("s_waitcnt lgkmcnt(0)" ::: "memory")
;     ...
;     float tv_[32];
; #pragma unroll
;     for (int i = 0; i < 32; ++i) tv_[i] = W[(size_t)(k0 + 2 * i + (lane >> 5)) * N + n0 + (lane & 31)];
; #pragma unroll
;     for (int i = 0; i < 32; ++i) scr[(2 * i + (lane >> 5)) * 33 + (lane & 31)] = tv_[i];
;     LDS_WAIT(); asm volatile("" ::: "memory");
; __device__ __forceinline__ void convert_range(LAS unsigned char* lds, const Params& p, const int lo, const int hi, const int gw, const int NGW) {
;     ...
;         if (r < 2 * I_PB) { const int l = r / I_PB; r -= l * I_PB; p0_transpose_item(p.in[17] + (size_t)l * LW * DM, LW, DM, (bf16*)(ws + WS_WCAT + l * SZ_WCAT), scr, r, lane, KCAT, PW); continue; } r -= 2 * I_PB;
.LBB0_297:
	s_andn2_saveexec_b64 s[46:47], s[46:47]
	s_cbranch_execz .LBB0_299
	v_add_u32_e32 v0, 0x1000, v5
	v_lshrrev_b32_e32 v0, 11, v0
	v_readlane_b32 s68, v251, 9
	v_lshlrev_b64 v[8:9], 24, v[0:1]
	v_readlane_b32 s70, v251, 11
	v_readlane_b32 s71, v251, 12
	s_mov_b32 s3, 0xc00000
	v_mov_b32_e32 v13, v1
	v_lshl_add_u64 v[26:27], s[70:71], 0, v[8:9]
	v_mov_b64_e32 v[8:9], s[0:1]
	v_mad_u64_u32 v[8:9], s[6:7], v0, s3, v[8:9]
	v_lshl_add_u64 v[12:13], v[26:27], 0, v[12:13]
	v_lshlrev_b32_e32 v0, 2, v2
	v_lshl_add_u64 v[12:13], v[12:13], 0, v[0:1]
	v_mov_b32_e32 v11, v1
	v_lshl_add_u64 v[10:11], v[12:13], 0, v[10:11]
	v_add_co_u32_e32 v12, vcc, s22, v10
	s_mov_b32 s3, 0x8000
	s_nop 0
	v_addc_co_u32_e32 v13, vcc, 0, v11, vcc
	global_load_dword v0, v[10:11], off
	global_load_dword v7, v[12:13], off
	v_add_co_u32_e32 v12, vcc, s3, v10
	s_mov_b32 s3, 0xc000
	s_nop 0
	v_addc_co_u32_e32 v13, vcc, 0, v11, vcc
	global_load_dword v26, v[12:13], off
	v_add_co_u32_e32 v12, vcc, s3, v10
	s_mov_b32 s3, 0x14000
	s_nop 0
	v_addc_co_u32_e32 v13, vcc, 0, v11, vcc
	global_load_dword v27, v[12:13], off
	v_add_co_u32_e32 v12, vcc, s15, v10
	s_mov_b64 s[6:7], 0x5000800
	s_nop 0
	v_addc_co_u32_e32 v13, vcc, 0, v11, vcc
	global_load_dword v28, v[12:13], off
	v_add_co_u32_e32 v12, vcc, s3, v10
	s_mov_b32 s3, 0x18000
	s_nop 0
	v_addc_co_u32_e32 v13, vcc, 0, v11, vcc
	global_load_dword v29, v[12:13], off
	v_add_co_u32_e32 v12, vcc, s3, v10
	s_mov_b32 s3, 0x1c000
	s_nop 0
	v_addc_co_u32_e32 v13, vcc, 0, v11, vcc
	global_load_dword v30, v[12:13], off
	v_add_co_u32_e32 v12, vcc, s3, v10
	s_mov_b32 s3, 0x20000
	s_nop 0
	v_addc_co_u32_e32 v13, vcc, 0, v11, vcc
	global_load_dword v31, v[12:13], off
	v_add_co_u32_e32 v12, vcc, s3, v10
	s_mov_b32 s3, 0x24000
	s_nop 0
	v_addc_co_u32_e32 v13, vcc, 0, v11, vcc
	global_load_dword v32, v[12:13], off
	v_add_co_u32_e32 v12, vcc, s3, v10
	s_mov_b32 s3, 0x28000
	s_nop 0
	v_addc_co_u32_e32 v13, vcc, 0, v11, vcc
	global_load_dword v33, v[12:13], off
	v_add_co_u32_e32 v12, vcc, s3, v10
	s_mov_b32 s3, 0x2c000
	s_nop 0
	v_addc_co_u32_e32 v13, vcc, 0, v11, vcc
	global_load_dword v34, v[12:13], off
	v_add_co_u32_e32 v12, vcc, s3, v10
	s_mov_b32 s3, 0x30000
	s_nop 0
	v_addc_co_u32_e32 v13, vcc, 0, v11, vcc
	global_load_dword v35, v[12:13], off
	v_add_co_u32_e32 v12, vcc, s3, v10
	s_mov_b32 s3, 0x34000
	s_nop 0
	v_addc_co_u32_e32 v13, vcc, 0, v11, vcc
	global_load_dword v36, v[12:13], off
	v_add_co_u32_e32 v12, vcc, s3, v10
	s_mov_b32 s3, 0x38000
	s_nop 0
	v_addc_co_u32_e32 v13, vcc, 0, v11, vcc
	global_load_dword v37, v[12:13], off
	v_add_co_u32_e32 v12, vcc, s3, v10
	s_mov_b32 s3, 0x3c000
	s_nop 0
	v_addc_co_u32_e32 v13, vcc, 0, v11, vcc
	global_load_dword v38, v[12:13], off
	v_add_co_u32_e32 v12, vcc, s3, v10
	s_mov_b32 s3, 0x44000
	s_nop 0
	v_addc_co_u32_e32 v13, vcc, 0, v11, vcc
	global_load_dword v39, v[12:13], off
	v_add_co_u32_e32 v12, vcc, s14, v10
	v_readlane_b32 s72, v251, 13
	s_nop 0
	v_addc_co_u32_e32 v13, vcc, 0, v11, vcc
	global_load_dword v40, v[12:13], off
	v_add_co_u32_e32 v12, vcc, s3, v10
	s_mov_b32 s3, 0x48000
	s_nop 0
	v_addc_co_u32_e32 v13, vcc, 0, v11, vcc
	global_load_dword v41, v[12:13], off
	v_add_co_u32_e32 v12, vcc, s3, v10
	s_mov_b32 s3, 0x4c000
	s_nop 0
	v_addc_co_u32_e32 v13, vcc, 0, v11, vcc
	global_load_dword v42, v[12:13], off
	v_add_co_u32_e32 v12, vcc, s3, v10
	s_mov_b32 s3, 0x50000
	s_nop 0
	v_addc_co_u32_e32 v13, vcc, 0, v11, vcc
	global_load_dword v43, v[12:13], off
	v_add_co_u32_e32 v12, vcc, s3, v10
	s_mov_b32 s3, 0x54000
	s_nop 0
	v_addc_co_u32_e32 v13, vcc, 0, v11, vcc
	global_load_dword v44, v[12:13], off
	v_add_co_u32_e32 v12, vcc, s3, v10
	s_mov_b32 s3, 0x58000
	s_nop 0
	v_addc_co_u32_e32 v13, vcc, 0, v11, vcc
	global_load_dword v45, v[12:13], off
	v_add_co_u32_e32 v12, vcc, s3, v10
	s_mov_b32 s3, 0x5c000
	s_nop 0
	v_addc_co_u32_e32 v13, vcc, 0, v11, vcc
	global_load_dword v46, v[12:13], off
	v_add_co_u32_e32 v12, vcc, s3, v10
	s_mov_b32 s3, 0x60000
	s_nop 0
	v_addc_co_u32_e32 v13, vcc, 0, v11, vcc
	global_load_dword v47, v[12:13], off
	v_add_co_u32_e32 v12, vcc, s3, v10
	s_mov_b32 s3, 0x64000
	s_nop 0
	v_addc_co_u32_e32 v13, vcc, 0, v11, vcc
	global_load_dword v48, v[12:13], off
	v_add_co_u32_e32 v12, vcc, s3, v10
	s_mov_b32 s3, 0x68000
	s_nop 0
	v_addc_co_u32_e32 v13, vcc, 0, v11, vcc
	global_load_dword v49, v[12:13], off
	v_add_co_u32_e32 v12, vcc, s3, v10
	s_mov_b32 s3, 0x6c000
	s_nop 0
	v_addc_co_u32_e32 v13, vcc, 0, v11, vcc
	global_load_dword v50, v[12:13], off
	v_add_co_u32_e32 v12, vcc, s3, v10
	s_mov_b32 s3, 0x70000
	s_nop 0
	v_addc_co_u32_e32 v13, vcc, 0, v11, vcc
	global_load_dword v51, v[12:13], off
	v_add_co_u32_e32 v12, vcc, s3, v10
	s_mov_b32 s3, 0x74000
	s_nop 0
	v_addc_co_u32_e32 v13, vcc, 0, v11, vcc
	global_load_dword v52, v[12:13], off
	v_add_co_u32_e32 v12, vcc, s3, v10
	s_mov_b32 s3, 0x78000
	s_nop 0
	v_addc_co_u32_e32 v13, vcc, 0, v11, vcc
	global_load_dword v53, v[12:13], off
	v_add_co_u32_e32 v12, vcc, s3, v10
	s_mov_b32 s3, 0x7c000
	s_nop 0
	v_addc_co_u32_e32 v13, vcc, 0, v11, vcc
	v_add_co_u32_e32 v10, vcc, s3, v10
	global_load_dword v12, v[12:13], off
	s_nop 0
	v_addc_co_u32_e32 v11, vcc, 0, v11, vcc
	global_load_dword v10, v[10:11], off
	s_waitcnt vmcnt(30)
	ds_write2_b32 v15, v0, v7 offset1:66
	s_waitcnt vmcnt(28)
	ds_write2_b32 v15, v26, v27 offset0:132 offset1:198
	v_add_u32_e32 v0, 0x400, v15
	s_waitcnt vmcnt(26)
	ds_write2_b32 v0, v28, v29 offset0:8 offset1:74
	s_waitcnt vmcnt(24)
	ds_write2_b32 v0, v30, v31 offset0:140 offset1:206
	v_add_u32_e32 v0, 0x800, v15
	s_waitcnt vmcnt(22)
	ds_write2_b32 v0, v32, v33 offset0:16 offset1:82
	s_waitcnt vmcnt(20)
; #define LAS __attribute__((address_space(3)))
; #define LDS_WAIT() asm volatile("s_waitcnt lgkmcnt(0)" ::: "memory")
; __device__ __forceinline__ unsigned pk2(float lo, float hi) { return f2bf(lo) | (f2bf(hi) << 16); }
;     ...
;     for (int i = 0; i < 32; ++i) scr[(2 * i + (lane >> 5)) * 33 + (lane & 31)] = tv_[i];
;     LDS_WAIT(); asm volatile("" ::: "memory");
;     const int c = lane & 7;
; #pragma unroll
;     for (int j = 0; j < 4; ++j) { const int n = (lane >> 3) + 8 * j; const LAS float* s = scr + (8 * c) * 33 + n;
;         v4u o; o.x = pk2(s[0 * 33], s[1 * 33]); o.y = pk2(s[2 * 33], s[3 * 33]); o.z = pk2(s[4 * 33], s[5 * 33]); o.w = pk2(s[6 * 33], s[7 * 33]);
;         *(v4u*)(WT + (size_t)(n0 + n) * ldw + koff + k0 + 8 * c) = o; }
;     LDS_WAIT(); asm volatile("" ::: "memory");
	ds_write2_b32 v0, v34, v35 offset0:148 offset1:214
	v_add_u32_e32 v0, 0xc00, v15
	s_waitcnt vmcnt(18)
	ds_write2_b32 v0, v36, v37 offset0:24 offset1:90
	s_waitcnt vmcnt(16)
	ds_write2_b32 v0, v38, v39 offset0:156 offset1:222
	v_add_u32_e32 v0, 0x1000, v15
	s_waitcnt vmcnt(14)
	ds_write2_b32 v0, v40, v41 offset0:32 offset1:98
	s_waitcnt vmcnt(12)
	ds_write2_b32 v0, v42, v43 offset0:164 offset1:230
	v_add_u32_e32 v0, 0x1400, v15
	s_waitcnt vmcnt(10)
	ds_write2_b32 v0, v44, v45 offset0:40 offset1:106
	s_waitcnt vmcnt(8)
	ds_write2_b32 v0, v46, v47 offset0:172 offset1:238
	v_add_u32_e32 v0, 0x1800, v15
	s_waitcnt vmcnt(6)
	ds_write2_b32 v0, v48, v49 offset0:48 offset1:114
	s_waitcnt vmcnt(4)
	ds_write2_b32 v0, v50, v51 offset0:180 offset1:246
	v_add_u32_e32 v0, 0x1c00, v15
	s_waitcnt vmcnt(2)
	ds_write2_b32 v0, v52, v53 offset0:56 offset1:122
	s_waitcnt vmcnt(0)
	ds_write2_b32 v0, v12, v10 offset0:188 offset1:254
	s_waitcnt lgkmcnt(0)
	v_mov_b32_e32 v7, v1
	v_lshl_add_u64 v[6:7], v[8:9], 0, v[6:7]
	v_lshlrev_b32_e32 v0, 1, v4
	v_lshl_add_u64 v[6:7], v[6:7], 0, v[0:1]
	ds_read_b32 v0, v17
	ds_read_b32 v8, v17 offset:132
	v_lshl_add_u64 v[6:7], v[6:7], 0, s[6:7]
	v_readlane_b32 s73, v251, 14
	v_readlane_b32 s72, v248, 24
	s_waitcnt lgkmcnt(0)
	v_bfe_u32 v9, v0, 16, 1
	v_add3_u32 v0, v0, v9, s26
	v_bfe_u32 v9, v8, 16, 1
	v_lshrrev_b32_e32 v0, 16, v0
	v_add3_u32 v8, v8, v9, s26
	v_and_or_b32 v8, v8, s24, v0
	ds_read_b32 v0, v17 offset:264
	ds_read_b32 v9, v17 offset:396
	v_readlane_b32 s73, v248, 25
	v_readlane_b32 s69, v251, 10
	v_readlane_b32 s74, v251, 15
	s_waitcnt lgkmcnt(1)
	v_bfe_u32 v10, v0, 16, 1
	v_add3_u32 v0, v0, v10, s26
	s_waitcnt lgkmcnt(0)
	v_bfe_u32 v10, v9, 16, 1
	v_lshrrev_b32_e32 v0, 16, v0
	v_add3_u32 v9, v9, v10, s26
	v_and_or_b32 v9, v9, s24, v0
	ds_read_b32 v0, v17 offset:528
	ds_read_b32 v10, v17 offset:660
	v_readlane_b32 s75, v251, 16
	s_waitcnt lgkmcnt(1)
	v_bfe_u32 v11, v0, 16, 1
	v_add3_u32 v0, v0, v11, s26
	s_waitcnt lgkmcnt(0)
	v_bfe_u32 v11, v10, 16, 1
	v_lshrrev_b32_e32 v0, 16, v0
	v_add3_u32 v10, v10, v11, s26
	v_and_or_b32 v10, v10, s24, v0
	ds_read_b32 v0, v17 offset:792
	ds_read_b32 v11, v17 offset:924
	s_waitcnt lgkmcnt(1)
	v_bfe_u32 v12, v0, 16, 1
	v_add3_u32 v0, v0, v12, s26
	s_waitcnt lgkmcnt(0)
	v_bfe_u32 v12, v11, 16, 1
	v_lshrrev_b32_e32 v0, 16, v0
	v_add3_u32 v11, v11, v12, s26
	v_and_or_b32 v11, v11, s24, v0
	v_mul_u32_u24_e32 v0, 0xc00, v25
	v_lshlrev_b32_e32 v0, 1, v0
	v_lshl_add_u64 v[12:13], v[6:7], 0, v[0:1]
	global_store_dwordx4 v[12:13], v[8:11], off
	ds_read_b32 v0, v17 offset:32
	ds_read_b32 v8, v17 offset:164
	s_waitcnt lgkmcnt(0)
	v_bfe_u32 v9, v0, 16, 1
	v_add3_u32 v0, v0, v9, s26
	v_bfe_u32 v9, v8, 16, 1
	v_lshrrev_b32_e32 v0, 16, v0
	v_add3_u32 v8, v8, v9, s26
	v_and_or_b32 v8, v8, s24, v0
	ds_read_b32 v0, v17 offset:296
	ds_read_b32 v9, v17 offset:428
	s_waitcnt lgkmcnt(0)
	v_bfe_u32 v10, v0, 16, 1
	v_add3_u32 v0, v0, v10, s26
	v_bfe_u32 v10, v9, 16, 1
	v_lshrrev_b32_e32 v0, 16, v0
	v_add3_u32 v9, v9, v10, s26
	v_and_or_b32 v9, v9, s24, v0
	ds_read_b32 v0, v17 offset:560
	ds_read_b32 v10, v17 offset:692
	s_waitcnt lgkmcnt(0)
	v_bfe_u32 v11, v0, 16, 1
	v_add3_u32 v0, v0, v11, s26
	v_bfe_u32 v11, v10, 16, 1
	v_lshrrev_b32_e32 v0, 16, v0
	v_add3_u32 v10, v10, v11, s26
	v_and_or_b32 v10, v10, s24, v0
	ds_read_b32 v0, v17 offset:824
	ds_read_b32 v11, v17 offset:956
	s_waitcnt lgkmcnt(0)
	v_bfe_u32 v12, v0, 16, 1
	v_add3_u32 v0, v0, v12, s26
	v_bfe_u32 v12, v11, 16, 1
	v_lshrrev_b32_e32 v0, 16, v0
	v_add3_u32 v11, v11, v12, s26
	v_and_or_b32 v11, v11, s24, v0
	v_mul_u32_u24_e32 v0, 0xc00, v24
	v_lshlrev_b32_e32 v0, 1, v0
	v_lshl_add_u64 v[12:13], v[6:7], 0, v[0:1]
	global_store_dwordx4 v[12:13], v[8:11], off
	ds_read_b32 v0, v17 offset:64
	ds_read_b32 v8, v17 offset:196
	s_waitcnt lgkmcnt(0)
	v_bfe_u32 v9, v0, 16, 1
	v_add3_u32 v0, v0, v9, s26
	v_bfe_u32 v9, v8, 16, 1
	v_lshrrev_b32_e32 v0, 16, v0
	v_add3_u32 v8, v8, v9, s26
	v_and_or_b32 v8, v8, s24, v0
	ds_read_b32 v0, v17 offset:328
	ds_read_b32 v9, v17 offset:460
	s_waitcnt lgkmcnt(0)
	v_bfe_u32 v10, v0, 16, 1
	v_add3_u32 v0, v0, v10, s26
	v_bfe_u32 v10, v9, 16, 1
	v_lshrrev_b32_e32 v0, 16, v0
	v_add3_u32 v9, v9, v10, s26
	v_and_or_b32 v9, v9, s24, v0
	ds_read_b32 v0, v17 offset:592
	ds_read_b32 v10, v17 offset:724
	s_waitcnt lgkmcnt(0)
	v_bfe_u32 v11, v0, 16, 1
	v_add3_u32 v0, v0, v11, s26
	v_bfe_u32 v11, v10, 16, 1
	v_lshrrev_b32_e32 v0, 16, v0
	v_add3_u32 v10, v10, v11, s26
	v_and_or_b32 v10, v10, s24, v0
	ds_read_b32 v0, v17 offset:856
	ds_read_b32 v11, v17 offset:988
	s_waitcnt lgkmcnt(0)
	v_bfe_u32 v12, v0, 16, 1
	v_add3_u32 v0, v0, v12, s26
	v_bfe_u32 v12, v11, 16, 1
	v_lshrrev_b32_e32 v0, 16, v0
	v_add3_u32 v11, v11, v12, s26
	v_and_or_b32 v11, v11, s24, v0
	v_mul_u32_u24_e32 v0, 0xc00, v23
	v_lshlrev_b32_e32 v0, 1, v0
	v_lshl_add_u64 v[12:13], v[6:7], 0, v[0:1]
	global_store_dwordx4 v[12:13], v[8:11], off
	ds_read_b32 v0, v17 offset:96
	ds_read_b32 v8, v17 offset:228
	s_waitcnt lgkmcnt(0)
	v_bfe_u32 v9, v0, 16, 1
	v_add3_u32 v0, v0, v9, s26
	v_bfe_u32 v9, v8, 16, 1
	v_lshrrev_b32_e32 v0, 16, v0
	v_add3_u32 v8, v8, v9, s26
	v_and_or_b32 v8, v8, s24, v0
	ds_read_b32 v0, v17 offset:360
	ds_read_b32 v9, v17 offset:492
	s_waitcnt lgkmcnt(0)
	v_bfe_u32 v10, v0, 16, 1
	v_add3_u32 v0, v0, v10, s26
	v_bfe_u32 v10, v9, 16, 1
	v_lshrrev_b32_e32 v0, 16, v0
	v_add3_u32 v9, v9, v10, s26
	v_and_or_b32 v9, v9, s24, v0
	ds_read_b32 v0, v17 offset:624
	ds_read_b32 v10, v17 offset:756
	s_waitcnt lgkmcnt(0)
	v_bfe_u32 v11, v0, 16, 1
	v_add3_u32 v0, v0, v11, s26
	v_bfe_u32 v11, v10, 16, 1
	v_lshrrev_b32_e32 v0, 16, v0
	v_add3_u32 v10, v10, v11, s26
	v_and_or_b32 v10, v10, s24, v0
	ds_read_b32 v0, v17 offset:888
	ds_read_b32 v11, v17 offset:1020
	s_waitcnt lgkmcnt(0)
	v_bfe_u32 v12, v0, 16, 1
	v_add3_u32 v0, v0, v12, s26
	v_bfe_u32 v12, v11, 16, 1
	v_lshrrev_b32_e32 v0, 16, v0
	v_add3_u32 v11, v11, v12, s26
	v_and_or_b32 v11, v11, s24, v0
	v_mul_u32_u24_e32 v0, 0xc00, v22
	v_lshlrev_b32_e32 v0, 1, v0
	v_lshl_add_u64 v[6:7], v[6:7], 0, v[0:1]
	global_store_dwordx4 v[6:7], v[8:11], off
	s_waitcnt lgkmcnt(0)

; #define LDS_WAIT() asm volatile("s_waitcnt lgkmcnt(0)" ::: "memory")
;     ...
;     float tv_[32];
; #pragma unroll
;     for (int i = 0; i < 32; ++i) tv_[i] = W[(size_t)(k0 + 2 * i + (lane >> 5)) * N + n0 + (lane & 31)];
; #pragma unroll
;     for (int i = 0; i < 32; ++i) scr[(2 * i + (lane >> 5)) * 33 + (lane & 31)] = tv_[i];
;     LDS_WAIT(); asm volatile("" ::: "memory");
; __device__ __forceinline__ void convert_range(LAS unsigned char* lds, const Params& p, const int lo, const int hi, const int gw, const int NGW) {
;     ...
;         if (r < 2 * I_PA) { const int l = r / I_PA; r -= l * I_PA; p0_transpose_item(p.in[16] + (size_t)l * PW * DM, PW, DM, (bf16*)(ws + WS_WCAT + l * SZ_WCAT), scr, r, lane, KCAT, 0); continue; } r -= 2 * I_PA;
.LBB0_300:
	s_andn2_saveexec_b64 s[44:45], s[44:45]
	s_cbranch_execz .LBB0_302
	v_add_u32_e32 v0, 0x1800, v5
	v_lshrrev_b32_e32 v0, 10, v0
	v_readlane_b32 s68, v251, 9
	v_lshlrev_b64 v[6:7], 23, v[0:1]
	v_readlane_b32 s69, v251, 10
	s_mov_b32 s3, 0xc00000
	v_and_b32_e32 v10, 0x7e0, v21
	v_lshl_add_u64 v[12:13], s[68:69], 0, v[6:7]
	v_mov_b64_e32 v[6:7], s[38:39]
	v_mad_u64_u32 v[6:7], s[6:7], v0, s3, v[6:7]
	v_and_b32_e32 v11, 0x3c0, v8
	v_lshlrev_b32_e32 v0, 2, v10
	v_or_b32_e32 v22, v11, v14
	v_lshl_add_u64 v[8:9], v[12:13], 0, v[0:1]
	v_lshlrev_b32_e32 v0, 2, v2
	v_lshl_add_u64 v[8:9], v[8:9], 0, v[0:1]
	v_lshlrev_b32_e32 v0, 13, v22
	v_lshl_add_u64 v[8:9], v[8:9], 0, v[0:1]
	v_add_co_u32_e32 v12, vcc, s22, v8
	s_mov_b32 s3, 0x8000
	s_nop 0
	v_addc_co_u32_e32 v13, vcc, 0, v9, vcc
	global_load_dword v0, v[8:9], off
	global_load_dword v22, v[12:13], off
	v_add_co_u32_e32 v12, vcc, s3, v8
	s_mov_b32 s3, 0xc000
	s_nop 0
	v_addc_co_u32_e32 v13, vcc, 0, v9, vcc
	global_load_dword v23, v[12:13], off
	v_add_co_u32_e32 v12, vcc, s3, v8
	s_mov_b32 s3, 0x14000
	s_nop 0
	v_addc_co_u32_e32 v13, vcc, 0, v9, vcc
	s_waitcnt lgkmcnt(0)
	global_load_dword v24, v[12:13], off
	v_add_co_u32_e32 v12, vcc, s15, v8
	v_readlane_b32 s72, v251, 13
	s_nop 0
	v_addc_co_u32_e32 v13, vcc, 0, v9, vcc
	global_load_dword v25, v[12:13], off
	v_add_co_u32_e32 v12, vcc, s3, v8
	s_mov_b32 s3, 0x18000
	s_nop 0
	v_addc_co_u32_e32 v13, vcc, 0, v9, vcc
	global_load_dword v26, v[12:13], off
	v_add_co_u32_e32 v12, vcc, s3, v8
	s_mov_b32 s3, 0x1c000
	s_nop 0
	v_addc_co_u32_e32 v13, vcc, 0, v9, vcc
	global_load_dword v27, v[12:13], off
	v_add_co_u32_e32 v12, vcc, s3, v8
	s_mov_b32 s3, 0x20000
	s_nop 0
	v_addc_co_u32_e32 v13, vcc, 0, v9, vcc
	global_load_dword v28, v[12:13], off
	v_add_co_u32_e32 v12, vcc, s3, v8
	s_mov_b32 s3, 0x24000
	s_nop 0
	v_addc_co_u32_e32 v13, vcc, 0, v9, vcc
	global_load_dword v29, v[12:13], off
	v_add_co_u32_e32 v12, vcc, s3, v8
	s_mov_b32 s3, 0x28000
	s_nop 0
	v_addc_co_u32_e32 v13, vcc, 0, v9, vcc
	global_load_dword v30, v[12:13], off
	v_add_co_u32_e32 v12, vcc, s3, v8
	s_mov_b32 s3, 0x2c000
	s_nop 0
	v_addc_co_u32_e32 v13, vcc, 0, v9, vcc
	global_load_dword v31, v[12:13], off
	v_add_co_u32_e32 v12, vcc, s3, v8
	s_mov_b32 s3, 0x30000
	s_nop 0
	v_addc_co_u32_e32 v13, vcc, 0, v9, vcc
	global_load_dword v32, v[12:13], off
	v_add_co_u32_e32 v12, vcc, s3, v8
	s_mov_b32 s3, 0x34000
	s_nop 0
	v_addc_co_u32_e32 v13, vcc, 0, v9, vcc
	global_load_dword v33, v[12:13], off
	v_add_co_u32_e32 v12, vcc, s3, v8
	s_mov_b32 s3, 0x38000
	s_nop 0
	v_addc_co_u32_e32 v13, vcc, 0, v9, vcc
	global_load_dword v34, v[12:13], off
	v_add_co_u32_e32 v12, vcc, s3, v8
	s_mov_b32 s3, 0x3c000
	s_nop 0
	v_addc_co_u32_e32 v13, vcc, 0, v9, vcc
	global_load_dword v35, v[12:13], off
	v_add_co_u32_e32 v12, vcc, s3, v8
	s_mov_b32 s3, 0x44000
	s_nop 0
	v_addc_co_u32_e32 v13, vcc, 0, v9, vcc
	global_load_dword v36, v[12:13], off
	v_add_co_u32_e32 v12, vcc, s14, v8
	v_readlane_b32 s73, v251, 14
	s_nop 0
	v_addc_co_u32_e32 v13, vcc, 0, v9, vcc
	global_load_dword v37, v[12:13], off
	v_add_co_u32_e32 v12, vcc, s3, v8
	s_mov_b32 s3, 0x48000
	s_nop 0
	v_addc_co_u32_e32 v13, vcc, 0, v9, vcc
	global_load_dword v38, v[12:13], off
	v_add_co_u32_e32 v12, vcc, s3, v8
	s_mov_b32 s3, 0x4c000
	s_nop 0
	v_addc_co_u32_e32 v13, vcc, 0, v9, vcc
	global_load_dword v39, v[12:13], off
	v_add_co_u32_e32 v12, vcc, s3, v8
	s_mov_b32 s3, 0x50000
	s_nop 0
	v_addc_co_u32_e32 v13, vcc, 0, v9, vcc
	global_load_dword v40, v[12:13], off
	v_add_co_u32_e32 v12, vcc, s3, v8
	s_mov_b32 s3, 0x54000
	s_nop 0
	v_addc_co_u32_e32 v13, vcc, 0, v9, vcc
	global_load_dword v41, v[12:13], off
	v_add_co_u32_e32 v12, vcc, s3, v8
	s_mov_b32 s3, 0x58000
	s_nop 0
	v_addc_co_u32_e32 v13, vcc, 0, v9, vcc
	global_load_dword v42, v[12:13], off
	v_add_co_u32_e32 v12, vcc, s3, v8
	s_mov_b32 s3, 0x5c000
	s_nop 0
	v_addc_co_u32_e32 v13, vcc, 0, v9, vcc
	global_load_dword v43, v[12:13], off
	v_add_co_u32_e32 v12, vcc, s3, v8
	s_mov_b32 s3, 0x60000
	s_nop 0
	v_addc_co_u32_e32 v13, vcc, 0, v9, vcc
	global_load_dword v44, v[12:13], off
	v_add_co_u32_e32 v12, vcc, s3, v8
	s_mov_b32 s3, 0x64000
	s_nop 0
	v_addc_co_u32_e32 v13, vcc, 0, v9, vcc
	global_load_dword v45, v[12:13], off
	v_add_co_u32_e32 v12, vcc, s3, v8
	s_mov_b32 s3, 0x68000
	s_nop 0
	v_addc_co_u32_e32 v13, vcc, 0, v9, vcc
	global_load_dword v46, v[12:13], off
	v_add_co_u32_e32 v12, vcc, s3, v8
	s_mov_b32 s3, 0x6c000
	s_nop 0
	v_addc_co_u32_e32 v13, vcc, 0, v9, vcc
	global_load_dword v47, v[12:13], off
	v_add_co_u32_e32 v12, vcc, s3, v8
	s_mov_b32 s3, 0x70000
	s_nop 0
	v_addc_co_u32_e32 v13, vcc, 0, v9, vcc
	global_load_dword v48, v[12:13], off
	v_add_co_u32_e32 v12, vcc, s3, v8
	s_mov_b32 s3, 0x74000
	s_nop 0
	v_addc_co_u32_e32 v13, vcc, 0, v9, vcc
	global_load_dword v49, v[12:13], off
	v_add_co_u32_e32 v12, vcc, s3, v8
	s_mov_b32 s3, 0x78000
	s_nop 0
	v_addc_co_u32_e32 v13, vcc, 0, v9, vcc
	global_load_dword v50, v[12:13], off
	v_add_co_u32_e32 v12, vcc, s3, v8
	s_mov_b32 s3, 0x7c000
	s_nop 0
	v_addc_co_u32_e32 v13, vcc, 0, v9, vcc
	v_add_co_u32_e32 v8, vcc, s3, v8
	global_load_dword v12, v[12:13], off
	s_nop 0
	v_addc_co_u32_e32 v9, vcc, 0, v9, vcc
	global_load_dword v8, v[8:9], off
	s_waitcnt vmcnt(30)
	ds_write2_b32 v15, v0, v22 offset1:66
	s_waitcnt vmcnt(28)
	ds_write2_b32 v15, v23, v24 offset0:132 offset1:198
	v_add_u32_e32 v0, 0x400, v15
	s_waitcnt vmcnt(26)
	ds_write2_b32 v0, v25, v26 offset0:8 offset1:74
	s_waitcnt vmcnt(24)
	ds_write2_b32 v0, v27, v28 offset0:140 offset1:206
	v_add_u32_e32 v0, 0x800, v15
	s_waitcnt vmcnt(22)
	ds_write2_b32 v0, v29, v30 offset0:16 offset1:82
	s_waitcnt vmcnt(20)
; #define LAS __attribute__((address_space(3)))
; #define LDS_WAIT() asm volatile("s_waitcnt lgkmcnt(0)" ::: "memory")
; __device__ __forceinline__ unsigned pk2(float lo, float hi) { return f2bf(lo) | (f2bf(hi) << 16); }
;     ...
;     for (int i = 0; i < 32; ++i) scr[(2 * i + (lane >> 5)) * 33 + (lane & 31)] = tv_[i];
;     LDS_WAIT(); asm volatile("" ::: "memory");
;     const int c = lane & 7;
; #pragma unroll
;     for (int j = 0; j < 4; ++j) { const int n = (lane >> 3) + 8 * j; const LAS float* s = scr + (8 * c) * 33 + n;
;         v4u o; o.x = pk2(s[0 * 33], s[1 * 33]); o.y = pk2(s[2 * 33], s[3 * 33]); o.z = pk2(s[4 * 33], s[5 * 33]); o.w = pk2(s[6 * 33], s[7 * 33]);
;         *(v4u*)(WT + (size_t)(n0 + n) * ldw + koff + k0 + 8 * c) = o; }
;     LDS_WAIT(); asm volatile("" ::: "memory");
	ds_write2_b32 v0, v31, v32 offset0:148 offset1:214
	v_add_u32_e32 v0, 0xc00, v15
	s_waitcnt vmcnt(18)
	ds_write2_b32 v0, v33, v34 offset0:24 offset1:90
	s_waitcnt vmcnt(16)
	ds_write2_b32 v0, v35, v36 offset0:156 offset1:222
	v_add_u32_e32 v0, 0x1000, v15
	s_waitcnt vmcnt(14)
	ds_write2_b32 v0, v37, v38 offset0:32 offset1:98
	s_waitcnt vmcnt(12)
	ds_write2_b32 v0, v39, v40 offset0:164 offset1:230
	v_add_u32_e32 v0, 0x1400, v15
	s_waitcnt vmcnt(10)
	ds_write2_b32 v0, v41, v42 offset0:40 offset1:106
	s_waitcnt vmcnt(8)
	ds_write2_b32 v0, v43, v44 offset0:172 offset1:238
	v_add_u32_e32 v0, 0x1800, v15
	s_waitcnt vmcnt(6)
	ds_write2_b32 v0, v45, v46 offset0:48 offset1:114
	s_waitcnt vmcnt(4)
	ds_write2_b32 v0, v47, v48 offset0:180 offset1:246
	v_add_u32_e32 v0, 0x1c00, v15
	s_waitcnt vmcnt(2)
	ds_write2_b32 v0, v49, v50 offset0:56 offset1:122
	s_waitcnt vmcnt(0)
	ds_write2_b32 v0, v12, v8 offset0:188 offset1:254
	s_waitcnt lgkmcnt(0)
	v_lshlrev_b32_e32 v0, 1, v11
	v_lshl_add_u64 v[6:7], v[6:7], 0, v[0:1]
	v_lshlrev_b32_e32 v0, 1, v4
	v_lshl_add_u64 v[6:7], v[6:7], 0, v[0:1]
	ds_read_b32 v0, v17
	ds_read_b32 v8, v17 offset:132
	v_readlane_b32 s72, v248, 24
	v_readlane_b32 s73, v248, 25
	v_readlane_b32 s70, v251, 11
	s_waitcnt lgkmcnt(0)
	v_bfe_u32 v9, v0, 16, 1
	v_add3_u32 v0, v0, v9, s26
	v_bfe_u32 v9, v8, 16, 1
	v_lshrrev_b32_e32 v0, 16, v0
	v_add3_u32 v8, v8, v9, s26
	v_and_or_b32 v22, v8, s24, v0
	ds_read_b32 v0, v17 offset:264
	ds_read_b32 v8, v17 offset:396
	v_readlane_b32 s71, v251, 12
	v_readlane_b32 s74, v251, 15
	v_readlane_b32 s75, v251, 16
	s_waitcnt lgkmcnt(1)
	v_bfe_u32 v9, v0, 16, 1
	v_add3_u32 v0, v0, v9, s26
	s_waitcnt lgkmcnt(0)
	v_bfe_u32 v9, v8, 16, 1
	v_lshrrev_b32_e32 v0, 16, v0
	v_add3_u32 v8, v8, v9, s26
	v_and_or_b32 v23, v8, s24, v0
	ds_read_b32 v0, v17 offset:528
	ds_read_b32 v8, v17 offset:660
	s_waitcnt lgkmcnt(1)
	v_bfe_u32 v9, v0, 16, 1
	v_add3_u32 v0, v0, v9, s26
	s_waitcnt lgkmcnt(0)
	v_bfe_u32 v9, v8, 16, 1
	v_lshrrev_b32_e32 v0, 16, v0
	v_add3_u32 v8, v8, v9, s26
	v_and_or_b32 v24, v8, s24, v0
	ds_read_b32 v0, v17 offset:792
	ds_read_b32 v8, v17 offset:924
	s_waitcnt lgkmcnt(1)
	v_bfe_u32 v9, v0, 16, 1
	v_add3_u32 v0, v0, v9, s26
	s_waitcnt lgkmcnt(0)
	v_bfe_u32 v9, v8, 16, 1
	v_lshrrev_b32_e32 v0, 16, v0
	v_add3_u32 v8, v8, v9, s26
	v_and_or_b32 v25, v8, s24, v0
	v_or_b32_e32 v0, v10, v16
	v_mul_u32_u24_e32 v0, 0xc00, v0
	v_lshlrev_b32_e32 v0, 1, v0
	v_lshl_add_u64 v[8:9], v[6:7], 0, v[0:1]
	global_store_dwordx4 v[8:9], v[22:25], off
	ds_read_b32 v0, v17 offset:32
	ds_read_b32 v8, v17 offset:164
	s_waitcnt lgkmcnt(0)
	v_bfe_u32 v9, v0, 16, 1
	v_add3_u32 v0, v0, v9, s26
	v_bfe_u32 v9, v8, 16, 1
	v_lshrrev_b32_e32 v0, 16, v0
	v_add3_u32 v8, v8, v9, s26
	v_and_or_b32 v22, v8, s24, v0
	ds_read_b32 v0, v17 offset:296
	ds_read_b32 v8, v17 offset:428
	s_waitcnt lgkmcnt(0)
	v_bfe_u32 v9, v0, 16, 1
	v_add3_u32 v0, v0, v9, s26
	v_bfe_u32 v9, v8, 16, 1
	v_lshrrev_b32_e32 v0, 16, v0
	v_add3_u32 v8, v8, v9, s26
	v_and_or_b32 v23, v8, s24, v0
	ds_read_b32 v0, v17 offset:560
	ds_read_b32 v8, v17 offset:692
	s_waitcnt lgkmcnt(0)
	v_bfe_u32 v9, v0, 16, 1
	v_add3_u32 v0, v0, v9, s26
	v_bfe_u32 v9, v8, 16, 1
	v_lshrrev_b32_e32 v0, 16, v0
	v_add3_u32 v8, v8, v9, s26
	v_and_or_b32 v24, v8, s24, v0
	ds_read_b32 v0, v17 offset:824
	ds_read_b32 v8, v17 offset:956
	s_waitcnt lgkmcnt(0)
	v_bfe_u32 v9, v0, 16, 1
	v_add3_u32 v0, v0, v9, s26
	v_bfe_u32 v9, v8, 16, 1
	v_lshrrev_b32_e32 v0, 16, v0
	v_add3_u32 v8, v8, v9, s26
	v_and_or_b32 v25, v8, s24, v0
	v_or_b32_e32 v0, v10, v18
	v_mul_u32_u24_e32 v0, 0xc00, v0
	v_lshlrev_b32_e32 v0, 1, v0
	v_lshl_add_u64 v[8:9], v[6:7], 0, v[0:1]
	global_store_dwordx4 v[8:9], v[22:25], off
	ds_read_b32 v0, v17 offset:64
	ds_read_b32 v8, v17 offset:196
	s_waitcnt lgkmcnt(0)
	v_bfe_u32 v9, v0, 16, 1
	v_add3_u32 v0, v0, v9, s26
	v_bfe_u32 v9, v8, 16, 1
	v_lshrrev_b32_e32 v0, 16, v0
	v_add3_u32 v8, v8, v9, s26
	v_and_or_b32 v22, v8, s24, v0
	ds_read_b32 v0, v17 offset:328
	ds_read_b32 v8, v17 offset:460
	s_waitcnt lgkmcnt(0)
	v_bfe_u32 v9, v0, 16, 1
	v_add3_u32 v0, v0, v9, s26
	v_bfe_u32 v9, v8, 16, 1
	v_lshrrev_b32_e32 v0, 16, v0
	v_add3_u32 v8, v8, v9, s26
	v_and_or_b32 v23, v8, s24, v0
	ds_read_b32 v0, v17 offset:592
	ds_read_b32 v8, v17 offset:724
	s_waitcnt lgkmcnt(0)
	v_bfe_u32 v9, v0, 16, 1
	v_add3_u32 v0, v0, v9, s26
	v_bfe_u32 v9, v8, 16, 1
	v_lshrrev_b32_e32 v0, 16, v0
	v_add3_u32 v8, v8, v9, s26
	v_and_or_b32 v24, v8, s24, v0
	ds_read_b32 v0, v17 offset:856
	ds_read_b32 v8, v17 offset:988
	s_waitcnt lgkmcnt(0)
	v_bfe_u32 v9, v0, 16, 1
	v_add3_u32 v0, v0, v9, s26
	v_bfe_u32 v9, v8, 16, 1
	v_lshrrev_b32_e32 v0, 16, v0
	v_add3_u32 v8, v8, v9, s26
	v_and_or_b32 v25, v8, s24, v0
	v_or_b32_e32 v0, v10, v19
	v_mul_u32_u24_e32 v0, 0xc00, v0
	v_lshlrev_b32_e32 v0, 1, v0
	v_lshl_add_u64 v[8:9], v[6:7], 0, v[0:1]
	global_store_dwordx4 v[8:9], v[22:25], off
	ds_read_b32 v0, v17 offset:96
	ds_read_b32 v8, v17 offset:228
	s_waitcnt lgkmcnt(0)
	v_bfe_u32 v9, v0, 16, 1
	v_add3_u32 v0, v0, v9, s26
	v_bfe_u32 v9, v8, 16, 1
	v_lshrrev_b32_e32 v0, 16, v0
	v_add3_u32 v8, v8, v9, s26
	v_and_or_b32 v22, v8, s24, v0
	ds_read_b32 v0, v17 offset:360
	ds_read_b32 v8, v17 offset:492
	s_waitcnt lgkmcnt(0)
	v_bfe_u32 v9, v0, 16, 1
	v_add3_u32 v0, v0, v9, s26
	v_bfe_u32 v9, v8, 16, 1
	v_lshrrev_b32_e32 v0, 16, v0
	v_add3_u32 v8, v8, v9, s26
	v_and_or_b32 v23, v8, s24, v0
	ds_read_b32 v0, v17 offset:624
	ds_read_b32 v8, v17 offset:756
	s_waitcnt lgkmcnt(0)
	v_bfe_u32 v9, v0, 16, 1
	v_add3_u32 v0, v0, v9, s26
	v_bfe_u32 v9, v8, 16, 1
	v_lshrrev_b32_e32 v0, 16, v0
	v_add3_u32 v8, v8, v9, s26
	v_and_or_b32 v24, v8, s24, v0
	ds_read_b32 v0, v17 offset:888
	ds_read_b32 v8, v17 offset:1020
	s_waitcnt lgkmcnt(0)
	v_bfe_u32 v9, v0, 16, 1
	v_add3_u32 v0, v0, v9, s26
	v_bfe_u32 v9, v8, 16, 1
	v_lshrrev_b32_e32 v0, 16, v0
	v_add3_u32 v8, v8, v9, s26
	v_and_or_b32 v25, v8, s24, v0
	v_or_b32_e32 v0, v10, v20
	v_mul_u32_u24_e32 v0, 0xc00, v0
	v_lshlrev_b32_e32 v0, 1, v0
	v_lshl_add_u64 v[6:7], v[6:7], 0, v[0:1]
	global_store_dwordx4 v[6:7], v[22:25], off
	s_waitcnt lgkmcnt(0)

; #define LDS_WAIT() asm volatile("s_waitcnt lgkmcnt(0)" ::: "memory")
;     ...
;     float tv_[32];
; #pragma unroll
;     for (int i = 0; i < 32; ++i) tv_[i] = W[(size_t)(k0 + 2 * i + (lane >> 5)) * N + n0 + (lane & 31)];
; #pragma unroll
;     for (int i = 0; i < 32; ++i) scr[(2 * i + (lane >> 5)) * 33 + (lane & 31)] = tv_[i];
;     LDS_WAIT(); asm volatile("" ::: "memory");
; __device__ __forceinline__ void convert_range(LAS unsigned char* lds, const Params& p, const int lo, const int hi, const int gw, const int NGW) {
;     ...
;         if (r < 2 * I_IN) { const int l = r / I_IN; r -= l * I_IN; p0_transpose_item(p.in[5] + (size_t)l * DM * NC, DM, NC, (bf16*)(ws + WS_WIN + l * SZ_WIN), scr, r, lane); continue; } r -= 2 * I_IN;
.LBB0_303:
	s_andn2_saveexec_b64 s[42:43], s[42:43]
	s_cbranch_execz .LBB0_292
	v_mul_hi_i32 v0, v8, s5
	v_lshrrev_b32_e32 v6, 31, v0
	v_ashrrev_i32_e32 v0, 12, v0
	v_add_u32_e32 v9, v0, v6
	v_readlane_b32 s60, v251, 21
	v_mul_i32_i24_e32 v0, 0xffffd800, v9
	s_movk_i32 s3, 0x6800
	v_readlane_b32 s70, v251, 31
	v_readlane_b32 s71, v251, 32
	v_add3_u32 v0, v0, v5, s3
	s_mov_b32 s3, 0x5000000
	v_mov_b64_e32 v[6:7], s[70:71]
	v_mad_i64_i32 v[10:11], s[6:7], v9, s3, v[6:7]
	v_mul_hi_i32 v6, v0, s5
	v_lshrrev_b32_e32 v7, 31, v6
	v_ashrrev_i32_e32 v6, 7, v6
	v_add_u32_e32 v6, v6, v7
	v_mul_i32_i24_e32 v7, 0x140, v6
	v_sub_u32_e32 v0, v0, v7
	v_lshlrev_b32_e32 v8, 6, v6
	v_lshlrev_b32_e32 v6, 5, v0
	v_ashrrev_i32_e32 v7, 31, v6
	v_lshl_add_u64 v[10:11], v[6:7], 2, v[10:11]
	v_lshlrev_b32_e32 v0, 2, v2
	v_or_b32_e32 v22, v8, v14
	v_lshl_add_u64 v[10:11], v[10:11], 0, v[0:1]
	v_mad_i64_i32 v[12:13], s[6:7], v22, s23, v[10:11]
	v_or_b32_e32 v7, 2, v22
	global_load_dword v0, v[12:13], off
	v_mad_i64_i32 v[12:13], s[6:7], v7, s23, v[10:11]
	global_load_dword v7, v[12:13], off
	v_or_b32_e32 v12, 4, v22
	v_mad_i64_i32 v[12:13], s[6:7], v12, s23, v[10:11]
	global_load_dword v23, v[12:13], off
	v_or_b32_e32 v12, 6, v22
	v_mad_i64_i32 v[12:13], s[6:7], v12, s23, v[10:11]
	s_waitcnt lgkmcnt(0)
	global_load_dword v24, v[12:13], off
	v_or_b32_e32 v12, 8, v22
	v_mad_i64_i32 v[12:13], s[6:7], v12, s23, v[10:11]
	global_load_dword v25, v[12:13], off
	v_or_b32_e32 v12, 10, v22
	v_mad_i64_i32 v[12:13], s[6:7], v12, s23, v[10:11]
	global_load_dword v26, v[12:13], off
	v_or_b32_e32 v12, 12, v22
	v_mad_i64_i32 v[12:13], s[6:7], v12, s23, v[10:11]
	global_load_dword v27, v[12:13], off
	v_or_b32_e32 v12, 14, v22
	v_mad_i64_i32 v[12:13], s[6:7], v12, s23, v[10:11]
	global_load_dword v28, v[12:13], off
	v_or_b32_e32 v12, 16, v22
	v_mad_i64_i32 v[12:13], s[6:7], v12, s23, v[10:11]
	global_load_dword v29, v[12:13], off
	v_or_b32_e32 v12, 18, v22
	v_mad_i64_i32 v[12:13], s[6:7], v12, s23, v[10:11]
	global_load_dword v30, v[12:13], off
	v_or_b32_e32 v12, 20, v22
	v_mad_i64_i32 v[12:13], s[6:7], v12, s23, v[10:11]
	global_load_dword v31, v[12:13], off
	v_or_b32_e32 v12, 22, v22
	v_mad_i64_i32 v[12:13], s[6:7], v12, s23, v[10:11]
	global_load_dword v32, v[12:13], off
	v_or_b32_e32 v12, 24, v22
	v_mad_i64_i32 v[12:13], s[6:7], v12, s23, v[10:11]
	global_load_dword v33, v[12:13], off
	v_or_b32_e32 v12, 26, v22
	v_mad_i64_i32 v[12:13], s[6:7], v12, s23, v[10:11]
	global_load_dword v34, v[12:13], off
	v_or_b32_e32 v12, 28, v22
	v_mad_i64_i32 v[12:13], s[6:7], v12, s23, v[10:11]
	global_load_dword v35, v[12:13], off
	v_or_b32_e32 v12, 30, v22
	v_mad_i64_i32 v[12:13], s[6:7], v12, s23, v[10:11]
	global_load_dword v36, v[12:13], off
	v_or_b32_e32 v12, 32, v22
	v_mad_i64_i32 v[12:13], s[6:7], v12, s23, v[10:11]
	global_load_dword v37, v[12:13], off
	v_or_b32_e32 v12, 34, v22
	v_mad_i64_i32 v[12:13], s[6:7], v12, s23, v[10:11]
	global_load_dword v38, v[12:13], off
	v_or_b32_e32 v12, 36, v22
	v_mad_i64_i32 v[12:13], s[6:7], v12, s23, v[10:11]
	global_load_dword v39, v[12:13], off
	v_or_b32_e32 v12, 38, v22
	v_mad_i64_i32 v[12:13], s[6:7], v12, s23, v[10:11]
	global_load_dword v40, v[12:13], off
	v_or_b32_e32 v12, 40, v22
	v_mad_i64_i32 v[12:13], s[6:7], v12, s23, v[10:11]
	global_load_dword v41, v[12:13], off
	v_or_b32_e32 v12, 42, v22
	v_mad_i64_i32 v[12:13], s[6:7], v12, s23, v[10:11]
	global_load_dword v42, v[12:13], off
	v_or_b32_e32 v12, 44, v22
	v_mad_i64_i32 v[12:13], s[6:7], v12, s23, v[10:11]
	global_load_dword v43, v[12:13], off
	v_or_b32_e32 v12, 46, v22
	v_mad_i64_i32 v[12:13], s[6:7], v12, s23, v[10:11]
	global_load_dword v44, v[12:13], off
	v_or_b32_e32 v12, 48, v22
	v_mad_i64_i32 v[12:13], s[6:7], v12, s23, v[10:11]
	global_load_dword v45, v[12:13], off
	v_or_b32_e32 v12, 50, v22
	v_mad_i64_i32 v[12:13], s[6:7], v12, s23, v[10:11]
	global_load_dword v46, v[12:13], off
	v_or_b32_e32 v12, 52, v22
	v_mad_i64_i32 v[12:13], s[6:7], v12, s23, v[10:11]
	global_load_dword v47, v[12:13], off
	v_or_b32_e32 v12, 54, v22
	v_mad_i64_i32 v[12:13], s[6:7], v12, s23, v[10:11]
	global_load_dword v48, v[12:13], off
	v_or_b32_e32 v12, 56, v22
	v_mad_i64_i32 v[12:13], s[6:7], v12, s23, v[10:11]
	global_load_dword v49, v[12:13], off
	v_or_b32_e32 v12, 58, v22
	v_mad_i64_i32 v[12:13], s[6:7], v12, s23, v[10:11]
	global_load_dword v50, v[12:13], off
	v_or_b32_e32 v12, 60, v22
	v_mad_i64_i32 v[12:13], s[6:7], v12, s23, v[10:11]
	global_load_dword v12, v[12:13], off
	v_or_b32_e32 v13, 62, v22
	v_mad_i64_i32 v[10:11], s[6:7], v13, s23, v[10:11]
	global_load_dword v13, v[10:11], off
	s_waitcnt vmcnt(30)
	ds_write2_b32 v15, v0, v7 offset1:66
	s_waitcnt vmcnt(28)
	ds_write2_b32 v15, v23, v24 offset0:132 offset1:198
	v_add_u32_e32 v0, 0x400, v15
	s_waitcnt vmcnt(26)
	ds_write2_b32 v0, v25, v26 offset0:8 offset1:74
	s_waitcnt vmcnt(24)
	ds_write2_b32 v0, v27, v28 offset0:140 offset1:206
	v_add_u32_e32 v0, 0x800, v15
	s_waitcnt vmcnt(22)
	ds_write2_b32 v0, v29, v30 offset0:16 offset1:82
	s_waitcnt vmcnt(20)
	ds_write2_b32 v0, v31, v32 offset0:148 offset1:214
	v_add_u32_e32 v0, 0xc00, v15
	s_waitcnt vmcnt(18)
	ds_write2_b32 v0, v33, v34 offset0:24 offset1:90
	s_waitcnt vmcnt(16)
	ds_write2_b32 v0, v35, v36 offset0:156 offset1:222
	v_add_u32_e32 v0, 0x1000, v15
	s_waitcnt vmcnt(14)
	ds_write2_b32 v0, v37, v38 offset0:32 offset1:98
	s_waitcnt vmcnt(12)
	ds_write2_b32 v0, v39, v40 offset0:164 offset1:230
	v_add_u32_e32 v0, 0x1400, v15
	s_waitcnt vmcnt(10)
	ds_write2_b32 v0, v41, v42 offset0:40 offset1:106
	s_waitcnt vmcnt(8)
	ds_write2_b32 v0, v43, v44 offset0:172 offset1:238
	v_add_u32_e32 v0, 0x1800, v15
	s_waitcnt vmcnt(6)
; #define LAS __attribute__((address_space(3)))
; #define LDS_WAIT() asm volatile("s_waitcnt lgkmcnt(0)" ::: "memory")
; __device__ __forceinline__ unsigned pk2(float lo, float hi) { return f2bf(lo) | (f2bf(hi) << 16); }
;     ...
;     for (int i = 0; i < 32; ++i) scr[(2 * i + (lane >> 5)) * 33 + (lane & 31)] = tv_[i];
;     LDS_WAIT(); asm volatile("" ::: "memory");
;     const int c = lane & 7;
; #pragma unroll
;     for (int j = 0; j < 4; ++j) { const int n = (lane >> 3) + 8 * j; const LAS float* s = scr + (8 * c) * 33 + n;
;         v4u o; o.x = pk2(s[0 * 33], s[1 * 33]); o.y = pk2(s[2 * 33], s[3 * 33]); o.z = pk2(s[4 * 33], s[5 * 33]); o.w = pk2(s[6 * 33], s[7 * 33]);
;         *(v4u*)(WT + (size_t)(n0 + n) * ldw + koff + k0 + 8 * c) = o; }
;     LDS_WAIT(); asm volatile("" ::: "memory");
	ds_write2_b32 v0, v45, v46 offset0:48 offset1:114
	s_waitcnt vmcnt(4)
	ds_write2_b32 v0, v47, v48 offset0:180 offset1:246
	v_add_u32_e32 v0, 0x1c00, v15
	s_waitcnt vmcnt(2)
	ds_write2_b32 v0, v49, v50 offset0:56 offset1:122
	s_waitcnt vmcnt(0)
	ds_write2_b32 v0, v12, v13 offset0:188 offset1:254
	v_mov_b64_e32 v[10:11], s[0:1]
	s_mov_b32 s3, 0x2800000
	s_waitcnt lgkmcnt(0)
	v_mad_i64_i32 v[10:11], s[6:7], v9, s3, v[10:11]
	v_ashrrev_i32_e32 v9, 31, v8
	ds_read_b32 v7, v17
	ds_read_b32 v12, v17 offset:528
	ds_read_b32 v22, v17 offset:924
	v_lshl_add_u64 v[8:9], v[8:9], 1, v[10:11]
	v_lshlrev_b32_e32 v0, 1, v4
	v_lshl_add_u64 v[8:9], v[8:9], 0, v[0:1]
	ds_read_b32 v0, v17 offset:132
	ds_read_b32 v11, v17 offset:264
	s_waitcnt lgkmcnt(0)
	v_bfe_u32 v10, v7, 16, 1
	v_add3_u32 v7, v7, v10, s26
	v_lshrrev_b32_e32 v7, 16, v7
	v_bfe_u32 v10, v0, 16, 1
	v_add3_u32 v0, v0, v10, s26
	v_and_or_b32 v10, v0, s24, v7
	ds_read_b32 v0, v17 offset:396
	ds_read_b32 v13, v17 offset:792
	v_bfe_u32 v7, v11, 16, 1
	v_add3_u32 v7, v11, v7, s26
	v_lshrrev_b32_e32 v7, 16, v7
	s_waitcnt lgkmcnt(1)
	v_bfe_u32 v11, v0, 16, 1
	v_add3_u32 v0, v0, v11, s26
	v_and_or_b32 v11, v0, s24, v7
	ds_read_b32 v0, v17 offset:660
	v_bfe_u32 v7, v12, 16, 1
	v_add3_u32 v7, v12, v7, s26
	v_lshrrev_b32_e32 v7, 16, v7
	v_readlane_b32 s72, v251, 33
	s_waitcnt lgkmcnt(0)
	v_bfe_u32 v12, v0, 16, 1
	v_add3_u32 v0, v0, v12, s26
	v_and_or_b32 v12, v0, s24, v7
	v_bfe_u32 v7, v22, 16, 1
	v_bfe_u32 v0, v13, 16, 1
	v_add3_u32 v7, v22, v7, s26
	v_or_b32_e32 v22, v6, v16
	v_add3_u32 v0, v13, v0, s26
	v_ashrrev_i32_e32 v23, 31, v22
	v_lshrrev_b32_e32 v0, 16, v0
	v_lshlrev_b64 v[22:23], 12, v[22:23]
	v_and_or_b32 v13, v7, s24, v0
	v_lshl_add_u64 v[22:23], v[8:9], 0, v[22:23]
	global_store_dwordx4 v[22:23], v[10:13], off
	ds_read_b32 v0, v17 offset:32
	ds_read_b32 v7, v17 offset:164
	ds_read_b32 v11, v17 offset:296
	ds_read_b32 v12, v17 offset:560
	ds_read_b32 v13, v17 offset:824
	s_waitcnt lgkmcnt(0)
	v_bfe_u32 v10, v0, 16, 1
	v_add3_u32 v0, v0, v10, s26
	v_bfe_u32 v10, v7, 16, 1
	v_lshrrev_b32_e32 v0, 16, v0
	v_add3_u32 v7, v7, v10, s26
	v_and_or_b32 v10, v7, s24, v0
	ds_read_b32 v0, v17 offset:428
	v_bfe_u32 v7, v11, 16, 1
	v_add3_u32 v7, v11, v7, s26
	v_lshrrev_b32_e32 v7, 16, v7
	ds_read_b32 v22, v17 offset:956
	s_waitcnt lgkmcnt(0)
	v_bfe_u32 v11, v0, 16, 1
	v_add3_u32 v0, v0, v11, s26
	v_and_or_b32 v11, v0, s24, v7
	ds_read_b32 v0, v17 offset:692
	v_bfe_u32 v7, v12, 16, 1
	v_add3_u32 v7, v12, v7, s26
	v_lshrrev_b32_e32 v7, 16, v7
	v_readlane_b32 s73, v251, 34
	s_waitcnt lgkmcnt(0)
	v_bfe_u32 v12, v0, 16, 1
	v_add3_u32 v0, v0, v12, s26
	v_and_or_b32 v12, v0, s24, v7
	v_bfe_u32 v7, v22, 16, 1
	v_bfe_u32 v0, v13, 16, 1
	v_add3_u32 v7, v22, v7, s26
	v_or_b32_e32 v22, v6, v18
	v_add3_u32 v0, v13, v0, s26
	v_ashrrev_i32_e32 v23, 31, v22
	v_lshrrev_b32_e32 v0, 16, v0
	v_lshlrev_b64 v[22:23], 12, v[22:23]
	v_and_or_b32 v13, v7, s24, v0
	v_lshl_add_u64 v[22:23], v[8:9], 0, v[22:23]
	global_store_dwordx4 v[22:23], v[10:13], off
	ds_read_b32 v0, v17 offset:64
	ds_read_b32 v7, v17 offset:196
	ds_read_b32 v11, v17 offset:328
	ds_read_b32 v12, v17 offset:592
	ds_read_b32 v13, v17 offset:856
	s_waitcnt lgkmcnt(0)
	v_bfe_u32 v10, v0, 16, 1
	v_add3_u32 v0, v0, v10, s26
	v_bfe_u32 v10, v7, 16, 1
	v_lshrrev_b32_e32 v0, 16, v0
	v_add3_u32 v7, v7, v10, s26
	v_and_or_b32 v10, v7, s24, v0
	ds_read_b32 v0, v17 offset:460
	v_bfe_u32 v7, v11, 16, 1
	v_add3_u32 v7, v11, v7, s26
	v_lshrrev_b32_e32 v7, 16, v7
	ds_read_b32 v22, v17 offset:988
	s_waitcnt lgkmcnt(0)
	v_bfe_u32 v11, v0, 16, 1
	v_add3_u32 v0, v0, v11, s26
	v_and_or_b32 v11, v0, s24, v7
	ds_read_b32 v0, v17 offset:724
	v_bfe_u32 v7, v12, 16, 1
	v_add3_u32 v7, v12, v7, s26
	v_lshrrev_b32_e32 v7, 16, v7
	v_readlane_b32 s72, v248, 24
	s_waitcnt lgkmcnt(0)
	v_bfe_u32 v12, v0, 16, 1
	v_add3_u32 v0, v0, v12, s26
	v_and_or_b32 v12, v0, s24, v7
	v_bfe_u32 v7, v22, 16, 1
	v_bfe_u32 v0, v13, 16, 1
	v_add3_u32 v7, v22, v7, s26
	v_or_b32_e32 v22, v6, v19
	v_add3_u32 v0, v13, v0, s26
	v_ashrrev_i32_e32 v23, 31, v22
	v_lshrrev_b32_e32 v0, 16, v0
	v_lshlrev_b64 v[22:23], 12, v[22:23]
	v_and_or_b32 v13, v7, s24, v0
	v_lshl_add_u64 v[22:23], v[8:9], 0, v[22:23]
	global_store_dwordx4 v[22:23], v[10:13], off
	ds_read_b32 v0, v17 offset:96
	ds_read_b32 v7, v17 offset:228
	ds_read_b32 v11, v17 offset:360
	ds_read_b32 v12, v17 offset:624
	ds_read_b32 v13, v17 offset:888
	s_waitcnt lgkmcnt(0)
	v_bfe_u32 v10, v0, 16, 1
	v_add3_u32 v0, v0, v10, s26
	v_bfe_u32 v10, v7, 16, 1
	v_lshrrev_b32_e32 v0, 16, v0
	v_add3_u32 v7, v7, v10, s26
	v_and_or_b32 v10, v7, s24, v0
	ds_read_b32 v0, v17 offset:492
	v_bfe_u32 v7, v11, 16, 1
	v_add3_u32 v7, v11, v7, s26
	v_lshrrev_b32_e32 v7, 16, v7
	ds_read_b32 v22, v17 offset:1020
	s_waitcnt lgkmcnt(0)
	v_bfe_u32 v11, v0, 16, 1
	v_add3_u32 v0, v0, v11, s26
	v_and_or_b32 v11, v0, s24, v7
	ds_read_b32 v0, v17 offset:756
	v_bfe_u32 v7, v12, 16, 1
	v_add3_u32 v7, v12, v7, s26
	v_lshrrev_b32_e32 v7, 16, v7
	v_or_b32_e32 v6, v6, v20
	s_waitcnt lgkmcnt(0)
	v_bfe_u32 v12, v0, 16, 1
	v_add3_u32 v0, v0, v12, s26
	v_and_or_b32 v12, v0, s24, v7
	v_bfe_u32 v0, v13, 16, 1
	v_add3_u32 v0, v13, v0, s26
	v_bfe_u32 v7, v22, 16, 1
	v_lshrrev_b32_e32 v0, 16, v0
	v_add3_u32 v7, v22, v7, s26
	v_and_or_b32 v13, v7, s24, v0
	v_ashrrev_i32_e32 v7, 31, v6
	v_lshlrev_b64 v[6:7], 12, v[6:7]
	v_lshl_add_u64 v[6:7], v[8:9], 0, v[6:7]
	global_store_dwordx4 v[6:7], v[10:13], off
	s_waitcnt lgkmcnt(0)
	v_readlane_b32 s73, v248, 25
	v_readlane_b32 s61, v251, 22
	v_readlane_b32 s62, v251, 23
	v_readlane_b32 s63, v251, 24
	v_readlane_b32 s64, v251, 25
	v_readlane_b32 s65, v251, 26
	v_readlane_b32 s66, v251, 27
	v_readlane_b32 s67, v251, 28
	v_readlane_b32 s68, v251, 29
	v_readlane_b32 s69, v251, 30
	v_readlane_b32 s74, v251, 35
	v_readlane_b32 s75, v251, 36
	s_branch .LBB0_292

; #define LDS_WAIT() asm volatile("s_waitcnt lgkmcnt(0)" ::: "memory")
;     ...
;     float tv_[32];
; #pragma unroll
;     for (int i = 0; i < 32; ++i) tv_[i] = W[(size_t)(k0 + 2 * i + (lane >> 5)) * N + n0 + (lane & 31)];
; #pragma unroll
;     for (int i = 0; i < 32; ++i) scr[(2 * i + (lane >> 5)) * 33 + (lane & 31)] = tv_[i];
;     LDS_WAIT(); asm volatile("" ::: "memory");
; __device__ __forceinline__ void convert_range(LAS unsigned char* lds, const Params& p, const int lo, const int hi, const int gw, const int NGW) {
;     ...
;     for (int it = lo + gw; it < hi; it += NGW) {
;         int r = it;
;         if (r < 2 * I_IN) { const int l = r / I_IN; r -= l * I_IN; p0_transpose_item(p.in[5] + (size_t)l * DM * NC, DM, NC, (bf16*)(ws + WS_WIN + l * SZ_WIN), scr, r, lane); continue; } r -= 2 * I_IN;
.LBB0_308:
	v_mul_hi_i32 v3, v10, s5
	v_lshrrev_b32_e32 v4, 31, v3
	v_ashrrev_i32_e32 v3, 12, v3
	v_add_u32_e32 v3, v3, v4
	v_mul_i32_i24_e32 v4, 0xffffd800, v3
	v_add_u32_e32 v8, v4, v10
	v_mov_b64_e32 v[4:5], s[46:47]
	v_mad_i64_i32 v[18:19], s[2:3], v3, s7, v[4:5]
	v_mov_b64_e32 v[4:5], s[0:1]
	v_mad_i64_i32 v[6:7], s[2:3], v3, s6, v[4:5]
	v_mul_hi_i32 v3, v8, s5
	v_lshrrev_b32_e32 v4, 31, v3
	v_ashrrev_i32_e32 v3, 7, v3
	v_add_u32_e32 v3, v3, v4
	v_mul_i32_i24_e32 v4, 0x140, v3
	v_sub_u32_e32 v4, v8, v4
	v_lshlrev_b32_e32 v4, 5, v4
	v_ashrrev_i32_e32 v5, 31, v4
	v_lshlrev_b32_e32 v8, 6, v3
	v_lshl_add_u64 v[18:19], v[4:5], 2, v[18:19]
	v_or_b32_e32 v46, v8, v11
	v_lshl_add_u64 v[42:43], v[18:19], 0, v[0:1]
	v_mad_i64_i32 v[18:19], s[2:3], v46, s23, v[42:43]
	v_or_b32_e32 v3, 2, v46
	global_load_dword v47, v[18:19], off
	v_mad_i64_i32 v[18:19], s[2:3], v3, s23, v[42:43]
	v_or_b32_e32 v3, 4, v46
	global_load_dword v48, v[18:19], off
	v_mad_i64_i32 v[18:19], s[2:3], v3, s23, v[42:43]
	v_or_b32_e32 v3, 6, v46
	global_load_dword v49, v[18:19], off
	v_mad_i64_i32 v[18:19], s[2:3], v3, s23, v[42:43]
	v_or_b32_e32 v3, 8, v46
	global_load_dword v50, v[18:19], off
	v_mad_i64_i32 v[18:19], s[2:3], v3, s23, v[42:43]
	v_or_b32_e32 v5, 10, v46
	global_load_dword v3, v[18:19], off
	v_mad_i64_i32 v[18:19], s[2:3], v5, s23, v[42:43]
	v_or_b32_e32 v5, 12, v46
	v_mad_i64_i32 v[20:21], s[2:3], v5, s23, v[42:43]
	v_or_b32_e32 v5, 14, v46
	global_load_dword v18, v[18:19], off
	v_or_b32_e32 v9, 18, v46
	global_load_dword v22, v[20:21], off
	v_mad_i64_i32 v[20:21], s[2:3], v5, s23, v[42:43]
	v_or_b32_e32 v5, 16, v46
	global_load_dword v30, v[20:21], off
	v_mad_i64_i32 v[20:21], s[2:3], v5, s23, v[42:43]
	global_load_dword v5, v[20:21], off
	v_mad_i64_i32 v[20:21], s[2:3], v9, s23, v[42:43]
	v_or_b32_e32 v9, 20, v46
	s_waitcnt lgkmcnt(0)
	v_mad_i64_i32 v[24:25], s[2:3], v9, s23, v[42:43]
	v_or_b32_e32 v9, 22, v46
	v_mad_i64_i32 v[26:27], s[2:3], v9, s23, v[42:43]
	v_or_b32_e32 v9, 24, v46
	global_load_dword v20, v[20:21], off
	v_or_b32_e32 v19, 26, v46
	global_load_dword v25, v[24:25], off
	v_or_b32_e32 v39, 60, v46
	global_load_dword v33, v[26:27], off
	v_mad_i64_i32 v[26:27], s[2:3], v9, s23, v[42:43]
	global_load_dword v9, v[26:27], off
	v_mad_i64_i32 v[26:27], s[2:3], v19, s23, v[42:43]
	v_or_b32_e32 v19, 28, v46
	global_load_dword v23, v[26:27], off
	v_mad_i64_i32 v[26:27], s[2:3], v19, s23, v[42:43]
	v_or_b32_e32 v19, 30, v46
	global_load_dword v28, v[26:27], off
	v_mad_i64_i32 v[26:27], s[2:3], v19, s23, v[42:43]
	v_or_b32_e32 v19, 32, v46
	global_load_dword v36, v[26:27], off
	v_mad_i64_i32 v[26:27], s[2:3], v19, s23, v[42:43]
	v_or_b32_e32 v21, 34, v46
	global_load_dword v19, v[26:27], off
	v_mad_i64_i32 v[26:27], s[2:3], v21, s23, v[42:43]
	v_or_b32_e32 v21, 36, v46
	v_mad_i64_i32 v[34:35], s[2:3], v21, s23, v[42:43]
	v_or_b32_e32 v21, 38, v46
	global_load_dword v26, v[26:27], off
	v_or_b32_e32 v24, 42, v46
	global_load_dword v31, v[34:35], off
	v_mad_i64_i32 v[34:35], s[2:3], v21, s23, v[42:43]
	v_or_b32_e32 v21, 40, v46
	global_load_dword v38, v[34:35], off
	v_mad_i64_i32 v[34:35], s[2:3], v21, s23, v[42:43]
	global_load_dword v21, v[34:35], off
	v_mad_i64_i32 v[34:35], s[2:3], v24, s23, v[42:43]
	v_or_b32_e32 v24, 44, v46
	global_load_dword v29, v[34:35], off
	v_mad_i64_i32 v[34:35], s[2:3], v24, s23, v[42:43]
	v_or_b32_e32 v24, 46, v46
	v_mad_i64_i32 v[40:41], s[2:3], v24, s23, v[42:43]
	v_or_b32_e32 v24, 48, v46
	v_mad_i64_i32 v[44:45], s[2:3], v24, s23, v[42:43]
	v_or_b32_e32 v27, 50, v46
	global_load_dword v34, v[34:35], off
	s_nop 0
	global_load_dword v40, v[40:41], off
	s_nop 0
	global_load_dword v24, v[44:45], off
	v_mad_i64_i32 v[44:45], s[2:3], v27, s23, v[42:43]
	v_or_b32_e32 v27, 52, v46
	global_load_dword v32, v[44:45], off
	v_mad_i64_i32 v[44:45], s[2:3], v27, s23, v[42:43]
	v_or_b32_e32 v27, 54, v46
	global_load_dword v37, v[44:45], off
	v_mad_i64_i32 v[44:45], s[2:3], v27, s23, v[42:43]
	v_or_b32_e32 v27, 56, v46
	global_load_dword v41, v[44:45], off
	v_mad_i64_i32 v[44:45], s[2:3], v27, s23, v[42:43]
	v_or_b32_e32 v35, 58, v46
	global_load_dword v27, v[44:45], off
	v_mad_i64_i32 v[44:45], s[2:3], v35, s23, v[42:43]
	global_load_dword v35, v[44:45], off
	v_mad_i64_i32 v[44:45], s[2:3], v39, s23, v[42:43]
	global_load_dword v39, v[44:45], off
	v_or_b32_e32 v44, 62, v46
	v_mad_i64_i32 v[42:43], s[2:3], v44, s23, v[42:43]
	global_load_dword v42, v[42:43], off
	v_add_u32_e32 v43, 0x400, v17
	s_waitcnt vmcnt(30)
	ds_write2_b32 v17, v47, v48 offset1:66
	s_waitcnt vmcnt(28)
	ds_write2_b32 v17, v49, v50 offset0:132 offset1:198
	s_waitcnt vmcnt(26)
	ds_write2_b32 v43, v3, v18 offset0:8 offset1:74
	s_waitcnt vmcnt(24)
	ds_write2_b32 v43, v22, v30 offset0:140 offset1:206
	v_add_u32_e32 v3, 0x800, v17
	s_waitcnt vmcnt(22)
	ds_write2_b32 v3, v5, v20 offset0:16 offset1:82
	s_waitcnt vmcnt(20)
	ds_write2_b32 v3, v25, v33 offset0:148 offset1:214
	v_add_u32_e32 v3, 0xc00, v17
	s_waitcnt vmcnt(18)
	ds_write2_b32 v3, v9, v23 offset0:24 offset1:90
	s_waitcnt vmcnt(16)
	ds_write2_b32 v3, v28, v36 offset0:156 offset1:222
	v_add_u32_e32 v3, 0x1000, v17
	s_waitcnt vmcnt(14)
	ds_write2_b32 v3, v19, v26 offset0:32 offset1:98
	s_waitcnt vmcnt(12)
	ds_write2_b32 v3, v31, v38 offset0:164 offset1:230
	v_add_u32_e32 v3, 0x1400, v17
	s_waitcnt vmcnt(10)
	ds_write2_b32 v3, v21, v29 offset0:40 offset1:106
	s_waitcnt vmcnt(8)
	ds_write2_b32 v3, v34, v40 offset0:172 offset1:238
	v_add_u32_e32 v3, 0x1800, v17
	s_waitcnt vmcnt(6)
; #define LAS __attribute__((address_space(3)))
; #define LDS_WAIT() asm volatile("s_waitcnt lgkmcnt(0)" ::: "memory")
; __device__ __forceinline__ unsigned pk2(float lo, float hi) { return f2bf(lo) | (f2bf(hi) << 16); }
;     ...
;     for (int i = 0; i < 32; ++i) scr[(2 * i + (lane >> 5)) * 33 + (lane & 31)] = tv_[i];
;     LDS_WAIT(); asm volatile("" ::: "memory");
;     const int c = lane & 7;
; #pragma unroll
;     for (int j = 0; j < 4; ++j) { const int n = (lane >> 3) + 8 * j; const LAS float* s = scr + (8 * c) * 33 + n;
;         v4u o; o.x = pk2(s[0 * 33], s[1 * 33]); o.y = pk2(s[2 * 33], s[3 * 33]); o.z = pk2(s[4 * 33], s[5 * 33]); o.w = pk2(s[6 * 33], s[7 * 33]);
;         *(v4u*)(WT + (size_t)(n0 + n) * ldw + koff + k0 + 8 * c) = o; }
;     LDS_WAIT(); asm volatile("" ::: "memory");
; __device__ __forceinline__ void convert_range(LAS unsigned char* lds, const Params& p, const int lo, const int hi, const int gw, const int NGW) {
;     ...
;     for (int it = lo + gw; it < hi; it += NGW) {
	ds_write2_b32 v3, v24, v32 offset0:48 offset1:114
	s_waitcnt vmcnt(4)
	ds_write2_b32 v3, v37, v41 offset0:180 offset1:246
	v_add_u32_e32 v3, 0x1c00, v17
	s_waitcnt vmcnt(2)
	ds_write2_b32 v3, v27, v35 offset0:56 offset1:122
	s_waitcnt vmcnt(0)
	ds_write2_b32 v3, v39, v42 offset0:188 offset1:254
	s_waitcnt lgkmcnt(0)
	v_ashrrev_i32_e32 v9, 31, v8
	v_lshl_add_u64 v[6:7], v[8:9], 1, v[6:7]
	v_mov_b32_e32 v3, v1
	v_lshl_add_u64 v[18:19], v[6:7], 0, v[2:3]
	ds_read_b32 v3, v13
	ds_read_b32 v5, v13 offset:132
	v_or_b32_e32 v20, v4, v12
	v_ashrrev_i32_e32 v21, 31, v20
	v_lshlrev_b64 v[20:21], 12, v[20:21]
	s_waitcnt lgkmcnt(0)
	v_bfe_u32 v6, v3, 16, 1
	v_add3_u32 v3, v3, v6, s26
	v_bfe_u32 v6, v5, 16, 1
	v_lshrrev_b32_e32 v3, 16, v3
	v_add3_u32 v5, v5, v6, s26
	v_and_or_b32 v6, v5, s24, v3
	ds_read_b32 v3, v13 offset:264
	ds_read_b32 v5, v13 offset:396
	v_lshl_add_u64 v[20:21], v[18:19], 0, v[20:21]
	s_movk_i32 s2, 0x2aff
	v_cmp_lt_i32_e32 vcc, s2, v10
	s_waitcnt lgkmcnt(1)
	v_bfe_u32 v7, v3, 16, 1
	v_add3_u32 v3, v3, v7, s26
	s_waitcnt lgkmcnt(0)
	v_bfe_u32 v7, v5, 16, 1
	v_lshrrev_b32_e32 v3, 16, v3
	v_add3_u32 v5, v5, v7, s26
	v_and_or_b32 v7, v5, s24, v3
	ds_read_b32 v3, v13 offset:528
	ds_read_b32 v5, v13 offset:660
	s_or_b64 s[18:19], vcc, s[18:19]
	s_waitcnt lgkmcnt(1)
	v_bfe_u32 v8, v3, 16, 1
	v_add3_u32 v3, v3, v8, s26
	s_waitcnt lgkmcnt(0)
	v_bfe_u32 v8, v5, 16, 1
	v_lshrrev_b32_e32 v3, 16, v3
	v_add3_u32 v5, v5, v8, s26
	v_and_or_b32 v8, v5, s24, v3
	ds_read_b32 v3, v13 offset:792
	ds_read_b32 v5, v13 offset:924
	s_waitcnt lgkmcnt(1)
	v_bfe_u32 v9, v3, 16, 1
	v_add3_u32 v3, v3, v9, s26
	s_waitcnt lgkmcnt(0)
	v_bfe_u32 v9, v5, 16, 1
	v_lshrrev_b32_e32 v3, 16, v3
	v_add3_u32 v5, v5, v9, s26
	v_and_or_b32 v9, v5, s24, v3
	global_store_dwordx4 v[20:21], v[6:9], off
	ds_read_b32 v3, v13 offset:32
	ds_read_b32 v5, v13 offset:164
	v_or_b32_e32 v20, v4, v14
	v_ashrrev_i32_e32 v21, 31, v20
	v_lshlrev_b64 v[20:21], 12, v[20:21]
	s_waitcnt lgkmcnt(0)
	v_bfe_u32 v6, v3, 16, 1
	v_add3_u32 v3, v3, v6, s26
	v_bfe_u32 v6, v5, 16, 1
	v_lshrrev_b32_e32 v3, 16, v3
	v_add3_u32 v5, v5, v6, s26
	v_and_or_b32 v6, v5, s24, v3
	ds_read_b32 v3, v13 offset:296
	ds_read_b32 v5, v13 offset:428
	v_lshl_add_u64 v[20:21], v[18:19], 0, v[20:21]
	s_waitcnt lgkmcnt(0)
	v_bfe_u32 v7, v3, 16, 1
	v_add3_u32 v3, v3, v7, s26
	v_bfe_u32 v7, v5, 16, 1
	v_lshrrev_b32_e32 v3, 16, v3
	v_add3_u32 v5, v5, v7, s26
	v_and_or_b32 v7, v5, s24, v3
	ds_read_b32 v3, v13 offset:560
	ds_read_b32 v5, v13 offset:692
	s_waitcnt lgkmcnt(0)
	v_bfe_u32 v8, v3, 16, 1
	v_add3_u32 v3, v3, v8, s26
	v_bfe_u32 v8, v5, 16, 1
	v_lshrrev_b32_e32 v3, 16, v3
	v_add3_u32 v5, v5, v8, s26
	v_and_or_b32 v8, v5, s24, v3
	ds_read_b32 v3, v13 offset:824
	ds_read_b32 v5, v13 offset:956
	s_waitcnt lgkmcnt(0)
	v_bfe_u32 v9, v3, 16, 1
	v_add3_u32 v3, v3, v9, s26
	v_bfe_u32 v9, v5, 16, 1
	v_lshrrev_b32_e32 v3, 16, v3
	v_add3_u32 v5, v5, v9, s26
	v_and_or_b32 v9, v5, s24, v3
	global_store_dwordx4 v[20:21], v[6:9], off
	ds_read_b32 v3, v13 offset:64
	ds_read_b32 v5, v13 offset:196
	v_or_b32_e32 v20, v4, v15
	v_ashrrev_i32_e32 v21, 31, v20
	v_lshlrev_b64 v[20:21], 12, v[20:21]
	s_waitcnt lgkmcnt(0)
	v_bfe_u32 v6, v3, 16, 1
	v_add3_u32 v3, v3, v6, s26
	v_bfe_u32 v6, v5, 16, 1
	v_lshrrev_b32_e32 v3, 16, v3
	v_add3_u32 v5, v5, v6, s26
	v_and_or_b32 v6, v5, s24, v3
	ds_read_b32 v3, v13 offset:328
	ds_read_b32 v5, v13 offset:460
	v_lshl_add_u64 v[20:21], v[18:19], 0, v[20:21]
	v_or_b32_e32 v4, v4, v16
	s_waitcnt lgkmcnt(0)
	v_bfe_u32 v7, v3, 16, 1
	v_add3_u32 v3, v3, v7, s26
	v_bfe_u32 v7, v5, 16, 1
	v_lshrrev_b32_e32 v3, 16, v3
	v_add3_u32 v5, v5, v7, s26
	v_and_or_b32 v7, v5, s24, v3
	ds_read_b32 v3, v13 offset:592
	ds_read_b32 v5, v13 offset:724
	s_waitcnt lgkmcnt(0)
	v_bfe_u32 v8, v3, 16, 1
	v_add3_u32 v3, v3, v8, s26
	v_bfe_u32 v8, v5, 16, 1
	v_lshrrev_b32_e32 v3, 16, v3
	v_add3_u32 v5, v5, v8, s26
	v_and_or_b32 v8, v5, s24, v3
	ds_read_b32 v3, v13 offset:856
	ds_read_b32 v5, v13 offset:988
	s_waitcnt lgkmcnt(0)
	v_bfe_u32 v9, v3, 16, 1
	v_add3_u32 v3, v3, v9, s26
	v_bfe_u32 v9, v5, 16, 1
	v_lshrrev_b32_e32 v3, 16, v3
	v_add3_u32 v5, v5, v9, s26
	v_and_or_b32 v9, v5, s24, v3
	global_store_dwordx4 v[20:21], v[6:9], off
	ds_read_b32 v3, v13 offset:96
	ds_read_b32 v5, v13 offset:228
	s_waitcnt lgkmcnt(0)
	v_bfe_u32 v6, v3, 16, 1
	v_add3_u32 v3, v3, v6, s26
	v_bfe_u32 v6, v5, 16, 1
	v_lshrrev_b32_e32 v3, 16, v3
	v_add3_u32 v5, v5, v6, s26
	v_and_or_b32 v6, v5, s24, v3
	ds_read_b32 v3, v13 offset:360
	ds_read_b32 v5, v13 offset:492
	s_waitcnt lgkmcnt(0)
	v_bfe_u32 v7, v3, 16, 1
	v_add3_u32 v3, v3, v7, s26
	v_bfe_u32 v7, v5, 16, 1
	v_lshrrev_b32_e32 v3, 16, v3
	v_add3_u32 v5, v5, v7, s26
	v_and_or_b32 v7, v5, s24, v3
	ds_read_b32 v3, v13 offset:624
	ds_read_b32 v5, v13 offset:756
	s_waitcnt lgkmcnt(0)
	v_bfe_u32 v8, v3, 16, 1
	v_add3_u32 v3, v3, v8, s26
	v_bfe_u32 v8, v5, 16, 1
	v_lshrrev_b32_e32 v3, 16, v3
	v_add3_u32 v5, v5, v8, s26
	v_and_or_b32 v8, v5, s24, v3
	ds_read_b32 v3, v13 offset:888
	ds_read_b32 v5, v13 offset:1020
	s_waitcnt lgkmcnt(0)
	v_bfe_u32 v9, v3, 16, 1
	v_add3_u32 v3, v3, v9, s26
	v_bfe_u32 v9, v5, 16, 1
	v_lshrrev_b32_e32 v3, 16, v3
	v_add3_u32 v5, v5, v9, s26
	v_and_or_b32 v9, v5, s24, v3
	v_ashrrev_i32_e32 v5, 31, v4
	v_lshlrev_b64 v[4:5], 12, v[4:5]
	v_lshl_add_u64 v[4:5], v[18:19], 0, v[4:5]
	global_store_dwordx4 v[4:5], v[6:9], off
	s_waitcnt lgkmcnt(0)
	v_add_u32_e32 v3, 0x300, v10
	v_mov_b32_e32 v10, v3
	s_andn2_b64 exec, exec, s[18:19]
	s_cbranch_execnz .LBB0_308

; __device__ __forceinline__ void mix_phase(LAS unsigned char* lds, const Params& p, const int layer) {
;     ...
;         if (u0 < NUB) {
;             const int nb = u0 & 15, c0 = nb * 128, ch = c0 + cw + fr;
;             { const bf16* WA = (const bf16*)(ws + WS_WA) + (size_t)(layer * 16 + nb) * 16384 + (size_t)(cw + fr) * 128 + fq * 8;
;               const bf16* WX = (const bf16*)(ws + WS_WX) + (size_t)(layer * 16 + nb) * 16384 + (size_t)(cw + fr) * 128 + fq * 8;
; #pragma unroll
;               for (int ks = 0; ks < 4; ++ks) { ba[ks] = *(const bf16x8*)(WA + ks * 32); bx[ks] = *(const bf16x8*)(WX + ks * 32); }
;               bav = p.in[12][layer * LW + ch]; bxv = p.in[14][layer * LW + ch]; c8v = ((const float*)(ws + WS_C8))[layer * LW + ch]; }
;             MIX_PREFETCH_B(u0);
.LBB0_364:
	v_readlane_b32 s0, v248, 16
	v_readlane_b32 s1, v248, 17
	v_readlane_b32 s12, v251, 1
	s_xor_b64 s[10:11], s[0:1], -1
	v_readlane_b32 s18, v251, 7
	v_readlane_b32 s19, v251, 8
	s_cmp_le_i32 s18, s2
	s_cselect_b64 s[0:1], -1, 0
	s_cmp_lt_i32 s2, s19
	s_cselect_b64 s[2:3], -1, 0
	s_and_b64 s[0:1], s[0:1], s[2:3]
	s_andn2_b64 vcc, exec, s[0:1]
	s_mov_b32 s0, s56
	v_readlane_b32 s13, v251, 2
	v_readlane_b32 s16, v251, 5
	v_readlane_b32 s17, v251, 6
	v_writelane_b32 v248, s0, 31
	v_readlane_b32 s14, v251, 3
	v_readlane_b32 s15, v251, 4
	v_writelane_b32 v248, s1, 32
	s_cbranch_vccnz .LBB0_711
	s_lshl_b32 s0, s56, 7
	v_mov_b32_e32 v130, v193
	v_writelane_b32 v248, s0, 33
	s_lshl_b32 s18, s56, 2
	v_readfirstlane_b32 s0, v130
	s_ashr_i32 s0, s0, 6
	s_lshl_b32 s34, s56, 18
	v_writelane_b32 v248, s0, 34
	s_mov_b64 s[14:15], s[16:17]
	v_readlane_b32 s0, v250, 60
	s_add_u32 s74, s14, 0x9f04000
	v_readlane_b32 s1, v250, 61
	v_and_b32_e32 v135, 15, v130
	v_bfe_u32 v137, v130, 4, 2
	s_addc_u32 s75, s15, 0
	s_andn2_b64 vcc, exec, s[0:1]
	v_writelane_b32 v248, s14, 35
	s_nop 1
	v_writelane_b32 v248, s15, 36
	s_cbranch_vccnz .LBB0_545
	v_readlane_b32 s0, v248, 34
	s_lshl_b32 s35, s0, 4
	v_readlane_b32 s0, v250, 63
	s_or_b32 s0, s34, s0
	v_readlane_b32 s1, v250, 62
	s_lshl_b32 s2, s56, 11
	s_add_i32 s3, s35, s1
	s_lshl_b32 s0, s0, 1
	s_waitcnt vmcnt(1)
	v_or_b32_e32 v2, s35, v135
	v_ashrrev_i32_e32 v3, 31, v2
	s_add_u32 s0, s14, s0
	v_lshlrev_b64 v[2:3], 8, v[2:3]
	s_addc_u32 s1, s15, 0
	v_lshlrev_b32_e32 v0, 4, v137
	v_lshl_add_u64 v[2:3], s[0:1], 0, v[2:3]
	v_lshl_add_u64 v[2:3], v[2:3], 0, v[0:1]
	s_mov_b64 s[0:1], 0x7900000
	v_lshl_add_u64 v[22:23], v[2:3], 0, s[0:1]
	s_mov_b64 s[0:1], 0x7a00000
	v_lshl_add_u64 v[30:31], v[2:3], 0, s[0:1]
	s_mov_b32 s0, 0x7900000
	v_add_co_u32_e32 v4, vcc, s0, v2
	s_mov_b32 s0, 0x7a00000
	s_nop 0
	v_addc_co_u32_e32 v5, vcc, 0, v3, vcc
	v_add_co_u32_e32 v6, vcc, s0, v2
	v_or_b32_e32 v132, s3, v135
	s_nop 0
	v_addc_co_u32_e32 v7, vcc, 0, v3, vcc
	v_add_u32_e32 v34, s2, v132
	global_load_dwordx4 v[2:5], v[4:5], off
	s_nop 0
	global_load_dwordx4 v[6:9], v[6:7], off
	s_nop 0
	global_load_dwordx4 v[10:13], v[22:23], off offset:64
	global_load_dwordx4 v[14:17], v[22:23], off offset:128
	global_load_dwordx4 v[18:21], v[30:31], off offset:64
	s_waitcnt lgkmcnt(0)
	global_load_dwordx4 v[22:25], v[22:23], off offset:192
	s_nop 0
	global_load_dwordx4 v[26:29], v[30:31], off offset:128
	s_nop 0
	global_load_dwordx4 v[30:33], v[30:31], off offset:192
	v_ashrrev_i32_e32 v35, 31, v34
	v_readlane_b32 s36, v251, 37
	v_lshlrev_b64 v[34:35], 2, v[34:35]
	v_readlane_b32 s44, v251, 45
	v_readlane_b32 s45, v251, 46
	v_readlane_b32 s48, v251, 49
	v_readlane_b32 s49, v251, 50
	v_lshl_add_u64 v[36:37], s[44:45], 0, v[34:35]
	global_load_dword v179, v[36:37], off
	v_lshl_add_u64 v[36:37], s[48:49], 0, v[34:35]
	v_lshl_add_u64 v[34:35], s[14:15], 0, v[34:35]
	v_add_co_u32_e32 v34, vcc, 0x7b00000, v34
	global_load_dword v224, v[36:37], off
	s_nop 0
	v_addc_co_u32_e32 v35, vcc, 0, v35, vcc
	global_load_dword v225, v[34:35], off
	v_readlane_b32 s0, v249, 42
	v_readlane_b32 s1, v249, 43
	s_mov_b32 s19, s80
	s_andn2_b64 vcc, exec, s[0:1]
	v_ashrrev_i32_e32 v226, 4, v130
	v_readlane_b32 s37, v251, 38
	v_readlane_b32 s38, v251, 39
	v_readlane_b32 s39, v251, 40
	v_readlane_b32 s40, v251, 41
	v_readlane_b32 s41, v251, 42
	v_readlane_b32 s42, v251, 43
	v_readlane_b32 s43, v251, 44
	v_readlane_b32 s46, v251, 47
	v_readlane_b32 s47, v251, 48
	v_readlane_b32 s50, v251, 51
	v_readlane_b32 s51, v251, 52
	s_cbranch_vccnz .LBB0_368
	v_readlane_b32 s0, v249, 44
	v_mov_b64_e32 v[50:51], s[74:75]
	v_lshlrev_b32_e32 v0, 4, v135
	v_add_u32_e32 v52, s0, v226
	v_mad_i64_i32 v[34:35], s[0:1], v52, s25, v[50:51]
	v_readlane_b32 s0, v250, 62
	v_and_b32_e32 v46, 0x7ff, v52
	s_lshl_b32 s0, s0, 1
	s_mov_b32 s1, s80
	v_lshl_add_u64 v[34:35], v[34:35], 0, s[0:1]
	v_cmp_gt_u32_e32 vcc, 3, v46
	v_lshl_add_u64 v[42:43], v[34:35], 0, v[0:1]
	s_mov_b64 s[12:13], 0x1000
	v_cndmask_b32_e64 v35, -1, 0, vcc
	v_cndmask_b32_e64 v34, v220, 0, vcc
	v_cmp_gt_u32_e32 vcc, 2, v46
	v_lshl_add_u64 v[44:45], v[42:43], 0, s[12:13]
	s_movk_i32 s3, 0x1000
	v_cndmask_b32_e64 v37, -1, 0, vcc
	v_cndmask_b32_e64 v36, v221, 0, vcc
	v_cmp_eq_u32_e32 vcc, 0, v46
	v_lshl_add_u64 v[34:35], v[44:45], 0, v[34:35]
	v_lshl_add_u64 v[38:39], v[44:45], 0, v[36:37]
	v_cndmask_b32_e64 v47, -1, 0, vcc
	v_cndmask_b32_e64 v46, v222, 0, vcc
	v_lshl_add_u64 v[44:45], v[44:45], 0, v[46:47]
	v_add_co_u32_e32 v46, vcc, s3, v42
	v_add_u32_e32 v52, 32, v52
	s_nop 0
	v_addc_co_u32_e32 v47, vcc, 0, v43, vcc
	v_and_b32_e32 v62, 0x7ff, v52
	v_mad_i64_i32 v[50:51], s[6:7], v52, s25, v[50:51]
	v_lshl_add_u64 v[50:51], v[50:51], 0, s[0:1]
	v_cmp_gt_u32_e32 vcc, 3, v62
	v_lshl_add_u64 v[58:59], v[50:51], 0, v[0:1]
	v_lshl_add_u64 v[60:61], v[58:59], 0, s[12:13]
	v_cndmask_b32_e64 v51, -1, 0, vcc
	v_cndmask_b32_e64 v50, v220, 0, vcc
	v_cmp_gt_u32_e32 vcc, 2, v62
	v_lshl_add_u64 v[50:51], v[60:61], 0, v[50:51]
	global_load_dwordx4 v[34:37], v[34:35], off
	s_nop 0
	global_load_dwordx4 v[38:41], v[38:39], off
	v_cndmask_b32_e64 v53, -1, 0, vcc
	v_cndmask_b32_e64 v52, v221, 0, vcc
	v_cmp_eq_u32_e32 vcc, 0, v62
	v_lshl_add_u64 v[54:55], v[60:61], 0, v[52:53]
	global_load_dwordx4 v[42:45], v[44:45], off
	s_nop 0
	global_load_dwordx4 v[46:49], v[46:47], off
	v_cndmask_b32_e64 v63, -1, 0, vcc
	v_cndmask_b32_e64 v62, v222, 0, vcc
	v_lshl_add_u64 v[60:61], v[60:61], 0, v[62:63]
	v_add_co_u32_e32 v62, vcc, 0x1000, v58
	global_load_dwordx4 v[50:53], v[50:51], off
	s_nop 0
	global_load_dwordx4 v[54:57], v[54:55], off
	v_addc_co_u32_e32 v63, vcc, 0, v59, vcc
	global_load_dwordx4 v[58:61], v[60:61], off
	s_nop 0
	global_load_dwordx4 v[62:65], v[62:63], off

; __device__ __forceinline__ void mix_phase(LAS unsigned char* lds, const Params& p, const int layer) {
;     ...
;             __syncthreads();
;             for (int i = tid; i < 5 * 128; i += NTHR) { const int k = i >> 7, cc = i & 127; CWL[i] = (k == 0) ? p.in[10][(size_t)layer * LW + c0 + cc] : p.in[9][((size_t)layer * 4 + (k - 1)) * LW + c0 + cc]; }
;             __syncthreads();
.LBB0_376:
	v_ashrrev_i32_e32 v72, 7, v68
	v_ashrrev_i32_e32 v0, 7, v69
	v_add_u32_e32 v72, -1, v72
	v_add_u32_e32 v76, -1, v0
	v_ashrrev_i32_e32 v73, 31, v72
	v_ashrrev_i32_e32 v77, 31, v76
	v_lshl_add_u64 v[72:73], s[18:19], 0, v[72:73]
	v_lshl_add_u64 v[76:77], s[18:19], 0, v[76:77]
	v_lshlrev_b64 v[72:73], 13, v[72:73]
	v_or_b32_e32 v78, s3, v68
	v_mov_b32_e32 v79, v1
	v_cmp_gt_u32_e32 vcc, s5, v68
	v_lshlrev_b64 v[76:77], 13, v[76:77]
	v_lshl_add_u64 v[72:73], v[66:67], 0, v[72:73]
	v_or_b32_e32 v0, s3, v69
	v_lshl_add_u64 v[78:79], v[78:79], 2, s[48:49]
	v_cmp_gt_u32_e64 s[0:1], s5, v69
	v_lshl_add_u64 v[76:77], v[66:67], 0, v[76:77]
	v_lshl_add_u64 v[80:81], v[0:1], 2, s[48:49]
	v_cndmask_b32_e32 v73, v73, v79, vcc
	v_cndmask_b32_e32 v72, v72, v78, vcc
	v_cndmask_b32_e64 v77, v77, v81, s[0:1]
	v_cndmask_b32_e64 v76, v76, v80, s[0:1]
	global_load_dword v0, v[72:73], off
	s_nop 0
	global_load_dword v72, v[76:77], off
	v_add_u32_e32 v70, -1, v70
	v_add_u32_e32 v73, 0xfffff800, v71
	v_cmp_eq_u32_e32 vcc, 0, v70
	v_add_u32_e32 v69, 0x400, v69
	v_add_u32_e32 v68, 0x400, v68
	s_or_b64 s[44:45], vcc, s[44:45]
	s_waitcnt vmcnt(1)
	ds_write_b32 v73, v0
	s_waitcnt vmcnt(0)
	ds_write_b32 v71, v72
	v_add_u32_e32 v71, 0x1000, v71
	s_andn2_b64 exec, exec, s[44:45]
	s_cbranch_execnz .LBB0_376

; #define LAS __attribute__((address_space(3)))
; __device__ __forceinline__ unsigned pk2(float lo, float hi) { return f2bf(lo) | (f2bf(hi) << 16); }
; #define BF8_TO_F32(vw, lo, hi) const f32x4 lo = {bflo(vw.x), bfhi(vw.x), bflo(vw.y), bfhi(vw.y)}, hi = {bflo(vw.z), bfhi(vw.z), bflo(vw.w), bfhi(vw.w)}
; __device__ __forceinline__ void mix_phase(LAS unsigned char* lds, const Params& p, const int layer) {
;     ...
;             } else {
;                 const float* sconv = p.in[3] + (size_t)layer * 128 * 3 * LW;
; #pragma unroll 1
;                 for (int i = 0; i < 2; ++i) {
;                     const int rl = (tid >> 4) + 32 * i, r = r0N + rl, c = c0 + q16 * 8, t = (r - NP) & 7, bs = (r - NP) >> 3;
;                     f32x4 x0 = *(const LAS f32x4*)(CWL + q16 * 8), x1 = *(const LAS f32x4*)(CWL + q16 * 8 + 4);
; #pragma unroll
;                     for (int k = 0; k < 4; ++k) { const int jb = 3 - k;
;                         const f32x4 w0 = *(const LAS f32x4*)(CWL + (k + 1) * 128 + q16 * 8), w1 = *(const LAS f32x4*)(CWL + (k + 1) * 128 + q16 * 8 + 4);
;                         if (jb <= t) { const v4u vw = *(const v4u*)(PROJ + (size_t)(r - jb) * NC + C_UB + c); BF8_TO_F32(vw, a0, a1); x0 += w0 * a0; x1 += w1 * a1; }
;                         else { const float* sp = sconv + ((size_t)bs * 3 + (3 + t - jb)) * LW + c; x0 += w0 * *(const f32x4*)sp; x1 += w1 * *(const f32x4*)(sp + 4); }
;                     }
;                     *(LAS f32x4*)(XCN + rl * 132 + q16 * 8) = x0; *(LAS f32x4*)(XCN + rl * 132 + q16 * 8 + 4) = x1;
;                     v4u o; o.x = pk2(x0[0], x0[1]); o.y = pk2(x0[2], x0[3]); o.z = pk2(x1[0], x1[1]); o.w = pk2(x1[2], x1[3]);
;                     *(LAS v4u*)(AtN + rl * 136 + q16 * 8) = o;
;                 }
.LBB0_387:
	s_or_b64 exec, exec, s[46:47]
	s_waitcnt lgkmcnt(0)
	s_waitcnt vmcnt(1)
	v_pk_fma_f32 v[66:67], v[74:75], v[86:87], v[66:67]
	v_mov_b64_e32 v[74:75], s[74:75]
	v_mad_i64_i32 v[74:75], s[2:3], v133, s25, v[74:75]
	v_lshl_add_u64 v[74:75], v[74:75], 0, v[0:1]
	s_movk_i32 s2, 0x1000
	s_waitcnt vmcnt(0)
	v_pk_fma_f32 v[72:73], v[80:81], v[84:85], v[72:73]
	v_pk_fma_f32 v[70:71], v[78:79], v[82:83], v[70:71]
	v_pk_fma_f32 v[68:69], v[76:77], v[88:89], v[68:69]
	v_add_co_u32_e32 v74, vcc, s2, v74
	v_pk_fma_f32 v[72:73], v[96:97], v[100:101], v[72:73]
	v_pk_fma_f32 v[70:71], v[94:95], v[98:99], v[70:71]
	v_pk_fma_f32 v[68:69], v[92:93], v[104:105], v[68:69]
	v_pk_fma_f32 v[66:67], v[90:91], v[102:103], v[66:67]
	v_addc_co_u32_e32 v75, vcc, 0, v75, vcc
	v_pk_fma_f32 v[78:79], v[112:113], v[116:117], v[72:73]
	v_pk_fma_f32 v[80:81], v[110:111], v[114:115], v[70:71]
	v_pk_fma_f32 v[82:83], v[108:109], v[120:121], v[68:69]
	v_pk_fma_f32 v[84:85], v[106:107], v[118:119], v[66:67]
	ds_read_b128 v[66:69], v125 offset:2048
	ds_read_b128 v[70:73], v125 offset:2064
	global_load_dwordx4 v[74:77], v[74:75], off
	s_movk_i32 s2, 0x210
	s_xor_b64 s[46:47], s[44:45], -1
	s_mov_b64 s[44:45], 0
	s_andn2_b64 vcc, exec, s[46:47]
	s_waitcnt lgkmcnt(0)
	s_waitcnt vmcnt(0)
	v_lshlrev_b32_e32 v88, 16, v74
	v_and_b32_e32 v89, 0xffff0000, v74
	v_lshlrev_b32_e32 v74, 16, v75
	v_and_b32_e32 v75, 0xffff0000, v75
	v_pk_fma_f32 v[66:67], v[66:67], v[88:89], v[80:81]
	v_lshlrev_b32_e32 v86, 16, v76
	v_and_b32_e32 v87, 0xffff0000, v76
	v_lshlrev_b32_e32 v76, 16, v77
	v_and_b32_e32 v77, 0xffff0000, v77
	v_pk_fma_f32 v[68:69], v[68:69], v[74:75], v[78:79]
	v_mad_u64_u32 v[74:75], s[2:3], v127, s2, v[124:125]
	v_bfe_u32 v0, v66, 16, 1
	v_pk_fma_f32 v[72:73], v[72:73], v[76:77], v[82:83]
	v_pk_fma_f32 v[70:71], v[70:71], v[86:87], v[84:85]
	ds_write_b128 v74, v[66:69]
	ds_write_b128 v74, v[70:73] offset:16
	v_add3_u32 v0, v66, v0, s26
	v_bfe_u32 v66, v67, 16, 1
	v_lshrrev_b32_e32 v0, 16, v0
	v_add3_u32 v66, v67, v66, s26
	v_and_or_b32 v66, v66, s24, v0
	v_bfe_u32 v0, v68, 16, 1
	v_add3_u32 v0, v68, v0, s26
	v_bfe_u32 v67, v69, 16, 1
	v_lshrrev_b32_e32 v0, 16, v0
	v_add3_u32 v67, v69, v67, s26
	v_and_or_b32 v67, v67, s24, v0
	v_bfe_u32 v0, v70, 16, 1
	v_add3_u32 v0, v70, v0, s26
	v_bfe_u32 v68, v71, 16, 1
	v_lshrrev_b32_e32 v0, 16, v0
	v_add3_u32 v68, v71, v68, s26
	v_and_or_b32 v68, v68, s24, v0
	v_bfe_u32 v0, v72, 16, 1
	v_add3_u32 v0, v72, v0, s26
	v_bfe_u32 v69, v73, 16, 1
	s_movk_i32 s2, 0x110
	v_lshrrev_b32_e32 v0, 16, v0
	v_add3_u32 v69, v73, v69, s26
	v_mad_u64_u32 v[70:71], s[2:3], v127, s2, v[126:127]
	v_and_or_b32 v69, v69, s24, v0
	s_mov_b32 s2, 32
	ds_write_b128 v70, v[66:69]
	s_cbranch_vccz .LBB0_400
.LBB0_388:
	ds_read_b128 v[70:73], v125
	ds_read_b128 v[66:69], v125 offset:16
	ds_read_b128 v[78:81], v125 offset:512
	ds_read_b128 v[74:77], v125 offset:528
	v_add_u32_e32 v127, s2, v226
	v_add_u32_e32 v133, s5, v127
	v_lshlrev_b32_e32 v0, 1, v136
	s_and_saveexec_b64 s[2:3], s[38:39]
	s_xor_b64 s[46:47], exec, s[2:3]
	s_cbranch_execz .LBB0_390
	v_add_u32_e32 v84, -3, v133
	v_mov_b64_e32 v[82:83], s[74:75]
	v_mad_i64_i32 v[82:83], s[2:3], v84, s25, v[82:83]
	v_lshl_add_u64 v[82:83], v[82:83], 0, v[0:1]
	v_add_co_u32_e32 v82, vcc, 0x1000, v82
	s_nop 1
	v_addc_co_u32_e32 v83, vcc, 0, v83, vcc
	global_load_dwordx4 v[86:89], v[82:83], off
	s_waitcnt lgkmcnt(0)
	s_waitcnt vmcnt(0)
	v_lshlrev_b32_e32 v82, 16, v86
	v_and_b32_e32 v83, 0xffff0000, v86
	v_lshlrev_b32_e32 v84, 16, v87
	v_and_b32_e32 v85, 0xffff0000, v87
	v_lshlrev_b32_e32 v86, 16, v88
	v_and_b32_e32 v87, 0xffff0000, v88
	v_lshlrev_b32_e32 v88, 16, v89
	v_and_b32_e32 v89, 0xffff0000, v89

; #define LAS __attribute__((address_space(3)))
; #define BF8_TO_F32(vw, lo, hi) const f32x4 lo = {bflo(vw.x), bfhi(vw.x), bflo(vw.y), bfhi(vw.y)}, hi = {bflo(vw.z), bfhi(vw.z), bflo(vw.w), bfhi(vw.w)}
; __device__ __forceinline__ void mix_phase(LAS unsigned char* lds, const Params& p, const int layer) {
;     ...
;                     for (int k = 0; k < 4; ++k) { const int jb = 3 - k;
;                         const f32x4 w0 = *(const LAS f32x4*)(CWL + (k + 1) * 128 + q16 * 8), w1 = *(const LAS f32x4*)(CWL + (k + 1) * 128 + q16 * 8 + 4);
;                         if (jb <= t) { const v4u vw = *(const v4u*)(PROJ + (size_t)(r - jb) * NC + C_UB + c); BF8_TO_F32(vw, a0, a1); x0 += w0 * a0; x1 += w1 * a1; }
;                         else { const float* sp = sconv + ((size_t)bs * 3 + (3 + t - jb)) * LW + c; x0 += w0 * *(const f32x4*)sp; x1 += w1 * *(const f32x4*)(sp + 4); }
;                     }
.LBB0_392:
	s_or_b64 exec, exec, s[46:47]
	ds_read_b128 v[94:97], v125 offset:1024
	ds_read_b128 v[90:93], v125 offset:1040
	s_and_saveexec_b64 s[2:3], s[40:41]
	s_xor_b64 s[46:47], exec, s[2:3]
	s_cbranch_execz .LBB0_394
	v_add_u32_e32 v100, -2, v133
	v_mov_b64_e32 v[98:99], s[74:75]
	v_mad_i64_i32 v[98:99], s[2:3], v100, s25, v[98:99]
	v_lshl_add_u64 v[98:99], v[98:99], 0, v[0:1]
	v_add_co_u32_e32 v98, vcc, 0x1000, v98
	s_nop 1
	v_addc_co_u32_e32 v99, vcc, 0, v99, vcc
	global_load_dwordx4 v[102:105], v[98:99], off
	s_waitcnt lgkmcnt(0)
	s_waitcnt vmcnt(0)
	v_lshlrev_b32_e32 v98, 16, v102
	v_and_b32_e32 v99, 0xffff0000, v102
	v_lshlrev_b32_e32 v100, 16, v103
	v_and_b32_e32 v101, 0xffff0000, v103
	v_lshlrev_b32_e32 v102, 16, v104
	v_and_b32_e32 v103, 0xffff0000, v104
	v_lshlrev_b32_e32 v104, 16, v105
	v_and_b32_e32 v105, 0xffff0000, v105

; #define LAS __attribute__((address_space(3)))
; #define BF8_TO_F32(vw, lo, hi) const f32x4 lo = {bflo(vw.x), bfhi(vw.x), bflo(vw.y), bfhi(vw.y)}, hi = {bflo(vw.z), bfhi(vw.z), bflo(vw.w), bfhi(vw.w)}
; __device__ __forceinline__ void mix_phase(LAS unsigned char* lds, const Params& p, const int layer) {
;     ...
;                     for (int k = 0; k < 4; ++k) { const int jb = 3 - k;
;                         const f32x4 w0 = *(const LAS f32x4*)(CWL + (k + 1) * 128 + q16 * 8), w1 = *(const LAS f32x4*)(CWL + (k + 1) * 128 + q16 * 8 + 4);
;                         if (jb <= t) { const v4u vw = *(const v4u*)(PROJ + (size_t)(r - jb) * NC + C_UB + c); BF8_TO_F32(vw, a0, a1); x0 += w0 * a0; x1 += w1 * a1; }
;                         else { const float* sp = sconv + ((size_t)bs * 3 + (3 + t - jb)) * LW + c; x0 += w0 * *(const f32x4*)sp; x1 += w1 * *(const f32x4*)(sp + 4); }
;                     }
.LBB0_396:
	s_or_b64 exec, exec, s[20:21]
	ds_read_b128 v[110:113], v125 offset:1536
	ds_read_b128 v[106:109], v125 offset:1552
	s_and_saveexec_b64 s[2:3], s[42:43]
	s_xor_b64 s[46:47], exec, s[2:3]
	s_cbranch_execz .LBB0_398
	v_add_u32_e32 v116, -1, v133
	v_mov_b64_e32 v[114:115], s[74:75]
	v_mad_i64_i32 v[114:115], s[2:3], v116, s25, v[114:115]
	v_lshl_add_u64 v[114:115], v[114:115], 0, v[0:1]
	v_add_co_u32_e32 v114, vcc, 0x1000, v114
	s_nop 1
	v_addc_co_u32_e32 v115, vcc, 0, v115, vcc
	global_load_dwordx4 v[118:121], v[114:115], off
	s_waitcnt lgkmcnt(0)
	s_waitcnt vmcnt(0)
	v_lshlrev_b32_e32 v114, 16, v118
	v_and_b32_e32 v115, 0xffff0000, v118
	v_lshlrev_b32_e32 v116, 16, v119
	v_and_b32_e32 v117, 0xffff0000, v119
	v_lshlrev_b32_e32 v118, 16, v120
	v_and_b32_e32 v119, 0xffff0000, v120
	v_lshlrev_b32_e32 v120, 16, v121
	v_and_b32_e32 v121, 0xffff0000, v121

; #define LAS __attribute__((address_space(3)))
; __device__ __forceinline__ unsigned pk2(float lo, float hi) { return f2bf(lo) | (f2bf(hi) << 16); }
; #define BF8_TO_F32(vw, lo, hi) const f32x4 lo = {bflo(vw.x), bfhi(vw.x), bflo(vw.y), bfhi(vw.y)}, hi = {bflo(vw.z), bfhi(vw.z), bflo(vw.w), bfhi(vw.w)}
; __device__ __forceinline__ void mix_phase(LAS unsigned char* lds, const Params& p, const int layer) {
;     ...
;             if (prtN) {
;                 const f32x4 cb0 = *(const LAS f32x4*)(CWL + q16 * 8), cb1 = *(const LAS f32x4*)(CWL + q16 * 8 + 4);
; #pragma unroll
;                 for (int i = 0; i < 2; ++i) {
;                     const int rl = (tid >> 4) + 32 * i, t = (r0N + rl) & 2047;
;                     f32x4 x0 = cb0, x1 = cb1;
; #pragma unroll
;                     for (int k = 0; k < 4; ++k) { const float f = ((3 - k) <= t) ? 1.0f : 0.0f;
;                         const f32x4 w0 = *(const LAS f32x4*)(CWL + (k + 1) * 128 + q16 * 8), w1 = *(const LAS f32x4*)(CWL + (k + 1) * 128 + q16 * 8 + 4);
;                         BF8_TO_F32(pre[i][k], a0, a1); x0 += w0 * (a0 * f); x1 += w1 * (a1 * f); }
;                     *(LAS f32x4*)(XCN + rl * 132 + q16 * 8) = x0; *(LAS f32x4*)(XCN + rl * 132 + q16 * 8 + 4) = x1;
;                     v4u o; o.x = pk2(x0[0], x0[1]); o.y = pk2(x0[2], x0[3]); o.z = pk2(x1[0], x1[1]); o.w = pk2(x1[2], x1[3]);
;                     *(LAS v4u*)(AtN + rl * 136 + q16 * 8) = o;
;                 }
.LBB0_401:
	s_movk_i32 s2, 0x110
	s_and_b64 vcc, exec, s[20:21]
	v_lshlrev_b32_e32 v138, 1, v134
	v_mul_lo_u32 v141, v226, s2
	s_cbranch_vccz .LBB0_403
	v_lshl_add_u32 v0, v134, 2, 0
	v_readlane_b32 s2, v249, 2
	v_add_u32_e32 v100, 0x21400, v0
	ds_read_b128 v[66:69], v100
	ds_read_b128 v[70:73], v100 offset:16
	v_add_u32_e32 v101, s2, v226
	v_and_b32_e32 v102, 0x7ff, v101
	ds_read_b128 v[74:77], v100 offset:512
	ds_read_b128 v[78:81], v100 offset:528
	v_cmp_gt_u32_e32 vcc, 3, v102
	s_waitcnt vmcnt(7)
	v_lshlrev_b32_e32 v84, 16, v34
	v_and_b32_e32 v85, 0xffff0000, v34
	v_cndmask_b32_e64 v82, 1.0, 0, vcc
	v_lshlrev_b32_e32 v86, 16, v35
	v_and_b32_e32 v87, 0xffff0000, v35
	v_lshlrev_b32_e32 v88, 16, v36
	v_and_b32_e32 v89, 0xffff0000, v36
	v_lshlrev_b32_e32 v90, 16, v37
	v_and_b32_e32 v91, 0xffff0000, v37
	v_pk_mul_f32 v[86:87], v[82:83], v[86:87] op_sel_hi:[0,1]
	v_pk_mul_f32 v[84:85], v[82:83], v[84:85] op_sel_hi:[0,1]
	s_waitcnt lgkmcnt(1)
	v_pk_fma_f32 v[84:85], v[84:85], v[74:75], v[66:67]
	v_pk_fma_f32 v[86:87], v[86:87], v[76:77], v[68:69]
	v_pk_mul_f32 v[74:75], v[82:83], v[90:91] op_sel_hi:[0,1]
	v_pk_mul_f32 v[76:77], v[82:83], v[88:89] op_sel_hi:[0,1]
	s_waitcnt lgkmcnt(0)
	v_pk_fma_f32 v[82:83], v[76:77], v[78:79], v[70:71]
	v_pk_fma_f32 v[88:89], v[74:75], v[80:81], v[72:73]
	ds_read_b128 v[74:77], v100 offset:1024
	ds_read_b128 v[78:81], v100 offset:1040
	v_cmp_gt_u32_e32 vcc, 2, v102
	s_waitcnt vmcnt(6)
	v_lshlrev_b32_e32 v92, 16, v38
	v_and_b32_e32 v93, 0xffff0000, v38
	v_cndmask_b32_e64 v90, 1.0, 0, vcc
	v_lshlrev_b32_e32 v94, 16, v39
	v_and_b32_e32 v95, 0xffff0000, v39
	v_lshlrev_b32_e32 v96, 16, v40
	v_and_b32_e32 v97, 0xffff0000, v40
	v_lshlrev_b32_e32 v98, 16, v41
	v_and_b32_e32 v99, 0xffff0000, v41
	v_pk_mul_f32 v[92:93], v[90:91], v[92:93] op_sel_hi:[0,1]
	v_pk_mul_f32 v[94:95], v[90:91], v[94:95] op_sel_hi:[0,1]
	s_waitcnt lgkmcnt(1)
	v_pk_fma_f32 v[86:87], v[94:95], v[76:77], v[86:87]
	v_pk_fma_f32 v[84:85], v[92:93], v[74:75], v[84:85]
	v_pk_mul_f32 v[74:75], v[90:91], v[96:97] op_sel_hi:[0,1]
	v_pk_mul_f32 v[76:77], v[90:91], v[98:99] op_sel_hi:[0,1]
	s_waitcnt lgkmcnt(0)
	v_pk_fma_f32 v[88:89], v[76:77], v[80:81], v[88:89]
	v_pk_fma_f32 v[82:83], v[74:75], v[78:79], v[82:83]
	ds_read_b128 v[74:77], v100 offset:1536
	ds_read_b128 v[78:81], v100 offset:1552
	v_cmp_eq_u32_e32 vcc, 0, v102
	s_waitcnt vmcnt(5)
	v_lshlrev_b32_e32 v92, 16, v42
	v_and_b32_e32 v93, 0xffff0000, v42
	v_cndmask_b32_e64 v90, 1.0, 0, vcc
	v_lshlrev_b32_e32 v94, 16, v43
	v_and_b32_e32 v95, 0xffff0000, v43
	v_lshlrev_b32_e32 v96, 16, v44
	v_and_b32_e32 v97, 0xffff0000, v44
	v_lshlrev_b32_e32 v98, 16, v45
	v_and_b32_e32 v99, 0xffff0000, v45
	v_pk_mul_f32 v[94:95], v[90:91], v[94:95] op_sel_hi:[0,1]
	v_pk_mul_f32 v[92:93], v[90:91], v[92:93] op_sel_hi:[0,1]
	s_waitcnt lgkmcnt(1)
	v_pk_fma_f32 v[84:85], v[92:93], v[74:75], v[84:85]
	v_pk_fma_f32 v[86:87], v[94:95], v[76:77], v[86:87]
	v_pk_mul_f32 v[74:75], v[90:91], v[98:99] op_sel_hi:[0,1]
	v_pk_mul_f32 v[76:77], v[90:91], v[96:97] op_sel_hi:[0,1]
	s_waitcnt lgkmcnt(0)
	v_pk_fma_f32 v[82:83], v[76:77], v[78:79], v[82:83]
	v_pk_fma_f32 v[88:89], v[74:75], v[80:81], v[88:89]
	ds_read_b128 v[74:77], v100 offset:2048
	ds_read_b128 v[78:81], v100 offset:2064
	s_waitcnt vmcnt(4)
	v_lshlrev_b32_e32 v90, 16, v46
	v_and_b32_e32 v91, 0xffff0000, v46
	v_lshlrev_b32_e32 v92, 16, v47
	v_and_b32_e32 v93, 0xffff0000, v47
	v_lshlrev_b32_e32 v94, 16, v48
	v_and_b32_e32 v95, 0xffff0000, v48
	s_waitcnt lgkmcnt(1)
	v_pk_fma_f32 v[74:75], v[74:75], v[90:91], v[84:85]
	s_movk_i32 s2, 0x210
	v_lshlrev_b32_e32 v96, 16, v49
	v_and_b32_e32 v97, 0xffff0000, v49
	v_pk_fma_f32 v[76:77], v[76:77], v[92:93], v[86:87]
	s_waitcnt lgkmcnt(0)
	v_pk_fma_f32 v[78:79], v[78:79], v[94:95], v[82:83]
	v_mad_u64_u32 v[82:83], s[2:3], v226, s2, v[0:1]
	v_bfe_u32 v0, v74, 16, 1
	v_pk_fma_f32 v[80:81], v[80:81], v[96:97], v[88:89]
	ds_write_b128 v82, v[74:77]
	ds_write_b128 v82, v[78:81] offset:16
	v_add3_u32 v0, v74, v0, s26
	v_bfe_u32 v74, v75, 16, 1
	v_lshrrev_b32_e32 v0, 16, v0
	v_add3_u32 v74, v75, v74, s26
	v_and_or_b32 v74, v74, s24, v0
	v_bfe_u32 v0, v76, 16, 1
	v_add3_u32 v0, v76, v0, s26
	v_bfe_u32 v75, v77, 16, 1
	v_lshrrev_b32_e32 v0, 16, v0
	v_add3_u32 v75, v77, v75, s26
	v_and_or_b32 v75, v75, s24, v0
	v_bfe_u32 v0, v78, 16, 1
	v_add3_u32 v0, v78, v0, s26
	v_bfe_u32 v76, v79, 16, 1
	v_lshrrev_b32_e32 v0, 16, v0
	v_add3_u32 v76, v79, v76, s26
	v_and_or_b32 v76, v76, s24, v0
	v_bfe_u32 v0, v80, 16, 1
	v_add3_u32 v0, v80, v0, s26
	v_bfe_u32 v77, v81, 16, 1
	v_lshrrev_b32_e32 v0, 16, v0
	v_add3_u32 v77, v81, v77, s26
	v_readlane_b32 s2, v248, 5
	v_and_or_b32 v77, v77, s24, v0
	v_add_u32_e32 v0, 32, v101
	v_add3_u32 v83, s2, v138, v141
	ds_write_b128 v83, v[74:77]
	v_and_b32_e32 v92, 0x7ff, v0
	ds_read_b128 v[74:77], v100 offset:512
	ds_read_b128 v[78:81], v100 offset:528
	v_cmp_gt_u32_e32 vcc, 3, v92
	s_waitcnt vmcnt(3)
	v_lshlrev_b32_e32 v84, 16, v50
	v_and_b32_e32 v85, 0xffff0000, v50
	v_cndmask_b32_e64 v0, 1.0, 0, vcc
	v_lshlrev_b32_e32 v86, 16, v51
	v_and_b32_e32 v87, 0xffff0000, v51
	v_lshlrev_b32_e32 v88, 16, v52
	v_and_b32_e32 v89, 0xffff0000, v52
	v_lshlrev_b32_e32 v90, 16, v53
	v_and_b32_e32 v91, 0xffff0000, v53
	v_pk_mul_f32 v[84:85], v[0:1], v[84:85] op_sel_hi:[0,1]
	v_pk_mul_f32 v[86:87], v[0:1], v[86:87] op_sel_hi:[0,1]
	s_waitcnt lgkmcnt(1)
	v_pk_fma_f32 v[76:77], v[86:87], v[76:77], v[68:69]
	v_pk_fma_f32 v[74:75], v[84:85], v[74:75], v[66:67]
	v_pk_mul_f32 v[66:67], v[0:1], v[88:89] op_sel_hi:[0,1]
	v_pk_mul_f32 v[68:69], v[0:1], v[90:91] op_sel_hi:[0,1]
	s_waitcnt lgkmcnt(0)
; #define LAS __attribute__((address_space(3)))
; __device__ __forceinline__ unsigned pk2(float lo, float hi) { return f2bf(lo) | (f2bf(hi) << 16); }
; #define BF8_TO_F32(vw, lo, hi) const f32x4 lo = {bflo(vw.x), bfhi(vw.x), bflo(vw.y), bfhi(vw.y)}, hi = {bflo(vw.z), bfhi(vw.z), bflo(vw.w), bfhi(vw.w)}
; __device__ __forceinline__ void mix_phase(LAS unsigned char* lds, const Params& p, const int layer) {
;     ...
;             if (prtN) {
;                 const f32x4 cb0 = *(const LAS f32x4*)(CWL + q16 * 8), cb1 = *(const LAS f32x4*)(CWL + q16 * 8 + 4);
; #pragma unroll
;                 for (int i = 0; i < 2; ++i) {
;                     const int rl = (tid >> 4) + 32 * i, t = (r0N + rl) & 2047;
;                     f32x4 x0 = cb0, x1 = cb1;
; #pragma unroll
;                     for (int k = 0; k < 4; ++k) { const float f = ((3 - k) <= t) ? 1.0f : 0.0f;
;                         const f32x4 w0 = *(const LAS f32x4*)(CWL + (k + 1) * 128 + q16 * 8), w1 = *(const LAS f32x4*)(CWL + (k + 1) * 128 + q16 * 8 + 4);
;                         BF8_TO_F32(pre[i][k], a0, a1); x0 += w0 * (a0 * f); x1 += w1 * (a1 * f); }
;                     *(LAS f32x4*)(XCN + rl * 132 + q16 * 8) = x0; *(LAS f32x4*)(XCN + rl * 132 + q16 * 8 + 4) = x1;
;                     v4u o; o.x = pk2(x0[0], x0[1]); o.y = pk2(x0[2], x0[3]); o.z = pk2(x1[0], x1[1]); o.w = pk2(x1[2], x1[3]);
;                     *(LAS v4u*)(AtN + rl * 136 + q16 * 8) = o;
;                 }
	v_pk_fma_f32 v[80:81], v[68:69], v[80:81], v[72:73]
	v_pk_fma_f32 v[78:79], v[66:67], v[78:79], v[70:71]
	ds_read_b128 v[66:69], v100 offset:1024
	ds_read_b128 v[70:73], v100 offset:1040
	v_cmp_gt_u32_e32 vcc, 2, v92
	s_waitcnt vmcnt(2)
	v_lshlrev_b32_e32 v84, 16, v54
	v_and_b32_e32 v85, 0xffff0000, v54
	v_cndmask_b32_e64 v0, 1.0, 0, vcc
	v_lshlrev_b32_e32 v86, 16, v55
	v_and_b32_e32 v87, 0xffff0000, v55
	v_lshlrev_b32_e32 v88, 16, v56
	v_and_b32_e32 v89, 0xffff0000, v56
	v_lshlrev_b32_e32 v90, 16, v57
	v_and_b32_e32 v91, 0xffff0000, v57
	v_pk_mul_f32 v[86:87], v[0:1], v[86:87] op_sel_hi:[0,1]
	v_pk_mul_f32 v[84:85], v[0:1], v[84:85] op_sel_hi:[0,1]
	s_waitcnt lgkmcnt(1)
	v_pk_fma_f32 v[74:75], v[84:85], v[66:67], v[74:75]
	v_pk_fma_f32 v[76:77], v[86:87], v[68:69], v[76:77]
	v_pk_mul_f32 v[66:67], v[0:1], v[90:91] op_sel_hi:[0,1]
	v_pk_mul_f32 v[68:69], v[0:1], v[88:89] op_sel_hi:[0,1]
	s_waitcnt lgkmcnt(0)
	v_pk_fma_f32 v[78:79], v[68:69], v[70:71], v[78:79]
	v_pk_fma_f32 v[80:81], v[66:67], v[72:73], v[80:81]
	ds_read_b128 v[66:69], v100 offset:1536
	ds_read_b128 v[70:73], v100 offset:1552
	v_cmp_eq_u32_e32 vcc, 0, v92
	s_waitcnt vmcnt(1)
	v_lshlrev_b32_e32 v84, 16, v58
	v_and_b32_e32 v85, 0xffff0000, v58
	v_cndmask_b32_e64 v0, 1.0, 0, vcc
	v_lshlrev_b32_e32 v86, 16, v59
	v_and_b32_e32 v87, 0xffff0000, v59
	v_lshlrev_b32_e32 v88, 16, v60
	v_and_b32_e32 v89, 0xffff0000, v60
	v_lshlrev_b32_e32 v90, 16, v61
	v_and_b32_e32 v91, 0xffff0000, v61
	v_pk_mul_f32 v[84:85], v[0:1], v[84:85] op_sel_hi:[0,1]
	v_pk_mul_f32 v[86:87], v[0:1], v[86:87] op_sel_hi:[0,1]
	s_waitcnt lgkmcnt(1)
	v_pk_fma_f32 v[76:77], v[86:87], v[68:69], v[76:77]
	v_pk_fma_f32 v[74:75], v[84:85], v[66:67], v[74:75]
	v_pk_mul_f32 v[66:67], v[0:1], v[88:89] op_sel_hi:[0,1]
	v_pk_mul_f32 v[68:69], v[0:1], v[90:91] op_sel_hi:[0,1]
	s_waitcnt lgkmcnt(0)
	v_pk_fma_f32 v[80:81], v[68:69], v[72:73], v[80:81]
	v_pk_fma_f32 v[78:79], v[66:67], v[70:71], v[78:79]
	ds_read_b128 v[66:69], v100 offset:2048
	ds_read_b128 v[70:73], v100 offset:2064
	s_waitcnt vmcnt(0)
	v_lshlrev_b32_e32 v84, 16, v62
	v_and_b32_e32 v85, 0xffff0000, v62
	v_lshlrev_b32_e32 v86, 16, v63
	v_and_b32_e32 v87, 0xffff0000, v63
	s_waitcnt lgkmcnt(1)
	v_pk_fma_f32 v[66:67], v[66:67], v[84:85], v[74:75]
	v_lshlrev_b32_e32 v88, 16, v64
	v_and_b32_e32 v89, 0xffff0000, v64
	v_lshlrev_b32_e32 v90, 16, v65
	v_and_b32_e32 v91, 0xffff0000, v65
	v_pk_fma_f32 v[68:69], v[68:69], v[86:87], v[76:77]
	v_bfe_u32 v0, v66, 16, 1
	s_waitcnt lgkmcnt(0)
	v_pk_fma_f32 v[70:71], v[70:71], v[88:89], v[78:79]
	v_pk_fma_f32 v[72:73], v[72:73], v[90:91], v[80:81]
	ds_write_b128 v82, v[66:69] offset:16896
	ds_write_b128 v82, v[70:73] offset:16912
	v_add3_u32 v0, v66, v0, s26
	v_bfe_u32 v66, v67, 16, 1
	v_lshrrev_b32_e32 v0, 16, v0
	v_add3_u32 v66, v67, v66, s26
	v_and_or_b32 v66, v66, s24, v0
	v_bfe_u32 v0, v68, 16, 1
	v_add3_u32 v0, v68, v0, s26
	v_bfe_u32 v67, v69, 16, 1
	v_lshrrev_b32_e32 v0, 16, v0
	v_add3_u32 v67, v69, v67, s26
	v_and_or_b32 v67, v67, s24, v0
	v_bfe_u32 v0, v70, 16, 1
	v_add3_u32 v0, v70, v0, s26
	v_bfe_u32 v68, v71, 16, 1
	v_lshrrev_b32_e32 v0, 16, v0
	v_add3_u32 v68, v71, v68, s26
	v_and_or_b32 v68, v68, s24, v0
	v_bfe_u32 v0, v72, 16, 1
	v_add3_u32 v0, v72, v0, s26
	v_bfe_u32 v69, v73, 16, 1
	v_lshrrev_b32_e32 v0, 16, v0
	v_add3_u32 v69, v73, v69, s26
	v_and_or_b32 v69, v69, s24, v0
	ds_write_b128 v83, v[66:69] offset:8704
; __device__ __forceinline__ void mix_phase(LAS unsigned char* lds, const Params& p, const int layer) {
;     ...
;             if (u0 + G < NUB) MIX_PREFETCH_B(u0 + G);
;             __syncthreads();
.LBB0_403:
	v_readlane_b32 s2, v249, 5
	v_readlane_b32 s3, v249, 6
	s_andn2_b64 vcc, exec, s[2:3]
	s_cbranch_vccnz .LBB0_406
	v_readlane_b32 s2, v249, 7
	v_readlane_b32 s3, v249, 8
	s_andn2_b64 vcc, exec, s[2:3]
	s_cbranch_vccnz .LBB0_406
	v_readlane_b32 s2, v249, 9
	s_waitcnt vmcnt(3)
	v_mov_b64_e32 v[50:51], s[74:75]
	s_mov_b32 s7, s80
	v_add_u32_e32 v0, s2, v226
	v_mad_i64_i32 v[34:35], s[2:3], v0, s25, v[50:51]
	v_readlane_b32 s2, v248, 6
	v_and_b32_e32 v46, 0x7ff, v0
	s_mov_b32 s6, s2
	v_lshl_add_u64 v[34:35], v[34:35], 0, s[6:7]
	v_mov_b32_e32 v139, v1
	v_cmp_gt_u32_e32 vcc, 3, v46
	v_lshl_add_u64 v[42:43], v[34:35], 0, v[138:139]
	s_mov_b64 s[12:13], 0x1000
	v_cndmask_b32_e64 v35, -1, 0, vcc
	v_cndmask_b32_e64 v34, v220, 0, vcc
	v_cmp_gt_u32_e32 vcc, 2, v46
	v_lshl_add_u64 v[44:45], v[42:43], 0, s[12:13]
	s_movk_i32 s2, 0x1000
	v_cndmask_b32_e64 v37, -1, 0, vcc
	v_cndmask_b32_e64 v36, v221, 0, vcc
	v_cmp_eq_u32_e32 vcc, 0, v46
	v_readlane_b32 s3, v248, 7
	v_lshl_add_u64 v[34:35], v[44:45], 0, v[34:35]
	v_cndmask_b32_e64 v47, -1, 0, vcc
	v_cndmask_b32_e64 v46, v222, 0, vcc
	v_lshl_add_u64 v[38:39], v[44:45], 0, v[36:37]
	v_lshl_add_u64 v[44:45], v[44:45], 0, v[46:47]
	v_add_co_u32_e32 v46, vcc, s2, v42
	v_add_u32_e32 v0, 32, v0
	s_nop 0
	v_addc_co_u32_e32 v47, vcc, 0, v43, vcc
	s_waitcnt vmcnt(0)
	v_and_b32_e32 v62, 0x7ff, v0
	v_mad_i64_i32 v[50:51], s[2:3], v0, s25, v[50:51]
	v_lshl_add_u64 v[50:51], v[50:51], 0, s[6:7]
	v_cmp_gt_u32_e32 vcc, 3, v62
	v_lshl_add_u64 v[58:59], v[50:51], 0, v[138:139]
	v_lshl_add_u64 v[60:61], v[58:59], 0, s[12:13]
	v_cndmask_b32_e64 v51, -1, 0, vcc
	v_cndmask_b32_e64 v50, v220, 0, vcc
	v_cmp_gt_u32_e32 vcc, 2, v62
	v_lshl_add_u64 v[50:51], v[60:61], 0, v[50:51]
	global_load_dwordx4 v[34:37], v[34:35], off
	s_nop 0
	global_load_dwordx4 v[38:41], v[38:39], off
	v_cndmask_b32_e64 v53, -1, 0, vcc
	v_cndmask_b32_e64 v52, v221, 0, vcc
	v_cmp_eq_u32_e32 vcc, 0, v62
	v_lshl_add_u64 v[54:55], v[60:61], 0, v[52:53]
	global_load_dwordx4 v[42:45], v[44:45], off
	s_nop 0
	global_load_dwordx4 v[46:49], v[46:47], off
	v_cndmask_b32_e64 v63, -1, 0, vcc
	v_cndmask_b32_e64 v62, v222, 0, vcc
	v_lshl_add_u64 v[60:61], v[60:61], 0, v[62:63]
	v_add_co_u32_e32 v62, vcc, 0x1000, v58
	global_load_dwordx4 v[50:53], v[50:51], off
	s_nop 0
	global_load_dwordx4 v[54:57], v[54:55], off
	v_addc_co_u32_e32 v63, vcc, 0, v59, vcc
	global_load_dwordx4 v[58:61], v[60:61], off
	s_nop 0
	global_load_dwordx4 v[62:65], v[62:63], off
	s_mov_b32 s2, s6
	v_writelane_b32 v248, s2, 6
	s_nop 1
	v_writelane_b32 v248, s3, 7
.LBB0_406:
	v_lshlrev_b32_e32 v0, 3, v137
	v_lshlrev_b32_e32 v66, 4, v130
	v_lshlrev_b32_e32 v70, 1, v0
	v_lshrrev_b32_e32 v0, 1, v137
	v_readlane_b32 s3, v248, 33
	v_and_b32_e32 v140, 0x70, v66
	v_and_b32_e32 v66, 64, v223
	v_or_b32_e32 v228, s3, v0
	v_add_u32_e32 v0, -16, v223
	v_cmp_lt_i32_e32 vcc, v0, v66
	v_ashrrev_i32_e32 v133, 31, v132
	s_mov_b64 s[6:7], 0x26308000
	v_cndmask_b32_e32 v0, v0, v223, vcc
	v_lshlrev_b32_e32 v229, 2, v0
	v_subrev_u32_e32 v0, 32, v223
	v_cmp_lt_i32_e32 vcc, v0, v66
	s_add_i32 s2, s56, 1
	v_readlane_b32 s5, v248, 3
	v_cndmask_b32_e32 v0, v0, v223, vcc
	v_lshlrev_b32_e32 v230, 2, v0
	v_or_b32_e32 v0, v66, v135
	v_lshl_add_u64 v[66:67], v[132:133], 3, s[14:15]
	v_lshl_add_u64 v[142:143], v[66:67], 0, s[6:7]
	v_lshlrev_b64 v[66:67], 2, v[132:133]
	v_lshlrev_b32_e32 v231, 2, v0
	v_lshl_add_u64 v[68:69], s[14:15], 0, v[66:67]
	s_mov_b64 s[6:7], 0x26508000
	v_readlane_b32 s56, v251, 21
	v_lshlrev_b32_e32 v0, 2, v136
	v_ashrrev_i32_e32 v139, 3, v130
	v_bfe_u32 v227, v130, 4, 1
	v_lshl_add_u32 v233, v134, 2, s5
	v_lshl_add_u64 v[144:145], v[68:69], 0, s[6:7]
	s_movk_i32 s5, 0x210
	v_mul_u32_u24_e32 v68, 0x110, v135
	v_readlane_b32 s57, v251, 22
	v_readlane_b32 s64, v251, 29
	v_readlane_b32 s65, v251, 30
	v_readlane_b32 s36, v248, 35
	v_lshl_add_u64 v[148:149], s[0:1], 0, v[0:1]
	v_readlane_b32 s0, v248, 5
	s_mov_b32 s3, 0
	v_or_b32_e32 v232, 0xc0, v231
	v_cmp_eq_u32_e64 s[38:39], 0, v227
	v_cmp_eq_u32_e64 s[40:41], 0, v137
	v_mul_lo_u32 v234, v139, s5
	v_mul_u32_u24_e32 v235, 0x840, v137
	v_mul_lo_u32 v236, v226, s5
	v_or_b32_e32 v237, 64, v231
	v_or_b32_e32 v238, 0x80, v231
	v_readlane_b32 s37, v248, 36
	v_readlane_b32 s56, v248, 31
	v_lshl_add_u64 v[146:147], s[64:65], 0, v[66:67]
	v_add3_u32 v239, s0, v70, v68
	v_lshlrev_b32_e32 v150, 1, v140
	v_lshlrev_b32_e32 v152, 1, v134
	s_mov_b32 s5, 0
	v_readlane_b32 s12, v251, 0
	s_waitcnt lgkmcnt(0)
	s_barrier
	v_readlane_b32 s58, v251, 23
	v_readlane_b32 s59, v251, 24
	v_readlane_b32 s60, v251, 25
	v_readlane_b32 s61, v251, 26
	v_readlane_b32 s62, v251, 27
	v_readlane_b32 s63, v251, 28
	v_readlane_b32 s66, v251, 31
	v_readlane_b32 s67, v251, 32
	v_readlane_b32 s68, v251, 33
	v_readlane_b32 s69, v251, 34
	v_readlane_b32 s70, v251, 35
	v_readlane_b32 s71, v251, 36
	v_readlane_b32 s57, v248, 32
	s_waitcnt vmcnt(0)
	s_branch .LBB0_409

; #define LAS __attribute__((address_space(3)))
; __device__ __forceinline__ unsigned pk2(float lo, float hi) { return f2bf(lo) | (f2bf(hi) << 16); }
; __device__ __forceinline__ float bflo(unsigned w) { return __uint_as_float(w << 16); }
; __device__ __forceinline__ float bfhi(unsigned w) { return __uint_as_float(w & 0xffff0000u); }
; __device__ __forceinline__ void mix_phase(LAS unsigned char* lds, const Params& p, const int layer) {
;     ...
; #pragma unroll
;                 for (int m = 0; m < 4; ++m)
; #pragma unroll
;                     for (int jj = 0; jj < 4; ++jj) XC[(m * 16 + fq * 4 + jj) * 132 + cw + fr] = hl[m][jj];
;                 __syncthreads();
;             {
;                 const int row = yrow, c16 = yc16; const size_t r = (size_t)(r0 + row);
;                 const v4u g0 = sgc0, g1 = sgc1;
;                 const f32x4 h0 = *(const LAS f32x4*)(XC + row * 132 + c16), h1 = *(const LAS f32x4*)(XC + row * 132 + c16 + 4),
;                             h2 = *(const LAS f32x4*)(XC + row * 132 + c16 + 8), h3 = *(const LAS f32x4*)(XC + row * 132 + c16 + 12);
;                 v4u o0, o1;
;                 o0.x = pk2(h0[0] * bflo(g0.x), h0[1] * bfhi(g0.x)); o0.y = pk2(h0[2] * bflo(g0.y), h0[3] * bfhi(g0.y)); o0.z = pk2(h1[0] * bflo(g0.z), h1[1] * bfhi(g0.z)); o0.w = pk2(h1[2] * bflo(g0.w), h1[3] * bfhi(g0.w));
;                 o1.x = pk2(h2[0] * bflo(g1.x), h2[1] * bfhi(g1.x)); o1.y = pk2(h2[2] * bflo(g1.y), h2[3] * bfhi(g1.y)); o1.z = pk2(h3[0] * bflo(g1.z), h3[1] * bfhi(g1.z)); o1.w = pk2(h3[2] * bflo(g1.w), h3[3] * bfhi(g1.w));
;                 bf16* yp = (bf16*)(ws + WS_YA) + r * KCAT + PW + c0 + c16;
;                 *(v4u*)yp = o0; *(v4u*)(yp + 8) = o1;
;             }
.LBB0_408:
	v_add_u32_e32 v0, 0x400, v151
	ds_write2_b32 v0, v156, v157 offset0:8 offset1:140
	v_add_u32_e32 v0, 0x2000, v151
	ds_write2_b32 v0, v78, v79 offset0:64 offset1:196
	v_add_u32_e32 v0, 0x2400, v151
	ds_write2_b32 v0, v168, v169 offset0:72 offset1:204
	v_add_u32_e32 v0, 0x4200, v151
	ds_write2_b32 v0, v76, v77 offset1:132
	v_add_u32_e32 v0, 0x4600, v151
	ds_write2_b32 v0, v180, v181 offset0:8 offset1:140
	v_add_u32_e32 v0, 0x6200, v151
	ds_write2_b32 v0, v74, v75 offset0:64 offset1:196
	v_add_u32_e32 v0, 0x6600, v151
	ds_write2_b32 v0, v190, v191 offset0:72 offset1:204
	v_lshlrev_b32_e32 v0, 2, v140
	v_add3_u32 v0, s6, v234, v0
	ds_write2_b32 v151, v80, v81 offset1:132
	s_waitcnt lgkmcnt(0)
	s_barrier
	ds_read_b128 v[74:77], v0
	ds_read_b128 v[78:81], v0 offset:16
	ds_read_b128 v[82:85], v0 offset:32
	ds_read_b128 v[86:89], v0 offset:48
	v_lshlrev_b32_e32 v91, 16, v71
	v_lshlrev_b32_e32 v90, 16, v70
	s_waitcnt lgkmcnt(0)
	v_mov_b32_e32 v93, v76
	v_and_b32_e32 v71, 0xffff0000, v71
	v_and_b32_e32 v70, 0xffff0000, v70
	v_mov_b32_e32 v76, v75
	v_mov_b32_e32 v92, v74
	v_pk_mul_f32 v[70:71], v[76:77], v[70:71]
	v_lshlrev_b32_e32 v75, 16, v73
	v_lshlrev_b32_e32 v74, 16, v72
	v_mov_b32_e32 v77, v80
	v_and_b32_e32 v73, 0xffff0000, v73
	v_and_b32_e32 v72, 0xffff0000, v72
	v_mov_b32_e32 v80, v79
	v_mov_b32_e32 v76, v78
	v_pk_mul_f32 v[72:73], v[80:81], v[72:73]
	v_pk_mul_f32 v[90:91], v[92:93], v[90:91]
	v_pk_mul_f32 v[74:75], v[76:77], v[74:75]
	v_bfe_u32 v0, v73, 16, 1
	v_bfe_u32 v76, v72, 16, 1
	v_bfe_u32 v77, v71, 16, 1
	v_bfe_u32 v78, v70, 16, 1
	v_add3_u32 v71, v71, v77, s26
	v_add3_u32 v72, v72, v76, s26
	v_add3_u32 v0, v73, v0, s26
	v_bfe_u32 v73, v90, 16, 1
	v_bfe_u32 v76, v91, 16, 1
	v_bfe_u32 v77, v74, 16, 1
	v_add3_u32 v70, v70, v78, s26
	v_bfe_u32 v78, v75, 16, 1
	v_add3_u32 v74, v74, v77, s26
	v_add3_u32 v76, v91, v76, s26
	v_add3_u32 v73, v90, v73, s26
	v_add3_u32 v75, v75, v78, s26
	v_lshrrev_b32_e32 v77, 16, v73
	v_lshrrev_b32_e32 v76, 16, v76
	v_lshrrev_b32_e32 v74, 16, v74
	v_lshrrev_b32_e32 v73, 16, v75
	v_and_or_b32 v72, v72, s24, v74
	v_and_or_b32 v71, v71, s24, v76
	v_and_or_b32 v70, v70, s24, v77
	v_lshlrev_b32_e32 v75, 16, v67
	v_lshlrev_b32_e32 v74, 16, v66
	v_mov_b32_e32 v76, v82
	v_mov_b32_e32 v77, v84
	v_pk_mul_f32 v[74:75], v[76:77], v[74:75]
	v_lshlrev_b32_e32 v77, 16, v69
	v_lshlrev_b32_e32 v76, 16, v68
	v_mov_b32_e32 v79, v88
	v_and_b32_e32 v69, 0xffff0000, v69
	v_and_b32_e32 v68, 0xffff0000, v68
	v_mov_b32_e32 v88, v87
	v_mov_b32_e32 v78, v86
	v_pk_mul_f32 v[68:69], v[88:89], v[68:69]
	v_and_or_b32 v73, v0, s24, v73
	v_and_b32_e32 v67, 0xffff0000, v67
	v_and_b32_e32 v66, 0xffff0000, v66
	v_mov_b32_e32 v84, v83
	v_pk_mul_f32 v[76:77], v[78:79], v[76:77]
	v_bfe_u32 v0, v69, 16, 1
	v_bfe_u32 v78, v68, 16, 1
	v_pk_mul_f32 v[66:67], v[84:85], v[66:67]
	v_add3_u32 v68, v68, v78, s26
	v_add3_u32 v0, v69, v0, s26
	v_bfe_u32 v69, v74, 16, 1
	v_bfe_u32 v78, v75, 16, 1
	v_bfe_u32 v79, v67, 16, 1
	v_bfe_u32 v80, v66, 16, 1
	v_add3_u32 v75, v75, v78, s26
	v_add3_u32 v69, v74, v69, s26
	v_add3_u32 v66, v66, v80, s26
	v_add3_u32 v67, v67, v79, s26
	v_lshrrev_b32_e32 v74, 16, v69
	v_lshrrev_b32_e32 v75, 16, v75
	v_and_or_b32 v67, v67, s24, v75
	v_and_or_b32 v66, v66, s24, v74
	v_mov_b64_e32 v[74:75], s[36:37]
	s_movk_i32 s0, 0x1800
	v_bfe_u32 v79, v76, 16, 1
	v_mad_i64_i32 v[74:75], s[0:1], v240, s0, v[74:75]
	s_mov_b32 s53, s80
	v_bfe_u32 v80, v77, 16, 1
	v_add3_u32 v76, v76, v79, s26
	v_lshl_add_u64 v[74:75], v[74:75], 0, s[52:53]
	v_mov_b32_e32 v151, v1
	v_add3_u32 v77, v77, v80, s26
	v_lshrrev_b32_e32 v76, 16, v76
	v_lshl_add_u64 v[74:75], v[74:75], 0, v[150:151]
	s_mov_b64 s[0:1], 0x15304800
	v_lshrrev_b32_e32 v69, 16, v77
	v_and_or_b32 v68, v68, s24, v76
	v_lshl_add_u64 v[76:77], v[74:75], 0, s[0:1]
	v_add_co_u32_e32 v74, vcc, 0x15304000, v74
	s_mov_b32 s12, s13
	s_nop 0
	v_addc_co_u32_e32 v75, vcc, 0, v75, vcc
	s_andn2_b64 vcc, exec, s[82:83]
	v_and_or_b32 v69, v0, s24, v69
	global_store_dwordx4 v[74:75], v[70:73], off offset:2048
	global_store_dwordx4 v[76:77], v[66:69], off offset:16
	s_cbranch_vccz .LBB0_545

; #define LAS __attribute__((address_space(3)))
; __device__ __forceinline__ void mix_phase(LAS unsigned char* lds, const Params& p, const int layer) {
;     ...
;             for (int u = u0; u < NUB; u += G) {
;                 const int s_ = u >> 4, r0 = mix_tile_row0(s_);
;                 const bool prt = s_ < 128;
;                 LAS float* XC = XC3 + xb * (33792 / 4); LAS bf16* At = At2 + ab * (17408 / 2);
;                 const int xbn = (xb == 2) ? 0 : xb + 1, abn = ab ^ 1;
;                 const v4u sgc0 = *(const v4u*)(PROJ + (size_t)(r0 + yrow) * NC + C_GB + c0 + yc16), sgc1 = *(const v4u*)(PROJ + (size_t)(r0 + yrow) * NC + C_GB + c0 + yc16 + 8);
;             f32x4 accr[4], acci[4];
; #pragma unroll
;             for (int m = 0; m < 4; ++m) { accr[m] = (f32x4){0.f, 0.f, 0.f, 0.f}; acci[m] = (f32x4){0.f, 0.f, 0.f, 0.f}; }
; #pragma unroll
;             for (int ks = 0; ks < 4; ++ks)
; #pragma unroll
;                 for (int m = 0; m < 4; ++m) { const bf16x8 a = *(const LAS bf16x8*)(At + (m * 16 + fr) * 136 + ks * 32 + fq * 8);
;                     accr[m] = __builtin_amdgcn_mfma_f32_16x16x32_bf16(a, ba[ks], accr[m], 0, 0, 0);
;                     acci[m] = __builtin_amdgcn_mfma_f32_16x16x32_bf16(a, bx[ks], acci[m], 0, 0, 0); }
;             float hl[4][4], pl[4][4];
;             float Hc = 0.f, Pc = 1.f;
;             const int gq = prt ? fq : (fq & 1);
;             float h0s[4] = {0.f, 0.f, 0.f, 0.f};
;             if (!prt) {
; #pragma unroll
;                 for (int m = 0; m < 4; ++m) h0s[m] = p.in[4][(size_t)(layer * 128 + ((r0 - NP) >> 3) + 2 * m + (fq >> 1)) * LW + ch];
.LBB0_413:
	v_add_u32_e32 v240, s7, v139
	v_mov_b64_e32 v[66:67], s[74:75]
	v_readlane_b32 s6, v250, 62
	v_mad_i64_i32 v[66:67], s[14:15], v240, s25, v[66:67]
	s_lshl_b32 s52, s6, 1
	s_mov_b32 s53, s80
	v_lshl_add_u64 v[66:67], v[66:67], 0, s[52:53]
	v_mov_b32_e32 v151, v1
	v_lshl_add_u64 v[66:67], v[66:67], 0, v[150:151]
	s_mov_b64 s[14:15], 0x2000
	v_lshl_add_u64 v[68:69], v[66:67], 0, s[14:15]
	v_add_co_u32_e32 v66, vcc, 0x2000, v66
	s_mul_i32 s6, s5, 0x4400
	s_nop 0
	v_addc_co_u32_e32 v67, vcc, 0, v67, vcc
	v_add_u32_e32 v0, s6, v239
	global_load_dwordx4 v[70:73], v[66:67], off
	s_nop 0
	global_load_dwordx4 v[66:69], v[68:69], off offset:16
	ds_read_b128 v[74:77], v0
	ds_read_b128 v[108:111], v0 offset:64
	s_waitcnt lgkmcnt(0)
	v_mfma_f32_16x16x32_bf16 v[78:81], v[74:77], v[2:5], 0
	ds_read_b128 v[82:85], v0 offset:4352
	ds_read_b128 v[90:93], v0 offset:8704
	ds_read_b128 v[98:101], v0 offset:13056
	v_mfma_f32_16x16x32_bf16 v[74:77], v[74:77], v[6:9], 0
	s_andn2_b64 vcc, exec, s[0:1]
	v_mov_b32_e32 v106, 0
	v_mfma_f32_16x16x32_bf16 v[78:81], v[108:111], v[10:13], v[78:81]
	v_mfma_f32_16x16x32_bf16 v[74:77], v[108:111], v[18:21], v[74:77]
	ds_read_b128 v[108:111], v0 offset:4416
	s_waitcnt lgkmcnt(3)
	v_mfma_f32_16x16x32_bf16 v[86:89], v[82:85], v[2:5], 0
	v_mfma_f32_16x16x32_bf16 v[82:85], v[82:85], v[6:9], 0
	s_waitcnt lgkmcnt(0)
	v_mfma_f32_16x16x32_bf16 v[86:89], v[108:111], v[10:13], v[86:89]
	v_mfma_f32_16x16x32_bf16 v[82:85], v[108:111], v[18:21], v[82:85]
	ds_read_b128 v[108:111], v0 offset:8768
	v_mfma_f32_16x16x32_bf16 v[94:97], v[90:93], v[2:5], 0
	v_mfma_f32_16x16x32_bf16 v[90:93], v[90:93], v[6:9], 0
	s_waitcnt lgkmcnt(0)
	v_mfma_f32_16x16x32_bf16 v[94:97], v[108:111], v[10:13], v[94:97]
	v_mfma_f32_16x16x32_bf16 v[90:93], v[108:111], v[18:21], v[90:93]
	ds_read_b128 v[108:111], v0 offset:13120
	v_mfma_f32_16x16x32_bf16 v[102:105], v[98:101], v[2:5], 0
	v_mfma_f32_16x16x32_bf16 v[98:101], v[98:101], v[6:9], 0
	s_waitcnt lgkmcnt(0)
	v_mfma_f32_16x16x32_bf16 v[102:105], v[108:111], v[10:13], v[102:105]
	v_mfma_f32_16x16x32_bf16 v[98:101], v[108:111], v[18:21], v[98:101]
	ds_read_b128 v[108:111], v0 offset:128
	s_waitcnt lgkmcnt(0)
	v_mfma_f32_16x16x32_bf16 v[78:81], v[108:111], v[14:17], v[78:81]
	v_mfma_f32_16x16x32_bf16 v[74:77], v[108:111], v[26:29], v[74:77]
	ds_read_b128 v[108:111], v0 offset:4480
	s_waitcnt lgkmcnt(0)
	v_mfma_f32_16x16x32_bf16 v[86:89], v[108:111], v[14:17], v[86:89]
	v_mfma_f32_16x16x32_bf16 v[82:85], v[108:111], v[26:29], v[82:85]
	ds_read_b128 v[108:111], v0 offset:8832
	s_waitcnt lgkmcnt(0)
	v_mfma_f32_16x16x32_bf16 v[112:115], v[108:111], v[14:17], v[94:97]
	v_mfma_f32_16x16x32_bf16 v[108:111], v[108:111], v[26:29], v[90:93]
	s_nop 2
	ds_read_b128 v[90:93], v0 offset:13184
	s_waitcnt lgkmcnt(0)
	v_mfma_f32_16x16x32_bf16 v[116:119], v[90:93], v[14:17], v[102:105]
	v_mfma_f32_16x16x32_bf16 v[120:123], v[90:93], v[26:29], v[98:101]
	ds_read_b128 v[90:93], v0 offset:192
	s_waitcnt lgkmcnt(0)
	v_mfma_f32_16x16x32_bf16 v[98:101], v[90:93], v[30:33], v[74:77]
	s_nop 2
	ds_read_b128 v[74:77], v0 offset:4544
	v_mfma_f32_16x16x32_bf16 v[102:105], v[90:93], v[22:25], v[78:81]
	s_waitcnt lgkmcnt(0)
	v_mfma_f32_16x16x32_bf16 v[94:97], v[74:77], v[22:25], v[86:89]
	v_mfma_f32_16x16x32_bf16 v[90:93], v[74:77], v[30:33], v[82:85]
	ds_read_b128 v[74:77], v0 offset:8896
	s_waitcnt lgkmcnt(0)
	v_mfma_f32_16x16x32_bf16 v[86:89], v[74:77], v[22:25], v[112:115]
	v_mfma_f32_16x16x32_bf16 v[82:85], v[74:77], v[30:33], v[108:111]
	ds_read_b128 v[74:77], v0 offset:13248
	v_mov_b32_e32 v0, 0
	s_waitcnt lgkmcnt(0)
	v_mfma_f32_16x16x32_bf16 v[78:81], v[74:77], v[22:25], v[116:119]
	v_mov_b32_e32 v109, 0
	v_mov_b32_e32 v108, 0
	v_mfma_f32_16x16x32_bf16 v[74:77], v[74:77], v[30:33], v[120:123]
	s_cbranch_vccnz .LBB0_415
	s_add_i32 s0, s7, 0xffffe000
	s_ashr_i32 s0, s0, 3
	v_add_u32_e32 v108, s0, v228
	v_ashrrev_i32_e32 v109, 31, v108
	v_lshlrev_b64 v[108:109], 13, v[108:109]
	v_lshl_add_u64 v[110:111], v[146:147], 0, v[108:109]
	v_add_co_u32_e32 v112, vcc, 0x4000, v110
	global_load_dword v109, v[110:111], off
	s_nop 0
	v_addc_co_u32_e32 v113, vcc, 0, v111, vcc
	global_load_dword v108, v[112:113], off
	v_add_co_u32_e32 v112, vcc, 0x8000, v110
	s_nop 1
	v_addc_co_u32_e32 v113, vcc, 0, v111, vcc
	v_add_co_u32_e32 v110, vcc, 0xc000, v110
	global_load_dword v106, v[112:113], off
	s_nop 0
	v_addc_co_u32_e32 v111, vcc, 0, v111, vcc
	global_load_dword v0, v[110:111], off

; __device__ __forceinline__ void mix_phase(LAS unsigned char* lds, const Params& p, const int layer) {
;     ...
;                 if (prt) {
;                 const int b_ = r0 >> 11, c_ = (r0 & 2047) >> 6;
;                 const unsigned tag = (unsigned)layer + 1u;
;                 unsigned long long* T1 = (unsigned long long*)(ws + WS_TOT2) + (size_t)(b_ * 32) * LW + ch;
;                 unsigned* PF = (unsigned*)(ws + WS_PREF2) + (size_t)(b_ * 32) * LW + ch;
;                 if (fq == 0) __hip_atomic_store(T1 + (size_t)c_ * LW, ((unsigned long long)__float_as_uint(Hc) << 32) | (unsigned long long)((__float_as_uint(Pc) & ~3u) | tag), RLX_AGENT);
;                 }
.LBB0_481:
	s_or_b64 exec, exec, s[0:1]
	s_and_b64 s[14:15], s[42:43], s[40:41]
	s_and_saveexec_b64 s[0:1], s[14:15]
	s_cbranch_execz .LBB0_483
	s_ashr_i32 s13, s7, 6
	s_and_b32 s14, s13, 0xffffffe0
	s_ashr_i32 s15, s14, 31
	s_lshl_b64 s[14:15], s[14:15], 14
	s_lshl_b32 s13, s7, 8
	v_lshl_add_u64 v[74:75], v[142:143], 0, s[14:15]
	s_and_b32 s14, s13, 0x7c000
	s_mov_b32 s15, s80
	v_lshl_add_u64 v[74:75], v[74:75], 0, s[14:15]
	s_waitcnt lgkmcnt(0)
	v_and_or_b32 v198, v241, -4, s2
	global_store_dwordx2 v[74:75], v[198:199], off sc1

; #define LAS __attribute__((address_space(3)))
; __device__ __forceinline__ unsigned pk2(float lo, float hi) { return f2bf(lo) | (f2bf(hi) << 16); }
; #define BF8_TO_F32(vw, lo, hi) const f32x4 lo = {bflo(vw.x), bfhi(vw.x), bflo(vw.y), bfhi(vw.y)}, hi = {bflo(vw.z), bfhi(vw.z), bflo(vw.w), bfhi(vw.w)}
; __device__ __forceinline__ void mix_phase(LAS unsigned char* lds, const Params& p, const int layer) {
;     ...
;                 for (int i = 0; i < 2; ++i) {
;                     const int rl = (tid >> 4) + 32 * i, r = r0N + rl, c = c0 + q16 * 8, t = (r - NP) & 7, bs = (r - NP) >> 3;
;                     f32x4 x0 = *(const LAS f32x4*)(CWL + q16 * 8), x1 = *(const LAS f32x4*)(CWL + q16 * 8 + 4);
; #pragma unroll
;                     for (int k = 0; k < 4; ++k) { const int jb = 3 - k;
;                         const f32x4 w0 = *(const LAS f32x4*)(CWL + (k + 1) * 128 + q16 * 8), w1 = *(const LAS f32x4*)(CWL + (k + 1) * 128 + q16 * 8 + 4);
;                         if (jb <= t) { const v4u vw = *(const v4u*)(PROJ + (size_t)(r - jb) * NC + C_UB + c); BF8_TO_F32(vw, a0, a1); x0 += w0 * a0; x1 += w1 * a1; }
;                         else { const float* sp = sconv + ((size_t)bs * 3 + (3 + t - jb)) * LW + c; x0 += w0 * *(const f32x4*)sp; x1 += w1 * *(const f32x4*)(sp + 4); }
;                     }
;                     *(LAS f32x4*)(XCN + rl * 132 + q16 * 8) = x0; *(LAS f32x4*)(XCN + rl * 132 + q16 * 8 + 4) = x1;
;                     v4u o; o.x = pk2(x0[0], x0[1]); o.y = pk2(x0[2], x0[3]); o.z = pk2(x1[0], x1[1]); o.w = pk2(x1[2], x1[3]);
;                     *(LAS v4u*)(AtN + rl * 136 + q16 * 8) = o;
.LBB0_490:
	s_or_b64 exec, exec, s[50:51]
	s_waitcnt lgkmcnt(0)
	s_waitcnt vmcnt(1)
	v_pk_fma_f32 v[74:75], v[82:83], v[94:95], v[74:75]
	v_mov_b64_e32 v[82:83], s[74:75]
	s_xor_b64 s[86:87], s[0:1], -1
	v_mad_i64_i32 v[82:83], s[0:1], v171, s25, v[82:83]
	v_lshl_add_u64 v[82:83], v[82:83], 0, v[0:1]
	s_movk_i32 s0, 0x1000
	s_waitcnt vmcnt(0)
	v_pk_fma_f32 v[80:81], v[88:89], v[92:93], v[80:81]
	v_pk_fma_f32 v[78:79], v[86:87], v[90:91], v[78:79]
	v_pk_fma_f32 v[76:77], v[84:85], v[96:97], v[76:77]
	v_add_co_u32_e32 v82, vcc, s0, v82
	v_pk_fma_f32 v[80:81], v[104:105], v[108:109], v[80:81]
	v_pk_fma_f32 v[78:79], v[102:103], v[106:107], v[78:79]
	v_pk_fma_f32 v[76:77], v[100:101], v[112:113], v[76:77]
	v_pk_fma_f32 v[74:75], v[98:99], v[110:111], v[74:75]
	v_addc_co_u32_e32 v83, vcc, 0, v83, vcc
	v_pk_fma_f32 v[86:87], v[120:121], v[124:125], v[80:81]
	v_pk_fma_f32 v[88:89], v[118:119], v[122:123], v[78:79]
	v_pk_fma_f32 v[90:91], v[116:117], v[128:129], v[76:77]
	v_pk_fma_f32 v[92:93], v[114:115], v[126:127], v[74:75]
	ds_read_b128 v[74:77], v233 offset:2048
	ds_read_b128 v[78:81], v233 offset:2064
	global_load_dwordx4 v[82:85], v[82:83], off
	s_movk_i32 s0, 0x210
	s_mov_b32 s17, 32
	s_andn2_b64 vcc, exec, s[86:87]
	s_waitcnt lgkmcnt(0)
	s_waitcnt vmcnt(0)
	v_lshlrev_b32_e32 v96, 16, v82
	v_and_b32_e32 v97, 0xffff0000, v82
	v_lshlrev_b32_e32 v82, 16, v83
	v_and_b32_e32 v83, 0xffff0000, v83
	v_pk_fma_f32 v[74:75], v[74:75], v[96:97], v[88:89]
	v_lshlrev_b32_e32 v94, 16, v84
	v_and_b32_e32 v95, 0xffff0000, v84
	v_lshlrev_b32_e32 v84, 16, v85
	v_and_b32_e32 v85, 0xffff0000, v85
	v_pk_fma_f32 v[76:77], v[76:77], v[82:83], v[86:87]
	v_mad_u64_u32 v[82:83], s[0:1], v159, s0, v[198:199]
	v_bfe_u32 v0, v74, 16, 1
	v_pk_fma_f32 v[80:81], v[80:81], v[84:85], v[90:91]
	v_pk_fma_f32 v[78:79], v[78:79], v[94:95], v[92:93]
	ds_write_b128 v82, v[74:77]
	ds_write_b128 v82, v[78:81] offset:16
	v_add3_u32 v0, v74, v0, s26
	v_bfe_u32 v74, v75, 16, 1
	v_lshrrev_b32_e32 v0, 16, v0
	v_add3_u32 v74, v75, v74, s26
	v_and_or_b32 v74, v74, s24, v0
	v_bfe_u32 v0, v76, 16, 1
	v_add3_u32 v0, v76, v0, s26
	v_bfe_u32 v75, v77, 16, 1
	v_lshrrev_b32_e32 v0, 16, v0
	v_add3_u32 v75, v77, v75, s26
	v_and_or_b32 v75, v75, s24, v0
	v_bfe_u32 v0, v78, 16, 1
	v_add3_u32 v0, v78, v0, s26
	v_bfe_u32 v76, v79, 16, 1
	v_lshrrev_b32_e32 v0, 16, v0
	v_add3_u32 v76, v79, v76, s26
	v_and_or_b32 v76, v76, s24, v0
	v_bfe_u32 v0, v80, 16, 1
	v_add3_u32 v0, v80, v0, s26
	v_bfe_u32 v77, v81, 16, 1
	s_movk_i32 s0, 0x110
	v_lshrrev_b32_e32 v0, 16, v0
	v_add3_u32 v77, v81, v77, s26
	v_mad_u64_u32 v[78:79], s[0:1], v159, s0, v[208:209]
	v_and_or_b32 v77, v77, s24, v0
	s_mov_b64 s[0:1], 0
	ds_write_b128 v78, v[74:77]
	s_cbranch_vccz .LBB0_503
.LBB0_491:
	ds_read_b128 v[78:81], v233
	ds_read_b128 v[74:77], v233 offset:16
	ds_read_b128 v[86:89], v233 offset:512
	ds_read_b128 v[82:85], v233 offset:528
	v_add_u32_e32 v159, s17, v226
	v_add_u32_e32 v171, s16, v159
	v_lshlrev_b32_e32 v0, 1, v136
	s_and_saveexec_b64 s[20:21], s[44:45]
	s_xor_b64 s[50:51], exec, s[20:21]
	s_cbranch_execz .LBB0_493
	v_add_u32_e32 v92, -3, v171
	v_mov_b64_e32 v[90:91], s[74:75]
	v_mad_i64_i32 v[90:91], s[20:21], v92, s25, v[90:91]
	v_lshl_add_u64 v[90:91], v[90:91], 0, v[0:1]
	v_add_co_u32_e32 v90, vcc, 0x1000, v90
	s_nop 1
	v_addc_co_u32_e32 v91, vcc, 0, v91, vcc
	global_load_dwordx4 v[94:97], v[90:91], off
	s_waitcnt lgkmcnt(0)
	s_waitcnt vmcnt(0)
	v_lshlrev_b32_e32 v90, 16, v94
	v_and_b32_e32 v91, 0xffff0000, v94
	v_lshlrev_b32_e32 v92, 16, v95
	v_and_b32_e32 v93, 0xffff0000, v95
	v_lshlrev_b32_e32 v94, 16, v96
	v_and_b32_e32 v95, 0xffff0000, v96
	v_lshlrev_b32_e32 v96, 16, v97
	v_and_b32_e32 v97, 0xffff0000, v97

; #define LAS __attribute__((address_space(3)))
; #define BF8_TO_F32(vw, lo, hi) const f32x4 lo = {bflo(vw.x), bfhi(vw.x), bflo(vw.y), bfhi(vw.y)}, hi = {bflo(vw.z), bfhi(vw.z), bflo(vw.w), bfhi(vw.w)}
; __device__ __forceinline__ void mix_phase(LAS unsigned char* lds, const Params& p, const int layer) {
;     ...
;                     for (int k = 0; k < 4; ++k) { const int jb = 3 - k;
;                         const f32x4 w0 = *(const LAS f32x4*)(CWL + (k + 1) * 128 + q16 * 8), w1 = *(const LAS f32x4*)(CWL + (k + 1) * 128 + q16 * 8 + 4);
;                         if (jb <= t) { const v4u vw = *(const v4u*)(PROJ + (size_t)(r - jb) * NC + C_UB + c); BF8_TO_F32(vw, a0, a1); x0 += w0 * a0; x1 += w1 * a1; }
.LBB0_495:
	s_or_b64 exec, exec, s[50:51]
	ds_read_b128 v[102:105], v233 offset:1024
	ds_read_b128 v[98:101], v233 offset:1040
	s_and_saveexec_b64 s[20:21], s[46:47]
	s_xor_b64 s[50:51], exec, s[20:21]
	s_cbranch_execz .LBB0_497
	v_add_u32_e32 v108, -2, v171
	v_mov_b64_e32 v[106:107], s[74:75]
	v_mad_i64_i32 v[106:107], s[20:21], v108, s25, v[106:107]
	v_lshl_add_u64 v[106:107], v[106:107], 0, v[0:1]
	v_add_co_u32_e32 v106, vcc, 0x1000, v106
	s_nop 1
	v_addc_co_u32_e32 v107, vcc, 0, v107, vcc
	global_load_dwordx4 v[110:113], v[106:107], off
	s_waitcnt lgkmcnt(0)
	s_waitcnt vmcnt(0)
	v_lshlrev_b32_e32 v106, 16, v110
	v_and_b32_e32 v107, 0xffff0000, v110
	v_lshlrev_b32_e32 v108, 16, v111
	v_and_b32_e32 v109, 0xffff0000, v111
	v_lshlrev_b32_e32 v110, 16, v112
	v_and_b32_e32 v111, 0xffff0000, v112
	v_lshlrev_b32_e32 v112, 16, v113
	v_and_b32_e32 v113, 0xffff0000, v113

; #define LAS __attribute__((address_space(3)))
; #define BF8_TO_F32(vw, lo, hi) const f32x4 lo = {bflo(vw.x), bfhi(vw.x), bflo(vw.y), bfhi(vw.y)}, hi = {bflo(vw.z), bfhi(vw.z), bflo(vw.w), bfhi(vw.w)}
; __device__ __forceinline__ void mix_phase(LAS unsigned char* lds, const Params& p, const int layer) {
;     ...
;                     for (int k = 0; k < 4; ++k) { const int jb = 3 - k;
;                         const f32x4 w0 = *(const LAS f32x4*)(CWL + (k + 1) * 128 + q16 * 8), w1 = *(const LAS f32x4*)(CWL + (k + 1) * 128 + q16 * 8 + 4);
;                         if (jb <= t) { const v4u vw = *(const v4u*)(PROJ + (size_t)(r - jb) * NC + C_UB + c); BF8_TO_F32(vw, a0, a1); x0 += w0 * a0; x1 += w1 * a1; }
.LBB0_499:
	s_or_b64 exec, exec, s[20:21]
	ds_read_b128 v[118:121], v233 offset:1536
	ds_read_b128 v[114:117], v233 offset:1552
	s_and_saveexec_b64 s[20:21], s[48:49]
	s_xor_b64 s[50:51], exec, s[20:21]
	s_cbranch_execz .LBB0_501
	v_add_u32_e32 v124, -1, v171
	v_mov_b64_e32 v[122:123], s[74:75]
	v_mad_i64_i32 v[122:123], s[20:21], v124, s25, v[122:123]
	v_lshl_add_u64 v[122:123], v[122:123], 0, v[0:1]
	v_add_co_u32_e32 v122, vcc, 0x1000, v122
	s_nop 1
	v_addc_co_u32_e32 v123, vcc, 0, v123, vcc
	global_load_dwordx4 v[126:129], v[122:123], off
	s_waitcnt lgkmcnt(0)
	s_waitcnt vmcnt(0)
	v_lshlrev_b32_e32 v122, 16, v126
	v_and_b32_e32 v123, 0xffff0000, v126
	v_lshlrev_b32_e32 v124, 16, v127
	v_and_b32_e32 v125, 0xffff0000, v127
	v_lshlrev_b32_e32 v126, 16, v128
	v_and_b32_e32 v127, 0xffff0000, v128
	v_lshlrev_b32_e32 v128, 16, v129
	v_and_b32_e32 v129, 0xffff0000, v129

; __device__ __forceinline__ void mix_phase(LAS unsigned char* lds, const Params& p, const int layer) {
;     ...
;                     if (u + 2 * G < NUB) MIX_PREFETCH_B(u + 2 * G);
.LBB0_510:
	v_add_u32_e32 v0, s14, v226
	v_mov_b64_e32 v[50:51], s[74:75]
	v_mad_i64_i32 v[34:35], s[0:1], v0, s25, v[50:51]
	s_lshl_b32 s0, s12, 8
	v_and_b32_e32 v46, 0x7ff, v0
	s_and_b32 s0, s0, 0xf00
	s_mov_b32 s1, s80
	v_lshl_add_u64 v[34:35], v[34:35], 0, s[0:1]
	v_mov_b32_e32 v153, v1
	v_cmp_gt_u32_e32 vcc, 3, v46
	v_lshl_add_u64 v[42:43], v[34:35], 0, v[152:153]
	s_mov_b64 s[16:17], 0x1000
	v_cndmask_b32_e64 v35, -1, 0, vcc
	v_cndmask_b32_e64 v34, v220, 0, vcc
	v_cmp_gt_u32_e32 vcc, 2, v46
	v_lshl_add_u64 v[44:45], v[42:43], 0, s[16:17]
	s_movk_i32 s12, 0x1000
	v_cndmask_b32_e64 v37, -1, 0, vcc
	v_cndmask_b32_e64 v36, v221, 0, vcc
	v_cmp_eq_u32_e32 vcc, 0, v46
	v_lshl_add_u64 v[34:35], v[44:45], 0, v[34:35]
	v_lshl_add_u64 v[38:39], v[44:45], 0, v[36:37]
	v_cndmask_b32_e64 v47, -1, 0, vcc
	v_cndmask_b32_e64 v46, v222, 0, vcc
	v_lshl_add_u64 v[44:45], v[44:45], 0, v[46:47]
	v_add_co_u32_e32 v46, vcc, s12, v42
	v_add_u32_e32 v0, 32, v0
	s_nop 0
	v_addc_co_u32_e32 v47, vcc, 0, v43, vcc
	v_and_b32_e32 v62, 0x7ff, v0
	v_mad_i64_i32 v[50:51], s[14:15], v0, s25, v[50:51]
	v_lshl_add_u64 v[50:51], v[50:51], 0, s[0:1]
	v_cmp_gt_u32_e32 vcc, 3, v62
	v_lshl_add_u64 v[58:59], v[50:51], 0, v[152:153]
	v_lshl_add_u64 v[60:61], v[58:59], 0, s[16:17]
	v_cndmask_b32_e64 v51, -1, 0, vcc
	v_cndmask_b32_e64 v50, v220, 0, vcc
	v_cmp_gt_u32_e32 vcc, 2, v62
	v_lshl_add_u64 v[50:51], v[60:61], 0, v[50:51]
	global_load_dwordx4 v[34:37], v[34:35], off
	s_nop 0
	global_load_dwordx4 v[38:41], v[38:39], off
	v_cndmask_b32_e64 v53, -1, 0, vcc
	v_cndmask_b32_e64 v52, v221, 0, vcc
	v_cmp_eq_u32_e32 vcc, 0, v62
	v_lshl_add_u64 v[54:55], v[60:61], 0, v[52:53]
	global_load_dwordx4 v[42:45], v[44:45], off
	s_nop 0
	global_load_dwordx4 v[46:49], v[46:47], off
	v_cndmask_b32_e64 v63, -1, 0, vcc
	v_cndmask_b32_e64 v62, v222, 0, vcc
	v_lshl_add_u64 v[60:61], v[60:61], 0, v[62:63]
	v_add_co_u32_e32 v62, vcc, 0x1000, v58
	global_load_dwordx4 v[50:53], v[50:51], off
	s_nop 0
	global_load_dwordx4 v[54:57], v[54:55], off
	v_addc_co_u32_e32 v63, vcc, 0, v59, vcc
	global_load_dwordx4 v[58:61], v[60:61], off
	s_nop 0
	global_load_dwordx4 v[62:65], v[62:63], off

; __device__ __forceinline__ void mix_phase(LAS unsigned char* lds, const Params& p, const int layer) {
;     ...
;                         for (;;) {
;                             bool v1 = true, v2 = true;
;                             if (jc >= 0) { w1 = __hip_atomic_load(T1 + (size_t)jc * LW, RLX_AGENT); w2 = __hip_atomic_load(PF + (size_t)jc * LW, RLX_AGENT);
;                                 v1 = (((unsigned)w1) & 3u) == tag; v2 = (w2 & 3u) == tag; }
.LBB0_518:
	s_or_b64 s[86:87], s[86:87], exec
	s_or_b64 s[90:91], s[90:91], exec
	s_and_saveexec_b64 s[46:47], s[0:1]
	s_cbranch_execz .LBB0_517
	global_load_dwordx2 v[88:89], v[90:91], off sc1
	global_load_dword v96, v[92:93], off sc1
	s_andn2_b64 s[16:17], s[86:87], exec
	s_waitcnt lgkmcnt(0)
	s_waitcnt vmcnt(1)
	v_and_b32_e32 v0, 3, v88
	v_cmp_eq_u32_e32 vcc, s2, v0
	s_waitcnt vmcnt(0)
	v_and_b32_e32 v0, 3, v96
	v_cmp_eq_u32_e64 s[44:45], s2, v0
	s_and_b64 s[20:21], s[44:45], exec
	s_or_b64 s[86:87], s[16:17], s[20:21]
	s_andn2_b64 s[16:17], s[90:91], exec
	s_and_b64 s[20:21], vcc, exec
	s_or_b64 s[90:91], s[16:17], s[20:21]
	s_branch .LBB0_517

; __device__ __forceinline__ void mix_phase(LAS unsigned char* lds, const Params& p, const int layer) {
;     ...
;                 const float Hout = Pc * Hin + Hc;
;                 if (fq == 0) __hip_atomic_store(PF + (size_t)c_ * LW, (__float_as_uint(Hout) & ~3u) | tag, RLX_AGENT);
.LBB0_541:
	s_waitcnt lgkmcnt(0)
	v_cndmask_b32_e64 v0, 0, v199, s[42:43]
	v_cndmask_b32_e64 v83, 1.0, v241, s[42:43]
	v_fmac_f32_e32 v0, v83, v82
	s_and_saveexec_b64 s[0:1], s[40:41]
	s_cbranch_execz .LBB0_543
	s_lshl_b32 s14, s7, 13
	s_mov_b32 s15, s80
	v_lshl_add_u64 v[84:85], v[84:85], 0, s[14:15]
	v_and_or_b32 v83, v0, -4, s2
	global_store_dword v[84:85], v83, off sc1

; __device__ __forceinline__ void mix_phase(LAS unsigned char* lds, const Params& p, const int layer) {
;     ...
;         int ua = (int)blockIdx.x;
;         if (ua < NUA) MIX_PREFETCH_A(ua);
.LBB0_545:
	v_readlane_b32 s0, v249, 11
	v_readlane_b32 s1, v249, 12
	s_andn2_b64 vcc, exec, s[0:1]
	s_waitcnt lgkmcnt(0)
	s_barrier
	s_cbranch_vccnz .LBB0_598
	v_readlane_b32 s0, v249, 17
	s_waitcnt vmcnt(1)
	v_mov_b64_e32 v[2:3], s[74:75]
	s_mov_b32 s43, s80
	v_or_b32_e32 v6, s0, v135
	v_readlane_b32 s0, v248, 34
	s_lshl_b32 s46, s0, 5
	v_mad_i64_i32 v[4:5], s[0:1], v6, s25, v[2:3]
	v_readlane_b32 s0, v249, 13
	s_ashr_i32 s47, s46, 31
	s_lshl_b32 s42, s0, 1
	v_or_b32_e32 v6, 16, v6
	v_lshl_add_u64 v[4:5], v[4:5], 0, s[42:43]
	s_lshl_b64 s[82:83], s[46:47], 1
	v_mad_i64_i32 v[2:3], s[0:1], v6, s25, v[2:3]
	v_lshl_add_u64 v[4:5], v[4:5], 0, s[82:83]
	v_lshlrev_b32_e32 v0, 3, v137
	v_lshl_add_u64 v[2:3], v[2:3], 0, s[42:43]
	v_lshl_add_u64 v[4:5], v[4:5], 0, v[0:1]
	v_lshl_add_u64 v[2:3], v[2:3], 0, s[82:83]
	v_lshl_add_u64 v[2:3], v[2:3], 0, v[0:1]
	global_load_dwordx2 v[108:109], v[4:5], off offset:2048
	global_load_dwordx2 v[104:105], v[2:3], off offset:2048
	global_load_dwordx2 v[102:103], v[2:3], off offset:2080
	global_load_dwordx2 v[106:107], v[4:5], off offset:2080
	v_readlane_b32 s2, v249, 14
	v_and_b32_e32 v18, 31, v130
	v_ashrrev_i32_e32 v121, 5, v130
	v_readlane_b32 s3, v249, 15
	s_mov_b64 s[0:1], -1
	s_andn2_b64 vcc, exec, s[2:3]
	v_lshlrev_b32_e32 v16, 3, v18
	v_add_u32_e32 v19, 16, v121
	v_add_u32_e32 v20, 32, v121
	s_cbranch_vccnz .LBB0_548
	v_lshlrev_b32_e32 v0, 3, v18
	v_add_u32_e32 v131, 16, v121
	v_add_u32_e32 v132, 32, v121
	s_mov_b64 s[0:1], 0
	v_mov_b32_e32 v133, v0
	v_mov_b64_e32 v[14:15], v[0:1]
.LBB0_548:
	s_andn2_b64 vcc, exec, s[0:1]
	v_cmp_gt_i32_e64 s[40:41], 47, v121
	v_cmp_gt_i32_e64 s[38:39], 31, v121
	v_cmp_gt_i32_e64 s[0:1], 15, v121
	s_cbranch_vccnz .LBB0_550
	s_add_u32 s2, s74, s42
	s_addc_u32 s3, s75, 0
	v_lshlrev_b32_e32 v0, 4, v18
	v_readlane_b32 s5, v249, 16
	v_lshl_add_u64 v[10:11], s[2:3], 0, v[0:1]
	v_readlane_b32 s6, v249, 18
	v_cmp_lt_i32_e32 vcc, s5, v121
	v_readlane_b32 s2, v249, 17
	v_add_u32_e32 v0, s6, v121
	s_and_b64 vcc, s[40:41], vcc
	v_mov_b32_e32 v12, s2
	v_cndmask_b32_e32 v0, v12, v0, vcc
	v_cmp_lt_i32_e32 vcc, s5, v19
	v_mad_i64_i32 v[2:3], s[2:3], v0, s25, v[10:11]
	v_add_u32_e32 v0, s6, v19
	s_and_b64 vcc, s[38:39], vcc
	v_cndmask_b32_e32 v0, v12, v0, vcc
	v_cmp_lt_i32_e32 vcc, s5, v20
	v_mad_i64_i32 v[6:7], s[2:3], v0, s25, v[10:11]
	v_add_u32_e32 v0, s6, v20
	s_and_b64 vcc, s[0:1], vcc
	v_cndmask_b32_e32 v0, v12, v0, vcc
	v_mad_i64_i32 v[10:11], s[0:1], v0, s25, v[10:11]
	global_load_dwordx4 v[2:5], v[2:3], off
	s_nop 0
	global_load_dwordx4 v[6:9], v[6:7], off
	v_mov_b32_e32 v17, v1
	global_load_dwordx4 v[10:13], v[10:11], off
	v_mov_b32_e32 v131, v19
	v_mov_b32_e32 v132, v20
	v_mov_b64_e32 v[14:15], v[16:17]
	v_mov_b32_e32 v133, v16

; #define LAS __attribute__((address_space(3)))
; #define BF8_TO_F32(vw, lo, hi) const f32x4 lo = {bflo(vw.x), bfhi(vw.x), bflo(vw.y), bfhi(vw.y)}, hi = {bflo(vw.z), bfhi(vw.z), bflo(vw.w), bfhi(vw.w)}
; __device__ __forceinline__ void mix_phase(LAS unsigned char* lds, const Params& p, const int layer) {
;     ...
;             __syncthreads();
;             if (g != g_cur) { g_cur = g;
;                 const bf16* WT = (const bf16*)(ws + WS_POOLW) + (size_t)(layer * 4 + g) * 65536 + (size_t)(wid * 32 + fr) * 256 + fq * 8;
; #pragma unroll
;                 for (int n = 0; n < 2; ++n)
; #pragma unroll
;                     for (int ks = 0; ks < 8; ++ks) b[n][ks] = *(const bf16x8*)(WT + (size_t)n * 16 * 256 + ks * 32);
; #pragma unroll
;                 for (int n = 0; n < 2; ++n) ps[n] = *(const f32x4*)(p.in[8] + layer * PW + g * 256 + wid * 32 + n * 16 + fq * 4); }
;             if (prt) {
;                 const int t0 = r0 & 2047;
; #pragma unroll
;                 for (int k = 0; k < 3; ++k) { const int i = i0 + 16 * k; const float f = ((i < 47) && (t0 - 15 + i >= 0)) ? 1.0f : 0.0f; BF8_TO_F32(vw[k], a0, a1);
;                     if (i < 47) { *(LAS f32x4*)(SL + i * 264 + q * 8) = a0 * f; *(LAS f32x4*)(SL + i * 264 + q * 8 + 4) = a1 * f; } }
;             } else {
;                 const float* spool = p.in[2] + (size_t)layer * 128 * 15 * PW; const int bs0 = (r0 - NP) >> 3;
; #pragma unroll 2
;                 for (int i = tid >> 5; i < 92; i += 16) { const int sq = i / 23, ii = i - sq * 23; f32x4 a0, a1;
;                     if (ii < 15) { const float* sp = spool + ((size_t)(bs0 + sq) * 15 + ii) * PW + col; a0 = *(const f32x4*)sp; a1 = *(const f32x4*)(sp + 4); }
.LBB0_551:
	s_and_b32 s12, s3, 3
	s_lshl_b32 s6, s12, 8
	s_cmp_eq_u32 s12, s5
	s_waitcnt lgkmcnt(0)
	s_barrier
	s_cbranch_scc1 .LBB0_553
	s_lshl_b32 s5, s34, 1
	s_lshl_b32 s7, s12, 17
	s_or_b32 s14, s7, s5
	s_mov_b32 s15, s80
	s_waitcnt vmcnt(10)
	v_lshl_add_u64 v[46:47], v[110:111], 0, s[14:15]
	global_load_dwordx4 v[42:45], v[46:47], off
	global_load_dwordx4 v[38:41], v[46:47], off offset:64
	global_load_dwordx4 v[34:37], v[46:47], off offset:128
	global_load_dwordx4 v[30:33], v[46:47], off offset:192
	global_load_dwordx4 v[26:29], v[46:47], off offset:256
	global_load_dwordx4 v[22:25], v[46:47], off offset:320
	global_load_dwordx4 v[18:21], v[46:47], off offset:384
	global_load_dwordx4 v[14:17], v[46:47], off offset:448
	v_add_co_u32_e32 v46, vcc, 0x2000, v46
	s_lshl_b32 s14, s6, 2
	s_nop 0
	v_addc_co_u32_e32 v47, vcc, 0, v47, vcc
	global_load_dwordx4 v[74:77], v[46:47], off
	global_load_dwordx4 v[70:73], v[46:47], off offset:64
	global_load_dwordx4 v[66:69], v[46:47], off offset:128
	s_waitcnt vmcnt(17)
	global_load_dwordx4 v[62:65], v[46:47], off offset:192
	global_load_dwordx4 v[58:61], v[46:47], off offset:256
	global_load_dwordx4 v[54:57], v[46:47], off offset:320
	global_load_dwordx4 v[50:53], v[46:47], off offset:384
	s_nop 0
	global_load_dwordx4 v[46:49], v[46:47], off offset:448
	v_lshl_add_u64 v[78:79], v[116:117], 0, s[14:15]
	global_load_dwordx4 v[82:85], v[78:79], off
	s_nop 0
	global_load_dwordx4 v[78:81], v[78:79], off offset:64
	s_mov_b32 s5, s12
	s_waitcnt vmcnt(0)
.LBB0_553:
	s_lshl_b32 s13, s3, 3
	s_and_b32 s7, s13, 0xffffffe0
	s_cmpk_lt_i32 s7, 0x2000
	s_cselect_b64 s[52:53], -1, 0
	s_cmpk_gt_i32 s7, 0x1fff
	s_mov_b64 s[20:21], -1
	s_cbranch_scc0 .LBB0_573
	s_and_saveexec_b64 s[48:49], s[38:39]
	s_cbranch_execz .LBB0_572
	s_add_i32 s14, s7, 0xffffe000
	v_or_b32_e32 v0, s6, v133
	s_lshr_b32 s14, s14, 3
	v_lshl_add_u64 v[94:95], v[0:1], 1, s[74:75]
	v_lshl_add_u64 v[96:97], v[0:1], 2, s[0:1]
	v_mov_b32_e32 v0, v121
	s_and_saveexec_b64 s[90:91], s[46:47]
	s_cbranch_execz .LBB0_561
	v_add_u32_e32 v0, s14, v141
	s_and_saveexec_b64 s[16:17], s[30:31]
	s_xor_b64 s[20:21], exec, s[16:17]
	s_cbranch_execz .LBB0_558
	v_lshl_add_u32 v0, v0, 3, v142
	v_mad_i64_i32 v[86:87], s[16:17], v0, s25, v[94:95]
	global_load_dwordx4 v[90:93], v[86:87], off
	s_waitcnt lgkmcnt(0)
	s_waitcnt vmcnt(0)
	v_lshlrev_b32_e32 v86, 16, v90
	v_and_b32_e32 v87, 0xffff0000, v90
	v_lshlrev_b32_e32 v88, 16, v91
	v_and_b32_e32 v89, 0xffff0000, v91
	v_lshlrev_b32_e32 v90, 16, v92
	v_and_b32_e32 v91, 0xffff0000, v92
	v_lshlrev_b32_e32 v92, 16, v93
	v_and_b32_e32 v93, 0xffff0000, v93

; #define BF8_TO_F32(vw, lo, hi) const f32x4 lo = {bflo(vw.x), bfhi(vw.x), bflo(vw.y), bfhi(vw.y)}, hi = {bflo(vw.z), bfhi(vw.z), bflo(vw.w), bfhi(vw.w)}
; __device__ __forceinline__ void mix_phase(LAS unsigned char* lds, const Params& p, const int layer) {
;     ...
;                 for (int i = tid >> 5; i < 92; i += 16) { const int sq = i / 23, ii = i - sq * 23; f32x4 a0, a1;
;                     if (ii < 15) { const float* sp = spool + ((size_t)(bs0 + sq) * 15 + ii) * PW + col; a0 = *(const f32x4*)sp; a1 = *(const f32x4*)(sp + 4); }
;                     else { const v4u vv = *(const v4u*)(PROJ + (size_t)(NP + (bs0 + sq) * 8 + (ii - 15)) * NC + C_UA + col); BF8_TO_F32(vv, c0_, c1_); a0 = c0_; a1 = c1_; }
.LBB0_564:
	s_mov_b32 s16, 0xb21642c9
	v_mul_hi_i32 v86, v0, s16
	v_add_u32_e32 v86, v86, v0
	v_lshrrev_b32_e32 v87, 31, v86
	v_ashrrev_i32_e32 v86, 4, v86
	v_add_u32_e32 v99, v86, v87
	s_movk_i32 s16, 0xffe9
	v_mad_u64_u32 v[100:101], s[16:17], v99, s16, v[0:1]
	v_cmp_lt_i32_e32 vcc, 14, v100
	s_and_saveexec_b64 s[16:17], vcc
	s_xor_b64 s[92:93], exec, s[16:17]
	s_cbranch_execz .LBB0_566
	v_mul_lo_u32 v86, v99, -15
	v_add_u32_e32 v87, s15, v0
	v_add3_u32 v86, v87, v86, -15
	v_mad_i64_i32 v[86:87], s[16:17], v86, s25, v[94:95]
	global_load_dwordx4 v[90:93], v[86:87], off
	s_waitcnt lgkmcnt(0)
	s_waitcnt vmcnt(0)
	v_lshlrev_b32_e32 v86, 16, v90
	v_and_b32_e32 v87, 0xffff0000, v90
	v_lshlrev_b32_e32 v88, 16, v91
	v_and_b32_e32 v89, 0xffff0000, v91
	v_lshlrev_b32_e32 v90, 16, v92
	v_and_b32_e32 v91, 0xffff0000, v92
	v_lshlrev_b32_e32 v92, 16, v93
	v_and_b32_e32 v93, 0xffff0000, v93

; #define LAS __attribute__((address_space(3)))
; #define BF8_TO_F32(vw, lo, hi) const f32x4 lo = {bflo(vw.x), bfhi(vw.x), bflo(vw.y), bfhi(vw.y)}, hi = {bflo(vw.z), bfhi(vw.z), bflo(vw.w), bfhi(vw.w)}
; __device__ __forceinline__ void mix_phase(LAS unsigned char* lds, const Params& p, const int layer) {
;     ...
;                 for (int i = tid >> 5; i < 92; i += 16) { const int sq = i / 23, ii = i - sq * 23; f32x4 a0, a1;
;                     if (ii < 15) { const float* sp = spool + ((size_t)(bs0 + sq) * 15 + ii) * PW + col; a0 = *(const f32x4*)sp; a1 = *(const f32x4*)(sp + 4); }
;                     else { const v4u vv = *(const v4u*)(PROJ + (size_t)(NP + (bs0 + sq) * 8 + (ii - 15)) * NC + C_UA + col); BF8_TO_F32(vv, c0_, c1_); a0 = c0_; a1 = c1_; }
;                     *(LAS f32x4*)(SL + i * 264 + q * 8) = a0; *(LAS f32x4*)(SL + i * 264 + q * 8 + 4) = a1; }
.LBB0_568:
	s_or_b64 exec, exec, s[92:93]
	s_waitcnt vmcnt(0)
	ds_write_b128 v98, v[86:89]
	ds_write_b128 v98, v[90:93] offset:16
	v_add_u32_e32 v86, 16, v0
	s_mov_b32 s16, 0xb21642c9
	v_mul_hi_i32 v87, v86, s16
	v_add_u32_e32 v87, v87, v86
	v_lshrrev_b32_e32 v88, 31, v87
	v_ashrrev_i32_e32 v87, 4, v87
	v_add_u32_e32 v99, v87, v88
	s_movk_i32 s16, 0xffe9
	v_mad_u64_u32 v[100:101], s[16:17], v99, s16, v[86:87]
	v_cmp_lt_i32_e32 vcc, 14, v100
	s_and_saveexec_b64 s[16:17], vcc
	s_xor_b64 s[92:93], exec, s[16:17]
	s_cbranch_execz .LBB0_570
	v_mul_lo_u32 v86, v99, -15
	v_add_u32_e32 v87, s15, v0
	v_add3_u32 v86, v87, v86, 1
	v_mad_i64_i32 v[86:87], s[16:17], v86, s25, v[94:95]
	global_load_dwordx4 v[90:93], v[86:87], off
	s_waitcnt lgkmcnt(0)
	s_waitcnt vmcnt(0)
	v_lshlrev_b32_e32 v86, 16, v90
	v_and_b32_e32 v87, 0xffff0000, v90
	v_lshlrev_b32_e32 v88, 16, v91
	v_and_b32_e32 v89, 0xffff0000, v91
	v_lshlrev_b32_e32 v90, 16, v92
	v_and_b32_e32 v91, 0xffff0000, v92
	v_lshlrev_b32_e32 v92, 16, v93
	v_and_b32_e32 v93, 0xffff0000, v93

; #define LAS __attribute__((address_space(3)))
; #define BF8_TO_F32(vw, lo, hi) const f32x4 lo = {bflo(vw.x), bfhi(vw.x), bflo(vw.y), bfhi(vw.y)}, hi = {bflo(vw.z), bfhi(vw.z), bflo(vw.w), bfhi(vw.w)}
; __device__ __forceinline__ void mix_phase(LAS unsigned char* lds, const Params& p, const int layer) {
;     ...
;             if (prt) {
;                 const int t0 = r0 & 2047;
; #pragma unroll
;                 for (int k = 0; k < 3; ++k) { const int i = i0 + 16 * k; const float f = ((i < 47) && (t0 - 15 + i >= 0)) ? 1.0f : 0.0f; BF8_TO_F32(vw[k], a0, a1);
;                     if (i < 47) { *(LAS f32x4*)(SL + i * 264 + q * 8) = a0 * f; *(LAS f32x4*)(SL + i * 264 + q * 8 + 4) = a1 * f; } }
.LBB0_573:
	s_andn2_b64 vcc, exec, s[20:21]
	s_cbranch_vccnz .LBB0_579
	s_and_b32 s13, s13, 0x7e0
	s_sub_i32 s13, 14, s13
	s_and_saveexec_b64 s[48:49], s[40:41]
	s_cbranch_execz .LBB0_582
	v_cmp_lt_i32_e32 vcc, s13, v121
	s_waitcnt vmcnt(2)
	v_and_b32_e32 v87, 0xffff0000, v3
	v_lshlrev_b32_e32 v86, 16, v3
	v_and_b32_e32 v95, 0xffff0000, v2
	v_lshlrev_b32_e32 v94, 16, v2
	v_cndmask_b32_e64 v0, 0, 1.0, vcc
	v_and_b32_e32 v91, 0xffff0000, v5
	v_lshlrev_b32_e32 v90, 16, v5
	v_and_b32_e32 v93, 0xffff0000, v4
	v_lshlrev_b32_e32 v92, 16, v4
	v_pk_mul_f32 v[88:89], v[0:1], v[86:87] op_sel_hi:[0,1]
	v_pk_mul_f32 v[86:87], v[0:1], v[94:95] op_sel_hi:[0,1]
	v_add_u32_e32 v94, v136, v138
	ds_write_b128 v94, v[86:89]
	v_pk_mul_f32 v[88:89], v[0:1], v[90:91] op_sel_hi:[0,1]
	v_pk_mul_f32 v[86:87], v[0:1], v[92:93] op_sel_hi:[0,1]
	ds_write_b128 v94, v[86:89] offset:16
	s_or_b64 exec, exec, s[48:49]
	s_and_saveexec_b64 s[48:49], s[42:43]
	s_cbranch_execnz .LBB0_583

; __device__ __forceinline__ void mix_phase(LAS unsigned char* lds, const Params& p, const int layer) {
;     ...
;             __syncthreads();
;             v2u sgc[2][2];
; #pragma unroll
;             for (int m = 0; m < 2; ++m)
; #pragma unroll
;                 for (int n = 0; n < 2; ++n) sgc[m][n] = sgv[m][n];
;             if (ua + G < NUA) MIX_PREFETCH_A(ua + G);
.LBB0_579:
	v_readlane_b32 s14, v251, 17
	s_add_i32 s3, s3, s14
	s_cmpk_gt_i32 s3, 0x47f
	s_cselect_b64 s[90:91], -1, 0
	s_and_b64 vcc, exec, s[90:91]
	s_waitcnt lgkmcnt(0)
	s_barrier
	v_readlane_b32 s15, v251, 18
	s_cbranch_vccnz .LBB0_584
	s_lshl_b32 s14, s3, 3
	s_and_b32 s13, s14, 0xffffffe0
	s_lshl_b32 s15, s3, 8
	v_or_b32_e32 v90, s13, v135
	s_and_b32 s15, s15, 0x300
	v_mov_b64_e32 v[86:87], s[74:75]
	v_mad_i64_i32 v[88:89], s[16:17], v90, s25, v[86:87]
	s_lshl_b32 s20, s15, 1
	s_mov_b32 s21, s80
	v_or_b32_e32 v90, 16, v90
	v_lshl_add_u64 v[88:89], v[88:89], 0, s[20:21]
	v_mad_i64_i32 v[86:87], s[16:17], v90, s25, v[86:87]
	v_lshl_add_u64 v[88:89], v[88:89], 0, s[82:83]
	v_lshlrev_b32_e32 v0, 1, v134
	v_lshl_add_u64 v[86:87], v[86:87], 0, s[20:21]
	v_lshl_add_u64 v[88:89], v[88:89], 0, v[0:1]
	v_lshl_add_u64 v[86:87], v[86:87], 0, s[82:83]
	v_lshl_add_u64 v[86:87], v[86:87], 0, v[0:1]
	global_load_dwordx2 v[122:123], v[88:89], off offset:2048
	global_load_dwordx2 v[124:125], v[86:87], off offset:2048
	global_load_dwordx2 v[126:127], v[86:87], off offset:2080
	global_load_dwordx2 v[128:129], v[88:89], off offset:2080
	s_cmpk_gt_i32 s13, 0x1fff
	s_cbranch_scc1 .LBB0_585
	s_and_b32 s14, s14, 0x7e0
	s_sub_i32 s16, 14, s14
	s_add_i32 s17, s13, -15
	v_cmp_lt_i32_e32 vcc, s16, v121
	v_add_u32_e32 v0, s17, v121
	s_waitcnt vmcnt(4)
	v_mov_b32_e32 v12, s13
	s_and_b64 vcc, s[40:41], vcc
	v_lshl_add_u64 v[10:11], v[112:113], 0, s[20:21]
	v_cndmask_b32_e32 v0, v12, v0, vcc
	v_cmp_lt_i32_e32 vcc, s16, v131
	v_mad_i64_i32 v[2:3], s[14:15], v0, s25, v[10:11]
	v_add_u32_e32 v0, s17, v131
	s_and_b64 vcc, s[42:43], vcc
	v_cndmask_b32_e32 v0, v12, v0, vcc
	v_cmp_lt_i32_e32 vcc, s16, v132
	v_mad_i64_i32 v[6:7], s[14:15], v0, s25, v[10:11]
	v_add_u32_e32 v0, s17, v132
	s_and_b64 vcc, s[44:45], vcc
	v_cndmask_b32_e32 v0, v12, v0, vcc
	v_mad_i64_i32 v[10:11], s[14:15], v0, s25, v[10:11]
	global_load_dwordx4 v[2:5], v[2:3], off
	s_nop 0
	global_load_dwordx4 v[6:9], v[6:7], off
	s_nop 0
	global_load_dwordx4 v[10:13], v[10:11], off
	s_branch .LBB0_585

; #define LAS __attribute__((address_space(3)))
; #define BF8_TO_F32(vw, lo, hi) const f32x4 lo = {bflo(vw.x), bfhi(vw.x), bflo(vw.y), bfhi(vw.y)}, hi = {bflo(vw.z), bfhi(vw.z), bflo(vw.w), bfhi(vw.w)}
; __device__ __forceinline__ void mix_phase(LAS unsigned char* lds, const Params& p, const int layer) {
;     ...
;                 for (int k = 0; k < 3; ++k) { const int i = i0 + 16 * k; const float f = ((i < 47) && (t0 - 15 + i >= 0)) ? 1.0f : 0.0f; BF8_TO_F32(vw[k], a0, a1);
;                     if (i < 47) { *(LAS f32x4*)(SL + i * 264 + q * 8) = a0 * f; *(LAS f32x4*)(SL + i * 264 + q * 8 + 4) = a1 * f; } }
;     ...
;             v2u sgc[2][2];
; #pragma unroll
;             for (int m = 0; m < 2; ++m)
; #pragma unroll
;                 for (int n = 0; n < 2; ++n) sgc[m][n] = sgv[m][n];
.LBB0_583:
	v_cmp_lt_i32_e32 vcc, s13, v131
	s_waitcnt vmcnt(1)
	v_and_b32_e32 v87, 0xffff0000, v7
	v_lshlrev_b32_e32 v86, 16, v7
	v_and_b32_e32 v95, 0xffff0000, v6
	v_lshlrev_b32_e32 v94, 16, v6
	v_cndmask_b32_e64 v0, 0, 1.0, vcc
	v_and_b32_e32 v91, 0xffff0000, v9
	v_lshlrev_b32_e32 v90, 16, v9
	v_and_b32_e32 v93, 0xffff0000, v8
	v_lshlrev_b32_e32 v92, 16, v8
	v_pk_mul_f32 v[88:89], v[0:1], v[86:87] op_sel_hi:[0,1]
	v_pk_mul_f32 v[86:87], v[0:1], v[94:95] op_sel_hi:[0,1]
	ds_write_b128 v144, v[86:89]
	v_pk_mul_f32 v[88:89], v[0:1], v[90:91] op_sel_hi:[0,1]
	v_pk_mul_f32 v[86:87], v[0:1], v[92:93] op_sel_hi:[0,1]
	ds_write_b128 v144, v[86:89] offset:16
	s_or_b64 exec, exec, s[48:49]
	s_and_saveexec_b64 s[48:49], s[44:45]
	s_cbranch_execnz .LBB0_577
	s_branch .LBB0_578
.LBB0_584:
	s_waitcnt vmcnt(1)
	v_mov_b64_e32 v[126:127], v[102:103]
	v_mov_b64_e32 v[124:125], v[104:105]
	s_waitcnt vmcnt(0)
	v_mov_b64_e32 v[128:129], v[106:107]
	v_mov_b64_e32 v[122:123], v[108:109]

; #define LAS __attribute__((address_space(3)))
; __device__ __forceinline__ unsigned pk2(float lo, float hi) { return f2bf(lo) | (f2bf(hi) << 16); }
; __device__ __forceinline__ void mix_phase(LAS unsigned char* lds, const Params& p, const int layer) {
;     ...
;             for (int i = 0; i < 2; ++i) {
;                 const int rl = (tid >> 5) + 16 * i, bi = prt ? rl + 15 : (rl >> 3) * 23 + 15 + (rl & 7), t = (r0 + rl) & 2047;
;                 const LAS float* sp = SL + bi * 264 + q * 8;
;                 const f32x4 u0 = *(const LAS f32x4*)sp, u1 = *(const LAS f32x4*)(sp + 4);
;                 f32x4 s0 = u0, s1 = u1;
; #pragma unroll 4
;                 for (int j = 1; j < w; ++j) { s0 += *(const LAS f32x4*)(sp - j * 264); s1 += *(const LAS f32x4*)(sp - j * 264 + 4); }
;                 const int cnt = (prt && t + 1 < w) ? t + 1 : w; const float inv = 1.0f / (float)cnt;
;                 const f32x4 d0 = s0 * inv - u0, d1 = s1 * inv - u1;
;                 v4u o; o.x = pk2(d0[0], d0[1]); o.y = pk2(d0[2], d0[3]); o.z = pk2(d1[0], d1[1]); o.w = pk2(d1[2], d1[3]);
;                 *(LAS v4u*)(At + rl * 264 + q * 8) = o;
;             }
;             __syncthreads();
.LBB0_596:
	ds_read_b128 v[150:153], v0
	ds_read_b128 v[154:157], v0 offset:16
	s_add_i32 s12, s12, -1
	v_add_u32_e32 v0, 0xfffffbe0, v0
	s_cmp_lg_u32 s12, 0
	s_waitcnt lgkmcnt(0)
	v_pk_add_f32 v[100:101], v[100:101], v[152:153]
	v_pk_add_f32 v[98:99], v[98:99], v[150:151]
	v_pk_add_f32 v[96:97], v[96:97], v[156:157]
	v_pk_add_f32 v[94:95], v[94:95], v[154:155]
	s_cbranch_scc1 .LBB0_596
	v_add_u32_e32 v0, s7, v131
	v_and_b32_e32 v0, 0x7ff, v0
	v_add_u32_e32 v0, 1, v0
	v_min_u32_e32 v0, s13, v0
	v_mov_b32_e32 v149, s13
	v_cndmask_b32_e64 v0, v149, v0, s[52:53]
	v_cvt_f32_ubyte0_e32 v0, v0
	v_div_scale_f32 v149, s[12:13], v0, v0, 1.0
	v_rcp_f32_e32 v150, v149
	v_xor_b32_e32 v93, 0x80000000, v93
	v_xor_b32_e32 v92, 0x80000000, v92
	v_xor_b32_e32 v89, 0x80000000, v89
	v_fma_f32 v151, -v149, v150, 1.0
	v_fmac_f32_e32 v150, v151, v150
	v_div_scale_f32 v151, vcc, 1.0, v0, 1.0
	v_mul_f32_e32 v152, v151, v150
	v_fma_f32 v153, -v149, v152, v151
	v_fmac_f32_e32 v152, v153, v150
	v_fma_f32 v149, -v149, v152, v151
	v_div_fmas_f32 v149, v149, v150, v152
	v_div_fixup_f32 v0, v149, v0, 1.0
	v_pk_fma_f32 v[90:91], v[0:1], v[98:99], v[90:91] op_sel_hi:[0,1,1] neg_lo:[0,0,1] neg_hi:[0,0,1]
	v_xor_b32_e32 v88, 0x80000000, v88
	v_pk_fma_f32 v[92:93], v[0:1], v[100:101], v[92:93] op_sel_hi:[0,1,1]
	v_pk_fma_f32 v[96:97], v[0:1], v[96:97], v[88:89] op_sel_hi:[0,1,1]
	v_pk_fma_f32 v[88:89], v[0:1], v[94:95], v[86:87] op_sel_hi:[0,1,1] neg_lo:[0,0,1] neg_hi:[0,0,1]
	v_bfe_u32 v0, v90, 16, 1
	v_add3_u32 v0, v90, v0, s26
	v_bfe_u32 v86, v91, 16, 1
	v_lshrrev_b32_e32 v0, 16, v0
	v_add3_u32 v86, v91, v86, s26
	v_and_or_b32 v86, v86, s24, v0
	v_bfe_u32 v0, v92, 16, 1
	v_add3_u32 v0, v92, v0, s26
	v_bfe_u32 v87, v93, 16, 1
	v_lshrrev_b32_e32 v0, 16, v0
	v_add3_u32 v87, v93, v87, s26
	v_and_or_b32 v87, v87, s24, v0
	v_bfe_u32 v0, v88, 16, 1
	v_add3_u32 v0, v88, v0, s26
	v_bfe_u32 v88, v89, 16, 1
	v_lshrrev_b32_e32 v0, 16, v0
	v_add3_u32 v88, v89, v88, s26
	v_and_or_b32 v88, v88, s24, v0
	v_bfe_u32 v0, v96, 16, 1
	v_add3_u32 v0, v96, v0, s26
	v_bfe_u32 v89, v97, 16, 1
	v_lshrrev_b32_e32 v0, 16, v0
	v_add3_u32 v89, v97, v89, s26
	v_and_or_b32 v89, v89, s24, v0
	ds_write_b128 v147, v[86:89]
	s_waitcnt lgkmcnt(0)
	s_barrier
; #define LAS __attribute__((address_space(3)))
; __device__ __forceinline__ unsigned pk2(float lo, float hi) { return f2bf(lo) | (f2bf(hi) << 16); }
; __device__ __forceinline__ float bflo(unsigned w) { return __uint_as_float(w << 16); }
; __device__ __forceinline__ float bfhi(unsigned w) { return __uint_as_float(w & 0xffff0000u); }
; __device__ __forceinline__ void mix_phase(LAS unsigned char* lds, const Params& p, const int layer) {
;     ...
;             f32x4 acc[2][2];
; #pragma unroll
;             for (int m = 0; m < 2; ++m)
; #pragma unroll
;                 for (int n = 0; n < 2; ++n) acc[m][n] = (f32x4){0.f, 0.f, 0.f, 0.f};
; #pragma unroll
;             for (int ks = 0; ks < 8; ++ks) {
;                 bf16x8 a[2];
; #pragma unroll
;                 for (int m = 0; m < 2; ++m) a[m] = *(const LAS bf16x8*)(At + (m * 16 + fr) * 264 + ks * 32 + fq * 8);
; #pragma unroll
;                 for (int m = 0; m < 2; ++m)
; #pragma unroll
;                     for (int n = 0; n < 2; ++n) acc[m][n] = __builtin_amdgcn_mfma_f32_16x16x32_bf16(b[n][ks], a[m], acc[m][n], 0, 0, 0);
;             }
;             bf16* YA = (bf16*)(ws + WS_YA);
; #pragma unroll
;             for (int m = 0; m < 2; ++m)
; #pragma unroll
;                 for (int n = 0; n < 2; ++n) { const int r = r0 + m * 16 + fr, ch = g * 256 + wid * 32 + n * 16 + fq * 4; const v2u sg = sgc[m][n];
;                     const f32x4 y = acc[m][n] * ps[n] * (f32x4){bflo(sg.x), bfhi(sg.x), bflo(sg.y), bfhi(sg.y)};
;                     v2u o; o.x = pk2(y[0], y[1]); o.y = pk2(y[2], y[3]); *(v2u*)(YA + (size_t)r * KCAT + ch) = o; }
	ds_read_b128 v[86:89], v148
	ds_read_b128 v[90:93], v148 offset:8448
	ds_read_b128 v[150:153], v148 offset:64
	ds_read_b128 v[154:157], v148 offset:8512
	s_waitcnt lgkmcnt(0)
	s_waitcnt vmcnt(15)
	v_mfma_f32_16x16x32_bf16 v[94:97], v[42:45], v[86:89], 0
	v_or_b32_e32 v0, s7, v135
	s_movk_i32 s12, 0x1800
	s_and_b64 vcc, exec, s[90:91]
	v_mfma_f32_16x16x32_bf16 v[86:89], v[74:77], v[86:89], 0
	v_mfma_f32_16x16x32_bf16 v[98:101], v[42:45], v[90:93], 0
	v_mfma_f32_16x16x32_bf16 v[90:93], v[74:77], v[90:93], 0
	v_mfma_f32_16x16x32_bf16 v[94:97], v[38:41], v[150:153], v[94:97]
	v_mfma_f32_16x16x32_bf16 v[86:89], v[70:73], v[150:153], v[86:89]
	v_mfma_f32_16x16x32_bf16 v[98:101], v[38:41], v[154:157], v[98:101]
	v_mfma_f32_16x16x32_bf16 v[90:93], v[70:73], v[154:157], v[90:93]
	ds_read_b128 v[150:153], v148 offset:128
	ds_read_b128 v[154:157], v148 offset:8576
	s_waitcnt lgkmcnt(1)
	v_mfma_f32_16x16x32_bf16 v[94:97], v[34:37], v[150:153], v[94:97]
	v_mfma_f32_16x16x32_bf16 v[86:89], v[66:69], v[150:153], v[86:89]
	s_waitcnt lgkmcnt(0)
	v_mfma_f32_16x16x32_bf16 v[98:101], v[34:37], v[154:157], v[98:101]
	v_mfma_f32_16x16x32_bf16 v[90:93], v[66:69], v[154:157], v[90:93]
	ds_read_b128 v[150:153], v148 offset:192
	ds_read_b128 v[154:157], v148 offset:8640
	s_waitcnt lgkmcnt(1)
	v_mfma_f32_16x16x32_bf16 v[94:97], v[30:33], v[150:153], v[94:97]
	s_waitcnt vmcnt(10)
	v_mfma_f32_16x16x32_bf16 v[86:89], v[62:65], v[150:153], v[86:89]
	s_waitcnt lgkmcnt(0)
	v_mfma_f32_16x16x32_bf16 v[98:101], v[30:33], v[154:157], v[98:101]
	v_mfma_f32_16x16x32_bf16 v[90:93], v[62:65], v[154:157], v[90:93]
	ds_read_b128 v[150:153], v148 offset:256
	ds_read_b128 v[154:157], v148 offset:8704
	s_waitcnt lgkmcnt(1)
	v_mfma_f32_16x16x32_bf16 v[94:97], v[26:29], v[150:153], v[94:97]
	v_mfma_f32_16x16x32_bf16 v[86:89], v[58:61], v[150:153], v[86:89]
	s_waitcnt lgkmcnt(0)
	v_mfma_f32_16x16x32_bf16 v[98:101], v[26:29], v[154:157], v[98:101]
	v_mfma_f32_16x16x32_bf16 v[90:93], v[58:61], v[154:157], v[90:93]
	ds_read_b128 v[150:153], v148 offset:320
	ds_read_b128 v[154:157], v148 offset:8768
	s_waitcnt lgkmcnt(1)
	v_mfma_f32_16x16x32_bf16 v[94:97], v[22:25], v[150:153], v[94:97]
	v_mfma_f32_16x16x32_bf16 v[86:89], v[54:57], v[150:153], v[86:89]
	s_waitcnt lgkmcnt(0)
	v_mfma_f32_16x16x32_bf16 v[98:101], v[22:25], v[154:157], v[98:101]
	v_mfma_f32_16x16x32_bf16 v[90:93], v[54:57], v[154:157], v[90:93]
	ds_read_b128 v[150:153], v148 offset:384
	ds_read_b128 v[154:157], v148 offset:8832
	s_waitcnt lgkmcnt(1)
	v_mfma_f32_16x16x32_bf16 v[94:97], v[18:21], v[150:153], v[94:97]
	v_mfma_f32_16x16x32_bf16 v[86:89], v[50:53], v[150:153], v[86:89]
	s_waitcnt lgkmcnt(0)
	v_mfma_f32_16x16x32_bf16 v[98:101], v[18:21], v[154:157], v[98:101]
	v_mfma_f32_16x16x32_bf16 v[90:93], v[50:53], v[154:157], v[90:93]
	ds_read_b128 v[150:153], v148 offset:448
	ds_read_b128 v[154:157], v148 offset:8896
	s_waitcnt lgkmcnt(1)
	v_mfma_f32_16x16x32_bf16 v[94:97], v[14:17], v[150:153], v[94:97]
	s_waitcnt lgkmcnt(0)
	v_mfma_f32_16x16x32_bf16 v[98:101], v[14:17], v[154:157], v[98:101]
	s_nop 5
	v_mul_f32_e64 v94, v82, v94
	v_mul_f32_e64 v95, v83, v95
	v_pk_mul_f32 v[96:97], v[84:85], v[96:97]
	v_mfma_f32_16x16x32_bf16 v[90:93], v[46:49], v[154:157], v[90:93]
	s_waitcnt vmcnt(7)
	v_lshlrev_b32_e32 v156, 16, v108
	v_and_b32_e32 v157, 0xffff0000, v108
	v_lshlrev_b32_e32 v108, 16, v109
	v_and_b32_e32 v109, 0xffff0000, v109
	v_pk_mul_f32 v[94:95], v[94:95], v[156:157]
	v_pk_mul_f32 v[96:97], v[96:97], v[108:109]
	v_bfe_u32 v108, v94, 16, 1
	v_add3_u32 v94, v94, v108, s26
	v_bfe_u32 v108, v95, 16, 1
	v_lshrrev_b32_e32 v94, 16, v94
	v_add3_u32 v95, v95, v108, s26
	v_and_or_b32 v94, v95, s24, v94
	v_bfe_u32 v95, v96, 16, 1
	v_mfma_f32_16x16x32_bf16 v[86:89], v[46:49], v[150:153], v[86:89]
	v_add_u32_e32 v150, s6, v137
	v_add3_u32 v95, v96, v95, s26
	v_bfe_u32 v96, v97, 16, 1
	v_mov_b64_e32 v[152:153], s[86:87]
	v_lshrrev_b32_e32 v95, 16, v95
	v_add3_u32 v96, v97, v96, s26
	v_ashrrev_i32_e32 v151, 31, v150
	v_mad_i64_i32 v[154:155], s[6:7], v0, s12, v[152:153]
	v_and_or_b32 v95, v96, s24, v95
	v_lshlrev_b64 v[96:97], 1, v[150:151]
	v_lshl_add_u64 v[108:109], v[154:155], 0, v[96:97]
	global_store_dwordx2 v[108:109], v[94:95], off
	v_pk_mul_f32 v[86:87], v[78:79], v[86:87]
	s_waitcnt vmcnt(5)
	v_lshlrev_b32_e32 v94, 16, v106
	v_and_b32_e32 v95, 0xffff0000, v106
	v_pk_mul_f32 v[86:87], v[86:87], v[94:95]
	v_pk_mul_f32 v[88:89], v[80:81], v[88:89]
	v_bfe_u32 v94, v86, 16, 1
	v_lshlrev_b32_e32 v106, 16, v107
	v_and_b32_e32 v107, 0xffff0000, v107
	v_add3_u32 v86, v86, v94, s26
	v_bfe_u32 v94, v87, 16, 1
	v_pk_mul_f32 v[88:89], v[88:89], v[106:107]
	v_lshrrev_b32_e32 v86, 16, v86
	v_add3_u32 v87, v87, v94, s26
	v_and_or_b32 v86, v87, s24, v86
	v_bfe_u32 v87, v88, 16, 1
	v_add3_u32 v87, v88, v87, s26
	v_bfe_u32 v88, v89, 16, 1
	v_lshrrev_b32_e32 v87, 16, v87
	v_add3_u32 v88, v89, v88, s26
	v_pk_mul_f32 v[94:95], v[82:83], v[98:99]
	v_lshlrev_b32_e32 v98, 16, v104
	v_and_b32_e32 v99, 0xffff0000, v104
	v_and_or_b32 v87, v88, s24, v87
	v_or_b32_e32 v0, 16, v0
	v_pk_mul_f32 v[94:95], v[94:95], v[98:99]
	global_store_dwordx2 v[108:109], v[86:87], off offset:32
	v_mad_i64_i32 v[86:87], s[6:7], v0, s12, v[152:153]
	v_bfe_u32 v0, v94, 16, 1
	v_pk_mul_f32 v[88:89], v[84:85], v[100:101]
	v_lshlrev_b32_e32 v100, 16, v105
	v_and_b32_e32 v101, 0xffff0000, v105
	v_add3_u32 v0, v94, v0, s26
	v_bfe_u32 v94, v95, 16, 1
	v_pk_mul_f32 v[88:89], v[88:89], v[100:101]
	v_lshrrev_b32_e32 v0, 16, v0
	v_add3_u32 v94, v95, v94, s26
	v_and_or_b32 v94, v94, s24, v0
	v_bfe_u32 v0, v88, 16, 1
	v_add3_u32 v0, v88, v0, s26
	v_bfe_u32 v88, v89, 16, 1
	v_lshrrev_b32_e32 v0, 16, v0
	v_add3_u32 v88, v89, v88, s26
	v_and_or_b32 v95, v88, s24, v0
	v_pk_mul_f32 v[88:89], v[80:81], v[92:93]
	v_pk_mul_f32 v[90:91], v[78:79], v[90:91]
	v_lshlrev_b32_e32 v92, 16, v102
	v_and_b32_e32 v93, 0xffff0000, v102
	v_pk_mul_f32 v[90:91], v[90:91], v[92:93]
	v_lshl_add_u64 v[86:87], v[86:87], 0, v[96:97]
	v_bfe_u32 v0, v90, 16, 1
	global_store_dwordx2 v[86:87], v[94:95], off
	v_lshlrev_b32_e32 v94, 16, v103
	v_and_b32_e32 v95, 0xffff0000, v103
	v_add3_u32 v0, v90, v0, s26
	v_bfe_u32 v90, v91, 16, 1
	v_pk_mul_f32 v[88:89], v[88:89], v[94:95]
	v_lshrrev_b32_e32 v0, 16, v0
	v_add3_u32 v90, v91, v90, s26
	v_and_or_b32 v90, v90, s24, v0
	v_bfe_u32 v0, v88, 16, 1
	v_add3_u32 v0, v88, v0, s26
	v_bfe_u32 v88, v89, 16, 1
	v_lshrrev_b32_e32 v0, 16, v0
	v_add3_u32 v88, v89, v88, s26
	v_readlane_b32 s6, v249, 62
	v_and_or_b32 v91, v88, s24, v0
	s_add_i32 s2, s2, s6
	s_waitcnt vmcnt(4)
	v_mov_b64_e32 v[102:103], v[126:127]
	v_mov_b64_e32 v[104:105], v[124:125]
	s_waitcnt vmcnt(3)
	v_mov_b64_e32 v[106:107], v[128:129]
	v_mov_b64_e32 v[108:109], v[122:123]
	global_store_dwordx2 v[86:87], v[90:91], off offset:32
	s_cbranch_vccz .LBB0_551

; __device__ __forceinline__ void mix_phase(LAS unsigned char* lds, const Params& p, const int layer) {
;     ...
;     for (int it0 = gt; it0 < N_ST; it0 += 3 * GT) {
;         const bf16* src[3]; const float* fsrc[3]; float* dst[3]; bool isf[3], ok[3];
; #pragma unroll
;         for (int k = 0; k < 3; ++k) {
;             const int it = it0 + k * GT; ok[k] = it < N_ST; int r = ok[k] ? it : 0; isf[k] = false; src[k] = PROJ; fsrc[k] = p.in[2];
;             if (r < N_PP) { const int c4 = r % (PW / 4), i = (r / (PW / 4)) % 15, b_ = r / (15 * (PW / 4));
;                 src[k] = PROJ + (size_t)(b_ * 2048 + 2033 + i) * NC + C_UA + c4 * 4; dst[k] = out + O_POOLP + ((size_t)(layer * 4 + b_) * 15 + i) * PW + c4 * 4; }
;             else if ((r -= N_PP) < N_CP) { const int c4 = r % (LW / 4), i = (r / (LW / 4)) % 3, b_ = r / (3 * (LW / 4));
;                 src[k] = PROJ + (size_t)(b_ * 2048 + 2045 + i) * NC + C_UB + c4 * 4; dst[k] = out + O_CONVP + ((size_t)(layer * 4 + b_) * 3 + i) * LW + c4 * 4; }
;             else if ((r -= N_CP) < N_PS) { const int c4 = r % (PW / 4), i = (r / (PW / 4)) % 15, bs = r / (15 * (PW / 4));
;                 dst[k] = out + O_POOLS + ((size_t)(layer * 128 + bs) * 15 + i) * PW + c4 * 4;
;                 if (i < 7) { isf[k] = true; fsrc[k] = p.in[2] + ((size_t)(layer * 128 + bs) * 15 + 8 + i) * PW + c4 * 4; } else src[k] = PROJ + (size_t)(NP + bs * 8 + (i - 7)) * NC + C_UA + c4 * 4; }
;             else { r -= N_PS; const int c4 = r % (LW / 4), i = (r / (LW / 4)) % 3, bs = r / (3 * (LW / 4));
;                 src[k] = PROJ + (size_t)(NP + bs * 8 + 5 + i) * NC + C_UB + c4 * 4; dst[k] = out + O_CONVS + ((size_t)(layer * 128 + bs) * 3 + i) * LW + c4 * 4; }
.LBB0_600:
	s_or_b64 exec, exec, s[0:1]
	s_add_i32 s0, s5, s5
	s_waitcnt vmcnt(3)
	v_add_u32_e32 v8, s0, v29
	s_mov_b32 s0, 0xad3ff
	v_cmp_lt_i32_e32 vcc, s0, v8
	v_readlane_b32 s0, v251, 17
	s_mulk_i32 s0, 0x1800
	s_or_b64 s[42:43], vcc, s[42:43]
	v_add_u32_e32 v28, s0, v28
	v_readlane_b32 s1, v251, 18
	s_andn2_b64 exec, exec, s[42:43]
	s_cbranch_execz .LBB0_657
.LBB0_601:
	v_readlane_b32 s56, v251, 21
	s_movk_i32 s0, 0x3bff
	v_readlane_b32 s60, v251, 25
	v_readlane_b32 s61, v251, 26
	v_mov_b32_e32 v14, s74
	v_mov_b32_e32 v15, s75
	v_cmp_lt_i32_e32 vcc, s0, v8
	v_mov_b64_e32 v[16:17], s[60:61]
	v_readlane_b32 s57, v251, 22
	v_readlane_b32 s58, v251, 23
	v_readlane_b32 s59, v251, 24
	v_readlane_b32 s62, v251, 27
	v_readlane_b32 s63, v251, 28
	v_readlane_b32 s64, v251, 29
	v_readlane_b32 s65, v251, 30
	v_readlane_b32 s66, v251, 31
	v_readlane_b32 s67, v251, 32
	v_readlane_b32 s68, v251, 33
	v_readlane_b32 s69, v251, 34
	v_readlane_b32 s70, v251, 35
	v_readlane_b32 s71, v251, 36
	s_and_saveexec_b64 s[0:1], vcc
	s_xor_b64 s[0:1], exec, s[0:1]
	s_cbranch_execz .LBB0_615
	v_readlane_b32 s56, v251, 21
	s_movk_i32 s2, 0x53ff
	v_readlane_b32 s60, v251, 25
	v_readlane_b32 s61, v251, 26
	v_cmp_lt_u32_e32 vcc, s2, v8
	v_readlane_b32 s57, v251, 22
	v_mov_b64_e32 v[16:17], s[60:61]
	v_readlane_b32 s58, v251, 23
	v_readlane_b32 s59, v251, 24
	v_readlane_b32 s62, v251, 27
	v_readlane_b32 s63, v251, 28
	v_readlane_b32 s64, v251, 29
	v_readlane_b32 s65, v251, 30
	v_readlane_b32 s66, v251, 31
	v_readlane_b32 s67, v251, 32
	v_readlane_b32 s68, v251, 33
	v_readlane_b32 s69, v251, 34
	v_readlane_b32 s70, v251, 35
	v_readlane_b32 s71, v251, 36
	s_and_saveexec_b64 s[2:3], vcc
	s_xor_b64 s[38:39], exec, s[2:3]
	s_cbranch_execz .LBB0_612
	s_mov_b32 s2, 0x7d3ff
	v_cmp_lt_u32_e32 vcc, s2, v8
	s_and_saveexec_b64 s[2:3], vcc
	s_xor_b64 s[44:45], exec, s[2:3]
	s_cbranch_execz .LBB0_605
	v_add_u32_e32 v0, 0xfff82c00, v8
	s_waitcnt vmcnt(1)
	v_lshrrev_b32_e32 v2, 9, v0
	v_mul_u32_u24_e32 v3, 0xaaab, v2
	v_lshrrev_b32_e32 v3, 17, v3
	s_mov_b32 s2, 0xaaaaaaab
	v_mul_lo_u16_e32 v3, 3, v3
	v_mul_hi_u32 v0, v0, s2
	v_sub_u16_e32 v4, v2, v3
	v_lshrrev_b32_e32 v5, 10, v0
	v_lshl_or_b32 v0, v5, 3, v4
	v_add_u32_e32 v0, 0x2005, v0
	v_mov_b64_e32 v[2:3], s[74:75]
	v_and_b32_e32 v6, 0x7fc, v28
	v_mad_u64_u32 v[2:3], s[2:3], v0, s25, v[2:3]
	v_lshlrev_b32_e32 v0, 1, v6
	v_lshl_add_u64 v[2:3], v[2:3], 0, v[0:1]
	s_mov_b64 s[2:3], 0x1000
	v_lshl_add_u64 v[14:15], v[2:3], 0, s[2:3]
	v_readlane_b32 s2, v248, 33
	v_readlane_b32 s56, v251, 21
	v_readlane_b32 s60, v251, 25
	v_add_u32_e32 v0, s2, v5
	v_mad_u32_u24 v0, v0, 3, v4
	v_lshlrev_b64 v[2:3], 13, v[0:1]
	v_lshl_add_u64 v[2:3], s[12:13], 0, v[2:3]
	v_lshlrev_b32_e32 v0, 2, v6
	v_readlane_b32 s61, v251, 26
	v_lshl_add_u64 v[18:19], v[2:3], 0, v[0:1]
	v_readlane_b32 s57, v251, 22
	v_readlane_b32 s58, v251, 23
	v_readlane_b32 s59, v251, 24
	v_readlane_b32 s62, v251, 27
	v_readlane_b32 s63, v251, 28
	v_readlane_b32 s64, v251, 29
	v_readlane_b32 s65, v251, 30
	v_readlane_b32 s66, v251, 31
	v_readlane_b32 s67, v251, 32
	v_readlane_b32 s68, v251, 33
	v_readlane_b32 s69, v251, 34
	v_readlane_b32 s70, v251, 35
	v_readlane_b32 s71, v251, 36
	v_mov_b64_e32 v[16:17], s[60:61]
.LBB0_605:
	s_or_saveexec_b64 s[46:47], s[44:45]
	s_mov_b64 s[44:45], 0
	s_xor_b64 exec, exec, s[46:47]
	s_cbranch_execz .LBB0_611
	v_add_u32_e32 v0, 0xffffac00, v8
	s_waitcnt vmcnt(1)
	v_lshrrev_b32_e32 v2, 8, v0
	v_mul_u32_u24_e32 v3, 0x8889, v2
	v_lshrrev_b32_e32 v3, 19, v3
	v_mul_lo_u16_e32 v3, 15, v3
	s_mov_b32 s2, 0x88888889
	v_sub_u16_e32 v2, v2, v3
	v_mul_hi_u32 v0, v0, s2
	v_lshrrev_b32_e32 v3, 11, v0
	v_and_b32_e32 v4, 0x3fc, v28
	v_cmp_lt_u16_e32 vcc, 6, v2
	s_and_saveexec_b64 s[2:3], vcc
	s_xor_b64 s[20:21], exec, s[2:3]
	v_lshlrev_b32_e32 v0, 3, v3
	s_movk_i32 s2, 0x1ff9
	v_add3_u32 v0, v0, v2, s2
	v_mov_b64_e32 v[6:7], s[74:75]
	v_mad_u64_u32 v[6:7], s[2:3], v0, s25, v[6:7]
	v_lshlrev_b32_e32 v0, 1, v4
	v_lshl_add_u64 v[14:15], v[6:7], 0, v[0:1]
	s_or_saveexec_b64 s[44:45], s[20:21]
	v_readlane_b32 s2, v248, 33
	v_readlane_b32 s56, v251, 21
	v_readlane_b32 s60, v251, 25
	v_add_u32_e32 v0, s2, v3
	v_mad_u32_u24 v0, v0, 15, v2
	v_readlane_b32 s61, v251, 26
	v_lshlrev_b64 v[2:3], 12, v[0:1]
	s_mov_b64 s[20:21], 0
	v_mov_b64_e32 v[16:17], s[60:61]
	v_lshlrev_b32_e32 v0, 2, v4
	v_readlane_b32 s57, v251, 22
	v_readlane_b32 s58, v251, 23
	v_readlane_b32 s59, v251, 24
	v_readlane_b32 s62, v251, 27
	v_readlane_b32 s63, v251, 28
	v_readlane_b32 s64, v251, 29
	v_readlane_b32 s65, v251, 30
	v_readlane_b32 s66, v251, 31
	v_readlane_b32 s67, v251, 32
	v_readlane_b32 s68, v251, 33
	v_readlane_b32 s69, v251, 34
	v_readlane_b32 s70, v251, 35
	v_readlane_b32 s71, v251, 36
	s_xor_b64 exec, exec, s[44:45]
	s_cbranch_execz .LBB0_610
	v_readlane_b32 s56, v251, 21
	v_readlane_b32 s60, v251, 25
	v_readlane_b32 s61, v251, 26
	s_mov_b64 s[2:3], 0x8000
	s_mov_b64 s[20:21], exec
	v_lshl_add_u64 v[4:5], s[60:61], 0, v[2:3]
	v_lshl_add_u64 v[4:5], v[4:5], 0, v[0:1]
	v_lshl_add_u64 v[16:17], v[4:5], 0, s[2:3]
	v_readlane_b32 s57, v251, 22
	v_readlane_b32 s58, v251, 23
	v_readlane_b32 s59, v251, 24
	v_readlane_b32 s62, v251, 27
	v_readlane_b32 s63, v251, 28
	v_readlane_b32 s64, v251, 29
	v_readlane_b32 s65, v251, 30
	v_readlane_b32 s66, v251, 31
	v_readlane_b32 s67, v251, 32
	v_readlane_b32 s68, v251, 33
	v_readlane_b32 s69, v251, 34
	v_readlane_b32 s70, v251, 35
	v_readlane_b32 s71, v251, 36

; __device__ __forceinline__ void mix_phase(LAS unsigned char* lds, const Params& p, const int layer) {
;     ...
;             else if ((r -= N_PP) < N_CP) { const int c4 = r % (LW / 4), i = (r / (LW / 4)) % 3, b_ = r / (3 * (LW / 4));
;                 src[k] = PROJ + (size_t)(b_ * 2048 + 2045 + i) * NC + C_UB + c4 * 4; dst[k] = out + O_CONVP + ((size_t)(layer * 4 + b_) * 3 + i) * LW + c4 * 4; }
.LBB0_612:
	s_andn2_saveexec_b64 s[38:39], s[38:39]
	s_cbranch_execz .LBB0_614
	v_add_u32_e32 v0, 0xffffc400, v8
	s_waitcnt vmcnt(1)
	v_lshrrev_b32_e32 v2, 9, v0
	v_mul_lo_u16_e32 v3, 0xab, v2
	v_lshrrev_b16_e32 v3, 9, v3
	v_mul_lo_u16_e32 v3, 3, v3
	v_sub_u16_e32 v2, v2, v3
	v_mul_u32_u24_e32 v0, 0xaaab, v0
	v_and_b32_e32 v4, 0xff, v2
	v_lshrrev_b32_e32 v5, 26, v0
	v_lshl_or_b32 v0, v5, 11, v4
	v_add_u32_e32 v0, 0x7fd, v0
	v_mov_b64_e32 v[2:3], s[74:75]
	v_and_b32_e32 v6, 0x7fc, v28
	v_mad_u64_u32 v[2:3], s[2:3], v0, s25, v[2:3]
	v_lshlrev_b32_e32 v0, 1, v6
	v_lshl_add_u64 v[2:3], v[2:3], 0, v[0:1]
	s_mov_b64 s[2:3], 0x1000
	v_add_u32_e32 v0, s18, v5
	v_lshl_add_u64 v[14:15], v[2:3], 0, s[2:3]
	v_mul_u32_u24_e32 v0, 3, v0
	v_readlane_b32 s2, v249, 24
	v_add_lshl_u32 v0, v0, v4, 13
	v_readlane_b32 s3, v249, 25
	s_andn2_b64 s[44:45], s[44:45], exec
	s_nop 0
	v_lshl_add_u64 v[2:3], s[2:3], 0, v[0:1]
	v_lshlrev_b32_e32 v0, 2, v6
	v_lshl_add_u64 v[18:19], v[2:3], 0, v[0:1]

; __device__ __forceinline__ void mix_phase(LAS unsigned char* lds, const Params& p, const int layer) {
;     ...
;         for (int k = 0; k < 3; ++k) {
;             const int it = it0 + k * GT; ok[k] = it < N_ST; int r = ok[k] ? it : 0; isf[k] = false; src[k] = PROJ; fsrc[k] = p.in[2];
;             if (r < N_PP) { const int c4 = r % (PW / 4), i = (r / (PW / 4)) % 15, b_ = r / (15 * (PW / 4));
;                 src[k] = PROJ + (size_t)(b_ * 2048 + 2033 + i) * NC + C_UA + c4 * 4; dst[k] = out + O_POOLP + ((size_t)(layer * 4 + b_) * 15 + i) * PW + c4 * 4; }
;             else if ((r -= N_PP) < N_CP) { const int c4 = r % (LW / 4), i = (r / (LW / 4)) % 3, b_ = r / (3 * (LW / 4));
;                 src[k] = PROJ + (size_t)(b_ * 2048 + 2045 + i) * NC + C_UB + c4 * 4; dst[k] = out + O_CONVP + ((size_t)(layer * 4 + b_) * 3 + i) * LW + c4 * 4; }
;             else if ((r -= N_CP) < N_PS) { const int c4 = r % (PW / 4), i = (r / (PW / 4)) % 15, bs = r / (15 * (PW / 4));
;                 dst[k] = out + O_POOLS + ((size_t)(layer * 128 + bs) * 15 + i) * PW + c4 * 4;
;                 if (i < 7) { isf[k] = true; fsrc[k] = p.in[2] + ((size_t)(layer * 128 + bs) * 15 + 8 + i) * PW + c4 * 4; } else src[k] = PROJ + (size_t)(NP + bs * 8 + (i - 7)) * NC + C_UA + c4 * 4; }
;             else { r -= N_PS; const int c4 = r % (LW / 4), i = (r / (LW / 4)) % 3, bs = r / (3 * (LW / 4));
;                 src[k] = PROJ + (size_t)(NP + bs * 8 + 5 + i) * NC + C_UB + c4 * 4; dst[k] = out + O_CONVS + ((size_t)(layer * 128 + bs) * 3 + i) * LW + c4 * 4; }
.LBB0_615:
	s_andn2_saveexec_b64 s[0:1], s[0:1]
	s_cbranch_execz .LBB0_617
	v_ashrrev_i32_e32 v0, 31, v8
	v_add_u32_sdwa v0, v8, v0 dst_sel:DWORD dst_unused:UNUSED_PAD src0_sel:DWORD src1_sel:BYTE_3
	v_ashrrev_i32_e32 v0, 8, v0
	s_waitcnt vmcnt(1)
	v_mul_i32_i24_e32 v2, 0x100, v0
	s_mov_b32 s2, 0x88888889
	v_sub_u32_e32 v4, v8, v2
	v_mul_hi_i32 v2, v0, s2
	v_add_u32_e32 v2, v2, v0
	v_lshrrev_b32_e32 v3, 31, v2
	v_ashrrev_i32_e32 v2, 3, v2
	v_add_u32_e32 v2, v2, v3
	v_mul_lo_u32 v2, v2, 15
	v_sub_u32_e32 v0, v0, v2
	v_mul_hi_i32 v2, v8, s2
	v_add_u32_e32 v2, v2, v8
	v_lshrrev_b32_e32 v3, 31, v2
	v_ashrrev_i32_e32 v2, 11, v2
	v_add_u32_e32 v6, v2, v3
	v_lshlrev_b32_e32 v2, 11, v6
	s_movk_i32 s2, 0x7f1
	v_add3_u32 v5, v0, v2, s2
	v_mov_b64_e32 v[2:3], s[74:75]
	v_lshlrev_b32_e32 v4, 2, v4
	v_mad_i64_i32 v[2:3], s[2:3], v5, s25, v[2:3]
	v_ashrrev_i32_e32 v5, 31, v4
	v_lshl_add_u64 v[14:15], v[4:5], 1, v[2:3]
	v_add_u32_e32 v2, s18, v6
	v_mad_i32_i24 v2, v2, 15, v0
	v_ashrrev_i32_e32 v3, 31, v2
	v_readlane_b32 s2, v249, 26
	v_lshlrev_b64 v[2:3], 12, v[2:3]
	v_readlane_b32 s3, v249, 27
	s_andn2_b64 s[44:45], s[44:45], exec
	s_nop 0
	v_lshl_add_u64 v[2:3], s[2:3], 0, v[2:3]
	v_lshl_add_u64 v[18:19], v[4:5], 2, v[2:3]
.LBB0_617:
	s_or_b64 exec, exec, s[0:1]
	v_add_u32_e32 v29, s5, v8
	s_mov_b32 s0, 0xad400
	v_cmp_gt_i32_e32 vcc, s0, v29
	v_readlane_b32 s56, v251, 21
	s_movk_i32 s0, 0x3bff
	v_cndmask_b32_e32 v0, 0, v29, vcc
	v_readlane_b32 s60, v251, 25
	v_readlane_b32 s61, v251, 26
	s_waitcnt vmcnt(1)
	v_mov_b32_e32 v2, s74
	v_mov_b32_e32 v3, s75
	v_cmp_lt_i32_e64 s[0:1], s0, v0
	v_mov_b64_e32 v[4:5], s[60:61]
	v_readlane_b32 s57, v251, 22
	v_readlane_b32 s58, v251, 23
	v_readlane_b32 s59, v251, 24
	v_readlane_b32 s62, v251, 27
	v_readlane_b32 s63, v251, 28
	v_readlane_b32 s64, v251, 29
	v_readlane_b32 s65, v251, 30
	v_readlane_b32 s66, v251, 31
	v_readlane_b32 s67, v251, 32
	v_readlane_b32 s68, v251, 33
	v_readlane_b32 s69, v251, 34
	v_readlane_b32 s70, v251, 35
	v_readlane_b32 s71, v251, 36
	s_and_saveexec_b64 s[2:3], s[0:1]
	s_xor_b64 s[38:39], exec, s[2:3]
	s_cbranch_execz .LBB0_631
	v_readlane_b32 s56, v251, 21
	s_movk_i32 s0, 0x53ff
	v_readlane_b32 s60, v251, 25
	v_readlane_b32 s61, v251, 26
	v_cmp_lt_u32_e64 s[0:1], s0, v0
	v_readlane_b32 s57, v251, 22
	v_mov_b64_e32 v[4:5], s[60:61]
	v_readlane_b32 s58, v251, 23
	v_readlane_b32 s59, v251, 24
	v_readlane_b32 s62, v251, 27
	v_readlane_b32 s63, v251, 28
	v_readlane_b32 s64, v251, 29
	v_readlane_b32 s65, v251, 30
	v_readlane_b32 s66, v251, 31
	v_readlane_b32 s67, v251, 32
	v_readlane_b32 s68, v251, 33
	v_readlane_b32 s69, v251, 34
	v_readlane_b32 s70, v251, 35
	v_readlane_b32 s71, v251, 36
	s_and_saveexec_b64 s[2:3], s[0:1]
	s_xor_b64 s[48:49], exec, s[2:3]
	s_cbranch_execz .LBB0_628
	s_mov_b32 s0, 0x7d3ff
	v_cmp_lt_u32_e64 s[0:1], s0, v0
	s_and_saveexec_b64 s[2:3], s[0:1]
	s_xor_b64 s[0:1], exec, s[2:3]
	s_cbranch_execz .LBB0_621
	v_add_u32_e32 v2, 0xfff82c00, v0
	v_lshrrev_b32_e32 v3, 9, v2
	s_mov_b32 s2, 0x55555556
	v_mul_hi_u32 v4, v3, s2
	s_mov_b32 s2, 0xaaaaaaab
	v_mul_u32_u24_e32 v4, 3, v4
	v_mul_hi_u32 v2, v2, s2
	v_sub_u32_e32 v4, v3, v4
	v_lshrrev_b32_e32 v5, 10, v2
	v_lshl_or_b32 v2, v5, 3, v4
	v_add_u32_e32 v6, 0x2005, v2
	v_mov_b64_e32 v[2:3], s[74:75]
	v_lshlrev_b32_e32 v0, 2, v0
	v_mad_u64_u32 v[2:3], s[2:3], v6, s25, v[2:3]
	v_and_b32_e32 v6, 0x7fc, v0
	v_lshlrev_b32_e32 v0, 1, v6
	v_lshl_add_u64 v[2:3], v[2:3], 0, v[0:1]
	s_mov_b64 s[2:3], 0x1000
	v_lshl_add_u64 v[2:3], v[2:3], 0, s[2:3]
	v_readlane_b32 s2, v248, 33
	v_readlane_b32 s56, v251, 21
	v_readlane_b32 s60, v251, 25
	v_add_u32_e32 v0, s2, v5
	v_mad_u32_u24 v0, v0, 3, v4
	v_lshlrev_b64 v[4:5], 13, v[0:1]
	v_lshl_add_u64 v[4:5], s[12:13], 0, v[4:5]
	v_lshlrev_b32_e32 v0, 2, v6
	v_readlane_b32 s61, v251, 26
	v_lshl_add_u64 v[20:21], v[4:5], 0, v[0:1]
	v_readlane_b32 s57, v251, 22
	v_mov_b64_e32 v[4:5], s[60:61]
	v_readlane_b32 s58, v251, 23
	v_readlane_b32 s59, v251, 24
	v_readlane_b32 s62, v251, 27
	v_readlane_b32 s63, v251, 28
	v_readlane_b32 s64, v251, 29
	v_readlane_b32 s65, v251, 30
	v_readlane_b32 s66, v251, 31
	v_readlane_b32 s67, v251, 32
	v_readlane_b32 s68, v251, 33
	v_readlane_b32 s69, v251, 34
	v_readlane_b32 s70, v251, 35
	v_readlane_b32 s71, v251, 36

; __device__ __forceinline__ void mix_phase(LAS unsigned char* lds, const Params& p, const int layer) {
;     ...
;         v2u wv[3]; f32x4 fv[3];
; #pragma unroll
;         for (int k = 0; k < 3; ++k) { wv[k] = *(const v2u*)src[k]; fv[k] = *(const f32x4*)fsrc[k]; }
.LBB0_649:
	s_or_b64 exec, exec, s[0:1]
	s_waitcnt lgkmcnt(0)
	global_load_dwordx2 v[26:27], v[2:3], off
	global_load_dwordx4 v[6:9], v[4:5], off
	global_load_dwordx2 v[24:25], v[10:11], off
	s_nop 0
	global_load_dwordx4 v[2:5], v[12:13], off
	s_xor_b64 s[0:1], s[44:45], -1
	s_and_saveexec_b64 s[2:3], s[0:1]
	s_xor_b64 s[0:1], exec, s[2:3]
	s_cbranch_execz .LBB0_653
	global_load_dwordx2 v[12:13], v[14:15], off
	s_waitcnt lgkmcnt(0)
	s_waitcnt vmcnt(0)
	v_lshlrev_b32_e32 v10, 16, v12
	v_and_b32_e32 v11, 0xffff0000, v12
	v_lshlrev_b32_e32 v12, 16, v13
	v_and_b32_e32 v13, 0xffff0000, v13
	s_andn2_saveexec_b64 s[0:1], s[0:1]
	s_cbranch_execnz .LBB0_654

; __device__ __forceinline__ float bflo(unsigned w) { return __uint_as_float(w << 16); }
; __device__ __forceinline__ float bfhi(unsigned w) { return __uint_as_float(w & 0xffff0000u); }
; __device__ __forceinline__ void mix_phase(LAS unsigned char* lds, const Params& p, const int layer) {
;     ...
; #pragma unroll
;         for (int k = 0; k < 3; ++k) { const f32x4 v = isf[k] ? fv[k] : (f32x4){bflo(wv[k].x), bfhi(wv[k].x), bflo(wv[k].y), bfhi(wv[k].y)}; if (ok[k]) *(f32x4*)dst[k] = v; }
.LBB0_652:
	s_waitcnt lgkmcnt(0)
	s_waitcnt vmcnt(4)
	v_lshlrev_b32_e32 v0, 16, v26
	v_and_b32_e32 v10, 0xffff0000, v26
	v_lshlrev_b32_e32 v11, 16, v27
	v_and_b32_e32 v12, 0xffff0000, v27
	s_waitcnt vmcnt(3)
	v_cndmask_b32_e64 v9, v12, v9, s[46:47]
	v_cndmask_b32_e64 v8, v11, v8, s[46:47]
	v_cndmask_b32_e64 v7, v10, v7, s[46:47]
	v_cndmask_b32_e64 v6, v0, v6, s[46:47]
	global_store_dwordx4 v[20:21], v[6:9], off
	s_or_b64 exec, exec, s[0:1]
	s_and_saveexec_b64 s[0:1], s[38:39]
	s_cbranch_execz .LBB0_600
	s_branch .LBB0_656

; __device__ __forceinline__ float bflo(unsigned w) { return __uint_as_float(w << 16); }
; __device__ __forceinline__ float bfhi(unsigned w) { return __uint_as_float(w & 0xffff0000u); }
; __device__ __forceinline__ void mix_phase(LAS unsigned char* lds, const Params& p, const int layer) {
;     ...
; #pragma unroll
;         for (int k = 0; k < 3; ++k) { const f32x4 v = isf[k] ? fv[k] : (f32x4){bflo(wv[k].x), bfhi(wv[k].x), bflo(wv[k].y), bfhi(wv[k].y)}; if (ok[k]) *(f32x4*)dst[k] = v; }
.LBB0_656:
	s_waitcnt lgkmcnt(0)
	s_waitcnt vmcnt(2)
	v_lshlrev_b32_e32 v0, 16, v24
	v_and_b32_e32 v6, 0xffff0000, v24
	v_lshlrev_b32_e32 v7, 16, v25
	v_and_b32_e32 v8, 0xffff0000, v25
	s_waitcnt vmcnt(1)
	v_cndmask_b32_e64 v5, v8, v5, s[48:49]
	v_cndmask_b32_e64 v4, v7, v4, s[48:49]
	v_cndmask_b32_e64 v3, v6, v3, s[48:49]
	v_cndmask_b32_e64 v2, v0, v2, s[48:49]
	global_store_dwordx4 v[22:23], v[2:5], off
	s_branch .LBB0_600

; #define PG8_STAGE(bufoff, gbase, voff) do { _Pragma("unroll") for (int _i = 0; _i < 2; ++_i) \
;         __builtin_amdgcn_global_load_lds((const unsigned*)((const char*)(gbase) + (voff)[_i]), (PG8_LAS unsigned*)(lds + (bufoff) + ldsw + _i * 8192), 16, 0, 0); } while (0)
; #define PG8_WAIT_V(n) asm volatile("s_waitcnt vmcnt(" #n ")" ::: "memory")
; #define PG8_BAR __builtin_amdgcn_s_barrier()
; template <class Epi, class Sched, bool ALIGN_EPI = false, bool SP2 = false>
; __device__ __forceinline__ void gemm_phase(PG8_LAS unsigned char* lds, const Gemm g, const Sched& S, const Epi& E) {
;     ...
;     for (int i = 0; i < 2; ++i) { int R, C; stage_rc(tid * 16 + i * 8192, R, C); const int Rb = Epi::PERM ? ((R & ~31) + perm32(R & 31)) : R;
;         voffA[i] = (unsigned)(R * K + C) * 2u; voffB[i] = (unsigned)(Rb * K + C) * 2u; }
;     const size_t kstep = (size_t)(BK * 2);
;     const size_t hstep = (size_t)HALF * K * 2;
;     const size_t tstep = 2 * hstep;
;     const unsigned ldsw = (unsigned)wid * 1024u;
;     const int aoff = lds_byte(wr * 64 + fr, fq * 8), boff = lds_byte(wc * 32 + fr, fq * 8);
;     ...
;     const char* cA = (const char*)g.A + (size_t)cur.pm * tstep; const char* cB = (const char*)g.Bt + (size_t)cur.pn * tstep;
;     S.a_ready(cur);
;     if constexpr (SP2) {
;         PG8_STAGE(PG8_SB(0, 0), cB, voffB); PG8_STAGE(PG8_SB(0, 1), cB + hstep, voffB); PG8_STAGE(PG8_SA(0, 0), cA, voffA); PG8_STAGE(PG8_SA(0, 1), cA + hstep, voffA);
;         if (wr == 1) PG8_BAR;
;         PG8_WAIT_V(2); PG8_BAR;
.LBB0_743:
	v_mov_b32_e32 v17, v193
	s_cmp_lt_i32 s95, 1
	v_readfirstlane_b32 s3, v17
	s_cbranch_scc1 .LBB0_767
	s_waitcnt vmcnt(1)
	v_lshlrev_b32_e32 v2, 4, v17
	v_add_u32_e32 v3, 0x2000, v2
	v_ashrrev_i32_e32 v0, 31, v3
	v_lshrrev_b32_e32 v0, 22, v0
	v_add_u32_e32 v0, v3, v0
	v_ashrrev_i32_e32 v0, 10, v0
	v_mul_i32_i24_e32 v4, 0x400, v0
	v_sub_u32_e32 v3, v3, v4
	v_lshrrev_b32_e32 v4, 4, v3
	s_ashr_i32 s2, s3, 6
	v_bitop3_b32 v3, v4, v3, 32 bitop3:0x6c
	s_ashr_i32 s20, s3, 8
	s_lshl_b32 s14, s2, 10
	s_ashr_i32 s15, s13, 3
	s_and_b32 s16, s13, 7
	v_ashrrev_i32_e32 v4, 31, v3
	s_cmp_lg_u32 s5, 1
	v_lshrrev_b32_e32 v4, 26, v4
	s_cselect_b64 s[38:39], -1, 0
	v_add_u32_e32 v4, v3, v4
	v_lshlrev_b32_e32 v5, 3, v0
	s_and_b64 s[6:7], s[38:39], exec
	v_ashrrev_i32_e32 v10, 6, v4
	v_and_b32_e32 v5, -16, v5
	s_cselect_b32 s5, 0, 0xc00
	v_readlane_b32 s6, v248, 33
	v_add_u32_e32 v5, v10, v5
	s_add_u32 s17, s6, s5
	v_readlane_b32 s6, v248, 35
	v_and_b32_e32 v6, 3, v10
	s_mov_b32 s21, 0x3fffe0
	v_lshrrev_b32_e32 v7, 2, v5
	v_lshlrev_b32_e32 v8, 1, v5
	v_and_b32_e32 v4, 0xc0, v4
	s_addc_u32 s33, s6, 0
	v_readlane_b32 s6, v248, 34
	v_and_or_b32 v6, v5, s21, v6
	v_and_b32_e32 v7, 4, v7
	v_and_b32_e32 v8, 24, v8
	v_sub_u32_e32 v3, v3, v4
	s_add_u32 s6, s6, s5
	v_readlane_b32 s5, v248, 37
	v_or3_b32 v6, v6, v7, v8
	v_lshlrev_b32_e32 v7, 5, v0
	v_ashrrev_i16_sdwa v3, v216, sext(v3) dst_sel:DWORD dst_unused:UNUSED_PAD src0_sel:DWORD src1_sel:BYTE_0
	s_addc_u32 s7, s5, 0
	v_and_b32_e32 v11, 32, v7
	v_bfe_i32 v12, v3, 0, 16
	s_movk_i32 s5, 0xc00
	v_mul_u32_u24_e32 v6, 0xc00, v6
	v_add_u32_e32 v3, v11, v12
	v_mul_lo_u32 v4, v5, s5
	v_add_lshl_u32 v168, v6, v3, 1
	v_add_lshl_u32 v170, v3, v4, 1
	v_bfe_i32 v3, v17, 27, 1
	v_lshrrev_b32_e32 v3, 22, v3
	v_add_u32_e32 v3, v2, v3
	v_and_b32_e32 v3, 0xfffffc00, v3
	v_sub_u32_e32 v2, v2, v3
	v_lshrrev_b32_e32 v3, 4, v2
	v_ashrrev_i32_e32 v4, 31, v17
	v_bitop3_b32 v2, v3, v2, 32 bitop3:0x6c
	v_lshrrev_b32_e32 v4, 26, v4
	v_ashrrev_i32_e32 v3, 31, v2
	v_add_u32_e32 v4, v17, v4
	v_lshrrev_b32_e32 v3, 26, v3
	v_ashrrev_i32_e32 v14, 6, v4
	v_add_u32_e32 v3, v2, v3
	v_lshlrev_b32_e32 v4, 3, v14
	v_ashrrev_i32_e32 v13, 6, v3
	v_and_b32_e32 v4, -16, v4
	v_add_u32_e32 v4, v13, v4
	v_and_b32_e32 v5, 3, v13
	v_lshrrev_b32_e32 v6, 2, v4
	v_lshlrev_b32_e32 v7, 1, v4
	v_and_b32_e32 v3, 0xc0, v3
	v_and_or_b32 v5, v4, s21, v5
	v_and_b32_e32 v6, 4, v6
	v_and_b32_e32 v7, 24, v7
	v_sub_u32_e32 v2, v2, v3
	v_or3_b32 v5, v5, v6, v7
	v_lshlrev_b32_e32 v6, 5, v14
	v_ashrrev_i16_sdwa v2, v216, sext(v2) dst_sel:DWORD dst_unused:UNUSED_PAD src0_sel:DWORD src1_sel:BYTE_0
	v_mul_lo_u32 v3, v4, s5
	s_mul_i32 s5, s16, 0x180000
	s_mov_b64 s[66:67], s[90:91]
	v_and_b32_e32 v15, 32, v6
	v_bfe_i32 v16, v2, 0, 16
	s_add_u32 s90, s6, s5
	v_mul_u32_u24_e32 v5, 0xc00, v5
	v_add_u32_e32 v2, v15, v16
	s_addc_u32 s91, s7, 0
	s_add_i32 s5, s14, 0
	v_add_lshl_u32 v172, v5, v2, 1
	s_add_i32 m0, s5, 0x10000
	s_mul_i32 s30, s15, 0x180000
	global_load_lds_dwordx4 v172, s[90:91]
	s_add_i32 m0, s5, 0x12000
	s_add_u32 s28, s90, 0xc0000
	global_load_lds_dwordx4 v168, s[90:91]
	s_addc_u32 s29, s91, 0
	s_add_i32 m0, s5, 0x14000
	s_mul_hi_i32 s21, s15, 0x180000
	global_load_lds_dwordx4 v172, s[28:29]
	s_add_i32 m0, s5, 0x16000
	s_add_u32 s52, s17, s30
	s_addc_u32 s53, s33, s21
	s_add_i32 s34, s5, 0x2000
	v_add_lshl_u32 v174, v2, v3, 1
	global_load_lds_dwordx4 v168, s[28:29]
	s_mov_b32 m0, s5
	s_add_u32 s30, s52, 0xc0000
	global_load_lds_dwordx4 v174, s[52:53]
	s_mov_b32 m0, s34
	s_addc_u32 s31, s53, 0
	s_add_i32 s28, s5, 0x4000
	global_load_lds_dwordx4 v170, s[52:53]
	s_mov_b32 m0, s28
	s_add_i32 s29, s5, 0x6000
	global_load_lds_dwordx4 v174, s[30:31]
	s_mov_b32 m0, s29
	v_mov_b32_e32 v173, v1
	global_load_lds_dwordx4 v170, s[30:31]
	v_mov_b32_e32 v169, v1
	v_mov_b32_e32 v175, v1
	v_mov_b32_e32 v171, v1
	s_cmp_eq_u32 s20, 1
	s_mov_b64 s[68:69], s[56:57]
	s_mov_b64 s[42:43], s[78:79]
	v_lshl_add_u64 v[8:9], s[90:91], 0, v[172:173]
	v_lshl_add_u64 v[6:7], s[90:91], 0, v[168:169]
	v_lshl_add_u64 v[2:3], s[52:53], 0, v[174:175]
	s_cselect_b64 s[40:41], -1, 0
	s_cmp_lg_u32 s20, 1
	v_lshl_add_u64 v[4:5], s[52:53], 0, v[170:171]
	s_cbranch_scc1 .LBB0_746
	s_barrier

;     __device__ __forceinline__ bool next(int i, pg8::Unit& u) const { if (i >= count) return false; const int L = start + i * stride; u.pm = L >> 3; u.pn = L & 7; return true; }
; template <class Epi, class Sched, bool ALIGN_EPI = false, bool SP2 = false>
; __device__ __forceinline__ void gemm_phase(PG8_LAS unsigned char* lds, const Gemm g, const Sched& S, const Epi& E) {
;     ...
;         const bool has_next = S.next(ui + 1, nxt);
;         const char* nA = has_next ? (const char*)g.A + (size_t)nxt.pm * tstep : cA; const char* nB = has_next ? (const char*)g.Bt + (size_t)nxt.pn * tstep : cB;
;         for (int t = 0; t < nt; t += 2) {
;             if constexpr (Epi::HOOK) { if (t == E.hook_t) E.hook(acc, cur, wr, wc, fr, fq); }
;             const bool last = (t == nt - 2);
;             const char* a1 = cA + (size_t)(t + 1) * kstep;
;             const char* a2 = last ? nA : cA + (size_t)(t + 2) * kstep; const char* b2 = last ? nB : cB + (size_t)(t + 2) * kstep;
;             const char* a3 = a2 + kstep; const char* b3 = b2 + kstep;
;     ...
; #pragma unroll
;         for (int a = 0; a < 2; ++a)
; #pragma unroll
;             for (int b = 0; b < 2; ++b)
; #pragma unroll
;                 for (int m = 0; m < 4; ++m)
; #pragma unroll
;                     for (int n = 0; n < 2; ++n) acc[a][b][m][n] = (f32x4){0.f, 0.f, 0.f, 0.f};
;         cur = nxt; cA = nA; cB = nB; ++ui;
.LBB0_753:
	s_add_u32 s20, s90, 0x100
	s_addc_u32 s21, s91, 0
	s_add_u32 s90, s52, 0xc0080
	v_mov_b32_e32 v2, v1
	v_mov_b32_e32 v3, v1
	s_addc_u32 s91, s53, 0
	v_mov_b32_e32 v0, v1
	v_mov_b64_e32 v[6:7], v[2:3]
	v_mov_b64_e32 v[10:11], v[2:3]
	v_mov_b64_e32 v[22:23], v[2:3]
	s_waitcnt lgkmcnt(0)
	v_mov_b64_e32 v[26:27], v[2:3]
	v_mov_b64_e32 v[38:39], v[2:3]
	v_mov_b64_e32 v[42:43], v[2:3]
	v_mov_b64_e32 v[54:55], v[2:3]
	v_mov_b64_e32 v[58:59], v[2:3]
	v_mov_b64_e32 v[14:15], v[2:3]
	v_mov_b64_e32 v[18:19], v[2:3]
	v_mov_b64_e32 v[30:31], v[2:3]
	v_mov_b64_e32 v[34:35], v[2:3]
	v_mov_b64_e32 v[46:47], v[2:3]
	v_mov_b64_e32 v[50:51], v[2:3]
	v_mov_b64_e32 v[62:63], v[2:3]
	v_mov_b64_e32 v[66:67], v[2:3]
	v_mov_b64_e32 v[70:71], v[2:3]
	v_mov_b64_e32 v[74:75], v[2:3]
	v_mov_b64_e32 v[86:87], v[2:3]
	v_mov_b64_e32 v[90:91], v[2:3]
	v_mov_b64_e32 v[102:103], v[2:3]
	v_mov_b64_e32 v[106:107], v[2:3]
	v_mov_b64_e32 v[126:127], v[2:3]
	v_mov_b64_e32 v[130:131], v[2:3]
	v_mov_b64_e32 v[78:79], v[2:3]
	v_mov_b64_e32 v[82:83], v[2:3]
	v_mov_b64_e32 v[94:95], v[2:3]
	v_mov_b64_e32 v[98:99], v[2:3]
	v_mov_b64_e32 v[110:111], v[2:3]
	v_mov_b64_e32 v[114:115], v[2:3]
	v_mov_b64_e32 v[118:119], v[2:3]
	v_mov_b64_e32 v[122:123], v[2:3]
	v_lshl_add_u32 v180, s15, 8, v190
	v_lshl_or_b32 v182, s16, 8, v192
	v_lshl_add_u64 v[184:185], s[90:91], 0, v[176:177]
	v_lshl_add_u64 v[186:187], s[90:91], 0, v[178:179]
	s_mov_b32 s57, 0
	s_mov_b64 s[90:91], 0
	v_mov_b64_e32 v[4:5], v[0:1]
	v_mov_b64_e32 v[8:9], v[0:1]
	v_mov_b64_e32 v[20:21], v[0:1]
	v_mov_b64_e32 v[24:25], v[0:1]
	v_mov_b64_e32 v[36:37], v[0:1]
	v_mov_b64_e32 v[40:41], v[0:1]
	v_mov_b64_e32 v[52:53], v[0:1]
	v_mov_b64_e32 v[56:57], v[0:1]
	v_mov_b64_e32 v[12:13], v[0:1]
	v_mov_b64_e32 v[16:17], v[0:1]
	v_mov_b64_e32 v[28:29], v[0:1]
	v_mov_b64_e32 v[32:33], v[0:1]
	v_mov_b64_e32 v[44:45], v[0:1]
	v_mov_b64_e32 v[48:49], v[0:1]
	v_mov_b64_e32 v[60:61], v[0:1]
	v_mov_b64_e32 v[64:65], v[0:1]
	v_mov_b64_e32 v[68:69], v[0:1]
	v_mov_b64_e32 v[72:73], v[0:1]
	v_mov_b64_e32 v[84:85], v[0:1]
	v_mov_b64_e32 v[88:89], v[0:1]
	v_mov_b64_e32 v[100:101], v[0:1]
	v_mov_b64_e32 v[104:105], v[0:1]
	v_mov_b64_e32 v[124:125], v[0:1]
	v_mov_b64_e32 v[128:129], v[0:1]
	v_mov_b64_e32 v[76:77], v[0:1]
	v_mov_b64_e32 v[80:81], v[0:1]
	v_mov_b64_e32 v[92:93], v[0:1]
	v_mov_b64_e32 v[96:97], v[0:1]
	v_mov_b64_e32 v[108:109], v[0:1]
	v_mov_b64_e32 v[112:113], v[0:1]
	v_mov_b64_e32 v[116:117], v[0:1]
	v_mov_b64_e32 v[120:121], v[0:1]
	s_branch .LBB0_755

;     __device__ __forceinline__ void hook(f32x4 (&acc)[2][2][4][2], const Unit& u, int wr, int wc, int fr, int fq) const {
;     ...
;         for (int bj = 0; bj < 2; ++bj) { const bf16_t* gp = G + (size_t)row0 * ldg + col0 + bj * HALF; ga[0][bj] = *(const u32x4*)(gp + 6144); gb[0][bj] = *(const u32x4*)(gp + 8192); }
; #pragma unroll
;         for (int g = 0; g < 8; ++g) { const int ai = g >> 2, m = g & 3, cb = g & 1, nb_ = cb ^ 1;
;             if (g < 7) { const int an = (g + 1) >> 2, mn = (g + 1) & 3;
; #pragma unroll
;                 for (int bj = 0; bj < 2; ++bj) { const bf16_t* gp = G + (size_t)(row0 + an * HALF + mn * 16) * ldg + col0 + bj * HALF; ga[nb_][bj] = *(const u32x4*)(gp + 6144); gb[nb_][bj] = *(const u32x4*)(gp + 8192); } }
; #pragma unroll
;             for (int bj = 0; bj < 2; ++bj) { f32x4 a0, a1, b0, b1; unpack_bf16x8(ga[cb][bj], a0, a1); unpack_bf16x8(gb[cb][bj], b0, b1);
; #pragma unroll
;                 for (int j = 0; j < 4; ++j) { a0[j] = a0[j] * __builtin_amdgcn_rcpf(fmaxf(b0[j], 1e-30f)); a1[j] = a1[j] * __builtin_amdgcn_rcpf(fmaxf(b1[j], 1e-30f)); }
;                 acc[ai][bj][m][0] = acc[ai][bj][m][0] * a0; acc[ai][bj][m][1] = acc[ai][bj][m][1] * a1; }
.LBB0_755:
	s_cmpk_eq_i32 s90, 0x800
	s_cselect_b64 s[92:93], -1, 0
	s_and_b64 s[92:93], s[38:39], s[92:93]
	s_andn2_b64 vcc, exec, s[92:93]
	s_cbranch_vccnz .LBB0_754
	v_mov_b32_e32 v0, v180
	v_mov_b32_e32 v132, v182
	v_mov_b64_e32 v[2:3], s[8:9]
	v_ashrrev_i32_e32 v133, 31, v132
	v_mad_i64_i32 v[134:135], s[92:93], v0, s25, v[2:3]
	v_lshlrev_b64 v[188:189], 1, v[132:133]
	v_lshl_add_u64 v[132:133], v[134:135], 0, v[188:189]
	v_add_co_u32_e32 v134, vcc, 0x3000, v132
	s_nop 1
	v_addc_co_u32_e32 v135, vcc, 0, v133, vcc
	v_add_co_u32_e32 v132, vcc, s22, v132
	global_load_dwordx4 v[156:159], v[134:135], off
	s_nop 0
	v_addc_co_u32_e32 v133, vcc, 0, v133, vcc
	global_load_dwordx4 v[160:163], v[132:133], off
	global_load_dwordx4 v[148:151], v[134:135], off offset:256
	global_load_dwordx4 v[152:155], v[132:133], off offset:256
	v_add_u32_e32 v132, 16, v0
	v_mad_i64_i32 v[132:133], s[92:93], v132, s25, v[2:3]
	v_lshl_add_u64 v[132:133], v[132:133], 0, v[188:189]
	v_add_co_u32_e32 v134, vcc, s27, v132
	s_waitcnt lgkmcnt(0)
	s_waitcnt vmcnt(3)
	v_lshlrev_b32_e32 v196, 16, v156
	v_addc_co_u32_e32 v135, vcc, 0, v133, vcc
	v_add_co_u32_e32 v136, vcc, s22, v132
	global_load_dwordx4 v[140:143], v[134:135], off
	s_nop 0
	v_addc_co_u32_e32 v137, vcc, 0, v133, vcc
	global_load_dwordx4 v[144:147], v[136:137], off
	s_nop 0
	global_load_dwordx4 v[132:135], v[134:135], off offset:256
	s_nop 0
	global_load_dwordx4 v[136:139], v[136:137], off offset:256
	s_waitcnt vmcnt(6)
	v_lshlrev_b32_e32 v195, 16, v161
	v_and_b32_e32 v198, 0xffff0000, v161
	v_lshlrev_b32_e32 v161, 16, v162
	v_max_f32_e32 v161, v161, v161
	v_lshlrev_b32_e32 v181, 16, v160
	v_and_b32_e32 v183, 0xffff0000, v160
	v_max_f32_e32 v161, 0xda24260, v161
	v_and_b32_e32 v199, 0xffff0000, v162
	v_max_f32_e32 v160, v181, v181
	v_rcp_f32_e32 v162, v161
	v_max_f32_e32 v161, v183, v183
	v_max_f32_e32 v160, 0xda24260, v160
	v_max_f32_e32 v161, 0xda24260, v161
	v_and_b32_e32 v197, 0xffff0000, v156
	v_max_f32_e32 v156, v199, v199
	v_rcp_f32_e32 v160, v160
	v_rcp_f32_e32 v161, v161
	v_max_f32_e32 v156, 0xda24260, v156
	v_lshlrev_b32_e32 v200, 16, v163
	v_and_b32_e32 v201, 0xffff0000, v163
	v_rcp_f32_e32 v163, v156
	v_max_f32_e32 v156, v195, v195
	v_pk_mul_f32 v[160:161], v[160:161], v[196:197]
	v_lshlrev_b32_e32 v196, 16, v158
	v_and_b32_e32 v197, 0xffff0000, v158
	v_max_f32_e32 v156, 0xda24260, v156
	v_pk_mul_f32 v[162:163], v[162:163], v[196:197]
	v_rcp_f32_e32 v196, v156
	v_max_f32_e32 v156, v200, v200
	v_max_f32_e32 v158, v198, v198
	v_lshlrev_b32_e32 v198, 16, v157
	v_and_b32_e32 v199, 0xffff0000, v157
	v_max_f32_e32 v157, v201, v201
	v_max_f32_e32 v156, 0xda24260, v156
	v_max_f32_e32 v157, 0xda24260, v157
	v_rcp_f32_e32 v156, v156
	v_rcp_f32_e32 v157, v157
	v_max_f32_e32 v158, 0xda24260, v158
	v_rcp_f32_e32 v197, v158
	v_lshlrev_b32_e32 v158, 16, v159
	v_and_b32_e32 v159, 0xffff0000, v159
	v_pk_mul_f32 v[156:157], v[156:157], v[158:159]
	s_waitcnt vmcnt(4)
	v_lshlrev_b32_e32 v158, 16, v153
	v_and_b32_e32 v159, 0xffff0000, v153
	v_lshlrev_b32_e32 v153, 16, v154
	v_max_f32_e32 v153, v153, v153
	v_pk_mul_f32 v[118:119], v[118:119], v[156:157]
	v_lshlrev_b32_e32 v156, 16, v152
	v_and_b32_e32 v157, 0xffff0000, v152
	v_max_f32_e32 v153, 0xda24260, v153
	v_pk_mul_f32 v[120:121], v[120:121], v[160:161]
	v_and_b32_e32 v160, 0xffff0000, v154
	v_max_f32_e32 v152, v156, v156
	v_rcp_f32_e32 v154, v153
	v_max_f32_e32 v153, v157, v157
	v_max_f32_e32 v152, 0xda24260, v152
	v_max_f32_e32 v153, 0xda24260, v153
	v_lshlrev_b32_e32 v156, 16, v148
	v_and_b32_e32 v157, 0xffff0000, v148
	v_max_f32_e32 v148, v160, v160
	v_rcp_f32_e32 v152, v152
	v_rcp_f32_e32 v153, v153
	v_max_f32_e32 v148, 0xda24260, v148
	v_pk_mul_f32 v[116:117], v[116:117], v[162:163]
	v_lshlrev_b32_e32 v161, 16, v155
	v_and_b32_e32 v162, 0xffff0000, v155
	v_rcp_f32_e32 v155, v148
	v_max_f32_e32 v148, v158, v158
	v_pk_mul_f32 v[152:153], v[152:153], v[156:157]
	v_lshlrev_b32_e32 v156, 16, v150
	v_and_b32_e32 v157, 0xffff0000, v150
	v_max_f32_e32 v148, 0xda24260, v148
	v_pk_mul_f32 v[154:155], v[154:155], v[156:157]
	v_rcp_f32_e32 v156, v148
	v_max_f32_e32 v148, v161, v161
	v_max_f32_e32 v150, v159, v159
	v_lshlrev_b32_e32 v158, 16, v149
	v_and_b32_e32 v159, 0xffff0000, v149
	v_max_f32_e32 v149, v162, v162
	v_max_f32_e32 v148, 0xda24260, v148
	v_max_f32_e32 v149, 0xda24260, v149
	v_rcp_f32_e32 v148, v148
	v_rcp_f32_e32 v149, v149
	v_max_f32_e32 v150, 0xda24260, v150
	v_rcp_f32_e32 v157, v150
	v_lshlrev_b32_e32 v150, 16, v151
	v_and_b32_e32 v151, 0xffff0000, v151
	v_pk_mul_f32 v[148:149], v[148:149], v[150:151]
	v_pk_mul_f32 v[128:129], v[128:129], v[152:153]
	v_pk_mul_f32 v[126:127], v[126:127], v[148:149]
	v_add_u32_e32 v148, 32, v0
	v_mad_i64_i32 v[148:149], s[92:93], v148, s25, v[2:3]
	v_lshl_add_u64 v[148:149], v[148:149], 0, v[188:189]
	v_add_co_u32_e32 v150, vcc, s27, v148
	s_waitcnt lgkmcnt(0)
	s_waitcnt vmcnt(2)
;     __device__ __forceinline__ void hook(f32x4 (&acc)[2][2][4][2], const Unit& u, int wr, int wc, int fr, int fq) const {
;     ...
;         for (int bj = 0; bj < 2; ++bj) { const bf16_t* gp = G + (size_t)row0 * ldg + col0 + bj * HALF; ga[0][bj] = *(const u32x4*)(gp + 6144); gb[0][bj] = *(const u32x4*)(gp + 8192); }
; #pragma unroll
;         for (int g = 0; g < 8; ++g) { const int ai = g >> 2, m = g & 3, cb = g & 1, nb_ = cb ^ 1;
;             if (g < 7) { const int an = (g + 1) >> 2, mn = (g + 1) & 3;
; #pragma unroll
;                 for (int bj = 0; bj < 2; ++bj) { const bf16_t* gp = G + (size_t)(row0 + an * HALF + mn * 16) * ldg + col0 + bj * HALF; ga[nb_][bj] = *(const u32x4*)(gp + 6144); gb[nb_][bj] = *(const u32x4*)(gp + 8192); } }
; #pragma unroll
;             for (int bj = 0; bj < 2; ++bj) { f32x4 a0, a1, b0, b1; unpack_bf16x8(ga[cb][bj], a0, a1); unpack_bf16x8(gb[cb][bj], b0, b1);
; #pragma unroll
;                 for (int j = 0; j < 4; ++j) { a0[j] = a0[j] * __builtin_amdgcn_rcpf(fmaxf(b0[j], 1e-30f)); a1[j] = a1[j] * __builtin_amdgcn_rcpf(fmaxf(b1[j], 1e-30f)); }
;                 acc[ai][bj][m][0] = acc[ai][bj][m][0] * a0; acc[ai][bj][m][1] = acc[ai][bj][m][1] * a1; }
	v_lshlrev_b32_e32 v162, 16, v145
	v_addc_co_u32_e32 v151, vcc, 0, v149, vcc
	v_add_co_u32_e32 v152, vcc, s22, v148
	v_and_b32_e32 v163, 0xffff0000, v145
	v_lshlrev_b32_e32 v145, 16, v146
	v_pk_mul_f32 v[196:197], v[196:197], v[198:199]
	v_pk_mul_f32 v[156:157], v[156:157], v[158:159]
	v_addc_co_u32_e32 v153, vcc, 0, v149, vcc
	v_max_f32_e32 v145, v145, v145
	v_pk_mul_f32 v[122:123], v[122:123], v[196:197]
	v_pk_mul_f32 v[130:131], v[130:131], v[156:157]
	v_pk_mul_f32 v[124:125], v[124:125], v[154:155]
	global_load_dwordx4 v[156:159], v[150:151], off
	global_load_dwordx4 v[196:199], v[152:153], off
	s_nop 0
	global_load_dwordx4 v[148:151], v[150:151], off offset:256
	s_nop 0
	global_load_dwordx4 v[152:155], v[152:153], off offset:256
	v_lshlrev_b32_e32 v160, 16, v144
	v_and_b32_e32 v161, 0xffff0000, v144
	v_max_f32_e32 v145, 0xda24260, v145
	v_and_b32_e32 v181, 0xffff0000, v146
	v_max_f32_e32 v144, v160, v160
	v_rcp_f32_e32 v146, v145
	v_max_f32_e32 v145, v161, v161
	v_max_f32_e32 v144, 0xda24260, v144
	v_max_f32_e32 v145, 0xda24260, v145
	v_lshlrev_b32_e32 v160, 16, v140
	v_and_b32_e32 v161, 0xffff0000, v140
	v_max_f32_e32 v140, v181, v181
	v_rcp_f32_e32 v144, v144
	v_rcp_f32_e32 v145, v145
	v_max_f32_e32 v140, 0xda24260, v140
	v_lshlrev_b32_e32 v183, 16, v147
	v_and_b32_e32 v195, 0xffff0000, v147
	v_rcp_f32_e32 v147, v140
	v_max_f32_e32 v140, v162, v162
	v_pk_mul_f32 v[144:145], v[144:145], v[160:161]
	v_lshlrev_b32_e32 v160, 16, v142
	v_and_b32_e32 v161, 0xffff0000, v142
	v_max_f32_e32 v140, 0xda24260, v140
	v_pk_mul_f32 v[146:147], v[146:147], v[160:161]
	v_rcp_f32_e32 v160, v140
	v_max_f32_e32 v140, v183, v183
	v_max_f32_e32 v142, v163, v163
	v_lshlrev_b32_e32 v162, 16, v141
	v_and_b32_e32 v163, 0xffff0000, v141
	v_max_f32_e32 v141, v195, v195
	v_max_f32_e32 v140, 0xda24260, v140
	v_max_f32_e32 v141, 0xda24260, v141
	v_rcp_f32_e32 v140, v140
	v_rcp_f32_e32 v141, v141
	v_max_f32_e32 v142, 0xda24260, v142
	v_rcp_f32_e32 v161, v142
	v_lshlrev_b32_e32 v142, 16, v143
	v_and_b32_e32 v143, 0xffff0000, v143
	v_pk_mul_f32 v[140:141], v[140:141], v[142:143]
	s_waitcnt vmcnt(4)
	v_lshlrev_b32_e32 v142, 16, v137
	v_and_b32_e32 v143, 0xffff0000, v137
	v_lshlrev_b32_e32 v137, 16, v138
	v_max_f32_e32 v137, v137, v137
	v_pk_mul_f32 v[110:111], v[110:111], v[140:141]
	v_lshlrev_b32_e32 v140, 16, v136
	v_and_b32_e32 v141, 0xffff0000, v136
	v_max_f32_e32 v137, 0xda24260, v137
	v_pk_mul_f32 v[112:113], v[112:113], v[144:145]
	v_and_b32_e32 v144, 0xffff0000, v138
	v_max_f32_e32 v136, v140, v140
	v_rcp_f32_e32 v138, v137
	v_max_f32_e32 v137, v141, v141
	v_max_f32_e32 v136, 0xda24260, v136
	v_max_f32_e32 v137, 0xda24260, v137
	v_lshlrev_b32_e32 v140, 16, v132
	v_and_b32_e32 v141, 0xffff0000, v132
	v_max_f32_e32 v132, v144, v144
	v_rcp_f32_e32 v136, v136
	v_rcp_f32_e32 v137, v137
	v_max_f32_e32 v132, 0xda24260, v132
	v_pk_mul_f32 v[108:109], v[108:109], v[146:147]
	v_lshlrev_b32_e32 v145, 16, v139
	v_and_b32_e32 v146, 0xffff0000, v139
	v_rcp_f32_e32 v139, v132
	v_max_f32_e32 v132, v142, v142
	v_pk_mul_f32 v[136:137], v[136:137], v[140:141]
	v_lshlrev_b32_e32 v140, 16, v134
	v_and_b32_e32 v141, 0xffff0000, v134
	v_max_f32_e32 v132, 0xda24260, v132
	v_pk_mul_f32 v[138:139], v[138:139], v[140:141]
	v_rcp_f32_e32 v140, v132
	v_max_f32_e32 v132, v145, v145
	v_max_f32_e32 v134, v143, v143
	v_lshlrev_b32_e32 v142, 16, v133
	v_and_b32_e32 v143, 0xffff0000, v133
	v_max_f32_e32 v133, v146, v146
	v_max_f32_e32 v132, 0xda24260, v132
	v_max_f32_e32 v133, 0xda24260, v133
	v_rcp_f32_e32 v132, v132
	v_rcp_f32_e32 v133, v133
	v_max_f32_e32 v134, 0xda24260, v134
	v_rcp_f32_e32 v141, v134
	v_lshlrev_b32_e32 v134, 16, v135
	v_and_b32_e32 v135, 0xffff0000, v135
	v_pk_mul_f32 v[132:133], v[132:133], v[134:135]
	v_pk_mul_f32 v[104:105], v[104:105], v[136:137]
	v_pk_mul_f32 v[102:103], v[102:103], v[132:133]
	v_add_u32_e32 v132, 48, v0
	v_mad_i64_i32 v[132:133], s[92:93], v132, s25, v[2:3]
	v_lshl_add_u64 v[132:133], v[132:133], 0, v[188:189]
	v_add_co_u32_e32 v134, vcc, s27, v132
	v_pk_mul_f32 v[160:161], v[160:161], v[162:163]
	s_nop 0
	v_addc_co_u32_e32 v135, vcc, 0, v133, vcc
	v_add_co_u32_e32 v136, vcc, s22, v132
	v_pk_mul_f32 v[140:141], v[140:141], v[142:143]
	s_nop 0
	v_addc_co_u32_e32 v137, vcc, 0, v133, vcc
	v_pk_mul_f32 v[114:115], v[114:115], v[160:161]
	v_pk_mul_f32 v[106:107], v[106:107], v[140:141]
	global_load_dwordx4 v[160:163], v[134:135], off
	global_load_dwordx4 v[210:213], v[136:137], off
	s_nop 0
	global_load_dwordx4 v[132:135], v[134:135], off offset:256
	s_nop 0
	global_load_dwordx4 v[140:143], v[136:137], off offset:256
	s_waitcnt lgkmcnt(0)
	s_waitcnt vmcnt(6)
	v_lshlrev_b32_e32 v136, 16, v196
	v_and_b32_e32 v137, 0xffff0000, v196
	v_pk_mul_f32 v[100:101], v[100:101], v[138:139]
	v_lshlrev_b32_e32 v138, 16, v198
	v_and_b32_e32 v139, 0xffff0000, v198
	v_max_f32_e32 v136, v136, v136
	v_max_f32_e32 v137, v137, v137
	v_max_f32_e32 v136, 0xda24260, v136
	v_max_f32_e32 v138, v138, v138
	v_max_f32_e32 v137, 0xda24260, v137
	v_max_f32_e32 v139, v139, v139
	v_rcp_f32_e32 v136, v136
	v_max_f32_e32 v138, 0xda24260, v138
	v_rcp_f32_e32 v137, v137
	v_max_f32_e32 v139, 0xda24260, v139
	v_rcp_f32_e32 v138, v138
	v_rcp_f32_e32 v139, v139
	v_lshlrev_b32_e32 v144, 16, v156
	v_and_b32_e32 v145, 0xffff0000, v156
	v_lshlrev_b32_e32 v181, 16, v199
	v_pk_mul_f32 v[136:137], v[136:137], v[144:145]
	v_lshlrev_b32_e32 v144, 16, v158
	v_and_b32_e32 v145, 0xffff0000, v158
	v_pk_mul_f32 v[138:139], v[138:139], v[144:145]
	v_max_f32_e32 v145, v181, v181
	v_lshlrev_b32_e32 v146, 16, v197
	v_and_b32_e32 v147, 0xffff0000, v197
	v_max_f32_e32 v145, 0xda24260, v145
	v_max_f32_e32 v144, v146, v146
	v_rcp_f32_e32 v146, v145
	v_max_f32_e32 v145, v147, v147
	v_max_f32_e32 v144, 0xda24260, v144
	v_max_f32_e32 v145, 0xda24260, v145
	v_pk_mul_f32 v[96:97], v[96:97], v[136:137]
	s_waitcnt vmcnt(4)
;     __device__ __forceinline__ void hook(f32x4 (&acc)[2][2][4][2], const Unit& u, int wr, int wc, int fr, int fq) const {
;     ...
;         for (int bj = 0; bj < 2; ++bj) { const bf16_t* gp = G + (size_t)row0 * ldg + col0 + bj * HALF; ga[0][bj] = *(const u32x4*)(gp + 6144); gb[0][bj] = *(const u32x4*)(gp + 8192); }
; #pragma unroll
;         for (int g = 0; g < 8; ++g) { const int ai = g >> 2, m = g & 3, cb = g & 1, nb_ = cb ^ 1;
;             if (g < 7) { const int an = (g + 1) >> 2, mn = (g + 1) & 3;
; #pragma unroll
;                 for (int bj = 0; bj < 2; ++bj) { const bf16_t* gp = G + (size_t)(row0 + an * HALF + mn * 16) * ldg + col0 + bj * HALF; ga[nb_][bj] = *(const u32x4*)(gp + 6144); gb[nb_][bj] = *(const u32x4*)(gp + 8192); } }
; #pragma unroll
;             for (int bj = 0; bj < 2; ++bj) { f32x4 a0, a1, b0, b1; unpack_bf16x8(ga[cb][bj], a0, a1); unpack_bf16x8(gb[cb][bj], b0, b1);
; #pragma unroll
;                 for (int j = 0; j < 4; ++j) { a0[j] = a0[j] * __builtin_amdgcn_rcpf(fmaxf(b0[j], 1e-30f)); a1[j] = a1[j] * __builtin_amdgcn_rcpf(fmaxf(b1[j], 1e-30f)); }
;                 acc[ai][bj][m][0] = acc[ai][bj][m][0] * a0; acc[ai][bj][m][1] = acc[ai][bj][m][1] * a1; }
	v_lshlrev_b32_e32 v136, 16, v152
	v_and_b32_e32 v137, 0xffff0000, v152
	v_and_b32_e32 v183, 0xffff0000, v199
	v_rcp_f32_e32 v144, v144
	v_rcp_f32_e32 v145, v145
	v_pk_mul_f32 v[92:93], v[92:93], v[138:139]
	v_lshlrev_b32_e32 v138, 16, v154
	v_and_b32_e32 v139, 0xffff0000, v154
	v_max_f32_e32 v136, v136, v136
	v_max_f32_e32 v137, v137, v137
	v_max_f32_e32 v147, v183, v183
	v_max_f32_e32 v136, 0xda24260, v136
	v_max_f32_e32 v138, v138, v138
	v_max_f32_e32 v137, 0xda24260, v137
	v_max_f32_e32 v139, v139, v139
	v_max_f32_e32 v147, 0xda24260, v147
	v_rcp_f32_e32 v136, v136
	v_max_f32_e32 v138, 0xda24260, v138
	v_rcp_f32_e32 v137, v137
	v_max_f32_e32 v139, 0xda24260, v139
	v_lshlrev_b32_e32 v156, 16, v157
	v_and_b32_e32 v157, 0xffff0000, v157
	v_rcp_f32_e32 v147, v147
	v_rcp_f32_e32 v138, v138
	v_rcp_f32_e32 v139, v139
	v_pk_mul_f32 v[144:145], v[144:145], v[156:157]
	v_lshlrev_b32_e32 v156, 16, v159
	v_pk_mul_f32 v[98:99], v[98:99], v[144:145]
	v_lshlrev_b32_e32 v144, 16, v148
	v_and_b32_e32 v145, 0xffff0000, v148
	v_and_b32_e32 v157, 0xffff0000, v159
	v_lshlrev_b32_e32 v152, 16, v155
	v_pk_mul_f32 v[136:137], v[136:137], v[144:145]
	v_lshlrev_b32_e32 v144, 16, v150
	v_and_b32_e32 v145, 0xffff0000, v150
	v_pk_mul_f32 v[146:147], v[146:147], v[156:157]
	v_pk_mul_f32 v[138:139], v[138:139], v[144:145]
	v_max_f32_e32 v145, v152, v152
	v_pk_mul_f32 v[94:95], v[94:95], v[146:147]
	v_lshlrev_b32_e32 v146, 16, v153
	v_and_b32_e32 v147, 0xffff0000, v153
	v_max_f32_e32 v145, 0xda24260, v145
	v_max_f32_e32 v144, v146, v146
	v_rcp_f32_e32 v146, v145
	v_max_f32_e32 v145, v147, v147
	v_and_b32_e32 v153, 0xffff0000, v155
	v_max_f32_e32 v144, 0xda24260, v144
	v_max_f32_e32 v145, 0xda24260, v145
	v_rcp_f32_e32 v144, v144
	v_rcp_f32_e32 v145, v145
	v_max_f32_e32 v147, v153, v153
	v_pk_mul_f32 v[88:89], v[88:89], v[136:137]
	v_add_u32_e32 v136, 0x80, v0
	v_max_f32_e32 v147, 0xda24260, v147
	v_mad_i64_i32 v[136:137], s[92:93], v136, s25, v[2:3]
	v_rcp_f32_e32 v147, v147
	v_lshl_add_u64 v[136:137], v[136:137], 0, v[188:189]
	v_lshlrev_b32_e32 v148, 16, v149
	v_and_b32_e32 v149, 0xffff0000, v149
	v_pk_mul_f32 v[84:85], v[84:85], v[138:139]
	v_add_co_u32_e32 v138, vcc, s27, v136
	v_pk_mul_f32 v[144:145], v[144:145], v[148:149]
	s_nop 0
	v_addc_co_u32_e32 v139, vcc, 0, v137, vcc
	v_lshlrev_b32_e32 v148, 16, v151
	v_and_b32_e32 v149, 0xffff0000, v151
	v_pk_mul_f32 v[90:91], v[90:91], v[144:145]
	v_add_co_u32_e32 v144, vcc, s22, v136
	v_pk_mul_f32 v[146:147], v[146:147], v[148:149]
	s_nop 0
	v_addc_co_u32_e32 v145, vcc, 0, v137, vcc
	v_pk_mul_f32 v[86:87], v[86:87], v[146:147]
	global_load_dwordx4 v[148:151], v[138:139], off
	global_load_dwordx4 v[156:159], v[144:145], off
	s_nop 0
	global_load_dwordx4 v[136:139], v[138:139], off offset:256
	s_nop 0
	global_load_dwordx4 v[144:147], v[144:145], off offset:256
	s_waitcnt vmcnt(6)
	v_lshlrev_b32_e32 v152, 16, v210
	v_and_b32_e32 v153, 0xffff0000, v210
	v_lshlrev_b32_e32 v154, 16, v212
	v_and_b32_e32 v155, 0xffff0000, v212
	v_max_f32_e32 v152, v152, v152
	v_max_f32_e32 v153, v153, v153
	v_max_f32_e32 v152, 0xda24260, v152
	v_max_f32_e32 v154, v154, v154
	v_max_f32_e32 v153, 0xda24260, v153
	v_max_f32_e32 v155, v155, v155
	v_rcp_f32_e32 v152, v152
	v_max_f32_e32 v154, 0xda24260, v154
	v_rcp_f32_e32 v153, v153
	v_max_f32_e32 v155, 0xda24260, v155
	v_rcp_f32_e32 v154, v154
	v_rcp_f32_e32 v155, v155
	v_lshlrev_b32_e32 v181, 16, v211
	v_lshlrev_b32_e32 v196, 16, v160
	v_and_b32_e32 v197, 0xffff0000, v160
	v_max_f32_e32 v160, v181, v181
	v_lshlrev_b32_e32 v195, 16, v213
	v_and_b32_e32 v200, 0xffff0000, v213
	v_pk_mul_f32 v[152:153], v[152:153], v[196:197]
	v_lshlrev_b32_e32 v196, 16, v162
	v_and_b32_e32 v197, 0xffff0000, v162
	v_max_f32_e32 v160, 0xda24260, v160
	v_pk_mul_f32 v[154:155], v[154:155], v[196:197]
	v_rcp_f32_e32 v196, v160
	v_max_f32_e32 v160, v195, v195
	v_lshlrev_b32_e32 v198, 16, v161
	v_and_b32_e32 v199, 0xffff0000, v161
	v_max_f32_e32 v161, v200, v200
	v_max_f32_e32 v160, 0xda24260, v160
	v_max_f32_e32 v161, 0xda24260, v161
	v_and_b32_e32 v183, 0xffff0000, v211
	v_rcp_f32_e32 v160, v160
	v_rcp_f32_e32 v161, v161
	v_max_f32_e32 v162, v183, v183
	v_max_f32_e32 v162, 0xda24260, v162
	v_pk_mul_f32 v[76:77], v[76:77], v[154:155]
	s_waitcnt vmcnt(4)
	v_lshlrev_b32_e32 v154, 16, v141
	v_and_b32_e32 v155, 0xffff0000, v141
	v_lshlrev_b32_e32 v141, 16, v142
	v_rcp_f32_e32 v197, v162
	v_lshlrev_b32_e32 v162, 16, v163
	v_and_b32_e32 v163, 0xffff0000, v163
	v_max_f32_e32 v141, v141, v141
	v_pk_mul_f32 v[160:161], v[160:161], v[162:163]
	v_pk_mul_f32 v[80:81], v[80:81], v[152:153]
	v_lshlrev_b32_e32 v152, 16, v140
	v_and_b32_e32 v153, 0xffff0000, v140
	v_max_f32_e32 v141, 0xda24260, v141
	v_pk_mul_f32 v[78:79], v[78:79], v[160:161]
	v_and_b32_e32 v160, 0xffff0000, v142
	v_max_f32_e32 v140, v152, v152
	v_rcp_f32_e32 v142, v141
	v_max_f32_e32 v141, v153, v153
	v_max_f32_e32 v140, 0xda24260, v140
	v_max_f32_e32 v141, 0xda24260, v141
	v_lshlrev_b32_e32 v152, 16, v132
	v_and_b32_e32 v153, 0xffff0000, v132
	v_max_f32_e32 v132, v160, v160
	v_rcp_f32_e32 v140, v140
	v_rcp_f32_e32 v141, v141
	v_max_f32_e32 v132, 0xda24260, v132
	v_lshlrev_b32_e32 v161, 16, v143
	v_and_b32_e32 v162, 0xffff0000, v143
	v_rcp_f32_e32 v143, v132
	v_max_f32_e32 v132, v154, v154
	v_pk_mul_f32 v[140:141], v[140:141], v[152:153]
	v_lshlrev_b32_e32 v152, 16, v134
	v_and_b32_e32 v153, 0xffff0000, v134
	v_max_f32_e32 v132, 0xda24260, v132
	v_pk_mul_f32 v[142:143], v[142:143], v[152:153]
	v_rcp_f32_e32 v152, v132
	v_max_f32_e32 v132, v161, v161
	v_max_f32_e32 v134, v155, v155
	v_lshlrev_b32_e32 v154, 16, v133
	v_and_b32_e32 v155, 0xffff0000, v133
	v_max_f32_e32 v133, v162, v162
	v_max_f32_e32 v132, 0xda24260, v132
	v_max_f32_e32 v133, 0xda24260, v133
	v_rcp_f32_e32 v132, v132
	v_rcp_f32_e32 v133, v133
	v_max_f32_e32 v134, 0xda24260, v134
	v_rcp_f32_e32 v153, v134
	v_lshlrev_b32_e32 v134, 16, v135
	v_and_b32_e32 v135, 0xffff0000, v135
	v_pk_mul_f32 v[132:133], v[132:133], v[134:135]
	v_pk_mul_f32 v[72:73], v[72:73], v[140:141]
	v_pk_mul_f32 v[70:71], v[70:71], v[132:133]
	v_add_u32_e32 v132, 0x90, v0
	v_mad_i64_i32 v[132:133], s[92:93], v132, s25, v[2:3]
	v_lshl_add_u64 v[132:133], v[132:133], 0, v[188:189]
	v_add_co_u32_e32 v134, vcc, s27, v132
	v_pk_mul_f32 v[152:153], v[152:153], v[154:155]
	s_nop 0
	v_addc_co_u32_e32 v135, vcc, 0, v133, vcc
	v_add_co_u32_e32 v140, vcc, s22, v132
	v_pk_mul_f32 v[74:75], v[74:75], v[152:153]
	s_nop 0
	v_addc_co_u32_e32 v141, vcc, 0, v133, vcc
	v_pk_mul_f32 v[68:69], v[68:69], v[142:143]
	global_load_dwordx4 v[152:155], v[134:135], off
	global_load_dwordx4 v[160:163], v[140:141], off
	s_nop 0
	global_load_dwordx4 v[132:135], v[134:135], off offset:256
	s_nop 0
	global_load_dwordx4 v[140:143], v[140:141], off offset:256
	v_pk_mul_f32 v[196:197], v[196:197], v[198:199]
	s_waitcnt lgkmcnt(0)
;     __device__ __forceinline__ void hook(f32x4 (&acc)[2][2][4][2], const Unit& u, int wr, int wc, int fr, int fq) const {
;     ...
;         for (int bj = 0; bj < 2; ++bj) { const bf16_t* gp = G + (size_t)row0 * ldg + col0 + bj * HALF; ga[0][bj] = *(const u32x4*)(gp + 6144); gb[0][bj] = *(const u32x4*)(gp + 8192); }
; #pragma unroll
;         for (int g = 0; g < 8; ++g) { const int ai = g >> 2, m = g & 3, cb = g & 1, nb_ = cb ^ 1;
;             if (g < 7) { const int an = (g + 1) >> 2, mn = (g + 1) & 3;
; #pragma unroll
;                 for (int bj = 0; bj < 2; ++bj) { const bf16_t* gp = G + (size_t)(row0 + an * HALF + mn * 16) * ldg + col0 + bj * HALF; ga[nb_][bj] = *(const u32x4*)(gp + 6144); gb[nb_][bj] = *(const u32x4*)(gp + 8192); } }
; #pragma unroll
;             for (int bj = 0; bj < 2; ++bj) { f32x4 a0, a1, b0, b1; unpack_bf16x8(ga[cb][bj], a0, a1); unpack_bf16x8(gb[cb][bj], b0, b1);
; #pragma unroll
;                 for (int j = 0; j < 4; ++j) { a0[j] = a0[j] * __builtin_amdgcn_rcpf(fmaxf(b0[j], 1e-30f)); a1[j] = a1[j] * __builtin_amdgcn_rcpf(fmaxf(b1[j], 1e-30f)); }
;                 acc[ai][bj][m][0] = acc[ai][bj][m][0] * a0; acc[ai][bj][m][1] = acc[ai][bj][m][1] * a1; }
	s_waitcnt vmcnt(6)
	v_lshlrev_b32_e32 v195, 16, v157
	v_and_b32_e32 v198, 0xffff0000, v157
	v_lshlrev_b32_e32 v157, 16, v158
	v_max_f32_e32 v157, v157, v157
	v_lshlrev_b32_e32 v181, 16, v156
	v_and_b32_e32 v183, 0xffff0000, v156
	v_max_f32_e32 v157, 0xda24260, v157
	v_and_b32_e32 v199, 0xffff0000, v158
	v_max_f32_e32 v156, v181, v181
	v_rcp_f32_e32 v158, v157
	v_max_f32_e32 v157, v183, v183
	v_pk_mul_f32 v[82:83], v[82:83], v[196:197]
	v_max_f32_e32 v156, 0xda24260, v156
	v_max_f32_e32 v157, 0xda24260, v157
	v_lshlrev_b32_e32 v196, 16, v148
	v_and_b32_e32 v197, 0xffff0000, v148
	v_max_f32_e32 v148, v199, v199
	v_rcp_f32_e32 v156, v156
	v_rcp_f32_e32 v157, v157
	v_max_f32_e32 v148, 0xda24260, v148
	v_lshlrev_b32_e32 v200, 16, v159
	v_and_b32_e32 v201, 0xffff0000, v159
	v_rcp_f32_e32 v159, v148
	v_max_f32_e32 v148, v195, v195
	v_pk_mul_f32 v[156:157], v[156:157], v[196:197]
	v_lshlrev_b32_e32 v196, 16, v150
	v_and_b32_e32 v197, 0xffff0000, v150
	v_max_f32_e32 v148, 0xda24260, v148
	v_pk_mul_f32 v[158:159], v[158:159], v[196:197]
	v_rcp_f32_e32 v196, v148
	v_max_f32_e32 v148, v200, v200
	v_max_f32_e32 v150, v198, v198
	v_lshlrev_b32_e32 v198, 16, v149
	v_and_b32_e32 v199, 0xffff0000, v149
	v_max_f32_e32 v149, v201, v201
	v_max_f32_e32 v148, 0xda24260, v148
	v_max_f32_e32 v149, 0xda24260, v149
	v_rcp_f32_e32 v148, v148
	v_rcp_f32_e32 v149, v149
	v_max_f32_e32 v150, 0xda24260, v150
	v_rcp_f32_e32 v197, v150
	v_lshlrev_b32_e32 v150, 16, v151
	v_and_b32_e32 v151, 0xffff0000, v151
	v_pk_mul_f32 v[148:149], v[148:149], v[150:151]
	s_waitcnt vmcnt(4)
	v_lshlrev_b32_e32 v150, 16, v145
	v_and_b32_e32 v151, 0xffff0000, v145
	v_lshlrev_b32_e32 v145, 16, v146
	v_max_f32_e32 v145, v145, v145
	v_pk_mul_f32 v[62:63], v[62:63], v[148:149]
	v_lshlrev_b32_e32 v148, 16, v144
	v_and_b32_e32 v149, 0xffff0000, v144
	v_max_f32_e32 v145, 0xda24260, v145
	v_pk_mul_f32 v[64:65], v[64:65], v[156:157]
	v_and_b32_e32 v156, 0xffff0000, v146
	v_max_f32_e32 v144, v148, v148
	v_rcp_f32_e32 v146, v145
	v_max_f32_e32 v145, v149, v149
	v_max_f32_e32 v144, 0xda24260, v144
	v_max_f32_e32 v145, 0xda24260, v145
	v_lshlrev_b32_e32 v148, 16, v136
	v_and_b32_e32 v149, 0xffff0000, v136
	v_max_f32_e32 v136, v156, v156
	v_rcp_f32_e32 v144, v144
	v_rcp_f32_e32 v145, v145
	v_max_f32_e32 v136, 0xda24260, v136
	v_pk_mul_f32 v[60:61], v[60:61], v[158:159]
	v_lshlrev_b32_e32 v157, 16, v147
	v_and_b32_e32 v158, 0xffff0000, v147
	v_rcp_f32_e32 v147, v136
	v_max_f32_e32 v136, v150, v150
	v_pk_mul_f32 v[144:145], v[144:145], v[148:149]
	v_lshlrev_b32_e32 v148, 16, v138
	v_and_b32_e32 v149, 0xffff0000, v138
	v_max_f32_e32 v136, 0xda24260, v136
	v_pk_mul_f32 v[146:147], v[146:147], v[148:149]
	v_rcp_f32_e32 v148, v136
	v_max_f32_e32 v136, v157, v157
	v_max_f32_e32 v138, v151, v151
	v_lshlrev_b32_e32 v150, 16, v137
	v_and_b32_e32 v151, 0xffff0000, v137
	v_max_f32_e32 v137, v158, v158
	v_max_f32_e32 v136, 0xda24260, v136
	v_max_f32_e32 v137, 0xda24260, v137
	v_rcp_f32_e32 v136, v136
	v_rcp_f32_e32 v137, v137
	v_max_f32_e32 v138, 0xda24260, v138
	v_rcp_f32_e32 v149, v138
	v_lshlrev_b32_e32 v138, 16, v139
	v_and_b32_e32 v139, 0xffff0000, v139
	v_pk_mul_f32 v[136:137], v[136:137], v[138:139]
	v_pk_mul_f32 v[56:57], v[56:57], v[144:145]
	v_pk_mul_f32 v[54:55], v[54:55], v[136:137]
	v_add_u32_e32 v136, 0xa0, v0
	v_mad_i64_i32 v[136:137], s[92:93], v136, s25, v[2:3]
	v_lshl_add_u64 v[136:137], v[136:137], 0, v[188:189]
	v_add_co_u32_e32 v138, vcc, s27, v136
	v_pk_mul_f32 v[148:149], v[148:149], v[150:151]
	s_nop 0
	v_addc_co_u32_e32 v139, vcc, 0, v137, vcc
	v_add_co_u32_e32 v144, vcc, s22, v136
	v_pk_mul_f32 v[58:59], v[58:59], v[148:149]
	s_nop 0
	v_addc_co_u32_e32 v145, vcc, 0, v137, vcc
	v_pk_mul_f32 v[52:53], v[52:53], v[146:147]
	global_load_dwordx4 v[148:151], v[138:139], off
	global_load_dwordx4 v[156:159], v[144:145], off
	s_nop 0
	global_load_dwordx4 v[136:139], v[138:139], off offset:256
	s_nop 0
	global_load_dwordx4 v[144:147], v[144:145], off offset:256
	v_pk_mul_f32 v[196:197], v[196:197], v[198:199]
	s_waitcnt vmcnt(6)
	v_lshlrev_b32_e32 v195, 16, v161
	v_and_b32_e32 v198, 0xffff0000, v161
	v_lshlrev_b32_e32 v161, 16, v162
	v_max_f32_e32 v161, v161, v161
	v_lshlrev_b32_e32 v181, 16, v160
	v_and_b32_e32 v183, 0xffff0000, v160
	v_max_f32_e32 v161, 0xda24260, v161
	v_and_b32_e32 v199, 0xffff0000, v162
	v_max_f32_e32 v160, v181, v181
	v_rcp_f32_e32 v162, v161
	v_max_f32_e32 v161, v183, v183
	v_pk_mul_f32 v[66:67], v[66:67], v[196:197]
	v_max_f32_e32 v160, 0xda24260, v160
	v_max_f32_e32 v161, 0xda24260, v161
	v_lshlrev_b32_e32 v196, 16, v152
	v_and_b32_e32 v197, 0xffff0000, v152
	v_max_f32_e32 v152, v199, v199
	v_rcp_f32_e32 v160, v160
	v_rcp_f32_e32 v161, v161
	v_max_f32_e32 v152, 0xda24260, v152
	v_lshlrev_b32_e32 v200, 16, v163
	v_and_b32_e32 v201, 0xffff0000, v163
	v_rcp_f32_e32 v163, v152
	v_max_f32_e32 v152, v195, v195
	v_pk_mul_f32 v[160:161], v[160:161], v[196:197]
	v_lshlrev_b32_e32 v196, 16, v154
	v_and_b32_e32 v197, 0xffff0000, v154
	v_max_f32_e32 v152, 0xda24260, v152
	v_pk_mul_f32 v[162:163], v[162:163], v[196:197]
	v_rcp_f32_e32 v196, v152
	v_max_f32_e32 v152, v200, v200
	v_max_f32_e32 v154, v198, v198
	v_lshlrev_b32_e32 v198, 16, v153
	v_and_b32_e32 v199, 0xffff0000, v153
	v_max_f32_e32 v153, v201, v201
	v_max_f32_e32 v152, 0xda24260, v152
	v_max_f32_e32 v153, 0xda24260, v153
	v_rcp_f32_e32 v152, v152
	v_rcp_f32_e32 v153, v153
	v_max_f32_e32 v154, 0xda24260, v154
	v_rcp_f32_e32 v197, v154
	v_lshlrev_b32_e32 v154, 16, v155
	v_and_b32_e32 v155, 0xffff0000, v155
	v_pk_mul_f32 v[152:153], v[152:153], v[154:155]
	s_waitcnt vmcnt(4)
;     __device__ __forceinline__ void hook(f32x4 (&acc)[2][2][4][2], const Unit& u, int wr, int wc, int fr, int fq) const {
;     ...
;         for (int bj = 0; bj < 2; ++bj) { const bf16_t* gp = G + (size_t)row0 * ldg + col0 + bj * HALF; ga[0][bj] = *(const u32x4*)(gp + 6144); gb[0][bj] = *(const u32x4*)(gp + 8192); }
; #pragma unroll
;         for (int g = 0; g < 8; ++g) { const int ai = g >> 2, m = g & 3, cb = g & 1, nb_ = cb ^ 1;
;             if (g < 7) { const int an = (g + 1) >> 2, mn = (g + 1) & 3;
; #pragma unroll
;                 for (int bj = 0; bj < 2; ++bj) { const bf16_t* gp = G + (size_t)(row0 + an * HALF + mn * 16) * ldg + col0 + bj * HALF; ga[nb_][bj] = *(const u32x4*)(gp + 6144); gb[nb_][bj] = *(const u32x4*)(gp + 8192); } }
; #pragma unroll
;             for (int bj = 0; bj < 2; ++bj) { f32x4 a0, a1, b0, b1; unpack_bf16x8(ga[cb][bj], a0, a1); unpack_bf16x8(gb[cb][bj], b0, b1);
; #pragma unroll
;                 for (int j = 0; j < 4; ++j) { a0[j] = a0[j] * __builtin_amdgcn_rcpf(fmaxf(b0[j], 1e-30f)); a1[j] = a1[j] * __builtin_amdgcn_rcpf(fmaxf(b1[j], 1e-30f)); }
;                 acc[ai][bj][m][0] = acc[ai][bj][m][0] * a0; acc[ai][bj][m][1] = acc[ai][bj][m][1] * a1; }
	v_lshlrev_b32_e32 v154, 16, v141
	v_and_b32_e32 v155, 0xffff0000, v141
	v_lshlrev_b32_e32 v141, 16, v142
	v_max_f32_e32 v141, v141, v141
	v_pk_mul_f32 v[46:47], v[46:47], v[152:153]
	v_lshlrev_b32_e32 v152, 16, v140
	v_and_b32_e32 v153, 0xffff0000, v140
	v_max_f32_e32 v141, 0xda24260, v141
	v_pk_mul_f32 v[48:49], v[48:49], v[160:161]
	v_and_b32_e32 v160, 0xffff0000, v142
	v_max_f32_e32 v140, v152, v152
	v_rcp_f32_e32 v142, v141
	v_max_f32_e32 v141, v153, v153
	v_max_f32_e32 v140, 0xda24260, v140
	v_max_f32_e32 v141, 0xda24260, v141
	v_lshlrev_b32_e32 v152, 16, v132
	v_and_b32_e32 v153, 0xffff0000, v132
	v_max_f32_e32 v132, v160, v160
	v_rcp_f32_e32 v140, v140
	v_rcp_f32_e32 v141, v141
	v_max_f32_e32 v132, 0xda24260, v132
	v_pk_mul_f32 v[44:45], v[44:45], v[162:163]
	v_lshlrev_b32_e32 v161, 16, v143
	v_and_b32_e32 v162, 0xffff0000, v143
	v_rcp_f32_e32 v143, v132
	v_max_f32_e32 v132, v154, v154
	v_pk_mul_f32 v[140:141], v[140:141], v[152:153]
	v_lshlrev_b32_e32 v152, 16, v134
	v_and_b32_e32 v153, 0xffff0000, v134
	v_max_f32_e32 v132, 0xda24260, v132
	v_pk_mul_f32 v[142:143], v[142:143], v[152:153]
	v_rcp_f32_e32 v152, v132
	v_max_f32_e32 v132, v161, v161
	v_max_f32_e32 v134, v155, v155
	v_lshlrev_b32_e32 v154, 16, v133
	v_and_b32_e32 v155, 0xffff0000, v133
	v_max_f32_e32 v133, v162, v162
	v_max_f32_e32 v132, 0xda24260, v132
	v_max_f32_e32 v133, 0xda24260, v133
	v_rcp_f32_e32 v132, v132
	v_rcp_f32_e32 v133, v133
	v_max_f32_e32 v134, 0xda24260, v134
	v_add_u32_e32 v0, 0xb0, v0
	v_rcp_f32_e32 v153, v134
	v_lshlrev_b32_e32 v134, 16, v135
	v_and_b32_e32 v135, 0xffff0000, v135
	v_mad_i64_i32 v[2:3], s[92:93], v0, s25, v[2:3]
	v_pk_mul_f32 v[132:133], v[132:133], v[134:135]
	v_lshl_add_u64 v[2:3], v[2:3], 0, v[188:189]
	v_pk_mul_f32 v[38:39], v[38:39], v[132:133]
	v_add_co_u32_e32 v132, vcc, s27, v2
	v_pk_mul_f32 v[152:153], v[152:153], v[154:155]
	s_nop 0
	v_addc_co_u32_e32 v133, vcc, 0, v3, vcc
	v_add_co_u32_e32 v2, vcc, s22, v2
	v_pk_mul_f32 v[42:43], v[42:43], v[152:153]
	s_nop 0
	v_addc_co_u32_e32 v3, vcc, 0, v3, vcc
	v_pk_mul_f32 v[40:41], v[40:41], v[140:141]
	v_pk_mul_f32 v[36:37], v[36:37], v[142:143]
	global_load_dwordx4 v[152:155], v[132:133], off
	global_load_dwordx4 v[160:163], v[2:3], off
	s_nop 0
	global_load_dwordx4 v[132:135], v[132:133], off offset:256
	s_nop 0
	global_load_dwordx4 v[140:143], v[2:3], off offset:256
	s_waitcnt lgkmcnt(0)
	s_waitcnt vmcnt(6)
	v_lshlrev_b32_e32 v0, 16, v156
	v_max_f32_e32 v0, v0, v0
	v_and_b32_e32 v3, 0xffff0000, v156
	v_lshlrev_b32_e32 v156, 16, v158
	v_max_f32_e32 v0, 0xda24260, v0
	v_rcp_f32_e32 v2, v0
	v_max_f32_e32 v0, v156, v156
	v_max_f32_e32 v0, 0xda24260, v0
	v_rcp_f32_e32 v156, v0
	v_max_f32_e32 v0, v3, v3
	v_lshlrev_b32_e32 v181, 16, v157
	v_and_b32_e32 v183, 0xffff0000, v157
	v_and_b32_e32 v157, 0xffff0000, v158
	v_max_f32_e32 v0, 0xda24260, v0
	v_rcp_f32_e32 v3, v0
	v_max_f32_e32 v0, v157, v157
	v_max_f32_e32 v0, 0xda24260, v0
	v_rcp_f32_e32 v157, v0
	v_lshlrev_b32_e32 v188, 16, v159
	v_and_b32_e32 v195, 0xffff0000, v159
	v_lshlrev_b32_e32 v158, 16, v148
	v_and_b32_e32 v159, 0xffff0000, v148
	v_max_f32_e32 v0, v181, v181
	v_pk_mul_f32 v[2:3], v[2:3], v[158:159]
	v_lshlrev_b32_e32 v158, 16, v150
	v_and_b32_e32 v159, 0xffff0000, v150
	v_max_f32_e32 v0, 0xda24260, v0
	v_pk_mul_f32 v[156:157], v[156:157], v[158:159]
	v_rcp_f32_e32 v158, v0
	v_max_f32_e32 v0, v188, v188
	v_max_f32_e32 v0, 0xda24260, v0
	v_rcp_f32_e32 v148, v0
	v_max_f32_e32 v0, v183, v183
	v_max_f32_e32 v0, 0xda24260, v0
	v_rcp_f32_e32 v159, v0
	v_max_f32_e32 v0, v195, v195
	v_max_f32_e32 v0, 0xda24260, v0
	v_lshlrev_b32_e32 v188, 16, v149
	v_and_b32_e32 v189, 0xffff0000, v149
	v_rcp_f32_e32 v149, v0
	s_waitcnt vmcnt(4)
	v_lshlrev_b32_e32 v0, 16, v144
	v_max_f32_e32 v0, v0, v0
	v_pk_mul_f32 v[32:33], v[32:33], v[2:3]
	v_and_b32_e32 v3, 0xffff0000, v144
	v_lshlrev_b32_e32 v144, 16, v146
	v_max_f32_e32 v0, 0xda24260, v0
	v_rcp_f32_e32 v2, v0
	v_max_f32_e32 v0, v144, v144
	v_lshlrev_b32_e32 v150, 16, v151
	v_and_b32_e32 v151, 0xffff0000, v151
	v_max_f32_e32 v0, 0xda24260, v0
	v_pk_mul_f32 v[148:149], v[148:149], v[150:151]
	v_rcp_f32_e32 v144, v0
	v_max_f32_e32 v0, v3, v3
	v_pk_mul_f32 v[30:31], v[30:31], v[148:149]
	v_lshlrev_b32_e32 v148, 16, v145
	v_and_b32_e32 v149, 0xffff0000, v145
	v_and_b32_e32 v145, 0xffff0000, v146
	v_max_f32_e32 v0, 0xda24260, v0
	v_rcp_f32_e32 v3, v0
	v_max_f32_e32 v0, v145, v145
	v_max_f32_e32 v0, 0xda24260, v0
	v_rcp_f32_e32 v145, v0
	v_lshlrev_b32_e32 v150, 16, v147
	v_and_b32_e32 v151, 0xffff0000, v147
	v_lshlrev_b32_e32 v146, 16, v136
	v_and_b32_e32 v147, 0xffff0000, v136
	v_max_f32_e32 v0, v148, v148
	v_pk_mul_f32 v[2:3], v[2:3], v[146:147]
	v_lshlrev_b32_e32 v146, 16, v138
	v_and_b32_e32 v147, 0xffff0000, v138
	v_max_f32_e32 v0, 0xda24260, v0
	v_pk_mul_f32 v[144:145], v[144:145], v[146:147]
	v_rcp_f32_e32 v146, v0
	v_max_f32_e32 v0, v150, v150
	v_max_f32_e32 v0, 0xda24260, v0
	v_rcp_f32_e32 v136, v0
	v_max_f32_e32 v0, v149, v149
	v_max_f32_e32 v0, 0xda24260, v0
	v_rcp_f32_e32 v147, v0
	v_max_f32_e32 v0, v151, v151
	v_max_f32_e32 v0, 0xda24260, v0
	v_lshlrev_b32_e32 v148, 16, v137
	v_and_b32_e32 v149, 0xffff0000, v137
	v_rcp_f32_e32 v137, v0
	v_lshlrev_b32_e32 v138, 16, v139
	v_and_b32_e32 v139, 0xffff0000, v139
	s_waitcnt vmcnt(2)
;     __device__ __forceinline__ void hook(f32x4 (&acc)[2][2][4][2], const Unit& u, int wr, int wc, int fr, int fq) const {
;     ...
;         for (int bj = 0; bj < 2; ++bj) { const bf16_t* gp = G + (size_t)row0 * ldg + col0 + bj * HALF; ga[0][bj] = *(const u32x4*)(gp + 6144); gb[0][bj] = *(const u32x4*)(gp + 8192); }
; #pragma unroll
;         for (int g = 0; g < 8; ++g) { const int ai = g >> 2, m = g & 3, cb = g & 1, nb_ = cb ^ 1;
;             if (g < 7) { const int an = (g + 1) >> 2, mn = (g + 1) & 3;
; #pragma unroll
;                 for (int bj = 0; bj < 2; ++bj) { const bf16_t* gp = G + (size_t)(row0 + an * HALF + mn * 16) * ldg + col0 + bj * HALF; ga[nb_][bj] = *(const u32x4*)(gp + 6144); gb[nb_][bj] = *(const u32x4*)(gp + 8192); } }
; #pragma unroll
;             for (int bj = 0; bj < 2; ++bj) { f32x4 a0, a1, b0, b1; unpack_bf16x8(ga[cb][bj], a0, a1); unpack_bf16x8(gb[cb][bj], b0, b1);
; #pragma unroll
;                 for (int j = 0; j < 4; ++j) { a0[j] = a0[j] * __builtin_amdgcn_rcpf(fmaxf(b0[j], 1e-30f)); a1[j] = a1[j] * __builtin_amdgcn_rcpf(fmaxf(b1[j], 1e-30f)); }
;                 acc[ai][bj][m][0] = acc[ai][bj][m][0] * a0; acc[ai][bj][m][1] = acc[ai][bj][m][1] * a1; }
	v_lshlrev_b32_e32 v0, 16, v160
	v_pk_mul_f32 v[136:137], v[136:137], v[138:139]
	v_max_f32_e32 v0, v0, v0
	v_pk_mul_f32 v[22:23], v[22:23], v[136:137]
	v_lshlrev_b32_e32 v136, 16, v162
	v_max_f32_e32 v0, 0xda24260, v0
	v_pk_mul_f32 v[24:25], v[24:25], v[2:3]
	v_rcp_f32_e32 v2, v0
	v_max_f32_e32 v0, v136, v136
	v_and_b32_e32 v3, 0xffff0000, v160
	v_max_f32_e32 v0, 0xda24260, v0
	v_rcp_f32_e32 v136, v0
	v_max_f32_e32 v0, v3, v3
	v_and_b32_e32 v137, 0xffff0000, v162
	v_max_f32_e32 v0, 0xda24260, v0
	v_rcp_f32_e32 v3, v0
	v_max_f32_e32 v0, v137, v137
	v_max_f32_e32 v0, 0xda24260, v0
	v_rcp_f32_e32 v137, v0
	v_pk_mul_f32 v[20:21], v[20:21], v[144:145]
	v_lshlrev_b32_e32 v144, 16, v161
	v_pk_mul_f32 v[146:147], v[146:147], v[148:149]
	v_lshlrev_b32_e32 v138, 16, v152
	v_and_b32_e32 v139, 0xffff0000, v152
	v_max_f32_e32 v0, v144, v144
	v_pk_mul_f32 v[26:27], v[26:27], v[146:147]
	v_lshlrev_b32_e32 v146, 16, v163
	v_pk_mul_f32 v[2:3], v[2:3], v[138:139]
	v_lshlrev_b32_e32 v138, 16, v154
	v_and_b32_e32 v139, 0xffff0000, v154
	v_max_f32_e32 v0, 0xda24260, v0
	v_pk_mul_f32 v[136:137], v[136:137], v[138:139]
	v_rcp_f32_e32 v138, v0
	v_max_f32_e32 v0, v146, v146
	v_and_b32_e32 v145, 0xffff0000, v161
	v_max_f32_e32 v0, 0xda24260, v0
	v_rcp_f32_e32 v144, v0
	v_max_f32_e32 v0, v145, v145
	v_and_b32_e32 v148, 0xffff0000, v163
	v_max_f32_e32 v0, 0xda24260, v0
	v_rcp_f32_e32 v139, v0
	v_max_f32_e32 v0, v148, v148
	v_max_f32_e32 v0, 0xda24260, v0
	v_rcp_f32_e32 v145, v0
	s_waitcnt vmcnt(0)
	v_lshlrev_b32_e32 v0, 16, v140
	v_max_f32_e32 v0, v0, v0
	v_pk_mul_f32 v[12:13], v[12:13], v[136:137]
	v_lshlrev_b32_e32 v136, 16, v142
	v_max_f32_e32 v0, 0xda24260, v0
	v_pk_mul_f32 v[16:17], v[16:17], v[2:3]
	v_rcp_f32_e32 v2, v0
	v_max_f32_e32 v0, v136, v136
	v_and_b32_e32 v3, 0xffff0000, v140
	v_max_f32_e32 v0, 0xda24260, v0
	v_rcp_f32_e32 v136, v0
	v_max_f32_e32 v0, v3, v3
	v_and_b32_e32 v137, 0xffff0000, v142
	v_max_f32_e32 v0, 0xda24260, v0
	v_rcp_f32_e32 v3, v0
	v_max_f32_e32 v0, v137, v137
	v_max_f32_e32 v0, 0xda24260, v0
	v_lshlrev_b32_e32 v146, 16, v153
	v_and_b32_e32 v147, 0xffff0000, v153
	v_rcp_f32_e32 v137, v0
	v_pk_mul_f32 v[138:139], v[138:139], v[146:147]
	v_lshlrev_b32_e32 v140, 16, v141
	v_pk_mul_f32 v[18:19], v[18:19], v[138:139]
	v_lshlrev_b32_e32 v138, 16, v132
	v_and_b32_e32 v139, 0xffff0000, v132
	v_max_f32_e32 v0, v140, v140
	v_lshlrev_b32_e32 v142, 16, v143
	v_pk_mul_f32 v[2:3], v[2:3], v[138:139]
	v_lshlrev_b32_e32 v138, 16, v134
	v_and_b32_e32 v139, 0xffff0000, v134
	v_max_f32_e32 v0, 0xda24260, v0
	v_pk_mul_f32 v[136:137], v[136:137], v[138:139]
	v_rcp_f32_e32 v138, v0
	v_max_f32_e32 v0, v142, v142
	v_and_b32_e32 v141, 0xffff0000, v141
	v_max_f32_e32 v0, 0xda24260, v0
	v_rcp_f32_e32 v132, v0
	v_max_f32_e32 v0, v141, v141
	v_and_b32_e32 v143, 0xffff0000, v143
	v_max_f32_e32 v0, 0xda24260, v0
	v_rcp_f32_e32 v139, v0
	v_max_f32_e32 v0, v143, v143
	v_max_f32_e32 v0, 0xda24260, v0
	v_lshlrev_b32_e32 v140, 16, v133
	v_and_b32_e32 v141, 0xffff0000, v133
	v_rcp_f32_e32 v133, v0
	v_lshlrev_b32_e32 v146, 16, v155
	v_and_b32_e32 v147, 0xffff0000, v155
	v_lshlrev_b32_e32 v134, 16, v135
	v_and_b32_e32 v135, 0xffff0000, v135
	v_pk_mul_f32 v[196:197], v[196:197], v[198:199]
	v_pk_mul_f32 v[158:159], v[158:159], v[188:189]
	v_pk_mul_f32 v[144:145], v[144:145], v[146:147]
	v_pk_mul_f32 v[138:139], v[138:139], v[140:141]
	v_pk_mul_f32 v[132:133], v[132:133], v[134:135]
	v_pk_mul_f32 v[50:51], v[50:51], v[196:197]
	v_pk_mul_f32 v[34:35], v[34:35], v[158:159]
	v_pk_mul_f32 v[28:29], v[28:29], v[156:157]
	v_pk_mul_f32 v[14:15], v[14:15], v[144:145]
	v_pk_mul_f32 v[10:11], v[10:11], v[138:139]
	v_pk_mul_f32 v[8:9], v[8:9], v[2:3]
	v_pk_mul_f32 v[6:7], v[6:7], v[132:133]
	v_pk_mul_f32 v[4:5], v[4:5], v[136:137]
	s_branch .LBB0_754

; __device__ __forceinline__ unsigned cvt_pk_bf16(float lo, float hi) { unsigned r; asm volatile("v_cvt_pk_bf16_f32 %0, %1, %2" : "=v"(r) : "v"(lo), "v"(hi)); return r; }
;     __device__ __forceinline__ void operator()(const f32x4 (&acc)[2][2][4][2], const Unit& u, int wr, int wc, int fr, int fq) const {
;     ...
;         if (raw) {
; #pragma unroll
;             for (int ai = 0; ai < 2; ++ai)
; #pragma unroll
;                 for (int m = 0; m < 4; ++m)
; #pragma unroll
;                     for (int bj = 0; bj < 2; ++bj) { const f32x4 v0 = acc[ai][bj][m][0], v1 = acc[ai][bj][m][1];
;                         u32x4 w; w.x = cvt_pk_bf16(v0[0], v0[1]); w.y = cvt_pk_bf16(v0[2], v0[3]); w.z = cvt_pk_bf16(v1[0], v1[1]); w.w = cvt_pk_bf16(v1[2], v1[3]);
;                         *(u32x4*)(O + (size_t)(row0 + ai * HALF + m * 16) * 2048 + col0 + bj * HALF) = w; }
;             return;
.LBB0_759:
	v_ashrrev_i32_e32 v181, 31, v180
	v_lshlrev_b64 v[2:3], 12, v[180:181]
	v_or_b32_e32 v142, 16, v180
	v_or_b32_e32 v140, 32, v180
	v_or_b32_e32 v138, 48, v180
	s_mov_b64 s[20:21], -1
	s_andn2_b64 vcc, exec, s[0:1]
	v_ashrrev_i32_e32 v183, 31, v182
	v_lshl_add_u64 v[144:145], s[18:19], 0, v[2:3]
	v_ashrrev_i32_e32 v143, 31, v142
	v_ashrrev_i32_e32 v141, 31, v140
	v_ashrrev_i32_e32 v139, 31, v138
	s_cbranch_vccnz .LBB0_762
	v_lshlrev_b64 v[136:137], 1, v[182:183]
	v_cvt_pk_bf16_f32 v132, v120, v121
	v_cvt_pk_bf16_f32 v133, v122, v123
	v_cvt_pk_bf16_f32 v134, v116, v117
	v_cvt_pk_bf16_f32 v135, v118, v119
	v_lshl_add_u64 v[2:3], v[144:145], 0, v[136:137]
	v_lshlrev_b64 v[146:147], 12, v[142:143]
	global_store_dwordx4 v[2:3], v[132:135], off
	v_lshl_add_u64 v[146:147], s[18:19], 0, v[146:147]
	v_lshl_add_u64 v[146:147], v[146:147], 0, v[136:137]
	v_cvt_pk_bf16_f32 v132, v128, v129
	v_cvt_pk_bf16_f32 v133, v130, v131
	v_cvt_pk_bf16_f32 v134, v124, v125
	v_cvt_pk_bf16_f32 v135, v126, v127
	global_store_dwordx4 v[2:3], v[132:135], off offset:256
	s_mov_b64 s[20:21], 0x80000
	s_nop 0
	v_cvt_pk_bf16_f32 v132, v112, v113
	v_cvt_pk_bf16_f32 v133, v114, v115
	v_cvt_pk_bf16_f32 v134, v108, v109
	v_cvt_pk_bf16_f32 v135, v110, v111
	global_store_dwordx4 v[146:147], v[132:135], off
	s_nop 1
	v_cvt_pk_bf16_f32 v132, v104, v105
	v_cvt_pk_bf16_f32 v133, v106, v107
	v_cvt_pk_bf16_f32 v134, v100, v101
	v_cvt_pk_bf16_f32 v135, v102, v103
	global_store_dwordx4 v[146:147], v[132:135], off offset:256
	v_lshlrev_b64 v[146:147], 12, v[140:141]
	v_lshl_add_u64 v[146:147], s[18:19], 0, v[146:147]
	v_cvt_pk_bf16_f32 v132, v96, v97
	v_cvt_pk_bf16_f32 v133, v98, v99
	v_cvt_pk_bf16_f32 v134, v92, v93
	v_cvt_pk_bf16_f32 v135, v94, v95
	v_lshl_add_u64 v[146:147], v[146:147], 0, v[136:137]
	global_store_dwordx4 v[146:147], v[132:135], off
	s_nop 1
	v_cvt_pk_bf16_f32 v132, v88, v89
	v_cvt_pk_bf16_f32 v133, v90, v91
	v_cvt_pk_bf16_f32 v134, v84, v85
	v_cvt_pk_bf16_f32 v135, v86, v87
	global_store_dwordx4 v[146:147], v[132:135], off offset:256
	v_lshlrev_b64 v[146:147], 12, v[138:139]
	v_lshl_add_u64 v[146:147], s[18:19], 0, v[146:147]
	v_cvt_pk_bf16_f32 v132, v80, v81
	v_cvt_pk_bf16_f32 v133, v82, v83
	v_cvt_pk_bf16_f32 v134, v76, v77
	v_cvt_pk_bf16_f32 v135, v78, v79
	v_lshl_add_u64 v[136:137], v[146:147], 0, v[136:137]
	global_store_dwordx4 v[136:137], v[132:135], off
	s_nop 1
	v_cvt_pk_bf16_f32 v132, v72, v73
	v_cvt_pk_bf16_f32 v133, v74, v75
	v_cvt_pk_bf16_f32 v134, v68, v69
	v_cvt_pk_bf16_f32 v135, v70, v71
	global_store_dwordx4 v[136:137], v[132:135], off offset:256
	v_lshl_add_u64 v[136:137], v[2:3], 0, s[20:21]
	s_mov_b32 s20, 0x80000
	v_add_co_u32_e32 v146, vcc, s20, v2
	v_cvt_pk_bf16_f32 v132, v64, v65
	v_cvt_pk_bf16_f32 v133, v66, v67
	v_cvt_pk_bf16_f32 v134, v60, v61
	v_cvt_pk_bf16_f32 v135, v62, v63
	s_nop 1
	v_addc_co_u32_e32 v147, vcc, 0, v3, vcc
	s_mov_b64 s[20:21], 0x90000
	global_store_dwordx4 v[146:147], v[132:135], off
	s_nop 1
	v_cvt_pk_bf16_f32 v132, v56, v57
	v_cvt_pk_bf16_f32 v133, v58, v59
	v_cvt_pk_bf16_f32 v134, v52, v53
	v_cvt_pk_bf16_f32 v135, v54, v55
	global_store_dwordx4 v[136:137], v[132:135], off offset:256
	v_lshl_add_u64 v[136:137], v[2:3], 0, s[20:21]
	s_mov_b32 s20, 0x90000
	v_add_co_u32_e32 v146, vcc, s20, v2
	v_cvt_pk_bf16_f32 v132, v48, v49
	v_cvt_pk_bf16_f32 v133, v50, v51
	v_cvt_pk_bf16_f32 v134, v44, v45
	v_cvt_pk_bf16_f32 v135, v46, v47
	s_nop 1
	v_addc_co_u32_e32 v147, vcc, 0, v3, vcc
	s_mov_b64 s[20:21], 0xa0000
	global_store_dwordx4 v[146:147], v[132:135], off
	s_nop 1
	v_cvt_pk_bf16_f32 v132, v40, v41
	v_cvt_pk_bf16_f32 v133, v42, v43
	v_cvt_pk_bf16_f32 v134, v36, v37
	v_cvt_pk_bf16_f32 v135, v38, v39
	global_store_dwordx4 v[136:137], v[132:135], off offset:256
	v_lshl_add_u64 v[136:137], v[2:3], 0, s[20:21]
	s_mov_b32 s20, 0xa0000
	v_add_co_u32_e32 v146, vcc, s20, v2
	v_cvt_pk_bf16_f32 v132, v32, v33
	v_cvt_pk_bf16_f32 v133, v34, v35
	v_cvt_pk_bf16_f32 v134, v28, v29
	v_cvt_pk_bf16_f32 v135, v30, v31
	s_nop 1
	v_addc_co_u32_e32 v147, vcc, 0, v3, vcc
	s_mov_b64 s[20:21], 0xb0000
	global_store_dwordx4 v[146:147], v[132:135], off
	s_nop 1
	v_cvt_pk_bf16_f32 v132, v24, v25
	v_cvt_pk_bf16_f32 v133, v26, v27
	v_cvt_pk_bf16_f32 v134, v20, v21
	v_cvt_pk_bf16_f32 v135, v22, v23
	global_store_dwordx4 v[136:137], v[132:135], off offset:256
	v_lshl_add_u64 v[136:137], v[2:3], 0, s[20:21]
	s_mov_b32 s20, 0xb0000
	v_add_co_u32_e32 v2, vcc, s20, v2
	v_cvt_pk_bf16_f32 v132, v16, v17
	v_cvt_pk_bf16_f32 v133, v18, v19
	v_cvt_pk_bf16_f32 v134, v12, v13
	v_cvt_pk_bf16_f32 v135, v14, v15
	s_nop 1
	v_addc_co_u32_e32 v3, vcc, 0, v3, vcc
	global_store_dwordx4 v[2:3], v[132:135], off
	s_nop 1
	v_cvt_pk_bf16_f32 v132, v8, v9
	v_cvt_pk_bf16_f32 v133, v10, v11
	v_cvt_pk_bf16_f32 v134, v4, v5
	v_cvt_pk_bf16_f32 v135, v6, v7
	global_store_dwordx4 v[136:137], v[132:135], off offset:256
	s_cbranch_execz .LBB0_763

; __device__ __forceinline__ unsigned cvt_pk_bf16(float lo, float hi) { unsigned r; asm volatile("v_cvt_pk_bf16_f32 %0, %1, %2" : "=v"(r) : "v"(lo), "v"(hi)); return r; }
;     __device__ __forceinline__ void operator()(const f32x4 (&acc)[2][2][4][2], const Unit& u, int wr, int wc, int fr, int fq) const {
;     ...
;         u32x4 gb[2][2];
; #pragma unroll
;         for (int bj = 0; bj < 2; ++bj) gb[0][bj] = *(const u32x4*)(G + (size_t)row0 * ldg + 8192 + col0 + bj * HALF);
; #pragma unroll
;         for (int g = 0; g < 8; ++g) { const int ai = g >> 2, m = g & 3, cb = g & 1, nb_ = cb ^ 1; const size_t row = (size_t)(row0 + ai * HALF + m * 16);
;             if (g < 7) { const int an = (g + 1) >> 2, mn = (g + 1) & 3;
; #pragma unroll
;                 for (int bj = 0; bj < 2; ++bj) gb[nb_][bj] = *(const u32x4*)(G + (size_t)(row0 + an * HALF + mn * 16) * ldg + 8192 + col0 + bj * HALF); }
; #pragma unroll
;             for (int bj = 0; bj < 2; ++bj) { f32x4 b0, b1; unpack_bf16x8(gb[cb][bj], b0, b1);
; #pragma unroll
;                 for (int j = 0; j < 4; ++j) { b0[j] = fmaxf(b0[j], 1e-30f); b1[j] = fmaxf(b1[j], 1e-30f); }
;                 const f32x4 v0 = acc[ai][bj][m][0] * b0, v1 = acc[ai][bj][m][1] * b1;
;                 u32x4 w; w.x = cvt_pk_bf16(v0[0], v0[1]); w.y = cvt_pk_bf16(v0[2], v0[3]); w.z = cvt_pk_bf16(v1[0], v1[1]); w.w = cvt_pk_bf16(v1[2], v1[3]);
;                 *(u32x4*)(O + row * 2048 + col0 + bj * HALF) = w; }
;             asm volatile("" ::: "memory"); }
.LBB0_763:
	v_mov_b64_e32 v[136:137], s[8:9]
	v_mad_i64_i32 v[132:133], s[20:21], v180, s25, v[136:137]
	v_lshlrev_b64 v[2:3], 1, v[182:183]
	v_lshl_add_u64 v[132:133], v[132:133], 0, v[2:3]
	s_mov_b64 s[44:45], 0x4000
	v_lshl_add_u64 v[134:135], v[132:133], 0, s[44:45]
	v_add_co_u32_e32 v132, vcc, 0x4000, v132
	v_mad_i64_i32 v[150:151], s[20:21], v142, s25, v[136:137]
	s_nop 0
	v_addc_co_u32_e32 v133, vcc, 0, v133, vcc
	v_lshl_add_u64 v[154:155], v[150:151], 0, v[2:3]
	v_add_co_u32_e32 v150, vcc, 0x4000, v154
	global_load_dwordx4 v[146:149], v[134:135], off offset:256
	s_nop 0
	v_addc_co_u32_e32 v151, vcc, 0, v155, vcc
	v_lshl_add_u64 v[154:155], v[154:155], 0, s[44:45]
	global_load_dwordx4 v[154:157], v[154:155], off offset:256
	v_lshl_add_u64 v[144:145], v[144:145], 0, v[2:3]
	global_load_dwordx4 v[132:135], v[132:133], off
	v_mad_i64_i32 v[158:159], s[20:21], v140, s25, v[136:137]
	global_load_dwordx4 v[150:153], v[150:151], off
	s_waitcnt lgkmcnt(0)
	s_waitcnt vmcnt(3)
	v_lshlrev_b32_e32 v0, 16, v146
	v_and_b32_e32 v146, 0xffff0000, v146
	v_lshlrev_b32_e32 v160, 16, v147
	v_and_b32_e32 v147, 0xffff0000, v147
	v_lshlrev_b32_e32 v161, 16, v148
	v_and_b32_e32 v148, 0xffff0000, v148
	v_lshlrev_b32_e32 v162, 16, v149
	v_and_b32_e32 v149, 0xffff0000, v149
	v_max_f32_e32 v0, v0, v0
	v_max_f32_e32 v161, v161, v161
	v_max_f32_e32 v146, v146, v146
	v_max_f32_e32 v148, v148, v148
	v_max_f32_e32 v160, v160, v160
	v_max_f32_e32 v162, v162, v162
	v_max_f32_e32 v147, v147, v147
	v_max_f32_e32 v149, v149, v149
	s_waitcnt vmcnt(1)
	v_lshlrev_b32_e32 v163, 16, v132
	v_and_b32_e32 v181, 0xffff0000, v132
	v_lshlrev_b32_e32 v182, 16, v133
	v_and_b32_e32 v183, 0xffff0000, v133
	v_lshlrev_b32_e32 v184, 16, v134
	v_and_b32_e32 v185, 0xffff0000, v134
	v_lshlrev_b32_e32 v186, 16, v135
	v_and_b32_e32 v187, 0xffff0000, v135
	v_max_f32_e32 v132, 0xda24260, v0
	v_max_f32_e32 v134, 0xda24260, v161
	v_max_f32_e32 v133, 0xda24260, v146
	v_max_f32_e32 v135, 0xda24260, v148
	v_max_f32_e32 v146, 0xda24260, v160
	v_max_f32_e32 v148, 0xda24260, v162
	v_max_f32_e32 v147, 0xda24260, v147
	v_max_f32_e32 v149, 0xda24260, v149
	v_max_f32_e32 v0, v163, v163
	v_max_f32_e32 v160, v184, v184
	v_max_f32_e32 v161, v181, v181
	v_max_f32_e32 v162, v185, v185
	v_max_f32_e32 v163, v182, v182
	v_max_f32_e32 v181, v186, v186
	v_max_f32_e32 v182, v183, v183
	v_max_f32_e32 v183, v187, v187
	v_pk_mul_f32 v[130:131], v[130:131], v[146:147]
	v_pk_mul_f32 v[128:129], v[128:129], v[132:133]
	v_pk_mul_f32 v[126:127], v[126:127], v[148:149]
	v_pk_mul_f32 v[124:125], v[124:125], v[134:135]
	v_max_f32_e32 v132, 0xda24260, v0
	v_max_f32_e32 v134, 0xda24260, v160
	v_max_f32_e32 v133, 0xda24260, v161
	v_max_f32_e32 v135, 0xda24260, v162
	v_max_f32_e32 v146, 0xda24260, v163
	v_max_f32_e32 v148, 0xda24260, v181
	v_max_f32_e32 v147, 0xda24260, v182
	v_max_f32_e32 v149, 0xda24260, v183
	v_pk_mul_f32 v[122:123], v[122:123], v[146:147]
	v_pk_mul_f32 v[120:121], v[120:121], v[132:133]
	v_pk_mul_f32 v[132:133], v[118:119], v[148:149]
	v_pk_mul_f32 v[118:119], v[116:117], v[134:135]
	v_cvt_pk_bf16_f32 v116, v120, v121
	v_cvt_pk_bf16_f32 v117, v122, v123
	s_waitcnt vmcnt(0)
	v_lshlrev_b32_e32 v0, 16, v150
	v_cvt_pk_bf16_f32 v118, v118, v119
	v_cvt_pk_bf16_f32 v119, v132, v133
	global_store_dwordx4 v[144:145], v[116:119], off
	v_max_f32_e32 v0, v0, v0
	v_lshlrev_b32_e32 v132, 16, v153
	v_cvt_pk_bf16_f32 v116, v128, v129
	v_cvt_pk_bf16_f32 v117, v130, v131
	v_lshlrev_b32_e32 v128, 16, v152
	v_cvt_pk_bf16_f32 v118, v124, v125
	v_cvt_pk_bf16_f32 v119, v126, v127
	global_store_dwordx4 v[144:145], v[116:119], off offset:256
	v_and_b32_e32 v127, 0xffff0000, v150
	v_max_f32_e32 v126, 0xda24260, v0
	v_lshl_add_u64 v[116:117], v[158:159], 0, v[2:3]
	v_max_f32_e32 v0, v128, v128
	v_lshl_add_u64 v[120:121], v[116:117], 0, s[44:45]
	v_add_co_u32_e32 v116, vcc, s22, v116
	v_and_b32_e32 v129, 0xffff0000, v152
	v_max_f32_e32 v128, 0xda24260, v0
	v_max_f32_e32 v0, v127, v127
	v_addc_co_u32_e32 v117, vcc, 0, v117, vcc
	v_lshlrev_b32_e32 v130, 16, v151
	v_max_f32_e32 v127, 0xda24260, v0
	v_max_f32_e32 v0, v129, v129
	global_load_dwordx4 v[116:119], v[116:117], off
	s_nop 0
	global_load_dwordx4 v[120:123], v[120:121], off offset:256
	v_max_f32_e32 v129, 0xda24260, v0
	v_max_f32_e32 v0, v130, v130
	v_and_b32_e32 v131, 0xffff0000, v151
	v_max_f32_e32 v130, 0xda24260, v0
	v_max_f32_e32 v0, v132, v132
	v_and_b32_e32 v133, 0xffff0000, v153
	v_max_f32_e32 v132, 0xda24260, v0
	v_max_f32_e32 v0, v131, v131
	v_max_f32_e32 v131, 0xda24260, v0
	v_max_f32_e32 v0, v133, v133
	v_lshlrev_b64 v[124:125], 12, v[142:143]
	v_max_f32_e32 v133, 0xda24260, v0
	v_pk_mul_f32 v[112:113], v[112:113], v[126:127]
	v_pk_mul_f32 v[126:127], v[110:111], v[132:133]
	v_pk_mul_f32 v[110:111], v[108:109], v[128:129]
	v_cvt_pk_bf16_f32 v108, v112, v113
	v_lshl_add_u64 v[112:113], s[18:19], 0, v[124:125]
	v_pk_mul_f32 v[114:115], v[114:115], v[130:131]
	v_lshl_add_u64 v[112:113], v[112:113], 0, v[2:3]
	v_cvt_pk_bf16_f32 v109, v114, v115
	v_cvt_pk_bf16_f32 v110, v110, v111
	v_lshlrev_b32_e32 v0, 16, v154
	v_cvt_pk_bf16_f32 v111, v126, v127
	global_store_dwordx4 v[112:113], v[108:111], off
	v_max_f32_e32 v0, v0, v0
	v_lshlrev_b32_e32 v114, 16, v155
	v_lshlrev_b32_e32 v110, 16, v156
	v_and_b32_e32 v109, 0xffff0000, v154
	v_max_f32_e32 v108, 0xda24260, v0
	v_max_f32_e32 v0, v110, v110
	v_and_b32_e32 v111, 0xffff0000, v156
	v_max_f32_e32 v110, 0xda24260, v0
	v_max_f32_e32 v0, v109, v109
	v_max_f32_e32 v109, 0xda24260, v0
	v_max_f32_e32 v0, v111, v111
	v_lshlrev_b32_e32 v124, 16, v157
	v_max_f32_e32 v111, 0xda24260, v0
	v_max_f32_e32 v0, v114, v114
	v_and_b32_e32 v115, 0xffff0000, v155
	v_max_f32_e32 v114, 0xda24260, v0
	v_max_f32_e32 v0, v124, v124
	v_and_b32_e32 v125, 0xffff0000, v157
	v_max_f32_e32 v124, 0xda24260, v0
	v_max_f32_e32 v0, v115, v115
	v_max_f32_e32 v115, 0xda24260, v0
	v_max_f32_e32 v0, v125, v125
	v_max_f32_e32 v125, 0xda24260, v0
	v_pk_mul_f32 v[106:107], v[106:107], v[114:115]
	v_pk_mul_f32 v[104:105], v[104:105], v[108:109]
	v_pk_mul_f32 v[108:109], v[102:103], v[124:125]
	v_pk_mul_f32 v[102:103], v[100:101], v[110:111]
	v_cvt_pk_bf16_f32 v100, v104, v105
	v_cvt_pk_bf16_f32 v101, v106, v107
	s_waitcnt lgkmcnt(0)
; __device__ __forceinline__ unsigned cvt_pk_bf16(float lo, float hi) { unsigned r; asm volatile("v_cvt_pk_bf16_f32 %0, %1, %2" : "=v"(r) : "v"(lo), "v"(hi)); return r; }
;     __device__ __forceinline__ void operator()(const f32x4 (&acc)[2][2][4][2], const Unit& u, int wr, int wc, int fr, int fq) const {
;     ...
;         u32x4 gb[2][2];
; #pragma unroll
;         for (int bj = 0; bj < 2; ++bj) gb[0][bj] = *(const u32x4*)(G + (size_t)row0 * ldg + 8192 + col0 + bj * HALF);
; #pragma unroll
;         for (int g = 0; g < 8; ++g) { const int ai = g >> 2, m = g & 3, cb = g & 1, nb_ = cb ^ 1; const size_t row = (size_t)(row0 + ai * HALF + m * 16);
;             if (g < 7) { const int an = (g + 1) >> 2, mn = (g + 1) & 3;
; #pragma unroll
;                 for (int bj = 0; bj < 2; ++bj) gb[nb_][bj] = *(const u32x4*)(G + (size_t)(row0 + an * HALF + mn * 16) * ldg + 8192 + col0 + bj * HALF); }
; #pragma unroll
;             for (int bj = 0; bj < 2; ++bj) { f32x4 b0, b1; unpack_bf16x8(gb[cb][bj], b0, b1);
; #pragma unroll
;                 for (int j = 0; j < 4; ++j) { b0[j] = fmaxf(b0[j], 1e-30f); b1[j] = fmaxf(b1[j], 1e-30f); }
;                 const f32x4 v0 = acc[ai][bj][m][0] * b0, v1 = acc[ai][bj][m][1] * b1;
;                 u32x4 w; w.x = cvt_pk_bf16(v0[0], v0[1]); w.y = cvt_pk_bf16(v0[2], v0[3]); w.z = cvt_pk_bf16(v1[0], v1[1]); w.w = cvt_pk_bf16(v1[2], v1[3]);
;                 *(u32x4*)(O + row * 2048 + col0 + bj * HALF) = w; }
;             asm volatile("" ::: "memory"); }
	s_waitcnt vmcnt(2)
	v_lshlrev_b32_e32 v0, 16, v116
	v_cvt_pk_bf16_f32 v102, v102, v103
	v_cvt_pk_bf16_f32 v103, v108, v109
	global_store_dwordx4 v[112:113], v[100:103], off offset:256
	v_lshlrev_b32_e32 v112, 16, v118
	v_max_f32_e32 v0, v0, v0
	v_mad_i64_i32 v[100:101], s[20:21], v138, s25, v[136:137]
	v_lshl_add_u64 v[100:101], v[100:101], 0, v[2:3]
	v_lshl_add_u64 v[104:105], v[100:101], 0, s[44:45]
	v_add_co_u32_e32 v100, vcc, s22, v100
	v_and_b32_e32 v111, 0xffff0000, v116
	s_nop 0
	v_addc_co_u32_e32 v101, vcc, 0, v101, vcc
	global_load_dwordx4 v[100:103], v[100:101], off
	s_nop 0
	global_load_dwordx4 v[104:107], v[104:105], off offset:256
	v_max_f32_e32 v110, 0xda24260, v0
	v_max_f32_e32 v0, v112, v112
	v_and_b32_e32 v113, 0xffff0000, v118
	v_max_f32_e32 v112, 0xda24260, v0
	v_max_f32_e32 v0, v111, v111
	v_lshlrev_b32_e32 v114, 16, v117
	v_max_f32_e32 v111, 0xda24260, v0
	v_max_f32_e32 v0, v113, v113
	v_lshlrev_b32_e32 v116, 16, v119
	v_max_f32_e32 v113, 0xda24260, v0
	v_max_f32_e32 v0, v114, v114
	v_and_b32_e32 v115, 0xffff0000, v117
	v_max_f32_e32 v114, 0xda24260, v0
	v_max_f32_e32 v0, v116, v116
	v_and_b32_e32 v117, 0xffff0000, v119
	v_max_f32_e32 v116, 0xda24260, v0
	v_max_f32_e32 v0, v115, v115
	v_max_f32_e32 v115, 0xda24260, v0
	v_max_f32_e32 v0, v117, v117
	v_lshlrev_b64 v[108:109], 12, v[140:141]
	v_max_f32_e32 v117, 0xda24260, v0
	v_pk_mul_f32 v[96:97], v[96:97], v[110:111]
	v_pk_mul_f32 v[110:111], v[94:95], v[116:117]
	v_pk_mul_f32 v[94:95], v[92:93], v[112:113]
	v_cvt_pk_bf16_f32 v92, v96, v97
	v_lshl_add_u64 v[96:97], s[18:19], 0, v[108:109]
	v_pk_mul_f32 v[98:99], v[98:99], v[114:115]
	v_lshl_add_u64 v[96:97], v[96:97], 0, v[2:3]
	v_cvt_pk_bf16_f32 v93, v98, v99
	v_cvt_pk_bf16_f32 v94, v94, v95
	s_waitcnt vmcnt(4)
	v_lshlrev_b32_e32 v0, 16, v120
	v_cvt_pk_bf16_f32 v95, v110, v111
	global_store_dwordx4 v[96:97], v[92:95], off
	v_max_f32_e32 v0, v0, v0
	v_lshlrev_b32_e32 v98, 16, v121
	v_lshlrev_b32_e32 v94, 16, v122
	v_and_b32_e32 v93, 0xffff0000, v120
	v_max_f32_e32 v92, 0xda24260, v0
	v_max_f32_e32 v0, v94, v94
	v_and_b32_e32 v95, 0xffff0000, v122
	v_max_f32_e32 v94, 0xda24260, v0
	v_max_f32_e32 v0, v93, v93
	v_max_f32_e32 v93, 0xda24260, v0
	v_max_f32_e32 v0, v95, v95
	v_lshlrev_b32_e32 v108, 16, v123
	v_max_f32_e32 v95, 0xda24260, v0
	v_max_f32_e32 v0, v98, v98
	v_and_b32_e32 v99, 0xffff0000, v121
	v_max_f32_e32 v98, 0xda24260, v0
	v_max_f32_e32 v0, v108, v108
	v_and_b32_e32 v109, 0xffff0000, v123
	v_max_f32_e32 v108, 0xda24260, v0
	v_max_f32_e32 v0, v99, v99
	v_max_f32_e32 v99, 0xda24260, v0
	v_max_f32_e32 v0, v109, v109
	v_max_f32_e32 v109, 0xda24260, v0
	v_pk_mul_f32 v[88:89], v[88:89], v[92:93]
	v_pk_mul_f32 v[92:93], v[86:87], v[108:109]
	v_pk_mul_f32 v[86:87], v[84:85], v[94:95]
	v_pk_mul_f32 v[90:91], v[90:91], v[98:99]
	v_cvt_pk_bf16_f32 v84, v88, v89
	v_lshlrev_b64 v[94:95], 12, v[138:139]
	v_cvt_pk_bf16_f32 v85, v90, v91
	v_cvt_pk_bf16_f32 v86, v86, v87
	v_cvt_pk_bf16_f32 v87, v92, v93
	v_add_u32_e32 v92, 0x80, v180
	global_store_dwordx4 v[96:97], v[84:87], off offset:256
	v_ashrrev_i32_e32 v93, 31, v92
	s_waitcnt lgkmcnt(0)
	s_waitcnt vmcnt(3)
	v_lshlrev_b32_e32 v0, 16, v100
	v_lshlrev_b32_e32 v98, 16, v102
	v_max_f32_e32 v0, v0, v0
	v_mad_i64_i32 v[84:85], s[20:21], v92, s25, v[136:137]
	v_and_b32_e32 v97, 0xffff0000, v100
	v_max_f32_e32 v96, 0xda24260, v0
	v_max_f32_e32 v0, v98, v98
	v_lshl_add_u64 v[84:85], v[84:85], 0, v[2:3]
	v_and_b32_e32 v99, 0xffff0000, v102
	v_max_f32_e32 v98, 0xda24260, v0
	v_max_f32_e32 v0, v97, v97
	v_lshl_add_u64 v[88:89], v[84:85], 0, s[44:45]
	v_add_co_u32_e32 v84, vcc, s22, v84
	v_lshlrev_b32_e32 v100, 16, v101
	v_max_f32_e32 v97, 0xda24260, v0
	v_max_f32_e32 v0, v99, v99
	v_addc_co_u32_e32 v85, vcc, 0, v85, vcc
	v_lshlrev_b32_e32 v102, 16, v103
	v_max_f32_e32 v99, 0xda24260, v0
	v_max_f32_e32 v0, v100, v100
	global_load_dwordx4 v[84:87], v[84:85], off
	s_nop 0
	global_load_dwordx4 v[88:91], v[88:89], off offset:256
	v_and_b32_e32 v101, 0xffff0000, v101
	v_max_f32_e32 v100, 0xda24260, v0
	v_max_f32_e32 v0, v102, v102
	v_and_b32_e32 v103, 0xffff0000, v103
	v_max_f32_e32 v102, 0xda24260, v0
	v_max_f32_e32 v0, v101, v101
	v_max_f32_e32 v101, 0xda24260, v0
	v_max_f32_e32 v0, v103, v103
	v_max_f32_e32 v103, 0xda24260, v0
	v_pk_mul_f32 v[80:81], v[80:81], v[96:97]
	v_pk_mul_f32 v[96:97], v[78:79], v[102:103]
	v_pk_mul_f32 v[78:79], v[76:77], v[98:99]
	v_cvt_pk_bf16_f32 v76, v80, v81
	v_lshl_add_u64 v[80:81], s[18:19], 0, v[94:95]
	v_pk_mul_f32 v[82:83], v[82:83], v[100:101]
	v_lshl_add_u64 v[80:81], v[80:81], 0, v[2:3]
	v_cvt_pk_bf16_f32 v77, v82, v83
	v_cvt_pk_bf16_f32 v78, v78, v79
	s_waitcnt vmcnt(4)
	v_lshlrev_b32_e32 v0, 16, v104
	v_cvt_pk_bf16_f32 v79, v96, v97
	global_store_dwordx4 v[80:81], v[76:79], off
	v_max_f32_e32 v0, v0, v0
	v_lshlrev_b32_e32 v82, 16, v105
	v_lshlrev_b32_e32 v78, 16, v106
	v_and_b32_e32 v77, 0xffff0000, v104
	v_max_f32_e32 v76, 0xda24260, v0
	v_max_f32_e32 v0, v78, v78
	v_and_b32_e32 v79, 0xffff0000, v106
	v_max_f32_e32 v78, 0xda24260, v0
	v_max_f32_e32 v0, v77, v77
	v_max_f32_e32 v77, 0xda24260, v0
	v_max_f32_e32 v0, v79, v79
	v_lshlrev_b32_e32 v94, 16, v107
	v_max_f32_e32 v79, 0xda24260, v0
	v_max_f32_e32 v0, v82, v82
	v_and_b32_e32 v83, 0xffff0000, v105
	v_max_f32_e32 v82, 0xda24260, v0
	v_max_f32_e32 v0, v94, v94
	v_and_b32_e32 v95, 0xffff0000, v107
	v_max_f32_e32 v94, 0xda24260, v0
	v_max_f32_e32 v0, v83, v83
	v_max_f32_e32 v83, 0xda24260, v0
	v_max_f32_e32 v0, v95, v95
	v_max_f32_e32 v95, 0xda24260, v0
	v_pk_mul_f32 v[72:73], v[72:73], v[76:77]
	v_pk_mul_f32 v[76:77], v[70:71], v[94:95]
	v_pk_mul_f32 v[70:71], v[68:69], v[78:79]
	v_pk_mul_f32 v[74:75], v[74:75], v[82:83]
	v_cvt_pk_bf16_f32 v68, v72, v73
	v_lshlrev_b64 v[78:79], 12, v[92:93]
	v_cvt_pk_bf16_f32 v69, v74, v75
	v_cvt_pk_bf16_f32 v70, v70, v71
	v_cvt_pk_bf16_f32 v71, v76, v77
	v_add_u32_e32 v76, 0x90, v180
	global_store_dwordx4 v[80:81], v[68:71], off offset:256
	v_ashrrev_i32_e32 v77, 31, v76
	s_waitcnt lgkmcnt(0)
; __device__ __forceinline__ unsigned cvt_pk_bf16(float lo, float hi) { unsigned r; asm volatile("v_cvt_pk_bf16_f32 %0, %1, %2" : "=v"(r) : "v"(lo), "v"(hi)); return r; }
;     __device__ __forceinline__ void operator()(const f32x4 (&acc)[2][2][4][2], const Unit& u, int wr, int wc, int fr, int fq) const {
;     ...
;         u32x4 gb[2][2];
; #pragma unroll
;         for (int bj = 0; bj < 2; ++bj) gb[0][bj] = *(const u32x4*)(G + (size_t)row0 * ldg + 8192 + col0 + bj * HALF);
; #pragma unroll
;         for (int g = 0; g < 8; ++g) { const int ai = g >> 2, m = g & 3, cb = g & 1, nb_ = cb ^ 1; const size_t row = (size_t)(row0 + ai * HALF + m * 16);
;             if (g < 7) { const int an = (g + 1) >> 2, mn = (g + 1) & 3;
; #pragma unroll
;                 for (int bj = 0; bj < 2; ++bj) gb[nb_][bj] = *(const u32x4*)(G + (size_t)(row0 + an * HALF + mn * 16) * ldg + 8192 + col0 + bj * HALF); }
; #pragma unroll
;             for (int bj = 0; bj < 2; ++bj) { f32x4 b0, b1; unpack_bf16x8(gb[cb][bj], b0, b1);
; #pragma unroll
;                 for (int j = 0; j < 4; ++j) { b0[j] = fmaxf(b0[j], 1e-30f); b1[j] = fmaxf(b1[j], 1e-30f); }
;                 const f32x4 v0 = acc[ai][bj][m][0] * b0, v1 = acc[ai][bj][m][1] * b1;
;                 u32x4 w; w.x = cvt_pk_bf16(v0[0], v0[1]); w.y = cvt_pk_bf16(v0[2], v0[3]); w.z = cvt_pk_bf16(v1[0], v1[1]); w.w = cvt_pk_bf16(v1[2], v1[3]);
;                 *(u32x4*)(O + row * 2048 + col0 + bj * HALF) = w; }
;             asm volatile("" ::: "memory"); }
	s_waitcnt vmcnt(3)
	v_lshlrev_b32_e32 v0, 16, v84
	v_mad_i64_i32 v[68:69], s[20:21], v76, s25, v[136:137]
	v_lshl_add_u64 v[68:69], v[68:69], 0, v[2:3]
	v_lshl_add_u64 v[72:73], v[68:69], 0, s[44:45]
	v_add_co_u32_e32 v68, vcc, s22, v68
	v_lshlrev_b32_e32 v82, 16, v86
	s_nop 0
	v_addc_co_u32_e32 v69, vcc, 0, v69, vcc
	global_load_dwordx4 v[68:71], v[68:69], off
	s_nop 0
	global_load_dwordx4 v[72:75], v[72:73], off offset:256
	v_max_f32_e32 v0, v0, v0
	v_and_b32_e32 v81, 0xffff0000, v84
	v_max_f32_e32 v80, 0xda24260, v0
	v_max_f32_e32 v0, v82, v82
	v_and_b32_e32 v83, 0xffff0000, v86
	v_max_f32_e32 v82, 0xda24260, v0
	v_max_f32_e32 v0, v81, v81
	v_lshlrev_b32_e32 v84, 16, v85
	v_max_f32_e32 v81, 0xda24260, v0
	v_max_f32_e32 v0, v83, v83
	v_lshlrev_b32_e32 v86, 16, v87
	v_max_f32_e32 v83, 0xda24260, v0
	v_max_f32_e32 v0, v84, v84
	v_and_b32_e32 v85, 0xffff0000, v85
	v_max_f32_e32 v84, 0xda24260, v0
	v_max_f32_e32 v0, v86, v86
	v_and_b32_e32 v87, 0xffff0000, v87
	v_max_f32_e32 v86, 0xda24260, v0
	v_max_f32_e32 v0, v85, v85
	v_max_f32_e32 v85, 0xda24260, v0
	v_max_f32_e32 v0, v87, v87
	v_max_f32_e32 v87, 0xda24260, v0
	v_pk_mul_f32 v[64:65], v[64:65], v[80:81]
	v_pk_mul_f32 v[80:81], v[62:63], v[86:87]
	v_pk_mul_f32 v[62:63], v[60:61], v[82:83]
	v_cvt_pk_bf16_f32 v60, v64, v65
	v_lshl_add_u64 v[64:65], s[18:19], 0, v[78:79]
	v_pk_mul_f32 v[66:67], v[66:67], v[84:85]
	v_lshl_add_u64 v[64:65], v[64:65], 0, v[2:3]
	v_cvt_pk_bf16_f32 v61, v66, v67
	v_cvt_pk_bf16_f32 v62, v62, v63
	s_waitcnt vmcnt(4)
	v_lshlrev_b32_e32 v0, 16, v88
	v_cvt_pk_bf16_f32 v63, v80, v81
	global_store_dwordx4 v[64:65], v[60:63], off
	v_max_f32_e32 v0, v0, v0
	v_lshlrev_b32_e32 v66, 16, v89
	v_lshlrev_b32_e32 v62, 16, v90
	v_and_b32_e32 v61, 0xffff0000, v88
	v_max_f32_e32 v60, 0xda24260, v0
	v_max_f32_e32 v0, v62, v62
	v_and_b32_e32 v63, 0xffff0000, v90
	v_max_f32_e32 v62, 0xda24260, v0
	v_max_f32_e32 v0, v61, v61
	v_max_f32_e32 v61, 0xda24260, v0
	v_max_f32_e32 v0, v63, v63
	v_lshlrev_b32_e32 v78, 16, v91
	v_max_f32_e32 v63, 0xda24260, v0
	v_max_f32_e32 v0, v66, v66
	v_and_b32_e32 v67, 0xffff0000, v89
	v_max_f32_e32 v66, 0xda24260, v0
	v_max_f32_e32 v0, v78, v78
	v_and_b32_e32 v79, 0xffff0000, v91
	v_max_f32_e32 v78, 0xda24260, v0
	v_max_f32_e32 v0, v67, v67
	v_max_f32_e32 v67, 0xda24260, v0
	v_max_f32_e32 v0, v79, v79
	v_max_f32_e32 v79, 0xda24260, v0
	v_pk_mul_f32 v[56:57], v[56:57], v[60:61]
	v_pk_mul_f32 v[60:61], v[54:55], v[78:79]
	v_pk_mul_f32 v[54:55], v[52:53], v[62:63]
	v_pk_mul_f32 v[58:59], v[58:59], v[66:67]
	v_cvt_pk_bf16_f32 v52, v56, v57
	v_lshlrev_b64 v[62:63], 12, v[76:77]
	v_cvt_pk_bf16_f32 v53, v58, v59
	v_cvt_pk_bf16_f32 v54, v54, v55
	v_cvt_pk_bf16_f32 v55, v60, v61
	global_store_dwordx4 v[64:65], v[52:55], off offset:256
	v_add_u32_e32 v60, 0xa0, v180
	s_waitcnt lgkmcnt(0)
	s_waitcnt vmcnt(3)
	v_lshlrev_b32_e32 v0, 16, v68
	v_lshlrev_b32_e32 v65, 16, v70
	v_max_f32_e32 v0, v0, v0
	v_and_b32_e32 v61, 0xffff0000, v68
	v_max_f32_e32 v64, 0xda24260, v0
	v_max_f32_e32 v0, v65, v65
	v_mad_i64_i32 v[52:53], s[20:21], v60, s25, v[136:137]
	v_and_b32_e32 v67, 0xffff0000, v70
	v_max_f32_e32 v66, 0xda24260, v0
	v_max_f32_e32 v0, v61, v61
	v_lshl_add_u64 v[52:53], v[52:53], 0, v[2:3]
	v_lshlrev_b32_e32 v68, 16, v69
	v_max_f32_e32 v65, 0xda24260, v0
	v_max_f32_e32 v0, v67, v67
	v_lshl_add_u64 v[56:57], v[52:53], 0, s[44:45]
	v_add_co_u32_e32 v52, vcc, s22, v52
	v_lshlrev_b32_e32 v70, 16, v71
	v_max_f32_e32 v67, 0xda24260, v0
	v_max_f32_e32 v0, v68, v68
	v_addc_co_u32_e32 v53, vcc, 0, v53, vcc
	v_and_b32_e32 v69, 0xffff0000, v69
	v_max_f32_e32 v68, 0xda24260, v0
	v_max_f32_e32 v0, v70, v70
	global_load_dwordx4 v[52:55], v[52:53], off
	s_nop 0
	global_load_dwordx4 v[56:59], v[56:57], off offset:256
	v_and_b32_e32 v71, 0xffff0000, v71
	v_max_f32_e32 v70, 0xda24260, v0
	v_max_f32_e32 v0, v69, v69
	v_max_f32_e32 v69, 0xda24260, v0
	v_max_f32_e32 v0, v71, v71
	v_max_f32_e32 v71, 0xda24260, v0
	v_pk_mul_f32 v[48:49], v[48:49], v[64:65]
	v_pk_mul_f32 v[64:65], v[46:47], v[70:71]
	v_pk_mul_f32 v[46:47], v[44:45], v[66:67]
	v_cvt_pk_bf16_f32 v44, v48, v49
	v_lshl_add_u64 v[48:49], s[18:19], 0, v[62:63]
	v_pk_mul_f32 v[50:51], v[50:51], v[68:69]
	v_lshl_add_u64 v[48:49], v[48:49], 0, v[2:3]
	v_cvt_pk_bf16_f32 v45, v50, v51
	v_cvt_pk_bf16_f32 v46, v46, v47
	s_waitcnt vmcnt(4)
	v_lshlrev_b32_e32 v0, 16, v72
	v_cvt_pk_bf16_f32 v47, v64, v65
	global_store_dwordx4 v[48:49], v[44:47], off
	v_max_f32_e32 v0, v0, v0
	v_lshlrev_b32_e32 v50, 16, v73
	v_lshlrev_b32_e32 v46, 16, v74
	v_and_b32_e32 v45, 0xffff0000, v72
	v_max_f32_e32 v44, 0xda24260, v0
	v_max_f32_e32 v0, v46, v46
	v_and_b32_e32 v47, 0xffff0000, v74
	v_max_f32_e32 v46, 0xda24260, v0
	v_max_f32_e32 v0, v45, v45
	v_max_f32_e32 v45, 0xda24260, v0
	v_max_f32_e32 v0, v47, v47
	v_lshlrev_b32_e32 v61, 16, v75
	v_max_f32_e32 v47, 0xda24260, v0
	v_max_f32_e32 v0, v50, v50
	v_and_b32_e32 v51, 0xffff0000, v73
	v_max_f32_e32 v50, 0xda24260, v0
	v_max_f32_e32 v0, v61, v61
	v_and_b32_e32 v63, 0xffff0000, v75
	v_max_f32_e32 v62, 0xda24260, v0
	v_max_f32_e32 v0, v51, v51
	v_max_f32_e32 v51, 0xda24260, v0
	v_max_f32_e32 v0, v63, v63
	v_max_f32_e32 v63, 0xda24260, v0
	v_pk_mul_f32 v[40:41], v[40:41], v[44:45]
	v_pk_mul_f32 v[44:45], v[38:39], v[62:63]
	v_pk_mul_f32 v[38:39], v[36:37], v[46:47]
	v_pk_mul_f32 v[42:43], v[42:43], v[50:51]
	v_cvt_pk_bf16_f32 v36, v40, v41
	v_ashrrev_i32_e32 v61, 31, v60
	v_cvt_pk_bf16_f32 v37, v42, v43
	v_cvt_pk_bf16_f32 v38, v38, v39
	v_cvt_pk_bf16_f32 v39, v44, v45
	v_add_u32_e32 v44, 0xb0, v180
	global_store_dwordx4 v[48:49], v[36:39], off offset:256
	v_lshlrev_b64 v[46:47], 12, v[60:61]
	v_ashrrev_i32_e32 v45, 31, v44
	v_mad_i64_i32 v[36:37], s[20:21], v44, s25, v[136:137]
	v_lshl_add_u64 v[40:41], v[36:37], 0, v[2:3]
	v_add_co_u32_e32 v36, vcc, s22, v40
	s_waitcnt lgkmcnt(0)
; __device__ __forceinline__ unsigned cvt_pk_bf16(float lo, float hi) { unsigned r; asm volatile("v_cvt_pk_bf16_f32 %0, %1, %2" : "=v"(r) : "v"(lo), "v"(hi)); return r; }
;     __device__ __forceinline__ void operator()(const f32x4 (&acc)[2][2][4][2], const Unit& u, int wr, int wc, int fr, int fq) const {
;     ...
;         u32x4 gb[2][2];
; #pragma unroll
;         for (int bj = 0; bj < 2; ++bj) gb[0][bj] = *(const u32x4*)(G + (size_t)row0 * ldg + 8192 + col0 + bj * HALF);
; #pragma unroll
;         for (int g = 0; g < 8; ++g) { const int ai = g >> 2, m = g & 3, cb = g & 1, nb_ = cb ^ 1; const size_t row = (size_t)(row0 + ai * HALF + m * 16);
;             if (g < 7) { const int an = (g + 1) >> 2, mn = (g + 1) & 3;
; #pragma unroll
;                 for (int bj = 0; bj < 2; ++bj) gb[nb_][bj] = *(const u32x4*)(G + (size_t)(row0 + an * HALF + mn * 16) * ldg + 8192 + col0 + bj * HALF); }
; #pragma unroll
;             for (int bj = 0; bj < 2; ++bj) { f32x4 b0, b1; unpack_bf16x8(gb[cb][bj], b0, b1);
; #pragma unroll
;                 for (int j = 0; j < 4; ++j) { b0[j] = fmaxf(b0[j], 1e-30f); b1[j] = fmaxf(b1[j], 1e-30f); }
;                 const f32x4 v0 = acc[ai][bj][m][0] * b0, v1 = acc[ai][bj][m][1] * b1;
;                 u32x4 w; w.x = cvt_pk_bf16(v0[0], v0[1]); w.y = cvt_pk_bf16(v0[2], v0[3]); w.z = cvt_pk_bf16(v1[0], v1[1]); w.w = cvt_pk_bf16(v1[2], v1[3]);
;                 *(u32x4*)(O + row * 2048 + col0 + bj * HALF) = w; }
;             asm volatile("" ::: "memory"); }
	s_waitcnt vmcnt(3)
	v_lshlrev_b32_e32 v0, 16, v52
	v_addc_co_u32_e32 v37, vcc, 0, v41, vcc
	global_load_dwordx4 v[36:39], v[36:37], off
	v_lshl_add_u64 v[40:41], v[40:41], 0, s[44:45]
	global_load_dwordx4 v[40:43], v[40:41], off offset:256
	v_lshlrev_b32_e32 v50, 16, v54
	v_max_f32_e32 v0, v0, v0
	v_and_b32_e32 v49, 0xffff0000, v52
	v_max_f32_e32 v48, 0xda24260, v0
	v_max_f32_e32 v0, v50, v50
	v_and_b32_e32 v51, 0xffff0000, v54
	v_max_f32_e32 v50, 0xda24260, v0
	v_max_f32_e32 v0, v49, v49
	v_lshlrev_b32_e32 v52, 16, v53
	v_max_f32_e32 v49, 0xda24260, v0
	v_max_f32_e32 v0, v51, v51
	v_lshlrev_b32_e32 v54, 16, v55
	v_max_f32_e32 v51, 0xda24260, v0
	v_max_f32_e32 v0, v52, v52
	v_and_b32_e32 v53, 0xffff0000, v53
	v_max_f32_e32 v52, 0xda24260, v0
	v_max_f32_e32 v0, v54, v54
	v_and_b32_e32 v55, 0xffff0000, v55
	v_max_f32_e32 v54, 0xda24260, v0
	v_max_f32_e32 v0, v53, v53
	v_max_f32_e32 v53, 0xda24260, v0
	v_max_f32_e32 v0, v55, v55
	v_max_f32_e32 v55, 0xda24260, v0
	v_pk_mul_f32 v[32:33], v[32:33], v[48:49]
	v_pk_mul_f32 v[48:49], v[30:31], v[54:55]
	v_pk_mul_f32 v[30:31], v[28:29], v[50:51]
	v_cvt_pk_bf16_f32 v28, v32, v33
	v_lshl_add_u64 v[32:33], s[18:19], 0, v[46:47]
	v_pk_mul_f32 v[34:35], v[34:35], v[52:53]
	v_lshl_add_u64 v[32:33], v[32:33], 0, v[2:3]
	v_cvt_pk_bf16_f32 v29, v34, v35
	v_cvt_pk_bf16_f32 v30, v30, v31
	s_waitcnt vmcnt(4)
	v_lshlrev_b32_e32 v0, 16, v56
	v_cvt_pk_bf16_f32 v31, v48, v49
	global_store_dwordx4 v[32:33], v[28:31], off
	v_max_f32_e32 v0, v0, v0
	v_lshlrev_b32_e32 v34, 16, v57
	v_lshlrev_b32_e32 v30, 16, v58
	v_and_b32_e32 v29, 0xffff0000, v56
	v_max_f32_e32 v28, 0xda24260, v0
	v_max_f32_e32 v0, v30, v30
	v_and_b32_e32 v31, 0xffff0000, v58
	v_max_f32_e32 v30, 0xda24260, v0
	v_max_f32_e32 v0, v29, v29
	v_max_f32_e32 v29, 0xda24260, v0
	v_max_f32_e32 v0, v31, v31
	v_lshlrev_b32_e32 v46, 16, v59
	v_max_f32_e32 v31, 0xda24260, v0
	v_max_f32_e32 v0, v34, v34
	v_and_b32_e32 v35, 0xffff0000, v57
	v_max_f32_e32 v34, 0xda24260, v0
	v_max_f32_e32 v0, v46, v46
	v_and_b32_e32 v47, 0xffff0000, v59
	v_max_f32_e32 v46, 0xda24260, v0
	v_max_f32_e32 v0, v35, v35
	v_max_f32_e32 v35, 0xda24260, v0
	v_max_f32_e32 v0, v47, v47
	v_max_f32_e32 v47, 0xda24260, v0
	v_pk_mul_f32 v[24:25], v[24:25], v[28:29]
	v_pk_mul_f32 v[28:29], v[22:23], v[46:47]
	v_pk_mul_f32 v[22:23], v[20:21], v[30:31]
	v_pk_mul_f32 v[26:27], v[26:27], v[34:35]
	v_cvt_pk_bf16_f32 v20, v24, v25
	s_waitcnt lgkmcnt(0)
	s_waitcnt vmcnt(2)
	v_lshlrev_b32_e32 v0, 16, v36
	v_cvt_pk_bf16_f32 v21, v26, v27
	v_cvt_pk_bf16_f32 v22, v22, v23
	v_cvt_pk_bf16_f32 v23, v28, v29
	v_lshlrev_b32_e32 v24, 16, v38
	v_max_f32_e32 v0, v0, v0
	global_store_dwordx4 v[32:33], v[20:23], off offset:256
	v_and_b32_e32 v25, 0xffff0000, v38
	v_lshlrev_b32_e32 v26, 16, v37
	v_and_b32_e32 v23, 0xffff0000, v36
	v_max_f32_e32 v22, 0xda24260, v0
	v_max_f32_e32 v0, v24, v24
	v_max_f32_e32 v24, 0xda24260, v0
	v_max_f32_e32 v0, v23, v23
	v_max_f32_e32 v23, 0xda24260, v0
	v_max_f32_e32 v0, v25, v25
	v_lshlrev_b32_e32 v28, 16, v39
	v_max_f32_e32 v25, 0xda24260, v0
	v_max_f32_e32 v0, v26, v26
	v_and_b32_e32 v27, 0xffff0000, v37
	v_max_f32_e32 v26, 0xda24260, v0
	v_max_f32_e32 v0, v28, v28
	v_and_b32_e32 v29, 0xffff0000, v39
	v_max_f32_e32 v28, 0xda24260, v0
	v_max_f32_e32 v0, v27, v27
	v_max_f32_e32 v27, 0xda24260, v0
	v_max_f32_e32 v0, v29, v29
	v_lshlrev_b64 v[20:21], 12, v[44:45]
	v_max_f32_e32 v29, 0xda24260, v0
	v_pk_mul_f32 v[16:17], v[16:17], v[22:23]
	v_pk_mul_f32 v[22:23], v[14:15], v[28:29]
	v_pk_mul_f32 v[14:15], v[12:13], v[24:25]
	v_cvt_pk_bf16_f32 v12, v16, v17
	v_lshl_add_u64 v[16:17], s[18:19], 0, v[20:21]
	v_lshl_add_u64 v[16:17], v[16:17], 0, v[2:3]
	s_waitcnt vmcnt(2)
	v_lshlrev_b32_e32 v0, 16, v40
	v_pk_mul_f32 v[18:19], v[18:19], v[26:27]
	v_max_f32_e32 v0, v0, v0
	v_cvt_pk_bf16_f32 v13, v18, v19
	v_cvt_pk_bf16_f32 v14, v14, v15
	v_cvt_pk_bf16_f32 v15, v22, v23
	global_store_dwordx4 v[16:17], v[12:15], off
	v_and_b32_e32 v3, 0xffff0000, v40
	v_max_f32_e32 v2, 0xda24260, v0
	v_lshlrev_b32_e32 v12, 16, v42
	v_max_f32_e32 v0, v12, v12
	v_and_b32_e32 v13, 0xffff0000, v42
	v_max_f32_e32 v12, 0xda24260, v0
	v_max_f32_e32 v0, v3, v3
	v_lshlrev_b32_e32 v14, 16, v41
	v_max_f32_e32 v3, 0xda24260, v0
	v_max_f32_e32 v0, v13, v13
	v_lshlrev_b32_e32 v18, 16, v43
	v_max_f32_e32 v13, 0xda24260, v0
	v_max_f32_e32 v0, v14, v14
	v_and_b32_e32 v15, 0xffff0000, v41
	v_max_f32_e32 v14, 0xda24260, v0
	v_max_f32_e32 v0, v18, v18
	v_and_b32_e32 v19, 0xffff0000, v43
	v_max_f32_e32 v18, 0xda24260, v0
	v_max_f32_e32 v0, v15, v15
	v_max_f32_e32 v15, 0xda24260, v0
	v_max_f32_e32 v0, v19, v19
	v_max_f32_e32 v19, 0xda24260, v0
	v_pk_mul_f32 v[2:3], v[8:9], v[2:3]
	v_pk_mul_f32 v[4:5], v[4:5], v[12:13]
	v_pk_mul_f32 v[10:11], v[10:11], v[14:15]
	v_pk_mul_f32 v[6:7], v[6:7], v[18:19]
	v_cvt_pk_bf16_f32 v2, v2, v3
	v_cvt_pk_bf16_f32 v3, v10, v11
	v_cvt_pk_bf16_f32 v4, v4, v5
	s_nop 0
	v_cvt_pk_bf16_f32 v5, v6, v7
	global_store_dwordx4 v[16:17], v[2:5], off offset:256
	s_cmp_eq_u32 s37, s3
	s_mov_b64 s[20:21], -1
	s_cbranch_scc1 .LBB0_748

; #define PG8_STAGE(bufoff, gbase, voff) do { _Pragma("unroll") for (int _i = 0; _i < 2; ++_i) \
;         __builtin_amdgcn_global_load_lds((const unsigned*)((const char*)(gbase) + (voff)[_i]), (PG8_LAS unsigned*)(lds + (bufoff) + ldsw + _i * 8192), 16, 0, 0); } while (0)
; #define PG8_WAIT_V(n) asm volatile("s_waitcnt vmcnt(" #n ")" ::: "memory")
; #define PG8_BAR __builtin_amdgcn_s_barrier()
; template <class Epi, class Sched, bool ALIGN_EPI = false, bool SP2 = false>
; __device__ __forceinline__ void gemm_phase(PG8_LAS unsigned char* lds, const Gemm g, const Sched& S, const Epi& E) {
;     ...
;     for (int i = 0; i < 2; ++i) { int R, C; stage_rc(tid * 16 + i * 8192, R, C); const int Rb = Epi::PERM ? ((R & ~31) + perm32(R & 31)) : R;
;         voffA[i] = (unsigned)(R * K + C) * 2u; voffB[i] = (unsigned)(Rb * K + C) * 2u; }
;     const size_t kstep = (size_t)(BK * 2);
;     const size_t hstep = (size_t)HALF * K * 2;
;     const size_t tstep = 2 * hstep;
;     const unsigned ldsw = (unsigned)wid * 1024u;
;     const int aoff = lds_byte(wr * 64 + fr, fq * 8), boff = lds_byte(wc * 32 + fr, fq * 8);
;     ...
;     const char* cA = (const char*)g.A + (size_t)cur.pm * tstep; const char* cB = (const char*)g.Bt + (size_t)cur.pn * tstep;
;     S.a_ready(cur);
;     if constexpr (SP2) {
;         PG8_STAGE(PG8_SB(0, 0), cB, voffB); PG8_STAGE(PG8_SB(0, 1), cB + hstep, voffB); PG8_STAGE(PG8_SA(0, 0), cA, voffA); PG8_STAGE(PG8_SA(0, 1), cA + hstep, voffA);
;         if (wr == 1) PG8_BAR;
;         PG8_WAIT_V(2); PG8_BAR;
;         PG8_STAGE(PG8_SB(1, 0), cB + kstep, voffB); PG8_STAGE(PG8_SA(1, 0), cA + kstep, voffA); PG8_STAGE(PG8_SB(1, 1), cB + hstep + kstep, voffB);
;         PG8_WAIT_V(6); PG8_BAR;
;     } else {
.LBB0_767:
	s_cmp_eq_u32 s35, 0
	s_cbranch_scc1 .LBB0_782
	v_mov_b32_e32 v16, v193
	s_cmp_lt_i32 s35, 1
	v_readfirstlane_b32 s14, v16
	s_cbranch_scc1 .LBB0_782
	v_lshlrev_b32_e32 v0, 4, v16
	s_waitcnt vmcnt(1)
	v_add_u32_e32 v2, 0x2000, v0
	v_ashrrev_i32_e32 v3, 31, v2
	v_lshrrev_b32_e32 v3, 22, v3
	v_add_u32_e32 v3, v2, v3
	v_ashrrev_i32_e32 v10, 10, v3
	v_mul_i32_i24_e32 v3, 0x400, v10
	v_sub_u32_e32 v2, v2, v3
	v_lshrrev_b32_e32 v3, 4, v2
	v_bitop3_b32 v2, v3, v2, 32 bitop3:0x6c
	v_ashrrev_i32_e32 v3, 31, v2
	v_lshrrev_b32_e32 v3, 26, v3
	v_add_u32_e32 v3, v2, v3
	v_lshlrev_b32_e32 v4, 3, v10
	v_ashrrev_i32_e32 v11, 6, v3
	v_and_b32_e32 v4, -16, v4
	v_add_u32_e32 v4, v11, v4
	v_and_b32_e32 v5, 3, v11
	s_mov_b32 s1, 0xfffe0
	v_lshrrev_b32_e32 v6, 2, v4
	v_lshlrev_b32_e32 v7, 1, v4
	v_and_b32_e32 v3, 0xc0, v3
	v_and_or_b32 v5, v4, s1, v5
	v_and_b32_e32 v6, 4, v6
	v_and_b32_e32 v7, 24, v7
	v_sub_u32_e32 v2, v2, v3
	v_or3_b32 v5, v5, v6, v7
	v_lshlrev_b32_e32 v6, 5, v10
	v_ashrrev_i16_sdwa v2, v216, sext(v2) dst_sel:DWORD dst_unused:UNUSED_PAD src0_sel:DWORD src1_sel:BYTE_0
	v_and_b32_e32 v6, 32, v6
	v_bfe_i32 v12, v2, 0, 16
	v_add_lshl_u32 v2, v6, v12, 1
	v_lshl_add_u32 v130, v5, 12, v2
	v_lshl_add_u32 v132, v4, 12, v2
	v_bfe_i32 v2, v16, 27, 1
	v_lshrrev_b32_e32 v2, 22, v2
	v_add_u32_e32 v2, v0, v2
	v_and_b32_e32 v2, 0xfffffc00, v2
	v_sub_u32_e32 v0, v0, v2
	v_lshrrev_b32_e32 v2, 4, v0
	v_ashrrev_i32_e32 v3, 31, v16
	v_bitop3_b32 v0, v2, v0, 32 bitop3:0x6c
	v_lshrrev_b32_e32 v3, 26, v3
	v_ashrrev_i32_e32 v2, 31, v0
	v_add_u32_e32 v3, v16, v3
	v_lshrrev_b32_e32 v2, 26, v2
	v_ashrrev_i32_e32 v14, 6, v3
	v_add_u32_e32 v2, v0, v2
	v_lshlrev_b32_e32 v3, 3, v14
	v_ashrrev_i32_e32 v13, 6, v2
	v_and_b32_e32 v3, -16, v3
	v_add_u32_e32 v3, v13, v3
	s_ashr_i32 s0, s81, 3
	v_and_b32_e32 v4, 3, v13
	v_lshrrev_b32_e32 v5, 2, v3
	v_lshlrev_b32_e32 v6, 1, v3
	v_and_b32_e32 v2, 0xc0, v2
	s_ashr_i32 s12, s14, 6
	s_and_b32 s18, s81, 7
	v_and_or_b32 v4, v3, s1, v4
	v_and_b32_e32 v5, 4, v5
	v_and_b32_e32 v6, 24, v6
	v_sub_u32_e32 v0, v0, v2
	s_ashr_i32 s1, s0, 31
	s_ashr_i32 s13, s14, 8
	s_lshl_b32 s2, s12, 10
	v_or3_b32 v4, v4, v5, v6
	v_lshlrev_b32_e32 v5, 5, v14
	v_ashrrev_i16_sdwa v0, v216, sext(v0) dst_sel:DWORD dst_unused:UNUSED_PAD src0_sel:DWORD src1_sel:BYTE_0
	s_lshl_b64 s[6:7], s[0:1], 20
	s_lshl_b32 s1, s18, 20
	v_and_b32_e32 v5, 32, v5
	v_bfe_i32 v15, v0, 0, 16
	s_add_u32 s38, s94, s1
	v_add_lshl_u32 v2, v5, v15, 1
	s_addc_u32 s39, s50, 0
	s_add_i32 s3, s2, 0
	v_lshl_add_u32 v0, v4, 12, v2
	s_add_i32 m0, s3, 0x10000
	v_lshl_add_u32 v134, v3, 12, v2
	global_load_lds_dwordx4 v0, s[38:39]
	s_add_i32 m0, s3, 0x12000
	s_add_u32 s16, s38, 0x80000
	global_load_lds_dwordx4 v130, s[38:39]
	s_addc_u32 s17, s39, 0
	s_add_i32 m0, s3, 0x14000
	v_mov_b32_e32 v131, v1
	global_load_lds_dwordx4 v0, s[16:17]
	s_add_i32 m0, s3, 0x16000
	s_add_u32 s40, s58, s6
	s_addc_u32 s41, s59, s7
	s_add_i32 s5, s3, 0x2000
	global_load_lds_dwordx4 v130, s[16:17]
	s_mov_b32 m0, s3
	s_add_u32 s16, s40, 0x80000
	global_load_lds_dwordx4 v134, s[40:41]
	s_mov_b32 m0, s5
	s_addc_u32 s17, s41, 0
	s_add_i32 s6, s3, 0x4000
	global_load_lds_dwordx4 v132, s[40:41]
	s_mov_b32 m0, s6
	s_add_i32 s7, s3, 0x6000
	global_load_lds_dwordx4 v134, s[16:17]
	s_mov_b32 m0, s7
	v_mov_b32_e32 v135, v1
	global_load_lds_dwordx4 v132, s[16:17]
	v_mov_b32_e32 v133, v1
	s_cmp_eq_u32 s13, 1
	v_lshl_add_u64 v[8:9], s[38:39], 0, v[0:1]
	v_lshl_add_u64 v[6:7], s[38:39], 0, v[130:131]
	v_lshl_add_u64 v[2:3], s[40:41], 0, v[134:135]
	s_cselect_b64 s[48:49], -1, 0
	s_cmp_lg_u32 s13, 1
	v_lshl_add_u64 v[4:5], s[40:41], 0, v[132:133]
	s_cbranch_scc1 .LBB0_771
	s_barrier
.LBB0_771:
	v_lshrrev_b32_e32 v18, 1, v16
	v_and_b32_e32 v18, 24, v18
	v_and_b32_e32 v17, 15, v16
	v_lshlrev_b32_e32 v19, 1, v18
	v_lshlrev_b32_e32 v16, 2, v16
	v_lshl_or_b32 v142, s13, 6, v17
	v_lshl_or_b32 v17, v17, 6, v19
	s_lshl_b32 s1, s13, 13
	v_and_b32_e32 v16, 32, v16
	v_bitop3_b32 v19, v17, s1, v16 bitop3:0xde
	s_lshl_b32 s1, s12, 5
	s_and_b32 s1, s1, 0x60
	s_lshl_b32 s12, s1, 7
	s_add_i32 m0, s3, 0x18000
	v_lshl_add_u64 v[8:9], v[8:9], 0, s[54:55]
	v_bitop3_b32 v143, v17, s12, v16 bitop3:0xde
	s_waitcnt vmcnt(2)
	s_barrier
	global_load_lds_dwordx4 v[8:9], off
	v_lshl_add_u64 v[6:7], v[6:7], 0, s[54:55]
	s_add_i32 m0, s3, 0x1a000
	s_add_i32 s12, s3, 0x8000
	s_add_i32 s13, s3, 0xa000
	global_load_lds_dwordx4 v[6:7], off
	v_lshl_add_u64 v[2:3], v[2:3], 0, s[54:55]
	s_mov_b32 m0, s12
	s_add_u32 s16, s38, 0x80080
	global_load_lds_dwordx4 v[2:3], off
	v_lshl_add_u64 v[2:3], v[4:5], 0, s[54:55]
	s_mov_b32 m0, s13
	s_addc_u32 s17, s39, 0
	global_load_lds_dwordx4 v[2:3], off
	s_add_i32 m0, s3, 0x1c000
	v_lshl_add_u64 v[2:3], s[16:17], 0, v[0:1]
	global_load_lds_dwordx4 v[2:3], off
	v_lshl_add_u64 v[2:3], s[16:17], 0, v[130:131]
	s_add_i32 m0, s3, 0x1e000
	s_cmpk_lt_u32 s14, 0x100
	global_load_lds_dwordx4 v[2:3], off
	v_lshlrev_b32_e32 v2, 15, v10
	v_and_b32_e32 v2, 0xffff0000, v2
	v_lshl_add_u32 v2, v11, 12, v2
	v_and_b32_e32 v3, 1, v10
	v_lshl_or_b32 v2, v3, 6, v2
	v_lshl_add_u32 v136, v12, 1, v2
	v_lshlrev_b32_e32 v2, 15, v14
	v_and_b32_e32 v2, 0xffff0000, v2
	s_waitcnt vmcnt(6)
	v_lshl_add_u32 v2, v13, 12, v2
	v_and_b32_e32 v3, 1, v14
	v_lshl_or_b32 v2, v3, 6, v2
	s_cselect_b64 s[52:53], -1, 0
	s_add_i32 s14, s35, -1
	v_or_b32_e32 v144, s1, v18
	v_mov_b32_e32 v137, v1
	v_lshl_add_u32 v138, v15, 1, v2
	v_mov_b32_e32 v139, v1
	s_mov_b32 s15, 0
	v_add_u32_e32 v145, 0, v19
	s_barrier
	s_branch .LBB0_774

; __device__ __forceinline__ unsigned cvt_pk_bf16(float lo, float hi) { unsigned r; asm volatile("v_cvt_pk_bf16_f32 %0, %1, %2" : "=v"(r) : "v"(lo), "v"(hi)); return r; }
;     __device__ __forceinline__ void operator()(const f32x4 (&acc)[2][2][4][2], const Unit& u, int wr, int wc, int fr, int fq) const {
;         const int row0 = u.pm * BM + wr * 64 + fr; const int col0 = u.pn * BM + wc * 32 + 8 * fq;
; #pragma unroll
;         for (int ai = 0; ai < 2; ++ai)
; #pragma unroll
;             for (int m = 0; m < 4; ++m) { bf16_t* rowp = O + (size_t)(row0 + ai * HALF + m * 16) * 2048 + col0;
; #pragma unroll
;                 for (int bj = 0; bj < 2; ++bj) { const f32x4 v0 = acc[ai][bj][m][0], v1 = acc[ai][bj][m][1];
;                     u32x4 w; w.x = cvt_pk_bf16(v0[0], v0[1]); w.y = cvt_pk_bf16(v0[2], v0[3]); w.z = cvt_pk_bf16(v1[0], v1[1]); w.w = cvt_pk_bf16(v1[2], v1[3]);
;                     *(u32x4*)(rowp + bj * HALF) = w; } }
;     }
.LBB0_778:
	v_lshl_add_u32 v146, s20, 8, v142
	v_lshl_or_b32 v140, s17, 8, v144
	v_ashrrev_i32_e32 v147, 31, v146
	v_ashrrev_i32_e32 v141, 31, v140
	v_lshlrev_b64 v[148:149], 12, v[146:147]
	v_lshl_add_u64 v[148:149], s[96:97], 0, v[148:149]
	v_lshlrev_b64 v[150:151], 1, v[140:141]
	v_lshl_add_u64 v[140:141], v[148:149], 0, v[150:151]
	v_cvt_pk_bf16_f32 v126, v126, v127
	v_cvt_pk_bf16_f32 v127, v128, v129
	v_cvt_pk_bf16_f32 v128, v122, v123
	v_cvt_pk_bf16_f32 v129, v124, v125
	global_store_dwordx4 v[140:141], v[126:129], off
	v_cvt_pk_bf16_f32 v114, v114, v115
	v_cvt_pk_bf16_f32 v115, v116, v117
	v_cvt_pk_bf16_f32 v116, v106, v107
	v_or_b32_e32 v106, 16, v146
	v_ashrrev_i32_e32 v107, 31, v106
	v_lshlrev_b64 v[106:107], 12, v[106:107]
	v_lshl_add_u64 v[106:107], s[96:97], 0, v[106:107]
	v_cvt_pk_bf16_f32 v117, v108, v109
	global_store_dwordx4 v[140:141], v[114:117], off offset:256
	s_mov_b32 s1, 0x80000
	s_mov_b64 s[20:21], 0x80000
	v_lshl_add_u64 v[114:115], v[106:107], 0, v[150:151]
	v_cvt_pk_bf16_f32 v106, v118, v119
	v_cvt_pk_bf16_f32 v107, v120, v121
	v_cvt_pk_bf16_f32 v108, v110, v111
	v_cvt_pk_bf16_f32 v109, v112, v113
	global_store_dwordx4 v[114:115], v[106:109], off
	v_cvt_pk_bf16_f32 v98, v98, v99
	v_cvt_pk_bf16_f32 v99, v100, v101
	v_cvt_pk_bf16_f32 v100, v90, v91
	v_or_b32_e32 v90, 32, v146
	v_ashrrev_i32_e32 v91, 31, v90
	v_lshlrev_b64 v[90:91], 12, v[90:91]
	v_lshl_add_u64 v[90:91], s[96:97], 0, v[90:91]
	v_cvt_pk_bf16_f32 v101, v92, v93
	global_store_dwordx4 v[114:115], v[98:101], off offset:256
	s_cmp_eq_u32 s16, s14
	s_movk_i32 s33, 0x7f
	v_lshl_add_u64 v[98:99], v[90:91], 0, v[150:151]
	v_cvt_pk_bf16_f32 v90, v102, v103
	v_cvt_pk_bf16_f32 v91, v104, v105
	v_cvt_pk_bf16_f32 v92, v94, v95
	v_cvt_pk_bf16_f32 v93, v96, v97
	global_store_dwordx4 v[98:99], v[90:93], off
	v_cvt_pk_bf16_f32 v82, v82, v83
	v_cvt_pk_bf16_f32 v83, v84, v85
	v_cvt_pk_bf16_f32 v84, v74, v75
	v_or_b32_e32 v74, 48, v146
	v_ashrrev_i32_e32 v75, 31, v74
	v_lshlrev_b64 v[74:75], 12, v[74:75]
	v_lshl_add_u64 v[74:75], s[96:97], 0, v[74:75]
	v_cvt_pk_bf16_f32 v85, v76, v77
	global_store_dwordx4 v[98:99], v[82:85], off offset:256
	s_nop 1
	v_lshl_add_u64 v[82:83], v[74:75], 0, v[150:151]
	v_cvt_pk_bf16_f32 v74, v86, v87
	v_cvt_pk_bf16_f32 v75, v88, v89
	v_cvt_pk_bf16_f32 v76, v78, v79
	v_cvt_pk_bf16_f32 v77, v80, v81
	global_store_dwordx4 v[82:83], v[74:77], off
	v_cvt_pk_bf16_f32 v70, v70, v71
	v_cvt_pk_bf16_f32 v71, v72, v73
	v_cvt_pk_bf16_f32 v72, v66, v67
	v_cvt_pk_bf16_f32 v73, v68, v69
	global_store_dwordx4 v[82:83], v[70:73], off offset:256
	v_cvt_pk_bf16_f32 v62, v62, v63
	v_cvt_pk_bf16_f32 v63, v64, v65
	v_cvt_pk_bf16_f32 v64, v58, v59
	v_add_co_u32_e32 v58, vcc, s1, v140
	v_lshl_add_u64 v[66:67], v[140:141], 0, s[20:21]
	s_nop 0
	v_addc_co_u32_e32 v59, vcc, 0, v141, vcc
	s_mov_b32 s1, 0x90000
	v_cvt_pk_bf16_f32 v65, v60, v61
	global_store_dwordx4 v[58:59], v[62:65], off
	v_cvt_pk_bf16_f32 v50, v50, v51
	v_cvt_pk_bf16_f32 v51, v52, v53
	v_cvt_pk_bf16_f32 v52, v42, v43
	v_cvt_pk_bf16_f32 v53, v44, v45
	global_store_dwordx4 v[66:67], v[50:53], off offset:256
	s_mov_b64 s[20:21], 0x90000
	v_cvt_pk_bf16_f32 v42, v54, v55
	v_cvt_pk_bf16_f32 v43, v56, v57
	v_cvt_pk_bf16_f32 v44, v46, v47
	v_add_co_u32_e32 v46, vcc, s1, v140
	v_lshl_add_u64 v[50:51], v[140:141], 0, s[20:21]
	s_nop 0
	v_addc_co_u32_e32 v47, vcc, 0, v141, vcc
	s_mov_b32 s1, 0xa0000
	v_cvt_pk_bf16_f32 v45, v48, v49
	global_store_dwordx4 v[46:47], v[42:45], off
	v_cvt_pk_bf16_f32 v34, v34, v35
	v_cvt_pk_bf16_f32 v35, v36, v37
	v_cvt_pk_bf16_f32 v36, v26, v27
	v_cvt_pk_bf16_f32 v37, v28, v29
	global_store_dwordx4 v[50:51], v[34:37], off offset:256
	s_mov_b64 s[20:21], 0xa0000
	v_cvt_pk_bf16_f32 v26, v38, v39
	v_cvt_pk_bf16_f32 v27, v40, v41
	v_cvt_pk_bf16_f32 v28, v30, v31
	v_add_co_u32_e32 v30, vcc, s1, v140
	v_lshl_add_u64 v[34:35], v[140:141], 0, s[20:21]
	s_nop 0
	v_addc_co_u32_e32 v31, vcc, 0, v141, vcc
	s_mov_b32 s1, 0xb0000
	v_cvt_pk_bf16_f32 v29, v32, v33
	global_store_dwordx4 v[30:31], v[26:29], off
	v_cvt_pk_bf16_f32 v18, v18, v19
	v_cvt_pk_bf16_f32 v19, v20, v21
	v_cvt_pk_bf16_f32 v20, v10, v11
	v_cvt_pk_bf16_f32 v21, v12, v13
	global_store_dwordx4 v[34:35], v[18:21], off offset:256
	s_mov_b64 s[20:21], 0xb0000
	v_cvt_pk_bf16_f32 v10, v22, v23
	v_cvt_pk_bf16_f32 v11, v24, v25
	v_cvt_pk_bf16_f32 v12, v14, v15
	v_add_co_u32_e32 v14, vcc, s1, v140
	v_lshl_add_u64 v[18:19], v[140:141], 0, s[20:21]
	s_nop 0
	v_addc_co_u32_e32 v15, vcc, 0, v141, vcc
	s_mov_b64 s[20:21], -1
	v_cvt_pk_bf16_f32 v13, v16, v17
	global_store_dwordx4 v[14:15], v[10:13], off
	v_cvt_pk_bf16_f32 v6, v6, v7
	v_cvt_pk_bf16_f32 v7, v8, v9
	v_cvt_pk_bf16_f32 v8, v2, v3
	v_cvt_pk_bf16_f32 v9, v4, v5
	global_store_dwordx4 v[18:19], v[6:9], off offset:256
	s_cbranch_scc1 .LBB0_773
	s_andn2_b64 vcc, exec, s[48:49]
	s_cbranch_vccnz .LBB0_772
	s_barrier
	s_branch .LBB0_772

; __device__ __forceinline__ int wave_id_l() { int t = threadIdx.x; asm volatile("" : "+v"(t)); return t >> 6; }
;     if (ldw == 0) ldw = K;
;     const int nblk = N / 32, kb = item / nblk, nb = item % nblk, k0 = 64 * kb, n0 = 32 * nb;
;     float tv_[32];
; #pragma unroll
;     for (int i = 0; i < 32; ++i) tv_[i] = W[(size_t)(k0 + 2 * i + (lane >> 5)) * N + n0 + (lane & 31)];
; #pragma unroll
;     for (int i = 0; i < 32; ++i) scr[(2 * i + (lane >> 5)) * 33 + (lane & 31)] = tv_[i];
; __global__ void __launch_bounds__(NTHR, 2) hybrid_fwd(Params p) {
;     ...
;                 if (l == 0 && split && step == 2 && (c < 32 || c >= 128)) {
;                     const int gw = (c < 32 ? c : c - 96) * NWAVES + wave_id_l(), NGW = (G - 96) * NWAVES;
;                     convert_range(lds, p, IT_IN + I_IN + W1_EARLY, IT_IN + 2 * I_IN, gw, NGW); }
.LBB0_782:
	s_cmp_eq_u32 s51, 2
	s_cselect_b64 s[0:1], -1, 0
	s_cmp_lg_u32 s51, 2
	s_cselect_b64 s[18:19], -1, 0
	s_and_b64 s[2:3], s[0:1], s[90:91]
	v_readlane_b32 s28, v248, 18
	v_readlane_b32 s30, v248, 20
	v_readlane_b32 s34, v248, 22
	s_andn2_b64 vcc, exec, s[2:3]
	v_readlane_b32 s29, v248, 19
	v_readlane_b32 s31, v248, 21
	v_readlane_b32 s35, v248, 23
	s_mov_b32 s5, 0x2800000
	s_mov_b32 s6, 0x5000000
	s_mov_b32 s12, 0xf800000
	s_cbranch_vccnz .LBB0_787
	v_mov_b32_e32 v0, v193
	v_readlane_b32 s68, v251, 1
	s_waitcnt vmcnt(1)
	v_ashrrev_i32_e32 v2, 6, v0
	v_readlane_b32 s2, v249, 39
	v_readlane_b32 s72, v251, 5
	v_readlane_b32 s73, v251, 6
	v_add_u32_e32 v10, s2, v2
	v_mov_b32_e32 v0, v193
	v_readlane_b32 s70, v251, 3
	v_readlane_b32 s71, v251, 4
	s_mov_b64 s[38:39], s[72:73]
	v_cmp_gt_i32_e32 vcc, s25, v10
	v_readlane_b32 s69, v251, 2
	v_readlane_b32 s74, v251, 7
	v_readlane_b32 s75, v251, 8
	s_and_saveexec_b64 s[40:41], vcc
	v_readlane_b32 s60, v251, 21
	v_readlane_b32 s70, v251, 31
	v_readlane_b32 s71, v251, 32
	v_readlane_b32 s61, v251, 22
	v_readlane_b32 s62, v251, 23
	v_readlane_b32 s63, v251, 24
	v_readlane_b32 s64, v251, 25
	v_readlane_b32 s65, v251, 26
	v_readlane_b32 s66, v251, 27
	v_readlane_b32 s67, v251, 28
	v_readlane_b32 s68, v251, 29
	v_readlane_b32 s69, v251, 30
	v_readlane_b32 s72, v251, 33
	v_readlane_b32 s73, v251, 34
	v_readlane_b32 s74, v251, 35
	v_readlane_b32 s75, v251, 36
	s_cbranch_execz .LBB0_786
	v_lshlrev_b32_e32 v2, 8, v0
	v_and_b32_e32 v2, 0xffffc000, v2
	v_add_u32_e32 v3, 0, v2
	v_bfe_u32 v11, v0, 5, 1
	v_and_b32_e32 v2, 31, v0
	v_bfe_u32 v12, v0, 3, 3
	v_lshlrev_b32_e32 v0, 3, v0
	v_and_b32_e32 v4, 56, v0
	v_lshl_add_u32 v5, v2, 2, v3
	v_mul_u32_u24_e32 v6, 0x84, v11
	v_mul_u32_u24_e32 v0, 0x84, v4
	v_lshlrev_b32_e32 v7, 2, v12
	v_add3_u32 v13, v3, v0, v7
	v_or_b32_e32 v14, 8, v12
	v_or_b32_e32 v15, 16, v12
	v_or_b32_e32 v16, 24, v12
	s_mov_b64 s[48:49], 0
	v_lshlrev_b32_e32 v0, 2, v2
	v_add_u32_e32 v17, v5, v6
	v_lshlrev_b32_e32 v2, 1, v4
.LBB0_785:
	v_mul_hi_i32 v3, v10, s15
	v_lshrrev_b32_e32 v4, 31, v3
	v_ashrrev_i32_e32 v3, 12, v3
	v_add_u32_e32 v3, v3, v4
	v_mul_i32_i24_e32 v4, 0xffffd800, v3
	v_add_u32_e32 v8, v4, v10
	v_mov_b64_e32 v[4:5], s[70:71]
	v_mad_i64_i32 v[18:19], s[2:3], v3, s6, v[4:5]
	v_mov_b64_e32 v[4:5], s[38:39]
	v_mad_i64_i32 v[6:7], s[2:3], v3, s5, v[4:5]
	v_mul_hi_i32 v3, v8, s15
	v_lshrrev_b32_e32 v4, 31, v3
	v_ashrrev_i32_e32 v3, 7, v3
	v_add_u32_e32 v3, v3, v4
	v_mul_i32_i24_e32 v4, 0x140, v3
	v_sub_u32_e32 v4, v8, v4
	v_lshlrev_b32_e32 v4, 5, v4
	v_ashrrev_i32_e32 v5, 31, v4
	v_lshlrev_b32_e32 v8, 6, v3
	v_lshl_add_u64 v[18:19], v[4:5], 2, v[18:19]
	v_or_b32_e32 v46, v8, v11
	v_lshl_add_u64 v[42:43], v[18:19], 0, v[0:1]
	v_mad_i64_i32 v[18:19], s[2:3], v46, s23, v[42:43]
	v_or_b32_e32 v3, 2, v46
	global_load_dword v47, v[18:19], off
	v_mad_i64_i32 v[18:19], s[2:3], v3, s23, v[42:43]
	v_or_b32_e32 v3, 4, v46
	global_load_dword v48, v[18:19], off
	v_mad_i64_i32 v[18:19], s[2:3], v3, s23, v[42:43]
	v_or_b32_e32 v3, 6, v46
	global_load_dword v49, v[18:19], off
	v_mad_i64_i32 v[18:19], s[2:3], v3, s23, v[42:43]
	v_or_b32_e32 v3, 8, v46
	global_load_dword v50, v[18:19], off
	v_mad_i64_i32 v[18:19], s[2:3], v3, s23, v[42:43]
	v_or_b32_e32 v5, 10, v46
	global_load_dword v3, v[18:19], off
	v_mad_i64_i32 v[18:19], s[2:3], v5, s23, v[42:43]
	v_or_b32_e32 v5, 12, v46
	v_mad_i64_i32 v[20:21], s[2:3], v5, s23, v[42:43]
	v_or_b32_e32 v5, 14, v46
	global_load_dword v18, v[18:19], off
	v_or_b32_e32 v9, 18, v46
	global_load_dword v22, v[20:21], off
	v_mad_i64_i32 v[20:21], s[2:3], v5, s23, v[42:43]
	v_or_b32_e32 v5, 16, v46
	global_load_dword v30, v[20:21], off
	v_mad_i64_i32 v[20:21], s[2:3], v5, s23, v[42:43]
	global_load_dword v5, v[20:21], off
	v_mad_i64_i32 v[20:21], s[2:3], v9, s23, v[42:43]
	v_or_b32_e32 v9, 20, v46
	s_waitcnt lgkmcnt(0)
	v_mad_i64_i32 v[24:25], s[2:3], v9, s23, v[42:43]
	v_or_b32_e32 v9, 22, v46
	v_mad_i64_i32 v[26:27], s[2:3], v9, s23, v[42:43]
	v_or_b32_e32 v9, 24, v46
	global_load_dword v20, v[20:21], off
	v_or_b32_e32 v19, 26, v46
	global_load_dword v25, v[24:25], off
	v_or_b32_e32 v39, 60, v46
	global_load_dword v33, v[26:27], off
	v_mad_i64_i32 v[26:27], s[2:3], v9, s23, v[42:43]
	global_load_dword v9, v[26:27], off
	v_mad_i64_i32 v[26:27], s[2:3], v19, s23, v[42:43]
	v_or_b32_e32 v19, 28, v46
	global_load_dword v23, v[26:27], off
	v_mad_i64_i32 v[26:27], s[2:3], v19, s23, v[42:43]
	v_or_b32_e32 v19, 30, v46
	global_load_dword v28, v[26:27], off
	v_mad_i64_i32 v[26:27], s[2:3], v19, s23, v[42:43]
	v_or_b32_e32 v19, 32, v46
	global_load_dword v36, v[26:27], off
	v_mad_i64_i32 v[26:27], s[2:3], v19, s23, v[42:43]
	v_or_b32_e32 v21, 34, v46
	global_load_dword v19, v[26:27], off
	v_mad_i64_i32 v[26:27], s[2:3], v21, s23, v[42:43]
	v_or_b32_e32 v21, 36, v46
	v_mad_i64_i32 v[34:35], s[2:3], v21, s23, v[42:43]
	v_or_b32_e32 v21, 38, v46
	global_load_dword v26, v[26:27], off
	v_or_b32_e32 v24, 42, v46
	global_load_dword v31, v[34:35], off
	v_mad_i64_i32 v[34:35], s[2:3], v21, s23, v[42:43]
	v_or_b32_e32 v21, 40, v46
	global_load_dword v38, v[34:35], off
	v_mad_i64_i32 v[34:35], s[2:3], v21, s23, v[42:43]
	global_load_dword v21, v[34:35], off
	v_mad_i64_i32 v[34:35], s[2:3], v24, s23, v[42:43]
	v_or_b32_e32 v24, 44, v46
	global_load_dword v29, v[34:35], off
	v_mad_i64_i32 v[34:35], s[2:3], v24, s23, v[42:43]
	v_or_b32_e32 v24, 46, v46
	v_mad_i64_i32 v[40:41], s[2:3], v24, s23, v[42:43]
	v_or_b32_e32 v24, 48, v46
	v_mad_i64_i32 v[44:45], s[2:3], v24, s23, v[42:43]
	v_or_b32_e32 v27, 50, v46
	global_load_dword v34, v[34:35], off
	s_nop 0
	global_load_dword v40, v[40:41], off
	s_nop 0
	global_load_dword v24, v[44:45], off
	v_mad_i64_i32 v[44:45], s[2:3], v27, s23, v[42:43]
	v_or_b32_e32 v27, 52, v46
	global_load_dword v32, v[44:45], off
	v_mad_i64_i32 v[44:45], s[2:3], v27, s23, v[42:43]
	v_or_b32_e32 v27, 54, v46
	global_load_dword v37, v[44:45], off
	v_mad_i64_i32 v[44:45], s[2:3], v27, s23, v[42:43]
	v_or_b32_e32 v27, 56, v46
	global_load_dword v41, v[44:45], off
	v_mad_i64_i32 v[44:45], s[2:3], v27, s23, v[42:43]
	v_or_b32_e32 v35, 58, v46
	global_load_dword v27, v[44:45], off
	v_mad_i64_i32 v[44:45], s[2:3], v35, s23, v[42:43]
	global_load_dword v35, v[44:45], off
	v_mad_i64_i32 v[44:45], s[2:3], v39, s23, v[42:43]
	global_load_dword v39, v[44:45], off
	v_or_b32_e32 v44, 62, v46
	v_mad_i64_i32 v[42:43], s[2:3], v44, s23, v[42:43]
	global_load_dword v42, v[42:43], off
	v_add_u32_e32 v43, 0x400, v17
	s_waitcnt vmcnt(30)
; #define LAS __attribute__((address_space(3)))
; #define LDS_WAIT() asm volatile("s_waitcnt lgkmcnt(0)" ::: "memory")
; __device__ __forceinline__ unsigned pk2(float lo, float hi) { return f2bf(lo) | (f2bf(hi) << 16); }
;     ...
; #pragma unroll
;     for (int i = 0; i < 32; ++i) tv_[i] = W[(size_t)(k0 + 2 * i + (lane >> 5)) * N + n0 + (lane & 31)];
; #pragma unroll
;     for (int i = 0; i < 32; ++i) scr[(2 * i + (lane >> 5)) * 33 + (lane & 31)] = tv_[i];
;     LDS_WAIT(); asm volatile("" ::: "memory");
;     const int c = lane & 7;
; #pragma unroll
;     for (int j = 0; j < 4; ++j) { const int n = (lane >> 3) + 8 * j; const LAS float* s = scr + (8 * c) * 33 + n;
;         v4u o; o.x = pk2(s[0 * 33], s[1 * 33]); o.y = pk2(s[2 * 33], s[3 * 33]); o.z = pk2(s[4 * 33], s[5 * 33]); o.w = pk2(s[6 * 33], s[7 * 33]);
;         *(v4u*)(WT + (size_t)(n0 + n) * ldw + koff + k0 + 8 * c) = o; }
;     LDS_WAIT(); asm volatile("" ::: "memory");
	ds_write2_b32 v17, v47, v48 offset1:66
	s_waitcnt vmcnt(28)
	ds_write2_b32 v17, v49, v50 offset0:132 offset1:198
	s_waitcnt vmcnt(26)
	ds_write2_b32 v43, v3, v18 offset0:8 offset1:74
	s_waitcnt vmcnt(24)
	ds_write2_b32 v43, v22, v30 offset0:140 offset1:206
	v_add_u32_e32 v3, 0x800, v17
	s_waitcnt vmcnt(22)
	ds_write2_b32 v3, v5, v20 offset0:16 offset1:82
	s_waitcnt vmcnt(20)
	ds_write2_b32 v3, v25, v33 offset0:148 offset1:214
	v_add_u32_e32 v3, 0xc00, v17
	s_waitcnt vmcnt(18)
	ds_write2_b32 v3, v9, v23 offset0:24 offset1:90
	s_waitcnt vmcnt(16)
	ds_write2_b32 v3, v28, v36 offset0:156 offset1:222
	v_add_u32_e32 v3, 0x1000, v17
	s_waitcnt vmcnt(14)
	ds_write2_b32 v3, v19, v26 offset0:32 offset1:98
	s_waitcnt vmcnt(12)
	ds_write2_b32 v3, v31, v38 offset0:164 offset1:230
	v_add_u32_e32 v3, 0x1400, v17
	s_waitcnt vmcnt(10)
	ds_write2_b32 v3, v21, v29 offset0:40 offset1:106
	s_waitcnt vmcnt(8)
	ds_write2_b32 v3, v34, v40 offset0:172 offset1:238
	v_add_u32_e32 v3, 0x1800, v17
	s_waitcnt vmcnt(6)
	ds_write2_b32 v3, v24, v32 offset0:48 offset1:114
	s_waitcnt vmcnt(4)
	ds_write2_b32 v3, v37, v41 offset0:180 offset1:246
	v_add_u32_e32 v3, 0x1c00, v17
	s_waitcnt vmcnt(2)
	ds_write2_b32 v3, v27, v35 offset0:56 offset1:122
	s_waitcnt vmcnt(0)
	ds_write2_b32 v3, v39, v42 offset0:188 offset1:254
	s_waitcnt lgkmcnt(0)
	v_ashrrev_i32_e32 v9, 31, v8
	v_lshl_add_u64 v[6:7], v[8:9], 1, v[6:7]
	v_mov_b32_e32 v3, v1
	v_lshl_add_u64 v[18:19], v[6:7], 0, v[2:3]
	ds_read_b32 v3, v13
	ds_read_b32 v5, v13 offset:132
	v_or_b32_e32 v20, v4, v12
	v_ashrrev_i32_e32 v21, 31, v20
	v_lshlrev_b64 v[20:21], 12, v[20:21]
	s_waitcnt lgkmcnt(1)
	v_bfe_u32 v6, v3, 16, 1
	v_add3_u32 v3, v3, v6, s26
	s_waitcnt lgkmcnt(0)
	v_bfe_u32 v6, v5, 16, 1
	v_lshrrev_b32_e32 v3, 16, v3
	v_add3_u32 v5, v5, v6, s26
	v_and_or_b32 v6, v5, s24, v3
	ds_read_b32 v3, v13 offset:264
	ds_read_b32 v5, v13 offset:396
	v_lshl_add_u64 v[20:21], v[18:19], 0, v[20:21]
	s_movk_i32 s2, 0x4aff
	v_cmp_lt_i32_e32 vcc, s2, v10
	s_waitcnt lgkmcnt(1)
	v_bfe_u32 v7, v3, 16, 1
	v_add3_u32 v3, v3, v7, s26
	s_waitcnt lgkmcnt(0)
	v_bfe_u32 v7, v5, 16, 1
	v_lshrrev_b32_e32 v3, 16, v3
	v_add3_u32 v5, v5, v7, s26
	v_and_or_b32 v7, v5, s24, v3
	ds_read_b32 v3, v13 offset:528
	ds_read_b32 v5, v13 offset:660
	s_or_b64 s[48:49], vcc, s[48:49]
	s_waitcnt lgkmcnt(1)
	v_bfe_u32 v8, v3, 16, 1
	v_add3_u32 v3, v3, v8, s26
	s_waitcnt lgkmcnt(0)
	v_bfe_u32 v8, v5, 16, 1
	v_lshrrev_b32_e32 v3, 16, v3
	v_add3_u32 v5, v5, v8, s26
	v_and_or_b32 v8, v5, s24, v3
	ds_read_b32 v3, v13 offset:792
	ds_read_b32 v5, v13 offset:924
	s_waitcnt lgkmcnt(1)
	v_bfe_u32 v9, v3, 16, 1
	v_add3_u32 v3, v3, v9, s26
	s_waitcnt lgkmcnt(0)
	v_bfe_u32 v9, v5, 16, 1
	v_lshrrev_b32_e32 v3, 16, v3
	v_add3_u32 v5, v5, v9, s26
	v_and_or_b32 v9, v5, s24, v3
	global_store_dwordx4 v[20:21], v[6:9], off
	ds_read_b32 v3, v13 offset:32
	ds_read_b32 v5, v13 offset:164
	v_or_b32_e32 v20, v4, v14
	v_ashrrev_i32_e32 v21, 31, v20
	v_lshlrev_b64 v[20:21], 12, v[20:21]
	s_waitcnt lgkmcnt(0)
	v_bfe_u32 v6, v3, 16, 1
	v_add3_u32 v3, v3, v6, s26
	v_bfe_u32 v6, v5, 16, 1
	v_lshrrev_b32_e32 v3, 16, v3
	v_add3_u32 v5, v5, v6, s26
	v_and_or_b32 v6, v5, s24, v3
	ds_read_b32 v3, v13 offset:296
	ds_read_b32 v5, v13 offset:428
	v_lshl_add_u64 v[20:21], v[18:19], 0, v[20:21]
	s_waitcnt lgkmcnt(0)
	v_bfe_u32 v7, v3, 16, 1
	v_add3_u32 v3, v3, v7, s26
	v_bfe_u32 v7, v5, 16, 1
	v_lshrrev_b32_e32 v3, 16, v3
	v_add3_u32 v5, v5, v7, s26
	v_and_or_b32 v7, v5, s24, v3
	ds_read_b32 v3, v13 offset:560
	ds_read_b32 v5, v13 offset:692
	s_waitcnt lgkmcnt(0)
	v_bfe_u32 v8, v3, 16, 1
	v_add3_u32 v3, v3, v8, s26
	v_bfe_u32 v8, v5, 16, 1
	v_lshrrev_b32_e32 v3, 16, v3
	v_add3_u32 v5, v5, v8, s26
	v_and_or_b32 v8, v5, s24, v3
	ds_read_b32 v3, v13 offset:824
	ds_read_b32 v5, v13 offset:956
	s_waitcnt lgkmcnt(0)
	v_bfe_u32 v9, v3, 16, 1
	v_add3_u32 v3, v3, v9, s26
	v_bfe_u32 v9, v5, 16, 1
	v_lshrrev_b32_e32 v3, 16, v3
	v_add3_u32 v5, v5, v9, s26
	v_and_or_b32 v9, v5, s24, v3
	global_store_dwordx4 v[20:21], v[6:9], off
	ds_read_b32 v3, v13 offset:64
	ds_read_b32 v5, v13 offset:196
	v_or_b32_e32 v20, v4, v15
	v_ashrrev_i32_e32 v21, 31, v20
	v_lshlrev_b64 v[20:21], 12, v[20:21]
	s_waitcnt lgkmcnt(0)
	v_bfe_u32 v6, v3, 16, 1
	v_add3_u32 v3, v3, v6, s26
	v_bfe_u32 v6, v5, 16, 1
	v_lshrrev_b32_e32 v3, 16, v3
	v_add3_u32 v5, v5, v6, s26
	v_and_or_b32 v6, v5, s24, v3
	ds_read_b32 v3, v13 offset:328
	ds_read_b32 v5, v13 offset:460
	v_lshl_add_u64 v[20:21], v[18:19], 0, v[20:21]
	v_or_b32_e32 v4, v4, v16
	s_waitcnt lgkmcnt(0)
	v_bfe_u32 v7, v3, 16, 1
	v_add3_u32 v3, v3, v7, s26
	v_bfe_u32 v7, v5, 16, 1
	v_lshrrev_b32_e32 v3, 16, v3
	v_add3_u32 v5, v5, v7, s26
	v_and_or_b32 v7, v5, s24, v3
	ds_read_b32 v3, v13 offset:592
	ds_read_b32 v5, v13 offset:724
	s_waitcnt lgkmcnt(0)
	v_bfe_u32 v8, v3, 16, 1
	v_add3_u32 v3, v3, v8, s26
	v_bfe_u32 v8, v5, 16, 1
	v_lshrrev_b32_e32 v3, 16, v3
	v_add3_u32 v5, v5, v8, s26
	v_and_or_b32 v8, v5, s24, v3
	ds_read_b32 v3, v13 offset:856
	ds_read_b32 v5, v13 offset:988
	s_waitcnt lgkmcnt(0)
	v_bfe_u32 v9, v3, 16, 1
	v_add3_u32 v3, v3, v9, s26
	v_bfe_u32 v9, v5, 16, 1
	v_lshrrev_b32_e32 v3, 16, v3
	v_add3_u32 v5, v5, v9, s26
	v_and_or_b32 v9, v5, s24, v3
	global_store_dwordx4 v[20:21], v[6:9], off
	ds_read_b32 v3, v13 offset:96
	ds_read_b32 v5, v13 offset:228
	s_waitcnt lgkmcnt(0)
	v_bfe_u32 v6, v3, 16, 1
	v_add3_u32 v3, v3, v6, s26
	v_bfe_u32 v6, v5, 16, 1
	v_lshrrev_b32_e32 v3, 16, v3
	v_add3_u32 v5, v5, v6, s26
	v_and_or_b32 v6, v5, s24, v3
	ds_read_b32 v3, v13 offset:360
	ds_read_b32 v5, v13 offset:492
	s_waitcnt lgkmcnt(0)
	v_bfe_u32 v7, v3, 16, 1
	v_add3_u32 v3, v3, v7, s26
	v_bfe_u32 v7, v5, 16, 1
	v_lshrrev_b32_e32 v3, 16, v3
	v_add3_u32 v5, v5, v7, s26
	v_and_or_b32 v7, v5, s24, v3
	ds_read_b32 v3, v13 offset:624
	ds_read_b32 v5, v13 offset:756
	s_waitcnt lgkmcnt(0)
	v_bfe_u32 v8, v3, 16, 1
	v_add3_u32 v3, v3, v8, s26
	v_bfe_u32 v8, v5, 16, 1
	v_lshrrev_b32_e32 v3, 16, v3
	v_add3_u32 v5, v5, v8, s26
	v_and_or_b32 v8, v5, s24, v3
	ds_read_b32 v3, v13 offset:888
	ds_read_b32 v5, v13 offset:1020
	s_waitcnt lgkmcnt(0)
	v_bfe_u32 v9, v3, 16, 1
	v_add3_u32 v3, v3, v9, s26
	v_bfe_u32 v9, v5, 16, 1
	v_lshrrev_b32_e32 v3, 16, v3
	v_add3_u32 v5, v5, v9, s26
	v_and_or_b32 v9, v5, s24, v3
	v_ashrrev_i32_e32 v5, 31, v4
	v_lshlrev_b64 v[4:5], 12, v[4:5]
	v_lshl_add_u64 v[4:5], v[18:19], 0, v[4:5]
	global_store_dwordx4 v[4:5], v[6:9], off
	s_waitcnt lgkmcnt(0)
	v_add_u32_e32 v3, 0x500, v10
	v_mov_b32_e32 v10, v3
	s_andn2_b64 exec, exec, s[48:49]
	s_cbranch_execnz .LBB0_785

; __device__ __forceinline__ void ln_phase(const Params& p, const int layer, const int row_lo, const int row_hi, const int wg_id, const int n_wg) {
;     int tid_ = threadIdx.x; asm volatile("" : "+v"(tid_)); const int tid = tid_, lane = tid & 63, wave = tid >> 6;
;     const int gw = wg_id * NWAVES + wave, NGW = n_wg * NWAVES;
;     unsigned char* ws = p.ws; asm volatile("" : "+s"(ws)); float* Z = p.out; bf16* XB = (bf16*)(ws + WS_XB);
;     const float* g = p.in[19] + layer * DM; const float* bb = p.in[20] + layer * DM;
;     const bf16* OB = (const bf16*)(ws + WS_TMP);
;     for (int m0 = row_lo + gw; m0 < row_hi; m0 += 2 * NGW) {
;         const int m1r = m0 + NGW; const bool ok1 = m1r < row_hi; const int m1 = ok1 ? m1r : m0;
;         const v2u* ob0 = (const v2u*)(OB + (size_t)m0 * DM) + lane; const v2u* ob1 = (const v2u*)(OB + (size_t)m1 * DM) + lane;
;         f32x4 v0[8], v1[8]; v2u w0[8], w1[8]; float s0 = 0.f, s1 = 0.f;
; __global__ void __launch_bounds__(NTHR, 2) hybrid_fwd(Params p) {
;     ...
;                 if (split && step == 2 && (c < 32 || c >= 128)) ln_phase(p, l, 0, LN_EARLY_SPLIT, c < 32 ? c : c - 96, G - 96);
.LBB0_787:
	v_readlane_b32 s2, v249, 34
	v_readlane_b32 s3, v249, 35
	s_and_b64 s[0:1], s[0:1], s[2:3]
	s_andn2_b64 vcc, exec, s[0:1]
	s_cbranch_vccnz .LBB0_860
	v_mov_b32_e32 v0, v193
	v_readlane_b32 s68, v251, 1
	s_waitcnt vmcnt(1)
	v_ashrrev_i32_e32 v2, 6, v0
	v_readlane_b32 s2, v249, 38
	v_readlane_b32 s72, v251, 5
	v_readlane_b32 s73, v251, 6
	v_add_u32_e32 v66, s2, v2
	s_movk_i32 s2, 0x1800
	s_mov_b64 s[0:1], s[72:73]
	v_cmp_gt_i32_e32 vcc, s2, v66
	v_readlane_b32 s69, v251, 2
	v_readlane_b32 s70, v251, 3
	v_readlane_b32 s71, v251, 4
	v_readlane_b32 s74, v251, 7
	v_readlane_b32 s75, v251, 8
	s_and_saveexec_b64 s[6:7], vcc
	s_cbranch_execz .LBB0_859
	s_add_u32 s2, s0, 0x21b04000
	v_and_b32_e32 v0, 63, v0
	s_addc_u32 s3, s1, 0
	v_lshlrev_b32_e32 v2, 3, v0
	v_mov_b32_e32 v3, v1
	v_lshl_add_u64 v[68:69], s[2:3], 0, v[2:3]
	v_lshl_add_u64 v[4:5], s[0:1], 0, v[2:3]
	s_mov_b64 s[0:1], 0x7b04000
	v_and_b32_e32 v3, 64, v223
	v_lshl_add_u64 v[70:71], v[4:5], 0, s[0:1]
	v_add_u32_e32 v3, 64, v3
	v_xor_b32_e32 v4, 1, v223
	v_cmp_lt_i32_e32 vcc, v4, v3
	v_readlane_b32 s0, v248, 40
	v_lshlrev_b32_e32 v0, 4, v0
	v_cndmask_b32_e32 v4, v223, v4, vcc
	v_lshlrev_b32_e32 v142, 2, v4
	v_xor_b32_e32 v4, 2, v223
	v_cmp_lt_i32_e32 vcc, v4, v3
	v_readlane_b32 s1, v248, 41
	v_ashrrev_i32_e32 v67, 31, v66
	v_cndmask_b32_e32 v4, v223, v4, vcc
	v_lshlrev_b32_e32 v143, 2, v4
	v_xor_b32_e32 v4, 4, v223
	v_cmp_lt_i32_e32 vcc, v4, v3
	v_lshl_add_u64 v[74:75], s[0:1], 0, v[0:1]
	v_readlane_b32 s0, v248, 38
	v_cndmask_b32_e32 v4, v223, v4, vcc
	v_lshlrev_b32_e32 v144, 2, v4
	v_xor_b32_e32 v4, 8, v223
	v_cmp_lt_i32_e32 vcc, v4, v3
	v_readlane_b32 s1, v248, 39
	v_readlane_b32 s68, v251, 1
	v_cndmask_b32_e32 v4, v223, v4, vcc
	v_lshlrev_b32_e32 v145, 2, v4
	v_xor_b32_e32 v4, 16, v223
	v_lshl_add_u64 v[76:77], s[0:1], 0, v[0:1]
	s_mov_b64 s[0:1], 0x1000
	v_cmp_lt_i32_e32 vcc, v4, v3
	v_lshl_add_u64 v[78:79], v[74:75], 0, s[0:1]
	v_lshl_add_u64 v[80:81], v[76:77], 0, s[0:1]
	s_mov_b64 s[0:1], 0x1400
	v_cndmask_b32_e32 v4, v223, v4, vcc
	v_lshl_add_u64 v[82:83], v[74:75], 0, s[0:1]
	v_lshl_add_u64 v[84:85], v[76:77], 0, s[0:1]
	s_mov_b64 s[0:1], 0x1800
	v_lshlrev_b32_e32 v146, 2, v4
	v_xor_b32_e32 v4, 32, v223
	v_lshl_add_u64 v[86:87], v[74:75], 0, s[0:1]
	v_lshl_add_u64 v[88:89], v[76:77], 0, s[0:1]
	s_mov_b64 s[0:1], 0x1c00
	v_cmp_lt_i32_e32 vcc, v4, v3
	v_lshl_add_u64 v[90:91], v[74:75], 0, s[0:1]
	v_lshl_add_u64 v[92:93], v[76:77], 0, s[0:1]
	s_mov_b64 s[0:1], s[46:47]
	s_mov_b32 s5, s50
	s_mov_b32 s13, s51
	v_readlane_b32 s36, v251, 21
	v_lshlrev_b64 v[6:7], 12, v[66:67]
	v_cndmask_b32_e32 v3, v223, v4, vcc
	v_readlane_b32 s70, v251, 3
	v_readlane_b32 s71, v251, 4
	v_readlane_b32 s37, v251, 22
	v_readlane_b32 s46, v251, 31
	v_readlane_b32 s47, v251, 32
	v_readlane_b32 s50, v251, 35
	v_readlane_b32 s51, v251, 36
	v_lshlrev_b64 v[4:5], 13, v[66:67]
	v_or_b32_e32 v6, v6, v2
	v_lshlrev_b32_e32 v147, 2, v3
	v_lshl_add_u64 v[72:73], s[70:71], 0, v[0:1]
	s_mov_b32 s51, s13
	s_mov_b32 s50, s5
	s_mov_b64 s[46:47], s[0:1]
	v_lshl_add_u64 v[94:95], s[36:37], 0, v[0:1]
	v_lshl_add_u64 v[96:97], s[36:37], 0, v[4:5]
	v_lshl_add_u64 v[98:99], s[2:3], 0, v[6:7]
	v_lshl_add_u64 v[100:101], s[70:71], 0, v[4:5]
	s_mov_b64 s[52:53], 0
	v_readlane_b32 s69, v251, 2
	v_readlane_b32 s72, v251, 5
	v_readlane_b32 s73, v251, 6
	v_readlane_b32 s74, v251, 7
	v_readlane_b32 s75, v251, 8
	v_readlane_b32 s38, v251, 23
	v_readlane_b32 s39, v251, 24
	v_readlane_b32 s40, v251, 25
	v_readlane_b32 s41, v251, 26
	v_readlane_b32 s42, v251, 27
	v_readlane_b32 s43, v251, 28
	v_readlane_b32 s44, v251, 29
	v_readlane_b32 s45, v251, 30
	v_readlane_b32 s48, v251, 33
	v_readlane_b32 s49, v251, 34
	s_branch .LBB0_792

; __device__ __forceinline__ float bflo(unsigned w) { return __uint_as_float(w << 16); }
; __device__ __forceinline__ float bfhi(unsigned w) { return __uint_as_float(w & 0xffff0000u); }
; __device__ __forceinline__ void ln_phase(const Params& p, const int layer, const int row_lo, const int row_hi, const int wg_id, const int n_wg) {
;     ...
;             const v2u* xb0 = (const v2u*)(XB + (size_t)m0 * DM) + lane; const v2u* xb1 = (const v2u*)(XB + (size_t)m1 * DM) + lane;
;             v2u a0[8], a1[8];
; #pragma unroll
;             for (int j = 0; j < 8; ++j) { a0[j] = xb0[64 * j]; a1[j] = xb1[64 * j]; w0[j] = ob0[64 * j]; w1[j] = ob1[64 * j]; }
; #pragma unroll
;             for (int j = 0; j < 8; ++j) { v0[j] = (f32x4){bflo(a0[j].x), bfhi(a0[j].x), bflo(a0[j].y), bfhi(a0[j].y)}; v1[j] = (f32x4){bflo(a1[j].x), bfhi(a1[j].x), bflo(a1[j].y), bfhi(a1[j].y)}; }
.LBB0_792:
	s_movk_i32 s0, 0x1300
	v_add_u32_e32 v2, 0x500, v66
	v_cmp_gt_i32_e64 s[38:39], s0, v66
	s_mov_b64 s[0:1], -1
	s_and_b64 vcc, exec, s[10:11]
	v_cndmask_b32_e64 v2, v66, v2, s[38:39]
	v_ashrrev_i32_e32 v3, 31, v2
	v_lshlrev_b64 v[104:105], 11, v[2:3]
	s_cbranch_vccz .LBB0_794
	v_add_co_u32_e32 v4, vcc, 0xe6000000, v98
	v_lshl_add_u64 v[2:3], v[104:105], 1, v[70:71]
	s_nop 0
	v_addc_co_u32_e32 v5, vcc, -1, v99, vcc
	v_add_co_u32_e32 v10, vcc, 0xe6000200, v98
	global_load_dwordx2 v[6:7], v[2:3], off
	global_load_dwordx2 v[8:9], v[2:3], off offset:512
	global_load_dwordx2 v[12:13], v[2:3], off offset:1024
	v_addc_co_u32_e32 v11, vcc, -1, v99, vcc
	v_add_co_u32_e32 v16, vcc, 0xe6000400, v98
	global_load_dwordx2 v[14:15], v[2:3], off offset:1536
	s_nop 0
	global_load_dwordx2 v[4:5], v[4:5], off
	s_nop 0
	global_load_dwordx2 v[10:11], v[10:11], off
	v_addc_co_u32_e32 v17, vcc, -1, v99, vcc
	v_add_co_u32_e32 v18, vcc, 0xe6000600, v98
	global_load_dwordx2 v[16:17], v[16:17], off
	s_nop 0
	v_addc_co_u32_e32 v19, vcc, -1, v99, vcc
	v_add_co_u32_e32 v20, vcc, 0xe6000800, v98
	global_load_dwordx2 v[18:19], v[18:19], off
	s_nop 0
	v_addc_co_u32_e32 v21, vcc, -1, v99, vcc
	v_add_co_u32_e32 v22, vcc, 0xe6000a00, v98
	global_load_dwordx2 v[20:21], v[20:21], off
	s_nop 0
	global_load_dwordx2 v[30:31], v[2:3], off offset:2048
	v_addc_co_u32_e32 v23, vcc, -1, v99, vcc
	global_load_dwordx2 v[32:33], v[22:23], off
	global_load_dwordx2 v[102:103], v[2:3], off offset:2560
	v_add_co_u32_e32 v22, vcc, 0xe6000c00, v98
	s_mov_b64 s[0:1], 0
	s_nop 0
	v_addc_co_u32_e32 v23, vcc, -1, v99, vcc
	global_load_dwordx2 v[106:107], v[22:23], off
	global_load_dwordx2 v[108:109], v[2:3], off offset:3072
	v_add_co_u32_e32 v22, vcc, 0xe6000e00, v98
	s_waitcnt lgkmcnt(0)
	s_waitcnt vmcnt(13)
	v_lshlrev_b32_e32 v58, 16, v6
	v_addc_co_u32_e32 v23, vcc, -1, v99, vcc
	global_load_dwordx2 v[110:111], v[22:23], off
	global_load_dwordx2 v[112:113], v[2:3], off offset:3584
	v_and_b32_e32 v59, 0xffff0000, v6
	v_lshlrev_b32_e32 v60, 16, v7
	v_and_b32_e32 v61, 0xffff0000, v7
	s_waitcnt vmcnt(14)
	v_lshlrev_b32_e32 v50, 16, v8
	v_and_b32_e32 v51, 0xffff0000, v8
	v_lshlrev_b32_e32 v52, 16, v9
	v_and_b32_e32 v53, 0xffff0000, v9
	s_waitcnt vmcnt(13)
	v_lshlrev_b32_e32 v42, 16, v12
	v_and_b32_e32 v43, 0xffff0000, v12
	v_lshlrev_b32_e32 v44, 16, v13
	v_and_b32_e32 v45, 0xffff0000, v13
	s_waitcnt vmcnt(12)
	v_lshlrev_b32_e32 v22, 16, v14
	s_waitcnt vmcnt(11)
	v_lshlrev_b32_e32 v62, 16, v4
	v_and_b32_e32 v63, 0xffff0000, v4
	v_lshlrev_b32_e32 v64, 16, v5
	v_and_b32_e32 v65, 0xffff0000, v5
	s_waitcnt vmcnt(10)
	v_lshlrev_b32_e32 v54, 16, v10
	v_and_b32_e32 v55, 0xffff0000, v10
	v_lshlrev_b32_e32 v56, 16, v11
	v_and_b32_e32 v57, 0xffff0000, v11
	s_waitcnt vmcnt(9)
	v_lshlrev_b32_e32 v46, 16, v16
	v_and_b32_e32 v47, 0xffff0000, v16
	v_lshlrev_b32_e32 v48, 16, v17
	v_and_b32_e32 v49, 0xffff0000, v17
	s_waitcnt vmcnt(8)
	v_lshlrev_b32_e32 v26, 16, v18
	v_and_b32_e32 v27, 0xffff0000, v18
	v_lshlrev_b32_e32 v28, 16, v19
	v_and_b32_e32 v29, 0xffff0000, v19
	v_and_b32_e32 v23, 0xffff0000, v14
	v_lshlrev_b32_e32 v24, 16, v15
	v_and_b32_e32 v25, 0xffff0000, v15
	s_waitcnt vmcnt(7)
	v_lshlrev_b32_e32 v34, 16, v20
	v_and_b32_e32 v35, 0xffff0000, v20
	v_lshlrev_b32_e32 v36, 16, v21
	v_and_b32_e32 v37, 0xffff0000, v21
	s_waitcnt vmcnt(6)
	v_lshlrev_b32_e32 v38, 16, v30
	v_and_b32_e32 v39, 0xffff0000, v30
	v_lshlrev_b32_e32 v40, 16, v31
	v_and_b32_e32 v41, 0xffff0000, v31
	s_waitcnt vmcnt(5)
	v_lshlrev_b32_e32 v14, 16, v32
	v_and_b32_e32 v15, 0xffff0000, v32
	v_lshlrev_b32_e32 v16, 16, v33
	v_and_b32_e32 v17, 0xffff0000, v33
	s_waitcnt vmcnt(4)
	v_lshlrev_b32_e32 v30, 16, v102
	v_and_b32_e32 v31, 0xffff0000, v102
	v_lshlrev_b32_e32 v32, 16, v103
	v_and_b32_e32 v33, 0xffff0000, v103
	s_waitcnt vmcnt(3)
	v_lshlrev_b32_e32 v6, 16, v106
	v_and_b32_e32 v7, 0xffff0000, v106
	v_lshlrev_b32_e32 v8, 16, v107
	v_and_b32_e32 v9, 0xffff0000, v107
	s_waitcnt vmcnt(2)
	v_lshlrev_b32_e32 v18, 16, v108
	v_and_b32_e32 v19, 0xffff0000, v108
	v_lshlrev_b32_e32 v20, 16, v109
	v_and_b32_e32 v21, 0xffff0000, v109
	s_waitcnt lgkmcnt(0)
	s_waitcnt vmcnt(1)
	v_lshlrev_b32_e32 v2, 16, v110
	v_and_b32_e32 v3, 0xffff0000, v110
	v_lshlrev_b32_e32 v4, 16, v111
	v_and_b32_e32 v5, 0xffff0000, v111
	s_waitcnt vmcnt(0)
	v_lshlrev_b32_e32 v10, 16, v112
	v_and_b32_e32 v11, 0xffff0000, v112
	v_lshlrev_b32_e32 v12, 16, v113
	v_and_b32_e32 v13, 0xffff0000, v113

; __device__ __forceinline__ float bflo(unsigned w) { return __uint_as_float(w << 16); }
; __device__ __forceinline__ float bfhi(unsigned w) { return __uint_as_float(w & 0xffff0000u); }
; __device__ __forceinline__ void ln_phase(const Params& p, const int layer, const int row_lo, const int row_hi, const int wg_id, const int n_wg) {
;     ...
;             for (int j = 0; j < 8; ++j) { a0[j] = xb0[64 * j]; a1[j] = xb1[64 * j]; w0[j] = ob0[64 * j]; w1[j] = ob1[64 * j]; }
;     ...
;         for (int j = 0; j < 8; ++j) { v0[j] = v0[j] * DN_ALPHA + (f32x4){bflo(w0[j].x), bfhi(w0[j].x), bflo(w0[j].y), bfhi(w0[j].y)};
;             v1[j] = v1[j] * DN_ALPHA + (f32x4){bflo(w1[j].x), bfhi(w1[j].x), bflo(w1[j].y), bfhi(w1[j].y)};
;             s0 += (v0[j].x + v0[j].y) + (v0[j].z + v0[j].w); s1 += (v1[j].x + v1[j].y) + (v1[j].z + v1[j].w); }
.LBB0_796:
	v_lshlrev_b64 v[102:103], 1, v[104:105]
	v_lshl_add_u64 v[110:111], v[68:69], 0, v[102:103]
	global_load_dwordx2 v[118:119], v[98:99], off offset:3584
	global_load_dwordx2 v[120:121], v[98:99], off offset:3072
	global_load_dwordx2 v[122:123], v[98:99], off offset:2560
	global_load_dwordx2 v[126:127], v[98:99], off offset:2048
	global_load_dwordx2 v[130:131], v[98:99], off offset:1536
	global_load_dwordx2 v[106:107], v[98:99], off offset:1024
	global_load_dwordx2 v[138:139], v[98:99], off offset:512
	global_load_dwordx2 v[112:113], v[98:99], off
	global_load_dwordx2 v[140:141], v[110:111], off
	global_load_dwordx2 v[148:149], v[110:111], off offset:512
	global_load_dwordx2 v[108:109], v[110:111], off offset:1024
	global_load_dwordx2 v[136:137], v[110:111], off offset:1536
	global_load_dwordx2 v[134:135], v[110:111], off offset:2048
	global_load_dwordx2 v[132:133], v[110:111], off offset:2560
	global_load_dwordx2 v[128:129], v[110:111], off offset:3072
	global_load_dwordx2 v[124:125], v[110:111], off offset:3584
	v_lshl_add_u64 v[104:105], v[104:105], 2, v[72:73]
	s_waitcnt lgkmcnt(0)
	s_waitcnt vmcnt(8)
	v_lshlrev_b32_e32 v110, 16, v112
	v_and_b32_e32 v111, 0xffff0000, v112
	v_lshlrev_b32_e32 v112, 16, v113
	v_and_b32_e32 v113, 0xffff0000, v113
	v_pk_fma_f32 v[114:115], v[64:65], s[4:5], v[112:113] op_sel_hi:[1,0,1]
	v_pk_fma_f32 v[116:117], v[62:63], s[4:5], v[110:111] op_sel_hi:[1,0,1]
	s_waitcnt vmcnt(7)
	v_lshlrev_b32_e32 v62, 16, v140
	v_and_b32_e32 v63, 0xffff0000, v140
	v_lshlrev_b32_e32 v64, 16, v141
	v_and_b32_e32 v65, 0xffff0000, v141
	v_pk_fma_f32 v[110:111], v[60:61], s[4:5], v[64:65] op_sel_hi:[1,0,1]
	v_pk_fma_f32 v[112:113], v[58:59], s[4:5], v[62:63] op_sel_hi:[1,0,1]
	v_lshlrev_b32_e32 v58, 16, v138
	v_and_b32_e32 v59, 0xffff0000, v138
	v_lshlrev_b32_e32 v60, 16, v139
	v_and_b32_e32 v61, 0xffff0000, v139
	v_pk_fma_f32 v[56:57], v[56:57], s[4:5], v[60:61] op_sel_hi:[1,0,1]
	v_pk_fma_f32 v[54:55], v[54:55], s[4:5], v[58:59] op_sel_hi:[1,0,1]
	s_waitcnt vmcnt(6)
	v_lshlrev_b32_e32 v58, 16, v148
	v_and_b32_e32 v59, 0xffff0000, v148
	v_lshlrev_b32_e32 v60, 16, v149
	v_and_b32_e32 v61, 0xffff0000, v149
	v_pk_fma_f32 v[52:53], v[52:53], s[4:5], v[60:61] op_sel_hi:[1,0,1]
	v_pk_fma_f32 v[50:51], v[50:51], s[4:5], v[58:59] op_sel_hi:[1,0,1]
	v_mov_b32_e32 v58, v54
	v_mov_b32_e32 v59, v116
	v_mov_b32_e32 v60, v55
	v_mov_b32_e32 v61, v117
	v_pk_add_f32 v[58:59], v[58:59], v[60:61]
	v_mov_b32_e32 v60, v57
	v_mov_b32_e32 v61, v115
	v_mov_b32_e32 v62, v56
	v_mov_b32_e32 v63, v114
	v_pk_add_f32 v[60:61], v[60:61], v[62:63]
	v_mov_b32_e32 v62, v111
	v_pk_add_f32 v[58:59], v[58:59], v[60:61]
	v_mov_b32_e32 v60, v113
	v_add_f32_e32 v59, 0, v59
	v_add_f32_e32 v139, v58, v59
	v_mov_b32_e32 v58, v112
	v_mov_b32_e32 v59, v50
	v_mov_b32_e32 v61, v51
	v_pk_add_f32 v[58:59], v[58:59], v[60:61]
	v_mov_b32_e32 v60, v110
	v_mov_b32_e32 v61, v52
	v_mov_b32_e32 v63, v53
	v_pk_add_f32 v[60:61], v[60:61], v[62:63]
	s_nop 0
	v_pk_add_f32 v[58:59], v[58:59], v[60:61]
	v_lshlrev_b32_e32 v60, 16, v107
	v_add_f32_e32 v58, 0, v58
	v_add_f32_e32 v140, v58, v59
	v_lshlrev_b32_e32 v58, 16, v106
	v_and_b32_e32 v59, 0xffff0000, v106
	v_and_b32_e32 v61, 0xffff0000, v107
	v_pk_fma_f32 v[46:47], v[46:47], s[4:5], v[58:59] op_sel_hi:[1,0,1]
	v_pk_fma_f32 v[48:49], v[48:49], s[4:5], v[60:61] op_sel_hi:[1,0,1]
	s_waitcnt vmcnt(5)
	v_lshlrev_b32_e32 v58, 16, v108
	v_and_b32_e32 v59, 0xffff0000, v108
	v_lshlrev_b32_e32 v60, 16, v109
	v_and_b32_e32 v61, 0xffff0000, v109
	v_pk_fma_f32 v[108:109], v[44:45], s[4:5], v[60:61] op_sel_hi:[1,0,1]
	v_pk_fma_f32 v[106:107], v[42:43], s[4:5], v[58:59] op_sel_hi:[1,0,1]
	v_mov_b32_e32 v42, v46
	v_mov_b32_e32 v43, v49
	v_pk_mov_b32 v[44:45], v[46:47], v[48:49] op_sel:[1,0]
	s_nop 0
	v_pk_add_f32 v[42:43], v[42:43], v[44:45]
	v_mov_b32_e32 v44, v106
	v_pk_add_f32 v[148:149], v[42:43], v[42:43] op_sel_hi:[0,1]
	v_pk_mov_b32 v[42:43], v[106:107], v[108:109] op_sel:[1,0]
	v_mov_b32_e32 v45, v109
	v_pk_add_f32 v[42:43], v[42:43], v[44:45]
	v_lshlrev_b32_e32 v44, 16, v131
	v_pk_add_f32 v[150:151], v[42:43], v[42:43] op_sel:[0,1] op_sel_hi:[1,0]
	v_lshlrev_b32_e32 v42, 16, v130
	v_and_b32_e32 v43, 0xffff0000, v130
	v_and_b32_e32 v45, 0xffff0000, v131
	v_pk_fma_f32 v[64:65], v[28:29], s[4:5], v[44:45] op_sel_hi:[1,0,1]
	v_pk_fma_f32 v[62:63], v[26:27], s[4:5], v[42:43] op_sel_hi:[1,0,1]
	v_lshlrev_b32_e32 v42, 16, v126
	v_and_b32_e32 v43, 0xffff0000, v126
	v_lshlrev_b32_e32 v44, 16, v127
	v_and_b32_e32 v45, 0xffff0000, v127
	s_waitcnt vmcnt(4)
	v_lshlrev_b32_e32 v26, 16, v136
	v_and_b32_e32 v27, 0xffff0000, v136
	v_lshlrev_b32_e32 v28, 16, v137
	v_and_b32_e32 v29, 0xffff0000, v137
	v_pk_fma_f32 v[44:45], v[36:37], s[4:5], v[44:45] op_sel_hi:[1,0,1]
	v_pk_fma_f32 v[42:43], v[34:35], s[4:5], v[42:43] op_sel_hi:[1,0,1]
	v_pk_fma_f32 v[60:61], v[24:25], s[4:5], v[28:29] op_sel_hi:[1,0,1]
	v_pk_fma_f32 v[58:59], v[22:23], s[4:5], v[26:27] op_sel_hi:[1,0,1]
	v_add_f32_e32 v23, v62, v63
	v_add_f32_e32 v25, v65, v64
	s_waitcnt vmcnt(3)
; __device__ __forceinline__ void ln_phase(const Params& p, const int layer, const int row_lo, const int row_hi, const int wg_id, const int n_wg) {
;     ...
;             s0 += (v0[j].x + v0[j].y) + (v0[j].z + v0[j].w); s1 += (v1[j].x + v1[j].y) + (v1[j].z + v1[j].w); }
;         const float mean0 = wave_sum(s0) * (1.f / DM), mean1 = wave_sum(s1) * (1.f / DM); float q0 = 0.f, q1 = 0.f;
; #pragma unroll
;         for (int j = 0; j < 8; ++j) { v0[j] = v0[j] - mean0; v1[j] = v1[j] - mean1;
	v_lshlrev_b32_e32 v34, 16, v134
	v_and_b32_e32 v35, 0xffff0000, v134
	v_lshlrev_b32_e32 v36, 16, v135
	v_and_b32_e32 v37, 0xffff0000, v135
	v_mov_b32_e32 v22, v42
	v_mov_b32_e32 v24, v43
	v_mov_b32_e32 v148, v45
	v_mov_b32_e32 v138, v44
	v_pk_fma_f32 v[40:41], v[40:41], s[4:5], v[36:37] op_sel_hi:[1,0,1]
	v_pk_fma_f32 v[38:39], v[38:39], s[4:5], v[34:35] op_sel_hi:[1,0,1]
	v_pk_add_f32 v[22:23], v[22:23], v[24:25]
	v_pk_add_f32 v[24:25], v[148:149], v[138:139]
	v_add_f32_e32 v26, v58, v59
	v_add_f32_e32 v28, v60, v61
	v_pk_add_f32 v[22:23], v[22:23], v[24:25]
	v_mov_b32_e32 v141, v38
	v_mov_b32_e32 v151, v39
	v_mov_b32_e32 v27, v40
	v_mov_b32_e32 v29, v41
	v_pk_add_f32 v[126:127], v[22:23], v[22:23] op_sel_hi:[0,1]
	v_pk_add_f32 v[22:23], v[140:141], v[150:151]
	v_pk_add_f32 v[24:25], v[26:27], v[28:29]
	s_nop 0
	v_pk_add_f32 v[22:23], v[22:23], v[24:25]
	v_lshlrev_b32_e32 v24, 16, v123
	v_pk_add_f32 v[130:131], v[22:23], v[22:23] op_sel:[0,1] op_sel_hi:[1,0]
	v_lshlrev_b32_e32 v22, 16, v122
	v_and_b32_e32 v23, 0xffff0000, v122
	v_and_b32_e32 v25, 0xffff0000, v123
	v_pk_fma_f32 v[34:35], v[14:15], s[4:5], v[22:23] op_sel_hi:[1,0,1]
	v_pk_fma_f32 v[36:37], v[16:17], s[4:5], v[24:25] op_sel_hi:[1,0,1]
	s_waitcnt vmcnt(2)
	v_lshlrev_b32_e32 v14, 16, v132
	v_and_b32_e32 v15, 0xffff0000, v132
	v_lshlrev_b32_e32 v16, 16, v133
	v_and_b32_e32 v17, 0xffff0000, v133
	v_pk_fma_f32 v[32:33], v[32:33], s[4:5], v[16:17] op_sel_hi:[1,0,1]
	v_pk_fma_f32 v[30:31], v[30:31], s[4:5], v[14:15] op_sel_hi:[1,0,1]
	v_mov_b32_e32 v14, v34
	v_mov_b32_e32 v15, v37
	v_pk_mov_b32 v[16:17], v[34:35], v[36:37] op_sel:[1,0]
	s_nop 0
	v_pk_add_f32 v[14:15], v[14:15], v[16:17]
	v_mov_b32_e32 v16, v30
	v_pk_add_f32 v[122:123], v[14:15], v[14:15] op_sel_hi:[0,1]
	v_pk_mov_b32 v[14:15], v[30:31], v[32:33] op_sel:[1,0]
	v_mov_b32_e32 v17, v33
	v_pk_add_f32 v[14:15], v[14:15], v[16:17]
	v_lshlrev_b32_e32 v16, 16, v121
	v_pk_add_f32 v[132:133], v[14:15], v[14:15] op_sel:[0,1] op_sel_hi:[1,0]
	v_lshlrev_b32_e32 v14, 16, v120
	v_and_b32_e32 v15, 0xffff0000, v120
	v_and_b32_e32 v17, 0xffff0000, v121
	v_pk_fma_f32 v[28:29], v[8:9], s[4:5], v[16:17] op_sel_hi:[1,0,1]
	v_pk_fma_f32 v[26:27], v[6:7], s[4:5], v[14:15] op_sel_hi:[1,0,1]
	s_waitcnt vmcnt(1)
	v_lshlrev_b32_e32 v8, 16, v129
	v_and_b32_e32 v9, 0xffff0000, v129
	v_lshlrev_b32_e32 v16, 16, v118
	v_and_b32_e32 v17, 0xffff0000, v118
	v_lshlrev_b32_e32 v14, 16, v119
	v_and_b32_e32 v15, 0xffff0000, v119
	v_lshlrev_b32_e32 v6, 16, v128
	v_and_b32_e32 v7, 0xffff0000, v128
	v_pk_fma_f32 v[24:25], v[20:21], s[4:5], v[8:9] op_sel_hi:[1,0,1]
	v_pk_fma_f32 v[14:15], v[4:5], s[4:5], v[14:15] op_sel_hi:[1,0,1]
	v_pk_fma_f32 v[20:21], v[2:3], s[4:5], v[16:17] op_sel_hi:[1,0,1]
	v_pk_fma_f32 v[22:23], v[18:19], s[4:5], v[6:7] op_sel_hi:[1,0,1]
	v_add_f32_e32 v7, v26, v27
	v_add_f32_e32 v9, v29, v28
	s_waitcnt vmcnt(0)
	v_lshlrev_b32_e32 v2, 16, v124
	v_and_b32_e32 v3, 0xffff0000, v124
	v_lshlrev_b32_e32 v4, 16, v125
	v_and_b32_e32 v5, 0xffff0000, v125
	v_mov_b32_e32 v6, v20
	v_mov_b32_e32 v8, v21
	v_mov_b32_e32 v122, v15
	v_mov_b32_e32 v126, v14
	v_pk_fma_f32 v[16:17], v[12:13], s[4:5], v[4:5] op_sel_hi:[1,0,1]
	v_pk_fma_f32 v[18:19], v[10:11], s[4:5], v[2:3] op_sel_hi:[1,0,1]
	v_pk_add_f32 v[2:3], v[6:7], v[8:9]
	v_pk_add_f32 v[4:5], v[122:123], v[126:127]
	v_add_f32_e32 v120, v22, v23
	v_add_f32_e32 v128, v24, v25
	v_pk_add_f32 v[2:3], v[2:3], v[4:5]
	v_mov_b32_e32 v131, v18
	v_mov_b32_e32 v133, v19
	v_mov_b32_e32 v121, v16
	v_mov_b32_e32 v129, v17
	v_add_f32_e32 v6, v2, v3
	v_pk_add_f32 v[2:3], v[130:131], v[132:133]
	v_pk_add_f32 v[4:5], v[120:121], v[128:129]
	s_nop 0
	v_pk_add_f32 v[2:3], v[2:3], v[4:5]
	s_nop 0
	v_add_f32_e32 v2, v2, v3
	ds_bpermute_b32 v3, v142, v6
	s_waitcnt lgkmcnt(0)
	v_add_f32_e32 v3, v6, v3
	ds_bpermute_b32 v4, v143, v3
	s_waitcnt lgkmcnt(0)
	v_add_f32_e32 v3, v3, v4
	ds_bpermute_b32 v4, v144, v3
	s_waitcnt lgkmcnt(0)
	v_add_f32_e32 v3, v3, v4
	ds_bpermute_b32 v4, v145, v3
	s_waitcnt lgkmcnt(0)
	v_add_f32_e32 v3, v3, v4
	ds_bpermute_b32 v4, v146, v3
	s_waitcnt lgkmcnt(0)
	v_add_f32_e32 v3, v3, v4
	ds_bpermute_b32 v4, v147, v3
	s_waitcnt lgkmcnt(0)
	v_add_f32_e32 v67, v3, v4
	ds_bpermute_b32 v3, v142, v2
	v_fmamk_f32 v117, v67, 0xba000000, v117
	v_fmac_f32_e32 v116, 0xba000000, v67
	v_fmamk_f32 v121, v67, 0xba000000, v55
	v_fmac_f32_e32 v54, 0xba000000, v67
	s_waitcnt lgkmcnt(0)
	v_add_f32_e32 v2, v2, v3
	ds_bpermute_b32 v3, v143, v2
	v_mov_b32_e32 v120, v117
	v_fmac_f32_e32 v114, 0xba000000, v67
	v_fmac_f32_e32 v56, 0xba000000, v67
	v_pk_mul_f32 v[4:5], v[120:121], v[120:121]
	s_waitcnt lgkmcnt(0)
	v_add_f32_e32 v2, v2, v3
	ds_bpermute_b32 v3, v144, v2
	v_fmamk_f32 v115, v67, 0xba000000, v115
	v_fmamk_f32 v127, v67, 0xba000000, v57
	v_mov_b32_e32 v126, v115
	v_fmamk_f32 v49, v67, 0xba000000, v49
	s_waitcnt lgkmcnt(0)
	v_add_f32_e32 v2, v2, v3
	ds_bpermute_b32 v3, v145, v2
	v_fmac_f32_e32 v48, 0xba000000, v67
	v_fmamk_f32 v47, v67, 0xba000000, v47
	v_fmac_f32_e32 v46, 0xba000000, v67
	v_fmac_f32_e32 v62, 0xba000000, v67
	s_waitcnt lgkmcnt(0)
	v_add_f32_e32 v2, v2, v3
	ds_bpermute_b32 v3, v146, v2
	v_fmac_f32_e32 v64, 0xba000000, v67
	v_fmamk_f32 v63, v67, 0xba000000, v63
	v_fmamk_f32 v65, v67, 0xba000000, v65
	v_fmamk_f32 v45, v67, 0xba000000, v45
	s_waitcnt lgkmcnt(0)
	v_add_f32_e32 v2, v2, v3
	ds_bpermute_b32 v3, v147, v2
	v_fmac_f32_e32 v44, 0xba000000, v67
	v_fmamk_f32 v43, v67, 0xba000000, v43
	v_fmac_f32_e32 v42, 0xba000000, v67
	v_fmamk_f32 v37, v67, 0xba000000, v37
	s_waitcnt lgkmcnt(0)
; __device__ __forceinline__ void ln_phase(const Params& p, const int layer, const int row_lo, const int row_hi, const int wg_id, const int n_wg) {
;     ...
;         for (int j = 0; j < 8; ++j) { v0[j] = v0[j] - mean0; v1[j] = v1[j] - mean1;
;             q0 += (v0[j].x * v0[j].x + v0[j].y * v0[j].y) + (v0[j].z * v0[j].z + v0[j].w * v0[j].w); q1 += (v1[j].x * v1[j].x + v1[j].y * v1[j].y) + (v1[j].z * v1[j].z + v1[j].w * v1[j].w); }
	v_add_f32_e32 v130, v2, v3
	v_mov_b32_e32 v2, v116
	v_mov_b32_e32 v3, v54
	v_pk_fma_f32 v[2:3], v[2:3], v[2:3], v[4:5]
	v_mov_b32_e32 v4, v114
	v_mov_b32_e32 v5, v56
	v_fmamk_f32 v113, v130, 0xba000000, v113
	v_pk_mul_f32 v[4:5], v[4:5], v[4:5]
	v_fmamk_f32 v111, v130, 0xba000000, v111
	v_fmac_f32_e32 v112, 0xba000000, v130
	v_fmamk_f32 v123, v130, 0xba000000, v51
	v_fmac_f32_e32 v50, 0xba000000, v130
	v_pk_fma_f32 v[4:5], v[126:127], v[126:127], v[4:5]
	v_mov_b32_e32 v122, v113
	v_fmac_f32_e32 v110, 0xba000000, v130
	v_fmamk_f32 v125, v130, 0xba000000, v53
	v_fmac_f32_e32 v52, 0xba000000, v130
	v_pk_add_f32 v[2:3], v[2:3], v[4:5]
	v_mov_b32_e32 v4, v112
	v_mov_b32_e32 v5, v50
	v_pk_mul_f32 v[6:7], v[122:123], v[122:123]
	v_mov_b32_e32 v124, v111
	v_pk_fma_f32 v[4:5], v[4:5], v[4:5], v[6:7]
	v_mov_b32_e32 v6, v110
	v_mov_b32_e32 v7, v52
	v_pk_mul_f32 v[8:9], v[124:125], v[124:125]
	v_fmamk_f32 v109, v130, 0xba000000, v109
	v_pk_fma_f32 v[6:7], v[6:7], v[6:7], v[8:9]
	v_pk_mul_f32 v[8:9], v[46:47], v[46:47]
	v_pk_add_f32 v[4:5], v[4:5], v[6:7]
	v_pk_mul_f32 v[6:7], v[48:49], v[48:49]
	v_fmac_f32_e32 v108, 0xba000000, v130
	v_fmamk_f32 v107, v130, 0xba000000, v107
	v_fmac_f32_e32 v106, 0xba000000, v130
	v_pk_mov_b32 v[10:11], v[8:9], v[6:7] op_sel:[1,0]
	v_mov_b32_e32 v9, v7
	v_pk_add_f32 v[2:3], v[2:3], v[2:3] op_sel_hi:[0,1]
	v_pk_add_f32 v[6:7], v[8:9], v[10:11]
	v_pk_mul_f32 v[8:9], v[108:109], v[108:109]
	v_pk_mul_f32 v[10:11], v[106:107], v[106:107]
	v_mul_f32_e32 v2, v62, v62
	v_pk_mov_b32 v[12:13], v[10:11], v[8:9] op_sel:[1,0]
	v_mov_b32_e32 v11, v9
	v_pk_add_f32 v[8:9], v[12:13], v[10:11]
	v_fmac_f32_e32 v58, 0xba000000, v130
	v_pk_fma_f32 v[10:11], v[62:63], v[62:63], v[2:3] op_sel_hi:[1,1,0]
	v_mul_f32_e32 v2, v64, v64
	v_fmac_f32_e32 v60, 0xba000000, v130
	v_fmamk_f32 v59, v130, 0xba000000, v59
	v_pk_fma_f32 v[12:13], v[64:65], v[64:65], v[2:3] op_sel_hi:[1,1,0]
	v_mul_f32_e32 v2, v58, v58
	v_fmamk_f32 v61, v130, 0xba000000, v61
	v_pk_fma_f32 v[118:119], v[58:59], v[58:59], v[2:3] op_sel_hi:[1,1,0]
	v_mul_f32_e32 v2, v60, v60
	v_pk_add_f32 v[4:5], v[4:5], v[4:5] op_sel_hi:[0,1]
	v_pk_add_f32 v[6:7], v[6:7], v[6:7] op_sel_hi:[0,1]
	v_pk_add_f32 v[8:9], v[8:9], v[8:9] op_sel_hi:[0,1]
	v_pk_fma_f32 v[128:129], v[60:61], v[60:61], v[2:3] op_sel_hi:[1,1,0]
	v_fmamk_f32 v41, v130, 0xba000000, v41
	v_fmac_f32_e32 v40, 0xba000000, v130
	v_fmamk_f32 v39, v130, 0xba000000, v39
	v_fmac_f32_e32 v38, 0xba000000, v130
	v_mul_f32_e32 v2, v44, v44
	v_mul_f32_e32 v6, v45, v45
	v_mul_f32_e32 v118, v38, v38
	v_mul_f32_e32 v128, v39, v39
	v_mul_f32_e32 v8, v40, v40
	v_mul_f32_e32 v4, v41, v41
	v_mul_f32_e32 v10, v42, v42
	v_mul_f32_e32 v12, v43, v43
	v_pk_add_f32 v[2:3], v[6:7], v[2:3]
	v_pk_add_f32 v[6:7], v[118:119], v[128:129]
	v_pk_add_f32 v[4:5], v[8:9], v[4:5]
	v_fmac_f32_e32 v36, 0xba000000, v67
	v_fmamk_f32 v35, v67, 0xba000000, v35
	v_fmac_f32_e32 v34, 0xba000000, v67
	v_pk_add_f32 v[10:11], v[10:11], v[12:13]
	v_pk_add_f32 v[4:5], v[6:7], v[4:5]
	v_pk_mul_f32 v[6:7], v[36:37], v[36:37]
	v_pk_mul_f32 v[8:9], v[34:35], v[34:35]
	v_pk_add_f32 v[2:3], v[10:11], v[2:3]
	v_fmamk_f32 v33, v130, 0xba000000, v33
	v_fmac_f32_e32 v32, 0xba000000, v130
	v_fmamk_f32 v31, v130, 0xba000000, v31
	v_fmac_f32_e32 v30, 0xba000000, v130
	v_pk_mov_b32 v[10:11], v[8:9], v[6:7] op_sel:[1,0]
	v_mov_b32_e32 v9, v7
	v_pk_add_f32 v[2:3], v[2:3], v[2:3] op_sel_hi:[0,1]
	v_pk_add_f32 v[6:7], v[8:9], v[10:11]
	v_pk_mul_f32 v[8:9], v[32:33], v[32:33]
	v_pk_mul_f32 v[10:11], v[30:31], v[30:31]
	v_fmac_f32_e32 v26, 0xba000000, v67
	v_pk_mov_b32 v[12:13], v[10:11], v[8:9] op_sel:[1,0]
	v_mov_b32_e32 v11, v9
	v_fmac_f32_e32 v28, 0xba000000, v67
	v_fmamk_f32 v27, v67, 0xba000000, v27
	v_mul_f32_e32 v2, v26, v26
	v_pk_add_f32 v[8:9], v[12:13], v[10:11]
	v_fmamk_f32 v29, v67, 0xba000000, v29
	v_fmac_f32_e32 v22, 0xba000000, v130
	v_pk_fma_f32 v[10:11], v[26:27], v[26:27], v[2:3] op_sel_hi:[1,1,0]
	v_mul_f32_e32 v2, v28, v28
	v_fmac_f32_e32 v24, 0xba000000, v130
	v_fmamk_f32 v23, v130, 0xba000000, v23
	v_pk_fma_f32 v[12:13], v[28:29], v[28:29], v[2:3] op_sel_hi:[1,1,0]
	v_mul_f32_e32 v2, v22, v22
	v_pk_add_f32 v[6:7], v[6:7], v[6:7] op_sel_hi:[0,1]
	v_fmamk_f32 v25, v130, 0xba000000, v25
	v_pk_fma_f32 v[118:119], v[22:23], v[22:23], v[2:3] op_sel_hi:[1,1,0]
	v_mul_f32_e32 v2, v24, v24
	v_fmamk_f32 v15, v67, 0xba000000, v15
	v_fmac_f32_e32 v14, 0xba000000, v67
	v_fmamk_f32 v21, v67, 0xba000000, v21
	v_fmac_f32_e32 v20, 0xba000000, v67
	v_pk_fma_f32 v[128:129], v[24:25], v[24:25], v[2:3] op_sel_hi:[1,1,0]
	v_mul_f32_e32 v10, v20, v20
	v_mul_f32_e32 v12, v21, v21
	v_mul_f32_e32 v2, v14, v14
	v_mul_f32_e32 v6, v15, v15
	v_pk_add_f32 v[4:5], v[4:5], v[4:5] op_sel_hi:[0,1]
	v_pk_add_f32 v[8:9], v[8:9], v[8:9] op_sel_hi:[0,1]
	v_fmamk_f32 v17, v130, 0xba000000, v17
	v_fmac_f32_e32 v16, 0xba000000, v130
	v_fmamk_f32 v19, v130, 0xba000000, v19
	v_fmac_f32_e32 v18, 0xba000000, v130
	v_pk_add_f32 v[10:11], v[10:11], v[12:13]
	v_pk_add_f32 v[2:3], v[6:7], v[2:3]
	v_mul_f32_e32 v118, v18, v18
	v_pk_add_f32 v[2:3], v[10:11], v[2:3]
	v_mul_f32_e32 v128, v19, v19
	v_mul_f32_e32 v8, v16, v16
	v_mul_f32_e32 v4, v17, v17
	v_add_f32_e32 v6, v2, v3
	v_pk_add_f32 v[2:3], v[118:119], v[128:129]
	v_pk_add_f32 v[4:5], v[8:9], v[4:5]
	v_lshl_add_u64 v[118:119], v[100:101], 0, v[0:1]
	v_pk_add_f32 v[2:3], v[2:3], v[4:5]
	s_nop 0
	v_add_f32_e32 v2, v2, v3
	ds_bpermute_b32 v3, v142, v6
	s_waitcnt lgkmcnt(0)
; __device__ __forceinline__ unsigned pk2(float lo, float hi) { return f2bf(lo) | (f2bf(hi) << 16); }
; __device__ __forceinline__ void ln_phase(const Params& p, const int layer, const int row_lo, const int row_hi, const int wg_id, const int n_wg) {
;     ...
;         const float rstd0 = 1.f / sqrtf(wave_sum(q0) * (1.f / DM) + LN_EPS), rstd1 = 1.f / sqrtf(wave_sum(q1) * (1.f / DM) + LN_EPS);
;         f32x4* zr0 = (f32x4*)(Z + (size_t)m0 * DM) + lane; f32x4* zr1 = (f32x4*)(Z + (size_t)m1 * DM) + lane;
;         unsigned long long* o80 = (unsigned long long*)(XB + (size_t)m0 * DM) + lane; unsigned long long* o81 = (unsigned long long*)(XB + (size_t)m1 * DM) + lane;
; #pragma unroll
;         for (int j = 0; j < 8; ++j) { const f32x4 gv = *((const f32x4*)g + lane + 64 * j), bv = *((const f32x4*)bb + lane + 64 * j);
;             const f32x4 y0 = v0[j] * rstd0 * gv + bv, y1 = v1[j] * rstd1 * gv + bv;
;             if (layer == 0) { o80[64 * j] = (unsigned long long)pk2(y0.x, y0.y) | ((unsigned long long)pk2(y0.z, y0.w) << 32);
;                 if (ok1) o81[64 * j] = (unsigned long long)pk2(y1.x, y1.y) | ((unsigned long long)pk2(y1.z, y1.w) << 32); }
;             else { zr0[64 * j] = y0; if (ok1) zr1[64 * j] = y1; } }
	v_add_f32_e32 v3, v6, v3
	ds_bpermute_b32 v4, v143, v3
	s_waitcnt lgkmcnt(0)
	v_add_f32_e32 v3, v3, v4
	ds_bpermute_b32 v4, v144, v3
	s_waitcnt lgkmcnt(0)
	v_add_f32_e32 v3, v3, v4
	ds_bpermute_b32 v4, v145, v3
	s_waitcnt lgkmcnt(0)
	v_add_f32_e32 v3, v3, v4
	ds_bpermute_b32 v4, v146, v3
	s_waitcnt lgkmcnt(0)
	v_add_f32_e32 v3, v3, v4
	ds_bpermute_b32 v4, v147, v3
	s_waitcnt lgkmcnt(0)
	v_add_f32_e32 v3, v3, v4
	v_fmamk_f32 v3, v3, 0x3a000000, v218
	v_cmp_gt_f32_e32 vcc, s12, v3
	v_mul_f32_e32 v4, 0x4f800000, v3
	s_nop 0
	v_cndmask_b32_e32 v3, v3, v4, vcc
	v_sqrt_f32_e32 v4, v3
	s_nop 0
	v_add_u32_e32 v5, -1, v4
	v_fma_f32 v6, -v5, v4, v3
	v_cmp_ge_f32_e64 s[0:1], 0, v6
	v_add_u32_e32 v6, 1, v4
	s_nop 0
	v_cndmask_b32_e64 v5, v4, v5, s[0:1]
	v_fma_f32 v4, -v6, v4, v3
	v_cmp_lt_f32_e64 s[0:1], 0, v4
	s_nop 1
	v_cndmask_b32_e64 v4, v5, v6, s[0:1]
	v_mul_f32_e32 v5, 0x37800000, v4
	v_cndmask_b32_e32 v4, v4, v5, vcc
	v_cmp_class_f32_e32 vcc, v3, v219
	s_nop 1
	v_cndmask_b32_e32 v3, v4, v3, vcc
	v_div_scale_f32 v4, s[0:1], v3, v3, 1.0
	v_rcp_f32_e32 v5, v4
	s_nop 0
	v_fma_f32 v6, -v4, v5, 1.0
	v_fmac_f32_e32 v5, v6, v5
	v_div_scale_f32 v6, vcc, 1.0, v3, 1.0
	v_mul_f32_e32 v7, v6, v5
	v_fma_f32 v8, -v4, v7, v6
	v_fmac_f32_e32 v7, v8, v5
	v_fma_f32 v4, -v4, v7, v6
	v_div_fmas_f32 v4, v4, v5, v7
	v_div_fixup_f32 v120, v4, v3, 1.0
	ds_bpermute_b32 v3, v142, v2
	v_pk_mul_f32 v[10:11], v[116:117], v[120:121] op_sel_hi:[1,0]
	v_pk_mul_f32 v[12:13], v[114:115], v[120:121] op_sel_hi:[1,0]
	s_waitcnt lgkmcnt(0)
	v_add_f32_e32 v2, v2, v3
	ds_bpermute_b32 v3, v143, v2
	s_waitcnt lgkmcnt(0)
	v_add_f32_e32 v2, v2, v3
	ds_bpermute_b32 v3, v144, v2
	s_waitcnt lgkmcnt(0)
	v_add_f32_e32 v2, v2, v3
	ds_bpermute_b32 v3, v145, v2
	s_waitcnt lgkmcnt(0)
	v_add_f32_e32 v2, v2, v3
	ds_bpermute_b32 v3, v146, v2
	s_waitcnt lgkmcnt(0)
	v_add_f32_e32 v2, v2, v3
	ds_bpermute_b32 v3, v147, v2
	s_waitcnt lgkmcnt(0)
	v_add_f32_e32 v2, v2, v3
	v_fmamk_f32 v2, v2, 0x3a000000, v218
	v_cmp_gt_f32_e32 vcc, s12, v2
	v_mul_f32_e32 v3, 0x4f800000, v2
	s_nop 0
	v_cndmask_b32_e32 v2, v2, v3, vcc
	v_sqrt_f32_e32 v3, v2
	s_nop 0
	v_add_u32_e32 v4, -1, v3
	v_fma_f32 v5, -v4, v3, v2
	v_cmp_ge_f32_e64 s[0:1], 0, v5
	v_add_u32_e32 v5, 1, v3
	s_nop 0
	v_cndmask_b32_e64 v4, v3, v4, s[0:1]
	v_fma_f32 v3, -v5, v3, v2
	v_cmp_lt_f32_e64 s[0:1], 0, v3
	s_nop 1
	v_cndmask_b32_e64 v3, v4, v5, s[0:1]
	v_mul_f32_e32 v4, 0x37800000, v3
	v_cndmask_b32_e32 v3, v3, v4, vcc
	v_cmp_class_f32_e32 vcc, v2, v219
	s_nop 1
	v_cndmask_b32_e32 v2, v3, v2, vcc
	v_div_scale_f32 v3, s[0:1], v2, v2, 1.0
	v_rcp_f32_e32 v4, v3
	s_mov_b64 s[0:1], -1
	v_fma_f32 v5, -v3, v4, 1.0
	v_fmac_f32_e32 v4, v5, v4
	v_div_scale_f32 v5, vcc, 1.0, v2, 1.0
	v_mul_f32_e32 v6, v5, v4
	v_fma_f32 v7, -v3, v6, v5
	v_fmac_f32_e32 v6, v7, v4
	v_fma_f32 v3, -v3, v6, v5
	v_div_fmas_f32 v3, v3, v4, v6
	v_div_fixup_f32 v122, v3, v2, 1.0
	global_load_dwordx4 v[2:5], v[74:75], off
	global_load_dwordx4 v[6:9], v[76:77], off
	v_pk_mul_f32 v[112:113], v[112:113], v[122:123] op_sel_hi:[1,0]
	v_pk_mul_f32 v[110:111], v[110:111], v[122:123] op_sel_hi:[1,0]
	s_and_b64 vcc, exec, s[10:11]
	s_waitcnt vmcnt(0)
	v_pk_fma_f32 v[12:13], v[4:5], v[12:13], v[8:9]
	v_pk_fma_f32 v[10:11], v[2:3], v[10:11], v[6:7]
	v_pk_fma_f32 v[4:5], v[4:5], v[110:111], v[8:9]
	v_pk_fma_f32 v[2:3], v[2:3], v[112:113], v[6:7]
	s_cbranch_vccz .LBB0_800
	global_store_dwordx4 v[118:119], v[10:13], off
	s_and_saveexec_b64 s[0:1], s[38:39]
	s_cbranch_execz .LBB0_799
	global_store_dwordx4 v[104:105], v[2:5], off

; __device__ __forceinline__ unsigned pk2(float lo, float hi) { return f2bf(lo) | (f2bf(hi) << 16); }
; __device__ __forceinline__ void ln_phase(const Params& p, const int layer, const int row_lo, const int row_hi, const int wg_id, const int n_wg) {
;     ...
;             if (layer == 0) { o80[64 * j] = (unsigned long long)pk2(y0.x, y0.y) | ((unsigned long long)pk2(y0.z, y0.w) << 32);
;                 if (ok1) o81[64 * j] = (unsigned long long)pk2(y1.x, y1.y) | ((unsigned long long)pk2(y1.z, y1.w) << 32); }
.LBB0_800:
	s_andn2_b64 vcc, exec, s[0:1]
	v_lshl_add_u64 v[102:103], v[70:71], 0, v[102:103]
	s_cbranch_vccnz .LBB0_804
	v_bfe_u32 v6, v10, 16, 1
	v_add3_u32 v6, v10, v6, s26
	v_bfe_u32 v7, v11, 16, 1
	v_lshrrev_b32_e32 v6, 16, v6
	v_add3_u32 v7, v11, v7, s26
	v_and_or_b32 v6, v7, s24, v6
	v_bfe_u32 v7, v12, 16, 1
	v_add3_u32 v7, v12, v7, s26
	v_bfe_u32 v8, v13, 16, 1
	v_lshrrev_b32_e32 v7, 16, v7
	v_add3_u32 v8, v13, v8, s26
	v_and_or_b32 v7, v8, s24, v7
	v_add_co_u32_e32 v8, vcc, 0xe6000000, v98
	s_nop 1
	v_addc_co_u32_e32 v9, vcc, -1, v99, vcc
	global_store_dwordx2 v[8:9], v[6:7], off
	s_and_saveexec_b64 s[0:1], s[38:39]
	s_cbranch_execz .LBB0_803
	v_bfe_u32 v6, v2, 16, 1
	v_add3_u32 v2, v2, v6, s26
	v_bfe_u32 v6, v3, 16, 1
	v_lshrrev_b32_e32 v2, 16, v2
	v_add3_u32 v3, v3, v6, s26
	v_and_or_b32 v2, v3, s24, v2
	v_bfe_u32 v3, v4, 16, 1
	v_add3_u32 v3, v4, v3, s26
	v_bfe_u32 v4, v5, 16, 1
	v_lshrrev_b32_e32 v3, 16, v3
	v_add3_u32 v4, v5, v4, s26
	v_and_or_b32 v3, v4, s24, v3
	global_store_dwordx2 v[102:103], v[2:3], off

; __device__ __forceinline__ unsigned pk2(float lo, float hi) { return f2bf(lo) | (f2bf(hi) << 16); }
; __device__ __forceinline__ void ln_phase(const Params& p, const int layer, const int row_lo, const int row_hi, const int wg_id, const int n_wg) {
;     ...
;             if (layer == 0) { o80[64 * j] = (unsigned long long)pk2(y0.x, y0.y) | ((unsigned long long)pk2(y0.z, y0.w) << 32);
;                 if (ok1) o81[64 * j] = (unsigned long long)pk2(y1.x, y1.y) | ((unsigned long long)pk2(y1.z, y1.w) << 32); }
.LBB0_808:
	s_andn2_b64 vcc, exec, s[0:1]
	s_cbranch_vccnz .LBB0_812
	v_bfe_u32 v10, v2, 16, 1
	v_add3_u32 v2, v2, v10, s26
	v_bfe_u32 v10, v3, 16, 1
	v_lshrrev_b32_e32 v2, 16, v2
	v_add3_u32 v3, v3, v10, s26
	v_and_or_b32 v2, v3, s24, v2
	v_bfe_u32 v3, v4, 16, 1
	v_add3_u32 v3, v4, v3, s26
	v_bfe_u32 v4, v5, 16, 1
	v_lshrrev_b32_e32 v3, 16, v3
	v_add3_u32 v4, v5, v4, s26
	v_and_or_b32 v3, v4, s24, v3
	v_add_co_u32_e32 v4, vcc, 0xe6000200, v98
	s_nop 1
	v_addc_co_u32_e32 v5, vcc, -1, v99, vcc
	global_store_dwordx2 v[4:5], v[2:3], off
	s_and_saveexec_b64 s[0:1], s[38:39]
	s_cbranch_execz .LBB0_811
	v_bfe_u32 v2, v6, 16, 1
	v_add3_u32 v2, v6, v2, s26
	v_bfe_u32 v3, v7, 16, 1
	v_lshrrev_b32_e32 v2, 16, v2
	v_add3_u32 v3, v7, v3, s26
	v_and_or_b32 v2, v3, s24, v2
	v_bfe_u32 v3, v8, 16, 1
	v_add3_u32 v3, v8, v3, s26
	v_bfe_u32 v4, v9, 16, 1
	v_lshrrev_b32_e32 v3, 16, v3
	v_add3_u32 v4, v9, v4, s26
	v_and_or_b32 v3, v4, s24, v3
	global_store_dwordx2 v[102:103], v[2:3], off offset:512

; __device__ __forceinline__ unsigned pk2(float lo, float hi) { return f2bf(lo) | (f2bf(hi) << 16); }
; __device__ __forceinline__ void ln_phase(const Params& p, const int layer, const int row_lo, const int row_hi, const int wg_id, const int n_wg) {
;     ...
;             if (layer == 0) { o80[64 * j] = (unsigned long long)pk2(y0.x, y0.y) | ((unsigned long long)pk2(y0.z, y0.w) << 32);
;                 if (ok1) o81[64 * j] = (unsigned long long)pk2(y1.x, y1.y) | ((unsigned long long)pk2(y1.z, y1.w) << 32); }
.LBB0_816:
	s_andn2_b64 vcc, exec, s[0:1]
	s_cbranch_vccnz .LBB0_820
	v_bfe_u32 v10, v6, 16, 1
	v_add3_u32 v6, v6, v10, s26
	v_bfe_u32 v10, v7, 16, 1
	v_lshrrev_b32_e32 v6, 16, v6
	v_add3_u32 v7, v7, v10, s26
	v_and_or_b32 v6, v7, s24, v6
	v_bfe_u32 v7, v8, 16, 1
	v_add3_u32 v7, v8, v7, s26
	v_bfe_u32 v8, v9, 16, 1
	v_lshrrev_b32_e32 v7, 16, v7
	v_add3_u32 v8, v9, v8, s26
	v_and_or_b32 v7, v8, s24, v7
	v_add_co_u32_e32 v8, vcc, 0xe6000400, v98
	s_nop 1
	v_addc_co_u32_e32 v9, vcc, -1, v99, vcc
	global_store_dwordx2 v[8:9], v[6:7], off
	s_and_saveexec_b64 s[0:1], s[38:39]
	s_cbranch_execz .LBB0_819
	v_bfe_u32 v6, v2, 16, 1
	v_add3_u32 v2, v2, v6, s26
	v_bfe_u32 v6, v3, 16, 1
	v_lshrrev_b32_e32 v2, 16, v2
	v_add3_u32 v3, v3, v6, s26
	v_and_or_b32 v2, v3, s24, v2
	v_bfe_u32 v3, v4, 16, 1
	v_add3_u32 v3, v4, v3, s26
	v_bfe_u32 v4, v5, 16, 1
	v_lshrrev_b32_e32 v3, 16, v3
	v_add3_u32 v4, v5, v4, s26
	v_and_or_b32 v3, v4, s24, v3
	global_store_dwordx2 v[102:103], v[2:3], off offset:1024

; __device__ __forceinline__ unsigned pk2(float lo, float hi) { return f2bf(lo) | (f2bf(hi) << 16); }
; __device__ __forceinline__ void ln_phase(const Params& p, const int layer, const int row_lo, const int row_hi, const int wg_id, const int n_wg) {
;     ...
;             if (layer == 0) { o80[64 * j] = (unsigned long long)pk2(y0.x, y0.y) | ((unsigned long long)pk2(y0.z, y0.w) << 32);
;                 if (ok1) o81[64 * j] = (unsigned long long)pk2(y1.x, y1.y) | ((unsigned long long)pk2(y1.z, y1.w) << 32); }
.LBB0_824:
	s_andn2_b64 vcc, exec, s[0:1]
	s_cbranch_vccnz .LBB0_828
	v_bfe_u32 v10, v6, 16, 1
	v_add3_u32 v6, v6, v10, s26
	v_bfe_u32 v10, v7, 16, 1
	v_lshrrev_b32_e32 v6, 16, v6
	v_add3_u32 v7, v7, v10, s26
	v_and_or_b32 v6, v7, s24, v6
	v_bfe_u32 v7, v8, 16, 1
	v_add3_u32 v7, v8, v7, s26
	v_bfe_u32 v8, v9, 16, 1
	v_lshrrev_b32_e32 v7, 16, v7
	v_add3_u32 v8, v9, v8, s26
	v_and_or_b32 v7, v8, s24, v7
	v_add_co_u32_e32 v8, vcc, 0xe6000600, v98
	s_nop 1
	v_addc_co_u32_e32 v9, vcc, -1, v99, vcc
	global_store_dwordx2 v[8:9], v[6:7], off
	s_and_saveexec_b64 s[0:1], s[38:39]
	s_cbranch_execz .LBB0_827
	v_bfe_u32 v6, v2, 16, 1
	v_add3_u32 v2, v2, v6, s26
	v_bfe_u32 v6, v3, 16, 1
	v_lshrrev_b32_e32 v2, 16, v2
	v_add3_u32 v3, v3, v6, s26
	v_and_or_b32 v2, v3, s24, v2
	v_bfe_u32 v3, v4, 16, 1
	v_add3_u32 v3, v4, v3, s26
	v_bfe_u32 v4, v5, 16, 1
	v_lshrrev_b32_e32 v3, 16, v3
	v_add3_u32 v4, v5, v4, s26
	v_and_or_b32 v3, v4, s24, v3
	global_store_dwordx2 v[102:103], v[2:3], off offset:1536

; __device__ __forceinline__ unsigned pk2(float lo, float hi) { return f2bf(lo) | (f2bf(hi) << 16); }
; __device__ __forceinline__ void ln_phase(const Params& p, const int layer, const int row_lo, const int row_hi, const int wg_id, const int n_wg) {
;     ...
;             if (layer == 0) { o80[64 * j] = (unsigned long long)pk2(y0.x, y0.y) | ((unsigned long long)pk2(y0.z, y0.w) << 32);
;                 if (ok1) o81[64 * j] = (unsigned long long)pk2(y1.x, y1.y) | ((unsigned long long)pk2(y1.z, y1.w) << 32); }
.LBB0_832:
	s_andn2_b64 vcc, exec, s[0:1]
	s_cbranch_vccnz .LBB0_836
	v_bfe_u32 v10, v6, 16, 1
	v_add3_u32 v6, v6, v10, s26
	v_bfe_u32 v10, v7, 16, 1
	v_lshrrev_b32_e32 v6, 16, v6
	v_add3_u32 v7, v7, v10, s26
	v_and_or_b32 v6, v7, s24, v6
	v_bfe_u32 v7, v8, 16, 1
	v_add3_u32 v7, v8, v7, s26
	v_bfe_u32 v8, v9, 16, 1
	v_lshrrev_b32_e32 v7, 16, v7
	v_add3_u32 v8, v9, v8, s26
	v_and_or_b32 v7, v8, s24, v7
	v_add_co_u32_e32 v8, vcc, 0xe6000800, v98
	s_nop 1
	v_addc_co_u32_e32 v9, vcc, -1, v99, vcc
	global_store_dwordx2 v[8:9], v[6:7], off
	s_and_saveexec_b64 s[0:1], s[38:39]
	s_cbranch_execz .LBB0_835
	v_bfe_u32 v6, v2, 16, 1
	v_add3_u32 v2, v2, v6, s26
	v_bfe_u32 v6, v3, 16, 1
	v_lshrrev_b32_e32 v2, 16, v2
	v_add3_u32 v3, v3, v6, s26
	v_and_or_b32 v2, v3, s24, v2
	v_bfe_u32 v3, v4, 16, 1
	v_add3_u32 v3, v4, v3, s26
	v_bfe_u32 v4, v5, 16, 1
	v_lshrrev_b32_e32 v3, 16, v3
	v_add3_u32 v4, v5, v4, s26
	v_and_or_b32 v3, v4, s24, v3
	global_store_dwordx2 v[102:103], v[2:3], off offset:2048

; __device__ __forceinline__ unsigned pk2(float lo, float hi) { return f2bf(lo) | (f2bf(hi) << 16); }
; __device__ __forceinline__ void ln_phase(const Params& p, const int layer, const int row_lo, const int row_hi, const int wg_id, const int n_wg) {
;     ...
;             if (layer == 0) { o80[64 * j] = (unsigned long long)pk2(y0.x, y0.y) | ((unsigned long long)pk2(y0.z, y0.w) << 32);
;                 if (ok1) o81[64 * j] = (unsigned long long)pk2(y1.x, y1.y) | ((unsigned long long)pk2(y1.z, y1.w) << 32); }
.LBB0_840:
	s_andn2_b64 vcc, exec, s[0:1]
	s_cbranch_vccnz .LBB0_844
	v_bfe_u32 v10, v6, 16, 1
	v_add3_u32 v6, v6, v10, s26
	v_bfe_u32 v10, v7, 16, 1
	v_lshrrev_b32_e32 v6, 16, v6
	v_add3_u32 v7, v7, v10, s26
	v_and_or_b32 v6, v7, s24, v6
	v_bfe_u32 v7, v8, 16, 1
	v_add3_u32 v7, v8, v7, s26
	v_bfe_u32 v8, v9, 16, 1
	v_lshrrev_b32_e32 v7, 16, v7
	v_add3_u32 v8, v9, v8, s26
	v_and_or_b32 v7, v8, s24, v7
	v_add_co_u32_e32 v8, vcc, 0xe6000a00, v98
	s_nop 1
	v_addc_co_u32_e32 v9, vcc, -1, v99, vcc
	global_store_dwordx2 v[8:9], v[6:7], off
	s_and_saveexec_b64 s[0:1], s[38:39]
	s_cbranch_execz .LBB0_843
	v_bfe_u32 v6, v2, 16, 1
	v_add3_u32 v2, v2, v6, s26
	v_bfe_u32 v6, v3, 16, 1
	v_lshrrev_b32_e32 v2, 16, v2
	v_add3_u32 v3, v3, v6, s26
	v_and_or_b32 v2, v3, s24, v2
	v_bfe_u32 v3, v4, 16, 1
	v_add3_u32 v3, v4, v3, s26
	v_bfe_u32 v4, v5, 16, 1
	v_lshrrev_b32_e32 v3, 16, v3
	v_add3_u32 v4, v5, v4, s26
	v_and_or_b32 v3, v4, s24, v3
	global_store_dwordx2 v[102:103], v[2:3], off offset:2560

; __device__ __forceinline__ unsigned pk2(float lo, float hi) { return f2bf(lo) | (f2bf(hi) << 16); }
; __device__ __forceinline__ void ln_phase(const Params& p, const int layer, const int row_lo, const int row_hi, const int wg_id, const int n_wg) {
;     ...
;             if (layer == 0) { o80[64 * j] = (unsigned long long)pk2(y0.x, y0.y) | ((unsigned long long)pk2(y0.z, y0.w) << 32);
;                 if (ok1) o81[64 * j] = (unsigned long long)pk2(y1.x, y1.y) | ((unsigned long long)pk2(y1.z, y1.w) << 32); }
.LBB0_848:
	s_andn2_b64 vcc, exec, s[0:1]
	s_cbranch_vccnz .LBB0_852
	v_bfe_u32 v10, v6, 16, 1
	v_add3_u32 v6, v6, v10, s26
	v_bfe_u32 v10, v7, 16, 1
	v_lshrrev_b32_e32 v6, 16, v6
	v_add3_u32 v7, v7, v10, s26
	v_and_or_b32 v6, v7, s24, v6
	v_bfe_u32 v7, v8, 16, 1
	v_add3_u32 v7, v8, v7, s26
	v_bfe_u32 v8, v9, 16, 1
	v_lshrrev_b32_e32 v7, 16, v7
	v_add3_u32 v8, v9, v8, s26
	v_and_or_b32 v7, v8, s24, v7
	v_add_co_u32_e32 v8, vcc, 0xe6000c00, v98
	s_nop 1
	v_addc_co_u32_e32 v9, vcc, -1, v99, vcc
	global_store_dwordx2 v[8:9], v[6:7], off
	s_and_saveexec_b64 s[0:1], s[38:39]
	s_cbranch_execz .LBB0_851
	v_bfe_u32 v6, v2, 16, 1
	v_add3_u32 v2, v2, v6, s26
	v_bfe_u32 v6, v3, 16, 1
	v_lshrrev_b32_e32 v2, 16, v2
	v_add3_u32 v3, v3, v6, s26
	v_and_or_b32 v2, v3, s24, v2
	v_bfe_u32 v3, v4, 16, 1
	v_add3_u32 v3, v4, v3, s26
	v_bfe_u32 v4, v5, 16, 1
	v_lshrrev_b32_e32 v3, 16, v3
	v_add3_u32 v4, v5, v4, s26
	v_and_or_b32 v3, v4, s24, v3
	global_store_dwordx2 v[102:103], v[2:3], off offset:3072

; __device__ __forceinline__ unsigned pk2(float lo, float hi) { return f2bf(lo) | (f2bf(hi) << 16); }
; __device__ __forceinline__ void ln_phase(const Params& p, const int layer, const int row_lo, const int row_hi, const int wg_id, const int n_wg) {
;     ...
;             if (layer == 0) { o80[64 * j] = (unsigned long long)pk2(y0.x, y0.y) | ((unsigned long long)pk2(y0.z, y0.w) << 32);
;                 if (ok1) o81[64 * j] = (unsigned long long)pk2(y1.x, y1.y) | ((unsigned long long)pk2(y1.z, y1.w) << 32); }
.LBB0_856:
	s_andn2_b64 vcc, exec, s[0:1]
	s_cbranch_vccnz .LBB0_791
	v_bfe_u32 v10, v6, 16, 1
	v_add3_u32 v6, v6, v10, s26
	v_bfe_u32 v10, v7, 16, 1
	v_lshrrev_b32_e32 v6, 16, v6
	v_add3_u32 v7, v7, v10, s26
	v_and_or_b32 v6, v7, s24, v6
	v_bfe_u32 v7, v8, 16, 1
	v_add3_u32 v7, v8, v7, s26
	v_bfe_u32 v8, v9, 16, 1
	v_lshrrev_b32_e32 v7, 16, v7
	v_add3_u32 v8, v9, v8, s26
	v_and_or_b32 v7, v8, s24, v7
	v_add_co_u32_e32 v8, vcc, 0xe6000e00, v98
	s_nop 1
	v_addc_co_u32_e32 v9, vcc, -1, v99, vcc
	global_store_dwordx2 v[8:9], v[6:7], off
	s_and_saveexec_b64 s[0:1], s[38:39]
	s_cbranch_execz .LBB0_790
	v_bfe_u32 v6, v2, 16, 1
	v_add3_u32 v2, v2, v6, s26
	v_bfe_u32 v6, v3, 16, 1
	v_lshrrev_b32_e32 v2, 16, v2
	v_add3_u32 v3, v3, v6, s26
	v_and_or_b32 v2, v3, s24, v2
	v_bfe_u32 v3, v4, 16, 1
	v_add3_u32 v3, v4, v3, s26
	v_bfe_u32 v4, v5, 16, 1
	v_lshrrev_b32_e32 v3, 16, v3
	v_add3_u32 v4, v5, v4, s26
	v_and_or_b32 v3, v4, s24, v3
	global_store_dwordx2 v[102:103], v[2:3], off offset:3584
	s_branch .LBB0_790

; __device__ __forceinline__ unsigned pk2(float lo, float hi) { return f2bf(lo) | (f2bf(hi) << 16); }
; __device__ __forceinline__ float bflo(unsigned w) { return __uint_as_float(w << 16); }
; __device__ __forceinline__ float bfhi(unsigned w) { return __uint_as_float(w & 0xffff0000u); }
; __global__ void __launch_bounds__(NTHR, 2) hybrid_fwd(Params p) {
;     ...
;                 if (split && step == 1) {
;                     const bf16* P0 = (const bf16*)(ws + WS_HL); const bf16* P1 = P0 + (size_t)MT * DM; bf16* MG = (bf16*)(ws + WS_PP);
;                     for (int it = c * NTHR + (int)threadIdx.x; it < 1024 * 256; it += G * NTHR) { const size_t r = (size_t)(NP + (it >> 8)); const int c8 = (it & 255) * 8;
;                         const v4u a = *(const v4u*)(P0 + r * DM + c8), b = *(const v4u*)(P1 + r * DM + c8), gq = *(const v4u*)(PROJ + r * NC + C_MB + c8);
;                         v4u o;
;                         o.x = pk2(fmaxf(bflo(gq.x), 1e-30f) * (bflo(a.x) + bflo(b.x)), fmaxf(bfhi(gq.x), 1e-30f) * (bfhi(a.x) + bfhi(b.x)));
;                         o.y = pk2(fmaxf(bflo(gq.y), 1e-30f) * (bflo(a.y) + bflo(b.y)), fmaxf(bfhi(gq.y), 1e-30f) * (bfhi(a.y) + bfhi(b.y)));
;                         o.z = pk2(fmaxf(bflo(gq.z), 1e-30f) * (bflo(a.z) + bflo(b.z)), fmaxf(bfhi(gq.z), 1e-30f) * (bfhi(a.z) + bfhi(b.z)));
;                         o.w = pk2(fmaxf(bflo(gq.w), 1e-30f) * (bflo(a.w) + bflo(b.w)), fmaxf(bfhi(gq.w), 1e-30f) * (bfhi(a.w) + bfhi(b.w)));
;                         *(v4u*)(MG + r * DM + c8) = o; }
.LBB0_915:
	s_cmp_lg_u32 s51, 1
	v_readlane_b32 s2, v249, 58
	s_cselect_b64 s[0:1], -1, 0
	v_readlane_b32 s3, v249, 59
	s_or_b64 s[0:1], s[2:3], s[0:1]
	s_and_b64 vcc, exec, s[0:1]
	s_cbranch_vccnz .LBB0_715
	s_mov_b64 s[0:1], exec
	v_readlane_b32 s2, v248, 10
	v_readlane_b32 s3, v248, 11
	s_and_b64 s[2:3], s[0:1], s[2:3]
	s_mov_b64 exec, s[2:3]
	s_cbranch_execz .LBB0_919
	s_mov_b64 s[18:19], 0
	s_waitcnt vmcnt(1)
	v_mov_b32_e32 v2, v209
	v_mov_b32_e32 v3, v207
.LBB0_918:
	v_ashrrev_i32_e32 v0, 8, v3
	v_add_u32_e32 v12, 0x2000, v0
	v_ashrrev_i32_e32 v13, 31, v12
	v_and_b32_e32 v0, 0x7f8, v2
	v_mov_b64_e32 v[14:15], s[8:9]
	v_lshlrev_b64 v[16:17], 12, v[12:13]
	v_lshlrev_b32_e32 v0, 1, v0
	v_mad_i64_i32 v[12:13], s[2:3], v12, s25, v[14:15]
	v_lshl_add_u64 v[12:13], v[12:13], 0, v[0:1]
	v_lshl_add_u64 v[4:5], s[46:47], 0, v[16:17]
	v_lshl_add_u64 v[8:9], s[56:57], 0, v[16:17]
	v_add_co_u32_e32 v12, vcc, s22, v12
	v_lshl_add_u64 v[4:5], v[4:5], 0, v[0:1]
	v_lshl_add_u64 v[8:9], v[8:9], 0, v[0:1]
	v_addc_co_u32_e32 v13, vcc, 0, v13, vcc
	global_load_dwordx4 v[4:7], v[4:5], off
	s_mov_b32 s2, 0x1ffff
	global_load_dwordx4 v[8:11], v[8:9], off
	v_cmp_lt_i32_e32 vcc, s2, v3
	global_load_dwordx4 v[12:15], v[12:13], off
	v_add_u32_e32 v2, 0x100000, v2
	s_or_b64 s[18:19], vcc, s[18:19]
	s_waitcnt lgkmcnt(0)
	s_waitcnt vmcnt(2)
	v_lshlrev_b32_e32 v21, 16, v5
	v_lshlrev_b32_e32 v20, 16, v4
	s_waitcnt vmcnt(1)
	v_lshlrev_b32_e32 v23, 16, v9
	v_lshlrev_b32_e32 v22, 16, v8
	s_waitcnt vmcnt(0)
	v_lshlrev_b32_e32 v18, 16, v12
	v_and_b32_e32 v12, 0xffff0000, v12
	v_lshlrev_b32_e32 v19, 16, v13
	v_and_b32_e32 v13, 0xffff0000, v13
	v_and_b32_e32 v5, 0xffff0000, v5
	v_and_b32_e32 v4, 0xffff0000, v4
	v_and_b32_e32 v9, 0xffff0000, v9
	v_and_b32_e32 v8, 0xffff0000, v8
	v_max_f32_e32 v12, v12, v12
	v_max_f32_e32 v13, v13, v13
	v_pk_add_f32 v[4:5], v[4:5], v[8:9]
	v_and_b32_e32 v9, 0xffff0000, v14
	v_max_f32_e32 v18, v18, v18
	v_max_f32_e32 v12, 0xda24260, v12
	v_max_f32_e32 v19, v19, v19
	v_max_f32_e32 v13, 0xda24260, v13
	v_max_f32_e32 v9, v9, v9
	v_max_f32_e32 v18, 0xda24260, v18
	v_max_f32_e32 v19, 0xda24260, v19
	v_pk_add_f32 v[20:21], v[20:21], v[22:23]
	v_pk_mul_f32 v[4:5], v[4:5], v[12:13]
	v_lshlrev_b32_e32 v8, 16, v14
	v_max_f32_e32 v12, 0xda24260, v9
	v_lshlrev_b32_e32 v9, 16, v15
	v_and_b32_e32 v13, 0xffff0000, v15
	v_pk_mul_f32 v[18:19], v[20:21], v[18:19]
	v_max_f32_e32 v8, v8, v8
	v_max_f32_e32 v9, v9, v9
	v_max_f32_e32 v13, v13, v13
	v_lshlrev_b32_e32 v15, 16, v7
	v_lshlrev_b32_e32 v14, 16, v6
	v_lshlrev_b32_e32 v21, 16, v11
	v_lshlrev_b32_e32 v20, 16, v10
	v_and_b32_e32 v7, 0xffff0000, v7
	v_and_b32_e32 v6, 0xffff0000, v6
	v_and_b32_e32 v11, 0xffff0000, v11
	v_and_b32_e32 v10, 0xffff0000, v10
	v_max_f32_e32 v8, 0xda24260, v8
	v_max_f32_e32 v9, 0xda24260, v9
	v_max_f32_e32 v13, 0xda24260, v13
	v_pk_add_f32 v[14:15], v[14:15], v[20:21]
	v_pk_add_f32 v[6:7], v[6:7], v[10:11]
	v_pk_mul_f32 v[8:9], v[14:15], v[8:9]
	v_pk_mul_f32 v[6:7], v[6:7], v[12:13]
	v_bfe_u32 v12, v5, 16, 1
	v_bfe_u32 v13, v4, 16, 1
	v_add3_u32 v4, v4, v13, s26
	v_add3_u32 v5, v5, v12, s26
	v_bfe_u32 v12, v8, 16, 1
	v_bfe_u32 v13, v9, 16, 1
	v_bfe_u32 v10, v7, 16, 1
	v_bfe_u32 v11, v6, 16, 1
	v_add3_u32 v9, v9, v13, s26
	v_add3_u32 v8, v8, v12, s26
	v_add3_u32 v6, v6, v11, s26
	v_add3_u32 v7, v7, v10, s26
	v_bfe_u32 v10, v18, 16, 1
	v_bfe_u32 v11, v19, 16, 1
	v_lshrrev_b32_e32 v8, 16, v8
	v_lshrrev_b32_e32 v9, 16, v9
	v_add3_u32 v11, v19, v11, s26
	v_add3_u32 v10, v18, v10, s26
	v_and_or_b32 v7, v7, s24, v9
	v_and_or_b32 v6, v6, s24, v8
	v_lshl_add_u64 v[8:9], s[58:59], 0, v[16:17]
	v_lshrrev_b32_e32 v10, 16, v10
	v_lshrrev_b32_e32 v11, 16, v11
	v_lshl_add_u64 v[8:9], v[8:9], 0, v[0:1]
	v_add_u32_e32 v0, 0x20000, v3
	v_and_or_b32 v5, v5, s24, v11
	v_and_or_b32 v4, v4, s24, v10
	v_mov_b32_e32 v3, v0
	global_store_dwordx4 v[8:9], v[4:7], off
	s_andn2_b64 exec, exec, s[18:19]
	s_cbranch_execnz .LBB0_918

; __device__ __forceinline__ void ln_phase(const Params& p, const int layer, const int row_lo, const int row_hi, const int wg_id, const int n_wg) {
;     int tid_ = threadIdx.x; asm volatile("" : "+v"(tid_)); const int tid = tid_, lane = tid & 63, wave = tid >> 6;
;     const int gw = wg_id * NWAVES + wave, NGW = n_wg * NWAVES;
;     unsigned char* ws = p.ws; asm volatile("" : "+s"(ws)); float* Z = p.out; bf16* XB = (bf16*)(ws + WS_XB);
;     const float* g = p.in[19] + layer * DM; const float* bb = p.in[20] + layer * DM;
;     const bf16* OB = (const bf16*)(ws + WS_TMP);
;     for (int m0 = row_lo + gw; m0 < row_hi; m0 += 2 * NGW) {
;         const int m1r = m0 + NGW; const bool ok1 = m1r < row_hi; const int m1 = ok1 ? m1r : m0;
;         const v2u* ob0 = (const v2u*)(OB + (size_t)m0 * DM) + lane; const v2u* ob1 = (const v2u*)(OB + (size_t)m1 * DM) + lane;
;         f32x4 v0[8], v1[8]; v2u w0[8], w1[8]; float s0 = 0.f, s1 = 0.f;
; __global__ void __launch_bounds__(NTHR, 2) hybrid_fwd(Params p) {
;     ...
;         if (IN(pb + 5)) ln_phase(p, l, (gridDim.x == 256) ? LN_EARLY_SPLIT : 0, MT, (int)blockIdx.x, (int)gridDim.x);
.LBB0_1024:
	s_add_i32 s0, s5, 6
	s_cmp_le_i32 s18, s0
	s_cselect_b64 s[8:9], -1, 0
	s_cmp_lt_i32 s0, s19
	s_cselect_b64 s[18:19], -1, 0
	s_and_b64 s[0:1], s[8:9], s[18:19]
	s_andn2_b64 vcc, exec, s[0:1]
	v_readlane_b32 s14, v248, 26
	v_readlane_b32 s15, v248, 27
	s_cbranch_vccnz .LBB0_1097
	v_mov_b32_e32 v0, v193
	v_readlane_b32 s36, v251, 1
	s_waitcnt vmcnt(1)
	v_ashrrev_i32_e32 v2, 6, v0
	v_readlane_b32 s2, v249, 37
	v_readlane_b32 s40, v251, 5
	v_readlane_b32 s41, v251, 6
	v_add_u32_e32 v66, s2, v2
	s_movk_i32 s2, 0x2400
	v_readlane_b32 s42, v251, 7
	v_readlane_b32 s43, v251, 8
	s_mov_b64 s[0:1], s[40:41]
	v_cmp_gt_i32_e32 vcc, s2, v66
	v_readlane_b32 s37, v251, 2
	v_readlane_b32 s38, v251, 3
	v_readlane_b32 s39, v251, 4
	s_and_saveexec_b64 s[42:43], vcc
	s_cbranch_execz .LBB0_1096
	v_and_b32_e32 v2, 63, v0
	s_add_u32 s2, s0, 0x21b04000
	v_lshlrev_b32_e32 v0, 3, v2
	s_addc_u32 s3, s1, 0
	v_lshl_add_u64 v[4:5], s[0:1], 0, v[0:1]
	s_mov_b64 s[0:1], 0x7b04000
	v_and_b32_e32 v3, 64, v223
	v_lshl_add_u64 v[70:71], v[4:5], 0, s[0:1]
	v_add_u32_e32 v3, 64, v3
	v_xor_b32_e32 v4, 1, v223
	v_cmp_lt_i32_e32 vcc, v4, v3
	s_lshl_b32 s6, s56, 11
	s_mov_b32 s7, s80
	v_cndmask_b32_e32 v4, v223, v4, vcc
	v_lshlrev_b32_e32 v142, 2, v4
	v_xor_b32_e32 v4, 2, v223
	v_cmp_lt_i32_e32 vcc, v4, v3
	s_lshl_b64 s[6:7], s[6:7], 2
	v_readlane_b32 s44, v251, 1
	v_cndmask_b32_e32 v4, v223, v4, vcc
	v_lshlrev_b32_e32 v143, 2, v4
	v_xor_b32_e32 v4, 4, v223
	v_cmp_lt_i32_e32 vcc, v4, v3
	v_readlane_b32 s45, v251, 2
	s_add_u32 s12, s44, s6
	v_cndmask_b32_e32 v4, v223, v4, vcc
	v_lshlrev_b32_e32 v144, 2, v4
	v_xor_b32_e32 v4, 8, v223
	v_cmp_lt_i32_e32 vcc, v4, v3
	v_readlane_b32 s68, v251, 9
	s_addc_u32 s13, s45, s7
	v_cndmask_b32_e32 v4, v223, v4, vcc
	v_lshlrev_b32_e32 v145, 2, v4
	v_xor_b32_e32 v4, 16, v223
	v_cmp_lt_i32_e32 vcc, v4, v3
	v_readlane_b32 s74, v251, 15
	v_readlane_b32 s75, v251, 16
	v_cndmask_b32_e32 v4, v223, v4, vcc
	v_lshlrev_b32_e32 v146, 2, v4
	v_xor_b32_e32 v4, 32, v223
	s_add_u32 s6, s74, s6
	v_cmp_lt_i32_e32 vcc, v4, v3
	s_addc_u32 s7, s75, s7
	v_mov_b32_e32 v5, v1
	v_cndmask_b32_e32 v3, v223, v4, vcc
	v_lshlrev_b32_e32 v4, 4, v2
	v_readlane_b32 s69, v251, 10
	v_readlane_b32 s70, v251, 11
	v_readlane_b32 s71, v251, 12
	v_readlane_b32 s72, v251, 13
	v_readlane_b32 s73, v251, 14
	v_lshl_add_u64 v[74:75], s[6:7], 0, v[4:5]
	v_lshl_add_u64 v[76:77], s[12:13], 0, v[4:5]
	s_mov_b64 s[0:1], 0x1000
	v_readlane_b32 s46, v251, 3
	v_readlane_b32 s47, v251, 4
	v_lshl_add_u64 v[78:79], v[74:75], 0, s[0:1]
	v_lshl_add_u64 v[80:81], v[76:77], 0, s[0:1]
	s_mov_b64 s[0:1], 0x1400
	v_ashrrev_i32_e32 v67, 31, v66
	v_readlane_b32 s60, v251, 21
	v_lshl_add_u64 v[72:73], s[46:47], 0, v[4:5]
	v_lshl_add_u64 v[82:83], v[74:75], 0, s[0:1]
	v_lshl_add_u64 v[84:85], v[76:77], 0, s[0:1]
	s_mov_b64 s[0:1], 0x1800
	v_lshlrev_b64 v[4:5], 12, v[66:67]
	v_readlane_b32 s72, v251, 33
	v_readlane_b32 s73, v251, 34
	v_lshl_add_u64 v[86:87], v[74:75], 0, s[0:1]
	v_lshl_add_u64 v[88:89], v[76:77], 0, s[0:1]
	s_mov_b64 s[0:1], 0x1c00
	v_or_b32_e32 v4, v4, v0
	v_readlane_b32 s61, v251, 22
	v_readlane_b32 s72, v248, 24
	v_lshl_add_u64 v[68:69], s[2:3], 0, v[0:1]
	v_lshlrev_b32_e32 v147, 2, v3
	v_lshl_add_u64 v[90:91], v[74:75], 0, s[0:1]
	v_lshl_add_u64 v[92:93], v[76:77], 0, s[0:1]
	v_lshlrev_b64 v[94:95], 13, v[66:67]
	v_lshl_add_u64 v[96:97], s[2:3], 0, v[4:5]
	s_mov_b64 s[44:45], 0
	v_lshlrev_b32_e32 v98, 4, v2
	v_mov_b64_e32 v[100:101], v[72:73]
	v_readlane_b32 s73, v248, 25
	s_mov_b64 s[46:47], s[60:61]
	v_readlane_b32 s48, v251, 5
	v_readlane_b32 s49, v251, 6
	v_readlane_b32 s50, v251, 7
	v_readlane_b32 s51, v251, 8
	v_readlane_b32 s62, v251, 23
	v_readlane_b32 s63, v251, 24
	v_readlane_b32 s64, v251, 25
	v_readlane_b32 s65, v251, 26
	v_readlane_b32 s66, v251, 27
	v_readlane_b32 s67, v251, 28
	v_readlane_b32 s68, v251, 29
	v_readlane_b32 s69, v251, 30
	v_readlane_b32 s70, v251, 31
	v_readlane_b32 s71, v251, 32
	v_readlane_b32 s74, v251, 35
	v_readlane_b32 s75, v251, 36
	s_branch .LBB0_1029

; __device__ __forceinline__ float bflo(unsigned w) { return __uint_as_float(w << 16); }
; __device__ __forceinline__ float bfhi(unsigned w) { return __uint_as_float(w & 0xffff0000u); }
; __device__ __forceinline__ void ln_phase(const Params& p, const int layer, const int row_lo, const int row_hi, const int wg_id, const int n_wg) {
;     ...
;     for (int m0 = row_lo + gw; m0 < row_hi; m0 += 2 * NGW) {
;         const int m1r = m0 + NGW; const bool ok1 = m1r < row_hi; const int m1 = ok1 ? m1r : m0;
;         const v2u* ob0 = (const v2u*)(OB + (size_t)m0 * DM) + lane; const v2u* ob1 = (const v2u*)(OB + (size_t)m1 * DM) + lane;
;         f32x4 v0[8], v1[8]; v2u w0[8], w1[8]; float s0 = 0.f, s1 = 0.f;
;         if (layer == 0) {
;             const f32x4* xr0 = (const f32x4*)((m0 < NP) ? p.in[0] + (size_t)m0 * DM : p.in[1] + (size_t)(m0 - NP) * DM) + lane;
;             const f32x4* xr1 = (const f32x4*)((m1 < NP) ? p.in[0] + (size_t)m1 * DM : p.in[1] + (size_t)(m1 - NP) * DM) + lane;
; #pragma unroll
;             for (int j = 0; j < 8; ++j) { v0[j] = xr0[64 * j]; v1[j] = xr1[64 * j]; w0[j] = ob0[64 * j]; w1[j] = ob1[64 * j]; }
;         } else {
;             const v2u* xb0 = (const v2u*)(XB + (size_t)m0 * DM) + lane; const v2u* xb1 = (const v2u*)(XB + (size_t)m1 * DM) + lane;
;             v2u a0[8], a1[8];
; #pragma unroll
;             for (int j = 0; j < 8; ++j) { a0[j] = xb0[64 * j]; a1[j] = xb1[64 * j]; w0[j] = ob0[64 * j]; w1[j] = ob1[64 * j]; }
; #pragma unroll
;             for (int j = 0; j < 8; ++j) { v0[j] = (f32x4){bflo(a0[j].x), bfhi(a0[j].x), bflo(a0[j].y), bfhi(a0[j].y)}; v1[j] = (f32x4){bflo(a1[j].x), bfhi(a1[j].x), bflo(a1[j].y), bfhi(a1[j].y)}; }
.LBB0_1029:
	v_readlane_b32 s0, v249, 62
	s_and_b64 vcc, exec, s[10:11]
	s_nop 0
	v_add_u32_e32 v0, s0, v66
	s_movk_i32 s0, 0x2400
	v_cmp_gt_i32_e64 s[38:39], s0, v0
	s_mov_b64 s[0:1], -1
	s_nop 0
	v_cndmask_b32_e64 v104, v66, v0, s[38:39]
	v_ashrrev_i32_e32 v105, 31, v104
	v_lshlrev_b64 v[102:103], 11, v[104:105]
	s_cbranch_vccz .LBB0_1031
	v_add_co_u32_e32 v4, vcc, 0xe6000000, v96
	v_lshl_add_u64 v[2:3], v[102:103], 1, v[70:71]
	s_nop 0
	v_addc_co_u32_e32 v5, vcc, -1, v97, vcc
	v_add_co_u32_e32 v10, vcc, 0xe6000200, v96
	global_load_dwordx2 v[6:7], v[2:3], off
	global_load_dwordx2 v[8:9], v[2:3], off offset:512
	global_load_dwordx2 v[12:13], v[2:3], off offset:1024
	v_addc_co_u32_e32 v11, vcc, -1, v97, vcc
	v_add_co_u32_e32 v16, vcc, 0xe6000400, v96
	global_load_dwordx2 v[14:15], v[2:3], off offset:1536
	s_nop 0
	global_load_dwordx2 v[4:5], v[4:5], off
	s_nop 0
	global_load_dwordx2 v[10:11], v[10:11], off
	v_addc_co_u32_e32 v17, vcc, -1, v97, vcc
	v_add_co_u32_e32 v18, vcc, 0xe6000600, v96
	global_load_dwordx2 v[16:17], v[16:17], off
	s_nop 0
	v_addc_co_u32_e32 v19, vcc, -1, v97, vcc
	v_add_co_u32_e32 v20, vcc, 0xe6000800, v96
	global_load_dwordx2 v[18:19], v[18:19], off
	s_nop 0
	v_addc_co_u32_e32 v21, vcc, -1, v97, vcc
	v_add_co_u32_e32 v22, vcc, 0xe6000a00, v96
	global_load_dwordx2 v[20:21], v[20:21], off
	s_nop 0
	global_load_dwordx2 v[30:31], v[2:3], off offset:2048
	v_addc_co_u32_e32 v23, vcc, -1, v97, vcc
	global_load_dwordx2 v[32:33], v[22:23], off
	global_load_dwordx2 v[106:107], v[2:3], off offset:2560
	v_add_co_u32_e32 v22, vcc, 0xe6000c00, v96
	s_mov_b64 s[0:1], 0
	s_nop 0
	v_addc_co_u32_e32 v23, vcc, -1, v97, vcc
	global_load_dwordx2 v[108:109], v[22:23], off
	global_load_dwordx2 v[110:111], v[2:3], off offset:3072
	v_add_co_u32_e32 v22, vcc, 0xe6000e00, v96
	s_waitcnt lgkmcnt(0)
	s_waitcnt vmcnt(13)
	v_lshlrev_b32_e32 v58, 16, v6
	v_addc_co_u32_e32 v23, vcc, -1, v97, vcc
	global_load_dwordx2 v[112:113], v[22:23], off
	global_load_dwordx2 v[114:115], v[2:3], off offset:3584
	v_and_b32_e32 v59, 0xffff0000, v6
	v_lshlrev_b32_e32 v60, 16, v7
	v_and_b32_e32 v61, 0xffff0000, v7
	s_waitcnt vmcnt(14)
	v_lshlrev_b32_e32 v50, 16, v8
	v_and_b32_e32 v51, 0xffff0000, v8
	v_lshlrev_b32_e32 v52, 16, v9
	v_and_b32_e32 v53, 0xffff0000, v9
	s_waitcnt vmcnt(13)
	v_lshlrev_b32_e32 v42, 16, v12
	v_and_b32_e32 v43, 0xffff0000, v12
	v_lshlrev_b32_e32 v44, 16, v13
	v_and_b32_e32 v45, 0xffff0000, v13
	s_waitcnt vmcnt(12)
	v_lshlrev_b32_e32 v22, 16, v14
	s_waitcnt vmcnt(11)
	v_lshlrev_b32_e32 v62, 16, v4
	v_and_b32_e32 v63, 0xffff0000, v4
	v_lshlrev_b32_e32 v64, 16, v5
	v_and_b32_e32 v65, 0xffff0000, v5
	s_waitcnt vmcnt(10)
	v_lshlrev_b32_e32 v54, 16, v10
	v_and_b32_e32 v55, 0xffff0000, v10
	v_lshlrev_b32_e32 v56, 16, v11
	v_and_b32_e32 v57, 0xffff0000, v11
	s_waitcnt vmcnt(9)
	v_lshlrev_b32_e32 v46, 16, v16
	v_and_b32_e32 v47, 0xffff0000, v16
	v_lshlrev_b32_e32 v48, 16, v17
	v_and_b32_e32 v49, 0xffff0000, v17
	s_waitcnt vmcnt(8)
	v_lshlrev_b32_e32 v26, 16, v18
	v_and_b32_e32 v27, 0xffff0000, v18
	v_lshlrev_b32_e32 v28, 16, v19
	v_and_b32_e32 v29, 0xffff0000, v19
	v_and_b32_e32 v23, 0xffff0000, v14
	v_lshlrev_b32_e32 v24, 16, v15
	v_and_b32_e32 v25, 0xffff0000, v15
	s_waitcnt vmcnt(7)
	v_lshlrev_b32_e32 v34, 16, v20
	v_and_b32_e32 v35, 0xffff0000, v20
	v_lshlrev_b32_e32 v36, 16, v21
	v_and_b32_e32 v37, 0xffff0000, v21
	s_waitcnt vmcnt(6)
	v_lshlrev_b32_e32 v38, 16, v30
	v_and_b32_e32 v39, 0xffff0000, v30
	v_lshlrev_b32_e32 v40, 16, v31
	v_and_b32_e32 v41, 0xffff0000, v31
	s_waitcnt vmcnt(5)
	v_lshlrev_b32_e32 v14, 16, v32
	v_and_b32_e32 v15, 0xffff0000, v32
	v_lshlrev_b32_e32 v16, 16, v33
	v_and_b32_e32 v17, 0xffff0000, v33
	s_waitcnt vmcnt(4)
	v_lshlrev_b32_e32 v30, 16, v106
	v_and_b32_e32 v31, 0xffff0000, v106
	v_lshlrev_b32_e32 v32, 16, v107
	v_and_b32_e32 v33, 0xffff0000, v107
	s_waitcnt vmcnt(3)
	v_lshlrev_b32_e32 v6, 16, v108
	v_and_b32_e32 v7, 0xffff0000, v108
	v_lshlrev_b32_e32 v8, 16, v109
	v_and_b32_e32 v9, 0xffff0000, v109
	s_waitcnt vmcnt(2)
	v_lshlrev_b32_e32 v18, 16, v110
	v_and_b32_e32 v19, 0xffff0000, v110
	v_lshlrev_b32_e32 v20, 16, v111
	v_and_b32_e32 v21, 0xffff0000, v111
	s_waitcnt lgkmcnt(0)
	s_waitcnt vmcnt(1)
	v_lshlrev_b32_e32 v2, 16, v112
	v_and_b32_e32 v3, 0xffff0000, v112
	v_lshlrev_b32_e32 v4, 16, v113
	v_and_b32_e32 v5, 0xffff0000, v113
	s_waitcnt vmcnt(0)
	v_lshlrev_b32_e32 v10, 16, v114
	v_and_b32_e32 v11, 0xffff0000, v114
	v_lshlrev_b32_e32 v12, 16, v115
	v_and_b32_e32 v13, 0xffff0000, v115

; __device__ __forceinline__ float bflo(unsigned w) { return __uint_as_float(w << 16); }
; __device__ __forceinline__ float bfhi(unsigned w) { return __uint_as_float(w & 0xffff0000u); }
; __device__ __forceinline__ void ln_phase(const Params& p, const int layer, const int row_lo, const int row_hi, const int wg_id, const int n_wg) {
;     ...
;             for (int j = 0; j < 8; ++j) { a0[j] = xb0[64 * j]; a1[j] = xb1[64 * j]; w0[j] = ob0[64 * j]; w1[j] = ob1[64 * j]; }
;     ...
;         for (int j = 0; j < 8; ++j) { v0[j] = v0[j] * DN_ALPHA + (f32x4){bflo(w0[j].x), bfhi(w0[j].x), bflo(w0[j].y), bfhi(w0[j].y)};
;             v1[j] = v1[j] * DN_ALPHA + (f32x4){bflo(w1[j].x), bfhi(w1[j].x), bflo(w1[j].y), bfhi(w1[j].y)};
;             s0 += (v0[j].x + v0[j].y) + (v0[j].z + v0[j].w); s1 += (v1[j].x + v1[j].y) + (v1[j].z + v1[j].w); }
.LBB0_1033:
	v_lshlrev_b64 v[104:105], 1, v[102:103]
	v_lshl_add_u64 v[110:111], v[68:69], 0, v[104:105]
	global_load_dwordx2 v[118:119], v[96:97], off offset:3584
	global_load_dwordx2 v[120:121], v[96:97], off offset:3072
	global_load_dwordx2 v[122:123], v[96:97], off offset:2560
	global_load_dwordx2 v[126:127], v[96:97], off offset:2048
	global_load_dwordx2 v[130:131], v[96:97], off offset:1536
	global_load_dwordx2 v[106:107], v[96:97], off offset:1024
	global_load_dwordx2 v[138:139], v[96:97], off offset:512
	global_load_dwordx2 v[112:113], v[96:97], off
	global_load_dwordx2 v[140:141], v[110:111], off
	global_load_dwordx2 v[148:149], v[110:111], off offset:512
	global_load_dwordx2 v[108:109], v[110:111], off offset:1024
	global_load_dwordx2 v[136:137], v[110:111], off offset:1536
	global_load_dwordx2 v[134:135], v[110:111], off offset:2048
	global_load_dwordx2 v[132:133], v[110:111], off offset:2560
	global_load_dwordx2 v[128:129], v[110:111], off offset:3072
	global_load_dwordx2 v[124:125], v[110:111], off offset:3584
	s_mov_b32 s2, 0xf800000
	v_lshl_add_u64 v[102:103], v[102:103], 2, v[72:73]
	s_waitcnt lgkmcnt(0)
	s_waitcnt vmcnt(8)
	v_lshlrev_b32_e32 v110, 16, v112
	v_and_b32_e32 v111, 0xffff0000, v112
	v_lshlrev_b32_e32 v112, 16, v113
	v_and_b32_e32 v113, 0xffff0000, v113
	v_pk_fma_f32 v[114:115], v[64:65], s[4:5], v[112:113] op_sel_hi:[1,0,1]
	v_pk_fma_f32 v[116:117], v[62:63], s[4:5], v[110:111] op_sel_hi:[1,0,1]
	s_waitcnt vmcnt(7)
	v_lshlrev_b32_e32 v62, 16, v140
	v_and_b32_e32 v63, 0xffff0000, v140
	v_lshlrev_b32_e32 v64, 16, v141
	v_and_b32_e32 v65, 0xffff0000, v141
	v_pk_fma_f32 v[110:111], v[60:61], s[4:5], v[64:65] op_sel_hi:[1,0,1]
	v_pk_fma_f32 v[112:113], v[58:59], s[4:5], v[62:63] op_sel_hi:[1,0,1]
	v_lshlrev_b32_e32 v58, 16, v138
	v_and_b32_e32 v59, 0xffff0000, v138
	v_lshlrev_b32_e32 v60, 16, v139
	v_and_b32_e32 v61, 0xffff0000, v139
	v_pk_fma_f32 v[56:57], v[56:57], s[4:5], v[60:61] op_sel_hi:[1,0,1]
	v_pk_fma_f32 v[54:55], v[54:55], s[4:5], v[58:59] op_sel_hi:[1,0,1]
	s_waitcnt vmcnt(6)
	v_lshlrev_b32_e32 v58, 16, v148
	v_and_b32_e32 v59, 0xffff0000, v148
	v_lshlrev_b32_e32 v60, 16, v149
	v_and_b32_e32 v61, 0xffff0000, v149
	v_pk_fma_f32 v[52:53], v[52:53], s[4:5], v[60:61] op_sel_hi:[1,0,1]
	v_pk_fma_f32 v[50:51], v[50:51], s[4:5], v[58:59] op_sel_hi:[1,0,1]
	v_mov_b32_e32 v58, v54
	v_mov_b32_e32 v59, v116
	v_mov_b32_e32 v60, v55
	v_mov_b32_e32 v61, v117
	v_pk_add_f32 v[58:59], v[58:59], v[60:61]
	v_mov_b32_e32 v60, v57
	v_mov_b32_e32 v61, v115
	v_mov_b32_e32 v62, v56
	v_mov_b32_e32 v63, v114
	v_pk_add_f32 v[60:61], v[60:61], v[62:63]
	v_mov_b32_e32 v62, v111
	v_pk_add_f32 v[58:59], v[58:59], v[60:61]
	v_mov_b32_e32 v60, v113
	v_add_f32_e32 v0, 0, v59
	v_add_f32_e32 v139, v58, v0
	v_mov_b32_e32 v58, v112
	v_mov_b32_e32 v59, v50
	v_mov_b32_e32 v61, v51
	v_pk_add_f32 v[58:59], v[58:59], v[60:61]
	v_mov_b32_e32 v60, v110
	v_mov_b32_e32 v61, v52
	v_mov_b32_e32 v63, v53
	v_pk_add_f32 v[60:61], v[60:61], v[62:63]
	s_nop 0
	v_pk_add_f32 v[58:59], v[58:59], v[60:61]
	v_lshlrev_b32_e32 v60, 16, v107
	v_add_f32_e32 v0, 0, v58
	v_add_f32_e32 v140, v0, v59
	v_lshlrev_b32_e32 v58, 16, v106
	v_and_b32_e32 v59, 0xffff0000, v106
	v_and_b32_e32 v61, 0xffff0000, v107
	v_pk_fma_f32 v[46:47], v[46:47], s[4:5], v[58:59] op_sel_hi:[1,0,1]
	v_pk_fma_f32 v[48:49], v[48:49], s[4:5], v[60:61] op_sel_hi:[1,0,1]
	s_waitcnt vmcnt(5)
	v_lshlrev_b32_e32 v58, 16, v108
	v_and_b32_e32 v59, 0xffff0000, v108
	v_lshlrev_b32_e32 v60, 16, v109
	v_and_b32_e32 v61, 0xffff0000, v109
	v_pk_fma_f32 v[108:109], v[44:45], s[4:5], v[60:61] op_sel_hi:[1,0,1]
	v_pk_fma_f32 v[106:107], v[42:43], s[4:5], v[58:59] op_sel_hi:[1,0,1]
	v_mov_b32_e32 v42, v46
	v_mov_b32_e32 v43, v49
	v_pk_mov_b32 v[44:45], v[46:47], v[48:49] op_sel:[1,0]
	s_nop 0
	v_pk_add_f32 v[42:43], v[42:43], v[44:45]
	v_mov_b32_e32 v44, v106
	v_pk_add_f32 v[148:149], v[42:43], v[42:43] op_sel_hi:[0,1]
	v_pk_mov_b32 v[42:43], v[106:107], v[108:109] op_sel:[1,0]
	v_mov_b32_e32 v45, v109
	v_pk_add_f32 v[42:43], v[42:43], v[44:45]
	v_lshlrev_b32_e32 v44, 16, v131
	v_pk_add_f32 v[150:151], v[42:43], v[42:43] op_sel:[0,1] op_sel_hi:[1,0]
	v_lshlrev_b32_e32 v42, 16, v130
	v_and_b32_e32 v43, 0xffff0000, v130
	v_and_b32_e32 v45, 0xffff0000, v131
	v_pk_fma_f32 v[64:65], v[28:29], s[4:5], v[44:45] op_sel_hi:[1,0,1]
	v_pk_fma_f32 v[62:63], v[26:27], s[4:5], v[42:43] op_sel_hi:[1,0,1]
	v_lshlrev_b32_e32 v42, 16, v126
	v_and_b32_e32 v43, 0xffff0000, v126
	v_lshlrev_b32_e32 v44, 16, v127
	v_and_b32_e32 v45, 0xffff0000, v127
	s_waitcnt vmcnt(4)
	v_lshlrev_b32_e32 v26, 16, v136
	v_and_b32_e32 v27, 0xffff0000, v136
	v_lshlrev_b32_e32 v28, 16, v137
	v_and_b32_e32 v29, 0xffff0000, v137
	v_pk_fma_f32 v[44:45], v[36:37], s[4:5], v[44:45] op_sel_hi:[1,0,1]
	v_pk_fma_f32 v[42:43], v[34:35], s[4:5], v[42:43] op_sel_hi:[1,0,1]
	v_pk_fma_f32 v[60:61], v[24:25], s[4:5], v[28:29] op_sel_hi:[1,0,1]
	v_pk_fma_f32 v[58:59], v[22:23], s[4:5], v[26:27] op_sel_hi:[1,0,1]
	v_add_f32_e32 v23, v62, v63
	v_add_f32_e32 v25, v65, v64
	s_waitcnt vmcnt(3)
; __device__ __forceinline__ void ln_phase(const Params& p, const int layer, const int row_lo, const int row_hi, const int wg_id, const int n_wg) {
;     ...
;             s0 += (v0[j].x + v0[j].y) + (v0[j].z + v0[j].w); s1 += (v1[j].x + v1[j].y) + (v1[j].z + v1[j].w); }
;         const float mean0 = wave_sum(s0) * (1.f / DM), mean1 = wave_sum(s1) * (1.f / DM); float q0 = 0.f, q1 = 0.f;
; #pragma unroll
;         for (int j = 0; j < 8; ++j) { v0[j] = v0[j] - mean0; v1[j] = v1[j] - mean1;
	v_lshlrev_b32_e32 v34, 16, v134
	v_and_b32_e32 v35, 0xffff0000, v134
	v_lshlrev_b32_e32 v36, 16, v135
	v_and_b32_e32 v37, 0xffff0000, v135
	v_mov_b32_e32 v22, v42
	v_mov_b32_e32 v24, v43
	v_mov_b32_e32 v148, v45
	v_mov_b32_e32 v138, v44
	v_pk_fma_f32 v[40:41], v[40:41], s[4:5], v[36:37] op_sel_hi:[1,0,1]
	v_pk_fma_f32 v[38:39], v[38:39], s[4:5], v[34:35] op_sel_hi:[1,0,1]
	v_pk_add_f32 v[22:23], v[22:23], v[24:25]
	v_pk_add_f32 v[24:25], v[148:149], v[138:139]
	v_add_f32_e32 v26, v58, v59
	v_add_f32_e32 v28, v60, v61
	v_pk_add_f32 v[22:23], v[22:23], v[24:25]
	v_mov_b32_e32 v141, v38
	v_mov_b32_e32 v151, v39
	v_mov_b32_e32 v27, v40
	v_mov_b32_e32 v29, v41
	v_pk_add_f32 v[126:127], v[22:23], v[22:23] op_sel_hi:[0,1]
	v_pk_add_f32 v[22:23], v[140:141], v[150:151]
	v_pk_add_f32 v[24:25], v[26:27], v[28:29]
	s_nop 0
	v_pk_add_f32 v[22:23], v[22:23], v[24:25]
	v_lshlrev_b32_e32 v24, 16, v123
	v_pk_add_f32 v[130:131], v[22:23], v[22:23] op_sel:[0,1] op_sel_hi:[1,0]
	v_lshlrev_b32_e32 v22, 16, v122
	v_and_b32_e32 v23, 0xffff0000, v122
	v_and_b32_e32 v25, 0xffff0000, v123
	v_pk_fma_f32 v[34:35], v[14:15], s[4:5], v[22:23] op_sel_hi:[1,0,1]
	v_pk_fma_f32 v[36:37], v[16:17], s[4:5], v[24:25] op_sel_hi:[1,0,1]
	s_waitcnt vmcnt(2)
	v_lshlrev_b32_e32 v14, 16, v132
	v_and_b32_e32 v15, 0xffff0000, v132
	v_lshlrev_b32_e32 v16, 16, v133
	v_and_b32_e32 v17, 0xffff0000, v133
	v_pk_fma_f32 v[32:33], v[32:33], s[4:5], v[16:17] op_sel_hi:[1,0,1]
	v_pk_fma_f32 v[30:31], v[30:31], s[4:5], v[14:15] op_sel_hi:[1,0,1]
	v_mov_b32_e32 v14, v34
	v_mov_b32_e32 v15, v37
	v_pk_mov_b32 v[16:17], v[34:35], v[36:37] op_sel:[1,0]
	s_nop 0
	v_pk_add_f32 v[14:15], v[14:15], v[16:17]
	v_mov_b32_e32 v16, v30
	v_pk_add_f32 v[122:123], v[14:15], v[14:15] op_sel_hi:[0,1]
	v_pk_mov_b32 v[14:15], v[30:31], v[32:33] op_sel:[1,0]
	v_mov_b32_e32 v17, v33
	v_pk_add_f32 v[14:15], v[14:15], v[16:17]
	v_lshlrev_b32_e32 v16, 16, v121
	v_pk_add_f32 v[132:133], v[14:15], v[14:15] op_sel:[0,1] op_sel_hi:[1,0]
	v_lshlrev_b32_e32 v14, 16, v120
	v_and_b32_e32 v15, 0xffff0000, v120
	v_and_b32_e32 v17, 0xffff0000, v121
	v_pk_fma_f32 v[28:29], v[8:9], s[4:5], v[16:17] op_sel_hi:[1,0,1]
	v_pk_fma_f32 v[26:27], v[6:7], s[4:5], v[14:15] op_sel_hi:[1,0,1]
	s_waitcnt vmcnt(1)
	v_lshlrev_b32_e32 v8, 16, v129
	v_and_b32_e32 v9, 0xffff0000, v129
	v_lshlrev_b32_e32 v16, 16, v118
	v_and_b32_e32 v17, 0xffff0000, v118
	v_lshlrev_b32_e32 v14, 16, v119
	v_and_b32_e32 v15, 0xffff0000, v119
	v_lshlrev_b32_e32 v6, 16, v128
	v_and_b32_e32 v7, 0xffff0000, v128
	v_pk_fma_f32 v[24:25], v[20:21], s[4:5], v[8:9] op_sel_hi:[1,0,1]
	v_pk_fma_f32 v[14:15], v[4:5], s[4:5], v[14:15] op_sel_hi:[1,0,1]
	v_pk_fma_f32 v[20:21], v[2:3], s[4:5], v[16:17] op_sel_hi:[1,0,1]
	v_pk_fma_f32 v[22:23], v[18:19], s[4:5], v[6:7] op_sel_hi:[1,0,1]
	v_add_f32_e32 v7, v26, v27
	v_add_f32_e32 v9, v29, v28
	s_waitcnt vmcnt(0)
	v_lshlrev_b32_e32 v2, 16, v124
	v_and_b32_e32 v3, 0xffff0000, v124
	v_lshlrev_b32_e32 v4, 16, v125
	v_and_b32_e32 v5, 0xffff0000, v125
	v_mov_b32_e32 v6, v20
	v_mov_b32_e32 v8, v21
	v_mov_b32_e32 v122, v15
	v_mov_b32_e32 v126, v14
	v_pk_fma_f32 v[16:17], v[12:13], s[4:5], v[4:5] op_sel_hi:[1,0,1]
	v_pk_fma_f32 v[18:19], v[10:11], s[4:5], v[2:3] op_sel_hi:[1,0,1]
	v_pk_add_f32 v[2:3], v[6:7], v[8:9]
	v_pk_add_f32 v[4:5], v[122:123], v[126:127]
	v_add_f32_e32 v120, v22, v23
	v_add_f32_e32 v128, v24, v25
	v_pk_add_f32 v[2:3], v[2:3], v[4:5]
	v_mov_b32_e32 v131, v18
	v_mov_b32_e32 v133, v19
	v_mov_b32_e32 v121, v16
	v_mov_b32_e32 v129, v17
	v_add_f32_e32 v0, v2, v3
	v_pk_add_f32 v[2:3], v[130:131], v[132:133]
	v_pk_add_f32 v[4:5], v[120:121], v[128:129]
	s_nop 0
	v_pk_add_f32 v[2:3], v[2:3], v[4:5]
	s_nop 0
	v_add_f32_e32 v2, v2, v3
	ds_bpermute_b32 v3, v142, v0
	s_waitcnt lgkmcnt(0)
	v_add_f32_e32 v0, v0, v3
	ds_bpermute_b32 v3, v143, v0
	s_waitcnt lgkmcnt(0)
	v_add_f32_e32 v0, v0, v3
	ds_bpermute_b32 v3, v144, v0
	s_waitcnt lgkmcnt(0)
	v_add_f32_e32 v0, v0, v3
	ds_bpermute_b32 v3, v145, v0
	s_waitcnt lgkmcnt(0)
	v_add_f32_e32 v0, v0, v3
	ds_bpermute_b32 v3, v146, v0
	s_waitcnt lgkmcnt(0)
	v_add_f32_e32 v0, v0, v3
	ds_bpermute_b32 v3, v147, v0
	s_waitcnt lgkmcnt(0)
	v_add_f32_e32 v67, v0, v3
	ds_bpermute_b32 v0, v142, v2
	v_fmamk_f32 v117, v67, 0xba000000, v117
	v_fmac_f32_e32 v116, 0xba000000, v67
	v_fmamk_f32 v119, v67, 0xba000000, v55
	v_fmac_f32_e32 v54, 0xba000000, v67
	s_waitcnt lgkmcnt(0)
	v_add_f32_e32 v0, v2, v0
	ds_bpermute_b32 v2, v143, v0
	v_mov_b32_e32 v118, v117
	v_fmac_f32_e32 v114, 0xba000000, v67
	v_fmac_f32_e32 v56, 0xba000000, v67
	v_mov_b32_e32 v3, v54
	s_waitcnt lgkmcnt(0)
	v_add_f32_e32 v0, v0, v2
	ds_bpermute_b32 v2, v144, v0
	v_pk_mul_f32 v[4:5], v[118:119], v[118:119]
	v_fmamk_f32 v115, v67, 0xba000000, v115
	v_fmamk_f32 v127, v67, 0xba000000, v57
	v_mov_b32_e32 v126, v115
	s_waitcnt lgkmcnt(0)
	v_add_f32_e32 v0, v0, v2
	ds_bpermute_b32 v2, v145, v0
	v_fmamk_f32 v49, v67, 0xba000000, v49
	v_fmac_f32_e32 v48, 0xba000000, v67
	v_fmamk_f32 v47, v67, 0xba000000, v47
	v_fmac_f32_e32 v46, 0xba000000, v67
	s_waitcnt lgkmcnt(0)
	v_add_f32_e32 v0, v0, v2
	ds_bpermute_b32 v2, v146, v0
	v_fmac_f32_e32 v62, 0xba000000, v67
	v_fmac_f32_e32 v64, 0xba000000, v67
	v_fmamk_f32 v63, v67, 0xba000000, v63
	v_fmamk_f32 v65, v67, 0xba000000, v65
	s_waitcnt lgkmcnt(0)
	v_add_f32_e32 v0, v0, v2
	ds_bpermute_b32 v2, v147, v0
	v_fmamk_f32 v45, v67, 0xba000000, v45
	v_fmac_f32_e32 v44, 0xba000000, v67
	v_fmamk_f32 v43, v67, 0xba000000, v43
	v_fmac_f32_e32 v42, 0xba000000, v67
	s_waitcnt lgkmcnt(0)
; __device__ __forceinline__ void ln_phase(const Params& p, const int layer, const int row_lo, const int row_hi, const int wg_id, const int n_wg) {
;     ...
;         for (int j = 0; j < 8; ++j) { v0[j] = v0[j] - mean0; v1[j] = v1[j] - mean1;
;             q0 += (v0[j].x * v0[j].x + v0[j].y * v0[j].y) + (v0[j].z * v0[j].z + v0[j].w * v0[j].w); q1 += (v1[j].x * v1[j].x + v1[j].y * v1[j].y) + (v1[j].z * v1[j].z + v1[j].w * v1[j].w); }
	v_add_f32_e32 v99, v0, v2
	v_mov_b32_e32 v2, v116
	v_pk_fma_f32 v[2:3], v[2:3], v[2:3], v[4:5]
	v_mov_b32_e32 v4, v114
	v_mov_b32_e32 v5, v56
	v_fmamk_f32 v113, v99, 0xba000000, v113
	v_pk_mul_f32 v[4:5], v[4:5], v[4:5]
	v_fmamk_f32 v111, v99, 0xba000000, v111
	v_fmac_f32_e32 v112, 0xba000000, v99
	v_fmamk_f32 v123, v99, 0xba000000, v51
	v_fmac_f32_e32 v50, 0xba000000, v99
	v_pk_fma_f32 v[4:5], v[126:127], v[126:127], v[4:5]
	v_mov_b32_e32 v122, v113
	v_fmac_f32_e32 v110, 0xba000000, v99
	v_fmamk_f32 v125, v99, 0xba000000, v53
	v_fmac_f32_e32 v52, 0xba000000, v99
	v_pk_add_f32 v[2:3], v[2:3], v[4:5]
	v_mov_b32_e32 v4, v112
	v_mov_b32_e32 v5, v50
	v_pk_mul_f32 v[6:7], v[122:123], v[122:123]
	v_mov_b32_e32 v124, v111
	v_pk_fma_f32 v[4:5], v[4:5], v[4:5], v[6:7]
	v_mov_b32_e32 v6, v110
	v_mov_b32_e32 v7, v52
	v_pk_mul_f32 v[8:9], v[124:125], v[124:125]
	v_fmamk_f32 v109, v99, 0xba000000, v109
	v_pk_fma_f32 v[6:7], v[6:7], v[6:7], v[8:9]
	v_pk_mul_f32 v[8:9], v[46:47], v[46:47]
	v_pk_add_f32 v[4:5], v[4:5], v[6:7]
	v_pk_mul_f32 v[6:7], v[48:49], v[48:49]
	v_fmac_f32_e32 v108, 0xba000000, v99
	v_fmamk_f32 v107, v99, 0xba000000, v107
	v_fmac_f32_e32 v106, 0xba000000, v99
	v_pk_mov_b32 v[10:11], v[8:9], v[6:7] op_sel:[1,0]
	v_mov_b32_e32 v9, v7
	v_pk_add_f32 v[6:7], v[8:9], v[10:11]
	v_pk_mul_f32 v[8:9], v[108:109], v[108:109]
	v_pk_mul_f32 v[10:11], v[106:107], v[106:107]
	v_mul_f32_e32 v0, v62, v62
	v_pk_mov_b32 v[12:13], v[10:11], v[8:9] op_sel:[1,0]
	v_mov_b32_e32 v11, v9
	v_pk_add_f32 v[8:9], v[12:13], v[10:11]
	v_fmac_f32_e32 v58, 0xba000000, v99
	v_pk_fma_f32 v[10:11], v[62:63], v[62:63], v[0:1] op_sel_hi:[1,1,0]
	v_mul_f32_e32 v0, v64, v64
	v_fmac_f32_e32 v60, 0xba000000, v99
	v_fmamk_f32 v59, v99, 0xba000000, v59
	v_pk_fma_f32 v[12:13], v[64:65], v[64:65], v[0:1] op_sel_hi:[1,1,0]
	v_mul_f32_e32 v0, v58, v58
	v_fmamk_f32 v61, v99, 0xba000000, v61
	v_pk_fma_f32 v[120:121], v[58:59], v[58:59], v[0:1] op_sel_hi:[1,1,0]
	v_mul_f32_e32 v0, v60, v60
	v_pk_add_f32 v[2:3], v[2:3], v[2:3] op_sel_hi:[0,1]
	v_pk_add_f32 v[4:5], v[4:5], v[4:5] op_sel_hi:[0,1]
	v_pk_add_f32 v[6:7], v[6:7], v[6:7] op_sel_hi:[0,1]
	v_pk_add_f32 v[8:9], v[8:9], v[8:9] op_sel_hi:[0,1]
	v_pk_fma_f32 v[128:129], v[60:61], v[60:61], v[0:1] op_sel_hi:[1,1,0]
	v_fmamk_f32 v41, v99, 0xba000000, v41
	v_fmac_f32_e32 v40, 0xba000000, v99
	v_fmamk_f32 v39, v99, 0xba000000, v39
	v_fmac_f32_e32 v38, 0xba000000, v99
	v_mul_f32_e32 v2, v44, v44
	v_mul_f32_e32 v6, v45, v45
	v_mul_f32_e32 v120, v38, v38
	v_mul_f32_e32 v128, v39, v39
	v_mul_f32_e32 v8, v40, v40
	v_mul_f32_e32 v4, v41, v41
	v_mul_f32_e32 v10, v42, v42
	v_mul_f32_e32 v12, v43, v43
	v_pk_add_f32 v[2:3], v[6:7], v[2:3]
	v_pk_add_f32 v[6:7], v[120:121], v[128:129]
	v_pk_add_f32 v[4:5], v[8:9], v[4:5]
	v_fmamk_f32 v37, v67, 0xba000000, v37
	v_fmac_f32_e32 v36, 0xba000000, v67
	v_fmamk_f32 v35, v67, 0xba000000, v35
	v_fmac_f32_e32 v34, 0xba000000, v67
	v_pk_add_f32 v[10:11], v[10:11], v[12:13]
	v_pk_add_f32 v[4:5], v[6:7], v[4:5]
	v_pk_mul_f32 v[6:7], v[36:37], v[36:37]
	v_pk_mul_f32 v[8:9], v[34:35], v[34:35]
	v_pk_add_f32 v[2:3], v[10:11], v[2:3]
	v_fmamk_f32 v33, v99, 0xba000000, v33
	v_fmac_f32_e32 v32, 0xba000000, v99
	v_fmamk_f32 v31, v99, 0xba000000, v31
	v_fmac_f32_e32 v30, 0xba000000, v99
	v_pk_mov_b32 v[10:11], v[8:9], v[6:7] op_sel:[1,0]
	v_mov_b32_e32 v9, v7
	v_pk_add_f32 v[6:7], v[8:9], v[10:11]
	v_pk_mul_f32 v[8:9], v[32:33], v[32:33]
	v_pk_mul_f32 v[10:11], v[30:31], v[30:31]
	v_fmac_f32_e32 v26, 0xba000000, v67
	v_pk_mov_b32 v[12:13], v[10:11], v[8:9] op_sel:[1,0]
	v_mov_b32_e32 v11, v9
	v_fmac_f32_e32 v28, 0xba000000, v67
	v_fmamk_f32 v27, v67, 0xba000000, v27
	v_mul_f32_e32 v0, v26, v26
	v_pk_add_f32 v[8:9], v[12:13], v[10:11]
	v_fmamk_f32 v29, v67, 0xba000000, v29
	v_fmac_f32_e32 v22, 0xba000000, v99
	v_pk_fma_f32 v[10:11], v[26:27], v[26:27], v[0:1] op_sel_hi:[1,1,0]
	v_mul_f32_e32 v0, v28, v28
	v_pk_add_f32 v[2:3], v[2:3], v[2:3] op_sel_hi:[0,1]
	v_pk_add_f32 v[6:7], v[6:7], v[6:7] op_sel_hi:[0,1]
	v_fmac_f32_e32 v24, 0xba000000, v99
	v_fmamk_f32 v23, v99, 0xba000000, v23
	v_pk_fma_f32 v[12:13], v[28:29], v[28:29], v[0:1] op_sel_hi:[1,1,0]
	v_mul_f32_e32 v0, v22, v22
	v_fmamk_f32 v15, v67, 0xba000000, v15
	v_fmac_f32_e32 v14, 0xba000000, v67
	v_fmamk_f32 v21, v67, 0xba000000, v21
	v_fmac_f32_e32 v20, 0xba000000, v67
	v_fmamk_f32 v25, v99, 0xba000000, v25
	v_pk_fma_f32 v[120:121], v[22:23], v[22:23], v[0:1] op_sel_hi:[1,1,0]
	v_mul_f32_e32 v0, v24, v24
	v_mul_f32_e32 v10, v20, v20
	v_mul_f32_e32 v12, v21, v21
	v_mul_f32_e32 v2, v14, v14
	v_mul_f32_e32 v6, v15, v15
	v_pk_add_f32 v[4:5], v[4:5], v[4:5] op_sel_hi:[0,1]
	v_pk_add_f32 v[8:9], v[8:9], v[8:9] op_sel_hi:[0,1]
	v_pk_fma_f32 v[128:129], v[24:25], v[24:25], v[0:1] op_sel_hi:[1,1,0]
	v_fmamk_f32 v17, v99, 0xba000000, v17
	v_fmac_f32_e32 v16, 0xba000000, v99
	v_fmamk_f32 v19, v99, 0xba000000, v19
	v_fmac_f32_e32 v18, 0xba000000, v99
	v_pk_add_f32 v[10:11], v[10:11], v[12:13]
	v_pk_add_f32 v[2:3], v[6:7], v[2:3]
	v_mul_f32_e32 v120, v18, v18
	v_pk_add_f32 v[2:3], v[10:11], v[2:3]
	v_mul_f32_e32 v128, v19, v19
	v_mul_f32_e32 v8, v16, v16
	v_mul_f32_e32 v4, v17, v17
	v_add_f32_e32 v0, v2, v3
	v_pk_add_f32 v[2:3], v[120:121], v[128:129]
	v_pk_add_f32 v[4:5], v[8:9], v[4:5]
	v_lshl_add_u64 v[120:121], v[100:101], 0, v[94:95]
	v_pk_add_f32 v[2:3], v[2:3], v[4:5]
	s_nop 0
	v_add_f32_e32 v2, v2, v3
	ds_bpermute_b32 v3, v142, v0
	s_waitcnt lgkmcnt(0)
; __device__ __forceinline__ unsigned pk2(float lo, float hi) { return f2bf(lo) | (f2bf(hi) << 16); }
; __device__ __forceinline__ void ln_phase(const Params& p, const int layer, const int row_lo, const int row_hi, const int wg_id, const int n_wg) {
;     ...
;         const float rstd0 = 1.f / sqrtf(wave_sum(q0) * (1.f / DM) + LN_EPS), rstd1 = 1.f / sqrtf(wave_sum(q1) * (1.f / DM) + LN_EPS);
;         f32x4* zr0 = (f32x4*)(Z + (size_t)m0 * DM) + lane; f32x4* zr1 = (f32x4*)(Z + (size_t)m1 * DM) + lane;
;         unsigned long long* o80 = (unsigned long long*)(XB + (size_t)m0 * DM) + lane; unsigned long long* o81 = (unsigned long long*)(XB + (size_t)m1 * DM) + lane;
; #pragma unroll
;         for (int j = 0; j < 8; ++j) { const f32x4 gv = *((const f32x4*)g + lane + 64 * j), bv = *((const f32x4*)bb + lane + 64 * j);
;             const f32x4 y0 = v0[j] * rstd0 * gv + bv, y1 = v1[j] * rstd1 * gv + bv;
;             if (layer == 0) { o80[64 * j] = (unsigned long long)pk2(y0.x, y0.y) | ((unsigned long long)pk2(y0.z, y0.w) << 32);
;                 if (ok1) o81[64 * j] = (unsigned long long)pk2(y1.x, y1.y) | ((unsigned long long)pk2(y1.z, y1.w) << 32); }
;             else { zr0[64 * j] = y0; if (ok1) zr1[64 * j] = y1; } }
	v_add_f32_e32 v0, v0, v3
	ds_bpermute_b32 v3, v143, v0
	s_waitcnt lgkmcnt(0)
	v_add_f32_e32 v0, v0, v3
	ds_bpermute_b32 v3, v144, v0
	s_waitcnt lgkmcnt(0)
	v_add_f32_e32 v0, v0, v3
	ds_bpermute_b32 v3, v145, v0
	s_waitcnt lgkmcnt(0)
	v_add_f32_e32 v0, v0, v3
	ds_bpermute_b32 v3, v146, v0
	s_waitcnt lgkmcnt(0)
	v_add_f32_e32 v0, v0, v3
	ds_bpermute_b32 v3, v147, v0
	s_waitcnt lgkmcnt(0)
	v_add_f32_e32 v0, v0, v3
	v_fmamk_f32 v0, v0, 0x3a000000, v218
	v_cmp_gt_f32_e32 vcc, s2, v0
	v_mul_f32_e32 v3, 0x4f800000, v0
	s_nop 0
	v_cndmask_b32_e32 v0, v0, v3, vcc
	v_sqrt_f32_e32 v3, v0
	s_nop 0
	v_add_u32_e32 v4, -1, v3
	v_fma_f32 v5, -v4, v3, v0
	v_cmp_ge_f32_e64 s[0:1], 0, v5
	v_add_u32_e32 v5, 1, v3
	s_nop 0
	v_cndmask_b32_e64 v4, v3, v4, s[0:1]
	v_fma_f32 v3, -v5, v3, v0
	v_cmp_lt_f32_e64 s[0:1], 0, v3
	s_nop 1
	v_cndmask_b32_e64 v3, v4, v5, s[0:1]
	v_mul_f32_e32 v4, 0x37800000, v3
	v_cndmask_b32_e32 v3, v3, v4, vcc
	v_cmp_class_f32_e32 vcc, v0, v219
	s_nop 1
	v_cndmask_b32_e32 v0, v3, v0, vcc
	v_div_scale_f32 v3, s[0:1], v0, v0, 1.0
	v_rcp_f32_e32 v4, v3
	s_nop 0
	v_fma_f32 v5, -v3, v4, 1.0
	v_fmac_f32_e32 v4, v5, v4
	v_div_scale_f32 v5, vcc, 1.0, v0, 1.0
	v_mul_f32_e32 v6, v5, v4
	v_fma_f32 v7, -v3, v6, v5
	v_fmac_f32_e32 v6, v7, v4
	v_fma_f32 v3, -v3, v6, v5
	v_div_fmas_f32 v3, v3, v4, v6
	v_div_fixup_f32 v118, v3, v0, 1.0
	ds_bpermute_b32 v0, v142, v2
	v_pk_mul_f32 v[10:11], v[116:117], v[118:119] op_sel_hi:[1,0]
	v_pk_mul_f32 v[12:13], v[114:115], v[118:119] op_sel_hi:[1,0]
	s_waitcnt lgkmcnt(0)
	v_add_f32_e32 v0, v2, v0
	ds_bpermute_b32 v2, v143, v0
	s_waitcnt lgkmcnt(0)
	v_add_f32_e32 v0, v0, v2
	ds_bpermute_b32 v2, v144, v0
	s_waitcnt lgkmcnt(0)
	v_add_f32_e32 v0, v0, v2
	ds_bpermute_b32 v2, v145, v0
	s_waitcnt lgkmcnt(0)
	v_add_f32_e32 v0, v0, v2
	ds_bpermute_b32 v2, v146, v0
	s_waitcnt lgkmcnt(0)
	v_add_f32_e32 v0, v0, v2
	ds_bpermute_b32 v2, v147, v0
	s_waitcnt lgkmcnt(0)
	v_add_f32_e32 v0, v0, v2
	v_fmamk_f32 v0, v0, 0x3a000000, v218
	v_cmp_gt_f32_e32 vcc, s2, v0
	v_mul_f32_e32 v2, 0x4f800000, v0
	s_nop 0
	v_cndmask_b32_e32 v0, v0, v2, vcc
	v_sqrt_f32_e32 v2, v0
	s_nop 0
	v_add_u32_e32 v3, -1, v2
	v_fma_f32 v4, -v3, v2, v0
	v_cmp_ge_f32_e64 s[0:1], 0, v4
	v_add_u32_e32 v4, 1, v2
	s_nop 0
	v_cndmask_b32_e64 v3, v2, v3, s[0:1]
	v_fma_f32 v2, -v4, v2, v0
	v_cmp_lt_f32_e64 s[0:1], 0, v2
	s_nop 1
	v_cndmask_b32_e64 v2, v3, v4, s[0:1]
	v_mul_f32_e32 v3, 0x37800000, v2
	v_cndmask_b32_e32 v2, v2, v3, vcc
	v_cmp_class_f32_e32 vcc, v0, v219
	s_nop 1
	v_cndmask_b32_e32 v0, v2, v0, vcc
	v_div_scale_f32 v2, s[0:1], v0, v0, 1.0
	v_rcp_f32_e32 v3, v2
	s_mov_b64 s[0:1], -1
	v_fma_f32 v4, -v2, v3, 1.0
	v_fmac_f32_e32 v3, v4, v3
	v_div_scale_f32 v4, vcc, 1.0, v0, 1.0
	v_mul_f32_e32 v5, v4, v3
	v_fma_f32 v6, -v2, v5, v4
	v_fmac_f32_e32 v5, v6, v3
	v_fma_f32 v2, -v2, v5, v4
	v_div_fmas_f32 v2, v2, v3, v5
	v_div_fixup_f32 v122, v2, v0, 1.0
	global_load_dwordx4 v[2:5], v[74:75], off
	global_load_dwordx4 v[6:9], v[76:77], off
	v_pk_mul_f32 v[112:113], v[112:113], v[122:123] op_sel_hi:[1,0]
	v_pk_mul_f32 v[110:111], v[110:111], v[122:123] op_sel_hi:[1,0]
	s_and_b64 vcc, exec, s[10:11]
	s_waitcnt vmcnt(0)
	v_pk_fma_f32 v[12:13], v[4:5], v[12:13], v[8:9]
	v_pk_fma_f32 v[10:11], v[2:3], v[10:11], v[6:7]
	v_pk_fma_f32 v[4:5], v[4:5], v[110:111], v[8:9]
	v_pk_fma_f32 v[2:3], v[2:3], v[112:113], v[6:7]
	s_cbranch_vccz .LBB0_1037
	global_store_dwordx4 v[120:121], v[10:13], off
	s_and_saveexec_b64 s[0:1], s[38:39]
	s_cbranch_execz .LBB0_1036
	global_store_dwordx4 v[102:103], v[2:5], off

; __device__ __forceinline__ unsigned pk2(float lo, float hi) { return f2bf(lo) | (f2bf(hi) << 16); }
; __device__ __forceinline__ void ln_phase(const Params& p, const int layer, const int row_lo, const int row_hi, const int wg_id, const int n_wg) {
;     ...
;             if (layer == 0) { o80[64 * j] = (unsigned long long)pk2(y0.x, y0.y) | ((unsigned long long)pk2(y0.z, y0.w) << 32);
;                 if (ok1) o81[64 * j] = (unsigned long long)pk2(y1.x, y1.y) | ((unsigned long long)pk2(y1.z, y1.w) << 32); }
.LBB0_1037:
	s_andn2_b64 vcc, exec, s[0:1]
	v_lshl_add_u64 v[104:105], v[70:71], 0, v[104:105]
	s_cbranch_vccnz .LBB0_1041
	v_bfe_u32 v0, v10, 16, 1
	v_add3_u32 v0, v10, v0, s26
	v_bfe_u32 v6, v11, 16, 1
	v_lshrrev_b32_e32 v0, 16, v0
	v_add3_u32 v6, v11, v6, s26
	v_and_or_b32 v6, v6, s24, v0
	v_bfe_u32 v0, v12, 16, 1
	v_add3_u32 v0, v12, v0, s26
	v_bfe_u32 v7, v13, 16, 1
	v_lshrrev_b32_e32 v0, 16, v0
	v_add3_u32 v7, v13, v7, s26
	v_add_co_u32_e32 v8, vcc, 0xe6000000, v96
	v_and_or_b32 v7, v7, s24, v0
	s_nop 0
	v_addc_co_u32_e32 v9, vcc, -1, v97, vcc
	global_store_dwordx2 v[8:9], v[6:7], off
	s_and_saveexec_b64 s[0:1], s[38:39]
	s_cbranch_execz .LBB0_1040
	v_bfe_u32 v0, v2, 16, 1
	v_add3_u32 v0, v2, v0, s26
	v_bfe_u32 v2, v3, 16, 1
	v_lshrrev_b32_e32 v0, 16, v0
	v_add3_u32 v2, v3, v2, s26
	v_and_or_b32 v2, v2, s24, v0
	v_bfe_u32 v0, v4, 16, 1
	v_add3_u32 v0, v4, v0, s26
	v_bfe_u32 v3, v5, 16, 1
	v_lshrrev_b32_e32 v0, 16, v0
	v_add3_u32 v3, v5, v3, s26
	v_and_or_b32 v3, v3, s24, v0
	global_store_dwordx2 v[104:105], v[2:3], off

; __device__ __forceinline__ unsigned pk2(float lo, float hi) { return f2bf(lo) | (f2bf(hi) << 16); }
; __device__ __forceinline__ void ln_phase(const Params& p, const int layer, const int row_lo, const int row_hi, const int wg_id, const int n_wg) {
;     ...
;             if (layer == 0) { o80[64 * j] = (unsigned long long)pk2(y0.x, y0.y) | ((unsigned long long)pk2(y0.z, y0.w) << 32);
;                 if (ok1) o81[64 * j] = (unsigned long long)pk2(y1.x, y1.y) | ((unsigned long long)pk2(y1.z, y1.w) << 32); }
.LBB0_1045:
	s_andn2_b64 vcc, exec, s[0:1]
	s_cbranch_vccnz .LBB0_1049
	v_bfe_u32 v0, v2, 16, 1
	v_add3_u32 v0, v2, v0, s26
	v_bfe_u32 v2, v3, 16, 1
	v_lshrrev_b32_e32 v0, 16, v0
	v_add3_u32 v2, v3, v2, s26
	v_and_or_b32 v2, v2, s24, v0
	v_bfe_u32 v0, v4, 16, 1
	v_add3_u32 v0, v4, v0, s26
	v_bfe_u32 v3, v5, 16, 1
	v_lshrrev_b32_e32 v0, 16, v0
	v_add3_u32 v3, v5, v3, s26
	v_add_co_u32_e32 v4, vcc, 0xe6000200, v96
	v_and_or_b32 v3, v3, s24, v0
	s_nop 0
	v_addc_co_u32_e32 v5, vcc, -1, v97, vcc
	global_store_dwordx2 v[4:5], v[2:3], off
	s_and_saveexec_b64 s[0:1], s[38:39]
	s_cbranch_execz .LBB0_1048
	v_bfe_u32 v0, v6, 16, 1
	v_add3_u32 v0, v6, v0, s26
	v_bfe_u32 v2, v7, 16, 1
	v_lshrrev_b32_e32 v0, 16, v0
	v_add3_u32 v2, v7, v2, s26
	v_and_or_b32 v2, v2, s24, v0
	v_bfe_u32 v0, v8, 16, 1
	v_add3_u32 v0, v8, v0, s26
	v_bfe_u32 v3, v9, 16, 1
	v_lshrrev_b32_e32 v0, 16, v0
	v_add3_u32 v3, v9, v3, s26
	v_and_or_b32 v3, v3, s24, v0
	global_store_dwordx2 v[104:105], v[2:3], off offset:512

; __device__ __forceinline__ unsigned pk2(float lo, float hi) { return f2bf(lo) | (f2bf(hi) << 16); }
; __device__ __forceinline__ void ln_phase(const Params& p, const int layer, const int row_lo, const int row_hi, const int wg_id, const int n_wg) {
;     ...
;             if (layer == 0) { o80[64 * j] = (unsigned long long)pk2(y0.x, y0.y) | ((unsigned long long)pk2(y0.z, y0.w) << 32);
;                 if (ok1) o81[64 * j] = (unsigned long long)pk2(y1.x, y1.y) | ((unsigned long long)pk2(y1.z, y1.w) << 32); }
.LBB0_1053:
	s_andn2_b64 vcc, exec, s[0:1]
	s_cbranch_vccnz .LBB0_1057
	v_bfe_u32 v0, v6, 16, 1
	v_add3_u32 v0, v6, v0, s26
	v_bfe_u32 v6, v7, 16, 1
	v_lshrrev_b32_e32 v0, 16, v0
	v_add3_u32 v6, v7, v6, s26
	v_and_or_b32 v6, v6, s24, v0
	v_bfe_u32 v0, v8, 16, 1
	v_add3_u32 v0, v8, v0, s26
	v_bfe_u32 v7, v9, 16, 1
	v_lshrrev_b32_e32 v0, 16, v0
	v_add3_u32 v7, v9, v7, s26
	v_add_co_u32_e32 v8, vcc, 0xe6000400, v96
	v_and_or_b32 v7, v7, s24, v0
	s_nop 0
	v_addc_co_u32_e32 v9, vcc, -1, v97, vcc
	global_store_dwordx2 v[8:9], v[6:7], off
	s_and_saveexec_b64 s[0:1], s[38:39]
	s_cbranch_execz .LBB0_1056
	v_bfe_u32 v0, v2, 16, 1
	v_add3_u32 v0, v2, v0, s26
	v_bfe_u32 v2, v3, 16, 1
	v_lshrrev_b32_e32 v0, 16, v0
	v_add3_u32 v2, v3, v2, s26
	v_and_or_b32 v2, v2, s24, v0
	v_bfe_u32 v0, v4, 16, 1
	v_add3_u32 v0, v4, v0, s26
	v_bfe_u32 v3, v5, 16, 1
	v_lshrrev_b32_e32 v0, 16, v0
	v_add3_u32 v3, v5, v3, s26
	v_and_or_b32 v3, v3, s24, v0
	global_store_dwordx2 v[104:105], v[2:3], off offset:1024

; __device__ __forceinline__ unsigned pk2(float lo, float hi) { return f2bf(lo) | (f2bf(hi) << 16); }
; __device__ __forceinline__ void ln_phase(const Params& p, const int layer, const int row_lo, const int row_hi, const int wg_id, const int n_wg) {
;     ...
;             if (layer == 0) { o80[64 * j] = (unsigned long long)pk2(y0.x, y0.y) | ((unsigned long long)pk2(y0.z, y0.w) << 32);
;                 if (ok1) o81[64 * j] = (unsigned long long)pk2(y1.x, y1.y) | ((unsigned long long)pk2(y1.z, y1.w) << 32); }
.LBB0_1061:
	s_andn2_b64 vcc, exec, s[0:1]
	s_cbranch_vccnz .LBB0_1065
	v_bfe_u32 v0, v6, 16, 1
	v_add3_u32 v0, v6, v0, s26
	v_bfe_u32 v6, v7, 16, 1
	v_lshrrev_b32_e32 v0, 16, v0
	v_add3_u32 v6, v7, v6, s26
	v_and_or_b32 v6, v6, s24, v0
	v_bfe_u32 v0, v8, 16, 1
	v_add3_u32 v0, v8, v0, s26
	v_bfe_u32 v7, v9, 16, 1
	v_lshrrev_b32_e32 v0, 16, v0
	v_add3_u32 v7, v9, v7, s26
	v_add_co_u32_e32 v8, vcc, 0xe6000600, v96
	v_and_or_b32 v7, v7, s24, v0
	s_nop 0
	v_addc_co_u32_e32 v9, vcc, -1, v97, vcc
	global_store_dwordx2 v[8:9], v[6:7], off
	s_and_saveexec_b64 s[0:1], s[38:39]
	s_cbranch_execz .LBB0_1064
	v_bfe_u32 v0, v2, 16, 1
	v_add3_u32 v0, v2, v0, s26
	v_bfe_u32 v2, v3, 16, 1
	v_lshrrev_b32_e32 v0, 16, v0
	v_add3_u32 v2, v3, v2, s26
	v_and_or_b32 v2, v2, s24, v0
	v_bfe_u32 v0, v4, 16, 1
	v_add3_u32 v0, v4, v0, s26
	v_bfe_u32 v3, v5, 16, 1
	v_lshrrev_b32_e32 v0, 16, v0
	v_add3_u32 v3, v5, v3, s26
	v_and_or_b32 v3, v3, s24, v0
	global_store_dwordx2 v[104:105], v[2:3], off offset:1536

; __device__ __forceinline__ unsigned pk2(float lo, float hi) { return f2bf(lo) | (f2bf(hi) << 16); }
; __device__ __forceinline__ void ln_phase(const Params& p, const int layer, const int row_lo, const int row_hi, const int wg_id, const int n_wg) {
;     ...
;             if (layer == 0) { o80[64 * j] = (unsigned long long)pk2(y0.x, y0.y) | ((unsigned long long)pk2(y0.z, y0.w) << 32);
;                 if (ok1) o81[64 * j] = (unsigned long long)pk2(y1.x, y1.y) | ((unsigned long long)pk2(y1.z, y1.w) << 32); }
.LBB0_1069:
	s_andn2_b64 vcc, exec, s[0:1]
	s_cbranch_vccnz .LBB0_1073
	v_bfe_u32 v0, v6, 16, 1
	v_add3_u32 v0, v6, v0, s26
	v_bfe_u32 v6, v7, 16, 1
	v_lshrrev_b32_e32 v0, 16, v0
	v_add3_u32 v6, v7, v6, s26
	v_and_or_b32 v6, v6, s24, v0
	v_bfe_u32 v0, v8, 16, 1
	v_add3_u32 v0, v8, v0, s26
	v_bfe_u32 v7, v9, 16, 1
	v_lshrrev_b32_e32 v0, 16, v0
	v_add3_u32 v7, v9, v7, s26
	v_add_co_u32_e32 v8, vcc, 0xe6000800, v96
	v_and_or_b32 v7, v7, s24, v0
	s_nop 0
	v_addc_co_u32_e32 v9, vcc, -1, v97, vcc
	global_store_dwordx2 v[8:9], v[6:7], off
	s_and_saveexec_b64 s[0:1], s[38:39]
	s_cbranch_execz .LBB0_1072
	v_bfe_u32 v0, v2, 16, 1
	v_add3_u32 v0, v2, v0, s26
	v_bfe_u32 v2, v3, 16, 1
	v_lshrrev_b32_e32 v0, 16, v0
	v_add3_u32 v2, v3, v2, s26
	v_and_or_b32 v2, v2, s24, v0
	v_bfe_u32 v0, v4, 16, 1
	v_add3_u32 v0, v4, v0, s26
	v_bfe_u32 v3, v5, 16, 1
	v_lshrrev_b32_e32 v0, 16, v0
	v_add3_u32 v3, v5, v3, s26
	v_and_or_b32 v3, v3, s24, v0
	global_store_dwordx2 v[104:105], v[2:3], off offset:2048

; __device__ __forceinline__ unsigned pk2(float lo, float hi) { return f2bf(lo) | (f2bf(hi) << 16); }
; __device__ __forceinline__ void ln_phase(const Params& p, const int layer, const int row_lo, const int row_hi, const int wg_id, const int n_wg) {
;     ...
;             if (layer == 0) { o80[64 * j] = (unsigned long long)pk2(y0.x, y0.y) | ((unsigned long long)pk2(y0.z, y0.w) << 32);
;                 if (ok1) o81[64 * j] = (unsigned long long)pk2(y1.x, y1.y) | ((unsigned long long)pk2(y1.z, y1.w) << 32); }
.LBB0_1077:
	s_andn2_b64 vcc, exec, s[0:1]
	s_cbranch_vccnz .LBB0_1081
	v_bfe_u32 v0, v6, 16, 1
	v_add3_u32 v0, v6, v0, s26
	v_bfe_u32 v6, v7, 16, 1
	v_lshrrev_b32_e32 v0, 16, v0
	v_add3_u32 v6, v7, v6, s26
	v_and_or_b32 v6, v6, s24, v0
	v_bfe_u32 v0, v8, 16, 1
	v_add3_u32 v0, v8, v0, s26
	v_bfe_u32 v7, v9, 16, 1
	v_lshrrev_b32_e32 v0, 16, v0
	v_add3_u32 v7, v9, v7, s26
	v_add_co_u32_e32 v8, vcc, 0xe6000a00, v96
	v_and_or_b32 v7, v7, s24, v0
	s_nop 0
	v_addc_co_u32_e32 v9, vcc, -1, v97, vcc
	global_store_dwordx2 v[8:9], v[6:7], off
	s_and_saveexec_b64 s[0:1], s[38:39]
	s_cbranch_execz .LBB0_1080
	v_bfe_u32 v0, v2, 16, 1
	v_add3_u32 v0, v2, v0, s26
	v_bfe_u32 v2, v3, 16, 1
	v_lshrrev_b32_e32 v0, 16, v0
	v_add3_u32 v2, v3, v2, s26
	v_and_or_b32 v2, v2, s24, v0
	v_bfe_u32 v0, v4, 16, 1
	v_add3_u32 v0, v4, v0, s26
	v_bfe_u32 v3, v5, 16, 1
	v_lshrrev_b32_e32 v0, 16, v0
	v_add3_u32 v3, v5, v3, s26
	v_and_or_b32 v3, v3, s24, v0
	global_store_dwordx2 v[104:105], v[2:3], off offset:2560

; __device__ __forceinline__ unsigned pk2(float lo, float hi) { return f2bf(lo) | (f2bf(hi) << 16); }
; __device__ __forceinline__ void ln_phase(const Params& p, const int layer, const int row_lo, const int row_hi, const int wg_id, const int n_wg) {
;     ...
;             if (layer == 0) { o80[64 * j] = (unsigned long long)pk2(y0.x, y0.y) | ((unsigned long long)pk2(y0.z, y0.w) << 32);
;                 if (ok1) o81[64 * j] = (unsigned long long)pk2(y1.x, y1.y) | ((unsigned long long)pk2(y1.z, y1.w) << 32); }
.LBB0_1085:
	s_andn2_b64 vcc, exec, s[0:1]
	s_cbranch_vccnz .LBB0_1089
	v_bfe_u32 v0, v6, 16, 1
	v_add3_u32 v0, v6, v0, s26
	v_bfe_u32 v6, v7, 16, 1
	v_lshrrev_b32_e32 v0, 16, v0
	v_add3_u32 v6, v7, v6, s26
	v_and_or_b32 v6, v6, s24, v0
	v_bfe_u32 v0, v8, 16, 1
	v_add3_u32 v0, v8, v0, s26
	v_bfe_u32 v7, v9, 16, 1
	v_lshrrev_b32_e32 v0, 16, v0
	v_add3_u32 v7, v9, v7, s26
	v_add_co_u32_e32 v8, vcc, 0xe6000c00, v96
	v_and_or_b32 v7, v7, s24, v0
	s_nop 0
	v_addc_co_u32_e32 v9, vcc, -1, v97, vcc
	global_store_dwordx2 v[8:9], v[6:7], off
	s_and_saveexec_b64 s[0:1], s[38:39]
	s_cbranch_execz .LBB0_1088
	v_bfe_u32 v0, v2, 16, 1
	v_add3_u32 v0, v2, v0, s26
	v_bfe_u32 v2, v3, 16, 1
	v_lshrrev_b32_e32 v0, 16, v0
	v_add3_u32 v2, v3, v2, s26
	v_and_or_b32 v2, v2, s24, v0
	v_bfe_u32 v0, v4, 16, 1
	v_add3_u32 v0, v4, v0, s26
	v_bfe_u32 v3, v5, 16, 1
	v_lshrrev_b32_e32 v0, 16, v0
	v_add3_u32 v3, v5, v3, s26
	v_and_or_b32 v3, v3, s24, v0
	global_store_dwordx2 v[104:105], v[2:3], off offset:3072

; __device__ __forceinline__ unsigned pk2(float lo, float hi) { return f2bf(lo) | (f2bf(hi) << 16); }
; __device__ __forceinline__ void ln_phase(const Params& p, const int layer, const int row_lo, const int row_hi, const int wg_id, const int n_wg) {
;     ...
;             if (layer == 0) { o80[64 * j] = (unsigned long long)pk2(y0.x, y0.y) | ((unsigned long long)pk2(y0.z, y0.w) << 32);
;                 if (ok1) o81[64 * j] = (unsigned long long)pk2(y1.x, y1.y) | ((unsigned long long)pk2(y1.z, y1.w) << 32); }
.LBB0_1093:
	s_andn2_b64 vcc, exec, s[0:1]
	s_cbranch_vccnz .LBB0_1028
	v_bfe_u32 v0, v6, 16, 1
	v_add3_u32 v0, v6, v0, s26
	v_bfe_u32 v6, v7, 16, 1
	v_lshrrev_b32_e32 v0, 16, v0
	v_add3_u32 v6, v7, v6, s26
	v_and_or_b32 v6, v6, s24, v0
	v_bfe_u32 v0, v8, 16, 1
	v_add3_u32 v0, v8, v0, s26
	v_bfe_u32 v7, v9, 16, 1
	v_lshrrev_b32_e32 v0, 16, v0
	v_add3_u32 v7, v9, v7, s26
	v_add_co_u32_e32 v8, vcc, 0xe6000e00, v96
	v_and_or_b32 v7, v7, s24, v0
	s_nop 0
	v_addc_co_u32_e32 v9, vcc, -1, v97, vcc
	global_store_dwordx2 v[8:9], v[6:7], off
	s_and_saveexec_b64 s[0:1], s[38:39]
	s_cbranch_execz .LBB0_1027
	v_bfe_u32 v0, v2, 16, 1
	v_add3_u32 v0, v2, v0, s26
	v_bfe_u32 v2, v3, 16, 1
	v_lshrrev_b32_e32 v0, 16, v0
	v_add3_u32 v2, v3, v2, s26
	v_and_or_b32 v2, v2, s24, v0
	v_bfe_u32 v0, v4, 16, 1
	v_add3_u32 v0, v4, v0, s26
	v_bfe_u32 v3, v5, 16, 1
	v_lshrrev_b32_e32 v0, 16, v0
	v_add3_u32 v3, v5, v3, s26
	v_and_or_b32 v3, v3, s24, v0
	global_store_dwordx2 v[104:105], v[2:3], off offset:3584
	s_branch .LBB0_1027
